# GEMM SP2: moved LDS-DMA pieces now issued after the 14th and 30th MFMA of the segment (was 6th/18th)
# speedup vs baseline: 1.0316x; 1.0061x over previous
; #define PG8_STAGE(bufoff, gbase, voff) do { _Pragma("unroll") for (int _i = 0; _i < 2; ++_i) \
;         __builtin_amdgcn_global_load_lds((const unsigned*)((const char*)(gbase) + (voff)[_i]), (PG8_LAS unsigned*)(lds + (bufoff) + ldsw + _i * 8192), 16, 0, 0); } while (0)
; #define PG8_LDA(dst, b, h) do { _Pragma("unroll") for (int m = 0; m < 4; ++m) _Pragma("unroll") for (int k = 0; k < 2; ++k) dst[m][k] = *(const PG8_LAS bf16x8*)(lds + PG8_SA(b, h) + aoff + m * 2048 + k * 1024); } while (0)
; #define PG8_LDB(dst, b, h) do { _Pragma("unroll") for (int n = 0; n < 2; ++n) _Pragma("unroll") for (int k = 0; k < 2; ++k) dst[n][k] = *(const PG8_LAS bf16x8*)(lds + PG8_SB(b, h) + boff + n * 2048 + k * 1024); } while (0)
; #define PG8_MMA(ai, bj, At, Bt) do { __builtin_amdgcn_s_setprio(1); _Pragma("unroll") for (int m = 0; m < 4; ++m) _Pragma("unroll") for (int n = 0; n < 2; ++n) _Pragma("unroll") for (int k = 0; k < 2; ++k) \
;         acc[ai][bj][m][n] = __builtin_amdgcn_mfma_f32_16x16x32_bf16(Bt[n][k], At[m][k], acc[ai][bj][m][n], 0, 0, 0); __builtin_amdgcn_s_setprio(0); } while (0)
; #define PG8_BAR __builtin_amdgcn_s_barrier()
; template <class Epi, class Sched, bool ALIGN_EPI = false, bool SP2 = false>
; __device__ __forceinline__ void gemm_phase(PG8_LAS unsigned char* lds, const Gemm g, const Sched& S, const Epi& E) {
;     ...
;         const bool has_next = S.next(ui + 1, nxt);
;         const char* nA = has_next ? (const char*)g.A + (size_t)nxt.pm * tstep : cA; const char* nB = has_next ? (const char*)g.Bt + (size_t)nxt.pn * tstep : cB;
;         for (int t = 0; t < nt; t += 2) {
;             const bool last = (t == nt - 2);
;             const char* a1 = cA + (size_t)(t + 1) * kstep;
;             const char* a2 = last ? nA : cA + (size_t)(t + 2) * kstep; const char* b2 = last ? nB : cB + (size_t)(t + 2) * kstep;
;             const char* a3 = a2 + kstep; const char* b3 = b2 + kstep;
;             if (last && has_next) S.a_ready(nxt);
;             if constexpr (SP2) {
;             PG8_LDB(B0, 0, 0); PG8_LDB(B1, 0, 1); PG8_SCHED; PG8_LDA(At, 0, 0); PG8_STAGE(PG8_SA(1, 1), a1 + hstep, voffA);
;             PG8_WAIT_V(8); PG8_WAIT_L(0); PG8_BAR; PG8_MMA(0, 0, At, B0); PG8_MMA(0, 1, At, B1); PG8_BAR; PG8_SCHED;
;             PG8_LDA(At, 0, 1); PG8_STAGE(PG8_SB(0, 0), b2, voffB); PG8_STAGE(PG8_SB(0, 1), b2 + hstep, voffB); PG8_STAGE(PG8_SA(0, 0), a2, voffA);
.LBB0_190:
	s_ashr_i32 s27, s26, 31
	s_lshl_b64 s[14:15], s[26:27], 19
	s_add_u32 s28, s22, s14
	s_addc_u32 s29, s23, s15
	s_and_b64 s[14:15], s[0:1], exec
	s_cselect_b32 s27, s29, s49
	s_cselect_b32 s67, s28, s48
	s_ashr_i32 s25, s24, 31
	s_lshl_b64 s[14:15], s[24:25], 19
	s_add_u32 s40, s94, s14
	s_addc_u32 s41, s96, s15
	s_and_b64 s[14:15], s[0:1], exec
	s_cselect_b32 s25, s41, s51
	s_cselect_b32 s86, s40, s50
	s_add_u32 s48, s48, 0x40080
	s_addc_u32 s49, s49, 0
	s_add_u32 s87, s50, 0x100
	s_addc_u32 s88, s51, 0
	s_mov_b32 s89, -2
	ds_read_b128 v[144:147], v155
	ds_read_b128 v[148:151], v155 offset:1024
	ds_read_b128 v[160:163], v155 offset:2048
	ds_read_b128 v[168:171], v155 offset:3072
	ds_read_b128 v[172:175], v156
	ds_read_b128 v[176:179], v156 offset:1024
	ds_read_b128 v[182:185], v156 offset:2048
	ds_read_b128 v[186:189], v156 offset:3072
	s_add_u32 s3, s48, 0xfffc0080
	s_addc_u32 s14, s49, -1
	s_cmp_eq_u32 s89, 12
	s_cselect_b32 s55, s27, s14
	s_cselect_b32 s54, s67, s3
	s_cselect_b32 s51, s25, s88
	s_cselect_b32 s50, s86, s87
	v_lshl_add_u64 v[164:165], s[48:49], 0, v[136:137]
	s_add_i32 m0, s45, 0xc000
	ds_read_b128 v[190:193], v157
	ds_read_b128 v[194:197], v157 offset:1024
	ds_read_b128 v[198:201], v157 offset:2048
	ds_read_b128 v[208:211], v157 offset:3072
	ds_read_b128 v[212:215], v157 offset:4096
	ds_read_b128 v[216:219], v157 offset:5120
	ds_read_b128 v[220:223], v157 offset:6144
	ds_read_b128 v[224:227], v157 offset:7168
	global_load_lds_dwordx4 v[164:165], off
	v_lshl_add_u64 v[164:165], s[48:49], 0, v[138:139]
	s_add_i32 m0, s45, 0xe000
	s_nop 0
	global_load_lds_dwordx4 v[164:165], off
	s_waitcnt vmcnt(8)
	s_waitcnt lgkmcnt(0)
	s_barrier
	s_setprio 1
	s_waitcnt lgkmcnt(0)
	v_mfma_f32_16x16x32_bf16 v[124:127], v[144:147], v[190:193], 0
	v_mfma_f32_16x16x32_bf16 v[120:123], v[160:163], v[190:193], 0
	v_mfma_f32_16x16x32_bf16 v[108:111], v[144:147], v[198:201], 0
	v_mfma_f32_16x16x32_bf16 v[104:107], v[160:163], v[198:201], 0
	v_mfma_f32_16x16x32_bf16 v[92:95], v[144:147], v[212:215], 0
	v_mfma_f32_16x16x32_bf16 v[88:91], v[160:163], v[212:215], 0
	v_mfma_f32_16x16x32_bf16 v[76:79], v[144:147], v[220:223], 0
	v_mfma_f32_16x16x32_bf16 v[72:75], v[160:163], v[220:223], 0
	v_mfma_f32_16x16x32_bf16 v[124:127], v[148:151], v[194:197], v[124:127]
	v_mfma_f32_16x16x32_bf16 v[120:123], v[168:171], v[194:197], v[120:123]
	v_mfma_f32_16x16x32_bf16 v[108:111], v[148:151], v[208:211], v[108:111]
	v_mfma_f32_16x16x32_bf16 v[104:107], v[168:171], v[208:211], v[104:107]
	v_mfma_f32_16x16x32_bf16 v[92:95], v[148:151], v[216:219], v[92:95]
	v_mfma_f32_16x16x32_bf16 v[88:91], v[168:171], v[216:219], v[88:91]
	v_mfma_f32_16x16x32_bf16 v[76:79], v[148:151], v[224:227], v[76:79]
	v_mfma_f32_16x16x32_bf16 v[72:75], v[168:171], v[224:227], v[72:75]
	s_setprio 0
	s_setprio 1
	v_mfma_f32_16x16x32_bf16 v[116:119], v[172:175], v[190:193], 0
	v_mfma_f32_16x16x32_bf16 v[112:115], v[182:185], v[190:193], 0
	v_mfma_f32_16x16x32_bf16 v[100:103], v[172:175], v[198:201], 0
	v_mfma_f32_16x16x32_bf16 v[96:99], v[182:185], v[198:201], 0
	v_mfma_f32_16x16x32_bf16 v[84:87], v[172:175], v[212:215], 0
	v_mfma_f32_16x16x32_bf16 v[80:83], v[182:185], v[212:215], 0
	v_mfma_f32_16x16x32_bf16 v[68:71], v[172:175], v[220:223], 0
	v_mfma_f32_16x16x32_bf16 v[64:67], v[182:185], v[220:223], 0
	v_mfma_f32_16x16x32_bf16 v[116:119], v[176:179], v[194:197], v[116:119]
	v_mfma_f32_16x16x32_bf16 v[112:115], v[186:189], v[194:197], v[112:115]
	v_mfma_f32_16x16x32_bf16 v[100:103], v[176:179], v[208:211], v[100:103]
	v_mfma_f32_16x16x32_bf16 v[96:99], v[186:189], v[208:211], v[96:99]
	v_mfma_f32_16x16x32_bf16 v[84:87], v[176:179], v[216:219], v[84:87]
	v_mfma_f32_16x16x32_bf16 v[80:83], v[186:189], v[216:219], v[80:83]
	v_mfma_f32_16x16x32_bf16 v[68:71], v[176:179], v[224:227], v[68:71]
	v_mfma_f32_16x16x32_bf16 v[64:67], v[186:189], v[224:227], v[64:67]
	s_setprio 0
	s_barrier
	s_add_i32 s3, s63, s43
	v_lshl_add_u64 v[164:165], s[50:51], 0, v[132:133]
	s_mov_b32 m0, s3
	ds_read_b128 v[190:193], v157 offset:16384
	ds_read_b128 v[194:197], v157 offset:17408
	ds_read_b128 v[198:201], v157 offset:18432
	ds_read_b128 v[208:211], v157 offset:19456
	ds_read_b128 v[212:215], v157 offset:20480
	ds_read_b128 v[216:219], v157 offset:21504
	ds_read_b128 v[220:223], v157 offset:22528
	ds_read_b128 v[224:227], v157 offset:23552
	global_load_lds_dwordx4 v[164:165], off
	s_add_i32 m0, s3, 0x2000
	s_add_u32 s14, s50, 0x40000
	v_lshl_add_u64 v[202:203], s[50:51], 0, v[128:129]
	s_addc_u32 s15, s51, 0
	s_add_i32 s3, s64, s43
	global_load_lds_dwordx4 v[202:203], off
	v_lshl_add_u64 v[228:229], s[14:15], 0, v[132:133]
	s_mov_b32 m0, s3
	global_load_lds_dwordx4 v[228:229], off
	v_lshl_add_u64 v[228:229], s[14:15], 0, v[128:129]
	s_add_i32 m0, s3, 0x2000
	s_nop 0
	global_load_lds_dwordx4 v[228:229], off
	s_waitcnt vmcnt(6)
	s_waitcnt lgkmcnt(0)
	s_barrier
; #define PG8_STAGE(bufoff, gbase, voff) do { _Pragma("unroll") for (int _i = 0; _i < 2; ++_i) \
;         __builtin_amdgcn_global_load_lds((const unsigned*)((const char*)(gbase) + (voff)[_i]), (PG8_LAS unsigned*)(lds + (bufoff) + ldsw + _i * 8192), 16, 0, 0); } while (0)
; #define PG8_LDA(dst, b, h) do { _Pragma("unroll") for (int m = 0; m < 4; ++m) _Pragma("unroll") for (int k = 0; k < 2; ++k) dst[m][k] = *(const PG8_LAS bf16x8*)(lds + PG8_SA(b, h) + aoff + m * 2048 + k * 1024); } while (0)
; #define PG8_LDB(dst, b, h) do { _Pragma("unroll") for (int n = 0; n < 2; ++n) _Pragma("unroll") for (int k = 0; k < 2; ++k) dst[n][k] = *(const PG8_LAS bf16x8*)(lds + PG8_SB(b, h) + boff + n * 2048 + k * 1024); } while (0)
; #define PG8_MMA(ai, bj, At, Bt) do { __builtin_amdgcn_s_setprio(1); _Pragma("unroll") for (int m = 0; m < 4; ++m) _Pragma("unroll") for (int n = 0; n < 2; ++n) _Pragma("unroll") for (int k = 0; k < 2; ++k) \
;         acc[ai][bj][m][n] = __builtin_amdgcn_mfma_f32_16x16x32_bf16(Bt[n][k], At[m][k], acc[ai][bj][m][n], 0, 0, 0); __builtin_amdgcn_s_setprio(0); } while (0)
; #define PG8_WAIT_V(n) asm volatile("s_waitcnt vmcnt(" #n ")" ::: "memory")
; #define PG8_WAIT_L(n) asm volatile("s_waitcnt lgkmcnt(" #n ")" ::: "memory")
; #define PG8_BAR __builtin_amdgcn_s_barrier()
; #define PG8_SCHED __builtin_amdgcn_sched_barrier(0)
; template <class Epi, class Sched, bool ALIGN_EPI = false, bool SP2 = false>
; __device__ __forceinline__ void gemm_phase(PG8_LAS unsigned char* lds, const Gemm g, const Sched& S, const Epi& E) {
;     ...
;             PG8_LDA(At, 0, 1); PG8_STAGE(PG8_SB(0, 0), b2, voffB); PG8_STAGE(PG8_SB(0, 1), b2 + hstep, voffB); PG8_STAGE(PG8_SA(0, 0), a2, voffA);
;             PG8_WAIT_V(8); PG8_WAIT_L(0); PG8_BAR; PG8_MMA(1, 0, At, B0); PG8_MMA(1, 1, At, B1); PG8_BAR; PG8_SCHED;
;             PG8_LDB(B0, 1, 0); PG8_LDB(B1, 1, 1); PG8_SCHED; PG8_LDA(At, 1, 0); PG8_STAGE(PG8_SA(0, 1), a2 + hstep, voffA);
;             PG8_WAIT_V(8); PG8_WAIT_L(0); PG8_BAR; PG8_MMA(0, 0, At, B0); PG8_MMA(0, 1, At, B1); PG8_BAR; PG8_SCHED;
	s_setprio 1
	s_waitcnt lgkmcnt(0)
	v_mfma_f32_16x16x32_bf16 v[60:63], v[144:147], v[190:193], 0
	v_mfma_f32_16x16x32_bf16 v[56:59], v[160:163], v[190:193], 0
	v_mfma_f32_16x16x32_bf16 v[44:47], v[144:147], v[198:201], 0
	v_mfma_f32_16x16x32_bf16 v[40:43], v[160:163], v[198:201], 0
	v_mfma_f32_16x16x32_bf16 v[28:31], v[144:147], v[212:215], 0
	v_mfma_f32_16x16x32_bf16 v[24:27], v[160:163], v[212:215], 0
	v_mfma_f32_16x16x32_bf16 v[12:15], v[144:147], v[220:223], 0
	v_mfma_f32_16x16x32_bf16 v[8:11], v[160:163], v[220:223], 0
	v_mfma_f32_16x16x32_bf16 v[60:63], v[148:151], v[194:197], v[60:63]
	v_mfma_f32_16x16x32_bf16 v[56:59], v[168:171], v[194:197], v[56:59]
	v_mfma_f32_16x16x32_bf16 v[44:47], v[148:151], v[208:211], v[44:47]
	v_mfma_f32_16x16x32_bf16 v[40:43], v[168:171], v[208:211], v[40:43]
	v_mfma_f32_16x16x32_bf16 v[28:31], v[148:151], v[216:219], v[28:31]
	v_mfma_f32_16x16x32_bf16 v[24:27], v[168:171], v[216:219], v[24:27]
	v_lshl_add_u64 v[228:229], s[54:55], 0, v[134:135]
	s_mov_b32 m0, s45
	s_nop 0
	global_load_lds_dwordx4 v[228:229], off
	v_mfma_f32_16x16x32_bf16 v[12:15], v[148:151], v[224:227], v[12:15]
	v_mfma_f32_16x16x32_bf16 v[8:11], v[168:171], v[224:227], v[8:11]
	s_setprio 0
	s_setprio 1
	v_mfma_f32_16x16x32_bf16 v[52:55], v[172:175], v[190:193], 0
	v_mfma_f32_16x16x32_bf16 v[48:51], v[182:185], v[190:193], 0
	v_mfma_f32_16x16x32_bf16 v[36:39], v[172:175], v[198:201], 0
	v_mfma_f32_16x16x32_bf16 v[32:35], v[182:185], v[198:201], 0
	v_mfma_f32_16x16x32_bf16 v[20:23], v[172:175], v[212:215], 0
	v_mfma_f32_16x16x32_bf16 v[16:19], v[182:185], v[212:215], 0
	v_mfma_f32_16x16x32_bf16 v[4:7], v[172:175], v[220:223], 0
	v_mfma_f32_16x16x32_bf16 v[0:3], v[182:185], v[220:223], 0
	v_mfma_f32_16x16x32_bf16 v[52:55], v[176:179], v[194:197], v[52:55]
	v_mfma_f32_16x16x32_bf16 v[48:51], v[186:189], v[194:197], v[48:51]
	v_mfma_f32_16x16x32_bf16 v[36:39], v[176:179], v[208:211], v[36:39]
	v_mfma_f32_16x16x32_bf16 v[32:35], v[186:189], v[208:211], v[32:35]
	v_mfma_f32_16x16x32_bf16 v[20:23], v[176:179], v[216:219], v[20:23]
	v_mfma_f32_16x16x32_bf16 v[16:19], v[186:189], v[216:219], v[16:19]
	v_lshl_add_u64 v[230:231], s[54:55], 0, v[130:131]
	s_mov_b32 m0, s57
	s_nop 0
	global_load_lds_dwordx4 v[230:231], off
	v_mfma_f32_16x16x32_bf16 v[4:7], v[176:179], v[224:227], v[4:7]
	v_mfma_f32_16x16x32_bf16 v[0:3], v[186:189], v[224:227], v[0:3]
	s_setprio 0
	s_barrier
	s_add_i32 s3, 0, 0x18000
	v_add_u32_e32 v159, s3, v153
	s_add_i32 s33, 0, 0x1c000
	ds_read_b128 v[144:147], v159
	ds_read_b128 v[148:151], v159 offset:1024
	ds_read_b128 v[160:163], v159 offset:2048
	ds_read_b128 v[168:171], v159 offset:3072
	v_add_u32_e32 v159, s33, v153
	ds_read_b128 v[172:175], v159
	ds_read_b128 v[176:179], v159 offset:1024
	ds_read_b128 v[182:185], v159 offset:2048
	ds_read_b128 v[186:189], v159 offset:3072
	s_add_u32 s14, s54, 0x40000
	s_addc_u32 s15, s55, 0
	s_mov_b32 m0, s58
	v_lshl_add_u64 v[232:233], s[14:15], 0, v[134:135]
	ds_read_b128 v[190:193], v157 offset:32768
	ds_read_b128 v[194:197], v157 offset:33792
	ds_read_b128 v[198:201], v157 offset:34816
	ds_read_b128 v[208:211], v157 offset:35840
	ds_read_b128 v[212:215], v157 offset:36864
	ds_read_b128 v[216:219], v157 offset:37888
	ds_read_b128 v[220:223], v157 offset:38912
	ds_read_b128 v[224:227], v157 offset:39936
	global_load_lds_dwordx4 v[232:233], off
	v_lshl_add_u64 v[232:233], s[14:15], 0, v[130:131]
	s_mov_b32 m0, s59
	s_nop 0
	global_load_lds_dwordx4 v[232:233], off
	s_waitcnt vmcnt(8)
	s_waitcnt lgkmcnt(0)
	s_barrier
	s_setprio 1
	s_waitcnt lgkmcnt(0)
	v_mfma_f32_16x16x32_bf16 v[124:127], v[144:147], v[190:193], v[124:127]
	v_mfma_f32_16x16x32_bf16 v[120:123], v[160:163], v[190:193], v[120:123]
	v_mfma_f32_16x16x32_bf16 v[108:111], v[144:147], v[198:201], v[108:111]
	v_mfma_f32_16x16x32_bf16 v[104:107], v[160:163], v[198:201], v[104:107]
	v_mfma_f32_16x16x32_bf16 v[92:95], v[144:147], v[212:215], v[92:95]
	v_mfma_f32_16x16x32_bf16 v[88:91], v[160:163], v[212:215], v[88:91]
	v_mfma_f32_16x16x32_bf16 v[76:79], v[144:147], v[220:223], v[76:79]
	v_mfma_f32_16x16x32_bf16 v[72:75], v[160:163], v[220:223], v[72:75]
	v_mfma_f32_16x16x32_bf16 v[124:127], v[148:151], v[194:197], v[124:127]
	v_mfma_f32_16x16x32_bf16 v[120:123], v[168:171], v[194:197], v[120:123]
	v_mfma_f32_16x16x32_bf16 v[108:111], v[148:151], v[208:211], v[108:111]
	v_mfma_f32_16x16x32_bf16 v[104:107], v[168:171], v[208:211], v[104:107]
	v_mfma_f32_16x16x32_bf16 v[92:95], v[148:151], v[216:219], v[92:95]
	v_mfma_f32_16x16x32_bf16 v[88:91], v[168:171], v[216:219], v[88:91]
	v_mfma_f32_16x16x32_bf16 v[76:79], v[148:151], v[224:227], v[76:79]
	v_mfma_f32_16x16x32_bf16 v[72:75], v[168:171], v[224:227], v[72:75]
	s_setprio 0
	s_setprio 1
	v_mfma_f32_16x16x32_bf16 v[116:119], v[172:175], v[190:193], v[116:119]
	v_mfma_f32_16x16x32_bf16 v[112:115], v[182:185], v[190:193], v[112:115]
	v_mfma_f32_16x16x32_bf16 v[100:103], v[172:175], v[198:201], v[100:103]
	v_mfma_f32_16x16x32_bf16 v[96:99], v[182:185], v[198:201], v[96:99]
	v_mfma_f32_16x16x32_bf16 v[84:87], v[172:175], v[212:215], v[84:87]
	v_mfma_f32_16x16x32_bf16 v[80:83], v[182:185], v[212:215], v[80:83]
	v_mfma_f32_16x16x32_bf16 v[68:71], v[172:175], v[220:223], v[68:71]
	v_mfma_f32_16x16x32_bf16 v[64:67], v[182:185], v[220:223], v[64:67]
	v_mfma_f32_16x16x32_bf16 v[116:119], v[176:179], v[194:197], v[116:119]
	v_mfma_f32_16x16x32_bf16 v[112:115], v[186:189], v[194:197], v[112:115]
	v_mfma_f32_16x16x32_bf16 v[100:103], v[176:179], v[208:211], v[100:103]
	v_mfma_f32_16x16x32_bf16 v[96:99], v[186:189], v[208:211], v[96:99]
	v_mfma_f32_16x16x32_bf16 v[84:87], v[176:179], v[216:219], v[84:87]
	v_mfma_f32_16x16x32_bf16 v[80:83], v[186:189], v[216:219], v[80:83]
	v_mfma_f32_16x16x32_bf16 v[68:71], v[176:179], v[224:227], v[68:71]
	v_mfma_f32_16x16x32_bf16 v[64:67], v[186:189], v[224:227], v[64:67]
	s_setprio 0
	s_barrier
; #define PG8_STAGE(bufoff, gbase, voff) do { _Pragma("unroll") for (int _i = 0; _i < 2; ++_i) \
;         __builtin_amdgcn_global_load_lds((const unsigned*)((const char*)(gbase) + (voff)[_i]), (PG8_LAS unsigned*)(lds + (bufoff) + ldsw + _i * 8192), 16, 0, 0); } while (0)
; #define PG8_LDA(dst, b, h) do { _Pragma("unroll") for (int m = 0; m < 4; ++m) _Pragma("unroll") for (int k = 0; k < 2; ++k) dst[m][k] = *(const PG8_LAS bf16x8*)(lds + PG8_SA(b, h) + aoff + m * 2048 + k * 1024); } while (0)
; #define PG8_LDB(dst, b, h) do { _Pragma("unroll") for (int n = 0; n < 2; ++n) _Pragma("unroll") for (int k = 0; k < 2; ++k) dst[n][k] = *(const PG8_LAS bf16x8*)(lds + PG8_SB(b, h) + boff + n * 2048 + k * 1024); } while (0)
; template <class Epi, class Sched, bool ALIGN_EPI = false, bool SP2 = false>
; __device__ __forceinline__ void gemm_phase(PG8_LAS unsigned char* lds, const Gemm g, const Sched& S, const Epi& E) {
;     ...
;         for (int t = 0; t < nt; t += 2) {
;             const bool last = (t == nt - 2);
;             const char* a1 = cA + (size_t)(t + 1) * kstep;
;             const char* a2 = last ? nA : cA + (size_t)(t + 2) * kstep; const char* b2 = last ? nB : cB + (size_t)(t + 2) * kstep;
;             const char* a3 = a2 + kstep; const char* b3 = b2 + kstep;
;             if (last && has_next) S.a_ready(nxt);
;             if constexpr (SP2) {
;             PG8_LDB(B0, 0, 0); PG8_LDB(B1, 0, 1); PG8_SCHED; PG8_LDA(At, 0, 0); PG8_STAGE(PG8_SA(1, 1), a1 + hstep, voffA);
;             PG8_WAIT_V(8); PG8_WAIT_L(0); PG8_BAR; PG8_MMA(0, 0, At, B0); PG8_MMA(0, 1, At, B1); PG8_BAR; PG8_SCHED;
;             PG8_LDA(At, 0, 1); PG8_STAGE(PG8_SB(0, 0), b2, voffB); PG8_STAGE(PG8_SB(0, 1), b2 + hstep, voffB); PG8_STAGE(PG8_SA(0, 0), a2, voffA);
;             PG8_WAIT_V(8); PG8_WAIT_L(0); PG8_BAR; PG8_MMA(1, 0, At, B0); PG8_MMA(1, 1, At, B1); PG8_BAR; PG8_SCHED;
;             PG8_LDB(B0, 1, 0); PG8_LDB(B1, 1, 1); PG8_SCHED; PG8_LDA(At, 1, 0); PG8_STAGE(PG8_SA(0, 1), a2 + hstep, voffA);
;             PG8_WAIT_V(8); PG8_WAIT_L(0); PG8_BAR; PG8_MMA(0, 0, At, B0); PG8_MMA(0, 1, At, B1); PG8_BAR; PG8_SCHED;
;             PG8_LDA(At, 1, 1); PG8_STAGE(PG8_SB(1, 0), b3, voffB); PG8_STAGE(PG8_SB(1, 1), b3 + hstep, voffB); PG8_STAGE(PG8_SA(1, 0), a3, voffA);
;             PG8_WAIT_V(8); PG8_WAIT_L(0); PG8_BAR; PG8_MMA(1, 0, At, B0); PG8_MMA(1, 1, At, B1); PG8_BAR; PG8_SCHED;
	s_add_i32 s3, s3, s43
	v_lshl_add_u64 v[164:165], v[164:165], 0, s[10:11]
	s_mov_b32 m0, s3
	ds_read_b128 v[190:193], v157 offset:49152
	ds_read_b128 v[194:197], v157 offset:50176
	ds_read_b128 v[198:201], v157 offset:51200
	ds_read_b128 v[208:211], v157 offset:52224
	ds_read_b128 v[212:215], v157 offset:53248
	ds_read_b128 v[216:219], v157 offset:54272
	ds_read_b128 v[220:223], v157 offset:55296
	ds_read_b128 v[224:227], v157 offset:56320
	global_load_lds_dwordx4 v[164:165], off
	s_add_i32 m0, s3, 0x2000
	s_add_u32 s14, s50, 0x40080
	v_lshl_add_u64 v[164:165], v[202:203], 0, s[10:11]
	s_addc_u32 s15, s51, 0
	s_add_i32 s3, s33, s43
	global_load_lds_dwordx4 v[164:165], off
	v_lshl_add_u64 v[164:165], s[14:15], 0, v[132:133]
	s_mov_b32 m0, s3
	s_nop 0
	global_load_lds_dwordx4 v[164:165], off
	v_lshl_add_u64 v[164:165], s[14:15], 0, v[128:129]
	s_add_i32 m0, s3, 0x2000
	s_nop 0
	global_load_lds_dwordx4 v[164:165], off
	s_waitcnt vmcnt(6)
	s_waitcnt lgkmcnt(0)
	s_barrier
	s_setprio 1
	s_waitcnt lgkmcnt(0)
	v_mfma_f32_16x16x32_bf16 v[60:63], v[144:147], v[190:193], v[60:63]
	v_mfma_f32_16x16x32_bf16 v[56:59], v[160:163], v[190:193], v[56:59]
	v_mfma_f32_16x16x32_bf16 v[44:47], v[144:147], v[198:201], v[44:47]
	v_mfma_f32_16x16x32_bf16 v[40:43], v[160:163], v[198:201], v[40:43]
	v_mfma_f32_16x16x32_bf16 v[28:31], v[144:147], v[212:215], v[28:31]
	v_mfma_f32_16x16x32_bf16 v[24:27], v[160:163], v[212:215], v[24:27]
	v_mfma_f32_16x16x32_bf16 v[12:15], v[144:147], v[220:223], v[12:15]
	v_mfma_f32_16x16x32_bf16 v[8:11], v[160:163], v[220:223], v[8:11]
	v_mfma_f32_16x16x32_bf16 v[60:63], v[148:151], v[194:197], v[60:63]
	v_mfma_f32_16x16x32_bf16 v[56:59], v[168:171], v[194:197], v[56:59]
	v_mfma_f32_16x16x32_bf16 v[44:47], v[148:151], v[208:211], v[44:47]
	v_mfma_f32_16x16x32_bf16 v[40:43], v[168:171], v[208:211], v[40:43]
	v_mfma_f32_16x16x32_bf16 v[28:31], v[148:151], v[216:219], v[28:31]
	v_mfma_f32_16x16x32_bf16 v[24:27], v[168:171], v[216:219], v[24:27]
	v_lshl_add_u64 v[164:165], v[228:229], 0, s[10:11]
	s_mov_b32 m0, s61
	s_nop 0
	global_load_lds_dwordx4 v[164:165], off
	v_mfma_f32_16x16x32_bf16 v[12:15], v[148:151], v[224:227], v[12:15]
	v_mfma_f32_16x16x32_bf16 v[8:11], v[168:171], v[224:227], v[8:11]
	s_setprio 0
	s_setprio 1
	v_mfma_f32_16x16x32_bf16 v[52:55], v[172:175], v[190:193], v[52:55]
	v_mfma_f32_16x16x32_bf16 v[48:51], v[182:185], v[190:193], v[48:51]
	v_mfma_f32_16x16x32_bf16 v[36:39], v[172:175], v[198:201], v[36:39]
	v_mfma_f32_16x16x32_bf16 v[32:35], v[182:185], v[198:201], v[32:35]
	v_mfma_f32_16x16x32_bf16 v[20:23], v[172:175], v[212:215], v[20:23]
	v_mfma_f32_16x16x32_bf16 v[16:19], v[182:185], v[212:215], v[16:19]
	v_mfma_f32_16x16x32_bf16 v[4:7], v[172:175], v[220:223], v[4:7]
	v_mfma_f32_16x16x32_bf16 v[0:3], v[182:185], v[220:223], v[0:3]
	v_mfma_f32_16x16x32_bf16 v[52:55], v[176:179], v[194:197], v[52:55]
	v_mfma_f32_16x16x32_bf16 v[48:51], v[186:189], v[194:197], v[48:51]
	v_mfma_f32_16x16x32_bf16 v[36:39], v[176:179], v[208:211], v[36:39]
	v_mfma_f32_16x16x32_bf16 v[32:35], v[186:189], v[208:211], v[32:35]
	v_mfma_f32_16x16x32_bf16 v[20:23], v[176:179], v[216:219], v[20:23]
	v_mfma_f32_16x16x32_bf16 v[16:19], v[186:189], v[216:219], v[16:19]
	v_lshl_add_u64 v[164:165], v[230:231], 0, s[10:11]
	s_mov_b32 m0, s62
	s_nop 0
	global_load_lds_dwordx4 v[164:165], off
	v_mfma_f32_16x16x32_bf16 v[4:7], v[176:179], v[224:227], v[4:7]
	v_mfma_f32_16x16x32_bf16 v[0:3], v[186:189], v[224:227], v[0:3]
	s_setprio 0
	s_barrier
	s_add_i32 s89, s89, 2
	s_add_u32 s48, s48, 0x100
	s_addc_u32 s49, s49, 0
	s_add_u32 s87, s87, 0x100
	s_addc_u32 s88, s88, 0
.LBB0_191:
	ds_read_b128 v[144:147], v155
	ds_read_b128 v[148:151], v155 offset:1024
	ds_read_b128 v[160:163], v155 offset:2048
	ds_read_b128 v[168:171], v155 offset:3072
	ds_read_b128 v[172:175], v156
	ds_read_b128 v[176:179], v156 offset:1024
	ds_read_b128 v[182:185], v156 offset:2048
	ds_read_b128 v[186:189], v156 offset:3072
	s_add_u32 s3, s48, 0xfffc0080
	s_addc_u32 s14, s49, -1
	s_cmp_eq_u32 s89, 12
	s_cselect_b32 s55, s27, s14
	s_cselect_b32 s54, s67, s3
	s_cselect_b32 s51, s25, s88
	s_cselect_b32 s50, s86, s87
	v_lshl_add_u64 v[164:165], s[48:49], 0, v[136:137]
	s_add_i32 m0, s45, 0xc000
	ds_read_b128 v[190:193], v157
	ds_read_b128 v[194:197], v157 offset:1024
	ds_read_b128 v[198:201], v157 offset:2048
	ds_read_b128 v[208:211], v157 offset:3072
	ds_read_b128 v[212:215], v157 offset:4096
	ds_read_b128 v[216:219], v157 offset:5120
	ds_read_b128 v[220:223], v157 offset:6144
	ds_read_b128 v[224:227], v157 offset:7168
	global_load_lds_dwordx4 v[164:165], off
	v_lshl_add_u64 v[164:165], s[48:49], 0, v[138:139]
	s_add_i32 m0, s45, 0xe000
	s_nop 0
	global_load_lds_dwordx4 v[164:165], off
	s_waitcnt vmcnt(8)
	s_waitcnt lgkmcnt(0)
	s_barrier
; #define PG8_STAGE(bufoff, gbase, voff) do { _Pragma("unroll") for (int _i = 0; _i < 2; ++_i) \
;         __builtin_amdgcn_global_load_lds((const unsigned*)((const char*)(gbase) + (voff)[_i]), (PG8_LAS unsigned*)(lds + (bufoff) + ldsw + _i * 8192), 16, 0, 0); } while (0)
; #define PG8_LDA(dst, b, h) do { _Pragma("unroll") for (int m = 0; m < 4; ++m) _Pragma("unroll") for (int k = 0; k < 2; ++k) dst[m][k] = *(const PG8_LAS bf16x8*)(lds + PG8_SA(b, h) + aoff + m * 2048 + k * 1024); } while (0)
; #define PG8_LDB(dst, b, h) do { _Pragma("unroll") for (int n = 0; n < 2; ++n) _Pragma("unroll") for (int k = 0; k < 2; ++k) dst[n][k] = *(const PG8_LAS bf16x8*)(lds + PG8_SB(b, h) + boff + n * 2048 + k * 1024); } while (0)
; #define PG8_MMA(ai, bj, At, Bt) do { __builtin_amdgcn_s_setprio(1); _Pragma("unroll") for (int m = 0; m < 4; ++m) _Pragma("unroll") for (int n = 0; n < 2; ++n) _Pragma("unroll") for (int k = 0; k < 2; ++k) \
;         acc[ai][bj][m][n] = __builtin_amdgcn_mfma_f32_16x16x32_bf16(Bt[n][k], At[m][k], acc[ai][bj][m][n], 0, 0, 0); __builtin_amdgcn_s_setprio(0); } while (0)
; #define PG8_WAIT_V(n) asm volatile("s_waitcnt vmcnt(" #n ")" ::: "memory")
; #define PG8_WAIT_L(n) asm volatile("s_waitcnt lgkmcnt(" #n ")" ::: "memory")
; #define PG8_BAR __builtin_amdgcn_s_barrier()
; #define PG8_SCHED __builtin_amdgcn_sched_barrier(0)
; template <class Epi, class Sched, bool ALIGN_EPI = false, bool SP2 = false>
; __device__ __forceinline__ void gemm_phase(PG8_LAS unsigned char* lds, const Gemm g, const Sched& S, const Epi& E) {
;     ...
;             PG8_LDB(B0, 0, 0); PG8_LDB(B1, 0, 1); PG8_SCHED; PG8_LDA(At, 0, 0); PG8_STAGE(PG8_SA(1, 1), a1 + hstep, voffA);
;             PG8_WAIT_V(8); PG8_WAIT_L(0); PG8_BAR; PG8_MMA(0, 0, At, B0); PG8_MMA(0, 1, At, B1); PG8_BAR; PG8_SCHED;
;             PG8_LDA(At, 0, 1); PG8_STAGE(PG8_SB(0, 0), b2, voffB); PG8_STAGE(PG8_SB(0, 1), b2 + hstep, voffB); PG8_STAGE(PG8_SA(0, 0), a2, voffA);
;             PG8_WAIT_V(8); PG8_WAIT_L(0); PG8_BAR; PG8_MMA(1, 0, At, B0); PG8_MMA(1, 1, At, B1); PG8_BAR; PG8_SCHED;
	s_setprio 1
	s_waitcnt lgkmcnt(0)
	v_mfma_f32_16x16x32_bf16 v[124:127], v[144:147], v[190:193], v[124:127]
	v_mfma_f32_16x16x32_bf16 v[120:123], v[160:163], v[190:193], v[120:123]
	v_mfma_f32_16x16x32_bf16 v[108:111], v[144:147], v[198:201], v[108:111]
	v_mfma_f32_16x16x32_bf16 v[104:107], v[160:163], v[198:201], v[104:107]
	v_mfma_f32_16x16x32_bf16 v[92:95], v[144:147], v[212:215], v[92:95]
	v_mfma_f32_16x16x32_bf16 v[88:91], v[160:163], v[212:215], v[88:91]
	v_mfma_f32_16x16x32_bf16 v[76:79], v[144:147], v[220:223], v[76:79]
	v_mfma_f32_16x16x32_bf16 v[72:75], v[160:163], v[220:223], v[72:75]
	v_mfma_f32_16x16x32_bf16 v[124:127], v[148:151], v[194:197], v[124:127]
	v_mfma_f32_16x16x32_bf16 v[120:123], v[168:171], v[194:197], v[120:123]
	v_mfma_f32_16x16x32_bf16 v[108:111], v[148:151], v[208:211], v[108:111]
	v_mfma_f32_16x16x32_bf16 v[104:107], v[168:171], v[208:211], v[104:107]
	v_mfma_f32_16x16x32_bf16 v[92:95], v[148:151], v[216:219], v[92:95]
	v_mfma_f32_16x16x32_bf16 v[88:91], v[168:171], v[216:219], v[88:91]
	v_mfma_f32_16x16x32_bf16 v[76:79], v[148:151], v[224:227], v[76:79]
	v_mfma_f32_16x16x32_bf16 v[72:75], v[168:171], v[224:227], v[72:75]
	s_setprio 0
	s_setprio 1
	v_mfma_f32_16x16x32_bf16 v[116:119], v[172:175], v[190:193], v[116:119]
	v_mfma_f32_16x16x32_bf16 v[112:115], v[182:185], v[190:193], v[112:115]
	v_mfma_f32_16x16x32_bf16 v[100:103], v[172:175], v[198:201], v[100:103]
	v_mfma_f32_16x16x32_bf16 v[96:99], v[182:185], v[198:201], v[96:99]
	v_mfma_f32_16x16x32_bf16 v[84:87], v[172:175], v[212:215], v[84:87]
	v_mfma_f32_16x16x32_bf16 v[80:83], v[182:185], v[212:215], v[80:83]
	v_mfma_f32_16x16x32_bf16 v[68:71], v[172:175], v[220:223], v[68:71]
	v_mfma_f32_16x16x32_bf16 v[64:67], v[182:185], v[220:223], v[64:67]
	v_mfma_f32_16x16x32_bf16 v[116:119], v[176:179], v[194:197], v[116:119]
	v_mfma_f32_16x16x32_bf16 v[112:115], v[186:189], v[194:197], v[112:115]
	v_mfma_f32_16x16x32_bf16 v[100:103], v[176:179], v[208:211], v[100:103]
	v_mfma_f32_16x16x32_bf16 v[96:99], v[186:189], v[208:211], v[96:99]
	v_mfma_f32_16x16x32_bf16 v[84:87], v[176:179], v[216:219], v[84:87]
	v_mfma_f32_16x16x32_bf16 v[80:83], v[186:189], v[216:219], v[80:83]
	v_mfma_f32_16x16x32_bf16 v[68:71], v[176:179], v[224:227], v[68:71]
	v_mfma_f32_16x16x32_bf16 v[64:67], v[186:189], v[224:227], v[64:67]
	s_setprio 0
	s_barrier
	s_add_i32 s3, s63, s43
	v_lshl_add_u64 v[164:165], s[50:51], 0, v[132:133]
	s_mov_b32 m0, s3
	ds_read_b128 v[190:193], v157 offset:16384
	ds_read_b128 v[194:197], v157 offset:17408
	ds_read_b128 v[198:201], v157 offset:18432
	ds_read_b128 v[208:211], v157 offset:19456
	ds_read_b128 v[212:215], v157 offset:20480
	ds_read_b128 v[216:219], v157 offset:21504
	ds_read_b128 v[220:223], v157 offset:22528
	ds_read_b128 v[224:227], v157 offset:23552
	global_load_lds_dwordx4 v[164:165], off
	s_add_i32 m0, s3, 0x2000
	s_add_u32 s14, s50, 0x40000
	v_lshl_add_u64 v[202:203], s[50:51], 0, v[128:129]
	s_addc_u32 s15, s51, 0
	s_add_i32 s3, s64, s43
	global_load_lds_dwordx4 v[202:203], off
	v_lshl_add_u64 v[228:229], s[14:15], 0, v[132:133]
	s_mov_b32 m0, s3
	global_load_lds_dwordx4 v[228:229], off
	v_lshl_add_u64 v[228:229], s[14:15], 0, v[128:129]
	s_add_i32 m0, s3, 0x2000
	s_nop 0
	global_load_lds_dwordx4 v[228:229], off
	s_waitcnt vmcnt(6)
	s_waitcnt lgkmcnt(0)
	s_barrier
	s_setprio 1
	s_waitcnt lgkmcnt(0)
	v_mfma_f32_16x16x32_bf16 v[60:63], v[144:147], v[190:193], v[60:63]
	v_mfma_f32_16x16x32_bf16 v[56:59], v[160:163], v[190:193], v[56:59]
	v_mfma_f32_16x16x32_bf16 v[44:47], v[144:147], v[198:201], v[44:47]
	v_mfma_f32_16x16x32_bf16 v[40:43], v[160:163], v[198:201], v[40:43]
	v_mfma_f32_16x16x32_bf16 v[28:31], v[144:147], v[212:215], v[28:31]
	v_mfma_f32_16x16x32_bf16 v[24:27], v[160:163], v[212:215], v[24:27]
	v_mfma_f32_16x16x32_bf16 v[12:15], v[144:147], v[220:223], v[12:15]
	v_mfma_f32_16x16x32_bf16 v[8:11], v[160:163], v[220:223], v[8:11]
	v_mfma_f32_16x16x32_bf16 v[60:63], v[148:151], v[194:197], v[60:63]
	v_mfma_f32_16x16x32_bf16 v[56:59], v[168:171], v[194:197], v[56:59]
	v_mfma_f32_16x16x32_bf16 v[44:47], v[148:151], v[208:211], v[44:47]
	v_mfma_f32_16x16x32_bf16 v[40:43], v[168:171], v[208:211], v[40:43]
	v_mfma_f32_16x16x32_bf16 v[28:31], v[148:151], v[216:219], v[28:31]
	v_mfma_f32_16x16x32_bf16 v[24:27], v[168:171], v[216:219], v[24:27]
	v_lshl_add_u64 v[228:229], s[54:55], 0, v[134:135]
	s_mov_b32 m0, s45
	s_nop 0
	global_load_lds_dwordx4 v[228:229], off
	v_mfma_f32_16x16x32_bf16 v[12:15], v[148:151], v[224:227], v[12:15]
	v_mfma_f32_16x16x32_bf16 v[8:11], v[168:171], v[224:227], v[8:11]
	s_setprio 0
	s_setprio 1
	v_mfma_f32_16x16x32_bf16 v[52:55], v[172:175], v[190:193], v[52:55]
	v_mfma_f32_16x16x32_bf16 v[48:51], v[182:185], v[190:193], v[48:51]
	v_mfma_f32_16x16x32_bf16 v[36:39], v[172:175], v[198:201], v[36:39]
	v_mfma_f32_16x16x32_bf16 v[32:35], v[182:185], v[198:201], v[32:35]
	v_mfma_f32_16x16x32_bf16 v[20:23], v[172:175], v[212:215], v[20:23]
	v_mfma_f32_16x16x32_bf16 v[16:19], v[182:185], v[212:215], v[16:19]
	v_mfma_f32_16x16x32_bf16 v[4:7], v[172:175], v[220:223], v[4:7]
	v_mfma_f32_16x16x32_bf16 v[0:3], v[182:185], v[220:223], v[0:3]
	v_mfma_f32_16x16x32_bf16 v[52:55], v[176:179], v[194:197], v[52:55]
	v_mfma_f32_16x16x32_bf16 v[48:51], v[186:189], v[194:197], v[48:51]
	v_mfma_f32_16x16x32_bf16 v[36:39], v[176:179], v[208:211], v[36:39]
	v_mfma_f32_16x16x32_bf16 v[32:35], v[186:189], v[208:211], v[32:35]
	v_mfma_f32_16x16x32_bf16 v[20:23], v[176:179], v[216:219], v[20:23]
	v_mfma_f32_16x16x32_bf16 v[16:19], v[186:189], v[216:219], v[16:19]
	v_lshl_add_u64 v[230:231], s[54:55], 0, v[130:131]
	s_mov_b32 m0, s57
	s_nop 0
	global_load_lds_dwordx4 v[230:231], off
	v_mfma_f32_16x16x32_bf16 v[4:7], v[176:179], v[224:227], v[4:7]
	v_mfma_f32_16x16x32_bf16 v[0:3], v[186:189], v[224:227], v[0:3]
	s_setprio 0
	s_barrier
; #define PG8_STAGE(bufoff, gbase, voff) do { _Pragma("unroll") for (int _i = 0; _i < 2; ++_i) \
;         __builtin_amdgcn_global_load_lds((const unsigned*)((const char*)(gbase) + (voff)[_i]), (PG8_LAS unsigned*)(lds + (bufoff) + ldsw + _i * 8192), 16, 0, 0); } while (0)
; #define PG8_LDA(dst, b, h) do { _Pragma("unroll") for (int m = 0; m < 4; ++m) _Pragma("unroll") for (int k = 0; k < 2; ++k) dst[m][k] = *(const PG8_LAS bf16x8*)(lds + PG8_SA(b, h) + aoff + m * 2048 + k * 1024); } while (0)
; #define PG8_LDB(dst, b, h) do { _Pragma("unroll") for (int n = 0; n < 2; ++n) _Pragma("unroll") for (int k = 0; k < 2; ++k) dst[n][k] = *(const PG8_LAS bf16x8*)(lds + PG8_SB(b, h) + boff + n * 2048 + k * 1024); } while (0)
; #define PG8_MMA(ai, bj, At, Bt) do { __builtin_amdgcn_s_setprio(1); _Pragma("unroll") for (int m = 0; m < 4; ++m) _Pragma("unroll") for (int n = 0; n < 2; ++n) _Pragma("unroll") for (int k = 0; k < 2; ++k) \
;         acc[ai][bj][m][n] = __builtin_amdgcn_mfma_f32_16x16x32_bf16(Bt[n][k], At[m][k], acc[ai][bj][m][n], 0, 0, 0); __builtin_amdgcn_s_setprio(0); } while (0)
; #define PG8_WAIT_V(n) asm volatile("s_waitcnt vmcnt(" #n ")" ::: "memory")
; #define PG8_WAIT_L(n) asm volatile("s_waitcnt lgkmcnt(" #n ")" ::: "memory")
; #define PG8_BAR __builtin_amdgcn_s_barrier()
; #define PG8_SCHED __builtin_amdgcn_sched_barrier(0)
; template <class Epi, class Sched, bool ALIGN_EPI = false, bool SP2 = false>
; __device__ __forceinline__ void gemm_phase(PG8_LAS unsigned char* lds, const Gemm g, const Sched& S, const Epi& E) {
;     ...
;             PG8_LDB(B0, 1, 0); PG8_LDB(B1, 1, 1); PG8_SCHED; PG8_LDA(At, 1, 0); PG8_STAGE(PG8_SA(0, 1), a2 + hstep, voffA);
;             PG8_WAIT_V(8); PG8_WAIT_L(0); PG8_BAR; PG8_MMA(0, 0, At, B0); PG8_MMA(0, 1, At, B1); PG8_BAR; PG8_SCHED;
	s_add_i32 s3, 0, 0x18000
	v_add_u32_e32 v159, s3, v153
	s_add_i32 s33, 0, 0x1c000
	ds_read_b128 v[144:147], v159
	ds_read_b128 v[148:151], v159 offset:1024
	ds_read_b128 v[160:163], v159 offset:2048
	ds_read_b128 v[168:171], v159 offset:3072
	v_add_u32_e32 v159, s33, v153
	ds_read_b128 v[172:175], v159
	ds_read_b128 v[176:179], v159 offset:1024
	ds_read_b128 v[182:185], v159 offset:2048
	ds_read_b128 v[186:189], v159 offset:3072
	s_add_u32 s14, s54, 0x40000
	s_addc_u32 s15, s55, 0
	s_mov_b32 m0, s58
	v_lshl_add_u64 v[232:233], s[14:15], 0, v[134:135]
	ds_read_b128 v[190:193], v157 offset:32768
	ds_read_b128 v[194:197], v157 offset:33792
	ds_read_b128 v[198:201], v157 offset:34816
	ds_read_b128 v[208:211], v157 offset:35840
	ds_read_b128 v[212:215], v157 offset:36864
	ds_read_b128 v[216:219], v157 offset:37888
	ds_read_b128 v[220:223], v157 offset:38912
	ds_read_b128 v[224:227], v157 offset:39936
	global_load_lds_dwordx4 v[232:233], off
	v_lshl_add_u64 v[232:233], s[14:15], 0, v[130:131]
	s_mov_b32 m0, s59
	s_nop 0
	global_load_lds_dwordx4 v[232:233], off
	s_waitcnt vmcnt(8)
	s_waitcnt lgkmcnt(0)
	s_barrier
	s_setprio 1
	s_waitcnt lgkmcnt(0)
	v_mfma_f32_16x16x32_bf16 v[124:127], v[144:147], v[190:193], v[124:127]
	v_mfma_f32_16x16x32_bf16 v[120:123], v[160:163], v[190:193], v[120:123]
	v_mfma_f32_16x16x32_bf16 v[108:111], v[144:147], v[198:201], v[108:111]
	v_mfma_f32_16x16x32_bf16 v[104:107], v[160:163], v[198:201], v[104:107]
	v_mfma_f32_16x16x32_bf16 v[92:95], v[144:147], v[212:215], v[92:95]
	v_mfma_f32_16x16x32_bf16 v[88:91], v[160:163], v[212:215], v[88:91]
	v_mfma_f32_16x16x32_bf16 v[76:79], v[144:147], v[220:223], v[76:79]
	v_mfma_f32_16x16x32_bf16 v[72:75], v[160:163], v[220:223], v[72:75]
	v_mfma_f32_16x16x32_bf16 v[124:127], v[148:151], v[194:197], v[124:127]
	v_mfma_f32_16x16x32_bf16 v[120:123], v[168:171], v[194:197], v[120:123]
	v_mfma_f32_16x16x32_bf16 v[108:111], v[148:151], v[208:211], v[108:111]
	v_mfma_f32_16x16x32_bf16 v[104:107], v[168:171], v[208:211], v[104:107]
	v_mfma_f32_16x16x32_bf16 v[92:95], v[148:151], v[216:219], v[92:95]
	v_mfma_f32_16x16x32_bf16 v[88:91], v[168:171], v[216:219], v[88:91]
	v_mfma_f32_16x16x32_bf16 v[76:79], v[148:151], v[224:227], v[76:79]
	v_mfma_f32_16x16x32_bf16 v[72:75], v[168:171], v[224:227], v[72:75]
	s_setprio 0
	s_setprio 1
	v_mfma_f32_16x16x32_bf16 v[116:119], v[172:175], v[190:193], v[116:119]
	v_mfma_f32_16x16x32_bf16 v[112:115], v[182:185], v[190:193], v[112:115]
	v_mfma_f32_16x16x32_bf16 v[100:103], v[172:175], v[198:201], v[100:103]
	v_mfma_f32_16x16x32_bf16 v[96:99], v[182:185], v[198:201], v[96:99]
	v_mfma_f32_16x16x32_bf16 v[84:87], v[172:175], v[212:215], v[84:87]
	v_mfma_f32_16x16x32_bf16 v[80:83], v[182:185], v[212:215], v[80:83]
	v_mfma_f32_16x16x32_bf16 v[68:71], v[172:175], v[220:223], v[68:71]
	v_mfma_f32_16x16x32_bf16 v[64:67], v[182:185], v[220:223], v[64:67]
	v_mfma_f32_16x16x32_bf16 v[116:119], v[176:179], v[194:197], v[116:119]
	v_mfma_f32_16x16x32_bf16 v[112:115], v[186:189], v[194:197], v[112:115]
	v_mfma_f32_16x16x32_bf16 v[100:103], v[176:179], v[208:211], v[100:103]
	v_mfma_f32_16x16x32_bf16 v[96:99], v[186:189], v[208:211], v[96:99]
	v_mfma_f32_16x16x32_bf16 v[84:87], v[176:179], v[216:219], v[84:87]
	v_mfma_f32_16x16x32_bf16 v[80:83], v[186:189], v[216:219], v[80:83]
	v_mfma_f32_16x16x32_bf16 v[68:71], v[176:179], v[224:227], v[68:71]
	v_mfma_f32_16x16x32_bf16 v[64:67], v[186:189], v[224:227], v[64:67]
	s_setprio 0
	s_barrier
; #define PG8_STAGE(bufoff, gbase, voff) do { _Pragma("unroll") for (int _i = 0; _i < 2; ++_i) \
;         __builtin_amdgcn_global_load_lds((const unsigned*)((const char*)(gbase) + (voff)[_i]), (PG8_LAS unsigned*)(lds + (bufoff) + ldsw + _i * 8192), 16, 0, 0); } while (0)
; #define PG8_LDA(dst, b, h) do { _Pragma("unroll") for (int m = 0; m < 4; ++m) _Pragma("unroll") for (int k = 0; k < 2; ++k) dst[m][k] = *(const PG8_LAS bf16x8*)(lds + PG8_SA(b, h) + aoff + m * 2048 + k * 1024); } while (0)
; #define PG8_MMA(ai, bj, At, Bt) do { __builtin_amdgcn_s_setprio(1); _Pragma("unroll") for (int m = 0; m < 4; ++m) _Pragma("unroll") for (int n = 0; n < 2; ++n) _Pragma("unroll") for (int k = 0; k < 2; ++k) \
;         acc[ai][bj][m][n] = __builtin_amdgcn_mfma_f32_16x16x32_bf16(Bt[n][k], At[m][k], acc[ai][bj][m][n], 0, 0, 0); __builtin_amdgcn_s_setprio(0); } while (0)
; #define PG8_WAIT_V(n) asm volatile("s_waitcnt vmcnt(" #n ")" ::: "memory")
; #define PG8_WAIT_L(n) asm volatile("s_waitcnt lgkmcnt(" #n ")" ::: "memory")
; #define PG8_BAR __builtin_amdgcn_s_barrier()
; #define PG8_SCHED __builtin_amdgcn_sched_barrier(0)
; __device__ __forceinline__ float row_rs(const float* ssp, int row) { const unsigned long long v = ((const unsigned long long*)ssp)[row];
;     return __builtin_amdgcn_rsqf((float)v * (1.0f / 4294967296.0f) * (1.0f / 1024.0f) + RMS_EPS); }
; template <class Epi, class Sched, bool ALIGN_EPI = false, bool SP2 = false>
; __device__ __forceinline__ void gemm_phase(PG8_LAS unsigned char* lds, const Gemm g, const Sched& S, const Epi& E) {
;     ...
;             PG8_LDA(At, 1, 1); PG8_STAGE(PG8_SB(1, 0), b3, voffB); PG8_STAGE(PG8_SB(1, 1), b3 + hstep, voffB); PG8_STAGE(PG8_SA(1, 0), a3, voffA);
;             PG8_WAIT_V(8); PG8_WAIT_L(0); PG8_BAR; PG8_MMA(1, 0, At, B0); PG8_MMA(1, 1, At, B1); PG8_BAR; PG8_SCHED;
	s_add_i32 s3, s3, s43
	v_lshl_add_u64 v[164:165], v[164:165], 0, s[10:11]
	s_mov_b32 m0, s3
	ds_read_b128 v[190:193], v157 offset:49152
	ds_read_b128 v[194:197], v157 offset:50176
	ds_read_b128 v[198:201], v157 offset:51200
	ds_read_b128 v[208:211], v157 offset:52224
	ds_read_b128 v[212:215], v157 offset:53248
	ds_read_b128 v[216:219], v157 offset:54272
	ds_read_b128 v[220:223], v157 offset:55296
	ds_read_b128 v[224:227], v157 offset:56320
	global_load_lds_dwordx4 v[164:165], off
	s_add_i32 m0, s3, 0x2000
	s_add_u32 s14, s50, 0x40080
	v_lshl_add_u64 v[164:165], v[202:203], 0, s[10:11]
	s_addc_u32 s15, s51, 0
	s_add_i32 s3, s33, s43
	global_load_lds_dwordx4 v[164:165], off
	v_lshl_add_u64 v[164:165], s[14:15], 0, v[132:133]
	s_mov_b32 m0, s3
	s_nop 0
	global_load_lds_dwordx4 v[164:165], off
	v_lshl_add_u64 v[164:165], s[14:15], 0, v[128:129]
	s_add_i32 m0, s3, 0x2000
	s_nop 0
	global_load_lds_dwordx4 v[164:165], off
	s_waitcnt vmcnt(6)
	s_waitcnt lgkmcnt(0)
	s_barrier
	s_setprio 1
	s_waitcnt lgkmcnt(0)
	v_mfma_f32_16x16x32_bf16 v[60:63], v[144:147], v[190:193], v[60:63]
	v_mfma_f32_16x16x32_bf16 v[56:59], v[160:163], v[190:193], v[56:59]
	v_mfma_f32_16x16x32_bf16 v[44:47], v[144:147], v[198:201], v[44:47]
	v_mfma_f32_16x16x32_bf16 v[40:43], v[160:163], v[198:201], v[40:43]
	v_mfma_f32_16x16x32_bf16 v[28:31], v[144:147], v[212:215], v[28:31]
	v_mfma_f32_16x16x32_bf16 v[24:27], v[160:163], v[212:215], v[24:27]
	v_mfma_f32_16x16x32_bf16 v[12:15], v[144:147], v[220:223], v[12:15]
	v_mfma_f32_16x16x32_bf16 v[8:11], v[160:163], v[220:223], v[8:11]
	v_mfma_f32_16x16x32_bf16 v[60:63], v[148:151], v[194:197], v[60:63]
	v_mfma_f32_16x16x32_bf16 v[56:59], v[168:171], v[194:197], v[56:59]
	v_mfma_f32_16x16x32_bf16 v[44:47], v[148:151], v[208:211], v[44:47]
	v_mfma_f32_16x16x32_bf16 v[40:43], v[168:171], v[208:211], v[40:43]
	v_mfma_f32_16x16x32_bf16 v[28:31], v[148:151], v[216:219], v[28:31]
	v_mfma_f32_16x16x32_bf16 v[24:27], v[168:171], v[216:219], v[24:27]
	v_lshl_add_u64 v[164:165], v[228:229], 0, s[10:11]
	s_mov_b32 m0, s61
	s_nop 0
	global_load_lds_dwordx4 v[164:165], off
	v_mfma_f32_16x16x32_bf16 v[12:15], v[148:151], v[224:227], v[12:15]
	v_mfma_f32_16x16x32_bf16 v[8:11], v[168:171], v[224:227], v[8:11]
	s_setprio 0
	s_setprio 1
	v_mfma_f32_16x16x32_bf16 v[52:55], v[172:175], v[190:193], v[52:55]
	v_mfma_f32_16x16x32_bf16 v[48:51], v[182:185], v[190:193], v[48:51]
	v_mfma_f32_16x16x32_bf16 v[36:39], v[172:175], v[198:201], v[36:39]
	v_mfma_f32_16x16x32_bf16 v[32:35], v[182:185], v[198:201], v[32:35]
	v_mfma_f32_16x16x32_bf16 v[20:23], v[172:175], v[212:215], v[20:23]
	v_mfma_f32_16x16x32_bf16 v[16:19], v[182:185], v[212:215], v[16:19]
	v_mfma_f32_16x16x32_bf16 v[4:7], v[172:175], v[220:223], v[4:7]
	v_mfma_f32_16x16x32_bf16 v[0:3], v[182:185], v[220:223], v[0:3]
	v_mfma_f32_16x16x32_bf16 v[52:55], v[176:179], v[194:197], v[52:55]
	v_mfma_f32_16x16x32_bf16 v[48:51], v[186:189], v[194:197], v[48:51]
	v_mfma_f32_16x16x32_bf16 v[36:39], v[176:179], v[208:211], v[36:39]
	v_mfma_f32_16x16x32_bf16 v[32:35], v[186:189], v[208:211], v[32:35]
	v_mfma_f32_16x16x32_bf16 v[20:23], v[176:179], v[216:219], v[20:23]
	v_mfma_f32_16x16x32_bf16 v[16:19], v[186:189], v[216:219], v[16:19]
	v_lshl_add_u64 v[164:165], v[230:231], 0, s[10:11]
	s_mov_b32 m0, s62
	s_nop 0
	global_load_lds_dwordx4 v[164:165], off
	v_mfma_f32_16x16x32_bf16 v[4:7], v[176:179], v[224:227], v[4:7]
	v_mfma_f32_16x16x32_bf16 v[0:3], v[186:189], v[224:227], v[0:3]
	s_setprio 0
	s_barrier
	s_add_i32 s89, s89, 2
	s_add_u32 s48, s48, 0x100
	s_addc_u32 s49, s49, 0
	s_add_u32 s87, s87, 0x100
	s_addc_u32 s88, s88, 0
	s_cmp_gt_u32 s89, 13
	s_cbranch_scc0 .LBB0_191
	v_lshl_add_u32 v144, s44, 8, v152
	v_ashrrev_i32_e32 v145, 31, v144
	v_lshl_add_u64 v[150:151], v[144:145], 3, s[6:7]
	global_load_dwordx2 v[182:183], v[150:151], off
	global_load_dwordx2 v[184:185], v[150:151], off offset:128
	global_load_dwordx2 v[186:187], v[150:151], off offset:256
	global_load_dwordx2 v[188:189], v[150:151], off offset:384
	global_load_dwordx2 v[190:191], v[150:151], off offset:1024
	global_load_dwordx2 v[192:193], v[150:151], off offset:1152
	global_load_dwordx2 v[194:195], v[150:151], off offset:1280
	global_load_dwordx2 v[196:197], v[150:151], off offset:1408
	s_and_b64 vcc, exec, s[16:17]
	s_cbranch_vccz .LBB0_194
	s_barrier

; #define PG8_STAGE(bufoff, gbase, voff) do { _Pragma("unroll") for (int _i = 0; _i < 2; ++_i) \
;         __builtin_amdgcn_global_load_lds((const unsigned*)((const char*)(gbase) + (voff)[_i]), (PG8_LAS unsigned*)(lds + (bufoff) + ldsw + _i * 8192), 16, 0, 0); } while (0)
; #define PG8_LDA(dst, b, h) do { _Pragma("unroll") for (int m = 0; m < 4; ++m) _Pragma("unroll") for (int k = 0; k < 2; ++k) dst[m][k] = *(const PG8_LAS bf16x8*)(lds + PG8_SA(b, h) + aoff + m * 2048 + k * 1024); } while (0)
; #define PG8_LDB(dst, b, h) do { _Pragma("unroll") for (int n = 0; n < 2; ++n) _Pragma("unroll") for (int k = 0; k < 2; ++k) dst[n][k] = *(const PG8_LAS bf16x8*)(lds + PG8_SB(b, h) + boff + n * 2048 + k * 1024); } while (0)
; #define PG8_MMA(ai, bj, At, Bt) do { __builtin_amdgcn_s_setprio(1); _Pragma("unroll") for (int m = 0; m < 4; ++m) _Pragma("unroll") for (int n = 0; n < 2; ++n) _Pragma("unroll") for (int k = 0; k < 2; ++k) \
;         acc[ai][bj][m][n] = __builtin_amdgcn_mfma_f32_16x16x32_bf16(Bt[n][k], At[m][k], acc[ai][bj][m][n], 0, 0, 0); __builtin_amdgcn_s_setprio(0); } while (0)
; #define PG8_BAR __builtin_amdgcn_s_barrier()
; template <class Epi, class Sched, bool ALIGN_EPI = false, bool SP2 = false>
; __device__ __forceinline__ void gemm_phase(PG8_LAS unsigned char* lds, const Gemm g, const Sched& S, const Epi& E) {
;     ...
;         const bool has_next = S.next(ui + 1, nxt);
;         const char* nA = has_next ? (const char*)g.A + (size_t)nxt.pm * tstep : cA; const char* nB = has_next ? (const char*)g.Bt + (size_t)nxt.pn * tstep : cB;
;         for (int t = 0; t < nt; t += 2) {
;             const bool last = (t == nt - 2);
;             const char* a1 = cA + (size_t)(t + 1) * kstep;
;             const char* a2 = last ? nA : cA + (size_t)(t + 2) * kstep; const char* b2 = last ? nB : cB + (size_t)(t + 2) * kstep;
;             const char* a3 = a2 + kstep; const char* b3 = b2 + kstep;
;             if (last && has_next) S.a_ready(nxt);
;             if constexpr (SP2) {
;             PG8_LDB(B0, 0, 0); PG8_LDB(B1, 0, 1); PG8_SCHED; PG8_LDA(At, 0, 0); PG8_STAGE(PG8_SA(1, 1), a1 + hstep, voffA);
;             PG8_WAIT_V(8); PG8_WAIT_L(0); PG8_BAR; PG8_MMA(0, 0, At, B0); PG8_MMA(0, 1, At, B1); PG8_BAR; PG8_SCHED;
;             PG8_LDA(At, 0, 1); PG8_STAGE(PG8_SB(0, 0), b2, voffB); PG8_STAGE(PG8_SB(0, 1), b2 + hstep, voffB); PG8_STAGE(PG8_SA(0, 0), a2, voffA);
.LBB0_268:
	s_add_u32 s91, s50, 0x100
	s_addc_u32 s92, s51, 0
	s_mov_b32 s93, -2
	s_waitcnt lgkmcnt(0)
	ds_read_b128 v[128:131], v165
	ds_read_b128 v[132:135], v165 offset:1024
	ds_read_b128 v[152:155], v165 offset:2048
	ds_read_b128 v[156:159], v165 offset:3072
	ds_read_b128 v[172:175], v168
	ds_read_b128 v[176:179], v168 offset:1024
	ds_read_b128 v[182:185], v168 offset:2048
	ds_read_b128 v[186:189], v168 offset:3072
	s_add_u32 s50, s10, 0x100
	s_addc_u32 s51, s11, 0
	s_cmp_eq_u32 s93, 40
	s_cselect_b32 s57, s1, s51
	s_cselect_b32 s56, s0, s50
	s_cselect_b32 s55, s49, s92
	s_cselect_b32 s54, s48, s91
	v_lshl_add_u64 v[160:161], s[10:11], 0, v[144:145]
	s_add_i32 m0, s58, 0xc000
	ds_read_b128 v[190:193], v169
	ds_read_b128 v[194:197], v169 offset:1024
	ds_read_b128 v[198:201], v169 offset:2048
	ds_read_b128 v[208:211], v169 offset:3072
	ds_read_b128 v[212:215], v169 offset:4096
	ds_read_b128 v[216:219], v169 offset:5120
	ds_read_b128 v[220:223], v169 offset:6144
	ds_read_b128 v[224:227], v169 offset:7168
	global_load_lds_dwordx4 v[160:161], off
	v_lshl_add_u64 v[160:161], s[10:11], 0, v[146:147]
	s_add_i32 m0, s58, 0xe000
	s_nop 0
	global_load_lds_dwordx4 v[160:161], off
	s_waitcnt vmcnt(8)
	s_waitcnt lgkmcnt(0)
	s_barrier
	s_setprio 1
	s_waitcnt lgkmcnt(0)
	v_mfma_f32_16x16x32_bf16 v[124:127], v[128:131], v[190:193], 0
	v_mfma_f32_16x16x32_bf16 v[120:123], v[152:155], v[190:193], 0
	v_mfma_f32_16x16x32_bf16 v[108:111], v[128:131], v[198:201], 0
	v_mfma_f32_16x16x32_bf16 v[104:107], v[152:155], v[198:201], 0
	v_mfma_f32_16x16x32_bf16 v[92:95], v[128:131], v[212:215], 0
	v_mfma_f32_16x16x32_bf16 v[88:91], v[152:155], v[212:215], 0
	v_mfma_f32_16x16x32_bf16 v[76:79], v[128:131], v[220:223], 0
	v_mfma_f32_16x16x32_bf16 v[72:75], v[152:155], v[220:223], 0
	v_mfma_f32_16x16x32_bf16 v[124:127], v[132:135], v[194:197], v[124:127]
	v_mfma_f32_16x16x32_bf16 v[120:123], v[156:159], v[194:197], v[120:123]
	v_mfma_f32_16x16x32_bf16 v[108:111], v[132:135], v[208:211], v[108:111]
	v_mfma_f32_16x16x32_bf16 v[104:107], v[156:159], v[208:211], v[104:107]
	v_mfma_f32_16x16x32_bf16 v[92:95], v[132:135], v[216:219], v[92:95]
	v_mfma_f32_16x16x32_bf16 v[88:91], v[156:159], v[216:219], v[88:91]
	v_mfma_f32_16x16x32_bf16 v[76:79], v[132:135], v[224:227], v[76:79]
	v_mfma_f32_16x16x32_bf16 v[72:75], v[156:159], v[224:227], v[72:75]
	s_setprio 0
	s_setprio 1
	v_mfma_f32_16x16x32_bf16 v[116:119], v[172:175], v[190:193], 0
	v_mfma_f32_16x16x32_bf16 v[112:115], v[182:185], v[190:193], 0
	v_mfma_f32_16x16x32_bf16 v[100:103], v[172:175], v[198:201], 0
	v_mfma_f32_16x16x32_bf16 v[96:99], v[182:185], v[198:201], 0
	v_mfma_f32_16x16x32_bf16 v[84:87], v[172:175], v[212:215], 0
	v_mfma_f32_16x16x32_bf16 v[80:83], v[182:185], v[212:215], 0
	v_mfma_f32_16x16x32_bf16 v[68:71], v[172:175], v[220:223], 0
	v_mfma_f32_16x16x32_bf16 v[64:67], v[182:185], v[220:223], 0
	v_mfma_f32_16x16x32_bf16 v[116:119], v[176:179], v[194:197], v[116:119]
	v_mfma_f32_16x16x32_bf16 v[112:115], v[186:189], v[194:197], v[112:115]
	v_mfma_f32_16x16x32_bf16 v[100:103], v[176:179], v[208:211], v[100:103]
	v_mfma_f32_16x16x32_bf16 v[96:99], v[186:189], v[208:211], v[96:99]
	v_mfma_f32_16x16x32_bf16 v[84:87], v[176:179], v[216:219], v[84:87]
	v_mfma_f32_16x16x32_bf16 v[80:83], v[186:189], v[216:219], v[80:83]
	v_mfma_f32_16x16x32_bf16 v[68:71], v[176:179], v[224:227], v[68:71]
	v_mfma_f32_16x16x32_bf16 v[64:67], v[186:189], v[224:227], v[64:67]
	s_setprio 0
	s_barrier
	s_add_i32 s3, s65, s43
	v_lshl_add_u64 v[160:161], s[54:55], 0, v[138:139]
	s_mov_b32 m0, s3
	ds_read_b128 v[190:193], v169 offset:16384
	ds_read_b128 v[194:197], v169 offset:17408
	ds_read_b128 v[198:201], v169 offset:18432
	ds_read_b128 v[208:211], v169 offset:19456
	ds_read_b128 v[212:215], v169 offset:20480
	ds_read_b128 v[216:219], v169 offset:21504
	ds_read_b128 v[220:223], v169 offset:22528
	ds_read_b128 v[224:227], v169 offset:23552
	global_load_lds_dwordx4 v[160:161], off
	s_add_i32 m0, s3, 0x2000
	s_add_u32 s10, s54, 0xb0000
	v_lshl_add_u64 v[202:203], s[54:55], 0, v[142:143]
	s_addc_u32 s11, s55, 0
	s_add_i32 s3, s66, s43
	global_load_lds_dwordx4 v[202:203], off
	v_lshl_add_u64 v[228:229], s[10:11], 0, v[138:139]
	s_mov_b32 m0, s3
	global_load_lds_dwordx4 v[228:229], off
	v_lshl_add_u64 v[228:229], s[10:11], 0, v[142:143]
	s_add_i32 m0, s3, 0x2000
	s_nop 0
	global_load_lds_dwordx4 v[228:229], off
	s_waitcnt vmcnt(6)
	s_waitcnt lgkmcnt(0)
	s_barrier
; #define PG8_STAGE(bufoff, gbase, voff) do { _Pragma("unroll") for (int _i = 0; _i < 2; ++_i) \
;         __builtin_amdgcn_global_load_lds((const unsigned*)((const char*)(gbase) + (voff)[_i]), (PG8_LAS unsigned*)(lds + (bufoff) + ldsw + _i * 8192), 16, 0, 0); } while (0)
; #define PG8_LDA(dst, b, h) do { _Pragma("unroll") for (int m = 0; m < 4; ++m) _Pragma("unroll") for (int k = 0; k < 2; ++k) dst[m][k] = *(const PG8_LAS bf16x8*)(lds + PG8_SA(b, h) + aoff + m * 2048 + k * 1024); } while (0)
; #define PG8_LDB(dst, b, h) do { _Pragma("unroll") for (int n = 0; n < 2; ++n) _Pragma("unroll") for (int k = 0; k < 2; ++k) dst[n][k] = *(const PG8_LAS bf16x8*)(lds + PG8_SB(b, h) + boff + n * 2048 + k * 1024); } while (0)
; #define PG8_MMA(ai, bj, At, Bt) do { __builtin_amdgcn_s_setprio(1); _Pragma("unroll") for (int m = 0; m < 4; ++m) _Pragma("unroll") for (int n = 0; n < 2; ++n) _Pragma("unroll") for (int k = 0; k < 2; ++k) \
;         acc[ai][bj][m][n] = __builtin_amdgcn_mfma_f32_16x16x32_bf16(Bt[n][k], At[m][k], acc[ai][bj][m][n], 0, 0, 0); __builtin_amdgcn_s_setprio(0); } while (0)
; #define PG8_WAIT_V(n) asm volatile("s_waitcnt vmcnt(" #n ")" ::: "memory")
; #define PG8_WAIT_L(n) asm volatile("s_waitcnt lgkmcnt(" #n ")" ::: "memory")
; #define PG8_BAR __builtin_amdgcn_s_barrier()
; #define PG8_SCHED __builtin_amdgcn_sched_barrier(0)
; template <class Epi, class Sched, bool ALIGN_EPI = false, bool SP2 = false>
; __device__ __forceinline__ void gemm_phase(PG8_LAS unsigned char* lds, const Gemm g, const Sched& S, const Epi& E) {
;     ...
;             PG8_LDA(At, 0, 1); PG8_STAGE(PG8_SB(0, 0), b2, voffB); PG8_STAGE(PG8_SB(0, 1), b2 + hstep, voffB); PG8_STAGE(PG8_SA(0, 0), a2, voffA);
;             PG8_WAIT_V(8); PG8_WAIT_L(0); PG8_BAR; PG8_MMA(1, 0, At, B0); PG8_MMA(1, 1, At, B1); PG8_BAR; PG8_SCHED;
;             PG8_LDB(B0, 1, 0); PG8_LDB(B1, 1, 1); PG8_SCHED; PG8_LDA(At, 1, 0); PG8_STAGE(PG8_SA(0, 1), a2 + hstep, voffA);
;             PG8_WAIT_V(8); PG8_WAIT_L(0); PG8_BAR; PG8_MMA(0, 0, At, B0); PG8_MMA(0, 1, At, B1); PG8_BAR; PG8_SCHED;
	s_setprio 1
	s_waitcnt lgkmcnt(0)
	v_mfma_f32_16x16x32_bf16 v[60:63], v[128:131], v[190:193], 0
	v_mfma_f32_16x16x32_bf16 v[56:59], v[152:155], v[190:193], 0
	v_mfma_f32_16x16x32_bf16 v[44:47], v[128:131], v[198:201], 0
	v_mfma_f32_16x16x32_bf16 v[40:43], v[152:155], v[198:201], 0
	v_mfma_f32_16x16x32_bf16 v[28:31], v[128:131], v[212:215], 0
	v_mfma_f32_16x16x32_bf16 v[24:27], v[152:155], v[212:215], 0
	v_mfma_f32_16x16x32_bf16 v[12:15], v[128:131], v[220:223], 0
	v_mfma_f32_16x16x32_bf16 v[8:11], v[152:155], v[220:223], 0
	v_mfma_f32_16x16x32_bf16 v[60:63], v[132:135], v[194:197], v[60:63]
	v_mfma_f32_16x16x32_bf16 v[56:59], v[156:159], v[194:197], v[56:59]
	v_mfma_f32_16x16x32_bf16 v[44:47], v[132:135], v[208:211], v[44:47]
	v_mfma_f32_16x16x32_bf16 v[40:43], v[156:159], v[208:211], v[40:43]
	v_mfma_f32_16x16x32_bf16 v[28:31], v[132:135], v[216:219], v[28:31]
	v_mfma_f32_16x16x32_bf16 v[24:27], v[156:159], v[216:219], v[24:27]
	v_lshl_add_u64 v[228:229], s[56:57], 0, v[136:137]
	s_mov_b32 m0, s58
	s_nop 0
	global_load_lds_dwordx4 v[228:229], off
	v_mfma_f32_16x16x32_bf16 v[12:15], v[132:135], v[224:227], v[12:15]
	v_mfma_f32_16x16x32_bf16 v[8:11], v[156:159], v[224:227], v[8:11]
	s_setprio 0
	s_setprio 1
	v_mfma_f32_16x16x32_bf16 v[52:55], v[172:175], v[190:193], 0
	v_mfma_f32_16x16x32_bf16 v[48:51], v[182:185], v[190:193], 0
	v_mfma_f32_16x16x32_bf16 v[36:39], v[172:175], v[198:201], 0
	v_mfma_f32_16x16x32_bf16 v[32:35], v[182:185], v[198:201], 0
	v_mfma_f32_16x16x32_bf16 v[20:23], v[172:175], v[212:215], 0
	v_mfma_f32_16x16x32_bf16 v[16:19], v[182:185], v[212:215], 0
	v_mfma_f32_16x16x32_bf16 v[4:7], v[172:175], v[220:223], 0
	v_mfma_f32_16x16x32_bf16 v[0:3], v[182:185], v[220:223], 0
	v_mfma_f32_16x16x32_bf16 v[52:55], v[176:179], v[194:197], v[52:55]
	v_mfma_f32_16x16x32_bf16 v[48:51], v[186:189], v[194:197], v[48:51]
	v_mfma_f32_16x16x32_bf16 v[36:39], v[176:179], v[208:211], v[36:39]
	v_mfma_f32_16x16x32_bf16 v[32:35], v[186:189], v[208:211], v[32:35]
	v_mfma_f32_16x16x32_bf16 v[20:23], v[176:179], v[216:219], v[20:23]
	v_mfma_f32_16x16x32_bf16 v[16:19], v[186:189], v[216:219], v[16:19]
	v_lshl_add_u64 v[230:231], s[56:57], 0, v[140:141]
	s_mov_b32 m0, s59
	s_nop 0
	global_load_lds_dwordx4 v[230:231], off
	v_mfma_f32_16x16x32_bf16 v[4:7], v[176:179], v[224:227], v[4:7]
	v_mfma_f32_16x16x32_bf16 v[0:3], v[186:189], v[224:227], v[0:3]
	s_setprio 0
	s_barrier
	s_add_i32 s3, 0, 0x18000
	s_add_i32 s14, 0, 0x1c000
	v_add_u32_e32 v156, s3, v163
	v_add_u32_e32 v171, s14, v163
	ds_read_b128 v[128:131], v156
	ds_read_b128 v[132:135], v156 offset:1024
	ds_read_b128 v[152:155], v156 offset:2048
	ds_read_b128 v[156:159], v156 offset:3072
	ds_read_b128 v[172:175], v171
	ds_read_b128 v[176:179], v171 offset:1024
	ds_read_b128 v[182:185], v171 offset:2048
	ds_read_b128 v[186:189], v171 offset:3072
	s_add_u32 s10, s56, 0xb0000
	s_addc_u32 s11, s57, 0
	s_mov_b32 m0, s60
	v_lshl_add_u64 v[232:233], s[10:11], 0, v[136:137]
	ds_read_b128 v[190:193], v169 offset:32768
	ds_read_b128 v[194:197], v169 offset:33792
	ds_read_b128 v[198:201], v169 offset:34816
	ds_read_b128 v[208:211], v169 offset:35840
	ds_read_b128 v[212:215], v169 offset:36864
	ds_read_b128 v[216:219], v169 offset:37888
	ds_read_b128 v[220:223], v169 offset:38912
	ds_read_b128 v[224:227], v169 offset:39936
	global_load_lds_dwordx4 v[232:233], off
	v_lshl_add_u64 v[232:233], s[10:11], 0, v[140:141]
	s_mov_b32 m0, s61
	s_nop 0
	global_load_lds_dwordx4 v[232:233], off
	s_waitcnt vmcnt(8)
	s_waitcnt lgkmcnt(0)
	s_barrier
	s_setprio 1
	s_waitcnt lgkmcnt(0)
	v_mfma_f32_16x16x32_bf16 v[124:127], v[128:131], v[190:193], v[124:127]
	v_mfma_f32_16x16x32_bf16 v[120:123], v[152:155], v[190:193], v[120:123]
	v_mfma_f32_16x16x32_bf16 v[108:111], v[128:131], v[198:201], v[108:111]
	v_mfma_f32_16x16x32_bf16 v[104:107], v[152:155], v[198:201], v[104:107]
	v_mfma_f32_16x16x32_bf16 v[92:95], v[128:131], v[212:215], v[92:95]
	v_mfma_f32_16x16x32_bf16 v[88:91], v[152:155], v[212:215], v[88:91]
	v_mfma_f32_16x16x32_bf16 v[76:79], v[128:131], v[220:223], v[76:79]
	v_mfma_f32_16x16x32_bf16 v[72:75], v[152:155], v[220:223], v[72:75]
	v_mfma_f32_16x16x32_bf16 v[124:127], v[132:135], v[194:197], v[124:127]
	v_mfma_f32_16x16x32_bf16 v[120:123], v[156:159], v[194:197], v[120:123]
	v_mfma_f32_16x16x32_bf16 v[108:111], v[132:135], v[208:211], v[108:111]
	v_mfma_f32_16x16x32_bf16 v[104:107], v[156:159], v[208:211], v[104:107]
	v_mfma_f32_16x16x32_bf16 v[92:95], v[132:135], v[216:219], v[92:95]
	v_mfma_f32_16x16x32_bf16 v[88:91], v[156:159], v[216:219], v[88:91]
	v_mfma_f32_16x16x32_bf16 v[76:79], v[132:135], v[224:227], v[76:79]
	v_mfma_f32_16x16x32_bf16 v[72:75], v[156:159], v[224:227], v[72:75]
	s_setprio 0
	s_setprio 1
	v_mfma_f32_16x16x32_bf16 v[116:119], v[172:175], v[190:193], v[116:119]
	v_mfma_f32_16x16x32_bf16 v[112:115], v[182:185], v[190:193], v[112:115]
	v_mfma_f32_16x16x32_bf16 v[100:103], v[172:175], v[198:201], v[100:103]
	v_mfma_f32_16x16x32_bf16 v[96:99], v[182:185], v[198:201], v[96:99]
	v_mfma_f32_16x16x32_bf16 v[84:87], v[172:175], v[212:215], v[84:87]
	v_mfma_f32_16x16x32_bf16 v[80:83], v[182:185], v[212:215], v[80:83]
	v_mfma_f32_16x16x32_bf16 v[68:71], v[172:175], v[220:223], v[68:71]
	v_mfma_f32_16x16x32_bf16 v[64:67], v[182:185], v[220:223], v[64:67]
	v_mfma_f32_16x16x32_bf16 v[116:119], v[176:179], v[194:197], v[116:119]
	v_mfma_f32_16x16x32_bf16 v[112:115], v[186:189], v[194:197], v[112:115]
	v_mfma_f32_16x16x32_bf16 v[100:103], v[176:179], v[208:211], v[100:103]
	v_mfma_f32_16x16x32_bf16 v[96:99], v[186:189], v[208:211], v[96:99]
	v_mfma_f32_16x16x32_bf16 v[84:87], v[176:179], v[216:219], v[84:87]
	v_mfma_f32_16x16x32_bf16 v[80:83], v[186:189], v[216:219], v[80:83]
	v_mfma_f32_16x16x32_bf16 v[68:71], v[176:179], v[224:227], v[68:71]
	v_mfma_f32_16x16x32_bf16 v[64:67], v[186:189], v[224:227], v[64:67]
	s_setprio 0
	s_barrier
; #define PG8_STAGE(bufoff, gbase, voff) do { _Pragma("unroll") for (int _i = 0; _i < 2; ++_i) \
;         __builtin_amdgcn_global_load_lds((const unsigned*)((const char*)(gbase) + (voff)[_i]), (PG8_LAS unsigned*)(lds + (bufoff) + ldsw + _i * 8192), 16, 0, 0); } while (0)
; #define PG8_LDA(dst, b, h) do { _Pragma("unroll") for (int m = 0; m < 4; ++m) _Pragma("unroll") for (int k = 0; k < 2; ++k) dst[m][k] = *(const PG8_LAS bf16x8*)(lds + PG8_SA(b, h) + aoff + m * 2048 + k * 1024); } while (0)
; #define PG8_LDB(dst, b, h) do { _Pragma("unroll") for (int n = 0; n < 2; ++n) _Pragma("unroll") for (int k = 0; k < 2; ++k) dst[n][k] = *(const PG8_LAS bf16x8*)(lds + PG8_SB(b, h) + boff + n * 2048 + k * 1024); } while (0)
; template <class Epi, class Sched, bool ALIGN_EPI = false, bool SP2 = false>
; __device__ __forceinline__ void gemm_phase(PG8_LAS unsigned char* lds, const Gemm g, const Sched& S, const Epi& E) {
;     ...
;         for (int t = 0; t < nt; t += 2) {
;             const bool last = (t == nt - 2);
;             const char* a1 = cA + (size_t)(t + 1) * kstep;
;             const char* a2 = last ? nA : cA + (size_t)(t + 2) * kstep; const char* b2 = last ? nB : cB + (size_t)(t + 2) * kstep;
;             const char* a3 = a2 + kstep; const char* b3 = b2 + kstep;
;             if (last && has_next) S.a_ready(nxt);
;             if constexpr (SP2) {
;             PG8_LDB(B0, 0, 0); PG8_LDB(B1, 0, 1); PG8_SCHED; PG8_LDA(At, 0, 0); PG8_STAGE(PG8_SA(1, 1), a1 + hstep, voffA);
;             PG8_WAIT_V(8); PG8_WAIT_L(0); PG8_BAR; PG8_MMA(0, 0, At, B0); PG8_MMA(0, 1, At, B1); PG8_BAR; PG8_SCHED;
;             PG8_LDA(At, 0, 1); PG8_STAGE(PG8_SB(0, 0), b2, voffB); PG8_STAGE(PG8_SB(0, 1), b2 + hstep, voffB); PG8_STAGE(PG8_SA(0, 0), a2, voffA);
;             PG8_WAIT_V(8); PG8_WAIT_L(0); PG8_BAR; PG8_MMA(1, 0, At, B0); PG8_MMA(1, 1, At, B1); PG8_BAR; PG8_SCHED;
;             PG8_LDB(B0, 1, 0); PG8_LDB(B1, 1, 1); PG8_SCHED; PG8_LDA(At, 1, 0); PG8_STAGE(PG8_SA(0, 1), a2 + hstep, voffA);
;             PG8_WAIT_V(8); PG8_WAIT_L(0); PG8_BAR; PG8_MMA(0, 0, At, B0); PG8_MMA(0, 1, At, B1); PG8_BAR; PG8_SCHED;
;             PG8_LDA(At, 1, 1); PG8_STAGE(PG8_SB(1, 0), b3, voffB); PG8_STAGE(PG8_SB(1, 1), b3 + hstep, voffB); PG8_STAGE(PG8_SA(1, 0), a3, voffA);
;             PG8_WAIT_V(8); PG8_WAIT_L(0); PG8_BAR; PG8_MMA(1, 0, At, B0); PG8_MMA(1, 1, At, B1); PG8_BAR; PG8_SCHED;
	s_add_i32 s3, s3, s43
	v_lshl_add_u64 v[160:161], v[160:161], 0, s[40:41]
	s_mov_b32 m0, s3
	ds_read_b128 v[190:193], v169 offset:49152
	ds_read_b128 v[194:197], v169 offset:50176
	ds_read_b128 v[198:201], v169 offset:51200
	ds_read_b128 v[208:211], v169 offset:52224
	ds_read_b128 v[212:215], v169 offset:53248
	ds_read_b128 v[216:219], v169 offset:54272
	ds_read_b128 v[220:223], v169 offset:55296
	ds_read_b128 v[224:227], v169 offset:56320
	global_load_lds_dwordx4 v[160:161], off
	s_add_i32 m0, s3, 0x2000
	s_add_u32 s10, s54, 0xb0080
	v_lshl_add_u64 v[160:161], v[202:203], 0, s[40:41]
	s_addc_u32 s11, s55, 0
	s_add_i32 s3, s14, s43
	global_load_lds_dwordx4 v[160:161], off
	v_lshl_add_u64 v[160:161], s[10:11], 0, v[138:139]
	s_mov_b32 m0, s3
	s_nop 0
	global_load_lds_dwordx4 v[160:161], off
	v_lshl_add_u64 v[160:161], s[10:11], 0, v[142:143]
	s_add_i32 m0, s3, 0x2000
	s_nop 0
	global_load_lds_dwordx4 v[160:161], off
	s_waitcnt vmcnt(6)
	s_waitcnt lgkmcnt(0)
	s_barrier
	s_setprio 1
	s_waitcnt lgkmcnt(0)
	v_mfma_f32_16x16x32_bf16 v[60:63], v[128:131], v[190:193], v[60:63]
	v_mfma_f32_16x16x32_bf16 v[56:59], v[152:155], v[190:193], v[56:59]
	v_mfma_f32_16x16x32_bf16 v[44:47], v[128:131], v[198:201], v[44:47]
	v_mfma_f32_16x16x32_bf16 v[40:43], v[152:155], v[198:201], v[40:43]
	v_mfma_f32_16x16x32_bf16 v[28:31], v[128:131], v[212:215], v[28:31]
	v_mfma_f32_16x16x32_bf16 v[24:27], v[152:155], v[212:215], v[24:27]
	v_mfma_f32_16x16x32_bf16 v[12:15], v[128:131], v[220:223], v[12:15]
	v_mfma_f32_16x16x32_bf16 v[8:11], v[152:155], v[220:223], v[8:11]
	v_mfma_f32_16x16x32_bf16 v[60:63], v[132:135], v[194:197], v[60:63]
	v_mfma_f32_16x16x32_bf16 v[56:59], v[156:159], v[194:197], v[56:59]
	v_mfma_f32_16x16x32_bf16 v[44:47], v[132:135], v[208:211], v[44:47]
	v_mfma_f32_16x16x32_bf16 v[40:43], v[156:159], v[208:211], v[40:43]
	v_mfma_f32_16x16x32_bf16 v[28:31], v[132:135], v[216:219], v[28:31]
	v_mfma_f32_16x16x32_bf16 v[24:27], v[156:159], v[216:219], v[24:27]
	v_lshl_add_u64 v[160:161], v[228:229], 0, s[40:41]
	s_mov_b32 m0, s63
	s_nop 0
	global_load_lds_dwordx4 v[160:161], off
	v_mfma_f32_16x16x32_bf16 v[12:15], v[132:135], v[224:227], v[12:15]
	v_mfma_f32_16x16x32_bf16 v[8:11], v[156:159], v[224:227], v[8:11]
	s_setprio 0
	s_setprio 1
	v_mfma_f32_16x16x32_bf16 v[52:55], v[172:175], v[190:193], v[52:55]
	v_mfma_f32_16x16x32_bf16 v[48:51], v[182:185], v[190:193], v[48:51]
	v_mfma_f32_16x16x32_bf16 v[36:39], v[172:175], v[198:201], v[36:39]
	v_mfma_f32_16x16x32_bf16 v[32:35], v[182:185], v[198:201], v[32:35]
	v_mfma_f32_16x16x32_bf16 v[20:23], v[172:175], v[212:215], v[20:23]
	v_mfma_f32_16x16x32_bf16 v[16:19], v[182:185], v[212:215], v[16:19]
	v_mfma_f32_16x16x32_bf16 v[4:7], v[172:175], v[220:223], v[4:7]
	v_mfma_f32_16x16x32_bf16 v[0:3], v[182:185], v[220:223], v[0:3]
	v_mfma_f32_16x16x32_bf16 v[52:55], v[176:179], v[194:197], v[52:55]
	v_mfma_f32_16x16x32_bf16 v[48:51], v[186:189], v[194:197], v[48:51]
	v_mfma_f32_16x16x32_bf16 v[36:39], v[176:179], v[208:211], v[36:39]
	v_mfma_f32_16x16x32_bf16 v[32:35], v[186:189], v[208:211], v[32:35]
	v_mfma_f32_16x16x32_bf16 v[20:23], v[176:179], v[216:219], v[20:23]
	v_mfma_f32_16x16x32_bf16 v[16:19], v[186:189], v[216:219], v[16:19]
	v_lshl_add_u64 v[160:161], v[230:231], 0, s[40:41]
	s_mov_b32 m0, s64
	s_nop 0
	global_load_lds_dwordx4 v[160:161], off
	v_mfma_f32_16x16x32_bf16 v[4:7], v[176:179], v[224:227], v[4:7]
	v_mfma_f32_16x16x32_bf16 v[0:3], v[186:189], v[224:227], v[0:3]
	s_setprio 0
	s_barrier
	s_add_i32 s93, s93, 2
	s_add_u32 s91, s91, 0x100
	s_addc_u32 s92, s92, 0
	s_mov_b64 s[10:11], s[50:51]
.LBB0_269:
	ds_read_b128 v[128:131], v165
	ds_read_b128 v[132:135], v165 offset:1024
	ds_read_b128 v[152:155], v165 offset:2048
	ds_read_b128 v[156:159], v165 offset:3072
	ds_read_b128 v[172:175], v168
	ds_read_b128 v[176:179], v168 offset:1024
	ds_read_b128 v[182:185], v168 offset:2048
	ds_read_b128 v[186:189], v168 offset:3072
	s_add_u32 s50, s10, 0x100
	s_addc_u32 s51, s11, 0
	s_cmp_eq_u32 s93, 40
	s_cselect_b32 s57, s1, s51
	s_cselect_b32 s56, s0, s50
	s_cselect_b32 s55, s49, s92
	s_cselect_b32 s54, s48, s91
	v_lshl_add_u64 v[160:161], s[10:11], 0, v[144:145]
	s_add_i32 m0, s58, 0xc000
	ds_read_b128 v[190:193], v169
	ds_read_b128 v[194:197], v169 offset:1024
	ds_read_b128 v[198:201], v169 offset:2048
	ds_read_b128 v[208:211], v169 offset:3072
	ds_read_b128 v[212:215], v169 offset:4096
	ds_read_b128 v[216:219], v169 offset:5120
	ds_read_b128 v[220:223], v169 offset:6144
	ds_read_b128 v[224:227], v169 offset:7168
	global_load_lds_dwordx4 v[160:161], off
	v_lshl_add_u64 v[160:161], s[10:11], 0, v[146:147]
	s_add_i32 m0, s58, 0xe000
	s_nop 0
	global_load_lds_dwordx4 v[160:161], off
	s_waitcnt vmcnt(8)
	s_waitcnt lgkmcnt(0)
	s_barrier
; #define PG8_STAGE(bufoff, gbase, voff) do { _Pragma("unroll") for (int _i = 0; _i < 2; ++_i) \
;         __builtin_amdgcn_global_load_lds((const unsigned*)((const char*)(gbase) + (voff)[_i]), (PG8_LAS unsigned*)(lds + (bufoff) + ldsw + _i * 8192), 16, 0, 0); } while (0)
; #define PG8_LDA(dst, b, h) do { _Pragma("unroll") for (int m = 0; m < 4; ++m) _Pragma("unroll") for (int k = 0; k < 2; ++k) dst[m][k] = *(const PG8_LAS bf16x8*)(lds + PG8_SA(b, h) + aoff + m * 2048 + k * 1024); } while (0)
; #define PG8_LDB(dst, b, h) do { _Pragma("unroll") for (int n = 0; n < 2; ++n) _Pragma("unroll") for (int k = 0; k < 2; ++k) dst[n][k] = *(const PG8_LAS bf16x8*)(lds + PG8_SB(b, h) + boff + n * 2048 + k * 1024); } while (0)
; #define PG8_MMA(ai, bj, At, Bt) do { __builtin_amdgcn_s_setprio(1); _Pragma("unroll") for (int m = 0; m < 4; ++m) _Pragma("unroll") for (int n = 0; n < 2; ++n) _Pragma("unroll") for (int k = 0; k < 2; ++k) \
;         acc[ai][bj][m][n] = __builtin_amdgcn_mfma_f32_16x16x32_bf16(Bt[n][k], At[m][k], acc[ai][bj][m][n], 0, 0, 0); __builtin_amdgcn_s_setprio(0); } while (0)
; #define PG8_WAIT_V(n) asm volatile("s_waitcnt vmcnt(" #n ")" ::: "memory")
; #define PG8_WAIT_L(n) asm volatile("s_waitcnt lgkmcnt(" #n ")" ::: "memory")
; #define PG8_BAR __builtin_amdgcn_s_barrier()
; #define PG8_SCHED __builtin_amdgcn_sched_barrier(0)
; template <class Epi, class Sched, bool ALIGN_EPI = false, bool SP2 = false>
; __device__ __forceinline__ void gemm_phase(PG8_LAS unsigned char* lds, const Gemm g, const Sched& S, const Epi& E) {
;     ...
;             PG8_LDB(B0, 0, 0); PG8_LDB(B1, 0, 1); PG8_SCHED; PG8_LDA(At, 0, 0); PG8_STAGE(PG8_SA(1, 1), a1 + hstep, voffA);
;             PG8_WAIT_V(8); PG8_WAIT_L(0); PG8_BAR; PG8_MMA(0, 0, At, B0); PG8_MMA(0, 1, At, B1); PG8_BAR; PG8_SCHED;
;             PG8_LDA(At, 0, 1); PG8_STAGE(PG8_SB(0, 0), b2, voffB); PG8_STAGE(PG8_SB(0, 1), b2 + hstep, voffB); PG8_STAGE(PG8_SA(0, 0), a2, voffA);
;             PG8_WAIT_V(8); PG8_WAIT_L(0); PG8_BAR; PG8_MMA(1, 0, At, B0); PG8_MMA(1, 1, At, B1); PG8_BAR; PG8_SCHED;
	s_setprio 1
	s_waitcnt lgkmcnt(0)
	v_mfma_f32_16x16x32_bf16 v[124:127], v[128:131], v[190:193], v[124:127]
	v_mfma_f32_16x16x32_bf16 v[120:123], v[152:155], v[190:193], v[120:123]
	v_mfma_f32_16x16x32_bf16 v[108:111], v[128:131], v[198:201], v[108:111]
	v_mfma_f32_16x16x32_bf16 v[104:107], v[152:155], v[198:201], v[104:107]
	v_mfma_f32_16x16x32_bf16 v[92:95], v[128:131], v[212:215], v[92:95]
	v_mfma_f32_16x16x32_bf16 v[88:91], v[152:155], v[212:215], v[88:91]
	v_mfma_f32_16x16x32_bf16 v[76:79], v[128:131], v[220:223], v[76:79]
	v_mfma_f32_16x16x32_bf16 v[72:75], v[152:155], v[220:223], v[72:75]
	v_mfma_f32_16x16x32_bf16 v[124:127], v[132:135], v[194:197], v[124:127]
	v_mfma_f32_16x16x32_bf16 v[120:123], v[156:159], v[194:197], v[120:123]
	v_mfma_f32_16x16x32_bf16 v[108:111], v[132:135], v[208:211], v[108:111]
	v_mfma_f32_16x16x32_bf16 v[104:107], v[156:159], v[208:211], v[104:107]
	v_mfma_f32_16x16x32_bf16 v[92:95], v[132:135], v[216:219], v[92:95]
	v_mfma_f32_16x16x32_bf16 v[88:91], v[156:159], v[216:219], v[88:91]
	v_mfma_f32_16x16x32_bf16 v[76:79], v[132:135], v[224:227], v[76:79]
	v_mfma_f32_16x16x32_bf16 v[72:75], v[156:159], v[224:227], v[72:75]
	s_setprio 0
	s_setprio 1
	v_mfma_f32_16x16x32_bf16 v[116:119], v[172:175], v[190:193], v[116:119]
	v_mfma_f32_16x16x32_bf16 v[112:115], v[182:185], v[190:193], v[112:115]
	v_mfma_f32_16x16x32_bf16 v[100:103], v[172:175], v[198:201], v[100:103]
	v_mfma_f32_16x16x32_bf16 v[96:99], v[182:185], v[198:201], v[96:99]
	v_mfma_f32_16x16x32_bf16 v[84:87], v[172:175], v[212:215], v[84:87]
	v_mfma_f32_16x16x32_bf16 v[80:83], v[182:185], v[212:215], v[80:83]
	v_mfma_f32_16x16x32_bf16 v[68:71], v[172:175], v[220:223], v[68:71]
	v_mfma_f32_16x16x32_bf16 v[64:67], v[182:185], v[220:223], v[64:67]
	v_mfma_f32_16x16x32_bf16 v[116:119], v[176:179], v[194:197], v[116:119]
	v_mfma_f32_16x16x32_bf16 v[112:115], v[186:189], v[194:197], v[112:115]
	v_mfma_f32_16x16x32_bf16 v[100:103], v[176:179], v[208:211], v[100:103]
	v_mfma_f32_16x16x32_bf16 v[96:99], v[186:189], v[208:211], v[96:99]
	v_mfma_f32_16x16x32_bf16 v[84:87], v[176:179], v[216:219], v[84:87]
	v_mfma_f32_16x16x32_bf16 v[80:83], v[186:189], v[216:219], v[80:83]
	v_mfma_f32_16x16x32_bf16 v[68:71], v[176:179], v[224:227], v[68:71]
	v_mfma_f32_16x16x32_bf16 v[64:67], v[186:189], v[224:227], v[64:67]
	s_setprio 0
	s_barrier
	s_add_i32 s3, s65, s43
	v_lshl_add_u64 v[160:161], s[54:55], 0, v[138:139]
	s_mov_b32 m0, s3
	ds_read_b128 v[190:193], v169 offset:16384
	ds_read_b128 v[194:197], v169 offset:17408
	ds_read_b128 v[198:201], v169 offset:18432
	ds_read_b128 v[208:211], v169 offset:19456
	ds_read_b128 v[212:215], v169 offset:20480
	ds_read_b128 v[216:219], v169 offset:21504
	ds_read_b128 v[220:223], v169 offset:22528
	ds_read_b128 v[224:227], v169 offset:23552
	global_load_lds_dwordx4 v[160:161], off
	s_add_i32 m0, s3, 0x2000
	s_add_u32 s10, s54, 0xb0000
	v_lshl_add_u64 v[202:203], s[54:55], 0, v[142:143]
	s_addc_u32 s11, s55, 0
	s_add_i32 s3, s66, s43
	global_load_lds_dwordx4 v[202:203], off
	v_lshl_add_u64 v[228:229], s[10:11], 0, v[138:139]
	s_mov_b32 m0, s3
	global_load_lds_dwordx4 v[228:229], off
	v_lshl_add_u64 v[228:229], s[10:11], 0, v[142:143]
	s_add_i32 m0, s3, 0x2000
	s_nop 0
	global_load_lds_dwordx4 v[228:229], off
	s_waitcnt vmcnt(6)
	s_waitcnt lgkmcnt(0)
	s_barrier
	s_setprio 1
	s_waitcnt lgkmcnt(0)
	v_mfma_f32_16x16x32_bf16 v[60:63], v[128:131], v[190:193], v[60:63]
	v_mfma_f32_16x16x32_bf16 v[56:59], v[152:155], v[190:193], v[56:59]
	v_mfma_f32_16x16x32_bf16 v[44:47], v[128:131], v[198:201], v[44:47]
	v_mfma_f32_16x16x32_bf16 v[40:43], v[152:155], v[198:201], v[40:43]
	v_mfma_f32_16x16x32_bf16 v[28:31], v[128:131], v[212:215], v[28:31]
	v_mfma_f32_16x16x32_bf16 v[24:27], v[152:155], v[212:215], v[24:27]
	v_mfma_f32_16x16x32_bf16 v[12:15], v[128:131], v[220:223], v[12:15]
	v_mfma_f32_16x16x32_bf16 v[8:11], v[152:155], v[220:223], v[8:11]
	v_mfma_f32_16x16x32_bf16 v[60:63], v[132:135], v[194:197], v[60:63]
	v_mfma_f32_16x16x32_bf16 v[56:59], v[156:159], v[194:197], v[56:59]
	v_mfma_f32_16x16x32_bf16 v[44:47], v[132:135], v[208:211], v[44:47]
	v_mfma_f32_16x16x32_bf16 v[40:43], v[156:159], v[208:211], v[40:43]
	v_mfma_f32_16x16x32_bf16 v[28:31], v[132:135], v[216:219], v[28:31]
	v_mfma_f32_16x16x32_bf16 v[24:27], v[156:159], v[216:219], v[24:27]
	v_lshl_add_u64 v[228:229], s[56:57], 0, v[136:137]
	s_mov_b32 m0, s58
	s_nop 0
	global_load_lds_dwordx4 v[228:229], off
	v_mfma_f32_16x16x32_bf16 v[12:15], v[132:135], v[224:227], v[12:15]
	v_mfma_f32_16x16x32_bf16 v[8:11], v[156:159], v[224:227], v[8:11]
	s_setprio 0
	s_setprio 1
	v_mfma_f32_16x16x32_bf16 v[52:55], v[172:175], v[190:193], v[52:55]
	v_mfma_f32_16x16x32_bf16 v[48:51], v[182:185], v[190:193], v[48:51]
	v_mfma_f32_16x16x32_bf16 v[36:39], v[172:175], v[198:201], v[36:39]
	v_mfma_f32_16x16x32_bf16 v[32:35], v[182:185], v[198:201], v[32:35]
	v_mfma_f32_16x16x32_bf16 v[20:23], v[172:175], v[212:215], v[20:23]
	v_mfma_f32_16x16x32_bf16 v[16:19], v[182:185], v[212:215], v[16:19]
	v_mfma_f32_16x16x32_bf16 v[4:7], v[172:175], v[220:223], v[4:7]
	v_mfma_f32_16x16x32_bf16 v[0:3], v[182:185], v[220:223], v[0:3]
	v_mfma_f32_16x16x32_bf16 v[52:55], v[176:179], v[194:197], v[52:55]
	v_mfma_f32_16x16x32_bf16 v[48:51], v[186:189], v[194:197], v[48:51]
	v_mfma_f32_16x16x32_bf16 v[36:39], v[176:179], v[208:211], v[36:39]
	v_mfma_f32_16x16x32_bf16 v[32:35], v[186:189], v[208:211], v[32:35]
	v_mfma_f32_16x16x32_bf16 v[20:23], v[176:179], v[216:219], v[20:23]
	v_mfma_f32_16x16x32_bf16 v[16:19], v[186:189], v[216:219], v[16:19]
	v_lshl_add_u64 v[230:231], s[56:57], 0, v[140:141]
	s_mov_b32 m0, s59
	s_nop 0
	global_load_lds_dwordx4 v[230:231], off
	v_mfma_f32_16x16x32_bf16 v[4:7], v[176:179], v[224:227], v[4:7]
	v_mfma_f32_16x16x32_bf16 v[0:3], v[186:189], v[224:227], v[0:3]
	s_setprio 0
	s_barrier
; #define PG8_STAGE(bufoff, gbase, voff) do { _Pragma("unroll") for (int _i = 0; _i < 2; ++_i) \
;         __builtin_amdgcn_global_load_lds((const unsigned*)((const char*)(gbase) + (voff)[_i]), (PG8_LAS unsigned*)(lds + (bufoff) + ldsw + _i * 8192), 16, 0, 0); } while (0)
; #define PG8_LDA(dst, b, h) do { _Pragma("unroll") for (int m = 0; m < 4; ++m) _Pragma("unroll") for (int k = 0; k < 2; ++k) dst[m][k] = *(const PG8_LAS bf16x8*)(lds + PG8_SA(b, h) + aoff + m * 2048 + k * 1024); } while (0)
; #define PG8_LDB(dst, b, h) do { _Pragma("unroll") for (int n = 0; n < 2; ++n) _Pragma("unroll") for (int k = 0; k < 2; ++k) dst[n][k] = *(const PG8_LAS bf16x8*)(lds + PG8_SB(b, h) + boff + n * 2048 + k * 1024); } while (0)
; #define PG8_MMA(ai, bj, At, Bt) do { __builtin_amdgcn_s_setprio(1); _Pragma("unroll") for (int m = 0; m < 4; ++m) _Pragma("unroll") for (int n = 0; n < 2; ++n) _Pragma("unroll") for (int k = 0; k < 2; ++k) \
;         acc[ai][bj][m][n] = __builtin_amdgcn_mfma_f32_16x16x32_bf16(Bt[n][k], At[m][k], acc[ai][bj][m][n], 0, 0, 0); __builtin_amdgcn_s_setprio(0); } while (0)
; #define PG8_WAIT_V(n) asm volatile("s_waitcnt vmcnt(" #n ")" ::: "memory")
; #define PG8_WAIT_L(n) asm volatile("s_waitcnt lgkmcnt(" #n ")" ::: "memory")
; #define PG8_BAR __builtin_amdgcn_s_barrier()
; #define PG8_SCHED __builtin_amdgcn_sched_barrier(0)
; template <class Epi, class Sched, bool ALIGN_EPI = false, bool SP2 = false>
; __device__ __forceinline__ void gemm_phase(PG8_LAS unsigned char* lds, const Gemm g, const Sched& S, const Epi& E) {
;     ...
;             PG8_LDB(B0, 1, 0); PG8_LDB(B1, 1, 1); PG8_SCHED; PG8_LDA(At, 1, 0); PG8_STAGE(PG8_SA(0, 1), a2 + hstep, voffA);
;             PG8_WAIT_V(8); PG8_WAIT_L(0); PG8_BAR; PG8_MMA(0, 0, At, B0); PG8_MMA(0, 1, At, B1); PG8_BAR; PG8_SCHED;
	s_add_i32 s3, 0, 0x18000
	s_add_i32 s14, 0, 0x1c000
	v_add_u32_e32 v156, s3, v163
	v_add_u32_e32 v171, s14, v163
	ds_read_b128 v[128:131], v156
	ds_read_b128 v[132:135], v156 offset:1024
	ds_read_b128 v[152:155], v156 offset:2048
	ds_read_b128 v[156:159], v156 offset:3072
	ds_read_b128 v[172:175], v171
	ds_read_b128 v[176:179], v171 offset:1024
	ds_read_b128 v[182:185], v171 offset:2048
	ds_read_b128 v[186:189], v171 offset:3072
	s_add_u32 s10, s56, 0xb0000
	s_addc_u32 s11, s57, 0
	s_mov_b32 m0, s60
	v_lshl_add_u64 v[232:233], s[10:11], 0, v[136:137]
	ds_read_b128 v[190:193], v169 offset:32768
	ds_read_b128 v[194:197], v169 offset:33792
	ds_read_b128 v[198:201], v169 offset:34816
	ds_read_b128 v[208:211], v169 offset:35840
	ds_read_b128 v[212:215], v169 offset:36864
	ds_read_b128 v[216:219], v169 offset:37888
	ds_read_b128 v[220:223], v169 offset:38912
	ds_read_b128 v[224:227], v169 offset:39936
	global_load_lds_dwordx4 v[232:233], off
	v_lshl_add_u64 v[232:233], s[10:11], 0, v[140:141]
	s_mov_b32 m0, s61
	s_nop 0
	global_load_lds_dwordx4 v[232:233], off
	s_waitcnt vmcnt(8)
	s_waitcnt lgkmcnt(0)
	s_barrier
	s_setprio 1
	s_waitcnt lgkmcnt(0)
	v_mfma_f32_16x16x32_bf16 v[124:127], v[128:131], v[190:193], v[124:127]
	v_mfma_f32_16x16x32_bf16 v[120:123], v[152:155], v[190:193], v[120:123]
	v_mfma_f32_16x16x32_bf16 v[108:111], v[128:131], v[198:201], v[108:111]
	v_mfma_f32_16x16x32_bf16 v[104:107], v[152:155], v[198:201], v[104:107]
	v_mfma_f32_16x16x32_bf16 v[92:95], v[128:131], v[212:215], v[92:95]
	v_mfma_f32_16x16x32_bf16 v[88:91], v[152:155], v[212:215], v[88:91]
	v_mfma_f32_16x16x32_bf16 v[76:79], v[128:131], v[220:223], v[76:79]
	v_mfma_f32_16x16x32_bf16 v[72:75], v[152:155], v[220:223], v[72:75]
	v_mfma_f32_16x16x32_bf16 v[124:127], v[132:135], v[194:197], v[124:127]
	v_mfma_f32_16x16x32_bf16 v[120:123], v[156:159], v[194:197], v[120:123]
	v_mfma_f32_16x16x32_bf16 v[108:111], v[132:135], v[208:211], v[108:111]
	v_mfma_f32_16x16x32_bf16 v[104:107], v[156:159], v[208:211], v[104:107]
	v_mfma_f32_16x16x32_bf16 v[92:95], v[132:135], v[216:219], v[92:95]
	v_mfma_f32_16x16x32_bf16 v[88:91], v[156:159], v[216:219], v[88:91]
	v_mfma_f32_16x16x32_bf16 v[76:79], v[132:135], v[224:227], v[76:79]
	v_mfma_f32_16x16x32_bf16 v[72:75], v[156:159], v[224:227], v[72:75]
	s_setprio 0
	s_setprio 1
	v_mfma_f32_16x16x32_bf16 v[116:119], v[172:175], v[190:193], v[116:119]
	v_mfma_f32_16x16x32_bf16 v[112:115], v[182:185], v[190:193], v[112:115]
	v_mfma_f32_16x16x32_bf16 v[100:103], v[172:175], v[198:201], v[100:103]
	v_mfma_f32_16x16x32_bf16 v[96:99], v[182:185], v[198:201], v[96:99]
	v_mfma_f32_16x16x32_bf16 v[84:87], v[172:175], v[212:215], v[84:87]
	v_mfma_f32_16x16x32_bf16 v[80:83], v[182:185], v[212:215], v[80:83]
	v_mfma_f32_16x16x32_bf16 v[68:71], v[172:175], v[220:223], v[68:71]
	v_mfma_f32_16x16x32_bf16 v[64:67], v[182:185], v[220:223], v[64:67]
	v_mfma_f32_16x16x32_bf16 v[116:119], v[176:179], v[194:197], v[116:119]
	v_mfma_f32_16x16x32_bf16 v[112:115], v[186:189], v[194:197], v[112:115]
	v_mfma_f32_16x16x32_bf16 v[100:103], v[176:179], v[208:211], v[100:103]
	v_mfma_f32_16x16x32_bf16 v[96:99], v[186:189], v[208:211], v[96:99]
	v_mfma_f32_16x16x32_bf16 v[84:87], v[176:179], v[216:219], v[84:87]
	v_mfma_f32_16x16x32_bf16 v[80:83], v[186:189], v[216:219], v[80:83]
	v_mfma_f32_16x16x32_bf16 v[68:71], v[176:179], v[224:227], v[68:71]
	v_mfma_f32_16x16x32_bf16 v[64:67], v[186:189], v[224:227], v[64:67]
	s_setprio 0
	s_barrier
; #define PG8_STAGE(bufoff, gbase, voff) do { _Pragma("unroll") for (int _i = 0; _i < 2; ++_i) \
;         __builtin_amdgcn_global_load_lds((const unsigned*)((const char*)(gbase) + (voff)[_i]), (PG8_LAS unsigned*)(lds + (bufoff) + ldsw + _i * 8192), 16, 0, 0); } while (0)
; #define PG8_LDA(dst, b, h) do { _Pragma("unroll") for (int m = 0; m < 4; ++m) _Pragma("unroll") for (int k = 0; k < 2; ++k) dst[m][k] = *(const PG8_LAS bf16x8*)(lds + PG8_SA(b, h) + aoff + m * 2048 + k * 1024); } while (0)
; #define PG8_MMA(ai, bj, At, Bt) do { __builtin_amdgcn_s_setprio(1); _Pragma("unroll") for (int m = 0; m < 4; ++m) _Pragma("unroll") for (int n = 0; n < 2; ++n) _Pragma("unroll") for (int k = 0; k < 2; ++k) \
;         acc[ai][bj][m][n] = __builtin_amdgcn_mfma_f32_16x16x32_bf16(Bt[n][k], At[m][k], acc[ai][bj][m][n], 0, 0, 0); __builtin_amdgcn_s_setprio(0); } while (0)
; #define PG8_WAIT_V(n) asm volatile("s_waitcnt vmcnt(" #n ")" ::: "memory")
; #define PG8_WAIT_L(n) asm volatile("s_waitcnt lgkmcnt(" #n ")" ::: "memory")
; #define PG8_BAR __builtin_amdgcn_s_barrier()
; #define PG8_SCHED __builtin_amdgcn_sched_barrier(0)
; template <class Epi, class Sched, bool ALIGN_EPI = false, bool SP2 = false>
; __device__ __forceinline__ void gemm_phase(PG8_LAS unsigned char* lds, const Gemm g, const Sched& S, const Epi& E) {
;     ...
;             PG8_LDA(At, 1, 1); PG8_STAGE(PG8_SB(1, 0), b3, voffB); PG8_STAGE(PG8_SB(1, 1), b3 + hstep, voffB); PG8_STAGE(PG8_SA(1, 0), a3, voffA);
;             PG8_WAIT_V(8); PG8_WAIT_L(0); PG8_BAR; PG8_MMA(1, 0, At, B0); PG8_MMA(1, 1, At, B1); PG8_BAR; PG8_SCHED;
;     ...
;         if constexpr (ALIGN_EPI) { if (wr == 0) PG8_BAR; }
	s_add_i32 s3, s3, s43
	v_lshl_add_u64 v[160:161], v[160:161], 0, s[40:41]
	s_mov_b32 m0, s3
	ds_read_b128 v[190:193], v169 offset:49152
	ds_read_b128 v[194:197], v169 offset:50176
	ds_read_b128 v[198:201], v169 offset:51200
	ds_read_b128 v[208:211], v169 offset:52224
	ds_read_b128 v[212:215], v169 offset:53248
	ds_read_b128 v[216:219], v169 offset:54272
	ds_read_b128 v[220:223], v169 offset:55296
	ds_read_b128 v[224:227], v169 offset:56320
	global_load_lds_dwordx4 v[160:161], off
	s_add_i32 m0, s3, 0x2000
	s_add_u32 s10, s54, 0xb0080
	v_lshl_add_u64 v[160:161], v[202:203], 0, s[40:41]
	s_addc_u32 s11, s55, 0
	s_add_i32 s3, s14, s43
	global_load_lds_dwordx4 v[160:161], off
	v_lshl_add_u64 v[160:161], s[10:11], 0, v[138:139]
	s_mov_b32 m0, s3
	s_nop 0
	global_load_lds_dwordx4 v[160:161], off
	v_lshl_add_u64 v[160:161], s[10:11], 0, v[142:143]
	s_add_i32 m0, s3, 0x2000
	s_nop 0
	global_load_lds_dwordx4 v[160:161], off
	s_waitcnt vmcnt(6)
	s_waitcnt lgkmcnt(0)
	s_barrier
	s_setprio 1
	s_waitcnt lgkmcnt(0)
	v_mfma_f32_16x16x32_bf16 v[60:63], v[128:131], v[190:193], v[60:63]
	v_mfma_f32_16x16x32_bf16 v[56:59], v[152:155], v[190:193], v[56:59]
	v_mfma_f32_16x16x32_bf16 v[44:47], v[128:131], v[198:201], v[44:47]
	v_mfma_f32_16x16x32_bf16 v[40:43], v[152:155], v[198:201], v[40:43]
	v_mfma_f32_16x16x32_bf16 v[28:31], v[128:131], v[212:215], v[28:31]
	v_mfma_f32_16x16x32_bf16 v[24:27], v[152:155], v[212:215], v[24:27]
	v_mfma_f32_16x16x32_bf16 v[12:15], v[128:131], v[220:223], v[12:15]
	v_mfma_f32_16x16x32_bf16 v[8:11], v[152:155], v[220:223], v[8:11]
	v_mfma_f32_16x16x32_bf16 v[60:63], v[132:135], v[194:197], v[60:63]
	v_mfma_f32_16x16x32_bf16 v[56:59], v[156:159], v[194:197], v[56:59]
	v_mfma_f32_16x16x32_bf16 v[44:47], v[132:135], v[208:211], v[44:47]
	v_mfma_f32_16x16x32_bf16 v[40:43], v[156:159], v[208:211], v[40:43]
	v_mfma_f32_16x16x32_bf16 v[28:31], v[132:135], v[216:219], v[28:31]
	v_mfma_f32_16x16x32_bf16 v[24:27], v[156:159], v[216:219], v[24:27]
	v_lshl_add_u64 v[160:161], v[228:229], 0, s[40:41]
	s_mov_b32 m0, s63
	s_nop 0
	global_load_lds_dwordx4 v[160:161], off
	v_mfma_f32_16x16x32_bf16 v[12:15], v[132:135], v[224:227], v[12:15]
	v_mfma_f32_16x16x32_bf16 v[8:11], v[156:159], v[224:227], v[8:11]
	s_setprio 0
	s_setprio 1
	v_mfma_f32_16x16x32_bf16 v[52:55], v[172:175], v[190:193], v[52:55]
	v_mfma_f32_16x16x32_bf16 v[48:51], v[182:185], v[190:193], v[48:51]
	v_mfma_f32_16x16x32_bf16 v[36:39], v[172:175], v[198:201], v[36:39]
	v_mfma_f32_16x16x32_bf16 v[32:35], v[182:185], v[198:201], v[32:35]
	v_mfma_f32_16x16x32_bf16 v[20:23], v[172:175], v[212:215], v[20:23]
	v_mfma_f32_16x16x32_bf16 v[16:19], v[182:185], v[212:215], v[16:19]
	v_mfma_f32_16x16x32_bf16 v[4:7], v[172:175], v[220:223], v[4:7]
	v_mfma_f32_16x16x32_bf16 v[0:3], v[182:185], v[220:223], v[0:3]
	v_mfma_f32_16x16x32_bf16 v[52:55], v[176:179], v[194:197], v[52:55]
	v_mfma_f32_16x16x32_bf16 v[48:51], v[186:189], v[194:197], v[48:51]
	v_mfma_f32_16x16x32_bf16 v[36:39], v[176:179], v[208:211], v[36:39]
	v_mfma_f32_16x16x32_bf16 v[32:35], v[186:189], v[208:211], v[32:35]
	v_mfma_f32_16x16x32_bf16 v[20:23], v[176:179], v[216:219], v[20:23]
	v_mfma_f32_16x16x32_bf16 v[16:19], v[186:189], v[216:219], v[16:19]
	v_lshl_add_u64 v[160:161], v[230:231], 0, s[40:41]
	s_mov_b32 m0, s64
	s_nop 0
	global_load_lds_dwordx4 v[160:161], off
	v_mfma_f32_16x16x32_bf16 v[4:7], v[176:179], v[224:227], v[4:7]
	v_mfma_f32_16x16x32_bf16 v[0:3], v[186:189], v[224:227], v[0:3]
	s_setprio 0
	s_barrier
	s_add_i32 s93, s93, 2
	s_add_u32 s91, s91, 0x100
	s_addc_u32 s92, s92, 0
	s_cmp_gt_u32 s93, 41
	s_mov_b64 s[10:11], s[50:51]
	s_cbranch_scc0 .LBB0_269
	s_and_b64 vcc, exec, s[44:45]
	s_cbranch_vccz .LBB0_272
	s_barrier

; #define PG8_STAGE(bufoff, gbase, voff) do { _Pragma("unroll") for (int _i = 0; _i < 2; ++_i) \
;         __builtin_amdgcn_global_load_lds((const unsigned*)((const char*)(gbase) + (voff)[_i]), (PG8_LAS unsigned*)(lds + (bufoff) + ldsw + _i * 8192), 16, 0, 0); } while (0)
; #define PG8_LDA(dst, b, h) do { _Pragma("unroll") for (int m = 0; m < 4; ++m) _Pragma("unroll") for (int k = 0; k < 2; ++k) dst[m][k] = *(const PG8_LAS bf16x8*)(lds + PG8_SA(b, h) + aoff + m * 2048 + k * 1024); } while (0)
; #define PG8_LDB(dst, b, h) do { _Pragma("unroll") for (int n = 0; n < 2; ++n) _Pragma("unroll") for (int k = 0; k < 2; ++k) dst[n][k] = *(const PG8_LAS bf16x8*)(lds + PG8_SB(b, h) + boff + n * 2048 + k * 1024); } while (0)
; #define PG8_MMA(ai, bj, At, Bt) do { __builtin_amdgcn_s_setprio(1); _Pragma("unroll") for (int m = 0; m < 4; ++m) _Pragma("unroll") for (int n = 0; n < 2; ++n) _Pragma("unroll") for (int k = 0; k < 2; ++k) \
;         acc[ai][bj][m][n] = __builtin_amdgcn_mfma_f32_16x16x32_bf16(Bt[n][k], At[m][k], acc[ai][bj][m][n], 0, 0, 0); __builtin_amdgcn_s_setprio(0); } while (0)
; #define PG8_BAR __builtin_amdgcn_s_barrier()
; template <class Epi, class Sched, bool ALIGN_EPI = false, bool SP2 = false>
; __device__ __forceinline__ void gemm_phase(PG8_LAS unsigned char* lds, const Gemm g, const Sched& S, const Epi& E) {
;     ...
;         const bool has_next = S.next(ui + 1, nxt);
;         const char* nA = has_next ? (const char*)g.A + (size_t)nxt.pm * tstep : cA; const char* nB = has_next ? (const char*)g.Bt + (size_t)nxt.pn * tstep : cB;
;         for (int t = 0; t < nt; t += 2) {
;             const bool last = (t == nt - 2);
;             const char* a1 = cA + (size_t)(t + 1) * kstep;
;             const char* a2 = last ? nA : cA + (size_t)(t + 2) * kstep; const char* b2 = last ? nB : cB + (size_t)(t + 2) * kstep;
;             const char* a3 = a2 + kstep; const char* b3 = b2 + kstep;
;             if (last && has_next) S.a_ready(nxt);
;             if constexpr (SP2) {
;             PG8_LDB(B0, 0, 0); PG8_LDB(B1, 0, 1); PG8_SCHED; PG8_LDA(At, 0, 0); PG8_STAGE(PG8_SA(1, 1), a1 + hstep, voffA);
;             PG8_WAIT_V(8); PG8_WAIT_L(0); PG8_BAR; PG8_MMA(0, 0, At, B0); PG8_MMA(0, 1, At, B1); PG8_BAR; PG8_SCHED;
;             PG8_LDA(At, 0, 1); PG8_STAGE(PG8_SB(0, 0), b2, voffB); PG8_STAGE(PG8_SB(0, 1), b2 + hstep, voffB); PG8_STAGE(PG8_SA(0, 0), a2, voffA);
.LBB0_416:
	s_ashr_i32 s45, s44, 31
	s_lshl_b64 s[14:15], s[44:45], 19
	s_add_u32 s48, s22, s14
	s_addc_u32 s49, s23, s15
	s_and_b64 s[14:15], s[6:7], exec
	s_cselect_b32 s45, s49, s55
	s_cselect_b32 s89, s48, s54
	s_ashr_i32 s41, s40, 31
	s_lshl_b64 s[14:15], s[40:41], 19
	s_add_u32 s50, s84, s14
	s_addc_u32 s51, s85, s15
	s_and_b64 s[14:15], s[6:7], exec
	s_cselect_b32 s41, s51, s57
	s_cselect_b32 s90, s50, s56
	s_add_u32 s54, s54, 0x40080
	s_addc_u32 s55, s55, 0
	s_add_u32 s91, s56, 0x100
	s_addc_u32 s92, s57, 0
	s_mov_b32 s93, -2
	ds_read_b128 v[154:157], v169
	ds_read_b128 v[158:161], v169 offset:1024
	ds_read_b128 v[162:165], v169 offset:2048
	ds_read_b128 v[174:177], v169 offset:3072
	ds_read_b128 v[182:185], v170
	ds_read_b128 v[186:189], v170 offset:1024
	ds_read_b128 v[190:193], v170 offset:2048
	ds_read_b128 v[194:197], v170 offset:3072
	s_add_u32 s3, s54, 0xfffc0080
	s_addc_u32 s14, s55, -1
	s_cmp_eq_u32 s93, 12
	s_cselect_b32 s59, s45, s14
	s_cselect_b32 s58, s89, s3
	s_cselect_b32 s57, s41, s92
	s_cselect_b32 s56, s90, s91
	v_lshl_add_u64 v[178:179], s[54:55], 0, v[146:147]
	s_add_i32 m0, s60, 0xc000
	ds_read_b128 v[198:201], v171
	ds_read_b128 v[208:211], v171 offset:1024
	ds_read_b128 v[212:215], v171 offset:2048
	ds_read_b128 v[216:219], v171 offset:3072
	ds_read_b128 v[220:223], v171 offset:4096
	ds_read_b128 v[224:227], v171 offset:5120
	ds_read_b128 v[228:231], v171 offset:6144
	ds_read_b128 v[232:235], v171 offset:7168
	global_load_lds_dwordx4 v[178:179], off
	v_lshl_add_u64 v[178:179], s[54:55], 0, v[148:149]
	s_add_i32 m0, s60, 0xe000
	s_nop 0
	global_load_lds_dwordx4 v[178:179], off
	s_waitcnt vmcnt(8)
	s_waitcnt lgkmcnt(0)
	s_barrier
	s_setprio 1
	s_waitcnt lgkmcnt(0)
	v_mfma_f32_16x16x32_bf16 v[124:127], v[154:157], v[198:201], 0
	v_mfma_f32_16x16x32_bf16 v[120:123], v[162:165], v[198:201], 0
	v_mfma_f32_16x16x32_bf16 v[116:119], v[154:157], v[212:215], 0
	v_mfma_f32_16x16x32_bf16 v[112:115], v[162:165], v[212:215], 0
	v_mfma_f32_16x16x32_bf16 v[108:111], v[154:157], v[220:223], 0
	v_mfma_f32_16x16x32_bf16 v[104:107], v[162:165], v[220:223], 0
	v_mfma_f32_16x16x32_bf16 v[100:103], v[154:157], v[228:231], 0
	v_mfma_f32_16x16x32_bf16 v[96:99], v[162:165], v[228:231], 0
	v_mfma_f32_16x16x32_bf16 v[124:127], v[158:161], v[208:211], v[124:127]
	v_mfma_f32_16x16x32_bf16 v[120:123], v[174:177], v[208:211], v[120:123]
	v_mfma_f32_16x16x32_bf16 v[116:119], v[158:161], v[216:219], v[116:119]
	v_mfma_f32_16x16x32_bf16 v[112:115], v[174:177], v[216:219], v[112:115]
	v_mfma_f32_16x16x32_bf16 v[108:111], v[158:161], v[224:227], v[108:111]
	v_mfma_f32_16x16x32_bf16 v[104:107], v[174:177], v[224:227], v[104:107]
	v_mfma_f32_16x16x32_bf16 v[100:103], v[158:161], v[232:235], v[100:103]
	v_mfma_f32_16x16x32_bf16 v[96:99], v[174:177], v[232:235], v[96:99]
	s_setprio 0
	s_setprio 1
	v_mfma_f32_16x16x32_bf16 v[68:71], v[182:185], v[198:201], 0
	v_mfma_f32_16x16x32_bf16 v[64:67], v[190:193], v[198:201], 0
	v_mfma_f32_16x16x32_bf16 v[52:55], v[182:185], v[212:215], 0
	v_mfma_f32_16x16x32_bf16 v[48:51], v[190:193], v[212:215], 0
	v_mfma_f32_16x16x32_bf16 v[44:47], v[182:185], v[220:223], 0
	v_mfma_f32_16x16x32_bf16 v[40:43], v[190:193], v[220:223], 0
	v_mfma_f32_16x16x32_bf16 v[36:39], v[182:185], v[228:231], 0
	v_mfma_f32_16x16x32_bf16 v[32:35], v[190:193], v[228:231], 0
	v_mfma_f32_16x16x32_bf16 v[68:71], v[186:189], v[208:211], v[68:71]
	v_mfma_f32_16x16x32_bf16 v[64:67], v[194:197], v[208:211], v[64:67]
	v_mfma_f32_16x16x32_bf16 v[52:55], v[186:189], v[216:219], v[52:55]
	v_mfma_f32_16x16x32_bf16 v[48:51], v[194:197], v[216:219], v[48:51]
	v_mfma_f32_16x16x32_bf16 v[44:47], v[186:189], v[224:227], v[44:47]
	v_mfma_f32_16x16x32_bf16 v[40:43], v[194:197], v[224:227], v[40:43]
	v_mfma_f32_16x16x32_bf16 v[36:39], v[186:189], v[232:235], v[36:39]
	v_mfma_f32_16x16x32_bf16 v[32:35], v[194:197], v[232:235], v[32:35]
	s_setprio 0
	s_barrier
	s_add_i32 s3, s86, s34
	v_lshl_add_u64 v[178:179], s[56:57], 0, v[132:133]
	s_mov_b32 m0, s3
	ds_read_b128 v[198:201], v171 offset:16384
	ds_read_b128 v[208:211], v171 offset:17408
	ds_read_b128 v[212:215], v171 offset:18432
	ds_read_b128 v[216:219], v171 offset:19456
	ds_read_b128 v[220:223], v171 offset:20480
	ds_read_b128 v[224:227], v171 offset:21504
	ds_read_b128 v[228:231], v171 offset:22528
	ds_read_b128 v[232:235], v171 offset:23552
	global_load_lds_dwordx4 v[178:179], off
	s_add_i32 m0, s3, 0x2000
	s_add_u32 s14, s56, 0x40000
	v_lshl_add_u64 v[202:203], s[56:57], 0, v[128:129]
	s_addc_u32 s15, s57, 0
	s_add_i32 s3, s87, s34
	global_load_lds_dwordx4 v[202:203], off
	v_lshl_add_u64 v[236:237], s[14:15], 0, v[132:133]
	s_mov_b32 m0, s3
	global_load_lds_dwordx4 v[236:237], off
	v_lshl_add_u64 v[236:237], s[14:15], 0, v[128:129]
	s_add_i32 m0, s3, 0x2000
	s_nop 0
	global_load_lds_dwordx4 v[236:237], off
	s_waitcnt vmcnt(6)
	s_waitcnt lgkmcnt(0)
	s_barrier
; #define PG8_STAGE(bufoff, gbase, voff) do { _Pragma("unroll") for (int _i = 0; _i < 2; ++_i) \
;         __builtin_amdgcn_global_load_lds((const unsigned*)((const char*)(gbase) + (voff)[_i]), (PG8_LAS unsigned*)(lds + (bufoff) + ldsw + _i * 8192), 16, 0, 0); } while (0)
; #define PG8_LDA(dst, b, h) do { _Pragma("unroll") for (int m = 0; m < 4; ++m) _Pragma("unroll") for (int k = 0; k < 2; ++k) dst[m][k] = *(const PG8_LAS bf16x8*)(lds + PG8_SA(b, h) + aoff + m * 2048 + k * 1024); } while (0)
; #define PG8_LDB(dst, b, h) do { _Pragma("unroll") for (int n = 0; n < 2; ++n) _Pragma("unroll") for (int k = 0; k < 2; ++k) dst[n][k] = *(const PG8_LAS bf16x8*)(lds + PG8_SB(b, h) + boff + n * 2048 + k * 1024); } while (0)
; #define PG8_MMA(ai, bj, At, Bt) do { __builtin_amdgcn_s_setprio(1); _Pragma("unroll") for (int m = 0; m < 4; ++m) _Pragma("unroll") for (int n = 0; n < 2; ++n) _Pragma("unroll") for (int k = 0; k < 2; ++k) \
;         acc[ai][bj][m][n] = __builtin_amdgcn_mfma_f32_16x16x32_bf16(Bt[n][k], At[m][k], acc[ai][bj][m][n], 0, 0, 0); __builtin_amdgcn_s_setprio(0); } while (0)
; #define PG8_WAIT_V(n) asm volatile("s_waitcnt vmcnt(" #n ")" ::: "memory")
; #define PG8_WAIT_L(n) asm volatile("s_waitcnt lgkmcnt(" #n ")" ::: "memory")
; #define PG8_BAR __builtin_amdgcn_s_barrier()
; #define PG8_SCHED __builtin_amdgcn_sched_barrier(0)
; template <class Epi, class Sched, bool ALIGN_EPI = false, bool SP2 = false>
; __device__ __forceinline__ void gemm_phase(PG8_LAS unsigned char* lds, const Gemm g, const Sched& S, const Epi& E) {
;     ...
;             PG8_WAIT_V(8); PG8_WAIT_L(0); PG8_BAR; PG8_MMA(1, 0, At, B0); PG8_MMA(1, 1, At, B1); PG8_BAR; PG8_SCHED;
;             PG8_LDB(B0, 1, 0); PG8_LDB(B1, 1, 1); PG8_SCHED; PG8_LDA(At, 1, 0); PG8_STAGE(PG8_SA(0, 1), a2 + hstep, voffA);
;             PG8_WAIT_V(8); PG8_WAIT_L(0); PG8_BAR; PG8_MMA(0, 0, At, B0); PG8_MMA(0, 1, At, B1); PG8_BAR; PG8_SCHED;
	s_setprio 1
	s_waitcnt lgkmcnt(0)
	v_mfma_f32_16x16x32_bf16 v[92:95], v[154:157], v[198:201], 0
	v_mfma_f32_16x16x32_bf16 v[88:91], v[162:165], v[198:201], 0
	v_mfma_f32_16x16x32_bf16 v[84:87], v[154:157], v[212:215], 0
	v_mfma_f32_16x16x32_bf16 v[80:83], v[162:165], v[212:215], 0
	v_mfma_f32_16x16x32_bf16 v[76:79], v[154:157], v[220:223], 0
	v_mfma_f32_16x16x32_bf16 v[72:75], v[162:165], v[220:223], 0
	v_mfma_f32_16x16x32_bf16 v[60:63], v[154:157], v[228:231], 0
	v_mfma_f32_16x16x32_bf16 v[56:59], v[162:165], v[228:231], 0
	v_mfma_f32_16x16x32_bf16 v[92:95], v[158:161], v[208:211], v[92:95]
	v_mfma_f32_16x16x32_bf16 v[88:91], v[174:177], v[208:211], v[88:91]
	v_mfma_f32_16x16x32_bf16 v[84:87], v[158:161], v[216:219], v[84:87]
	v_mfma_f32_16x16x32_bf16 v[80:83], v[174:177], v[216:219], v[80:83]
	v_mfma_f32_16x16x32_bf16 v[76:79], v[158:161], v[224:227], v[76:79]
	v_mfma_f32_16x16x32_bf16 v[72:75], v[174:177], v[224:227], v[72:75]
	v_lshl_add_u64 v[236:237], s[58:59], 0, v[134:135]
	s_mov_b32 m0, s60
	s_nop 0
	global_load_lds_dwordx4 v[236:237], off
	v_mfma_f32_16x16x32_bf16 v[60:63], v[158:161], v[232:235], v[60:63]
	v_mfma_f32_16x16x32_bf16 v[56:59], v[174:177], v[232:235], v[56:59]
	s_setprio 0
	s_setprio 1
	v_mfma_f32_16x16x32_bf16 v[28:31], v[182:185], v[198:201], 0
	v_mfma_f32_16x16x32_bf16 v[24:27], v[190:193], v[198:201], 0
	v_mfma_f32_16x16x32_bf16 v[20:23], v[182:185], v[212:215], 0
	v_mfma_f32_16x16x32_bf16 v[16:19], v[190:193], v[212:215], 0
	v_mfma_f32_16x16x32_bf16 v[12:15], v[182:185], v[220:223], 0
	v_mfma_f32_16x16x32_bf16 v[8:11], v[190:193], v[220:223], 0
	v_mfma_f32_16x16x32_bf16 v[4:7], v[182:185], v[228:231], 0
	v_mfma_f32_16x16x32_bf16 v[0:3], v[190:193], v[228:231], 0
	v_mfma_f32_16x16x32_bf16 v[28:31], v[186:189], v[208:211], v[28:31]
	v_mfma_f32_16x16x32_bf16 v[24:27], v[194:197], v[208:211], v[24:27]
	v_mfma_f32_16x16x32_bf16 v[20:23], v[186:189], v[216:219], v[20:23]
	v_mfma_f32_16x16x32_bf16 v[16:19], v[194:197], v[216:219], v[16:19]
	v_mfma_f32_16x16x32_bf16 v[12:15], v[186:189], v[224:227], v[12:15]
	v_mfma_f32_16x16x32_bf16 v[8:11], v[194:197], v[224:227], v[8:11]
	v_lshl_add_u64 v[238:239], s[58:59], 0, v[130:131]
	s_mov_b32 m0, s61
	s_nop 0
	global_load_lds_dwordx4 v[238:239], off
	v_mfma_f32_16x16x32_bf16 v[4:7], v[186:189], v[232:235], v[4:7]
	v_mfma_f32_16x16x32_bf16 v[0:3], v[194:197], v[232:235], v[0:3]
	s_setprio 0
	s_barrier
	s_add_i32 s3, 0, 0x18000
	v_add_u32_e32 v136, s3, v143
	s_add_i32 s33, 0, 0x1c000
	ds_read_b128 v[154:157], v136
	ds_read_b128 v[158:161], v136 offset:1024
	ds_read_b128 v[162:165], v136 offset:2048
	ds_read_b128 v[174:177], v136 offset:3072
	v_add_u32_e32 v136, s33, v143
	ds_read_b128 v[182:185], v136
	ds_read_b128 v[186:189], v136 offset:1024
	ds_read_b128 v[190:193], v136 offset:2048
	ds_read_b128 v[194:197], v136 offset:3072
	s_add_u32 s14, s58, 0x40000
	s_addc_u32 s15, s59, 0
	s_mov_b32 m0, s62
	v_lshl_add_u64 v[240:241], s[14:15], 0, v[134:135]
	ds_read_b128 v[198:201], v171 offset:32768
	ds_read_b128 v[208:211], v171 offset:33792
	ds_read_b128 v[212:215], v171 offset:34816
	ds_read_b128 v[216:219], v171 offset:35840
	ds_read_b128 v[220:223], v171 offset:36864
	ds_read_b128 v[224:227], v171 offset:37888
	ds_read_b128 v[228:231], v171 offset:38912
	ds_read_b128 v[232:235], v171 offset:39936
	global_load_lds_dwordx4 v[240:241], off
	v_lshl_add_u64 v[240:241], s[14:15], 0, v[130:131]
	s_mov_b32 m0, s63
	s_nop 0
	global_load_lds_dwordx4 v[240:241], off
	s_waitcnt vmcnt(8)
	s_waitcnt lgkmcnt(0)
	s_barrier
	s_setprio 1
	s_waitcnt lgkmcnt(0)
	v_mfma_f32_16x16x32_bf16 v[124:127], v[154:157], v[198:201], v[124:127]
	v_mfma_f32_16x16x32_bf16 v[120:123], v[162:165], v[198:201], v[120:123]
	v_mfma_f32_16x16x32_bf16 v[116:119], v[154:157], v[212:215], v[116:119]
	v_mfma_f32_16x16x32_bf16 v[112:115], v[162:165], v[212:215], v[112:115]
	v_mfma_f32_16x16x32_bf16 v[108:111], v[154:157], v[220:223], v[108:111]
	v_mfma_f32_16x16x32_bf16 v[104:107], v[162:165], v[220:223], v[104:107]
	v_mfma_f32_16x16x32_bf16 v[100:103], v[154:157], v[228:231], v[100:103]
	v_mfma_f32_16x16x32_bf16 v[96:99], v[162:165], v[228:231], v[96:99]
	v_mfma_f32_16x16x32_bf16 v[124:127], v[158:161], v[208:211], v[124:127]
	v_mfma_f32_16x16x32_bf16 v[120:123], v[174:177], v[208:211], v[120:123]
	v_mfma_f32_16x16x32_bf16 v[116:119], v[158:161], v[216:219], v[116:119]
	v_mfma_f32_16x16x32_bf16 v[112:115], v[174:177], v[216:219], v[112:115]
	v_mfma_f32_16x16x32_bf16 v[108:111], v[158:161], v[224:227], v[108:111]
	v_mfma_f32_16x16x32_bf16 v[104:107], v[174:177], v[224:227], v[104:107]
	v_mfma_f32_16x16x32_bf16 v[100:103], v[158:161], v[232:235], v[100:103]
	v_mfma_f32_16x16x32_bf16 v[96:99], v[174:177], v[232:235], v[96:99]
	s_setprio 0
	s_setprio 1
	v_mfma_f32_16x16x32_bf16 v[68:71], v[182:185], v[198:201], v[68:71]
	v_mfma_f32_16x16x32_bf16 v[64:67], v[190:193], v[198:201], v[64:67]
	v_mfma_f32_16x16x32_bf16 v[52:55], v[182:185], v[212:215], v[52:55]
	v_mfma_f32_16x16x32_bf16 v[48:51], v[190:193], v[212:215], v[48:51]
	v_mfma_f32_16x16x32_bf16 v[44:47], v[182:185], v[220:223], v[44:47]
	v_mfma_f32_16x16x32_bf16 v[40:43], v[190:193], v[220:223], v[40:43]
	v_mfma_f32_16x16x32_bf16 v[36:39], v[182:185], v[228:231], v[36:39]
	v_mfma_f32_16x16x32_bf16 v[32:35], v[190:193], v[228:231], v[32:35]
	v_mfma_f32_16x16x32_bf16 v[68:71], v[186:189], v[208:211], v[68:71]
	v_mfma_f32_16x16x32_bf16 v[64:67], v[194:197], v[208:211], v[64:67]
	v_mfma_f32_16x16x32_bf16 v[52:55], v[186:189], v[216:219], v[52:55]
	v_mfma_f32_16x16x32_bf16 v[48:51], v[194:197], v[216:219], v[48:51]
	v_mfma_f32_16x16x32_bf16 v[44:47], v[186:189], v[224:227], v[44:47]
	v_mfma_f32_16x16x32_bf16 v[40:43], v[194:197], v[224:227], v[40:43]
	v_mfma_f32_16x16x32_bf16 v[36:39], v[186:189], v[232:235], v[36:39]
	v_mfma_f32_16x16x32_bf16 v[32:35], v[194:197], v[232:235], v[32:35]
	s_setprio 0
	s_barrier
; #define PG8_STAGE(bufoff, gbase, voff) do { _Pragma("unroll") for (int _i = 0; _i < 2; ++_i) \
;         __builtin_amdgcn_global_load_lds((const unsigned*)((const char*)(gbase) + (voff)[_i]), (PG8_LAS unsigned*)(lds + (bufoff) + ldsw + _i * 8192), 16, 0, 0); } while (0)
; #define PG8_LDA(dst, b, h) do { _Pragma("unroll") for (int m = 0; m < 4; ++m) _Pragma("unroll") for (int k = 0; k < 2; ++k) dst[m][k] = *(const PG8_LAS bf16x8*)(lds + PG8_SA(b, h) + aoff + m * 2048 + k * 1024); } while (0)
; #define PG8_LDB(dst, b, h) do { _Pragma("unroll") for (int n = 0; n < 2; ++n) _Pragma("unroll") for (int k = 0; k < 2; ++k) dst[n][k] = *(const PG8_LAS bf16x8*)(lds + PG8_SB(b, h) + boff + n * 2048 + k * 1024); } while (0)
; #define PG8_MMA(ai, bj, At, Bt) do { __builtin_amdgcn_s_setprio(1); _Pragma("unroll") for (int m = 0; m < 4; ++m) _Pragma("unroll") for (int n = 0; n < 2; ++n) _Pragma("unroll") for (int k = 0; k < 2; ++k) \
;         acc[ai][bj][m][n] = __builtin_amdgcn_mfma_f32_16x16x32_bf16(Bt[n][k], At[m][k], acc[ai][bj][m][n], 0, 0, 0); __builtin_amdgcn_s_setprio(0); } while (0)
; #define PG8_WAIT_V(n) asm volatile("s_waitcnt vmcnt(" #n ")" ::: "memory")
; #define PG8_BAR __builtin_amdgcn_s_barrier()
; template <class Epi, class Sched, bool ALIGN_EPI = false, bool SP2 = false>
; __device__ __forceinline__ void gemm_phase(PG8_LAS unsigned char* lds, const Gemm g, const Sched& S, const Epi& E) {
;     ...
;         for (int t = 0; t < nt; t += 2) {
;             const bool last = (t == nt - 2);
;             const char* a1 = cA + (size_t)(t + 1) * kstep;
;             const char* a2 = last ? nA : cA + (size_t)(t + 2) * kstep; const char* b2 = last ? nB : cB + (size_t)(t + 2) * kstep;
;             const char* a3 = a2 + kstep; const char* b3 = b2 + kstep;
;             if (last && has_next) S.a_ready(nxt);
;             if constexpr (SP2) {
;             PG8_LDB(B0, 0, 0); PG8_LDB(B1, 0, 1); PG8_SCHED; PG8_LDA(At, 0, 0); PG8_STAGE(PG8_SA(1, 1), a1 + hstep, voffA);
;             PG8_WAIT_V(8); PG8_WAIT_L(0); PG8_BAR; PG8_MMA(0, 0, At, B0); PG8_MMA(0, 1, At, B1); PG8_BAR; PG8_SCHED;
;     ...
;             PG8_LDA(At, 1, 1); PG8_STAGE(PG8_SB(1, 0), b3, voffB); PG8_STAGE(PG8_SB(1, 1), b3 + hstep, voffB); PG8_STAGE(PG8_SA(1, 0), a3, voffA);
;             PG8_WAIT_V(8); PG8_WAIT_L(0); PG8_BAR; PG8_MMA(1, 0, At, B0); PG8_MMA(1, 1, At, B1); PG8_BAR; PG8_SCHED;
	s_add_i32 s3, s3, s34
	v_lshl_add_u64 v[178:179], v[178:179], 0, s[8:9]
	s_mov_b32 m0, s3
	ds_read_b128 v[198:201], v171 offset:49152
	ds_read_b128 v[208:211], v171 offset:50176
	ds_read_b128 v[212:215], v171 offset:51200
	ds_read_b128 v[216:219], v171 offset:52224
	ds_read_b128 v[220:223], v171 offset:53248
	ds_read_b128 v[224:227], v171 offset:54272
	ds_read_b128 v[228:231], v171 offset:55296
	ds_read_b128 v[232:235], v171 offset:56320
	global_load_lds_dwordx4 v[178:179], off
	s_add_i32 m0, s3, 0x2000
	s_add_u32 s14, s56, 0x40080
	v_lshl_add_u64 v[178:179], v[202:203], 0, s[8:9]
	s_addc_u32 s15, s57, 0
	s_add_i32 s3, s33, s34
	global_load_lds_dwordx4 v[178:179], off
	v_lshl_add_u64 v[178:179], s[14:15], 0, v[132:133]
	s_mov_b32 m0, s3
	s_nop 0
	global_load_lds_dwordx4 v[178:179], off
	v_lshl_add_u64 v[178:179], s[14:15], 0, v[128:129]
	s_add_i32 m0, s3, 0x2000
	s_nop 0
	global_load_lds_dwordx4 v[178:179], off
	s_waitcnt vmcnt(6)
	s_waitcnt lgkmcnt(0)
	s_barrier
	s_setprio 1
	s_waitcnt lgkmcnt(0)
	v_mfma_f32_16x16x32_bf16 v[92:95], v[154:157], v[198:201], v[92:95]
	v_mfma_f32_16x16x32_bf16 v[88:91], v[162:165], v[198:201], v[88:91]
	v_mfma_f32_16x16x32_bf16 v[84:87], v[154:157], v[212:215], v[84:87]
	v_mfma_f32_16x16x32_bf16 v[80:83], v[162:165], v[212:215], v[80:83]
	v_mfma_f32_16x16x32_bf16 v[76:79], v[154:157], v[220:223], v[76:79]
	v_mfma_f32_16x16x32_bf16 v[72:75], v[162:165], v[220:223], v[72:75]
	v_mfma_f32_16x16x32_bf16 v[60:63], v[154:157], v[228:231], v[60:63]
	v_mfma_f32_16x16x32_bf16 v[56:59], v[162:165], v[228:231], v[56:59]
	v_mfma_f32_16x16x32_bf16 v[92:95], v[158:161], v[208:211], v[92:95]
	v_mfma_f32_16x16x32_bf16 v[88:91], v[174:177], v[208:211], v[88:91]
	v_mfma_f32_16x16x32_bf16 v[84:87], v[158:161], v[216:219], v[84:87]
	v_mfma_f32_16x16x32_bf16 v[80:83], v[174:177], v[216:219], v[80:83]
	v_mfma_f32_16x16x32_bf16 v[76:79], v[158:161], v[224:227], v[76:79]
	v_mfma_f32_16x16x32_bf16 v[72:75], v[174:177], v[224:227], v[72:75]
	v_lshl_add_u64 v[178:179], v[236:237], 0, s[8:9]
	s_mov_b32 m0, s66
	s_nop 0
	global_load_lds_dwordx4 v[178:179], off
	v_mfma_f32_16x16x32_bf16 v[60:63], v[158:161], v[232:235], v[60:63]
	v_mfma_f32_16x16x32_bf16 v[56:59], v[174:177], v[232:235], v[56:59]
	s_setprio 0
	s_setprio 1
	v_mfma_f32_16x16x32_bf16 v[28:31], v[182:185], v[198:201], v[28:31]
	v_mfma_f32_16x16x32_bf16 v[24:27], v[190:193], v[198:201], v[24:27]
	v_mfma_f32_16x16x32_bf16 v[20:23], v[182:185], v[212:215], v[20:23]
	v_mfma_f32_16x16x32_bf16 v[16:19], v[190:193], v[212:215], v[16:19]
	v_mfma_f32_16x16x32_bf16 v[12:15], v[182:185], v[220:223], v[12:15]
	v_mfma_f32_16x16x32_bf16 v[8:11], v[190:193], v[220:223], v[8:11]
	v_mfma_f32_16x16x32_bf16 v[4:7], v[182:185], v[228:231], v[4:7]
	v_mfma_f32_16x16x32_bf16 v[0:3], v[190:193], v[228:231], v[0:3]
	v_mfma_f32_16x16x32_bf16 v[28:31], v[186:189], v[208:211], v[28:31]
	v_mfma_f32_16x16x32_bf16 v[24:27], v[194:197], v[208:211], v[24:27]
	v_mfma_f32_16x16x32_bf16 v[20:23], v[186:189], v[216:219], v[20:23]
	v_mfma_f32_16x16x32_bf16 v[16:19], v[194:197], v[216:219], v[16:19]
	v_mfma_f32_16x16x32_bf16 v[12:15], v[186:189], v[224:227], v[12:15]
	v_mfma_f32_16x16x32_bf16 v[8:11], v[194:197], v[224:227], v[8:11]
	v_lshl_add_u64 v[178:179], v[238:239], 0, s[8:9]
	s_mov_b32 m0, s67
	s_nop 0
	global_load_lds_dwordx4 v[178:179], off
	v_mfma_f32_16x16x32_bf16 v[4:7], v[186:189], v[232:235], v[4:7]
	v_mfma_f32_16x16x32_bf16 v[0:3], v[194:197], v[232:235], v[0:3]
	s_setprio 0
	s_barrier
	s_add_i32 s93, s93, 2
	s_add_u32 s54, s54, 0x100
	s_addc_u32 s55, s55, 0
	s_add_u32 s91, s91, 0x100
	s_addc_u32 s92, s92, 0
.LBB0_417:
	ds_read_b128 v[154:157], v169
	ds_read_b128 v[158:161], v169 offset:1024
	ds_read_b128 v[162:165], v169 offset:2048
	ds_read_b128 v[174:177], v169 offset:3072
	ds_read_b128 v[182:185], v170
	ds_read_b128 v[186:189], v170 offset:1024
	ds_read_b128 v[190:193], v170 offset:2048
	ds_read_b128 v[194:197], v170 offset:3072
	s_add_u32 s3, s54, 0xfffc0080
	s_addc_u32 s14, s55, -1
	s_cmp_eq_u32 s93, 12
	s_cselect_b32 s59, s45, s14
	s_cselect_b32 s58, s89, s3
	s_cselect_b32 s57, s41, s92
	s_cselect_b32 s56, s90, s91
	v_lshl_add_u64 v[178:179], s[54:55], 0, v[146:147]
	s_add_i32 m0, s60, 0xc000
	ds_read_b128 v[198:201], v171
	ds_read_b128 v[208:211], v171 offset:1024
	ds_read_b128 v[212:215], v171 offset:2048
	ds_read_b128 v[216:219], v171 offset:3072
	ds_read_b128 v[220:223], v171 offset:4096
	ds_read_b128 v[224:227], v171 offset:5120
	ds_read_b128 v[228:231], v171 offset:6144
	ds_read_b128 v[232:235], v171 offset:7168
	global_load_lds_dwordx4 v[178:179], off
	v_lshl_add_u64 v[178:179], s[54:55], 0, v[148:149]
	s_add_i32 m0, s60, 0xe000
	s_nop 0
	global_load_lds_dwordx4 v[178:179], off
	s_waitcnt vmcnt(8)
	s_waitcnt lgkmcnt(0)
	s_barrier
; #define PG8_STAGE(bufoff, gbase, voff) do { _Pragma("unroll") for (int _i = 0; _i < 2; ++_i) \
;         __builtin_amdgcn_global_load_lds((const unsigned*)((const char*)(gbase) + (voff)[_i]), (PG8_LAS unsigned*)(lds + (bufoff) + ldsw + _i * 8192), 16, 0, 0); } while (0)
; #define PG8_LDA(dst, b, h) do { _Pragma("unroll") for (int m = 0; m < 4; ++m) _Pragma("unroll") for (int k = 0; k < 2; ++k) dst[m][k] = *(const PG8_LAS bf16x8*)(lds + PG8_SA(b, h) + aoff + m * 2048 + k * 1024); } while (0)
; #define PG8_MMA(ai, bj, At, Bt) do { __builtin_amdgcn_s_setprio(1); _Pragma("unroll") for (int m = 0; m < 4; ++m) _Pragma("unroll") for (int n = 0; n < 2; ++n) _Pragma("unroll") for (int k = 0; k < 2; ++k) \
;         acc[ai][bj][m][n] = __builtin_amdgcn_mfma_f32_16x16x32_bf16(Bt[n][k], At[m][k], acc[ai][bj][m][n], 0, 0, 0); __builtin_amdgcn_s_setprio(0); } while (0)
; #define PG8_WAIT_V(n) asm volatile("s_waitcnt vmcnt(" #n ")" ::: "memory")
; #define PG8_WAIT_L(n) asm volatile("s_waitcnt lgkmcnt(" #n ")" ::: "memory")
; #define PG8_BAR __builtin_amdgcn_s_barrier()
; #define PG8_SCHED __builtin_amdgcn_sched_barrier(0)
; template <class Epi, class Sched, bool ALIGN_EPI = false, bool SP2 = false>
; __device__ __forceinline__ void gemm_phase(PG8_LAS unsigned char* lds, const Gemm g, const Sched& S, const Epi& E) {
;     ...
;             PG8_WAIT_V(8); PG8_WAIT_L(0); PG8_BAR; PG8_MMA(0, 0, At, B0); PG8_MMA(0, 1, At, B1); PG8_BAR; PG8_SCHED;
;             PG8_LDA(At, 0, 1); PG8_STAGE(PG8_SB(0, 0), b2, voffB); PG8_STAGE(PG8_SB(0, 1), b2 + hstep, voffB); PG8_STAGE(PG8_SA(0, 0), a2, voffA);
;             PG8_WAIT_V(8); PG8_WAIT_L(0); PG8_BAR; PG8_MMA(1, 0, At, B0); PG8_MMA(1, 1, At, B1); PG8_BAR; PG8_SCHED;
	s_setprio 1
	s_waitcnt lgkmcnt(0)
	v_mfma_f32_16x16x32_bf16 v[124:127], v[154:157], v[198:201], v[124:127]
	v_mfma_f32_16x16x32_bf16 v[120:123], v[162:165], v[198:201], v[120:123]
	v_mfma_f32_16x16x32_bf16 v[116:119], v[154:157], v[212:215], v[116:119]
	v_mfma_f32_16x16x32_bf16 v[112:115], v[162:165], v[212:215], v[112:115]
	v_mfma_f32_16x16x32_bf16 v[108:111], v[154:157], v[220:223], v[108:111]
	v_mfma_f32_16x16x32_bf16 v[104:107], v[162:165], v[220:223], v[104:107]
	v_mfma_f32_16x16x32_bf16 v[100:103], v[154:157], v[228:231], v[100:103]
	v_mfma_f32_16x16x32_bf16 v[96:99], v[162:165], v[228:231], v[96:99]
	v_mfma_f32_16x16x32_bf16 v[124:127], v[158:161], v[208:211], v[124:127]
	v_mfma_f32_16x16x32_bf16 v[120:123], v[174:177], v[208:211], v[120:123]
	v_mfma_f32_16x16x32_bf16 v[116:119], v[158:161], v[216:219], v[116:119]
	v_mfma_f32_16x16x32_bf16 v[112:115], v[174:177], v[216:219], v[112:115]
	v_mfma_f32_16x16x32_bf16 v[108:111], v[158:161], v[224:227], v[108:111]
	v_mfma_f32_16x16x32_bf16 v[104:107], v[174:177], v[224:227], v[104:107]
	v_mfma_f32_16x16x32_bf16 v[100:103], v[158:161], v[232:235], v[100:103]
	v_mfma_f32_16x16x32_bf16 v[96:99], v[174:177], v[232:235], v[96:99]
	s_setprio 0
	s_setprio 1
	v_mfma_f32_16x16x32_bf16 v[68:71], v[182:185], v[198:201], v[68:71]
	v_mfma_f32_16x16x32_bf16 v[64:67], v[190:193], v[198:201], v[64:67]
	v_mfma_f32_16x16x32_bf16 v[52:55], v[182:185], v[212:215], v[52:55]
	v_mfma_f32_16x16x32_bf16 v[48:51], v[190:193], v[212:215], v[48:51]
	v_mfma_f32_16x16x32_bf16 v[44:47], v[182:185], v[220:223], v[44:47]
	v_mfma_f32_16x16x32_bf16 v[40:43], v[190:193], v[220:223], v[40:43]
	v_mfma_f32_16x16x32_bf16 v[36:39], v[182:185], v[228:231], v[36:39]
	v_mfma_f32_16x16x32_bf16 v[32:35], v[190:193], v[228:231], v[32:35]
	v_mfma_f32_16x16x32_bf16 v[68:71], v[186:189], v[208:211], v[68:71]
	v_mfma_f32_16x16x32_bf16 v[64:67], v[194:197], v[208:211], v[64:67]
	v_mfma_f32_16x16x32_bf16 v[52:55], v[186:189], v[216:219], v[52:55]
	v_mfma_f32_16x16x32_bf16 v[48:51], v[194:197], v[216:219], v[48:51]
	v_mfma_f32_16x16x32_bf16 v[44:47], v[186:189], v[224:227], v[44:47]
	v_mfma_f32_16x16x32_bf16 v[40:43], v[194:197], v[224:227], v[40:43]
	v_mfma_f32_16x16x32_bf16 v[36:39], v[186:189], v[232:235], v[36:39]
	v_mfma_f32_16x16x32_bf16 v[32:35], v[194:197], v[232:235], v[32:35]
	s_setprio 0
	s_barrier
	s_add_i32 s3, s86, s34
	v_lshl_add_u64 v[178:179], s[56:57], 0, v[132:133]
	s_mov_b32 m0, s3
	ds_read_b128 v[198:201], v171 offset:16384
	ds_read_b128 v[208:211], v171 offset:17408
	ds_read_b128 v[212:215], v171 offset:18432
	ds_read_b128 v[216:219], v171 offset:19456
	ds_read_b128 v[220:223], v171 offset:20480
	ds_read_b128 v[224:227], v171 offset:21504
	ds_read_b128 v[228:231], v171 offset:22528
	ds_read_b128 v[232:235], v171 offset:23552
	global_load_lds_dwordx4 v[178:179], off
	s_add_i32 m0, s3, 0x2000
	s_add_u32 s14, s56, 0x40000
	v_lshl_add_u64 v[202:203], s[56:57], 0, v[128:129]
	s_addc_u32 s15, s57, 0
	s_add_i32 s3, s87, s34
	global_load_lds_dwordx4 v[202:203], off
	v_lshl_add_u64 v[236:237], s[14:15], 0, v[132:133]
	s_mov_b32 m0, s3
	global_load_lds_dwordx4 v[236:237], off
	v_lshl_add_u64 v[236:237], s[14:15], 0, v[128:129]
	s_add_i32 m0, s3, 0x2000
	s_nop 0
	global_load_lds_dwordx4 v[236:237], off
	s_waitcnt vmcnt(6)
	s_waitcnt lgkmcnt(0)
	s_barrier
	s_setprio 1
	s_waitcnt lgkmcnt(0)
	v_mfma_f32_16x16x32_bf16 v[92:95], v[154:157], v[198:201], v[92:95]
	v_mfma_f32_16x16x32_bf16 v[88:91], v[162:165], v[198:201], v[88:91]
	v_mfma_f32_16x16x32_bf16 v[84:87], v[154:157], v[212:215], v[84:87]
	v_mfma_f32_16x16x32_bf16 v[80:83], v[162:165], v[212:215], v[80:83]
	v_mfma_f32_16x16x32_bf16 v[76:79], v[154:157], v[220:223], v[76:79]
	v_mfma_f32_16x16x32_bf16 v[72:75], v[162:165], v[220:223], v[72:75]
	v_mfma_f32_16x16x32_bf16 v[60:63], v[154:157], v[228:231], v[60:63]
	v_mfma_f32_16x16x32_bf16 v[56:59], v[162:165], v[228:231], v[56:59]
	v_mfma_f32_16x16x32_bf16 v[92:95], v[158:161], v[208:211], v[92:95]
	v_mfma_f32_16x16x32_bf16 v[88:91], v[174:177], v[208:211], v[88:91]
	v_mfma_f32_16x16x32_bf16 v[84:87], v[158:161], v[216:219], v[84:87]
	v_mfma_f32_16x16x32_bf16 v[80:83], v[174:177], v[216:219], v[80:83]
	v_mfma_f32_16x16x32_bf16 v[76:79], v[158:161], v[224:227], v[76:79]
	v_mfma_f32_16x16x32_bf16 v[72:75], v[174:177], v[224:227], v[72:75]
	v_lshl_add_u64 v[236:237], s[58:59], 0, v[134:135]
	s_mov_b32 m0, s60
	s_nop 0
	global_load_lds_dwordx4 v[236:237], off
	v_mfma_f32_16x16x32_bf16 v[60:63], v[158:161], v[232:235], v[60:63]
	v_mfma_f32_16x16x32_bf16 v[56:59], v[174:177], v[232:235], v[56:59]
	s_setprio 0
	s_setprio 1
	v_mfma_f32_16x16x32_bf16 v[28:31], v[182:185], v[198:201], v[28:31]
	v_mfma_f32_16x16x32_bf16 v[24:27], v[190:193], v[198:201], v[24:27]
	v_mfma_f32_16x16x32_bf16 v[20:23], v[182:185], v[212:215], v[20:23]
	v_mfma_f32_16x16x32_bf16 v[16:19], v[190:193], v[212:215], v[16:19]
	v_mfma_f32_16x16x32_bf16 v[12:15], v[182:185], v[220:223], v[12:15]
	v_mfma_f32_16x16x32_bf16 v[8:11], v[190:193], v[220:223], v[8:11]
	v_mfma_f32_16x16x32_bf16 v[4:7], v[182:185], v[228:231], v[4:7]
	v_mfma_f32_16x16x32_bf16 v[0:3], v[190:193], v[228:231], v[0:3]
	v_mfma_f32_16x16x32_bf16 v[28:31], v[186:189], v[208:211], v[28:31]
	v_mfma_f32_16x16x32_bf16 v[24:27], v[194:197], v[208:211], v[24:27]
	v_mfma_f32_16x16x32_bf16 v[20:23], v[186:189], v[216:219], v[20:23]
	v_mfma_f32_16x16x32_bf16 v[16:19], v[194:197], v[216:219], v[16:19]
	v_mfma_f32_16x16x32_bf16 v[12:15], v[186:189], v[224:227], v[12:15]
	v_mfma_f32_16x16x32_bf16 v[8:11], v[194:197], v[224:227], v[8:11]
	v_lshl_add_u64 v[238:239], s[58:59], 0, v[130:131]
	s_mov_b32 m0, s61
	s_nop 0
	global_load_lds_dwordx4 v[238:239], off
	v_mfma_f32_16x16x32_bf16 v[4:7], v[186:189], v[232:235], v[4:7]
	v_mfma_f32_16x16x32_bf16 v[0:3], v[194:197], v[232:235], v[0:3]
	s_setprio 0
	s_barrier
; #define PG8_STAGE(bufoff, gbase, voff) do { _Pragma("unroll") for (int _i = 0; _i < 2; ++_i) \
;         __builtin_amdgcn_global_load_lds((const unsigned*)((const char*)(gbase) + (voff)[_i]), (PG8_LAS unsigned*)(lds + (bufoff) + ldsw + _i * 8192), 16, 0, 0); } while (0)
; #define PG8_LDA(dst, b, h) do { _Pragma("unroll") for (int m = 0; m < 4; ++m) _Pragma("unroll") for (int k = 0; k < 2; ++k) dst[m][k] = *(const PG8_LAS bf16x8*)(lds + PG8_SA(b, h) + aoff + m * 2048 + k * 1024); } while (0)
; #define PG8_LDB(dst, b, h) do { _Pragma("unroll") for (int n = 0; n < 2; ++n) _Pragma("unroll") for (int k = 0; k < 2; ++k) dst[n][k] = *(const PG8_LAS bf16x8*)(lds + PG8_SB(b, h) + boff + n * 2048 + k * 1024); } while (0)
; #define PG8_MMA(ai, bj, At, Bt) do { __builtin_amdgcn_s_setprio(1); _Pragma("unroll") for (int m = 0; m < 4; ++m) _Pragma("unroll") for (int n = 0; n < 2; ++n) _Pragma("unroll") for (int k = 0; k < 2; ++k) \
;         acc[ai][bj][m][n] = __builtin_amdgcn_mfma_f32_16x16x32_bf16(Bt[n][k], At[m][k], acc[ai][bj][m][n], 0, 0, 0); __builtin_amdgcn_s_setprio(0); } while (0)
; #define PG8_WAIT_V(n) asm volatile("s_waitcnt vmcnt(" #n ")" ::: "memory")
; #define PG8_WAIT_L(n) asm volatile("s_waitcnt lgkmcnt(" #n ")" ::: "memory")
; #define PG8_BAR __builtin_amdgcn_s_barrier()
; #define PG8_SCHED __builtin_amdgcn_sched_barrier(0)
; template <class Epi, class Sched, bool ALIGN_EPI = false, bool SP2 = false>
; __device__ __forceinline__ void gemm_phase(PG8_LAS unsigned char* lds, const Gemm g, const Sched& S, const Epi& E) {
;     ...
;             PG8_LDB(B0, 1, 0); PG8_LDB(B1, 1, 1); PG8_SCHED; PG8_LDA(At, 1, 0); PG8_STAGE(PG8_SA(0, 1), a2 + hstep, voffA);
;             PG8_WAIT_V(8); PG8_WAIT_L(0); PG8_BAR; PG8_MMA(0, 0, At, B0); PG8_MMA(0, 1, At, B1); PG8_BAR; PG8_SCHED;
	s_add_i32 s3, 0, 0x18000
	v_add_u32_e32 v136, s3, v143
	s_add_i32 s33, 0, 0x1c000
	ds_read_b128 v[154:157], v136
	ds_read_b128 v[158:161], v136 offset:1024
	ds_read_b128 v[162:165], v136 offset:2048
	ds_read_b128 v[174:177], v136 offset:3072
	v_add_u32_e32 v136, s33, v143
	ds_read_b128 v[182:185], v136
	ds_read_b128 v[186:189], v136 offset:1024
	ds_read_b128 v[190:193], v136 offset:2048
	ds_read_b128 v[194:197], v136 offset:3072
	s_add_u32 s14, s58, 0x40000
	s_addc_u32 s15, s59, 0
	s_mov_b32 m0, s62
	v_lshl_add_u64 v[240:241], s[14:15], 0, v[134:135]
	ds_read_b128 v[198:201], v171 offset:32768
	ds_read_b128 v[208:211], v171 offset:33792
	ds_read_b128 v[212:215], v171 offset:34816
	ds_read_b128 v[216:219], v171 offset:35840
	ds_read_b128 v[220:223], v171 offset:36864
	ds_read_b128 v[224:227], v171 offset:37888
	ds_read_b128 v[228:231], v171 offset:38912
	ds_read_b128 v[232:235], v171 offset:39936
	global_load_lds_dwordx4 v[240:241], off
	v_lshl_add_u64 v[240:241], s[14:15], 0, v[130:131]
	s_mov_b32 m0, s63
	s_nop 0
	global_load_lds_dwordx4 v[240:241], off
	s_waitcnt vmcnt(8)
	s_waitcnt lgkmcnt(0)
	s_barrier
	s_setprio 1
	s_waitcnt lgkmcnt(0)
	v_mfma_f32_16x16x32_bf16 v[124:127], v[154:157], v[198:201], v[124:127]
	v_mfma_f32_16x16x32_bf16 v[120:123], v[162:165], v[198:201], v[120:123]
	v_mfma_f32_16x16x32_bf16 v[116:119], v[154:157], v[212:215], v[116:119]
	v_mfma_f32_16x16x32_bf16 v[112:115], v[162:165], v[212:215], v[112:115]
	v_mfma_f32_16x16x32_bf16 v[108:111], v[154:157], v[220:223], v[108:111]
	v_mfma_f32_16x16x32_bf16 v[104:107], v[162:165], v[220:223], v[104:107]
	v_mfma_f32_16x16x32_bf16 v[100:103], v[154:157], v[228:231], v[100:103]
	v_mfma_f32_16x16x32_bf16 v[96:99], v[162:165], v[228:231], v[96:99]
	v_mfma_f32_16x16x32_bf16 v[124:127], v[158:161], v[208:211], v[124:127]
	v_mfma_f32_16x16x32_bf16 v[120:123], v[174:177], v[208:211], v[120:123]
	v_mfma_f32_16x16x32_bf16 v[116:119], v[158:161], v[216:219], v[116:119]
	v_mfma_f32_16x16x32_bf16 v[112:115], v[174:177], v[216:219], v[112:115]
	v_mfma_f32_16x16x32_bf16 v[108:111], v[158:161], v[224:227], v[108:111]
	v_mfma_f32_16x16x32_bf16 v[104:107], v[174:177], v[224:227], v[104:107]
	v_mfma_f32_16x16x32_bf16 v[100:103], v[158:161], v[232:235], v[100:103]
	v_mfma_f32_16x16x32_bf16 v[96:99], v[174:177], v[232:235], v[96:99]
	s_setprio 0
	s_setprio 1
	v_mfma_f32_16x16x32_bf16 v[68:71], v[182:185], v[198:201], v[68:71]
	v_mfma_f32_16x16x32_bf16 v[64:67], v[190:193], v[198:201], v[64:67]
	v_mfma_f32_16x16x32_bf16 v[52:55], v[182:185], v[212:215], v[52:55]
	v_mfma_f32_16x16x32_bf16 v[48:51], v[190:193], v[212:215], v[48:51]
	v_mfma_f32_16x16x32_bf16 v[44:47], v[182:185], v[220:223], v[44:47]
	v_mfma_f32_16x16x32_bf16 v[40:43], v[190:193], v[220:223], v[40:43]
	v_mfma_f32_16x16x32_bf16 v[36:39], v[182:185], v[228:231], v[36:39]
	v_mfma_f32_16x16x32_bf16 v[32:35], v[190:193], v[228:231], v[32:35]
	v_mfma_f32_16x16x32_bf16 v[68:71], v[186:189], v[208:211], v[68:71]
	v_mfma_f32_16x16x32_bf16 v[64:67], v[194:197], v[208:211], v[64:67]
	v_mfma_f32_16x16x32_bf16 v[52:55], v[186:189], v[216:219], v[52:55]
	v_mfma_f32_16x16x32_bf16 v[48:51], v[194:197], v[216:219], v[48:51]
	v_mfma_f32_16x16x32_bf16 v[44:47], v[186:189], v[224:227], v[44:47]
	v_mfma_f32_16x16x32_bf16 v[40:43], v[194:197], v[224:227], v[40:43]
	v_mfma_f32_16x16x32_bf16 v[36:39], v[186:189], v[232:235], v[36:39]
	v_mfma_f32_16x16x32_bf16 v[32:35], v[194:197], v[232:235], v[32:35]
	s_setprio 0
	s_barrier
; #define PG8_STAGE(bufoff, gbase, voff) do { _Pragma("unroll") for (int _i = 0; _i < 2; ++_i) \
;         __builtin_amdgcn_global_load_lds((const unsigned*)((const char*)(gbase) + (voff)[_i]), (PG8_LAS unsigned*)(lds + (bufoff) + ldsw + _i * 8192), 16, 0, 0); } while (0)
; #define PG8_LDA(dst, b, h) do { _Pragma("unroll") for (int m = 0; m < 4; ++m) _Pragma("unroll") for (int k = 0; k < 2; ++k) dst[m][k] = *(const PG8_LAS bf16x8*)(lds + PG8_SA(b, h) + aoff + m * 2048 + k * 1024); } while (0)
; #define PG8_MMA(ai, bj, At, Bt) do { __builtin_amdgcn_s_setprio(1); _Pragma("unroll") for (int m = 0; m < 4; ++m) _Pragma("unroll") for (int n = 0; n < 2; ++n) _Pragma("unroll") for (int k = 0; k < 2; ++k) \
;         acc[ai][bj][m][n] = __builtin_amdgcn_mfma_f32_16x16x32_bf16(Bt[n][k], At[m][k], acc[ai][bj][m][n], 0, 0, 0); __builtin_amdgcn_s_setprio(0); } while (0)
; #define PG8_WAIT_V(n) asm volatile("s_waitcnt vmcnt(" #n ")" ::: "memory")
; #define PG8_WAIT_L(n) asm volatile("s_waitcnt lgkmcnt(" #n ")" ::: "memory")
; #define PG8_BAR __builtin_amdgcn_s_barrier()
; #define PG8_SCHED __builtin_amdgcn_sched_barrier(0)
; template <class Epi, class Sched, bool ALIGN_EPI = false, bool SP2 = false>
; __device__ __forceinline__ void gemm_phase(PG8_LAS unsigned char* lds, const Gemm g, const Sched& S, const Epi& E) {
;     ...
;             PG8_LDA(At, 1, 1); PG8_STAGE(PG8_SB(1, 0), b3, voffB); PG8_STAGE(PG8_SB(1, 1), b3 + hstep, voffB); PG8_STAGE(PG8_SA(1, 0), a3, voffA);
;             PG8_WAIT_V(8); PG8_WAIT_L(0); PG8_BAR; PG8_MMA(1, 0, At, B0); PG8_MMA(1, 1, At, B1); PG8_BAR; PG8_SCHED;
	s_add_i32 s3, s3, s34
	v_lshl_add_u64 v[178:179], v[178:179], 0, s[8:9]
	s_mov_b32 m0, s3
	ds_read_b128 v[198:201], v171 offset:49152
	ds_read_b128 v[208:211], v171 offset:50176
	ds_read_b128 v[212:215], v171 offset:51200
	ds_read_b128 v[216:219], v171 offset:52224
	ds_read_b128 v[220:223], v171 offset:53248
	ds_read_b128 v[224:227], v171 offset:54272
	ds_read_b128 v[228:231], v171 offset:55296
	ds_read_b128 v[232:235], v171 offset:56320
	global_load_lds_dwordx4 v[178:179], off
	s_add_i32 m0, s3, 0x2000
	s_add_u32 s14, s56, 0x40080
	v_lshl_add_u64 v[178:179], v[202:203], 0, s[8:9]
	s_addc_u32 s15, s57, 0
	s_add_i32 s3, s33, s34
	global_load_lds_dwordx4 v[178:179], off
	v_lshl_add_u64 v[178:179], s[14:15], 0, v[132:133]
	s_mov_b32 m0, s3
	s_nop 0
	global_load_lds_dwordx4 v[178:179], off
	v_lshl_add_u64 v[178:179], s[14:15], 0, v[128:129]
	s_add_i32 m0, s3, 0x2000
	s_nop 0
	global_load_lds_dwordx4 v[178:179], off
	s_waitcnt vmcnt(6)
	s_waitcnt lgkmcnt(0)
	s_barrier
	s_setprio 1
	s_waitcnt lgkmcnt(0)
	v_mfma_f32_16x16x32_bf16 v[92:95], v[154:157], v[198:201], v[92:95]
	v_mfma_f32_16x16x32_bf16 v[88:91], v[162:165], v[198:201], v[88:91]
	v_mfma_f32_16x16x32_bf16 v[84:87], v[154:157], v[212:215], v[84:87]
	v_mfma_f32_16x16x32_bf16 v[80:83], v[162:165], v[212:215], v[80:83]
	v_mfma_f32_16x16x32_bf16 v[76:79], v[154:157], v[220:223], v[76:79]
	v_mfma_f32_16x16x32_bf16 v[72:75], v[162:165], v[220:223], v[72:75]
	v_mfma_f32_16x16x32_bf16 v[60:63], v[154:157], v[228:231], v[60:63]
	v_mfma_f32_16x16x32_bf16 v[56:59], v[162:165], v[228:231], v[56:59]
	v_mfma_f32_16x16x32_bf16 v[92:95], v[158:161], v[208:211], v[92:95]
	v_mfma_f32_16x16x32_bf16 v[88:91], v[174:177], v[208:211], v[88:91]
	v_mfma_f32_16x16x32_bf16 v[84:87], v[158:161], v[216:219], v[84:87]
	v_mfma_f32_16x16x32_bf16 v[80:83], v[174:177], v[216:219], v[80:83]
	v_mfma_f32_16x16x32_bf16 v[76:79], v[158:161], v[224:227], v[76:79]
	v_mfma_f32_16x16x32_bf16 v[72:75], v[174:177], v[224:227], v[72:75]
	v_lshl_add_u64 v[178:179], v[236:237], 0, s[8:9]
	s_mov_b32 m0, s66
	s_nop 0
	global_load_lds_dwordx4 v[178:179], off
	v_mfma_f32_16x16x32_bf16 v[60:63], v[158:161], v[232:235], v[60:63]
	v_mfma_f32_16x16x32_bf16 v[56:59], v[174:177], v[232:235], v[56:59]
	s_setprio 0
	s_setprio 1
	v_mfma_f32_16x16x32_bf16 v[28:31], v[182:185], v[198:201], v[28:31]
	v_mfma_f32_16x16x32_bf16 v[24:27], v[190:193], v[198:201], v[24:27]
	v_mfma_f32_16x16x32_bf16 v[20:23], v[182:185], v[212:215], v[20:23]
	v_mfma_f32_16x16x32_bf16 v[16:19], v[190:193], v[212:215], v[16:19]
	v_mfma_f32_16x16x32_bf16 v[12:15], v[182:185], v[220:223], v[12:15]
	v_mfma_f32_16x16x32_bf16 v[8:11], v[190:193], v[220:223], v[8:11]
	v_mfma_f32_16x16x32_bf16 v[4:7], v[182:185], v[228:231], v[4:7]
	v_mfma_f32_16x16x32_bf16 v[0:3], v[190:193], v[228:231], v[0:3]
	v_mfma_f32_16x16x32_bf16 v[28:31], v[186:189], v[208:211], v[28:31]
	v_mfma_f32_16x16x32_bf16 v[24:27], v[194:197], v[208:211], v[24:27]
	v_mfma_f32_16x16x32_bf16 v[20:23], v[186:189], v[216:219], v[20:23]
	v_mfma_f32_16x16x32_bf16 v[16:19], v[194:197], v[216:219], v[16:19]
	v_mfma_f32_16x16x32_bf16 v[12:15], v[186:189], v[224:227], v[12:15]
	v_mfma_f32_16x16x32_bf16 v[8:11], v[194:197], v[224:227], v[8:11]
	v_lshl_add_u64 v[178:179], v[238:239], 0, s[8:9]
	s_mov_b32 m0, s67
	s_nop 0
	global_load_lds_dwordx4 v[178:179], off
	v_mfma_f32_16x16x32_bf16 v[4:7], v[186:189], v[232:235], v[4:7]
	v_mfma_f32_16x16x32_bf16 v[0:3], v[194:197], v[232:235], v[0:3]
	s_setprio 0
	s_barrier
	s_add_i32 s93, s93, 2
	s_add_u32 s54, s54, 0x100
	s_addc_u32 s55, s55, 0
	s_add_u32 s91, s91, 0x100
	s_addc_u32 s92, s92, 0
	s_cmp_gt_u32 s93, 13
	s_cbranch_scc0 .LBB0_417
	s_and_b64 vcc, exec, s[10:11]
	s_cbranch_vccz .LBB0_420
	s_barrier

; #define PG8_STAGE(bufoff, gbase, voff) do { _Pragma("unroll") for (int _i = 0; _i < 2; ++_i) \
;         __builtin_amdgcn_global_load_lds((const unsigned*)((const char*)(gbase) + (voff)[_i]), (PG8_LAS unsigned*)(lds + (bufoff) + ldsw + _i * 8192), 16, 0, 0); } while (0)
; #define PG8_LDA(dst, b, h) do { _Pragma("unroll") for (int m = 0; m < 4; ++m) _Pragma("unroll") for (int k = 0; k < 2; ++k) dst[m][k] = *(const PG8_LAS bf16x8*)(lds + PG8_SA(b, h) + aoff + m * 2048 + k * 1024); } while (0)
; #define PG8_LDB(dst, b, h) do { _Pragma("unroll") for (int n = 0; n < 2; ++n) _Pragma("unroll") for (int k = 0; k < 2; ++k) dst[n][k] = *(const PG8_LAS bf16x8*)(lds + PG8_SB(b, h) + boff + n * 2048 + k * 1024); } while (0)
; #define PG8_MMA(ai, bj, At, Bt) do { __builtin_amdgcn_s_setprio(1); _Pragma("unroll") for (int m = 0; m < 4; ++m) _Pragma("unroll") for (int n = 0; n < 2; ++n) _Pragma("unroll") for (int k = 0; k < 2; ++k) \
;         acc[ai][bj][m][n] = __builtin_amdgcn_mfma_f32_16x16x32_bf16(Bt[n][k], At[m][k], acc[ai][bj][m][n], 0, 0, 0); __builtin_amdgcn_s_setprio(0); } while (0)
; #define PG8_BAR __builtin_amdgcn_s_barrier()
; template <class Epi, class Sched, bool ALIGN_EPI = false, bool SP2 = false>
; __device__ __forceinline__ void gemm_phase(PG8_LAS unsigned char* lds, const Gemm g, const Sched& S, const Epi& E) {
;     ...
;         const bool has_next = S.next(ui + 1, nxt);
;         const char* nA = has_next ? (const char*)g.A + (size_t)nxt.pm * tstep : cA; const char* nB = has_next ? (const char*)g.Bt + (size_t)nxt.pn * tstep : cB;
;         for (int t = 0; t < nt; t += 2) {
;             const bool last = (t == nt - 2);
;             const char* a1 = cA + (size_t)(t + 1) * kstep;
;             const char* a2 = last ? nA : cA + (size_t)(t + 2) * kstep; const char* b2 = last ? nB : cB + (size_t)(t + 2) * kstep;
;             const char* a3 = a2 + kstep; const char* b3 = b2 + kstep;
;             if (last && has_next) S.a_ready(nxt);
;             if constexpr (SP2) {
;             PG8_LDB(B0, 0, 0); PG8_LDB(B1, 0, 1); PG8_SCHED; PG8_LDA(At, 0, 0); PG8_STAGE(PG8_SA(1, 1), a1 + hstep, voffA);
;             PG8_WAIT_V(8); PG8_WAIT_L(0); PG8_BAR; PG8_MMA(0, 0, At, B0); PG8_MMA(0, 1, At, B1); PG8_BAR; PG8_SCHED;
;             PG8_LDA(At, 0, 1); PG8_STAGE(PG8_SB(0, 0), b2, voffB); PG8_STAGE(PG8_SB(0, 1), b2 + hstep, voffB); PG8_STAGE(PG8_SA(0, 0), a2, voffA);
.LBB0_458:
	s_ashr_i32 s49, s48, 31
	s_lshl_b64 s[14:15], s[48:49], 19
	s_add_u32 s50, s34, s14
	s_addc_u32 s51, s43, s15
	s_and_b64 s[14:15], s[40:41], exec
	s_cselect_b32 s49, s51, s59
	s_cselect_b32 s55, s50, s58
	s_ashr_i32 s45, s44, 31
	s_lshl_b64 s[14:15], s[44:45], 19
	v_readlane_b32 s3, v250, 13
	s_add_u32 s52, s3, s14
	v_readlane_b32 s3, v250, 14
	s_addc_u32 s53, s3, s15
	s_and_b64 s[14:15], s[40:41], exec
	s_cselect_b32 s45, s53, s61
	s_cselect_b32 s57, s52, s60
	s_add_u32 s58, s58, 0x40080
	s_addc_u32 s59, s59, 0
	s_add_u32 s96, s60, 0x100
	s_addc_u32 s97, s61, 0
	s_mov_b32 vcc_lo, -2
	ds_read_b128 v[170:173], v165
	ds_read_b128 v[174:177], v165 offset:1024
	ds_read_b128 v[182:185], v165 offset:2048
	ds_read_b128 v[186:189], v165 offset:3072
	ds_read_b128 v[190:193], v168
	ds_read_b128 v[194:197], v168 offset:1024
	ds_read_b128 v[198:201], v168 offset:2048
	ds_read_b128 v[208:211], v168 offset:3072
	s_add_u32 s3, s58, 0xfffc0080
	s_addc_u32 s14, s59, -1
	s_cmp_eq_u32 vcc_lo, 12
	s_cselect_b32 s63, s49, s14
	s_cselect_b32 s62, s55, s3
	s_cselect_b32 s61, s45, s97
	s_cselect_b32 s60, s57, s96
	v_lshl_add_u64 v[178:179], s[58:59], 0, v[160:161]
	s_add_i32 m0, s85, 0xc000
	ds_read_b128 v[212:215], v164
	ds_read_b128 v[216:219], v164 offset:1024
	ds_read_b128 v[220:223], v164 offset:2048
	ds_read_b128 v[224:227], v164 offset:3072
	ds_read_b128 v[228:231], v164 offset:4096
	ds_read_b128 v[232:235], v164 offset:5120
	ds_read_b128 v[236:239], v164 offset:6144
	ds_read_b128 v[240:243], v164 offset:7168
	global_load_lds_dwordx4 v[178:179], off
	v_lshl_add_u64 v[178:179], s[58:59], 0, v[162:163]
	s_add_i32 m0, s85, 0xe000
	s_nop 0
	global_load_lds_dwordx4 v[178:179], off
	s_waitcnt vmcnt(8)
	s_waitcnt lgkmcnt(0)
	s_barrier
	s_setprio 1
	s_waitcnt lgkmcnt(0)
	v_mfma_f32_16x16x32_bf16 v[124:127], v[170:173], v[212:215], 0
	v_mfma_f32_16x16x32_bf16 v[120:123], v[182:185], v[212:215], 0
	v_mfma_f32_16x16x32_bf16 v[116:119], v[170:173], v[220:223], 0
	v_mfma_f32_16x16x32_bf16 v[112:115], v[182:185], v[220:223], 0
	v_mfma_f32_16x16x32_bf16 v[108:111], v[170:173], v[228:231], 0
	v_mfma_f32_16x16x32_bf16 v[104:107], v[182:185], v[228:231], 0
	v_mfma_f32_16x16x32_bf16 v[100:103], v[170:173], v[236:239], 0
	v_mfma_f32_16x16x32_bf16 v[96:99], v[182:185], v[236:239], 0
	v_mfma_f32_16x16x32_bf16 v[124:127], v[174:177], v[216:219], v[124:127]
	v_mfma_f32_16x16x32_bf16 v[120:123], v[186:189], v[216:219], v[120:123]
	v_mfma_f32_16x16x32_bf16 v[116:119], v[174:177], v[224:227], v[116:119]
	v_mfma_f32_16x16x32_bf16 v[112:115], v[186:189], v[224:227], v[112:115]
	v_mfma_f32_16x16x32_bf16 v[108:111], v[174:177], v[232:235], v[108:111]
	v_mfma_f32_16x16x32_bf16 v[104:107], v[186:189], v[232:235], v[104:107]
	v_mfma_f32_16x16x32_bf16 v[100:103], v[174:177], v[240:243], v[100:103]
	v_mfma_f32_16x16x32_bf16 v[96:99], v[186:189], v[240:243], v[96:99]
	s_setprio 0
	s_setprio 1
	v_mfma_f32_16x16x32_bf16 v[60:63], v[190:193], v[212:215], 0
	v_mfma_f32_16x16x32_bf16 v[56:59], v[198:201], v[212:215], 0
	v_mfma_f32_16x16x32_bf16 v[52:55], v[190:193], v[220:223], 0
	v_mfma_f32_16x16x32_bf16 v[48:51], v[198:201], v[220:223], 0
	v_mfma_f32_16x16x32_bf16 v[44:47], v[190:193], v[228:231], 0
	v_mfma_f32_16x16x32_bf16 v[40:43], v[198:201], v[228:231], 0
	v_mfma_f32_16x16x32_bf16 v[36:39], v[190:193], v[236:239], 0
	v_mfma_f32_16x16x32_bf16 v[32:35], v[198:201], v[236:239], 0
	v_mfma_f32_16x16x32_bf16 v[60:63], v[194:197], v[216:219], v[60:63]
	v_mfma_f32_16x16x32_bf16 v[56:59], v[208:211], v[216:219], v[56:59]
	v_mfma_f32_16x16x32_bf16 v[52:55], v[194:197], v[224:227], v[52:55]
	v_mfma_f32_16x16x32_bf16 v[48:51], v[208:211], v[224:227], v[48:51]
	v_mfma_f32_16x16x32_bf16 v[44:47], v[194:197], v[232:235], v[44:47]
	v_mfma_f32_16x16x32_bf16 v[40:43], v[208:211], v[232:235], v[40:43]
	v_mfma_f32_16x16x32_bf16 v[36:39], v[194:197], v[240:243], v[36:39]
	v_mfma_f32_16x16x32_bf16 v[32:35], v[208:211], v[240:243], v[32:35]
	s_setprio 0
	s_barrier
	s_add_i32 s3, s94, s84
	v_lshl_add_u64 v[178:179], s[60:61], 0, v[130:131]
	s_mov_b32 m0, s3
	ds_read_b128 v[212:215], v164 offset:16384
	ds_read_b128 v[216:219], v164 offset:17408
	ds_read_b128 v[220:223], v164 offset:18432
	ds_read_b128 v[224:227], v164 offset:19456
	ds_read_b128 v[228:231], v164 offset:20480
	ds_read_b128 v[232:235], v164 offset:21504
	ds_read_b128 v[236:239], v164 offset:22528
	ds_read_b128 v[240:243], v164 offset:23552
	global_load_lds_dwordx4 v[178:179], off
	s_add_i32 m0, s3, 0x2000
	s_add_u32 s14, s60, 0x40000
	v_lshl_add_u64 v[202:203], s[60:61], 0, v[134:135]
	s_addc_u32 s15, s61, 0
	s_add_i32 s3, s95, s84
	global_load_lds_dwordx4 v[202:203], off
	v_lshl_add_u64 v[244:245], s[14:15], 0, v[130:131]
	s_mov_b32 m0, s3
	global_load_lds_dwordx4 v[244:245], off
	v_lshl_add_u64 v[244:245], s[14:15], 0, v[134:135]
	s_add_i32 m0, s3, 0x2000
	s_nop 0
	global_load_lds_dwordx4 v[244:245], off
	s_waitcnt vmcnt(6)
	s_waitcnt lgkmcnt(0)
	s_barrier
; #define PG8_STAGE(bufoff, gbase, voff) do { _Pragma("unroll") for (int _i = 0; _i < 2; ++_i) \
;         __builtin_amdgcn_global_load_lds((const unsigned*)((const char*)(gbase) + (voff)[_i]), (PG8_LAS unsigned*)(lds + (bufoff) + ldsw + _i * 8192), 16, 0, 0); } while (0)
; #define PG8_LDA(dst, b, h) do { _Pragma("unroll") for (int m = 0; m < 4; ++m) _Pragma("unroll") for (int k = 0; k < 2; ++k) dst[m][k] = *(const PG8_LAS bf16x8*)(lds + PG8_SA(b, h) + aoff + m * 2048 + k * 1024); } while (0)
; #define PG8_LDB(dst, b, h) do { _Pragma("unroll") for (int n = 0; n < 2; ++n) _Pragma("unroll") for (int k = 0; k < 2; ++k) dst[n][k] = *(const PG8_LAS bf16x8*)(lds + PG8_SB(b, h) + boff + n * 2048 + k * 1024); } while (0)
; #define PG8_MMA(ai, bj, At, Bt) do { __builtin_amdgcn_s_setprio(1); _Pragma("unroll") for (int m = 0; m < 4; ++m) _Pragma("unroll") for (int n = 0; n < 2; ++n) _Pragma("unroll") for (int k = 0; k < 2; ++k) \
;         acc[ai][bj][m][n] = __builtin_amdgcn_mfma_f32_16x16x32_bf16(Bt[n][k], At[m][k], acc[ai][bj][m][n], 0, 0, 0); __builtin_amdgcn_s_setprio(0); } while (0)
; #define PG8_WAIT_V(n) asm volatile("s_waitcnt vmcnt(" #n ")" ::: "memory")
; #define PG8_WAIT_L(n) asm volatile("s_waitcnt lgkmcnt(" #n ")" ::: "memory")
; #define PG8_BAR __builtin_amdgcn_s_barrier()
; #define PG8_SCHED __builtin_amdgcn_sched_barrier(0)
; template <class Epi, class Sched, bool ALIGN_EPI = false, bool SP2 = false>
; __device__ __forceinline__ void gemm_phase(PG8_LAS unsigned char* lds, const Gemm g, const Sched& S, const Epi& E) {
;     ...
;             PG8_WAIT_V(8); PG8_WAIT_L(0); PG8_BAR; PG8_MMA(1, 0, At, B0); PG8_MMA(1, 1, At, B1); PG8_BAR; PG8_SCHED;
;             PG8_LDB(B0, 1, 0); PG8_LDB(B1, 1, 1); PG8_SCHED; PG8_LDA(At, 1, 0); PG8_STAGE(PG8_SA(0, 1), a2 + hstep, voffA);
;             PG8_WAIT_V(8); PG8_WAIT_L(0); PG8_BAR; PG8_MMA(0, 0, At, B0); PG8_MMA(0, 1, At, B1); PG8_BAR; PG8_SCHED;
	s_setprio 1
	s_waitcnt lgkmcnt(0)
	v_mfma_f32_16x16x32_bf16 v[92:95], v[170:173], v[212:215], 0
	v_mfma_f32_16x16x32_bf16 v[88:91], v[182:185], v[212:215], 0
	v_mfma_f32_16x16x32_bf16 v[84:87], v[170:173], v[220:223], 0
	v_mfma_f32_16x16x32_bf16 v[80:83], v[182:185], v[220:223], 0
	v_mfma_f32_16x16x32_bf16 v[76:79], v[170:173], v[228:231], 0
	v_mfma_f32_16x16x32_bf16 v[72:75], v[182:185], v[228:231], 0
	v_mfma_f32_16x16x32_bf16 v[68:71], v[170:173], v[236:239], 0
	v_mfma_f32_16x16x32_bf16 v[64:67], v[182:185], v[236:239], 0
	v_mfma_f32_16x16x32_bf16 v[92:95], v[174:177], v[216:219], v[92:95]
	v_mfma_f32_16x16x32_bf16 v[88:91], v[186:189], v[216:219], v[88:91]
	v_mfma_f32_16x16x32_bf16 v[84:87], v[174:177], v[224:227], v[84:87]
	v_mfma_f32_16x16x32_bf16 v[80:83], v[186:189], v[224:227], v[80:83]
	v_mfma_f32_16x16x32_bf16 v[76:79], v[174:177], v[232:235], v[76:79]
	v_mfma_f32_16x16x32_bf16 v[72:75], v[186:189], v[232:235], v[72:75]
	v_lshl_add_u64 v[244:245], s[62:63], 0, v[128:129]
	s_mov_b32 m0, s85
	s_nop 0
	global_load_lds_dwordx4 v[244:245], off
	v_mfma_f32_16x16x32_bf16 v[68:71], v[174:177], v[240:243], v[68:71]
	v_mfma_f32_16x16x32_bf16 v[64:67], v[186:189], v[240:243], v[64:67]
	s_setprio 0
	s_setprio 1
	v_mfma_f32_16x16x32_bf16 v[28:31], v[190:193], v[212:215], 0
	v_mfma_f32_16x16x32_bf16 v[24:27], v[198:201], v[212:215], 0
	v_mfma_f32_16x16x32_bf16 v[20:23], v[190:193], v[220:223], 0
	v_mfma_f32_16x16x32_bf16 v[16:19], v[198:201], v[220:223], 0
	v_mfma_f32_16x16x32_bf16 v[12:15], v[190:193], v[228:231], 0
	v_mfma_f32_16x16x32_bf16 v[8:11], v[198:201], v[228:231], 0
	v_mfma_f32_16x16x32_bf16 v[4:7], v[190:193], v[236:239], 0
	v_mfma_f32_16x16x32_bf16 v[0:3], v[198:201], v[236:239], 0
	v_mfma_f32_16x16x32_bf16 v[28:31], v[194:197], v[216:219], v[28:31]
	v_mfma_f32_16x16x32_bf16 v[24:27], v[208:211], v[216:219], v[24:27]
	v_mfma_f32_16x16x32_bf16 v[20:23], v[194:197], v[224:227], v[20:23]
	v_mfma_f32_16x16x32_bf16 v[16:19], v[208:211], v[224:227], v[16:19]
	v_mfma_f32_16x16x32_bf16 v[12:15], v[194:197], v[232:235], v[12:15]
	v_mfma_f32_16x16x32_bf16 v[8:11], v[208:211], v[232:235], v[8:11]
	v_lshl_add_u64 v[246:247], s[62:63], 0, v[132:133]
	s_mov_b32 m0, s86
	s_nop 0
	global_load_lds_dwordx4 v[246:247], off
	v_mfma_f32_16x16x32_bf16 v[4:7], v[194:197], v[240:243], v[4:7]
	v_mfma_f32_16x16x32_bf16 v[0:3], v[208:211], v[240:243], v[0:3]
	s_setprio 0
	s_barrier
	s_add_i32 s3, 0, 0x18000
	v_add_u32_e32 v136, s3, v141
	s_add_i32 s33, 0, 0x1c000
	ds_read_b128 v[170:173], v136
	ds_read_b128 v[174:177], v136 offset:1024
	ds_read_b128 v[182:185], v136 offset:2048
	ds_read_b128 v[186:189], v136 offset:3072
	v_add_u32_e32 v136, s33, v141
	ds_read_b128 v[190:193], v136
	ds_read_b128 v[194:197], v136 offset:1024
	ds_read_b128 v[198:201], v136 offset:2048
	ds_read_b128 v[208:211], v136 offset:3072
	s_add_u32 s14, s62, 0x40000
	s_addc_u32 s15, s63, 0
	s_mov_b32 m0, s87
	v_lshl_add_u64 v[248:249], s[14:15], 0, v[128:129]
	ds_read_b128 v[212:215], v164 offset:32768
	ds_read_b128 v[216:219], v164 offset:33792
	ds_read_b128 v[220:223], v164 offset:34816
	ds_read_b128 v[224:227], v164 offset:35840
	ds_read_b128 v[228:231], v164 offset:36864
	ds_read_b128 v[232:235], v164 offset:37888
	ds_read_b128 v[236:239], v164 offset:38912
	ds_read_b128 v[240:243], v164 offset:39936
	global_load_lds_dwordx4 v[248:249], off
	v_lshl_add_u64 v[248:249], s[14:15], 0, v[132:133]
	s_mov_b32 m0, s88
	s_nop 0
	global_load_lds_dwordx4 v[248:249], off
	s_waitcnt vmcnt(8)
	s_waitcnt lgkmcnt(0)
	s_barrier
	s_setprio 1
	s_waitcnt lgkmcnt(0)
	v_mfma_f32_16x16x32_bf16 v[124:127], v[170:173], v[212:215], v[124:127]
	v_mfma_f32_16x16x32_bf16 v[120:123], v[182:185], v[212:215], v[120:123]
	v_mfma_f32_16x16x32_bf16 v[116:119], v[170:173], v[220:223], v[116:119]
	v_mfma_f32_16x16x32_bf16 v[112:115], v[182:185], v[220:223], v[112:115]
	v_mfma_f32_16x16x32_bf16 v[108:111], v[170:173], v[228:231], v[108:111]
	v_mfma_f32_16x16x32_bf16 v[104:107], v[182:185], v[228:231], v[104:107]
	v_mfma_f32_16x16x32_bf16 v[100:103], v[170:173], v[236:239], v[100:103]
	v_mfma_f32_16x16x32_bf16 v[96:99], v[182:185], v[236:239], v[96:99]
	v_mfma_f32_16x16x32_bf16 v[124:127], v[174:177], v[216:219], v[124:127]
	v_mfma_f32_16x16x32_bf16 v[120:123], v[186:189], v[216:219], v[120:123]
	v_mfma_f32_16x16x32_bf16 v[116:119], v[174:177], v[224:227], v[116:119]
	v_mfma_f32_16x16x32_bf16 v[112:115], v[186:189], v[224:227], v[112:115]
	v_mfma_f32_16x16x32_bf16 v[108:111], v[174:177], v[232:235], v[108:111]
	v_mfma_f32_16x16x32_bf16 v[104:107], v[186:189], v[232:235], v[104:107]
	v_mfma_f32_16x16x32_bf16 v[100:103], v[174:177], v[240:243], v[100:103]
	v_mfma_f32_16x16x32_bf16 v[96:99], v[186:189], v[240:243], v[96:99]
	s_setprio 0
	s_setprio 1
	v_mfma_f32_16x16x32_bf16 v[60:63], v[190:193], v[212:215], v[60:63]
	v_mfma_f32_16x16x32_bf16 v[56:59], v[198:201], v[212:215], v[56:59]
	v_mfma_f32_16x16x32_bf16 v[52:55], v[190:193], v[220:223], v[52:55]
	v_mfma_f32_16x16x32_bf16 v[48:51], v[198:201], v[220:223], v[48:51]
	v_mfma_f32_16x16x32_bf16 v[44:47], v[190:193], v[228:231], v[44:47]
	v_mfma_f32_16x16x32_bf16 v[40:43], v[198:201], v[228:231], v[40:43]
	v_mfma_f32_16x16x32_bf16 v[36:39], v[190:193], v[236:239], v[36:39]
	v_mfma_f32_16x16x32_bf16 v[32:35], v[198:201], v[236:239], v[32:35]
	v_mfma_f32_16x16x32_bf16 v[60:63], v[194:197], v[216:219], v[60:63]
	v_mfma_f32_16x16x32_bf16 v[56:59], v[208:211], v[216:219], v[56:59]
	v_mfma_f32_16x16x32_bf16 v[52:55], v[194:197], v[224:227], v[52:55]
	v_mfma_f32_16x16x32_bf16 v[48:51], v[208:211], v[224:227], v[48:51]
	v_mfma_f32_16x16x32_bf16 v[44:47], v[194:197], v[232:235], v[44:47]
	v_mfma_f32_16x16x32_bf16 v[40:43], v[208:211], v[232:235], v[40:43]
	v_mfma_f32_16x16x32_bf16 v[36:39], v[194:197], v[240:243], v[36:39]
	v_mfma_f32_16x16x32_bf16 v[32:35], v[208:211], v[240:243], v[32:35]
	s_setprio 0
	s_barrier
; #define PG8_STAGE(bufoff, gbase, voff) do { _Pragma("unroll") for (int _i = 0; _i < 2; ++_i) \
;         __builtin_amdgcn_global_load_lds((const unsigned*)((const char*)(gbase) + (voff)[_i]), (PG8_LAS unsigned*)(lds + (bufoff) + ldsw + _i * 8192), 16, 0, 0); } while (0)
; #define PG8_LDA(dst, b, h) do { _Pragma("unroll") for (int m = 0; m < 4; ++m) _Pragma("unroll") for (int k = 0; k < 2; ++k) dst[m][k] = *(const PG8_LAS bf16x8*)(lds + PG8_SA(b, h) + aoff + m * 2048 + k * 1024); } while (0)
; #define PG8_LDB(dst, b, h) do { _Pragma("unroll") for (int n = 0; n < 2; ++n) _Pragma("unroll") for (int k = 0; k < 2; ++k) dst[n][k] = *(const PG8_LAS bf16x8*)(lds + PG8_SB(b, h) + boff + n * 2048 + k * 1024); } while (0)
; #define PG8_MMA(ai, bj, At, Bt) do { __builtin_amdgcn_s_setprio(1); _Pragma("unroll") for (int m = 0; m < 4; ++m) _Pragma("unroll") for (int n = 0; n < 2; ++n) _Pragma("unroll") for (int k = 0; k < 2; ++k) \
;         acc[ai][bj][m][n] = __builtin_amdgcn_mfma_f32_16x16x32_bf16(Bt[n][k], At[m][k], acc[ai][bj][m][n], 0, 0, 0); __builtin_amdgcn_s_setprio(0); } while (0)
; #define PG8_WAIT_V(n) asm volatile("s_waitcnt vmcnt(" #n ")" ::: "memory")
; #define PG8_WAIT_L(n) asm volatile("s_waitcnt lgkmcnt(" #n ")" ::: "memory")
; #define PG8_BAR __builtin_amdgcn_s_barrier()
; #define PG8_SCHED __builtin_amdgcn_sched_barrier(0)
; template <class Epi, class Sched, bool ALIGN_EPI = false, bool SP2 = false>
; __device__ __forceinline__ void gemm_phase(PG8_LAS unsigned char* lds, const Gemm g, const Sched& S, const Epi& E) {
;     ...
;             const bool last = (t == nt - 2);
;             const char* a1 = cA + (size_t)(t + 1) * kstep;
;             const char* a2 = last ? nA : cA + (size_t)(t + 2) * kstep; const char* b2 = last ? nB : cB + (size_t)(t + 2) * kstep;
;             const char* a3 = a2 + kstep; const char* b3 = b2 + kstep;
;             if (last && has_next) S.a_ready(nxt);
;             if constexpr (SP2) {
;             PG8_LDB(B0, 0, 0); PG8_LDB(B1, 0, 1); PG8_SCHED; PG8_LDA(At, 0, 0); PG8_STAGE(PG8_SA(1, 1), a1 + hstep, voffA);
;     ...
;             PG8_LDA(At, 1, 1); PG8_STAGE(PG8_SB(1, 0), b3, voffB); PG8_STAGE(PG8_SB(1, 1), b3 + hstep, voffB); PG8_STAGE(PG8_SA(1, 0), a3, voffA);
;             PG8_WAIT_V(8); PG8_WAIT_L(0); PG8_BAR; PG8_MMA(1, 0, At, B0); PG8_MMA(1, 1, At, B1); PG8_BAR; PG8_SCHED;
	s_add_i32 s3, s3, s84
	v_lshl_add_u64 v[178:179], v[178:179], 0, s[8:9]
	s_mov_b32 m0, s3
	ds_read_b128 v[212:215], v164 offset:49152
	ds_read_b128 v[216:219], v164 offset:50176
	ds_read_b128 v[220:223], v164 offset:51200
	ds_read_b128 v[224:227], v164 offset:52224
	ds_read_b128 v[228:231], v164 offset:53248
	ds_read_b128 v[232:235], v164 offset:54272
	ds_read_b128 v[236:239], v164 offset:55296
	ds_read_b128 v[240:243], v164 offset:56320
	global_load_lds_dwordx4 v[178:179], off
	s_add_i32 m0, s3, 0x2000
	s_add_u32 s14, s60, 0x40080
	v_lshl_add_u64 v[178:179], v[202:203], 0, s[8:9]
	s_addc_u32 s15, s61, 0
	s_add_i32 s3, s33, s84
	global_load_lds_dwordx4 v[178:179], off
	v_lshl_add_u64 v[178:179], s[14:15], 0, v[130:131]
	s_mov_b32 m0, s3
	s_nop 0
	global_load_lds_dwordx4 v[178:179], off
	v_lshl_add_u64 v[178:179], s[14:15], 0, v[134:135]
	s_add_i32 m0, s3, 0x2000
	s_nop 0
	global_load_lds_dwordx4 v[178:179], off
	s_waitcnt vmcnt(6)
	s_waitcnt lgkmcnt(0)
	s_barrier
	s_setprio 1
	s_waitcnt lgkmcnt(0)
	v_mfma_f32_16x16x32_bf16 v[92:95], v[170:173], v[212:215], v[92:95]
	v_mfma_f32_16x16x32_bf16 v[88:91], v[182:185], v[212:215], v[88:91]
	v_mfma_f32_16x16x32_bf16 v[84:87], v[170:173], v[220:223], v[84:87]
	v_mfma_f32_16x16x32_bf16 v[80:83], v[182:185], v[220:223], v[80:83]
	v_mfma_f32_16x16x32_bf16 v[76:79], v[170:173], v[228:231], v[76:79]
	v_mfma_f32_16x16x32_bf16 v[72:75], v[182:185], v[228:231], v[72:75]
	v_mfma_f32_16x16x32_bf16 v[68:71], v[170:173], v[236:239], v[68:71]
	v_mfma_f32_16x16x32_bf16 v[64:67], v[182:185], v[236:239], v[64:67]
	v_mfma_f32_16x16x32_bf16 v[92:95], v[174:177], v[216:219], v[92:95]
	v_mfma_f32_16x16x32_bf16 v[88:91], v[186:189], v[216:219], v[88:91]
	v_mfma_f32_16x16x32_bf16 v[84:87], v[174:177], v[224:227], v[84:87]
	v_mfma_f32_16x16x32_bf16 v[80:83], v[186:189], v[224:227], v[80:83]
	v_mfma_f32_16x16x32_bf16 v[76:79], v[174:177], v[232:235], v[76:79]
	v_mfma_f32_16x16x32_bf16 v[72:75], v[186:189], v[232:235], v[72:75]
	v_lshl_add_u64 v[178:179], v[244:245], 0, s[8:9]
	s_mov_b32 m0, s90
	s_nop 0
	global_load_lds_dwordx4 v[178:179], off
	v_mfma_f32_16x16x32_bf16 v[68:71], v[174:177], v[240:243], v[68:71]
	v_mfma_f32_16x16x32_bf16 v[64:67], v[186:189], v[240:243], v[64:67]
	s_setprio 0
	s_setprio 1
	v_mfma_f32_16x16x32_bf16 v[28:31], v[190:193], v[212:215], v[28:31]
	v_mfma_f32_16x16x32_bf16 v[24:27], v[198:201], v[212:215], v[24:27]
	v_mfma_f32_16x16x32_bf16 v[20:23], v[190:193], v[220:223], v[20:23]
	v_mfma_f32_16x16x32_bf16 v[16:19], v[198:201], v[220:223], v[16:19]
	v_mfma_f32_16x16x32_bf16 v[12:15], v[190:193], v[228:231], v[12:15]
	v_mfma_f32_16x16x32_bf16 v[8:11], v[198:201], v[228:231], v[8:11]
	v_mfma_f32_16x16x32_bf16 v[4:7], v[190:193], v[236:239], v[4:7]
	v_mfma_f32_16x16x32_bf16 v[0:3], v[198:201], v[236:239], v[0:3]
	v_mfma_f32_16x16x32_bf16 v[28:31], v[194:197], v[216:219], v[28:31]
	v_mfma_f32_16x16x32_bf16 v[24:27], v[208:211], v[216:219], v[24:27]
	v_mfma_f32_16x16x32_bf16 v[20:23], v[194:197], v[224:227], v[20:23]
	v_mfma_f32_16x16x32_bf16 v[16:19], v[208:211], v[224:227], v[16:19]
	v_mfma_f32_16x16x32_bf16 v[12:15], v[194:197], v[232:235], v[12:15]
	v_mfma_f32_16x16x32_bf16 v[8:11], v[208:211], v[232:235], v[8:11]
	v_lshl_add_u64 v[178:179], v[246:247], 0, s[8:9]
	s_mov_b32 m0, s91
	s_nop 0
	global_load_lds_dwordx4 v[178:179], off
	v_mfma_f32_16x16x32_bf16 v[4:7], v[194:197], v[240:243], v[4:7]
	v_mfma_f32_16x16x32_bf16 v[0:3], v[208:211], v[240:243], v[0:3]
	s_setprio 0
	s_barrier
	s_add_i32 vcc_lo, vcc_lo, 2
	s_add_u32 s58, s58, 0x100
	s_addc_u32 s59, s59, 0
	s_add_u32 s96, s96, 0x100
	s_addc_u32 s97, s97, 0
.LBB0_459:
	ds_read_b128 v[170:173], v165
	ds_read_b128 v[174:177], v165 offset:1024
	ds_read_b128 v[182:185], v165 offset:2048
	ds_read_b128 v[186:189], v165 offset:3072
	ds_read_b128 v[190:193], v168
	ds_read_b128 v[194:197], v168 offset:1024
	ds_read_b128 v[198:201], v168 offset:2048
	ds_read_b128 v[208:211], v168 offset:3072
	s_add_u32 s3, s58, 0xfffc0080
	s_addc_u32 s14, s59, -1
	s_cmp_eq_u32 vcc_lo, 12
	s_cselect_b32 s63, s49, s14
	s_cselect_b32 s62, s55, s3
	s_cselect_b32 s61, s45, s97
	s_cselect_b32 s60, s57, s96
	v_lshl_add_u64 v[178:179], s[58:59], 0, v[160:161]
	s_add_i32 m0, s85, 0xc000
	ds_read_b128 v[212:215], v164
	ds_read_b128 v[216:219], v164 offset:1024
	ds_read_b128 v[220:223], v164 offset:2048
	ds_read_b128 v[224:227], v164 offset:3072
	ds_read_b128 v[228:231], v164 offset:4096
	ds_read_b128 v[232:235], v164 offset:5120
	ds_read_b128 v[236:239], v164 offset:6144
	ds_read_b128 v[240:243], v164 offset:7168
	global_load_lds_dwordx4 v[178:179], off
	v_lshl_add_u64 v[178:179], s[58:59], 0, v[162:163]
	s_add_i32 m0, s85, 0xe000
	s_nop 0
	global_load_lds_dwordx4 v[178:179], off
	s_waitcnt vmcnt(8)
	s_waitcnt lgkmcnt(0)
	s_barrier
; #define PG8_STAGE(bufoff, gbase, voff) do { _Pragma("unroll") for (int _i = 0; _i < 2; ++_i) \
;         __builtin_amdgcn_global_load_lds((const unsigned*)((const char*)(gbase) + (voff)[_i]), (PG8_LAS unsigned*)(lds + (bufoff) + ldsw + _i * 8192), 16, 0, 0); } while (0)
; #define PG8_LDA(dst, b, h) do { _Pragma("unroll") for (int m = 0; m < 4; ++m) _Pragma("unroll") for (int k = 0; k < 2; ++k) dst[m][k] = *(const PG8_LAS bf16x8*)(lds + PG8_SA(b, h) + aoff + m * 2048 + k * 1024); } while (0)
; #define PG8_MMA(ai, bj, At, Bt) do { __builtin_amdgcn_s_setprio(1); _Pragma("unroll") for (int m = 0; m < 4; ++m) _Pragma("unroll") for (int n = 0; n < 2; ++n) _Pragma("unroll") for (int k = 0; k < 2; ++k) \
;         acc[ai][bj][m][n] = __builtin_amdgcn_mfma_f32_16x16x32_bf16(Bt[n][k], At[m][k], acc[ai][bj][m][n], 0, 0, 0); __builtin_amdgcn_s_setprio(0); } while (0)
; #define PG8_WAIT_V(n) asm volatile("s_waitcnt vmcnt(" #n ")" ::: "memory")
; #define PG8_WAIT_L(n) asm volatile("s_waitcnt lgkmcnt(" #n ")" ::: "memory")
; #define PG8_BAR __builtin_amdgcn_s_barrier()
; #define PG8_SCHED __builtin_amdgcn_sched_barrier(0)
; template <class Epi, class Sched, bool ALIGN_EPI = false, bool SP2 = false>
; __device__ __forceinline__ void gemm_phase(PG8_LAS unsigned char* lds, const Gemm g, const Sched& S, const Epi& E) {
;     ...
;             PG8_WAIT_V(8); PG8_WAIT_L(0); PG8_BAR; PG8_MMA(0, 0, At, B0); PG8_MMA(0, 1, At, B1); PG8_BAR; PG8_SCHED;
;             PG8_LDA(At, 0, 1); PG8_STAGE(PG8_SB(0, 0), b2, voffB); PG8_STAGE(PG8_SB(0, 1), b2 + hstep, voffB); PG8_STAGE(PG8_SA(0, 0), a2, voffA);
;             PG8_WAIT_V(8); PG8_WAIT_L(0); PG8_BAR; PG8_MMA(1, 0, At, B0); PG8_MMA(1, 1, At, B1); PG8_BAR; PG8_SCHED;
	s_setprio 1
	s_waitcnt lgkmcnt(0)
	v_mfma_f32_16x16x32_bf16 v[124:127], v[170:173], v[212:215], v[124:127]
	v_mfma_f32_16x16x32_bf16 v[120:123], v[182:185], v[212:215], v[120:123]
	v_mfma_f32_16x16x32_bf16 v[116:119], v[170:173], v[220:223], v[116:119]
	v_mfma_f32_16x16x32_bf16 v[112:115], v[182:185], v[220:223], v[112:115]
	v_mfma_f32_16x16x32_bf16 v[108:111], v[170:173], v[228:231], v[108:111]
	v_mfma_f32_16x16x32_bf16 v[104:107], v[182:185], v[228:231], v[104:107]
	v_mfma_f32_16x16x32_bf16 v[100:103], v[170:173], v[236:239], v[100:103]
	v_mfma_f32_16x16x32_bf16 v[96:99], v[182:185], v[236:239], v[96:99]
	v_mfma_f32_16x16x32_bf16 v[124:127], v[174:177], v[216:219], v[124:127]
	v_mfma_f32_16x16x32_bf16 v[120:123], v[186:189], v[216:219], v[120:123]
	v_mfma_f32_16x16x32_bf16 v[116:119], v[174:177], v[224:227], v[116:119]
	v_mfma_f32_16x16x32_bf16 v[112:115], v[186:189], v[224:227], v[112:115]
	v_mfma_f32_16x16x32_bf16 v[108:111], v[174:177], v[232:235], v[108:111]
	v_mfma_f32_16x16x32_bf16 v[104:107], v[186:189], v[232:235], v[104:107]
	v_mfma_f32_16x16x32_bf16 v[100:103], v[174:177], v[240:243], v[100:103]
	v_mfma_f32_16x16x32_bf16 v[96:99], v[186:189], v[240:243], v[96:99]
	s_setprio 0
	s_setprio 1
	v_mfma_f32_16x16x32_bf16 v[60:63], v[190:193], v[212:215], v[60:63]
	v_mfma_f32_16x16x32_bf16 v[56:59], v[198:201], v[212:215], v[56:59]
	v_mfma_f32_16x16x32_bf16 v[52:55], v[190:193], v[220:223], v[52:55]
	v_mfma_f32_16x16x32_bf16 v[48:51], v[198:201], v[220:223], v[48:51]
	v_mfma_f32_16x16x32_bf16 v[44:47], v[190:193], v[228:231], v[44:47]
	v_mfma_f32_16x16x32_bf16 v[40:43], v[198:201], v[228:231], v[40:43]
	v_mfma_f32_16x16x32_bf16 v[36:39], v[190:193], v[236:239], v[36:39]
	v_mfma_f32_16x16x32_bf16 v[32:35], v[198:201], v[236:239], v[32:35]
	v_mfma_f32_16x16x32_bf16 v[60:63], v[194:197], v[216:219], v[60:63]
	v_mfma_f32_16x16x32_bf16 v[56:59], v[208:211], v[216:219], v[56:59]
	v_mfma_f32_16x16x32_bf16 v[52:55], v[194:197], v[224:227], v[52:55]
	v_mfma_f32_16x16x32_bf16 v[48:51], v[208:211], v[224:227], v[48:51]
	v_mfma_f32_16x16x32_bf16 v[44:47], v[194:197], v[232:235], v[44:47]
	v_mfma_f32_16x16x32_bf16 v[40:43], v[208:211], v[232:235], v[40:43]
	v_mfma_f32_16x16x32_bf16 v[36:39], v[194:197], v[240:243], v[36:39]
	v_mfma_f32_16x16x32_bf16 v[32:35], v[208:211], v[240:243], v[32:35]
	s_setprio 0
	s_barrier
	s_add_i32 s3, s94, s84
	v_lshl_add_u64 v[178:179], s[60:61], 0, v[130:131]
	s_mov_b32 m0, s3
	ds_read_b128 v[212:215], v164 offset:16384
	ds_read_b128 v[216:219], v164 offset:17408
	ds_read_b128 v[220:223], v164 offset:18432
	ds_read_b128 v[224:227], v164 offset:19456
	ds_read_b128 v[228:231], v164 offset:20480
	ds_read_b128 v[232:235], v164 offset:21504
	ds_read_b128 v[236:239], v164 offset:22528
	ds_read_b128 v[240:243], v164 offset:23552
	global_load_lds_dwordx4 v[178:179], off
	s_add_i32 m0, s3, 0x2000
	s_add_u32 s14, s60, 0x40000
	v_lshl_add_u64 v[202:203], s[60:61], 0, v[134:135]
	s_addc_u32 s15, s61, 0
	s_add_i32 s3, s95, s84
	global_load_lds_dwordx4 v[202:203], off
	v_lshl_add_u64 v[244:245], s[14:15], 0, v[130:131]
	s_mov_b32 m0, s3
	global_load_lds_dwordx4 v[244:245], off
	v_lshl_add_u64 v[244:245], s[14:15], 0, v[134:135]
	s_add_i32 m0, s3, 0x2000
	s_nop 0
	global_load_lds_dwordx4 v[244:245], off
	s_waitcnt vmcnt(6)
	s_waitcnt lgkmcnt(0)
	s_barrier
	s_setprio 1
	s_waitcnt lgkmcnt(0)
	v_mfma_f32_16x16x32_bf16 v[92:95], v[170:173], v[212:215], v[92:95]
	v_mfma_f32_16x16x32_bf16 v[88:91], v[182:185], v[212:215], v[88:91]
	v_mfma_f32_16x16x32_bf16 v[84:87], v[170:173], v[220:223], v[84:87]
	v_mfma_f32_16x16x32_bf16 v[80:83], v[182:185], v[220:223], v[80:83]
	v_mfma_f32_16x16x32_bf16 v[76:79], v[170:173], v[228:231], v[76:79]
	v_mfma_f32_16x16x32_bf16 v[72:75], v[182:185], v[228:231], v[72:75]
	v_mfma_f32_16x16x32_bf16 v[68:71], v[170:173], v[236:239], v[68:71]
	v_mfma_f32_16x16x32_bf16 v[64:67], v[182:185], v[236:239], v[64:67]
	v_mfma_f32_16x16x32_bf16 v[92:95], v[174:177], v[216:219], v[92:95]
	v_mfma_f32_16x16x32_bf16 v[88:91], v[186:189], v[216:219], v[88:91]
	v_mfma_f32_16x16x32_bf16 v[84:87], v[174:177], v[224:227], v[84:87]
	v_mfma_f32_16x16x32_bf16 v[80:83], v[186:189], v[224:227], v[80:83]
	v_mfma_f32_16x16x32_bf16 v[76:79], v[174:177], v[232:235], v[76:79]
	v_mfma_f32_16x16x32_bf16 v[72:75], v[186:189], v[232:235], v[72:75]
	v_lshl_add_u64 v[244:245], s[62:63], 0, v[128:129]
	s_mov_b32 m0, s85
	s_nop 0
	global_load_lds_dwordx4 v[244:245], off
	v_mfma_f32_16x16x32_bf16 v[68:71], v[174:177], v[240:243], v[68:71]
	v_mfma_f32_16x16x32_bf16 v[64:67], v[186:189], v[240:243], v[64:67]
	s_setprio 0
	s_setprio 1
	v_mfma_f32_16x16x32_bf16 v[28:31], v[190:193], v[212:215], v[28:31]
	v_mfma_f32_16x16x32_bf16 v[24:27], v[198:201], v[212:215], v[24:27]
	v_mfma_f32_16x16x32_bf16 v[20:23], v[190:193], v[220:223], v[20:23]
	v_mfma_f32_16x16x32_bf16 v[16:19], v[198:201], v[220:223], v[16:19]
	v_mfma_f32_16x16x32_bf16 v[12:15], v[190:193], v[228:231], v[12:15]
	v_mfma_f32_16x16x32_bf16 v[8:11], v[198:201], v[228:231], v[8:11]
	v_mfma_f32_16x16x32_bf16 v[4:7], v[190:193], v[236:239], v[4:7]
	v_mfma_f32_16x16x32_bf16 v[0:3], v[198:201], v[236:239], v[0:3]
	v_mfma_f32_16x16x32_bf16 v[28:31], v[194:197], v[216:219], v[28:31]
	v_mfma_f32_16x16x32_bf16 v[24:27], v[208:211], v[216:219], v[24:27]
	v_mfma_f32_16x16x32_bf16 v[20:23], v[194:197], v[224:227], v[20:23]
	v_mfma_f32_16x16x32_bf16 v[16:19], v[208:211], v[224:227], v[16:19]
	v_mfma_f32_16x16x32_bf16 v[12:15], v[194:197], v[232:235], v[12:15]
	v_mfma_f32_16x16x32_bf16 v[8:11], v[208:211], v[232:235], v[8:11]
	v_lshl_add_u64 v[246:247], s[62:63], 0, v[132:133]
	s_mov_b32 m0, s86
	s_nop 0
	global_load_lds_dwordx4 v[246:247], off
	v_mfma_f32_16x16x32_bf16 v[4:7], v[194:197], v[240:243], v[4:7]
	v_mfma_f32_16x16x32_bf16 v[0:3], v[208:211], v[240:243], v[0:3]
	s_setprio 0
	s_barrier
; #define PG8_STAGE(bufoff, gbase, voff) do { _Pragma("unroll") for (int _i = 0; _i < 2; ++_i) \
;         __builtin_amdgcn_global_load_lds((const unsigned*)((const char*)(gbase) + (voff)[_i]), (PG8_LAS unsigned*)(lds + (bufoff) + ldsw + _i * 8192), 16, 0, 0); } while (0)
; #define PG8_LDA(dst, b, h) do { _Pragma("unroll") for (int m = 0; m < 4; ++m) _Pragma("unroll") for (int k = 0; k < 2; ++k) dst[m][k] = *(const PG8_LAS bf16x8*)(lds + PG8_SA(b, h) + aoff + m * 2048 + k * 1024); } while (0)
; #define PG8_LDB(dst, b, h) do { _Pragma("unroll") for (int n = 0; n < 2; ++n) _Pragma("unroll") for (int k = 0; k < 2; ++k) dst[n][k] = *(const PG8_LAS bf16x8*)(lds + PG8_SB(b, h) + boff + n * 2048 + k * 1024); } while (0)
; #define PG8_MMA(ai, bj, At, Bt) do { __builtin_amdgcn_s_setprio(1); _Pragma("unroll") for (int m = 0; m < 4; ++m) _Pragma("unroll") for (int n = 0; n < 2; ++n) _Pragma("unroll") for (int k = 0; k < 2; ++k) \
;         acc[ai][bj][m][n] = __builtin_amdgcn_mfma_f32_16x16x32_bf16(Bt[n][k], At[m][k], acc[ai][bj][m][n], 0, 0, 0); __builtin_amdgcn_s_setprio(0); } while (0)
; #define PG8_WAIT_V(n) asm volatile("s_waitcnt vmcnt(" #n ")" ::: "memory")
; #define PG8_WAIT_L(n) asm volatile("s_waitcnt lgkmcnt(" #n ")" ::: "memory")
; #define PG8_BAR __builtin_amdgcn_s_barrier()
; #define PG8_SCHED __builtin_amdgcn_sched_barrier(0)
; template <class Epi, class Sched, bool ALIGN_EPI = false, bool SP2 = false>
; __device__ __forceinline__ void gemm_phase(PG8_LAS unsigned char* lds, const Gemm g, const Sched& S, const Epi& E) {
;     ...
;             PG8_LDB(B0, 1, 0); PG8_LDB(B1, 1, 1); PG8_SCHED; PG8_LDA(At, 1, 0); PG8_STAGE(PG8_SA(0, 1), a2 + hstep, voffA);
;             PG8_WAIT_V(8); PG8_WAIT_L(0); PG8_BAR; PG8_MMA(0, 0, At, B0); PG8_MMA(0, 1, At, B1); PG8_BAR; PG8_SCHED;
	s_add_i32 s3, 0, 0x18000
	v_add_u32_e32 v136, s3, v141
	s_add_i32 s33, 0, 0x1c000
	ds_read_b128 v[170:173], v136
	ds_read_b128 v[174:177], v136 offset:1024
	ds_read_b128 v[182:185], v136 offset:2048
	ds_read_b128 v[186:189], v136 offset:3072
	v_add_u32_e32 v136, s33, v141
	ds_read_b128 v[190:193], v136
	ds_read_b128 v[194:197], v136 offset:1024
	ds_read_b128 v[198:201], v136 offset:2048
	ds_read_b128 v[208:211], v136 offset:3072
	s_add_u32 s14, s62, 0x40000
	s_addc_u32 s15, s63, 0
	s_mov_b32 m0, s87
	v_lshl_add_u64 v[248:249], s[14:15], 0, v[128:129]
	ds_read_b128 v[212:215], v164 offset:32768
	ds_read_b128 v[216:219], v164 offset:33792
	ds_read_b128 v[220:223], v164 offset:34816
	ds_read_b128 v[224:227], v164 offset:35840
	ds_read_b128 v[228:231], v164 offset:36864
	ds_read_b128 v[232:235], v164 offset:37888
	ds_read_b128 v[236:239], v164 offset:38912
	ds_read_b128 v[240:243], v164 offset:39936
	global_load_lds_dwordx4 v[248:249], off
	v_lshl_add_u64 v[248:249], s[14:15], 0, v[132:133]
	s_mov_b32 m0, s88
	s_nop 0
	global_load_lds_dwordx4 v[248:249], off
	s_waitcnt vmcnt(8)
	s_waitcnt lgkmcnt(0)
	s_barrier
	s_setprio 1
	s_waitcnt lgkmcnt(0)
	v_mfma_f32_16x16x32_bf16 v[124:127], v[170:173], v[212:215], v[124:127]
	v_mfma_f32_16x16x32_bf16 v[120:123], v[182:185], v[212:215], v[120:123]
	v_mfma_f32_16x16x32_bf16 v[116:119], v[170:173], v[220:223], v[116:119]
	v_mfma_f32_16x16x32_bf16 v[112:115], v[182:185], v[220:223], v[112:115]
	v_mfma_f32_16x16x32_bf16 v[108:111], v[170:173], v[228:231], v[108:111]
	v_mfma_f32_16x16x32_bf16 v[104:107], v[182:185], v[228:231], v[104:107]
	v_mfma_f32_16x16x32_bf16 v[100:103], v[170:173], v[236:239], v[100:103]
	v_mfma_f32_16x16x32_bf16 v[96:99], v[182:185], v[236:239], v[96:99]
	v_mfma_f32_16x16x32_bf16 v[124:127], v[174:177], v[216:219], v[124:127]
	v_mfma_f32_16x16x32_bf16 v[120:123], v[186:189], v[216:219], v[120:123]
	v_mfma_f32_16x16x32_bf16 v[116:119], v[174:177], v[224:227], v[116:119]
	v_mfma_f32_16x16x32_bf16 v[112:115], v[186:189], v[224:227], v[112:115]
	v_mfma_f32_16x16x32_bf16 v[108:111], v[174:177], v[232:235], v[108:111]
	v_mfma_f32_16x16x32_bf16 v[104:107], v[186:189], v[232:235], v[104:107]
	v_mfma_f32_16x16x32_bf16 v[100:103], v[174:177], v[240:243], v[100:103]
	v_mfma_f32_16x16x32_bf16 v[96:99], v[186:189], v[240:243], v[96:99]
	s_setprio 0
	s_setprio 1
	v_mfma_f32_16x16x32_bf16 v[60:63], v[190:193], v[212:215], v[60:63]
	v_mfma_f32_16x16x32_bf16 v[56:59], v[198:201], v[212:215], v[56:59]
	v_mfma_f32_16x16x32_bf16 v[52:55], v[190:193], v[220:223], v[52:55]
	v_mfma_f32_16x16x32_bf16 v[48:51], v[198:201], v[220:223], v[48:51]
	v_mfma_f32_16x16x32_bf16 v[44:47], v[190:193], v[228:231], v[44:47]
	v_mfma_f32_16x16x32_bf16 v[40:43], v[198:201], v[228:231], v[40:43]
	v_mfma_f32_16x16x32_bf16 v[36:39], v[190:193], v[236:239], v[36:39]
	v_mfma_f32_16x16x32_bf16 v[32:35], v[198:201], v[236:239], v[32:35]
	v_mfma_f32_16x16x32_bf16 v[60:63], v[194:197], v[216:219], v[60:63]
	v_mfma_f32_16x16x32_bf16 v[56:59], v[208:211], v[216:219], v[56:59]
	v_mfma_f32_16x16x32_bf16 v[52:55], v[194:197], v[224:227], v[52:55]
	v_mfma_f32_16x16x32_bf16 v[48:51], v[208:211], v[224:227], v[48:51]
	v_mfma_f32_16x16x32_bf16 v[44:47], v[194:197], v[232:235], v[44:47]
	v_mfma_f32_16x16x32_bf16 v[40:43], v[208:211], v[232:235], v[40:43]
	v_mfma_f32_16x16x32_bf16 v[36:39], v[194:197], v[240:243], v[36:39]
	v_mfma_f32_16x16x32_bf16 v[32:35], v[208:211], v[240:243], v[32:35]
	s_setprio 0
	s_barrier
; #define PG8_STAGE(bufoff, gbase, voff) do { _Pragma("unroll") for (int _i = 0; _i < 2; ++_i) \
;         __builtin_amdgcn_global_load_lds((const unsigned*)((const char*)(gbase) + (voff)[_i]), (PG8_LAS unsigned*)(lds + (bufoff) + ldsw + _i * 8192), 16, 0, 0); } while (0)
; #define PG8_LDA(dst, b, h) do { _Pragma("unroll") for (int m = 0; m < 4; ++m) _Pragma("unroll") for (int k = 0; k < 2; ++k) dst[m][k] = *(const PG8_LAS bf16x8*)(lds + PG8_SA(b, h) + aoff + m * 2048 + k * 1024); } while (0)
; #define PG8_MMA(ai, bj, At, Bt) do { __builtin_amdgcn_s_setprio(1); _Pragma("unroll") for (int m = 0; m < 4; ++m) _Pragma("unroll") for (int n = 0; n < 2; ++n) _Pragma("unroll") for (int k = 0; k < 2; ++k) \
;         acc[ai][bj][m][n] = __builtin_amdgcn_mfma_f32_16x16x32_bf16(Bt[n][k], At[m][k], acc[ai][bj][m][n], 0, 0, 0); __builtin_amdgcn_s_setprio(0); } while (0)
; #define PG8_WAIT_V(n) asm volatile("s_waitcnt vmcnt(" #n ")" ::: "memory")
; #define PG8_WAIT_L(n) asm volatile("s_waitcnt lgkmcnt(" #n ")" ::: "memory")
; #define PG8_BAR __builtin_amdgcn_s_barrier()
; #define PG8_SCHED __builtin_amdgcn_sched_barrier(0)
; template <class Epi, class Sched, bool ALIGN_EPI = false, bool SP2 = false>
; __device__ __forceinline__ void gemm_phase(PG8_LAS unsigned char* lds, const Gemm g, const Sched& S, const Epi& E) {
;     ...
;             PG8_LDA(At, 1, 1); PG8_STAGE(PG8_SB(1, 0), b3, voffB); PG8_STAGE(PG8_SB(1, 1), b3 + hstep, voffB); PG8_STAGE(PG8_SA(1, 0), a3, voffA);
;             PG8_WAIT_V(8); PG8_WAIT_L(0); PG8_BAR; PG8_MMA(1, 0, At, B0); PG8_MMA(1, 1, At, B1); PG8_BAR; PG8_SCHED;
	s_add_i32 s3, s3, s84
	v_lshl_add_u64 v[178:179], v[178:179], 0, s[8:9]
	s_mov_b32 m0, s3
	ds_read_b128 v[212:215], v164 offset:49152
	ds_read_b128 v[216:219], v164 offset:50176
	ds_read_b128 v[220:223], v164 offset:51200
	ds_read_b128 v[224:227], v164 offset:52224
	ds_read_b128 v[228:231], v164 offset:53248
	ds_read_b128 v[232:235], v164 offset:54272
	ds_read_b128 v[236:239], v164 offset:55296
	ds_read_b128 v[240:243], v164 offset:56320
	global_load_lds_dwordx4 v[178:179], off
	s_add_i32 m0, s3, 0x2000
	s_add_u32 s14, s60, 0x40080
	v_lshl_add_u64 v[178:179], v[202:203], 0, s[8:9]
	s_addc_u32 s15, s61, 0
	s_add_i32 s3, s33, s84
	global_load_lds_dwordx4 v[178:179], off
	v_lshl_add_u64 v[178:179], s[14:15], 0, v[130:131]
	s_mov_b32 m0, s3
	s_nop 0
	global_load_lds_dwordx4 v[178:179], off
	v_lshl_add_u64 v[178:179], s[14:15], 0, v[134:135]
	s_add_i32 m0, s3, 0x2000
	s_nop 0
	global_load_lds_dwordx4 v[178:179], off
	s_waitcnt vmcnt(6)
	s_waitcnt lgkmcnt(0)
	s_barrier
	s_setprio 1
	s_waitcnt lgkmcnt(0)
	v_mfma_f32_16x16x32_bf16 v[92:95], v[170:173], v[212:215], v[92:95]
	v_mfma_f32_16x16x32_bf16 v[88:91], v[182:185], v[212:215], v[88:91]
	v_mfma_f32_16x16x32_bf16 v[84:87], v[170:173], v[220:223], v[84:87]
	v_mfma_f32_16x16x32_bf16 v[80:83], v[182:185], v[220:223], v[80:83]
	v_mfma_f32_16x16x32_bf16 v[76:79], v[170:173], v[228:231], v[76:79]
	v_mfma_f32_16x16x32_bf16 v[72:75], v[182:185], v[228:231], v[72:75]
	v_mfma_f32_16x16x32_bf16 v[68:71], v[170:173], v[236:239], v[68:71]
	v_mfma_f32_16x16x32_bf16 v[64:67], v[182:185], v[236:239], v[64:67]
	v_mfma_f32_16x16x32_bf16 v[92:95], v[174:177], v[216:219], v[92:95]
	v_mfma_f32_16x16x32_bf16 v[88:91], v[186:189], v[216:219], v[88:91]
	v_mfma_f32_16x16x32_bf16 v[84:87], v[174:177], v[224:227], v[84:87]
	v_mfma_f32_16x16x32_bf16 v[80:83], v[186:189], v[224:227], v[80:83]
	v_mfma_f32_16x16x32_bf16 v[76:79], v[174:177], v[232:235], v[76:79]
	v_mfma_f32_16x16x32_bf16 v[72:75], v[186:189], v[232:235], v[72:75]
	v_lshl_add_u64 v[178:179], v[244:245], 0, s[8:9]
	s_mov_b32 m0, s90
	s_nop 0
	global_load_lds_dwordx4 v[178:179], off
	v_mfma_f32_16x16x32_bf16 v[68:71], v[174:177], v[240:243], v[68:71]
	v_mfma_f32_16x16x32_bf16 v[64:67], v[186:189], v[240:243], v[64:67]
	s_setprio 0
	s_setprio 1
	v_mfma_f32_16x16x32_bf16 v[28:31], v[190:193], v[212:215], v[28:31]
	v_mfma_f32_16x16x32_bf16 v[24:27], v[198:201], v[212:215], v[24:27]
	v_mfma_f32_16x16x32_bf16 v[20:23], v[190:193], v[220:223], v[20:23]
	v_mfma_f32_16x16x32_bf16 v[16:19], v[198:201], v[220:223], v[16:19]
	v_mfma_f32_16x16x32_bf16 v[12:15], v[190:193], v[228:231], v[12:15]
	v_mfma_f32_16x16x32_bf16 v[8:11], v[198:201], v[228:231], v[8:11]
	v_mfma_f32_16x16x32_bf16 v[4:7], v[190:193], v[236:239], v[4:7]
	v_mfma_f32_16x16x32_bf16 v[0:3], v[198:201], v[236:239], v[0:3]
	v_mfma_f32_16x16x32_bf16 v[28:31], v[194:197], v[216:219], v[28:31]
	v_mfma_f32_16x16x32_bf16 v[24:27], v[208:211], v[216:219], v[24:27]
	v_mfma_f32_16x16x32_bf16 v[20:23], v[194:197], v[224:227], v[20:23]
	v_mfma_f32_16x16x32_bf16 v[16:19], v[208:211], v[224:227], v[16:19]
	v_mfma_f32_16x16x32_bf16 v[12:15], v[194:197], v[232:235], v[12:15]
	v_mfma_f32_16x16x32_bf16 v[8:11], v[208:211], v[232:235], v[8:11]
	v_lshl_add_u64 v[178:179], v[246:247], 0, s[8:9]
	s_mov_b32 m0, s91
	s_nop 0
	global_load_lds_dwordx4 v[178:179], off
	v_mfma_f32_16x16x32_bf16 v[4:7], v[194:197], v[240:243], v[4:7]
	v_mfma_f32_16x16x32_bf16 v[0:3], v[208:211], v[240:243], v[0:3]
	s_setprio 0
	s_barrier
	s_add_i32 vcc_lo, vcc_lo, 2
	s_add_u32 s58, s58, 0x100
	s_addc_u32 s59, s59, 0
	s_add_u32 s96, s96, 0x100
	s_addc_u32 s97, s97, 0
	s_cmp_gt_u32 vcc_lo, 13
	s_cbranch_scc0 .LBB0_459
	s_and_b64 vcc, exec, s[10:11]
	s_cbranch_vccz .LBB0_462
	s_barrier

; #define PG8_STAGE(bufoff, gbase, voff) do { _Pragma("unroll") for (int _i = 0; _i < 2; ++_i) \
;         __builtin_amdgcn_global_load_lds((const unsigned*)((const char*)(gbase) + (voff)[_i]), (PG8_LAS unsigned*)(lds + (bufoff) + ldsw + _i * 8192), 16, 0, 0); } while (0)
; #define PG8_LDA(dst, b, h) do { _Pragma("unroll") for (int m = 0; m < 4; ++m) _Pragma("unroll") for (int k = 0; k < 2; ++k) dst[m][k] = *(const PG8_LAS bf16x8*)(lds + PG8_SA(b, h) + aoff + m * 2048 + k * 1024); } while (0)
; #define PG8_LDB(dst, b, h) do { _Pragma("unroll") for (int n = 0; n < 2; ++n) _Pragma("unroll") for (int k = 0; k < 2; ++k) dst[n][k] = *(const PG8_LAS bf16x8*)(lds + PG8_SB(b, h) + boff + n * 2048 + k * 1024); } while (0)
; #define PG8_MMA(ai, bj, At, Bt) do { __builtin_amdgcn_s_setprio(1); _Pragma("unroll") for (int m = 0; m < 4; ++m) _Pragma("unroll") for (int n = 0; n < 2; ++n) _Pragma("unroll") for (int k = 0; k < 2; ++k) \
;         acc[ai][bj][m][n] = __builtin_amdgcn_mfma_f32_16x16x32_bf16(Bt[n][k], At[m][k], acc[ai][bj][m][n], 0, 0, 0); __builtin_amdgcn_s_setprio(0); } while (0)
; #define PG8_WAIT_V(n) asm volatile("s_waitcnt vmcnt(" #n ")" ::: "memory")
; #define PG8_WAIT_L(n) asm volatile("s_waitcnt lgkmcnt(" #n ")" ::: "memory")
; #define PG8_BAR __builtin_amdgcn_s_barrier()
; #define PG8_SCHED __builtin_amdgcn_sched_barrier(0)
; template <class Epi, class Sched, bool ALIGN_EPI = false, bool SP2 = false>
; __device__ __forceinline__ void gemm_phase(PG8_LAS unsigned char* lds, const Gemm g, const Sched& S, const Epi& E) {
;     ...
;             const bool last = (t == nt - 2);
;             const char* a1 = cA + (size_t)(t + 1) * kstep;
;             const char* a2 = last ? nA : cA + (size_t)(t + 2) * kstep; const char* b2 = last ? nB : cB + (size_t)(t + 2) * kstep;
;             const char* a3 = a2 + kstep; const char* b3 = b2 + kstep;
;             if (last && has_next) S.a_ready(nxt);
;             if constexpr (SP2) {
;             PG8_LDB(B0, 0, 0); PG8_LDB(B1, 0, 1); PG8_SCHED; PG8_LDA(At, 0, 0); PG8_STAGE(PG8_SA(1, 1), a1 + hstep, voffA);
;             PG8_WAIT_V(8); PG8_WAIT_L(0); PG8_BAR; PG8_MMA(0, 0, At, B0); PG8_MMA(0, 1, At, B1); PG8_BAR; PG8_SCHED;
;             PG8_LDA(At, 0, 1); PG8_STAGE(PG8_SB(0, 0), b2, voffB); PG8_STAGE(PG8_SB(0, 1), b2 + hstep, voffB); PG8_STAGE(PG8_SA(0, 0), a2, voffA);
.LBB0_495:
	ds_read_b128 v[170:173], v165
	ds_read_b128 v[174:177], v165 offset:1024
	ds_read_b128 v[182:185], v165 offset:2048
	ds_read_b128 v[186:189], v165 offset:3072
	ds_read_b128 v[190:193], v168
	ds_read_b128 v[194:197], v168 offset:1024
	ds_read_b128 v[198:201], v168 offset:2048
	ds_read_b128 v[208:211], v168 offset:3072
	s_add_u32 s3, s60, 0xfffc0080
	s_addc_u32 s14, s61, -1
	s_cmp_eq_u32 s97, 12
	s_cselect_b32 s65, s49, s14
	s_cselect_b32 s64, s57, s3
	s_cselect_b32 s63, s45, s96
	s_cselect_b32 s62, s94, s95
	v_lshl_add_u64 v[178:179], s[60:61], 0, v[160:161]
	s_add_i32 m0, s59, 0xc000
	ds_read_b128 v[212:215], v164
	ds_read_b128 v[216:219], v164 offset:1024
	ds_read_b128 v[220:223], v164 offset:2048
	ds_read_b128 v[224:227], v164 offset:3072
	ds_read_b128 v[228:231], v164 offset:4096
	ds_read_b128 v[232:235], v164 offset:5120
	ds_read_b128 v[236:239], v164 offset:6144
	ds_read_b128 v[240:243], v164 offset:7168
	global_load_lds_dwordx4 v[178:179], off
	v_lshl_add_u64 v[178:179], s[60:61], 0, v[162:163]
	s_add_i32 m0, s59, 0xe000
	s_nop 0
	global_load_lds_dwordx4 v[178:179], off
	s_waitcnt vmcnt(8)
	s_waitcnt lgkmcnt(0)
	s_barrier
	s_setprio 1
	s_waitcnt lgkmcnt(0)
	v_mfma_f32_16x16x32_bf16 v[124:127], v[170:173], v[212:215], v[124:127]
	v_mfma_f32_16x16x32_bf16 v[120:123], v[182:185], v[212:215], v[120:123]
	v_mfma_f32_16x16x32_bf16 v[116:119], v[170:173], v[220:223], v[116:119]
	v_mfma_f32_16x16x32_bf16 v[112:115], v[182:185], v[220:223], v[112:115]
	v_mfma_f32_16x16x32_bf16 v[108:111], v[170:173], v[228:231], v[108:111]
	v_mfma_f32_16x16x32_bf16 v[104:107], v[182:185], v[228:231], v[104:107]
	v_mfma_f32_16x16x32_bf16 v[100:103], v[170:173], v[236:239], v[100:103]
	v_mfma_f32_16x16x32_bf16 v[96:99], v[182:185], v[236:239], v[96:99]
	v_mfma_f32_16x16x32_bf16 v[124:127], v[174:177], v[216:219], v[124:127]
	v_mfma_f32_16x16x32_bf16 v[120:123], v[186:189], v[216:219], v[120:123]
	v_mfma_f32_16x16x32_bf16 v[116:119], v[174:177], v[224:227], v[116:119]
	v_mfma_f32_16x16x32_bf16 v[112:115], v[186:189], v[224:227], v[112:115]
	v_mfma_f32_16x16x32_bf16 v[108:111], v[174:177], v[232:235], v[108:111]
	v_mfma_f32_16x16x32_bf16 v[104:107], v[186:189], v[232:235], v[104:107]
	v_mfma_f32_16x16x32_bf16 v[100:103], v[174:177], v[240:243], v[100:103]
	v_mfma_f32_16x16x32_bf16 v[96:99], v[186:189], v[240:243], v[96:99]
	s_setprio 0
	s_setprio 1
	v_mfma_f32_16x16x32_bf16 v[60:63], v[190:193], v[212:215], v[60:63]
	v_mfma_f32_16x16x32_bf16 v[56:59], v[198:201], v[212:215], v[56:59]
	v_mfma_f32_16x16x32_bf16 v[52:55], v[190:193], v[220:223], v[52:55]
	v_mfma_f32_16x16x32_bf16 v[48:51], v[198:201], v[220:223], v[48:51]
	v_mfma_f32_16x16x32_bf16 v[44:47], v[190:193], v[228:231], v[44:47]
	v_mfma_f32_16x16x32_bf16 v[40:43], v[198:201], v[228:231], v[40:43]
	v_mfma_f32_16x16x32_bf16 v[36:39], v[190:193], v[236:239], v[36:39]
	v_mfma_f32_16x16x32_bf16 v[32:35], v[198:201], v[236:239], v[32:35]
	v_mfma_f32_16x16x32_bf16 v[60:63], v[194:197], v[216:219], v[60:63]
	v_mfma_f32_16x16x32_bf16 v[56:59], v[208:211], v[216:219], v[56:59]
	v_mfma_f32_16x16x32_bf16 v[52:55], v[194:197], v[224:227], v[52:55]
	v_mfma_f32_16x16x32_bf16 v[48:51], v[208:211], v[224:227], v[48:51]
	v_mfma_f32_16x16x32_bf16 v[44:47], v[194:197], v[232:235], v[44:47]
	v_mfma_f32_16x16x32_bf16 v[40:43], v[208:211], v[232:235], v[40:43]
	v_mfma_f32_16x16x32_bf16 v[36:39], v[194:197], v[240:243], v[36:39]
	v_mfma_f32_16x16x32_bf16 v[32:35], v[208:211], v[240:243], v[32:35]
	s_setprio 0
	s_barrier
	s_add_i32 s3, s92, s75
	v_lshl_add_u64 v[178:179], s[62:63], 0, v[130:131]
	s_mov_b32 m0, s3
	ds_read_b128 v[212:215], v164 offset:16384
	ds_read_b128 v[216:219], v164 offset:17408
	ds_read_b128 v[220:223], v164 offset:18432
	ds_read_b128 v[224:227], v164 offset:19456
	ds_read_b128 v[228:231], v164 offset:20480
	ds_read_b128 v[232:235], v164 offset:21504
	ds_read_b128 v[236:239], v164 offset:22528
	ds_read_b128 v[240:243], v164 offset:23552
	global_load_lds_dwordx4 v[178:179], off
	s_add_i32 m0, s3, 0x2000
	s_add_u32 s14, s62, 0x40000
	v_lshl_add_u64 v[202:203], s[62:63], 0, v[134:135]
	s_addc_u32 s15, s63, 0
	s_add_i32 s3, s93, s75
	global_load_lds_dwordx4 v[202:203], off
	v_lshl_add_u64 v[244:245], s[14:15], 0, v[130:131]
	s_mov_b32 m0, s3
	global_load_lds_dwordx4 v[244:245], off
	v_lshl_add_u64 v[244:245], s[14:15], 0, v[134:135]
	s_add_i32 m0, s3, 0x2000
	s_nop 0
	global_load_lds_dwordx4 v[244:245], off
	s_waitcnt vmcnt(6)
	s_waitcnt lgkmcnt(0)
	s_barrier
; #define PG8_STAGE(bufoff, gbase, voff) do { _Pragma("unroll") for (int _i = 0; _i < 2; ++_i) \
;         __builtin_amdgcn_global_load_lds((const unsigned*)((const char*)(gbase) + (voff)[_i]), (PG8_LAS unsigned*)(lds + (bufoff) + ldsw + _i * 8192), 16, 0, 0); } while (0)
; #define PG8_LDA(dst, b, h) do { _Pragma("unroll") for (int m = 0; m < 4; ++m) _Pragma("unroll") for (int k = 0; k < 2; ++k) dst[m][k] = *(const PG8_LAS bf16x8*)(lds + PG8_SA(b, h) + aoff + m * 2048 + k * 1024); } while (0)
; #define PG8_LDB(dst, b, h) do { _Pragma("unroll") for (int n = 0; n < 2; ++n) _Pragma("unroll") for (int k = 0; k < 2; ++k) dst[n][k] = *(const PG8_LAS bf16x8*)(lds + PG8_SB(b, h) + boff + n * 2048 + k * 1024); } while (0)
; #define PG8_MMA(ai, bj, At, Bt) do { __builtin_amdgcn_s_setprio(1); _Pragma("unroll") for (int m = 0; m < 4; ++m) _Pragma("unroll") for (int n = 0; n < 2; ++n) _Pragma("unroll") for (int k = 0; k < 2; ++k) \
;         acc[ai][bj][m][n] = __builtin_amdgcn_mfma_f32_16x16x32_bf16(Bt[n][k], At[m][k], acc[ai][bj][m][n], 0, 0, 0); __builtin_amdgcn_s_setprio(0); } while (0)
; #define PG8_WAIT_V(n) asm volatile("s_waitcnt vmcnt(" #n ")" ::: "memory")
; #define PG8_WAIT_L(n) asm volatile("s_waitcnt lgkmcnt(" #n ")" ::: "memory")
; #define PG8_BAR __builtin_amdgcn_s_barrier()
; #define PG8_SCHED __builtin_amdgcn_sched_barrier(0)
; template <class Epi, class Sched, bool ALIGN_EPI = false, bool SP2 = false>
; __device__ __forceinline__ void gemm_phase(PG8_LAS unsigned char* lds, const Gemm g, const Sched& S, const Epi& E) {
;     ...
;             PG8_WAIT_V(8); PG8_WAIT_L(0); PG8_BAR; PG8_MMA(1, 0, At, B0); PG8_MMA(1, 1, At, B1); PG8_BAR; PG8_SCHED;
;             PG8_LDB(B0, 1, 0); PG8_LDB(B1, 1, 1); PG8_SCHED; PG8_LDA(At, 1, 0); PG8_STAGE(PG8_SA(0, 1), a2 + hstep, voffA);
;             PG8_WAIT_V(8); PG8_WAIT_L(0); PG8_BAR; PG8_MMA(0, 0, At, B0); PG8_MMA(0, 1, At, B1); PG8_BAR; PG8_SCHED;
	s_setprio 1
	s_waitcnt lgkmcnt(0)
	v_mfma_f32_16x16x32_bf16 v[92:95], v[170:173], v[212:215], v[92:95]
	v_mfma_f32_16x16x32_bf16 v[88:91], v[182:185], v[212:215], v[88:91]
	v_mfma_f32_16x16x32_bf16 v[84:87], v[170:173], v[220:223], v[84:87]
	v_mfma_f32_16x16x32_bf16 v[80:83], v[182:185], v[220:223], v[80:83]
	v_mfma_f32_16x16x32_bf16 v[76:79], v[170:173], v[228:231], v[76:79]
	v_mfma_f32_16x16x32_bf16 v[72:75], v[182:185], v[228:231], v[72:75]
	v_mfma_f32_16x16x32_bf16 v[68:71], v[170:173], v[236:239], v[68:71]
	v_mfma_f32_16x16x32_bf16 v[64:67], v[182:185], v[236:239], v[64:67]
	v_mfma_f32_16x16x32_bf16 v[92:95], v[174:177], v[216:219], v[92:95]
	v_mfma_f32_16x16x32_bf16 v[88:91], v[186:189], v[216:219], v[88:91]
	v_mfma_f32_16x16x32_bf16 v[84:87], v[174:177], v[224:227], v[84:87]
	v_mfma_f32_16x16x32_bf16 v[80:83], v[186:189], v[224:227], v[80:83]
	v_mfma_f32_16x16x32_bf16 v[76:79], v[174:177], v[232:235], v[76:79]
	v_mfma_f32_16x16x32_bf16 v[72:75], v[186:189], v[232:235], v[72:75]
	v_lshl_add_u64 v[244:245], s[64:65], 0, v[128:129]
	s_mov_b32 m0, s59
	s_nop 0
	global_load_lds_dwordx4 v[244:245], off
	v_mfma_f32_16x16x32_bf16 v[68:71], v[174:177], v[240:243], v[68:71]
	v_mfma_f32_16x16x32_bf16 v[64:67], v[186:189], v[240:243], v[64:67]
	s_setprio 0
	s_setprio 1
	v_mfma_f32_16x16x32_bf16 v[28:31], v[190:193], v[212:215], v[28:31]
	v_mfma_f32_16x16x32_bf16 v[24:27], v[198:201], v[212:215], v[24:27]
	v_mfma_f32_16x16x32_bf16 v[20:23], v[190:193], v[220:223], v[20:23]
	v_mfma_f32_16x16x32_bf16 v[16:19], v[198:201], v[220:223], v[16:19]
	v_mfma_f32_16x16x32_bf16 v[12:15], v[190:193], v[228:231], v[12:15]
	v_mfma_f32_16x16x32_bf16 v[8:11], v[198:201], v[228:231], v[8:11]
	v_mfma_f32_16x16x32_bf16 v[4:7], v[190:193], v[236:239], v[4:7]
	v_mfma_f32_16x16x32_bf16 v[0:3], v[198:201], v[236:239], v[0:3]
	v_mfma_f32_16x16x32_bf16 v[28:31], v[194:197], v[216:219], v[28:31]
	v_mfma_f32_16x16x32_bf16 v[24:27], v[208:211], v[216:219], v[24:27]
	v_mfma_f32_16x16x32_bf16 v[20:23], v[194:197], v[224:227], v[20:23]
	v_mfma_f32_16x16x32_bf16 v[16:19], v[208:211], v[224:227], v[16:19]
	v_mfma_f32_16x16x32_bf16 v[12:15], v[194:197], v[232:235], v[12:15]
	v_mfma_f32_16x16x32_bf16 v[8:11], v[208:211], v[232:235], v[8:11]
	v_lshl_add_u64 v[246:247], s[64:65], 0, v[132:133]
	s_mov_b32 m0, s84
	s_nop 0
	global_load_lds_dwordx4 v[246:247], off
	v_mfma_f32_16x16x32_bf16 v[4:7], v[194:197], v[240:243], v[4:7]
	v_mfma_f32_16x16x32_bf16 v[0:3], v[208:211], v[240:243], v[0:3]
	s_setprio 0
	s_barrier
	s_add_i32 s3, 0, 0x18000
	v_add_u32_e32 v136, s3, v141
	s_add_i32 s33, 0, 0x1c000
	ds_read_b128 v[170:173], v136
	ds_read_b128 v[174:177], v136 offset:1024
	ds_read_b128 v[182:185], v136 offset:2048
	ds_read_b128 v[186:189], v136 offset:3072
	v_add_u32_e32 v136, s33, v141
	ds_read_b128 v[190:193], v136
	ds_read_b128 v[194:197], v136 offset:1024
	ds_read_b128 v[198:201], v136 offset:2048
	ds_read_b128 v[208:211], v136 offset:3072
	s_add_u32 s14, s64, 0x40000
	s_addc_u32 s15, s65, 0
	s_mov_b32 m0, s85
	v_lshl_add_u64 v[248:249], s[14:15], 0, v[128:129]
	ds_read_b128 v[212:215], v164 offset:32768
	ds_read_b128 v[216:219], v164 offset:33792
	ds_read_b128 v[220:223], v164 offset:34816
	ds_read_b128 v[224:227], v164 offset:35840
	ds_read_b128 v[228:231], v164 offset:36864
	ds_read_b128 v[232:235], v164 offset:37888
	ds_read_b128 v[236:239], v164 offset:38912
	ds_read_b128 v[240:243], v164 offset:39936
	global_load_lds_dwordx4 v[248:249], off
	v_lshl_add_u64 v[248:249], s[14:15], 0, v[132:133]
	s_mov_b32 m0, s86
	s_nop 0
	global_load_lds_dwordx4 v[248:249], off
	s_waitcnt vmcnt(8)
	s_waitcnt lgkmcnt(0)
	s_barrier
	s_setprio 1
	s_waitcnt lgkmcnt(0)
	v_mfma_f32_16x16x32_bf16 v[124:127], v[170:173], v[212:215], v[124:127]
	v_mfma_f32_16x16x32_bf16 v[120:123], v[182:185], v[212:215], v[120:123]
	v_mfma_f32_16x16x32_bf16 v[116:119], v[170:173], v[220:223], v[116:119]
	v_mfma_f32_16x16x32_bf16 v[112:115], v[182:185], v[220:223], v[112:115]
	v_mfma_f32_16x16x32_bf16 v[108:111], v[170:173], v[228:231], v[108:111]
	v_mfma_f32_16x16x32_bf16 v[104:107], v[182:185], v[228:231], v[104:107]
	v_mfma_f32_16x16x32_bf16 v[100:103], v[170:173], v[236:239], v[100:103]
	v_mfma_f32_16x16x32_bf16 v[96:99], v[182:185], v[236:239], v[96:99]
	v_mfma_f32_16x16x32_bf16 v[124:127], v[174:177], v[216:219], v[124:127]
	v_mfma_f32_16x16x32_bf16 v[120:123], v[186:189], v[216:219], v[120:123]
	v_mfma_f32_16x16x32_bf16 v[116:119], v[174:177], v[224:227], v[116:119]
	v_mfma_f32_16x16x32_bf16 v[112:115], v[186:189], v[224:227], v[112:115]
	v_mfma_f32_16x16x32_bf16 v[108:111], v[174:177], v[232:235], v[108:111]
	v_mfma_f32_16x16x32_bf16 v[104:107], v[186:189], v[232:235], v[104:107]
	v_mfma_f32_16x16x32_bf16 v[100:103], v[174:177], v[240:243], v[100:103]
	v_mfma_f32_16x16x32_bf16 v[96:99], v[186:189], v[240:243], v[96:99]
	s_setprio 0
	s_setprio 1
	v_mfma_f32_16x16x32_bf16 v[60:63], v[190:193], v[212:215], v[60:63]
	v_mfma_f32_16x16x32_bf16 v[56:59], v[198:201], v[212:215], v[56:59]
	v_mfma_f32_16x16x32_bf16 v[52:55], v[190:193], v[220:223], v[52:55]
	v_mfma_f32_16x16x32_bf16 v[48:51], v[198:201], v[220:223], v[48:51]
	v_mfma_f32_16x16x32_bf16 v[44:47], v[190:193], v[228:231], v[44:47]
	v_mfma_f32_16x16x32_bf16 v[40:43], v[198:201], v[228:231], v[40:43]
	v_mfma_f32_16x16x32_bf16 v[36:39], v[190:193], v[236:239], v[36:39]
	v_mfma_f32_16x16x32_bf16 v[32:35], v[198:201], v[236:239], v[32:35]
	v_mfma_f32_16x16x32_bf16 v[60:63], v[194:197], v[216:219], v[60:63]
	v_mfma_f32_16x16x32_bf16 v[56:59], v[208:211], v[216:219], v[56:59]
	v_mfma_f32_16x16x32_bf16 v[52:55], v[194:197], v[224:227], v[52:55]
	v_mfma_f32_16x16x32_bf16 v[48:51], v[208:211], v[224:227], v[48:51]
	v_mfma_f32_16x16x32_bf16 v[44:47], v[194:197], v[232:235], v[44:47]
	v_mfma_f32_16x16x32_bf16 v[40:43], v[208:211], v[232:235], v[40:43]
	v_mfma_f32_16x16x32_bf16 v[36:39], v[194:197], v[240:243], v[36:39]
	v_mfma_f32_16x16x32_bf16 v[32:35], v[208:211], v[240:243], v[32:35]
	s_setprio 0
	s_barrier
; #define PG8_STAGE(bufoff, gbase, voff) do { _Pragma("unroll") for (int _i = 0; _i < 2; ++_i) \
;         __builtin_amdgcn_global_load_lds((const unsigned*)((const char*)(gbase) + (voff)[_i]), (PG8_LAS unsigned*)(lds + (bufoff) + ldsw + _i * 8192), 16, 0, 0); } while (0)
; #define PG8_LDA(dst, b, h) do { _Pragma("unroll") for (int m = 0; m < 4; ++m) _Pragma("unroll") for (int k = 0; k < 2; ++k) dst[m][k] = *(const PG8_LAS bf16x8*)(lds + PG8_SA(b, h) + aoff + m * 2048 + k * 1024); } while (0)
; #define PG8_MMA(ai, bj, At, Bt) do { __builtin_amdgcn_s_setprio(1); _Pragma("unroll") for (int m = 0; m < 4; ++m) _Pragma("unroll") for (int n = 0; n < 2; ++n) _Pragma("unroll") for (int k = 0; k < 2; ++k) \
;         acc[ai][bj][m][n] = __builtin_amdgcn_mfma_f32_16x16x32_bf16(Bt[n][k], At[m][k], acc[ai][bj][m][n], 0, 0, 0); __builtin_amdgcn_s_setprio(0); } while (0)
; #define PG8_WAIT_V(n) asm volatile("s_waitcnt vmcnt(" #n ")" ::: "memory")
; #define PG8_WAIT_L(n) asm volatile("s_waitcnt lgkmcnt(" #n ")" ::: "memory")
; #define PG8_BAR __builtin_amdgcn_s_barrier()
; #define PG8_SCHED __builtin_amdgcn_sched_barrier(0)
; template <class Epi, class Sched, bool ALIGN_EPI = false, bool SP2 = false>
; __device__ __forceinline__ void gemm_phase(PG8_LAS unsigned char* lds, const Gemm g, const Sched& S, const Epi& E) {
;     ...
;             PG8_LDA(At, 1, 1); PG8_STAGE(PG8_SB(1, 0), b3, voffB); PG8_STAGE(PG8_SB(1, 1), b3 + hstep, voffB); PG8_STAGE(PG8_SA(1, 0), a3, voffA);
;             PG8_WAIT_V(8); PG8_WAIT_L(0); PG8_BAR; PG8_MMA(1, 0, At, B0); PG8_MMA(1, 1, At, B1); PG8_BAR; PG8_SCHED;
	s_add_i32 s3, s3, s75
	v_lshl_add_u64 v[178:179], v[178:179], 0, s[10:11]
	s_mov_b32 m0, s3
	ds_read_b128 v[212:215], v164 offset:49152
	ds_read_b128 v[216:219], v164 offset:50176
	ds_read_b128 v[220:223], v164 offset:51200
	ds_read_b128 v[224:227], v164 offset:52224
	ds_read_b128 v[228:231], v164 offset:53248
	ds_read_b128 v[232:235], v164 offset:54272
	ds_read_b128 v[236:239], v164 offset:55296
	ds_read_b128 v[240:243], v164 offset:56320
	global_load_lds_dwordx4 v[178:179], off
	s_add_i32 m0, s3, 0x2000
	s_add_u32 s14, s62, 0x40080
	v_lshl_add_u64 v[178:179], v[202:203], 0, s[10:11]
	s_addc_u32 s15, s63, 0
	s_add_i32 s3, s33, s75
	global_load_lds_dwordx4 v[178:179], off
	v_lshl_add_u64 v[178:179], s[14:15], 0, v[130:131]
	s_mov_b32 m0, s3
	s_nop 0
	global_load_lds_dwordx4 v[178:179], off
	v_lshl_add_u64 v[178:179], s[14:15], 0, v[134:135]
	s_add_i32 m0, s3, 0x2000
	s_nop 0
	global_load_lds_dwordx4 v[178:179], off
	s_waitcnt vmcnt(6)
	s_waitcnt lgkmcnt(0)
	s_barrier
	s_setprio 1
	s_waitcnt lgkmcnt(0)
	v_mfma_f32_16x16x32_bf16 v[92:95], v[170:173], v[212:215], v[92:95]
	v_mfma_f32_16x16x32_bf16 v[88:91], v[182:185], v[212:215], v[88:91]
	v_mfma_f32_16x16x32_bf16 v[84:87], v[170:173], v[220:223], v[84:87]
	v_mfma_f32_16x16x32_bf16 v[80:83], v[182:185], v[220:223], v[80:83]
	v_mfma_f32_16x16x32_bf16 v[76:79], v[170:173], v[228:231], v[76:79]
	v_mfma_f32_16x16x32_bf16 v[72:75], v[182:185], v[228:231], v[72:75]
	v_mfma_f32_16x16x32_bf16 v[68:71], v[170:173], v[236:239], v[68:71]
	v_mfma_f32_16x16x32_bf16 v[64:67], v[182:185], v[236:239], v[64:67]
	v_mfma_f32_16x16x32_bf16 v[92:95], v[174:177], v[216:219], v[92:95]
	v_mfma_f32_16x16x32_bf16 v[88:91], v[186:189], v[216:219], v[88:91]
	v_mfma_f32_16x16x32_bf16 v[84:87], v[174:177], v[224:227], v[84:87]
	v_mfma_f32_16x16x32_bf16 v[80:83], v[186:189], v[224:227], v[80:83]
	v_mfma_f32_16x16x32_bf16 v[76:79], v[174:177], v[232:235], v[76:79]
	v_mfma_f32_16x16x32_bf16 v[72:75], v[186:189], v[232:235], v[72:75]
	v_lshl_add_u64 v[178:179], v[244:245], 0, s[10:11]
	s_mov_b32 m0, s88
	s_nop 0
	global_load_lds_dwordx4 v[178:179], off
	v_mfma_f32_16x16x32_bf16 v[68:71], v[174:177], v[240:243], v[68:71]
	v_mfma_f32_16x16x32_bf16 v[64:67], v[186:189], v[240:243], v[64:67]
	s_setprio 0
	s_setprio 1
	v_mfma_f32_16x16x32_bf16 v[28:31], v[190:193], v[212:215], v[28:31]
	v_mfma_f32_16x16x32_bf16 v[24:27], v[198:201], v[212:215], v[24:27]
	v_mfma_f32_16x16x32_bf16 v[20:23], v[190:193], v[220:223], v[20:23]
	v_mfma_f32_16x16x32_bf16 v[16:19], v[198:201], v[220:223], v[16:19]
	v_mfma_f32_16x16x32_bf16 v[12:15], v[190:193], v[228:231], v[12:15]
	v_mfma_f32_16x16x32_bf16 v[8:11], v[198:201], v[228:231], v[8:11]
	v_mfma_f32_16x16x32_bf16 v[4:7], v[190:193], v[236:239], v[4:7]
	v_mfma_f32_16x16x32_bf16 v[0:3], v[198:201], v[236:239], v[0:3]
	v_mfma_f32_16x16x32_bf16 v[28:31], v[194:197], v[216:219], v[28:31]
	v_mfma_f32_16x16x32_bf16 v[24:27], v[208:211], v[216:219], v[24:27]
	v_mfma_f32_16x16x32_bf16 v[20:23], v[194:197], v[224:227], v[20:23]
	v_mfma_f32_16x16x32_bf16 v[16:19], v[208:211], v[224:227], v[16:19]
	v_mfma_f32_16x16x32_bf16 v[12:15], v[194:197], v[232:235], v[12:15]
	v_mfma_f32_16x16x32_bf16 v[8:11], v[208:211], v[232:235], v[8:11]
	v_lshl_add_u64 v[178:179], v[246:247], 0, s[10:11]
	s_mov_b32 m0, s89
	s_nop 0
	global_load_lds_dwordx4 v[178:179], off
	v_mfma_f32_16x16x32_bf16 v[4:7], v[194:197], v[240:243], v[4:7]
	v_mfma_f32_16x16x32_bf16 v[0:3], v[208:211], v[240:243], v[0:3]
	s_setprio 0
	s_barrier
	s_add_i32 s97, s97, 2
	s_add_u32 s60, s60, 0x100
	s_addc_u32 s61, s61, 0
	s_add_u32 s95, s95, 0x100
	s_addc_u32 s96, s96, 0
	s_cmp_lt_u32 s97, 14
	s_cbranch_scc1 .LBB0_495
	s_andn2_b64 vcc, exec, s[40:41]
	s_cbranch_vccnz .LBB0_498
	s_barrier

; #define PG8_STAGE(bufoff, gbase, voff) do { _Pragma("unroll") for (int _i = 0; _i < 2; ++_i) \
;         __builtin_amdgcn_global_load_lds((const unsigned*)((const char*)(gbase) + (voff)[_i]), (PG8_LAS unsigned*)(lds + (bufoff) + ldsw + _i * 8192), 16, 0, 0); } while (0)
; #define PG8_LDA(dst, b, h) do { _Pragma("unroll") for (int m = 0; m < 4; ++m) _Pragma("unroll") for (int k = 0; k < 2; ++k) dst[m][k] = *(const PG8_LAS bf16x8*)(lds + PG8_SA(b, h) + aoff + m * 2048 + k * 1024); } while (0)
; #define PG8_LDB(dst, b, h) do { _Pragma("unroll") for (int n = 0; n < 2; ++n) _Pragma("unroll") for (int k = 0; k < 2; ++k) dst[n][k] = *(const PG8_LAS bf16x8*)(lds + PG8_SB(b, h) + boff + n * 2048 + k * 1024); } while (0)
; #define PG8_MMA(ai, bj, At, Bt) do { __builtin_amdgcn_s_setprio(1); _Pragma("unroll") for (int m = 0; m < 4; ++m) _Pragma("unroll") for (int n = 0; n < 2; ++n) _Pragma("unroll") for (int k = 0; k < 2; ++k) \
;         acc[ai][bj][m][n] = __builtin_amdgcn_mfma_f32_16x16x32_bf16(Bt[n][k], At[m][k], acc[ai][bj][m][n], 0, 0, 0); __builtin_amdgcn_s_setprio(0); } while (0)
; #define PG8_BAR __builtin_amdgcn_s_barrier()
; template <class Epi, class Sched, bool ALIGN_EPI = false, bool SP2 = false>
; __device__ __forceinline__ void gemm_phase(PG8_LAS unsigned char* lds, const Gemm g, const Sched& S, const Epi& E) {
;     ...
;         const bool has_next = S.next(ui + 1, nxt);
;         const char* nA = has_next ? (const char*)g.A + (size_t)nxt.pm * tstep : cA; const char* nB = has_next ? (const char*)g.Bt + (size_t)nxt.pn * tstep : cB;
;         for (int t = 0; t < nt; t += 2) {
;             const bool last = (t == nt - 2);
;             const char* a1 = cA + (size_t)(t + 1) * kstep;
;             const char* a2 = last ? nA : cA + (size_t)(t + 2) * kstep; const char* b2 = last ? nB : cB + (size_t)(t + 2) * kstep;
;             const char* a3 = a2 + kstep; const char* b3 = b2 + kstep;
;             if (last && has_next) S.a_ready(nxt);
;             if constexpr (SP2) {
;             PG8_LDB(B0, 0, 0); PG8_LDB(B1, 0, 1); PG8_SCHED; PG8_LDA(At, 0, 0); PG8_STAGE(PG8_SA(1, 1), a1 + hstep, voffA);
;             PG8_WAIT_V(8); PG8_WAIT_L(0); PG8_BAR; PG8_MMA(0, 0, At, B0); PG8_MMA(0, 1, At, B1); PG8_BAR; PG8_SCHED;
;             PG8_LDA(At, 0, 1); PG8_STAGE(PG8_SB(0, 0), b2, voffB); PG8_STAGE(PG8_SB(0, 1), b2 + hstep, voffB); PG8_STAGE(PG8_SA(0, 0), a2, voffA);
.LBB0_649:
	s_ashr_i32 s51, s50, 31
	s_lshl_b64 s[14:15], s[50:51], 19
	s_add_u32 s52, s40, s14
	s_addc_u32 s53, s41, s15
	s_and_b64 s[14:15], s[8:9], exec
	s_cselect_b32 s51, s53, s61
	s_cselect_b32 s57, s52, s60
	s_ashr_i32 s49, s48, 31
	s_lshl_b64 s[14:15], s[48:49], 19
	s_add_u32 s54, s82, s14
	s_addc_u32 s55, s83, s15
	s_and_b64 s[14:15], s[8:9], exec
	s_cselect_b32 s49, s55, s63
	s_cselect_b32 s89, s54, s62
	s_add_u32 s60, s60, 0x40080
	s_addc_u32 s61, s61, 0
	s_add_u32 s90, s62, 0x100
	s_addc_u32 s91, s63, 0
	s_mov_b32 s92, -2
	s_waitcnt lgkmcnt(0)
	s_waitcnt vmcnt(0)
	ds_read_b128 v[148:151], v155
	ds_read_b128 v[160:163], v155 offset:1024
	ds_read_b128 v[164:167], v155 offset:2048
	ds_read_b128 v[168:171], v155 offset:3072
	ds_read_b128 v[172:175], v156
	ds_read_b128 v[176:179], v156 offset:1024
	ds_read_b128 v[182:185], v156 offset:2048
	ds_read_b128 v[186:189], v156 offset:3072
	s_add_u32 s3, s60, 0xfffc0080
	s_addc_u32 s14, s61, -1
	s_cmp_eq_u32 s92, 12
	s_cselect_b32 s65, s51, s14
	s_cselect_b32 s64, s57, s3
	s_cselect_b32 s63, s49, s91
	s_cselect_b32 s62, s89, s90
	v_lshl_add_u64 v[202:203], s[60:61], 0, v[140:141]
	s_add_i32 m0, s43, 0xc000
	ds_read_b128 v[190:193], v157
	ds_read_b128 v[194:197], v157 offset:1024
	ds_read_b128 v[198:201], v157 offset:2048
	ds_read_b128 v[208:211], v157 offset:3072
	ds_read_b128 v[212:215], v157 offset:4096
	ds_read_b128 v[216:219], v157 offset:5120
	ds_read_b128 v[220:223], v157 offset:6144
	ds_read_b128 v[224:227], v157 offset:7168
	global_load_lds_dwordx4 v[202:203], off
	v_lshl_add_u64 v[202:203], s[60:61], 0, v[142:143]
	s_add_i32 m0, s43, 0xe000
	s_nop 0
	global_load_lds_dwordx4 v[202:203], off
	s_waitcnt vmcnt(8)
	s_waitcnt lgkmcnt(0)
	s_barrier
	s_setprio 1
	s_waitcnt lgkmcnt(0)
	v_mfma_f32_16x16x32_bf16 v[124:127], v[148:151], v[190:193], 0
	v_mfma_f32_16x16x32_bf16 v[120:123], v[164:167], v[190:193], 0
	v_mfma_f32_16x16x32_bf16 v[108:111], v[148:151], v[198:201], 0
	v_mfma_f32_16x16x32_bf16 v[104:107], v[164:167], v[198:201], 0
	v_mfma_f32_16x16x32_bf16 v[92:95], v[148:151], v[212:215], 0
	v_mfma_f32_16x16x32_bf16 v[88:91], v[164:167], v[212:215], 0
	v_mfma_f32_16x16x32_bf16 v[76:79], v[148:151], v[220:223], 0
	v_mfma_f32_16x16x32_bf16 v[72:75], v[164:167], v[220:223], 0
	v_mfma_f32_16x16x32_bf16 v[124:127], v[160:163], v[194:197], v[124:127]
	v_mfma_f32_16x16x32_bf16 v[120:123], v[168:171], v[194:197], v[120:123]
	v_mfma_f32_16x16x32_bf16 v[108:111], v[160:163], v[208:211], v[108:111]
	v_mfma_f32_16x16x32_bf16 v[104:107], v[168:171], v[208:211], v[104:107]
	v_mfma_f32_16x16x32_bf16 v[92:95], v[160:163], v[216:219], v[92:95]
	v_mfma_f32_16x16x32_bf16 v[88:91], v[168:171], v[216:219], v[88:91]
	v_mfma_f32_16x16x32_bf16 v[76:79], v[160:163], v[224:227], v[76:79]
	v_mfma_f32_16x16x32_bf16 v[72:75], v[168:171], v[224:227], v[72:75]
	s_setprio 0
	s_setprio 1
	v_mfma_f32_16x16x32_bf16 v[116:119], v[172:175], v[190:193], 0
	v_mfma_f32_16x16x32_bf16 v[112:115], v[182:185], v[190:193], 0
	v_mfma_f32_16x16x32_bf16 v[100:103], v[172:175], v[198:201], 0
	v_mfma_f32_16x16x32_bf16 v[96:99], v[182:185], v[198:201], 0
	v_mfma_f32_16x16x32_bf16 v[84:87], v[172:175], v[212:215], 0
	v_mfma_f32_16x16x32_bf16 v[80:83], v[182:185], v[212:215], 0
	v_mfma_f32_16x16x32_bf16 v[68:71], v[172:175], v[220:223], 0
	v_mfma_f32_16x16x32_bf16 v[64:67], v[182:185], v[220:223], 0
	v_mfma_f32_16x16x32_bf16 v[116:119], v[176:179], v[194:197], v[116:119]
	v_mfma_f32_16x16x32_bf16 v[112:115], v[186:189], v[194:197], v[112:115]
	v_mfma_f32_16x16x32_bf16 v[100:103], v[176:179], v[208:211], v[100:103]
	v_mfma_f32_16x16x32_bf16 v[96:99], v[186:189], v[208:211], v[96:99]
	v_mfma_f32_16x16x32_bf16 v[84:87], v[176:179], v[216:219], v[84:87]
	v_mfma_f32_16x16x32_bf16 v[80:83], v[186:189], v[216:219], v[80:83]
	v_mfma_f32_16x16x32_bf16 v[68:71], v[176:179], v[224:227], v[68:71]
	v_mfma_f32_16x16x32_bf16 v[64:67], v[186:189], v[224:227], v[64:67]
	s_setprio 0
	s_barrier
	s_add_i32 s3, s85, s34
	v_lshl_add_u64 v[202:203], s[62:63], 0, v[134:135]
	s_mov_b32 m0, s3
	ds_read_b128 v[190:193], v157 offset:16384
	ds_read_b128 v[194:197], v157 offset:17408
	ds_read_b128 v[198:201], v157 offset:18432
	ds_read_b128 v[208:211], v157 offset:19456
	ds_read_b128 v[212:215], v157 offset:20480
	ds_read_b128 v[216:219], v157 offset:21504
	ds_read_b128 v[220:223], v157 offset:22528
	ds_read_b128 v[224:227], v157 offset:23552
	global_load_lds_dwordx4 v[202:203], off
	s_add_i32 m0, s3, 0x2000
	s_add_u32 s14, s62, 0x40000
	v_lshl_add_u64 v[228:229], s[62:63], 0, v[138:139]
	s_addc_u32 s15, s63, 0
	s_add_i32 s3, s86, s34
	global_load_lds_dwordx4 v[228:229], off
	v_lshl_add_u64 v[230:231], s[14:15], 0, v[134:135]
	s_mov_b32 m0, s3
	global_load_lds_dwordx4 v[230:231], off
	v_lshl_add_u64 v[230:231], s[14:15], 0, v[138:139]
	s_add_i32 m0, s3, 0x2000
	s_nop 0
	global_load_lds_dwordx4 v[230:231], off
	s_waitcnt vmcnt(6)
	s_waitcnt lgkmcnt(0)
	s_barrier
; #define PG8_STAGE(bufoff, gbase, voff) do { _Pragma("unroll") for (int _i = 0; _i < 2; ++_i) \
;         __builtin_amdgcn_global_load_lds((const unsigned*)((const char*)(gbase) + (voff)[_i]), (PG8_LAS unsigned*)(lds + (bufoff) + ldsw + _i * 8192), 16, 0, 0); } while (0)
; #define PG8_LDA(dst, b, h) do { _Pragma("unroll") for (int m = 0; m < 4; ++m) _Pragma("unroll") for (int k = 0; k < 2; ++k) dst[m][k] = *(const PG8_LAS bf16x8*)(lds + PG8_SA(b, h) + aoff + m * 2048 + k * 1024); } while (0)
; #define PG8_LDB(dst, b, h) do { _Pragma("unroll") for (int n = 0; n < 2; ++n) _Pragma("unroll") for (int k = 0; k < 2; ++k) dst[n][k] = *(const PG8_LAS bf16x8*)(lds + PG8_SB(b, h) + boff + n * 2048 + k * 1024); } while (0)
; #define PG8_MMA(ai, bj, At, Bt) do { __builtin_amdgcn_s_setprio(1); _Pragma("unroll") for (int m = 0; m < 4; ++m) _Pragma("unroll") for (int n = 0; n < 2; ++n) _Pragma("unroll") for (int k = 0; k < 2; ++k) \
;         acc[ai][bj][m][n] = __builtin_amdgcn_mfma_f32_16x16x32_bf16(Bt[n][k], At[m][k], acc[ai][bj][m][n], 0, 0, 0); __builtin_amdgcn_s_setprio(0); } while (0)
; #define PG8_WAIT_V(n) asm volatile("s_waitcnt vmcnt(" #n ")" ::: "memory")
; #define PG8_WAIT_L(n) asm volatile("s_waitcnt lgkmcnt(" #n ")" ::: "memory")
; #define PG8_BAR __builtin_amdgcn_s_barrier()
; #define PG8_SCHED __builtin_amdgcn_sched_barrier(0)
; template <class Epi, class Sched, bool ALIGN_EPI = false, bool SP2 = false>
; __device__ __forceinline__ void gemm_phase(PG8_LAS unsigned char* lds, const Gemm g, const Sched& S, const Epi& E) {
;     ...
;             PG8_WAIT_V(8); PG8_WAIT_L(0); PG8_BAR; PG8_MMA(1, 0, At, B0); PG8_MMA(1, 1, At, B1); PG8_BAR; PG8_SCHED;
;             PG8_LDB(B0, 1, 0); PG8_LDB(B1, 1, 1); PG8_SCHED; PG8_LDA(At, 1, 0); PG8_STAGE(PG8_SA(0, 1), a2 + hstep, voffA);
;             PG8_WAIT_V(8); PG8_WAIT_L(0); PG8_BAR; PG8_MMA(0, 0, At, B0); PG8_MMA(0, 1, At, B1); PG8_BAR; PG8_SCHED;
	s_setprio 1
	s_waitcnt lgkmcnt(0)
	v_mfma_f32_16x16x32_bf16 v[60:63], v[148:151], v[190:193], 0
	v_mfma_f32_16x16x32_bf16 v[56:59], v[164:167], v[190:193], 0
	v_mfma_f32_16x16x32_bf16 v[44:47], v[148:151], v[198:201], 0
	v_mfma_f32_16x16x32_bf16 v[40:43], v[164:167], v[198:201], 0
	v_mfma_f32_16x16x32_bf16 v[28:31], v[148:151], v[212:215], 0
	v_mfma_f32_16x16x32_bf16 v[24:27], v[164:167], v[212:215], 0
	v_mfma_f32_16x16x32_bf16 v[12:15], v[148:151], v[220:223], 0
	v_mfma_f32_16x16x32_bf16 v[8:11], v[164:167], v[220:223], 0
	v_mfma_f32_16x16x32_bf16 v[60:63], v[160:163], v[194:197], v[60:63]
	v_mfma_f32_16x16x32_bf16 v[56:59], v[168:171], v[194:197], v[56:59]
	v_mfma_f32_16x16x32_bf16 v[44:47], v[160:163], v[208:211], v[44:47]
	v_mfma_f32_16x16x32_bf16 v[40:43], v[168:171], v[208:211], v[40:43]
	v_mfma_f32_16x16x32_bf16 v[28:31], v[160:163], v[216:219], v[28:31]
	v_mfma_f32_16x16x32_bf16 v[24:27], v[168:171], v[216:219], v[24:27]
	v_lshl_add_u64 v[230:231], s[64:65], 0, v[132:133]
	s_mov_b32 m0, s43
	s_nop 0
	global_load_lds_dwordx4 v[230:231], off
	v_mfma_f32_16x16x32_bf16 v[12:15], v[160:163], v[224:227], v[12:15]
	v_mfma_f32_16x16x32_bf16 v[8:11], v[168:171], v[224:227], v[8:11]
	s_setprio 0
	s_setprio 1
	v_mfma_f32_16x16x32_bf16 v[52:55], v[172:175], v[190:193], 0
	v_mfma_f32_16x16x32_bf16 v[48:51], v[182:185], v[190:193], 0
	v_mfma_f32_16x16x32_bf16 v[36:39], v[172:175], v[198:201], 0
	v_mfma_f32_16x16x32_bf16 v[32:35], v[182:185], v[198:201], 0
	v_mfma_f32_16x16x32_bf16 v[20:23], v[172:175], v[212:215], 0
	v_mfma_f32_16x16x32_bf16 v[16:19], v[182:185], v[212:215], 0
	v_mfma_f32_16x16x32_bf16 v[4:7], v[172:175], v[220:223], 0
	v_mfma_f32_16x16x32_bf16 v[0:3], v[182:185], v[220:223], 0
	v_mfma_f32_16x16x32_bf16 v[52:55], v[176:179], v[194:197], v[52:55]
	v_mfma_f32_16x16x32_bf16 v[48:51], v[186:189], v[194:197], v[48:51]
	v_mfma_f32_16x16x32_bf16 v[36:39], v[176:179], v[208:211], v[36:39]
	v_mfma_f32_16x16x32_bf16 v[32:35], v[186:189], v[208:211], v[32:35]
	v_mfma_f32_16x16x32_bf16 v[20:23], v[176:179], v[216:219], v[20:23]
	v_mfma_f32_16x16x32_bf16 v[16:19], v[186:189], v[216:219], v[16:19]
	v_lshl_add_u64 v[232:233], s[64:65], 0, v[136:137]
	s_mov_b32 m0, s59
	s_nop 0
	global_load_lds_dwordx4 v[232:233], off
	v_mfma_f32_16x16x32_bf16 v[4:7], v[176:179], v[224:227], v[4:7]
	v_mfma_f32_16x16x32_bf16 v[0:3], v[186:189], v[224:227], v[0:3]
	s_setprio 0
	s_barrier
	s_add_i32 s3, 0, 0x18000
	v_add_u32_e32 v159, s3, v131
	s_add_i32 s33, 0, 0x1c000
	ds_read_b128 v[148:151], v159
	ds_read_b128 v[160:163], v159 offset:1024
	ds_read_b128 v[164:167], v159 offset:2048
	ds_read_b128 v[168:171], v159 offset:3072
	v_add_u32_e32 v159, s33, v131
	ds_read_b128 v[172:175], v159
	ds_read_b128 v[176:179], v159 offset:1024
	ds_read_b128 v[182:185], v159 offset:2048
	ds_read_b128 v[186:189], v159 offset:3072
	s_add_u32 s14, s64, 0x40000
	s_addc_u32 s15, s65, 0
	s_mov_b32 m0, s66
	v_lshl_add_u64 v[234:235], s[14:15], 0, v[132:133]
	ds_read_b128 v[190:193], v157 offset:32768
	ds_read_b128 v[194:197], v157 offset:33792
	ds_read_b128 v[198:201], v157 offset:34816
	ds_read_b128 v[208:211], v157 offset:35840
	ds_read_b128 v[212:215], v157 offset:36864
	ds_read_b128 v[216:219], v157 offset:37888
	ds_read_b128 v[220:223], v157 offset:38912
	ds_read_b128 v[224:227], v157 offset:39936
	global_load_lds_dwordx4 v[234:235], off
	v_lshl_add_u64 v[234:235], s[14:15], 0, v[136:137]
	s_mov_b32 m0, s67
	s_nop 0
	global_load_lds_dwordx4 v[234:235], off
	s_waitcnt vmcnt(8)
	s_waitcnt lgkmcnt(0)
	s_barrier
	s_setprio 1
	s_waitcnt lgkmcnt(0)
	v_mfma_f32_16x16x32_bf16 v[124:127], v[148:151], v[190:193], v[124:127]
	v_mfma_f32_16x16x32_bf16 v[120:123], v[164:167], v[190:193], v[120:123]
	v_mfma_f32_16x16x32_bf16 v[108:111], v[148:151], v[198:201], v[108:111]
	v_mfma_f32_16x16x32_bf16 v[104:107], v[164:167], v[198:201], v[104:107]
	v_mfma_f32_16x16x32_bf16 v[92:95], v[148:151], v[212:215], v[92:95]
	v_mfma_f32_16x16x32_bf16 v[88:91], v[164:167], v[212:215], v[88:91]
	v_mfma_f32_16x16x32_bf16 v[76:79], v[148:151], v[220:223], v[76:79]
	v_mfma_f32_16x16x32_bf16 v[72:75], v[164:167], v[220:223], v[72:75]
	v_mfma_f32_16x16x32_bf16 v[124:127], v[160:163], v[194:197], v[124:127]
	v_mfma_f32_16x16x32_bf16 v[120:123], v[168:171], v[194:197], v[120:123]
	v_mfma_f32_16x16x32_bf16 v[108:111], v[160:163], v[208:211], v[108:111]
	v_mfma_f32_16x16x32_bf16 v[104:107], v[168:171], v[208:211], v[104:107]
	v_mfma_f32_16x16x32_bf16 v[92:95], v[160:163], v[216:219], v[92:95]
	v_mfma_f32_16x16x32_bf16 v[88:91], v[168:171], v[216:219], v[88:91]
	v_mfma_f32_16x16x32_bf16 v[76:79], v[160:163], v[224:227], v[76:79]
	v_mfma_f32_16x16x32_bf16 v[72:75], v[168:171], v[224:227], v[72:75]
	s_setprio 0
	s_setprio 1
	v_mfma_f32_16x16x32_bf16 v[116:119], v[172:175], v[190:193], v[116:119]
	v_mfma_f32_16x16x32_bf16 v[112:115], v[182:185], v[190:193], v[112:115]
	v_mfma_f32_16x16x32_bf16 v[100:103], v[172:175], v[198:201], v[100:103]
	v_mfma_f32_16x16x32_bf16 v[96:99], v[182:185], v[198:201], v[96:99]
	v_mfma_f32_16x16x32_bf16 v[84:87], v[172:175], v[212:215], v[84:87]
	v_mfma_f32_16x16x32_bf16 v[80:83], v[182:185], v[212:215], v[80:83]
	v_mfma_f32_16x16x32_bf16 v[68:71], v[172:175], v[220:223], v[68:71]
	v_mfma_f32_16x16x32_bf16 v[64:67], v[182:185], v[220:223], v[64:67]
	v_mfma_f32_16x16x32_bf16 v[116:119], v[176:179], v[194:197], v[116:119]
	v_mfma_f32_16x16x32_bf16 v[112:115], v[186:189], v[194:197], v[112:115]
	v_mfma_f32_16x16x32_bf16 v[100:103], v[176:179], v[208:211], v[100:103]
	v_mfma_f32_16x16x32_bf16 v[96:99], v[186:189], v[208:211], v[96:99]
	v_mfma_f32_16x16x32_bf16 v[84:87], v[176:179], v[216:219], v[84:87]
	v_mfma_f32_16x16x32_bf16 v[80:83], v[186:189], v[216:219], v[80:83]
	v_mfma_f32_16x16x32_bf16 v[68:71], v[176:179], v[224:227], v[68:71]
	v_mfma_f32_16x16x32_bf16 v[64:67], v[186:189], v[224:227], v[64:67]
	s_setprio 0
	s_barrier
; #define PG8_STAGE(bufoff, gbase, voff) do { _Pragma("unroll") for (int _i = 0; _i < 2; ++_i) \
;         __builtin_amdgcn_global_load_lds((const unsigned*)((const char*)(gbase) + (voff)[_i]), (PG8_LAS unsigned*)(lds + (bufoff) + ldsw + _i * 8192), 16, 0, 0); } while (0)
; #define PG8_LDA(dst, b, h) do { _Pragma("unroll") for (int m = 0; m < 4; ++m) _Pragma("unroll") for (int k = 0; k < 2; ++k) dst[m][k] = *(const PG8_LAS bf16x8*)(lds + PG8_SA(b, h) + aoff + m * 2048 + k * 1024); } while (0)
; #define PG8_LDB(dst, b, h) do { _Pragma("unroll") for (int n = 0; n < 2; ++n) _Pragma("unroll") for (int k = 0; k < 2; ++k) dst[n][k] = *(const PG8_LAS bf16x8*)(lds + PG8_SB(b, h) + boff + n * 2048 + k * 1024); } while (0)
; #define PG8_MMA(ai, bj, At, Bt) do { __builtin_amdgcn_s_setprio(1); _Pragma("unroll") for (int m = 0; m < 4; ++m) _Pragma("unroll") for (int n = 0; n < 2; ++n) _Pragma("unroll") for (int k = 0; k < 2; ++k) \
;         acc[ai][bj][m][n] = __builtin_amdgcn_mfma_f32_16x16x32_bf16(Bt[n][k], At[m][k], acc[ai][bj][m][n], 0, 0, 0); __builtin_amdgcn_s_setprio(0); } while (0)
; #define PG8_WAIT_V(n) asm volatile("s_waitcnt vmcnt(" #n ")" ::: "memory")
; #define PG8_WAIT_L(n) asm volatile("s_waitcnt lgkmcnt(" #n ")" ::: "memory")
; #define PG8_BAR __builtin_amdgcn_s_barrier()
; #define PG8_SCHED __builtin_amdgcn_sched_barrier(0)
; template <class Epi, class Sched, bool ALIGN_EPI = false, bool SP2 = false>
; __device__ __forceinline__ void gemm_phase(PG8_LAS unsigned char* lds, const Gemm g, const Sched& S, const Epi& E) {
;     ...
;             const bool last = (t == nt - 2);
;             const char* a1 = cA + (size_t)(t + 1) * kstep;
;             const char* a2 = last ? nA : cA + (size_t)(t + 2) * kstep; const char* b2 = last ? nB : cB + (size_t)(t + 2) * kstep;
;             const char* a3 = a2 + kstep; const char* b3 = b2 + kstep;
;             if (last && has_next) S.a_ready(nxt);
;             if constexpr (SP2) {
;             PG8_LDB(B0, 0, 0); PG8_LDB(B1, 0, 1); PG8_SCHED; PG8_LDA(At, 0, 0); PG8_STAGE(PG8_SA(1, 1), a1 + hstep, voffA);
;     ...
;             PG8_LDA(At, 1, 1); PG8_STAGE(PG8_SB(1, 0), b3, voffB); PG8_STAGE(PG8_SB(1, 1), b3 + hstep, voffB); PG8_STAGE(PG8_SA(1, 0), a3, voffA);
;             PG8_WAIT_V(8); PG8_WAIT_L(0); PG8_BAR; PG8_MMA(1, 0, At, B0); PG8_MMA(1, 1, At, B1); PG8_BAR; PG8_SCHED;
	s_add_i32 s3, s3, s34
	v_lshl_add_u64 v[202:203], v[202:203], 0, s[38:39]
	s_mov_b32 m0, s3
	ds_read_b128 v[190:193], v157 offset:49152
	ds_read_b128 v[194:197], v157 offset:50176
	ds_read_b128 v[198:201], v157 offset:51200
	ds_read_b128 v[208:211], v157 offset:52224
	ds_read_b128 v[212:215], v157 offset:53248
	ds_read_b128 v[216:219], v157 offset:54272
	ds_read_b128 v[220:223], v157 offset:55296
	ds_read_b128 v[224:227], v157 offset:56320
	global_load_lds_dwordx4 v[202:203], off
	s_add_i32 m0, s3, 0x2000
	s_add_u32 s14, s62, 0x40080
	v_lshl_add_u64 v[202:203], v[228:229], 0, s[38:39]
	s_addc_u32 s15, s63, 0
	s_add_i32 s3, s33, s34
	global_load_lds_dwordx4 v[202:203], off
	v_lshl_add_u64 v[202:203], s[14:15], 0, v[134:135]
	s_mov_b32 m0, s3
	s_nop 0
	global_load_lds_dwordx4 v[202:203], off
	v_lshl_add_u64 v[202:203], s[14:15], 0, v[138:139]
	s_add_i32 m0, s3, 0x2000
	s_nop 0
	global_load_lds_dwordx4 v[202:203], off
	s_waitcnt vmcnt(6)
	s_waitcnt lgkmcnt(0)
	s_barrier
	s_setprio 1
	s_waitcnt lgkmcnt(0)
	v_mfma_f32_16x16x32_bf16 v[60:63], v[148:151], v[190:193], v[60:63]
	v_mfma_f32_16x16x32_bf16 v[56:59], v[164:167], v[190:193], v[56:59]
	v_mfma_f32_16x16x32_bf16 v[44:47], v[148:151], v[198:201], v[44:47]
	v_mfma_f32_16x16x32_bf16 v[40:43], v[164:167], v[198:201], v[40:43]
	v_mfma_f32_16x16x32_bf16 v[28:31], v[148:151], v[212:215], v[28:31]
	v_mfma_f32_16x16x32_bf16 v[24:27], v[164:167], v[212:215], v[24:27]
	v_mfma_f32_16x16x32_bf16 v[12:15], v[148:151], v[220:223], v[12:15]
	v_mfma_f32_16x16x32_bf16 v[8:11], v[164:167], v[220:223], v[8:11]
	v_mfma_f32_16x16x32_bf16 v[60:63], v[160:163], v[194:197], v[60:63]
	v_mfma_f32_16x16x32_bf16 v[56:59], v[168:171], v[194:197], v[56:59]
	v_mfma_f32_16x16x32_bf16 v[44:47], v[160:163], v[208:211], v[44:47]
	v_mfma_f32_16x16x32_bf16 v[40:43], v[168:171], v[208:211], v[40:43]
	v_mfma_f32_16x16x32_bf16 v[28:31], v[160:163], v[216:219], v[28:31]
	v_mfma_f32_16x16x32_bf16 v[24:27], v[168:171], v[216:219], v[24:27]
	v_lshl_add_u64 v[202:203], v[230:231], 0, s[38:39]
	s_mov_b32 m0, s75
	s_nop 0
	global_load_lds_dwordx4 v[202:203], off
	v_mfma_f32_16x16x32_bf16 v[12:15], v[160:163], v[224:227], v[12:15]
	v_mfma_f32_16x16x32_bf16 v[8:11], v[168:171], v[224:227], v[8:11]
	s_setprio 0
	s_setprio 1
	v_mfma_f32_16x16x32_bf16 v[52:55], v[172:175], v[190:193], v[52:55]
	v_mfma_f32_16x16x32_bf16 v[48:51], v[182:185], v[190:193], v[48:51]
	v_mfma_f32_16x16x32_bf16 v[36:39], v[172:175], v[198:201], v[36:39]
	v_mfma_f32_16x16x32_bf16 v[32:35], v[182:185], v[198:201], v[32:35]
	v_mfma_f32_16x16x32_bf16 v[20:23], v[172:175], v[212:215], v[20:23]
	v_mfma_f32_16x16x32_bf16 v[16:19], v[182:185], v[212:215], v[16:19]
	v_mfma_f32_16x16x32_bf16 v[4:7], v[172:175], v[220:223], v[4:7]
	v_mfma_f32_16x16x32_bf16 v[0:3], v[182:185], v[220:223], v[0:3]
	v_mfma_f32_16x16x32_bf16 v[52:55], v[176:179], v[194:197], v[52:55]
	v_mfma_f32_16x16x32_bf16 v[48:51], v[186:189], v[194:197], v[48:51]
	v_mfma_f32_16x16x32_bf16 v[36:39], v[176:179], v[208:211], v[36:39]
	v_mfma_f32_16x16x32_bf16 v[32:35], v[186:189], v[208:211], v[32:35]
	v_mfma_f32_16x16x32_bf16 v[20:23], v[176:179], v[216:219], v[20:23]
	v_mfma_f32_16x16x32_bf16 v[16:19], v[186:189], v[216:219], v[16:19]
	v_lshl_add_u64 v[202:203], v[232:233], 0, s[38:39]
	s_mov_b32 m0, s84
	s_nop 0
	global_load_lds_dwordx4 v[202:203], off
	v_mfma_f32_16x16x32_bf16 v[4:7], v[176:179], v[224:227], v[4:7]
	v_mfma_f32_16x16x32_bf16 v[0:3], v[186:189], v[224:227], v[0:3]
	s_setprio 0
	s_barrier
	s_add_i32 s92, s92, 2
	s_add_u32 s60, s60, 0x100
	s_addc_u32 s61, s61, 0
	s_add_u32 s90, s90, 0x100
	s_addc_u32 s91, s91, 0
.LBB0_650:
	ds_read_b128 v[148:151], v155
	ds_read_b128 v[160:163], v155 offset:1024
	ds_read_b128 v[164:167], v155 offset:2048
	ds_read_b128 v[168:171], v155 offset:3072
	ds_read_b128 v[172:175], v156
	ds_read_b128 v[176:179], v156 offset:1024
	ds_read_b128 v[182:185], v156 offset:2048
	ds_read_b128 v[186:189], v156 offset:3072
	s_add_u32 s3, s60, 0xfffc0080
	s_addc_u32 s14, s61, -1
	s_cmp_eq_u32 s92, 12
	s_cselect_b32 s65, s51, s14
	s_cselect_b32 s64, s57, s3
	s_cselect_b32 s63, s49, s91
	s_cselect_b32 s62, s89, s90
	v_lshl_add_u64 v[202:203], s[60:61], 0, v[140:141]
	s_add_i32 m0, s43, 0xc000
	ds_read_b128 v[190:193], v157
	ds_read_b128 v[194:197], v157 offset:1024
	ds_read_b128 v[198:201], v157 offset:2048
	ds_read_b128 v[208:211], v157 offset:3072
	ds_read_b128 v[212:215], v157 offset:4096
	ds_read_b128 v[216:219], v157 offset:5120
	ds_read_b128 v[220:223], v157 offset:6144
	ds_read_b128 v[224:227], v157 offset:7168
	global_load_lds_dwordx4 v[202:203], off
	v_lshl_add_u64 v[202:203], s[60:61], 0, v[142:143]
	s_add_i32 m0, s43, 0xe000
	s_nop 0
	global_load_lds_dwordx4 v[202:203], off
	s_waitcnt vmcnt(8)
	s_waitcnt lgkmcnt(0)
	s_barrier
; #define PG8_STAGE(bufoff, gbase, voff) do { _Pragma("unroll") for (int _i = 0; _i < 2; ++_i) \
;         __builtin_amdgcn_global_load_lds((const unsigned*)((const char*)(gbase) + (voff)[_i]), (PG8_LAS unsigned*)(lds + (bufoff) + ldsw + _i * 8192), 16, 0, 0); } while (0)
; #define PG8_LDA(dst, b, h) do { _Pragma("unroll") for (int m = 0; m < 4; ++m) _Pragma("unroll") for (int k = 0; k < 2; ++k) dst[m][k] = *(const PG8_LAS bf16x8*)(lds + PG8_SA(b, h) + aoff + m * 2048 + k * 1024); } while (0)
; #define PG8_MMA(ai, bj, At, Bt) do { __builtin_amdgcn_s_setprio(1); _Pragma("unroll") for (int m = 0; m < 4; ++m) _Pragma("unroll") for (int n = 0; n < 2; ++n) _Pragma("unroll") for (int k = 0; k < 2; ++k) \
;         acc[ai][bj][m][n] = __builtin_amdgcn_mfma_f32_16x16x32_bf16(Bt[n][k], At[m][k], acc[ai][bj][m][n], 0, 0, 0); __builtin_amdgcn_s_setprio(0); } while (0)
; #define PG8_WAIT_V(n) asm volatile("s_waitcnt vmcnt(" #n ")" ::: "memory")
; #define PG8_WAIT_L(n) asm volatile("s_waitcnt lgkmcnt(" #n ")" ::: "memory")
; #define PG8_BAR __builtin_amdgcn_s_barrier()
; #define PG8_SCHED __builtin_amdgcn_sched_barrier(0)
; template <class Epi, class Sched, bool ALIGN_EPI = false, bool SP2 = false>
; __device__ __forceinline__ void gemm_phase(PG8_LAS unsigned char* lds, const Gemm g, const Sched& S, const Epi& E) {
;     ...
;             PG8_WAIT_V(8); PG8_WAIT_L(0); PG8_BAR; PG8_MMA(0, 0, At, B0); PG8_MMA(0, 1, At, B1); PG8_BAR; PG8_SCHED;
;             PG8_LDA(At, 0, 1); PG8_STAGE(PG8_SB(0, 0), b2, voffB); PG8_STAGE(PG8_SB(0, 1), b2 + hstep, voffB); PG8_STAGE(PG8_SA(0, 0), a2, voffA);
;             PG8_WAIT_V(8); PG8_WAIT_L(0); PG8_BAR; PG8_MMA(1, 0, At, B0); PG8_MMA(1, 1, At, B1); PG8_BAR; PG8_SCHED;
	s_setprio 1
	s_waitcnt lgkmcnt(0)
	v_mfma_f32_16x16x32_bf16 v[124:127], v[148:151], v[190:193], v[124:127]
	v_mfma_f32_16x16x32_bf16 v[120:123], v[164:167], v[190:193], v[120:123]
	v_mfma_f32_16x16x32_bf16 v[108:111], v[148:151], v[198:201], v[108:111]
	v_mfma_f32_16x16x32_bf16 v[104:107], v[164:167], v[198:201], v[104:107]
	v_mfma_f32_16x16x32_bf16 v[92:95], v[148:151], v[212:215], v[92:95]
	v_mfma_f32_16x16x32_bf16 v[88:91], v[164:167], v[212:215], v[88:91]
	v_mfma_f32_16x16x32_bf16 v[76:79], v[148:151], v[220:223], v[76:79]
	v_mfma_f32_16x16x32_bf16 v[72:75], v[164:167], v[220:223], v[72:75]
	v_mfma_f32_16x16x32_bf16 v[124:127], v[160:163], v[194:197], v[124:127]
	v_mfma_f32_16x16x32_bf16 v[120:123], v[168:171], v[194:197], v[120:123]
	v_mfma_f32_16x16x32_bf16 v[108:111], v[160:163], v[208:211], v[108:111]
	v_mfma_f32_16x16x32_bf16 v[104:107], v[168:171], v[208:211], v[104:107]
	v_mfma_f32_16x16x32_bf16 v[92:95], v[160:163], v[216:219], v[92:95]
	v_mfma_f32_16x16x32_bf16 v[88:91], v[168:171], v[216:219], v[88:91]
	v_mfma_f32_16x16x32_bf16 v[76:79], v[160:163], v[224:227], v[76:79]
	v_mfma_f32_16x16x32_bf16 v[72:75], v[168:171], v[224:227], v[72:75]
	s_setprio 0
	s_setprio 1
	v_mfma_f32_16x16x32_bf16 v[116:119], v[172:175], v[190:193], v[116:119]
	v_mfma_f32_16x16x32_bf16 v[112:115], v[182:185], v[190:193], v[112:115]
	v_mfma_f32_16x16x32_bf16 v[100:103], v[172:175], v[198:201], v[100:103]
	v_mfma_f32_16x16x32_bf16 v[96:99], v[182:185], v[198:201], v[96:99]
	v_mfma_f32_16x16x32_bf16 v[84:87], v[172:175], v[212:215], v[84:87]
	v_mfma_f32_16x16x32_bf16 v[80:83], v[182:185], v[212:215], v[80:83]
	v_mfma_f32_16x16x32_bf16 v[68:71], v[172:175], v[220:223], v[68:71]
	v_mfma_f32_16x16x32_bf16 v[64:67], v[182:185], v[220:223], v[64:67]
	v_mfma_f32_16x16x32_bf16 v[116:119], v[176:179], v[194:197], v[116:119]
	v_mfma_f32_16x16x32_bf16 v[112:115], v[186:189], v[194:197], v[112:115]
	v_mfma_f32_16x16x32_bf16 v[100:103], v[176:179], v[208:211], v[100:103]
	v_mfma_f32_16x16x32_bf16 v[96:99], v[186:189], v[208:211], v[96:99]
	v_mfma_f32_16x16x32_bf16 v[84:87], v[176:179], v[216:219], v[84:87]
	v_mfma_f32_16x16x32_bf16 v[80:83], v[186:189], v[216:219], v[80:83]
	v_mfma_f32_16x16x32_bf16 v[68:71], v[176:179], v[224:227], v[68:71]
	v_mfma_f32_16x16x32_bf16 v[64:67], v[186:189], v[224:227], v[64:67]
	s_setprio 0
	s_barrier
	s_add_i32 s3, s85, s34
	v_lshl_add_u64 v[202:203], s[62:63], 0, v[134:135]
	s_mov_b32 m0, s3
	ds_read_b128 v[190:193], v157 offset:16384
	ds_read_b128 v[194:197], v157 offset:17408
	ds_read_b128 v[198:201], v157 offset:18432
	ds_read_b128 v[208:211], v157 offset:19456
	ds_read_b128 v[212:215], v157 offset:20480
	ds_read_b128 v[216:219], v157 offset:21504
	ds_read_b128 v[220:223], v157 offset:22528
	ds_read_b128 v[224:227], v157 offset:23552
	global_load_lds_dwordx4 v[202:203], off
	s_add_i32 m0, s3, 0x2000
	s_add_u32 s14, s62, 0x40000
	v_lshl_add_u64 v[228:229], s[62:63], 0, v[138:139]
	s_addc_u32 s15, s63, 0
	s_add_i32 s3, s86, s34
	global_load_lds_dwordx4 v[228:229], off
	v_lshl_add_u64 v[230:231], s[14:15], 0, v[134:135]
	s_mov_b32 m0, s3
	global_load_lds_dwordx4 v[230:231], off
	v_lshl_add_u64 v[230:231], s[14:15], 0, v[138:139]
	s_add_i32 m0, s3, 0x2000
	s_nop 0
	global_load_lds_dwordx4 v[230:231], off
	s_waitcnt vmcnt(6)
	s_waitcnt lgkmcnt(0)
	s_barrier
	s_setprio 1
	s_waitcnt lgkmcnt(0)
	v_mfma_f32_16x16x32_bf16 v[60:63], v[148:151], v[190:193], v[60:63]
	v_mfma_f32_16x16x32_bf16 v[56:59], v[164:167], v[190:193], v[56:59]
	v_mfma_f32_16x16x32_bf16 v[44:47], v[148:151], v[198:201], v[44:47]
	v_mfma_f32_16x16x32_bf16 v[40:43], v[164:167], v[198:201], v[40:43]
	v_mfma_f32_16x16x32_bf16 v[28:31], v[148:151], v[212:215], v[28:31]
	v_mfma_f32_16x16x32_bf16 v[24:27], v[164:167], v[212:215], v[24:27]
	v_mfma_f32_16x16x32_bf16 v[12:15], v[148:151], v[220:223], v[12:15]
	v_mfma_f32_16x16x32_bf16 v[8:11], v[164:167], v[220:223], v[8:11]
	v_mfma_f32_16x16x32_bf16 v[60:63], v[160:163], v[194:197], v[60:63]
	v_mfma_f32_16x16x32_bf16 v[56:59], v[168:171], v[194:197], v[56:59]
	v_mfma_f32_16x16x32_bf16 v[44:47], v[160:163], v[208:211], v[44:47]
	v_mfma_f32_16x16x32_bf16 v[40:43], v[168:171], v[208:211], v[40:43]
	v_mfma_f32_16x16x32_bf16 v[28:31], v[160:163], v[216:219], v[28:31]
	v_mfma_f32_16x16x32_bf16 v[24:27], v[168:171], v[216:219], v[24:27]
	v_lshl_add_u64 v[230:231], s[64:65], 0, v[132:133]
	s_mov_b32 m0, s43
	s_nop 0
	global_load_lds_dwordx4 v[230:231], off
	v_mfma_f32_16x16x32_bf16 v[12:15], v[160:163], v[224:227], v[12:15]
	v_mfma_f32_16x16x32_bf16 v[8:11], v[168:171], v[224:227], v[8:11]
	s_setprio 0
	s_setprio 1
	v_mfma_f32_16x16x32_bf16 v[52:55], v[172:175], v[190:193], v[52:55]
	v_mfma_f32_16x16x32_bf16 v[48:51], v[182:185], v[190:193], v[48:51]
	v_mfma_f32_16x16x32_bf16 v[36:39], v[172:175], v[198:201], v[36:39]
	v_mfma_f32_16x16x32_bf16 v[32:35], v[182:185], v[198:201], v[32:35]
	v_mfma_f32_16x16x32_bf16 v[20:23], v[172:175], v[212:215], v[20:23]
	v_mfma_f32_16x16x32_bf16 v[16:19], v[182:185], v[212:215], v[16:19]
	v_mfma_f32_16x16x32_bf16 v[4:7], v[172:175], v[220:223], v[4:7]
	v_mfma_f32_16x16x32_bf16 v[0:3], v[182:185], v[220:223], v[0:3]
	v_mfma_f32_16x16x32_bf16 v[52:55], v[176:179], v[194:197], v[52:55]
	v_mfma_f32_16x16x32_bf16 v[48:51], v[186:189], v[194:197], v[48:51]
	v_mfma_f32_16x16x32_bf16 v[36:39], v[176:179], v[208:211], v[36:39]
	v_mfma_f32_16x16x32_bf16 v[32:35], v[186:189], v[208:211], v[32:35]
	v_mfma_f32_16x16x32_bf16 v[20:23], v[176:179], v[216:219], v[20:23]
	v_mfma_f32_16x16x32_bf16 v[16:19], v[186:189], v[216:219], v[16:19]
	v_lshl_add_u64 v[232:233], s[64:65], 0, v[136:137]
	s_mov_b32 m0, s59
	s_nop 0
	global_load_lds_dwordx4 v[232:233], off
	v_mfma_f32_16x16x32_bf16 v[4:7], v[176:179], v[224:227], v[4:7]
	v_mfma_f32_16x16x32_bf16 v[0:3], v[186:189], v[224:227], v[0:3]
	s_setprio 0
	s_barrier
; #define PG8_STAGE(bufoff, gbase, voff) do { _Pragma("unroll") for (int _i = 0; _i < 2; ++_i) \
;         __builtin_amdgcn_global_load_lds((const unsigned*)((const char*)(gbase) + (voff)[_i]), (PG8_LAS unsigned*)(lds + (bufoff) + ldsw + _i * 8192), 16, 0, 0); } while (0)
; #define PG8_LDA(dst, b, h) do { _Pragma("unroll") for (int m = 0; m < 4; ++m) _Pragma("unroll") for (int k = 0; k < 2; ++k) dst[m][k] = *(const PG8_LAS bf16x8*)(lds + PG8_SA(b, h) + aoff + m * 2048 + k * 1024); } while (0)
; #define PG8_LDB(dst, b, h) do { _Pragma("unroll") for (int n = 0; n < 2; ++n) _Pragma("unroll") for (int k = 0; k < 2; ++k) dst[n][k] = *(const PG8_LAS bf16x8*)(lds + PG8_SB(b, h) + boff + n * 2048 + k * 1024); } while (0)
; #define PG8_MMA(ai, bj, At, Bt) do { __builtin_amdgcn_s_setprio(1); _Pragma("unroll") for (int m = 0; m < 4; ++m) _Pragma("unroll") for (int n = 0; n < 2; ++n) _Pragma("unroll") for (int k = 0; k < 2; ++k) \
;         acc[ai][bj][m][n] = __builtin_amdgcn_mfma_f32_16x16x32_bf16(Bt[n][k], At[m][k], acc[ai][bj][m][n], 0, 0, 0); __builtin_amdgcn_s_setprio(0); } while (0)
; #define PG8_WAIT_V(n) asm volatile("s_waitcnt vmcnt(" #n ")" ::: "memory")
; #define PG8_WAIT_L(n) asm volatile("s_waitcnt lgkmcnt(" #n ")" ::: "memory")
; #define PG8_BAR __builtin_amdgcn_s_barrier()
; #define PG8_SCHED __builtin_amdgcn_sched_barrier(0)
; template <class Epi, class Sched, bool ALIGN_EPI = false, bool SP2 = false>
; __device__ __forceinline__ void gemm_phase(PG8_LAS unsigned char* lds, const Gemm g, const Sched& S, const Epi& E) {
;     ...
;             PG8_LDB(B0, 1, 0); PG8_LDB(B1, 1, 1); PG8_SCHED; PG8_LDA(At, 1, 0); PG8_STAGE(PG8_SA(0, 1), a2 + hstep, voffA);
;             PG8_WAIT_V(8); PG8_WAIT_L(0); PG8_BAR; PG8_MMA(0, 0, At, B0); PG8_MMA(0, 1, At, B1); PG8_BAR; PG8_SCHED;
	s_add_i32 s3, 0, 0x18000
	v_add_u32_e32 v159, s3, v131
	s_add_i32 s33, 0, 0x1c000
	ds_read_b128 v[148:151], v159
	ds_read_b128 v[160:163], v159 offset:1024
	ds_read_b128 v[164:167], v159 offset:2048
	ds_read_b128 v[168:171], v159 offset:3072
	v_add_u32_e32 v159, s33, v131
	ds_read_b128 v[172:175], v159
	ds_read_b128 v[176:179], v159 offset:1024
	ds_read_b128 v[182:185], v159 offset:2048
	ds_read_b128 v[186:189], v159 offset:3072
	s_add_u32 s14, s64, 0x40000
	s_addc_u32 s15, s65, 0
	s_mov_b32 m0, s66
	v_lshl_add_u64 v[234:235], s[14:15], 0, v[132:133]
	ds_read_b128 v[190:193], v157 offset:32768
	ds_read_b128 v[194:197], v157 offset:33792
	ds_read_b128 v[198:201], v157 offset:34816
	ds_read_b128 v[208:211], v157 offset:35840
	ds_read_b128 v[212:215], v157 offset:36864
	ds_read_b128 v[216:219], v157 offset:37888
	ds_read_b128 v[220:223], v157 offset:38912
	ds_read_b128 v[224:227], v157 offset:39936
	global_load_lds_dwordx4 v[234:235], off
	v_lshl_add_u64 v[234:235], s[14:15], 0, v[136:137]
	s_mov_b32 m0, s67
	s_nop 0
	global_load_lds_dwordx4 v[234:235], off
	s_waitcnt vmcnt(8)
	s_waitcnt lgkmcnt(0)
	s_barrier
	s_setprio 1
	s_waitcnt lgkmcnt(0)
	v_mfma_f32_16x16x32_bf16 v[124:127], v[148:151], v[190:193], v[124:127]
	v_mfma_f32_16x16x32_bf16 v[120:123], v[164:167], v[190:193], v[120:123]
	v_mfma_f32_16x16x32_bf16 v[108:111], v[148:151], v[198:201], v[108:111]
	v_mfma_f32_16x16x32_bf16 v[104:107], v[164:167], v[198:201], v[104:107]
	v_mfma_f32_16x16x32_bf16 v[92:95], v[148:151], v[212:215], v[92:95]
	v_mfma_f32_16x16x32_bf16 v[88:91], v[164:167], v[212:215], v[88:91]
	v_mfma_f32_16x16x32_bf16 v[76:79], v[148:151], v[220:223], v[76:79]
	v_mfma_f32_16x16x32_bf16 v[72:75], v[164:167], v[220:223], v[72:75]
	v_mfma_f32_16x16x32_bf16 v[124:127], v[160:163], v[194:197], v[124:127]
	v_mfma_f32_16x16x32_bf16 v[120:123], v[168:171], v[194:197], v[120:123]
	v_mfma_f32_16x16x32_bf16 v[108:111], v[160:163], v[208:211], v[108:111]
	v_mfma_f32_16x16x32_bf16 v[104:107], v[168:171], v[208:211], v[104:107]
	v_mfma_f32_16x16x32_bf16 v[92:95], v[160:163], v[216:219], v[92:95]
	v_mfma_f32_16x16x32_bf16 v[88:91], v[168:171], v[216:219], v[88:91]
	v_mfma_f32_16x16x32_bf16 v[76:79], v[160:163], v[224:227], v[76:79]
	v_mfma_f32_16x16x32_bf16 v[72:75], v[168:171], v[224:227], v[72:75]
	s_setprio 0
	s_setprio 1
	v_mfma_f32_16x16x32_bf16 v[116:119], v[172:175], v[190:193], v[116:119]
	v_mfma_f32_16x16x32_bf16 v[112:115], v[182:185], v[190:193], v[112:115]
	v_mfma_f32_16x16x32_bf16 v[100:103], v[172:175], v[198:201], v[100:103]
	v_mfma_f32_16x16x32_bf16 v[96:99], v[182:185], v[198:201], v[96:99]
	v_mfma_f32_16x16x32_bf16 v[84:87], v[172:175], v[212:215], v[84:87]
	v_mfma_f32_16x16x32_bf16 v[80:83], v[182:185], v[212:215], v[80:83]
	v_mfma_f32_16x16x32_bf16 v[68:71], v[172:175], v[220:223], v[68:71]
	v_mfma_f32_16x16x32_bf16 v[64:67], v[182:185], v[220:223], v[64:67]
	v_mfma_f32_16x16x32_bf16 v[116:119], v[176:179], v[194:197], v[116:119]
	v_mfma_f32_16x16x32_bf16 v[112:115], v[186:189], v[194:197], v[112:115]
	v_mfma_f32_16x16x32_bf16 v[100:103], v[176:179], v[208:211], v[100:103]
	v_mfma_f32_16x16x32_bf16 v[96:99], v[186:189], v[208:211], v[96:99]
	v_mfma_f32_16x16x32_bf16 v[84:87], v[176:179], v[216:219], v[84:87]
	v_mfma_f32_16x16x32_bf16 v[80:83], v[186:189], v[216:219], v[80:83]
	v_mfma_f32_16x16x32_bf16 v[68:71], v[176:179], v[224:227], v[68:71]
	v_mfma_f32_16x16x32_bf16 v[64:67], v[186:189], v[224:227], v[64:67]
	s_setprio 0
	s_barrier
; #define PG8_STAGE(bufoff, gbase, voff) do { _Pragma("unroll") for (int _i = 0; _i < 2; ++_i) \
;         __builtin_amdgcn_global_load_lds((const unsigned*)((const char*)(gbase) + (voff)[_i]), (PG8_LAS unsigned*)(lds + (bufoff) + ldsw + _i * 8192), 16, 0, 0); } while (0)
; #define PG8_LDA(dst, b, h) do { _Pragma("unroll") for (int m = 0; m < 4; ++m) _Pragma("unroll") for (int k = 0; k < 2; ++k) dst[m][k] = *(const PG8_LAS bf16x8*)(lds + PG8_SA(b, h) + aoff + m * 2048 + k * 1024); } while (0)
; #define PG8_MMA(ai, bj, At, Bt) do { __builtin_amdgcn_s_setprio(1); _Pragma("unroll") for (int m = 0; m < 4; ++m) _Pragma("unroll") for (int n = 0; n < 2; ++n) _Pragma("unroll") for (int k = 0; k < 2; ++k) \
;         acc[ai][bj][m][n] = __builtin_amdgcn_mfma_f32_16x16x32_bf16(Bt[n][k], At[m][k], acc[ai][bj][m][n], 0, 0, 0); __builtin_amdgcn_s_setprio(0); } while (0)
; #define PG8_WAIT_V(n) asm volatile("s_waitcnt vmcnt(" #n ")" ::: "memory")
; #define PG8_WAIT_L(n) asm volatile("s_waitcnt lgkmcnt(" #n ")" ::: "memory")
; #define PG8_BAR __builtin_amdgcn_s_barrier()
; #define PG8_SCHED __builtin_amdgcn_sched_barrier(0)
; template <class Epi, class Sched, bool ALIGN_EPI = false, bool SP2 = false>
; __device__ __forceinline__ void gemm_phase(PG8_LAS unsigned char* lds, const Gemm g, const Sched& S, const Epi& E) {
;     ...
;             PG8_LDA(At, 1, 1); PG8_STAGE(PG8_SB(1, 0), b3, voffB); PG8_STAGE(PG8_SB(1, 1), b3 + hstep, voffB); PG8_STAGE(PG8_SA(1, 0), a3, voffA);
;             PG8_WAIT_V(8); PG8_WAIT_L(0); PG8_BAR; PG8_MMA(1, 0, At, B0); PG8_MMA(1, 1, At, B1); PG8_BAR; PG8_SCHED;
	s_add_i32 s3, s3, s34
	v_lshl_add_u64 v[202:203], v[202:203], 0, s[38:39]
	s_mov_b32 m0, s3
	ds_read_b128 v[190:193], v157 offset:49152
	ds_read_b128 v[194:197], v157 offset:50176
	ds_read_b128 v[198:201], v157 offset:51200
	ds_read_b128 v[208:211], v157 offset:52224
	ds_read_b128 v[212:215], v157 offset:53248
	ds_read_b128 v[216:219], v157 offset:54272
	ds_read_b128 v[220:223], v157 offset:55296
	ds_read_b128 v[224:227], v157 offset:56320
	global_load_lds_dwordx4 v[202:203], off
	s_add_i32 m0, s3, 0x2000
	s_add_u32 s14, s62, 0x40080
	v_lshl_add_u64 v[202:203], v[228:229], 0, s[38:39]
	s_addc_u32 s15, s63, 0
	s_add_i32 s3, s33, s34
	global_load_lds_dwordx4 v[202:203], off
	v_lshl_add_u64 v[202:203], s[14:15], 0, v[134:135]
	s_mov_b32 m0, s3
	s_nop 0
	global_load_lds_dwordx4 v[202:203], off
	v_lshl_add_u64 v[202:203], s[14:15], 0, v[138:139]
	s_add_i32 m0, s3, 0x2000
	s_nop 0
	global_load_lds_dwordx4 v[202:203], off
	s_waitcnt vmcnt(6)
	s_waitcnt lgkmcnt(0)
	s_barrier
	s_setprio 1
	s_waitcnt lgkmcnt(0)
	v_mfma_f32_16x16x32_bf16 v[60:63], v[148:151], v[190:193], v[60:63]
	v_mfma_f32_16x16x32_bf16 v[56:59], v[164:167], v[190:193], v[56:59]
	v_mfma_f32_16x16x32_bf16 v[44:47], v[148:151], v[198:201], v[44:47]
	v_mfma_f32_16x16x32_bf16 v[40:43], v[164:167], v[198:201], v[40:43]
	v_mfma_f32_16x16x32_bf16 v[28:31], v[148:151], v[212:215], v[28:31]
	v_mfma_f32_16x16x32_bf16 v[24:27], v[164:167], v[212:215], v[24:27]
	v_mfma_f32_16x16x32_bf16 v[12:15], v[148:151], v[220:223], v[12:15]
	v_mfma_f32_16x16x32_bf16 v[8:11], v[164:167], v[220:223], v[8:11]
	v_mfma_f32_16x16x32_bf16 v[60:63], v[160:163], v[194:197], v[60:63]
	v_mfma_f32_16x16x32_bf16 v[56:59], v[168:171], v[194:197], v[56:59]
	v_mfma_f32_16x16x32_bf16 v[44:47], v[160:163], v[208:211], v[44:47]
	v_mfma_f32_16x16x32_bf16 v[40:43], v[168:171], v[208:211], v[40:43]
	v_mfma_f32_16x16x32_bf16 v[28:31], v[160:163], v[216:219], v[28:31]
	v_mfma_f32_16x16x32_bf16 v[24:27], v[168:171], v[216:219], v[24:27]
	v_lshl_add_u64 v[202:203], v[230:231], 0, s[38:39]
	s_mov_b32 m0, s75
	s_nop 0
	global_load_lds_dwordx4 v[202:203], off
	v_mfma_f32_16x16x32_bf16 v[12:15], v[160:163], v[224:227], v[12:15]
	v_mfma_f32_16x16x32_bf16 v[8:11], v[168:171], v[224:227], v[8:11]
	s_setprio 0
	s_setprio 1
	v_mfma_f32_16x16x32_bf16 v[52:55], v[172:175], v[190:193], v[52:55]
	v_mfma_f32_16x16x32_bf16 v[48:51], v[182:185], v[190:193], v[48:51]
	v_mfma_f32_16x16x32_bf16 v[36:39], v[172:175], v[198:201], v[36:39]
	v_mfma_f32_16x16x32_bf16 v[32:35], v[182:185], v[198:201], v[32:35]
	v_mfma_f32_16x16x32_bf16 v[20:23], v[172:175], v[212:215], v[20:23]
	v_mfma_f32_16x16x32_bf16 v[16:19], v[182:185], v[212:215], v[16:19]
	v_mfma_f32_16x16x32_bf16 v[4:7], v[172:175], v[220:223], v[4:7]
	v_mfma_f32_16x16x32_bf16 v[0:3], v[182:185], v[220:223], v[0:3]
	v_mfma_f32_16x16x32_bf16 v[52:55], v[176:179], v[194:197], v[52:55]
	v_mfma_f32_16x16x32_bf16 v[48:51], v[186:189], v[194:197], v[48:51]
	v_mfma_f32_16x16x32_bf16 v[36:39], v[176:179], v[208:211], v[36:39]
	v_mfma_f32_16x16x32_bf16 v[32:35], v[186:189], v[208:211], v[32:35]
	v_mfma_f32_16x16x32_bf16 v[20:23], v[176:179], v[216:219], v[20:23]
	v_mfma_f32_16x16x32_bf16 v[16:19], v[186:189], v[216:219], v[16:19]
	v_lshl_add_u64 v[202:203], v[232:233], 0, s[38:39]
	s_mov_b32 m0, s84
	s_nop 0
	global_load_lds_dwordx4 v[202:203], off
	v_mfma_f32_16x16x32_bf16 v[4:7], v[176:179], v[224:227], v[4:7]
	v_mfma_f32_16x16x32_bf16 v[0:3], v[186:189], v[224:227], v[0:3]
	s_setprio 0
	s_barrier
	s_add_i32 s92, s92, 2
	s_add_u32 s60, s60, 0x100
	s_addc_u32 s61, s61, 0
	s_add_u32 s90, s90, 0x100
	s_addc_u32 s91, s91, 0
	s_cmp_gt_u32 s92, 13
	s_cbranch_scc0 .LBB0_650
	s_and_b64 vcc, exec, s[44:45]
	s_cbranch_vccz .LBB0_653
	s_barrier

; #define PG8_STAGE(bufoff, gbase, voff) do { _Pragma("unroll") for (int _i = 0; _i < 2; ++_i) \
;         __builtin_amdgcn_global_load_lds((const unsigned*)((const char*)(gbase) + (voff)[_i]), (PG8_LAS unsigned*)(lds + (bufoff) + ldsw + _i * 8192), 16, 0, 0); } while (0)
; #define PG8_LDA(dst, b, h) do { _Pragma("unroll") for (int m = 0; m < 4; ++m) _Pragma("unroll") for (int k = 0; k < 2; ++k) dst[m][k] = *(const PG8_LAS bf16x8*)(lds + PG8_SA(b, h) + aoff + m * 2048 + k * 1024); } while (0)
; #define PG8_LDB(dst, b, h) do { _Pragma("unroll") for (int n = 0; n < 2; ++n) _Pragma("unroll") for (int k = 0; k < 2; ++k) dst[n][k] = *(const PG8_LAS bf16x8*)(lds + PG8_SB(b, h) + boff + n * 2048 + k * 1024); } while (0)
; #define PG8_MMA(ai, bj, At, Bt) do { __builtin_amdgcn_s_setprio(1); _Pragma("unroll") for (int m = 0; m < 4; ++m) _Pragma("unroll") for (int n = 0; n < 2; ++n) _Pragma("unroll") for (int k = 0; k < 2; ++k) \
;         acc[ai][bj][m][n] = __builtin_amdgcn_mfma_f32_16x16x32_bf16(Bt[n][k], At[m][k], acc[ai][bj][m][n], 0, 0, 0); __builtin_amdgcn_s_setprio(0); } while (0)
; #define PG8_BAR __builtin_amdgcn_s_barrier()
; template <class Epi, class Sched, bool ALIGN_EPI = false, bool SP2 = false>
; __device__ __forceinline__ void gemm_phase(PG8_LAS unsigned char* lds, const Gemm g, const Sched& S, const Epi& E) {
;     ...
;         const bool has_next = S.next(ui + 1, nxt);
;         const char* nA = has_next ? (const char*)g.A + (size_t)nxt.pm * tstep : cA; const char* nB = has_next ? (const char*)g.Bt + (size_t)nxt.pn * tstep : cB;
;         for (int t = 0; t < nt; t += 2) {
;             const bool last = (t == nt - 2);
;             const char* a1 = cA + (size_t)(t + 1) * kstep;
;             const char* a2 = last ? nA : cA + (size_t)(t + 2) * kstep; const char* b2 = last ? nB : cB + (size_t)(t + 2) * kstep;
;             const char* a3 = a2 + kstep; const char* b3 = b2 + kstep;
;             if (last && has_next) S.a_ready(nxt);
;             if constexpr (SP2) {
;             PG8_LDB(B0, 0, 0); PG8_LDB(B1, 0, 1); PG8_SCHED; PG8_LDA(At, 0, 0); PG8_STAGE(PG8_SA(1, 1), a1 + hstep, voffA);
;             PG8_WAIT_V(8); PG8_WAIT_L(0); PG8_BAR; PG8_MMA(0, 0, At, B0); PG8_MMA(0, 1, At, B1); PG8_BAR; PG8_SCHED;
;             PG8_LDA(At, 0, 1); PG8_STAGE(PG8_SB(0, 0), b2, voffB); PG8_STAGE(PG8_SB(0, 1), b2 + hstep, voffB); PG8_STAGE(PG8_SA(0, 0), a2, voffA);
.LBB0_737:
	s_ashr_i32 s51, s50, 31
	s_lshl_b64 s[14:15], s[50:51], 19
	s_add_u32 s52, s22, s14
	s_addc_u32 s53, s23, s15
	s_and_b64 s[14:15], s[8:9], exec
	s_cselect_b32 s51, s53, s57
	s_cselect_b32 s82, s52, s56
	s_ashr_i32 s49, s48, 31
	s_lshl_b64 s[14:15], s[48:49], 19
	v_readlane_b32 s3, v250, 15
	s_add_u32 s54, s3, s14
	v_readlane_b32 s3, v250, 16
	s_addc_u32 s55, s3, s15
	s_and_b64 s[14:15], s[8:9], exec
	s_cselect_b32 s49, s55, s59
	s_cselect_b32 s83, s54, s58
	s_add_u32 s56, s56, 0x40080
	s_addc_u32 s57, s57, 0
	s_add_u32 s84, s58, 0x100
	s_addc_u32 s85, s59, 0
	s_mov_b32 s86, -2
	s_waitcnt vmcnt(0)
	ds_read_b128 v[148:151], v155
	ds_read_b128 v[160:163], v155 offset:1024
	ds_read_b128 v[164:167], v155 offset:2048
	ds_read_b128 v[168:171], v155 offset:3072
	ds_read_b128 v[172:175], v156
	ds_read_b128 v[176:179], v156 offset:1024
	ds_read_b128 v[182:185], v156 offset:2048
	ds_read_b128 v[186:189], v156 offset:3072
	s_add_u32 s3, s56, 0xfffc0080
	s_addc_u32 s14, s57, -1
	s_cmp_eq_u32 s86, 12
	s_cselect_b32 s61, s51, s14
	s_cselect_b32 s60, s82, s3
	s_cselect_b32 s59, s49, s85
	s_cselect_b32 s58, s83, s84
	v_lshl_add_u64 v[202:203], s[56:57], 0, v[140:141]
	s_add_i32 m0, s43, 0xc000
	ds_read_b128 v[190:193], v157
	ds_read_b128 v[194:197], v157 offset:1024
	ds_read_b128 v[198:201], v157 offset:2048
	ds_read_b128 v[208:211], v157 offset:3072
	ds_read_b128 v[212:215], v157 offset:4096
	ds_read_b128 v[216:219], v157 offset:5120
	ds_read_b128 v[220:223], v157 offset:6144
	ds_read_b128 v[224:227], v157 offset:7168
	global_load_lds_dwordx4 v[202:203], off
	v_lshl_add_u64 v[202:203], s[56:57], 0, v[142:143]
	s_add_i32 m0, s43, 0xe000
	s_nop 0
	global_load_lds_dwordx4 v[202:203], off
	s_waitcnt vmcnt(8)
	s_waitcnt lgkmcnt(0)
	s_barrier
	s_setprio 1
	s_waitcnt lgkmcnt(0)
	v_mfma_f32_16x16x32_bf16 v[124:127], v[148:151], v[190:193], 0
	v_mfma_f32_16x16x32_bf16 v[120:123], v[164:167], v[190:193], 0
	v_mfma_f32_16x16x32_bf16 v[108:111], v[148:151], v[198:201], 0
	v_mfma_f32_16x16x32_bf16 v[104:107], v[164:167], v[198:201], 0
	v_mfma_f32_16x16x32_bf16 v[92:95], v[148:151], v[212:215], 0
	v_mfma_f32_16x16x32_bf16 v[88:91], v[164:167], v[212:215], 0
	v_mfma_f32_16x16x32_bf16 v[76:79], v[148:151], v[220:223], 0
	v_mfma_f32_16x16x32_bf16 v[72:75], v[164:167], v[220:223], 0
	v_mfma_f32_16x16x32_bf16 v[124:127], v[160:163], v[194:197], v[124:127]
	v_mfma_f32_16x16x32_bf16 v[120:123], v[168:171], v[194:197], v[120:123]
	v_mfma_f32_16x16x32_bf16 v[108:111], v[160:163], v[208:211], v[108:111]
	v_mfma_f32_16x16x32_bf16 v[104:107], v[168:171], v[208:211], v[104:107]
	v_mfma_f32_16x16x32_bf16 v[92:95], v[160:163], v[216:219], v[92:95]
	v_mfma_f32_16x16x32_bf16 v[88:91], v[168:171], v[216:219], v[88:91]
	v_mfma_f32_16x16x32_bf16 v[76:79], v[160:163], v[224:227], v[76:79]
	v_mfma_f32_16x16x32_bf16 v[72:75], v[168:171], v[224:227], v[72:75]
	s_setprio 0
	s_setprio 1
	v_mfma_f32_16x16x32_bf16 v[116:119], v[172:175], v[190:193], 0
	v_mfma_f32_16x16x32_bf16 v[112:115], v[182:185], v[190:193], 0
	v_mfma_f32_16x16x32_bf16 v[100:103], v[172:175], v[198:201], 0
	v_mfma_f32_16x16x32_bf16 v[96:99], v[182:185], v[198:201], 0
	v_mfma_f32_16x16x32_bf16 v[84:87], v[172:175], v[212:215], 0
	v_mfma_f32_16x16x32_bf16 v[80:83], v[182:185], v[212:215], 0
	v_mfma_f32_16x16x32_bf16 v[68:71], v[172:175], v[220:223], 0
	v_mfma_f32_16x16x32_bf16 v[64:67], v[182:185], v[220:223], 0
	v_mfma_f32_16x16x32_bf16 v[116:119], v[176:179], v[194:197], v[116:119]
	v_mfma_f32_16x16x32_bf16 v[112:115], v[186:189], v[194:197], v[112:115]
	v_mfma_f32_16x16x32_bf16 v[100:103], v[176:179], v[208:211], v[100:103]
	v_mfma_f32_16x16x32_bf16 v[96:99], v[186:189], v[208:211], v[96:99]
	v_mfma_f32_16x16x32_bf16 v[84:87], v[176:179], v[216:219], v[84:87]
	v_mfma_f32_16x16x32_bf16 v[80:83], v[186:189], v[216:219], v[80:83]
	v_mfma_f32_16x16x32_bf16 v[68:71], v[176:179], v[224:227], v[68:71]
	v_mfma_f32_16x16x32_bf16 v[64:67], v[186:189], v[224:227], v[64:67]
	s_setprio 0
	s_barrier
	s_add_i32 s3, s74, s34
	v_lshl_add_u64 v[202:203], s[58:59], 0, v[136:137]
	s_mov_b32 m0, s3
	ds_read_b128 v[190:193], v157 offset:16384
	ds_read_b128 v[194:197], v157 offset:17408
	ds_read_b128 v[198:201], v157 offset:18432
	ds_read_b128 v[208:211], v157 offset:19456
	ds_read_b128 v[212:215], v157 offset:20480
	ds_read_b128 v[216:219], v157 offset:21504
	ds_read_b128 v[220:223], v157 offset:22528
	ds_read_b128 v[224:227], v157 offset:23552
	global_load_lds_dwordx4 v[202:203], off
	s_add_i32 m0, s3, 0x2000
	s_add_u32 s14, s58, 0x40000
	v_lshl_add_u64 v[228:229], s[58:59], 0, v[132:133]
	s_addc_u32 s15, s59, 0
	s_add_i32 s3, s75, s34
	global_load_lds_dwordx4 v[228:229], off
	v_lshl_add_u64 v[230:231], s[14:15], 0, v[136:137]
	s_mov_b32 m0, s3
	global_load_lds_dwordx4 v[230:231], off
	v_lshl_add_u64 v[230:231], s[14:15], 0, v[132:133]
	s_add_i32 m0, s3, 0x2000
	s_nop 0
	global_load_lds_dwordx4 v[230:231], off
	s_waitcnt vmcnt(6)
	s_waitcnt lgkmcnt(0)
	s_barrier
; #define PG8_STAGE(bufoff, gbase, voff) do { _Pragma("unroll") for (int _i = 0; _i < 2; ++_i) \
;         __builtin_amdgcn_global_load_lds((const unsigned*)((const char*)(gbase) + (voff)[_i]), (PG8_LAS unsigned*)(lds + (bufoff) + ldsw + _i * 8192), 16, 0, 0); } while (0)
; #define PG8_LDA(dst, b, h) do { _Pragma("unroll") for (int m = 0; m < 4; ++m) _Pragma("unroll") for (int k = 0; k < 2; ++k) dst[m][k] = *(const PG8_LAS bf16x8*)(lds + PG8_SA(b, h) + aoff + m * 2048 + k * 1024); } while (0)
; #define PG8_LDB(dst, b, h) do { _Pragma("unroll") for (int n = 0; n < 2; ++n) _Pragma("unroll") for (int k = 0; k < 2; ++k) dst[n][k] = *(const PG8_LAS bf16x8*)(lds + PG8_SB(b, h) + boff + n * 2048 + k * 1024); } while (0)
; #define PG8_MMA(ai, bj, At, Bt) do { __builtin_amdgcn_s_setprio(1); _Pragma("unroll") for (int m = 0; m < 4; ++m) _Pragma("unroll") for (int n = 0; n < 2; ++n) _Pragma("unroll") for (int k = 0; k < 2; ++k) \
;         acc[ai][bj][m][n] = __builtin_amdgcn_mfma_f32_16x16x32_bf16(Bt[n][k], At[m][k], acc[ai][bj][m][n], 0, 0, 0); __builtin_amdgcn_s_setprio(0); } while (0)
; #define PG8_WAIT_V(n) asm volatile("s_waitcnt vmcnt(" #n ")" ::: "memory")
; #define PG8_WAIT_L(n) asm volatile("s_waitcnt lgkmcnt(" #n ")" ::: "memory")
; #define PG8_BAR __builtin_amdgcn_s_barrier()
; #define PG8_SCHED __builtin_amdgcn_sched_barrier(0)
; template <class Epi, class Sched, bool ALIGN_EPI = false, bool SP2 = false>
; __device__ __forceinline__ void gemm_phase(PG8_LAS unsigned char* lds, const Gemm g, const Sched& S, const Epi& E) {
;     ...
;             PG8_WAIT_V(8); PG8_WAIT_L(0); PG8_BAR; PG8_MMA(1, 0, At, B0); PG8_MMA(1, 1, At, B1); PG8_BAR; PG8_SCHED;
;             PG8_LDB(B0, 1, 0); PG8_LDB(B1, 1, 1); PG8_SCHED; PG8_LDA(At, 1, 0); PG8_STAGE(PG8_SA(0, 1), a2 + hstep, voffA);
;             PG8_WAIT_V(8); PG8_WAIT_L(0); PG8_BAR; PG8_MMA(0, 0, At, B0); PG8_MMA(0, 1, At, B1); PG8_BAR; PG8_SCHED;
	s_setprio 1
	s_waitcnt lgkmcnt(0)
	v_mfma_f32_16x16x32_bf16 v[60:63], v[148:151], v[190:193], 0
	v_mfma_f32_16x16x32_bf16 v[56:59], v[164:167], v[190:193], 0
	v_mfma_f32_16x16x32_bf16 v[44:47], v[148:151], v[198:201], 0
	v_mfma_f32_16x16x32_bf16 v[40:43], v[164:167], v[198:201], 0
	v_mfma_f32_16x16x32_bf16 v[28:31], v[148:151], v[212:215], 0
	v_mfma_f32_16x16x32_bf16 v[24:27], v[164:167], v[212:215], 0
	v_mfma_f32_16x16x32_bf16 v[12:15], v[148:151], v[220:223], 0
	v_mfma_f32_16x16x32_bf16 v[8:11], v[164:167], v[220:223], 0
	v_mfma_f32_16x16x32_bf16 v[60:63], v[160:163], v[194:197], v[60:63]
	v_mfma_f32_16x16x32_bf16 v[56:59], v[168:171], v[194:197], v[56:59]
	v_mfma_f32_16x16x32_bf16 v[44:47], v[160:163], v[208:211], v[44:47]
	v_mfma_f32_16x16x32_bf16 v[40:43], v[168:171], v[208:211], v[40:43]
	v_mfma_f32_16x16x32_bf16 v[28:31], v[160:163], v[216:219], v[28:31]
	v_mfma_f32_16x16x32_bf16 v[24:27], v[168:171], v[216:219], v[24:27]
	v_lshl_add_u64 v[230:231], s[60:61], 0, v[138:139]
	s_mov_b32 m0, s43
	s_nop 0
	global_load_lds_dwordx4 v[230:231], off
	v_mfma_f32_16x16x32_bf16 v[12:15], v[160:163], v[224:227], v[12:15]
	v_mfma_f32_16x16x32_bf16 v[8:11], v[168:171], v[224:227], v[8:11]
	s_setprio 0
	s_setprio 1
	v_mfma_f32_16x16x32_bf16 v[52:55], v[172:175], v[190:193], 0
	v_mfma_f32_16x16x32_bf16 v[48:51], v[182:185], v[190:193], 0
	v_mfma_f32_16x16x32_bf16 v[36:39], v[172:175], v[198:201], 0
	v_mfma_f32_16x16x32_bf16 v[32:35], v[182:185], v[198:201], 0
	v_mfma_f32_16x16x32_bf16 v[20:23], v[172:175], v[212:215], 0
	v_mfma_f32_16x16x32_bf16 v[16:19], v[182:185], v[212:215], 0
	v_mfma_f32_16x16x32_bf16 v[4:7], v[172:175], v[220:223], 0
	v_mfma_f32_16x16x32_bf16 v[0:3], v[182:185], v[220:223], 0
	v_mfma_f32_16x16x32_bf16 v[52:55], v[176:179], v[194:197], v[52:55]
	v_mfma_f32_16x16x32_bf16 v[48:51], v[186:189], v[194:197], v[48:51]
	v_mfma_f32_16x16x32_bf16 v[36:39], v[176:179], v[208:211], v[36:39]
	v_mfma_f32_16x16x32_bf16 v[32:35], v[186:189], v[208:211], v[32:35]
	v_mfma_f32_16x16x32_bf16 v[20:23], v[176:179], v[216:219], v[20:23]
	v_mfma_f32_16x16x32_bf16 v[16:19], v[186:189], v[216:219], v[16:19]
	v_lshl_add_u64 v[232:233], s[60:61], 0, v[134:135]
	s_mov_b32 m0, s62
	s_nop 0
	global_load_lds_dwordx4 v[232:233], off
	v_mfma_f32_16x16x32_bf16 v[4:7], v[176:179], v[224:227], v[4:7]
	v_mfma_f32_16x16x32_bf16 v[0:3], v[186:189], v[224:227], v[0:3]
	s_setprio 0
	s_barrier
	s_add_i32 s3, 0, 0x18000
	v_add_u32_e32 v159, s3, v131
	s_add_i32 s33, 0, 0x1c000
	ds_read_b128 v[148:151], v159
	ds_read_b128 v[160:163], v159 offset:1024
	ds_read_b128 v[164:167], v159 offset:2048
	ds_read_b128 v[168:171], v159 offset:3072
	v_add_u32_e32 v159, s33, v131
	ds_read_b128 v[172:175], v159
	ds_read_b128 v[176:179], v159 offset:1024
	ds_read_b128 v[182:185], v159 offset:2048
	ds_read_b128 v[186:189], v159 offset:3072
	s_add_u32 s14, s60, 0x40000
	s_addc_u32 s15, s61, 0
	s_mov_b32 m0, s63
	v_lshl_add_u64 v[234:235], s[14:15], 0, v[138:139]
	ds_read_b128 v[190:193], v157 offset:32768
	ds_read_b128 v[194:197], v157 offset:33792
	ds_read_b128 v[198:201], v157 offset:34816
	ds_read_b128 v[208:211], v157 offset:35840
	ds_read_b128 v[212:215], v157 offset:36864
	ds_read_b128 v[216:219], v157 offset:37888
	ds_read_b128 v[220:223], v157 offset:38912
	ds_read_b128 v[224:227], v157 offset:39936
	global_load_lds_dwordx4 v[234:235], off
	v_lshl_add_u64 v[234:235], s[14:15], 0, v[134:135]
	s_mov_b32 m0, s64
	s_nop 0
	global_load_lds_dwordx4 v[234:235], off
	s_waitcnt vmcnt(8)
	s_waitcnt lgkmcnt(0)
	s_barrier
	s_setprio 1
	s_waitcnt lgkmcnt(0)
	v_mfma_f32_16x16x32_bf16 v[124:127], v[148:151], v[190:193], v[124:127]
	v_mfma_f32_16x16x32_bf16 v[120:123], v[164:167], v[190:193], v[120:123]
	v_mfma_f32_16x16x32_bf16 v[108:111], v[148:151], v[198:201], v[108:111]
	v_mfma_f32_16x16x32_bf16 v[104:107], v[164:167], v[198:201], v[104:107]
	v_mfma_f32_16x16x32_bf16 v[92:95], v[148:151], v[212:215], v[92:95]
	v_mfma_f32_16x16x32_bf16 v[88:91], v[164:167], v[212:215], v[88:91]
	v_mfma_f32_16x16x32_bf16 v[76:79], v[148:151], v[220:223], v[76:79]
	v_mfma_f32_16x16x32_bf16 v[72:75], v[164:167], v[220:223], v[72:75]
	v_mfma_f32_16x16x32_bf16 v[124:127], v[160:163], v[194:197], v[124:127]
	v_mfma_f32_16x16x32_bf16 v[120:123], v[168:171], v[194:197], v[120:123]
	v_mfma_f32_16x16x32_bf16 v[108:111], v[160:163], v[208:211], v[108:111]
	v_mfma_f32_16x16x32_bf16 v[104:107], v[168:171], v[208:211], v[104:107]
	v_mfma_f32_16x16x32_bf16 v[92:95], v[160:163], v[216:219], v[92:95]
	v_mfma_f32_16x16x32_bf16 v[88:91], v[168:171], v[216:219], v[88:91]
	v_mfma_f32_16x16x32_bf16 v[76:79], v[160:163], v[224:227], v[76:79]
	v_mfma_f32_16x16x32_bf16 v[72:75], v[168:171], v[224:227], v[72:75]
	s_setprio 0
	s_setprio 1
	v_mfma_f32_16x16x32_bf16 v[116:119], v[172:175], v[190:193], v[116:119]
	v_mfma_f32_16x16x32_bf16 v[112:115], v[182:185], v[190:193], v[112:115]
	v_mfma_f32_16x16x32_bf16 v[100:103], v[172:175], v[198:201], v[100:103]
	v_mfma_f32_16x16x32_bf16 v[96:99], v[182:185], v[198:201], v[96:99]
	v_mfma_f32_16x16x32_bf16 v[84:87], v[172:175], v[212:215], v[84:87]
	v_mfma_f32_16x16x32_bf16 v[80:83], v[182:185], v[212:215], v[80:83]
	v_mfma_f32_16x16x32_bf16 v[68:71], v[172:175], v[220:223], v[68:71]
	v_mfma_f32_16x16x32_bf16 v[64:67], v[182:185], v[220:223], v[64:67]
	v_mfma_f32_16x16x32_bf16 v[116:119], v[176:179], v[194:197], v[116:119]
	v_mfma_f32_16x16x32_bf16 v[112:115], v[186:189], v[194:197], v[112:115]
	v_mfma_f32_16x16x32_bf16 v[100:103], v[176:179], v[208:211], v[100:103]
	v_mfma_f32_16x16x32_bf16 v[96:99], v[186:189], v[208:211], v[96:99]
	v_mfma_f32_16x16x32_bf16 v[84:87], v[176:179], v[216:219], v[84:87]
	v_mfma_f32_16x16x32_bf16 v[80:83], v[186:189], v[216:219], v[80:83]
	v_mfma_f32_16x16x32_bf16 v[68:71], v[176:179], v[224:227], v[68:71]
	v_mfma_f32_16x16x32_bf16 v[64:67], v[186:189], v[224:227], v[64:67]
	s_setprio 0
	s_barrier
; #define PG8_STAGE(bufoff, gbase, voff) do { _Pragma("unroll") for (int _i = 0; _i < 2; ++_i) \
;         __builtin_amdgcn_global_load_lds((const unsigned*)((const char*)(gbase) + (voff)[_i]), (PG8_LAS unsigned*)(lds + (bufoff) + ldsw + _i * 8192), 16, 0, 0); } while (0)
; #define PG8_LDA(dst, b, h) do { _Pragma("unroll") for (int m = 0; m < 4; ++m) _Pragma("unroll") for (int k = 0; k < 2; ++k) dst[m][k] = *(const PG8_LAS bf16x8*)(lds + PG8_SA(b, h) + aoff + m * 2048 + k * 1024); } while (0)
; #define PG8_LDB(dst, b, h) do { _Pragma("unroll") for (int n = 0; n < 2; ++n) _Pragma("unroll") for (int k = 0; k < 2; ++k) dst[n][k] = *(const PG8_LAS bf16x8*)(lds + PG8_SB(b, h) + boff + n * 2048 + k * 1024); } while (0)
; #define PG8_MMA(ai, bj, At, Bt) do { __builtin_amdgcn_s_setprio(1); _Pragma("unroll") for (int m = 0; m < 4; ++m) _Pragma("unroll") for (int n = 0; n < 2; ++n) _Pragma("unroll") for (int k = 0; k < 2; ++k) \
;         acc[ai][bj][m][n] = __builtin_amdgcn_mfma_f32_16x16x32_bf16(Bt[n][k], At[m][k], acc[ai][bj][m][n], 0, 0, 0); __builtin_amdgcn_s_setprio(0); } while (0)
; #define PG8_WAIT_V(n) asm volatile("s_waitcnt vmcnt(" #n ")" ::: "memory")
; #define PG8_WAIT_L(n) asm volatile("s_waitcnt lgkmcnt(" #n ")" ::: "memory")
; #define PG8_BAR __builtin_amdgcn_s_barrier()
; #define PG8_SCHED __builtin_amdgcn_sched_barrier(0)
; template <class Epi, class Sched, bool ALIGN_EPI = false, bool SP2 = false>
; __device__ __forceinline__ void gemm_phase(PG8_LAS unsigned char* lds, const Gemm g, const Sched& S, const Epi& E) {
;     ...
;             const bool last = (t == nt - 2);
;             const char* a1 = cA + (size_t)(t + 1) * kstep;
;             const char* a2 = last ? nA : cA + (size_t)(t + 2) * kstep; const char* b2 = last ? nB : cB + (size_t)(t + 2) * kstep;
;             const char* a3 = a2 + kstep; const char* b3 = b2 + kstep;
;             if (last && has_next) S.a_ready(nxt);
;             if constexpr (SP2) {
;             PG8_LDB(B0, 0, 0); PG8_LDB(B1, 0, 1); PG8_SCHED; PG8_LDA(At, 0, 0); PG8_STAGE(PG8_SA(1, 1), a1 + hstep, voffA);
;     ...
;             PG8_LDA(At, 1, 1); PG8_STAGE(PG8_SB(1, 0), b3, voffB); PG8_STAGE(PG8_SB(1, 1), b3 + hstep, voffB); PG8_STAGE(PG8_SA(1, 0), a3, voffA);
;             PG8_WAIT_V(8); PG8_WAIT_L(0); PG8_BAR; PG8_MMA(1, 0, At, B0); PG8_MMA(1, 1, At, B1); PG8_BAR; PG8_SCHED;
	s_add_i32 s3, s3, s34
	v_lshl_add_u64 v[202:203], v[202:203], 0, s[38:39]
	s_mov_b32 m0, s3
	ds_read_b128 v[190:193], v157 offset:49152
	ds_read_b128 v[194:197], v157 offset:50176
	ds_read_b128 v[198:201], v157 offset:51200
	ds_read_b128 v[208:211], v157 offset:52224
	ds_read_b128 v[212:215], v157 offset:53248
	ds_read_b128 v[216:219], v157 offset:54272
	ds_read_b128 v[220:223], v157 offset:55296
	ds_read_b128 v[224:227], v157 offset:56320
	global_load_lds_dwordx4 v[202:203], off
	s_add_i32 m0, s3, 0x2000
	s_add_u32 s14, s58, 0x40080
	v_lshl_add_u64 v[202:203], v[228:229], 0, s[38:39]
	s_addc_u32 s15, s59, 0
	s_add_i32 s3, s33, s34
	global_load_lds_dwordx4 v[202:203], off
	v_lshl_add_u64 v[202:203], s[14:15], 0, v[136:137]
	s_mov_b32 m0, s3
	s_nop 0
	global_load_lds_dwordx4 v[202:203], off
	v_lshl_add_u64 v[202:203], s[14:15], 0, v[132:133]
	s_add_i32 m0, s3, 0x2000
	s_nop 0
	global_load_lds_dwordx4 v[202:203], off
	s_waitcnt vmcnt(6)
	s_waitcnt lgkmcnt(0)
	s_barrier
	s_setprio 1
	s_waitcnt lgkmcnt(0)
	v_mfma_f32_16x16x32_bf16 v[60:63], v[148:151], v[190:193], v[60:63]
	v_mfma_f32_16x16x32_bf16 v[56:59], v[164:167], v[190:193], v[56:59]
	v_mfma_f32_16x16x32_bf16 v[44:47], v[148:151], v[198:201], v[44:47]
	v_mfma_f32_16x16x32_bf16 v[40:43], v[164:167], v[198:201], v[40:43]
	v_mfma_f32_16x16x32_bf16 v[28:31], v[148:151], v[212:215], v[28:31]
	v_mfma_f32_16x16x32_bf16 v[24:27], v[164:167], v[212:215], v[24:27]
	v_mfma_f32_16x16x32_bf16 v[12:15], v[148:151], v[220:223], v[12:15]
	v_mfma_f32_16x16x32_bf16 v[8:11], v[164:167], v[220:223], v[8:11]
	v_mfma_f32_16x16x32_bf16 v[60:63], v[160:163], v[194:197], v[60:63]
	v_mfma_f32_16x16x32_bf16 v[56:59], v[168:171], v[194:197], v[56:59]
	v_mfma_f32_16x16x32_bf16 v[44:47], v[160:163], v[208:211], v[44:47]
	v_mfma_f32_16x16x32_bf16 v[40:43], v[168:171], v[208:211], v[40:43]
	v_mfma_f32_16x16x32_bf16 v[28:31], v[160:163], v[216:219], v[28:31]
	v_mfma_f32_16x16x32_bf16 v[24:27], v[168:171], v[216:219], v[24:27]
	v_lshl_add_u64 v[202:203], v[230:231], 0, s[38:39]
	s_mov_b32 m0, s66
	s_nop 0
	global_load_lds_dwordx4 v[202:203], off
	v_mfma_f32_16x16x32_bf16 v[12:15], v[160:163], v[224:227], v[12:15]
	v_mfma_f32_16x16x32_bf16 v[8:11], v[168:171], v[224:227], v[8:11]
	s_setprio 0
	s_setprio 1
	v_mfma_f32_16x16x32_bf16 v[52:55], v[172:175], v[190:193], v[52:55]
	v_mfma_f32_16x16x32_bf16 v[48:51], v[182:185], v[190:193], v[48:51]
	v_mfma_f32_16x16x32_bf16 v[36:39], v[172:175], v[198:201], v[36:39]
	v_mfma_f32_16x16x32_bf16 v[32:35], v[182:185], v[198:201], v[32:35]
	v_mfma_f32_16x16x32_bf16 v[20:23], v[172:175], v[212:215], v[20:23]
	v_mfma_f32_16x16x32_bf16 v[16:19], v[182:185], v[212:215], v[16:19]
	v_mfma_f32_16x16x32_bf16 v[4:7], v[172:175], v[220:223], v[4:7]
	v_mfma_f32_16x16x32_bf16 v[0:3], v[182:185], v[220:223], v[0:3]
	v_mfma_f32_16x16x32_bf16 v[52:55], v[176:179], v[194:197], v[52:55]
	v_mfma_f32_16x16x32_bf16 v[48:51], v[186:189], v[194:197], v[48:51]
	v_mfma_f32_16x16x32_bf16 v[36:39], v[176:179], v[208:211], v[36:39]
	v_mfma_f32_16x16x32_bf16 v[32:35], v[186:189], v[208:211], v[32:35]
	v_mfma_f32_16x16x32_bf16 v[20:23], v[176:179], v[216:219], v[20:23]
	v_mfma_f32_16x16x32_bf16 v[16:19], v[186:189], v[216:219], v[16:19]
	v_lshl_add_u64 v[202:203], v[232:233], 0, s[38:39]
	s_mov_b32 m0, s67
	s_nop 0
	global_load_lds_dwordx4 v[202:203], off
	v_mfma_f32_16x16x32_bf16 v[4:7], v[176:179], v[224:227], v[4:7]
	v_mfma_f32_16x16x32_bf16 v[0:3], v[186:189], v[224:227], v[0:3]
	s_setprio 0
	s_barrier
	s_add_i32 s86, s86, 2
	s_add_u32 s56, s56, 0x100
	s_addc_u32 s57, s57, 0
	s_add_u32 s84, s84, 0x100
	s_addc_u32 s85, s85, 0
.LBB0_738:
	ds_read_b128 v[148:151], v155
	ds_read_b128 v[160:163], v155 offset:1024
	ds_read_b128 v[164:167], v155 offset:2048
	ds_read_b128 v[168:171], v155 offset:3072
	ds_read_b128 v[172:175], v156
	ds_read_b128 v[176:179], v156 offset:1024
	ds_read_b128 v[182:185], v156 offset:2048
	ds_read_b128 v[186:189], v156 offset:3072
	s_add_u32 s3, s56, 0xfffc0080
	s_addc_u32 s14, s57, -1
	s_cmp_eq_u32 s86, 12
	s_cselect_b32 s61, s51, s14
	s_cselect_b32 s60, s82, s3
	s_cselect_b32 s59, s49, s85
	s_cselect_b32 s58, s83, s84
	v_lshl_add_u64 v[202:203], s[56:57], 0, v[140:141]
	s_add_i32 m0, s43, 0xc000
	ds_read_b128 v[190:193], v157
	ds_read_b128 v[194:197], v157 offset:1024
	ds_read_b128 v[198:201], v157 offset:2048
	ds_read_b128 v[208:211], v157 offset:3072
	ds_read_b128 v[212:215], v157 offset:4096
	ds_read_b128 v[216:219], v157 offset:5120
	ds_read_b128 v[220:223], v157 offset:6144
	ds_read_b128 v[224:227], v157 offset:7168
	global_load_lds_dwordx4 v[202:203], off
	v_lshl_add_u64 v[202:203], s[56:57], 0, v[142:143]
	s_add_i32 m0, s43, 0xe000
	s_nop 0
	global_load_lds_dwordx4 v[202:203], off
	s_waitcnt vmcnt(8)
	s_waitcnt lgkmcnt(0)
	s_barrier
; #define PG8_STAGE(bufoff, gbase, voff) do { _Pragma("unroll") for (int _i = 0; _i < 2; ++_i) \
;         __builtin_amdgcn_global_load_lds((const unsigned*)((const char*)(gbase) + (voff)[_i]), (PG8_LAS unsigned*)(lds + (bufoff) + ldsw + _i * 8192), 16, 0, 0); } while (0)
; #define PG8_LDA(dst, b, h) do { _Pragma("unroll") for (int m = 0; m < 4; ++m) _Pragma("unroll") for (int k = 0; k < 2; ++k) dst[m][k] = *(const PG8_LAS bf16x8*)(lds + PG8_SA(b, h) + aoff + m * 2048 + k * 1024); } while (0)
; #define PG8_MMA(ai, bj, At, Bt) do { __builtin_amdgcn_s_setprio(1); _Pragma("unroll") for (int m = 0; m < 4; ++m) _Pragma("unroll") for (int n = 0; n < 2; ++n) _Pragma("unroll") for (int k = 0; k < 2; ++k) \
;         acc[ai][bj][m][n] = __builtin_amdgcn_mfma_f32_16x16x32_bf16(Bt[n][k], At[m][k], acc[ai][bj][m][n], 0, 0, 0); __builtin_amdgcn_s_setprio(0); } while (0)
; #define PG8_WAIT_V(n) asm volatile("s_waitcnt vmcnt(" #n ")" ::: "memory")
; #define PG8_WAIT_L(n) asm volatile("s_waitcnt lgkmcnt(" #n ")" ::: "memory")
; #define PG8_BAR __builtin_amdgcn_s_barrier()
; #define PG8_SCHED __builtin_amdgcn_sched_barrier(0)
; template <class Epi, class Sched, bool ALIGN_EPI = false, bool SP2 = false>
; __device__ __forceinline__ void gemm_phase(PG8_LAS unsigned char* lds, const Gemm g, const Sched& S, const Epi& E) {
;     ...
;             PG8_WAIT_V(8); PG8_WAIT_L(0); PG8_BAR; PG8_MMA(0, 0, At, B0); PG8_MMA(0, 1, At, B1); PG8_BAR; PG8_SCHED;
;             PG8_LDA(At, 0, 1); PG8_STAGE(PG8_SB(0, 0), b2, voffB); PG8_STAGE(PG8_SB(0, 1), b2 + hstep, voffB); PG8_STAGE(PG8_SA(0, 0), a2, voffA);
;             PG8_WAIT_V(8); PG8_WAIT_L(0); PG8_BAR; PG8_MMA(1, 0, At, B0); PG8_MMA(1, 1, At, B1); PG8_BAR; PG8_SCHED;
	s_setprio 1
	s_waitcnt lgkmcnt(0)
	v_mfma_f32_16x16x32_bf16 v[124:127], v[148:151], v[190:193], v[124:127]
	v_mfma_f32_16x16x32_bf16 v[120:123], v[164:167], v[190:193], v[120:123]
	v_mfma_f32_16x16x32_bf16 v[108:111], v[148:151], v[198:201], v[108:111]
	v_mfma_f32_16x16x32_bf16 v[104:107], v[164:167], v[198:201], v[104:107]
	v_mfma_f32_16x16x32_bf16 v[92:95], v[148:151], v[212:215], v[92:95]
	v_mfma_f32_16x16x32_bf16 v[88:91], v[164:167], v[212:215], v[88:91]
	v_mfma_f32_16x16x32_bf16 v[76:79], v[148:151], v[220:223], v[76:79]
	v_mfma_f32_16x16x32_bf16 v[72:75], v[164:167], v[220:223], v[72:75]
	v_mfma_f32_16x16x32_bf16 v[124:127], v[160:163], v[194:197], v[124:127]
	v_mfma_f32_16x16x32_bf16 v[120:123], v[168:171], v[194:197], v[120:123]
	v_mfma_f32_16x16x32_bf16 v[108:111], v[160:163], v[208:211], v[108:111]
	v_mfma_f32_16x16x32_bf16 v[104:107], v[168:171], v[208:211], v[104:107]
	v_mfma_f32_16x16x32_bf16 v[92:95], v[160:163], v[216:219], v[92:95]
	v_mfma_f32_16x16x32_bf16 v[88:91], v[168:171], v[216:219], v[88:91]
	v_mfma_f32_16x16x32_bf16 v[76:79], v[160:163], v[224:227], v[76:79]
	v_mfma_f32_16x16x32_bf16 v[72:75], v[168:171], v[224:227], v[72:75]
	s_setprio 0
	s_setprio 1
	v_mfma_f32_16x16x32_bf16 v[116:119], v[172:175], v[190:193], v[116:119]
	v_mfma_f32_16x16x32_bf16 v[112:115], v[182:185], v[190:193], v[112:115]
	v_mfma_f32_16x16x32_bf16 v[100:103], v[172:175], v[198:201], v[100:103]
	v_mfma_f32_16x16x32_bf16 v[96:99], v[182:185], v[198:201], v[96:99]
	v_mfma_f32_16x16x32_bf16 v[84:87], v[172:175], v[212:215], v[84:87]
	v_mfma_f32_16x16x32_bf16 v[80:83], v[182:185], v[212:215], v[80:83]
	v_mfma_f32_16x16x32_bf16 v[68:71], v[172:175], v[220:223], v[68:71]
	v_mfma_f32_16x16x32_bf16 v[64:67], v[182:185], v[220:223], v[64:67]
	v_mfma_f32_16x16x32_bf16 v[116:119], v[176:179], v[194:197], v[116:119]
	v_mfma_f32_16x16x32_bf16 v[112:115], v[186:189], v[194:197], v[112:115]
	v_mfma_f32_16x16x32_bf16 v[100:103], v[176:179], v[208:211], v[100:103]
	v_mfma_f32_16x16x32_bf16 v[96:99], v[186:189], v[208:211], v[96:99]
	v_mfma_f32_16x16x32_bf16 v[84:87], v[176:179], v[216:219], v[84:87]
	v_mfma_f32_16x16x32_bf16 v[80:83], v[186:189], v[216:219], v[80:83]
	v_mfma_f32_16x16x32_bf16 v[68:71], v[176:179], v[224:227], v[68:71]
	v_mfma_f32_16x16x32_bf16 v[64:67], v[186:189], v[224:227], v[64:67]
	s_setprio 0
	s_barrier
	s_add_i32 s3, s74, s34
	v_lshl_add_u64 v[202:203], s[58:59], 0, v[136:137]
	s_mov_b32 m0, s3
	ds_read_b128 v[190:193], v157 offset:16384
	ds_read_b128 v[194:197], v157 offset:17408
	ds_read_b128 v[198:201], v157 offset:18432
	ds_read_b128 v[208:211], v157 offset:19456
	ds_read_b128 v[212:215], v157 offset:20480
	ds_read_b128 v[216:219], v157 offset:21504
	ds_read_b128 v[220:223], v157 offset:22528
	ds_read_b128 v[224:227], v157 offset:23552
	global_load_lds_dwordx4 v[202:203], off
	s_add_i32 m0, s3, 0x2000
	s_add_u32 s14, s58, 0x40000
	v_lshl_add_u64 v[228:229], s[58:59], 0, v[132:133]
	s_addc_u32 s15, s59, 0
	s_add_i32 s3, s75, s34
	global_load_lds_dwordx4 v[228:229], off
	v_lshl_add_u64 v[230:231], s[14:15], 0, v[136:137]
	s_mov_b32 m0, s3
	global_load_lds_dwordx4 v[230:231], off
	v_lshl_add_u64 v[230:231], s[14:15], 0, v[132:133]
	s_add_i32 m0, s3, 0x2000
	s_nop 0
	global_load_lds_dwordx4 v[230:231], off
	s_waitcnt vmcnt(6)
	s_waitcnt lgkmcnt(0)
	s_barrier
	s_setprio 1
	s_waitcnt lgkmcnt(0)
	v_mfma_f32_16x16x32_bf16 v[60:63], v[148:151], v[190:193], v[60:63]
	v_mfma_f32_16x16x32_bf16 v[56:59], v[164:167], v[190:193], v[56:59]
	v_mfma_f32_16x16x32_bf16 v[44:47], v[148:151], v[198:201], v[44:47]
	v_mfma_f32_16x16x32_bf16 v[40:43], v[164:167], v[198:201], v[40:43]
	v_mfma_f32_16x16x32_bf16 v[28:31], v[148:151], v[212:215], v[28:31]
	v_mfma_f32_16x16x32_bf16 v[24:27], v[164:167], v[212:215], v[24:27]
	v_mfma_f32_16x16x32_bf16 v[12:15], v[148:151], v[220:223], v[12:15]
	v_mfma_f32_16x16x32_bf16 v[8:11], v[164:167], v[220:223], v[8:11]
	v_mfma_f32_16x16x32_bf16 v[60:63], v[160:163], v[194:197], v[60:63]
	v_mfma_f32_16x16x32_bf16 v[56:59], v[168:171], v[194:197], v[56:59]
	v_mfma_f32_16x16x32_bf16 v[44:47], v[160:163], v[208:211], v[44:47]
	v_mfma_f32_16x16x32_bf16 v[40:43], v[168:171], v[208:211], v[40:43]
	v_mfma_f32_16x16x32_bf16 v[28:31], v[160:163], v[216:219], v[28:31]
	v_mfma_f32_16x16x32_bf16 v[24:27], v[168:171], v[216:219], v[24:27]
	v_lshl_add_u64 v[230:231], s[60:61], 0, v[138:139]
	s_mov_b32 m0, s43
	s_nop 0
	global_load_lds_dwordx4 v[230:231], off
	v_mfma_f32_16x16x32_bf16 v[12:15], v[160:163], v[224:227], v[12:15]
	v_mfma_f32_16x16x32_bf16 v[8:11], v[168:171], v[224:227], v[8:11]
	s_setprio 0
	s_setprio 1
	v_mfma_f32_16x16x32_bf16 v[52:55], v[172:175], v[190:193], v[52:55]
	v_mfma_f32_16x16x32_bf16 v[48:51], v[182:185], v[190:193], v[48:51]
	v_mfma_f32_16x16x32_bf16 v[36:39], v[172:175], v[198:201], v[36:39]
	v_mfma_f32_16x16x32_bf16 v[32:35], v[182:185], v[198:201], v[32:35]
	v_mfma_f32_16x16x32_bf16 v[20:23], v[172:175], v[212:215], v[20:23]
	v_mfma_f32_16x16x32_bf16 v[16:19], v[182:185], v[212:215], v[16:19]
	v_mfma_f32_16x16x32_bf16 v[4:7], v[172:175], v[220:223], v[4:7]
	v_mfma_f32_16x16x32_bf16 v[0:3], v[182:185], v[220:223], v[0:3]
	v_mfma_f32_16x16x32_bf16 v[52:55], v[176:179], v[194:197], v[52:55]
	v_mfma_f32_16x16x32_bf16 v[48:51], v[186:189], v[194:197], v[48:51]
	v_mfma_f32_16x16x32_bf16 v[36:39], v[176:179], v[208:211], v[36:39]
	v_mfma_f32_16x16x32_bf16 v[32:35], v[186:189], v[208:211], v[32:35]
	v_mfma_f32_16x16x32_bf16 v[20:23], v[176:179], v[216:219], v[20:23]
	v_mfma_f32_16x16x32_bf16 v[16:19], v[186:189], v[216:219], v[16:19]
	v_lshl_add_u64 v[232:233], s[60:61], 0, v[134:135]
	s_mov_b32 m0, s62
	s_nop 0
	global_load_lds_dwordx4 v[232:233], off
	v_mfma_f32_16x16x32_bf16 v[4:7], v[176:179], v[224:227], v[4:7]
	v_mfma_f32_16x16x32_bf16 v[0:3], v[186:189], v[224:227], v[0:3]
	s_setprio 0
	s_barrier
; #define PG8_STAGE(bufoff, gbase, voff) do { _Pragma("unroll") for (int _i = 0; _i < 2; ++_i) \
;         __builtin_amdgcn_global_load_lds((const unsigned*)((const char*)(gbase) + (voff)[_i]), (PG8_LAS unsigned*)(lds + (bufoff) + ldsw + _i * 8192), 16, 0, 0); } while (0)
; #define PG8_LDA(dst, b, h) do { _Pragma("unroll") for (int m = 0; m < 4; ++m) _Pragma("unroll") for (int k = 0; k < 2; ++k) dst[m][k] = *(const PG8_LAS bf16x8*)(lds + PG8_SA(b, h) + aoff + m * 2048 + k * 1024); } while (0)
; #define PG8_LDB(dst, b, h) do { _Pragma("unroll") for (int n = 0; n < 2; ++n) _Pragma("unroll") for (int k = 0; k < 2; ++k) dst[n][k] = *(const PG8_LAS bf16x8*)(lds + PG8_SB(b, h) + boff + n * 2048 + k * 1024); } while (0)
; #define PG8_MMA(ai, bj, At, Bt) do { __builtin_amdgcn_s_setprio(1); _Pragma("unroll") for (int m = 0; m < 4; ++m) _Pragma("unroll") for (int n = 0; n < 2; ++n) _Pragma("unroll") for (int k = 0; k < 2; ++k) \
;         acc[ai][bj][m][n] = __builtin_amdgcn_mfma_f32_16x16x32_bf16(Bt[n][k], At[m][k], acc[ai][bj][m][n], 0, 0, 0); __builtin_amdgcn_s_setprio(0); } while (0)
; #define PG8_WAIT_V(n) asm volatile("s_waitcnt vmcnt(" #n ")" ::: "memory")
; #define PG8_WAIT_L(n) asm volatile("s_waitcnt lgkmcnt(" #n ")" ::: "memory")
; #define PG8_BAR __builtin_amdgcn_s_barrier()
; #define PG8_SCHED __builtin_amdgcn_sched_barrier(0)
; template <class Epi, class Sched, bool ALIGN_EPI = false, bool SP2 = false>
; __device__ __forceinline__ void gemm_phase(PG8_LAS unsigned char* lds, const Gemm g, const Sched& S, const Epi& E) {
;     ...
;             PG8_LDB(B0, 1, 0); PG8_LDB(B1, 1, 1); PG8_SCHED; PG8_LDA(At, 1, 0); PG8_STAGE(PG8_SA(0, 1), a2 + hstep, voffA);
;             PG8_WAIT_V(8); PG8_WAIT_L(0); PG8_BAR; PG8_MMA(0, 0, At, B0); PG8_MMA(0, 1, At, B1); PG8_BAR; PG8_SCHED;
	s_add_i32 s3, 0, 0x18000
	v_add_u32_e32 v159, s3, v131
	s_add_i32 s33, 0, 0x1c000
	ds_read_b128 v[148:151], v159
	ds_read_b128 v[160:163], v159 offset:1024
	ds_read_b128 v[164:167], v159 offset:2048
	ds_read_b128 v[168:171], v159 offset:3072
	v_add_u32_e32 v159, s33, v131
	ds_read_b128 v[172:175], v159
	ds_read_b128 v[176:179], v159 offset:1024
	ds_read_b128 v[182:185], v159 offset:2048
	ds_read_b128 v[186:189], v159 offset:3072
	s_add_u32 s14, s60, 0x40000
	s_addc_u32 s15, s61, 0
	s_mov_b32 m0, s63
	v_lshl_add_u64 v[234:235], s[14:15], 0, v[138:139]
	ds_read_b128 v[190:193], v157 offset:32768
	ds_read_b128 v[194:197], v157 offset:33792
	ds_read_b128 v[198:201], v157 offset:34816
	ds_read_b128 v[208:211], v157 offset:35840
	ds_read_b128 v[212:215], v157 offset:36864
	ds_read_b128 v[216:219], v157 offset:37888
	ds_read_b128 v[220:223], v157 offset:38912
	ds_read_b128 v[224:227], v157 offset:39936
	global_load_lds_dwordx4 v[234:235], off
	v_lshl_add_u64 v[234:235], s[14:15], 0, v[134:135]
	s_mov_b32 m0, s64
	s_nop 0
	global_load_lds_dwordx4 v[234:235], off
	s_waitcnt vmcnt(8)
	s_waitcnt lgkmcnt(0)
	s_barrier
	s_setprio 1
	s_waitcnt lgkmcnt(0)
	v_mfma_f32_16x16x32_bf16 v[124:127], v[148:151], v[190:193], v[124:127]
	v_mfma_f32_16x16x32_bf16 v[120:123], v[164:167], v[190:193], v[120:123]
	v_mfma_f32_16x16x32_bf16 v[108:111], v[148:151], v[198:201], v[108:111]
	v_mfma_f32_16x16x32_bf16 v[104:107], v[164:167], v[198:201], v[104:107]
	v_mfma_f32_16x16x32_bf16 v[92:95], v[148:151], v[212:215], v[92:95]
	v_mfma_f32_16x16x32_bf16 v[88:91], v[164:167], v[212:215], v[88:91]
	v_mfma_f32_16x16x32_bf16 v[76:79], v[148:151], v[220:223], v[76:79]
	v_mfma_f32_16x16x32_bf16 v[72:75], v[164:167], v[220:223], v[72:75]
	v_mfma_f32_16x16x32_bf16 v[124:127], v[160:163], v[194:197], v[124:127]
	v_mfma_f32_16x16x32_bf16 v[120:123], v[168:171], v[194:197], v[120:123]
	v_mfma_f32_16x16x32_bf16 v[108:111], v[160:163], v[208:211], v[108:111]
	v_mfma_f32_16x16x32_bf16 v[104:107], v[168:171], v[208:211], v[104:107]
	v_mfma_f32_16x16x32_bf16 v[92:95], v[160:163], v[216:219], v[92:95]
	v_mfma_f32_16x16x32_bf16 v[88:91], v[168:171], v[216:219], v[88:91]
	v_mfma_f32_16x16x32_bf16 v[76:79], v[160:163], v[224:227], v[76:79]
	v_mfma_f32_16x16x32_bf16 v[72:75], v[168:171], v[224:227], v[72:75]
	s_setprio 0
	s_setprio 1
	v_mfma_f32_16x16x32_bf16 v[116:119], v[172:175], v[190:193], v[116:119]
	v_mfma_f32_16x16x32_bf16 v[112:115], v[182:185], v[190:193], v[112:115]
	v_mfma_f32_16x16x32_bf16 v[100:103], v[172:175], v[198:201], v[100:103]
	v_mfma_f32_16x16x32_bf16 v[96:99], v[182:185], v[198:201], v[96:99]
	v_mfma_f32_16x16x32_bf16 v[84:87], v[172:175], v[212:215], v[84:87]
	v_mfma_f32_16x16x32_bf16 v[80:83], v[182:185], v[212:215], v[80:83]
	v_mfma_f32_16x16x32_bf16 v[68:71], v[172:175], v[220:223], v[68:71]
	v_mfma_f32_16x16x32_bf16 v[64:67], v[182:185], v[220:223], v[64:67]
	v_mfma_f32_16x16x32_bf16 v[116:119], v[176:179], v[194:197], v[116:119]
	v_mfma_f32_16x16x32_bf16 v[112:115], v[186:189], v[194:197], v[112:115]
	v_mfma_f32_16x16x32_bf16 v[100:103], v[176:179], v[208:211], v[100:103]
	v_mfma_f32_16x16x32_bf16 v[96:99], v[186:189], v[208:211], v[96:99]
	v_mfma_f32_16x16x32_bf16 v[84:87], v[176:179], v[216:219], v[84:87]
	v_mfma_f32_16x16x32_bf16 v[80:83], v[186:189], v[216:219], v[80:83]
	v_mfma_f32_16x16x32_bf16 v[68:71], v[176:179], v[224:227], v[68:71]
	v_mfma_f32_16x16x32_bf16 v[64:67], v[186:189], v[224:227], v[64:67]
	s_setprio 0
	s_barrier
; #define PG8_STAGE(bufoff, gbase, voff) do { _Pragma("unroll") for (int _i = 0; _i < 2; ++_i) \
;         __builtin_amdgcn_global_load_lds((const unsigned*)((const char*)(gbase) + (voff)[_i]), (PG8_LAS unsigned*)(lds + (bufoff) + ldsw + _i * 8192), 16, 0, 0); } while (0)
; #define PG8_LDA(dst, b, h) do { _Pragma("unroll") for (int m = 0; m < 4; ++m) _Pragma("unroll") for (int k = 0; k < 2; ++k) dst[m][k] = *(const PG8_LAS bf16x8*)(lds + PG8_SA(b, h) + aoff + m * 2048 + k * 1024); } while (0)
; #define PG8_WAIT_V(n) asm volatile("s_waitcnt vmcnt(" #n ")" ::: "memory")
; template <class Epi, class Sched, bool ALIGN_EPI = false, bool SP2 = false>
; __device__ __forceinline__ void gemm_phase(PG8_LAS unsigned char* lds, const Gemm g, const Sched& S, const Epi& E) {
;     ...
;             PG8_LDA(At, 1, 1); PG8_STAGE(PG8_SB(1, 0), b3, voffB); PG8_STAGE(PG8_SB(1, 1), b3 + hstep, voffB); PG8_STAGE(PG8_SA(1, 0), a3, voffA);
;             PG8_WAIT_V(8); PG8_WAIT_L(0); PG8_BAR; PG8_MMA(1, 0, At, B0); PG8_MMA(1, 1, At, B1); PG8_BAR; PG8_SCHED;
;             } else {
;             PG8_LDB(B0, 0, 0); PG8_SCHED; PG8_LDA(At, 0, 0); PG8_STAGE(PG8_SA(1, 1), a1 + hstep, voffA);
;             PG8_WAIT_L(8); PG8_BAR; PG8_WAIT_L(0); PG8_MMA(0, 0, At, B0); PG8_BAR; PG8_SCHED;
;             PG8_LDB(B1, 0, 1); PG8_STAGE(PG8_SB(0, 0), b2, voffB);
;             PG8_BAR; PG8_WAIT_L(0); PG8_MMA(0, 1, At, B1); PG8_BAR;
;             PG8_LDA(At, 0, 1); PG8_STAGE(PG8_SA(0, 0), a2, voffA);
;             PG8_BAR; PG8_WAIT_L(0); PG8_MMA(1, 0, At, B0); PG8_BAR; PG8_SCHED;
;             PG8_STAGE(PG8_SB(0, 1), b2 + hstep, voffB);
;             PG8_WAIT_V(6); PG8_BAR; PG8_MMA(1, 1, At, B1); PG8_BAR;
;             PG8_LDB(B0, 1, 0); PG8_SCHED; PG8_LDA(At, 1, 0); PG8_STAGE(PG8_SA(0, 1), a2 + hstep, voffA);
;             PG8_WAIT_L(8); PG8_BAR; PG8_WAIT_L(0); PG8_MMA(0, 0, At, B0); PG8_BAR; PG8_SCHED;
;             PG8_LDB(B1, 1, 1); PG8_STAGE(PG8_SB(1, 0), b3, voffB);
;             PG8_BAR; PG8_WAIT_L(0); PG8_MMA(0, 1, At, B1); PG8_BAR;
;             PG8_LDA(At, 1, 1); PG8_STAGE(PG8_SA(1, 0), a3, voffA);
;             PG8_BAR; PG8_WAIT_L(0); PG8_MMA(1, 0, At, B0); PG8_BAR; PG8_SCHED;
;             PG8_STAGE(PG8_SB(1, 1), b3 + hstep, voffB);
;             PG8_WAIT_V(6); PG8_BAR; PG8_MMA(1, 1, At, B1); PG8_BAR;
;             }
;         }
;         if constexpr (ALIGN_EPI) { if (wr == 0) PG8_BAR; }
	s_add_i32 s3, s3, s34
	v_lshl_add_u64 v[202:203], v[202:203], 0, s[38:39]
	s_mov_b32 m0, s3
	ds_read_b128 v[190:193], v157 offset:49152
	ds_read_b128 v[194:197], v157 offset:50176
	ds_read_b128 v[198:201], v157 offset:51200
	ds_read_b128 v[208:211], v157 offset:52224
	ds_read_b128 v[212:215], v157 offset:53248
	ds_read_b128 v[216:219], v157 offset:54272
	ds_read_b128 v[220:223], v157 offset:55296
	ds_read_b128 v[224:227], v157 offset:56320
	global_load_lds_dwordx4 v[202:203], off
	s_add_i32 m0, s3, 0x2000
	s_add_u32 s14, s58, 0x40080
	v_lshl_add_u64 v[202:203], v[228:229], 0, s[38:39]
	s_addc_u32 s15, s59, 0
	s_add_i32 s3, s33, s34
	global_load_lds_dwordx4 v[202:203], off
	v_lshl_add_u64 v[202:203], s[14:15], 0, v[136:137]
	s_mov_b32 m0, s3
	s_nop 0
	global_load_lds_dwordx4 v[202:203], off
	v_lshl_add_u64 v[202:203], s[14:15], 0, v[132:133]
	s_add_i32 m0, s3, 0x2000
	s_nop 0
	global_load_lds_dwordx4 v[202:203], off
	s_waitcnt vmcnt(6)
	s_waitcnt lgkmcnt(0)
	s_barrier
	s_setprio 1
	s_waitcnt lgkmcnt(0)
	v_mfma_f32_16x16x32_bf16 v[60:63], v[148:151], v[190:193], v[60:63]
	v_mfma_f32_16x16x32_bf16 v[56:59], v[164:167], v[190:193], v[56:59]
	v_mfma_f32_16x16x32_bf16 v[44:47], v[148:151], v[198:201], v[44:47]
	v_mfma_f32_16x16x32_bf16 v[40:43], v[164:167], v[198:201], v[40:43]
	v_mfma_f32_16x16x32_bf16 v[28:31], v[148:151], v[212:215], v[28:31]
	v_mfma_f32_16x16x32_bf16 v[24:27], v[164:167], v[212:215], v[24:27]
	v_mfma_f32_16x16x32_bf16 v[12:15], v[148:151], v[220:223], v[12:15]
	v_mfma_f32_16x16x32_bf16 v[8:11], v[164:167], v[220:223], v[8:11]
	v_mfma_f32_16x16x32_bf16 v[60:63], v[160:163], v[194:197], v[60:63]
	v_mfma_f32_16x16x32_bf16 v[56:59], v[168:171], v[194:197], v[56:59]
	v_mfma_f32_16x16x32_bf16 v[44:47], v[160:163], v[208:211], v[44:47]
	v_mfma_f32_16x16x32_bf16 v[40:43], v[168:171], v[208:211], v[40:43]
	v_mfma_f32_16x16x32_bf16 v[28:31], v[160:163], v[216:219], v[28:31]
	v_mfma_f32_16x16x32_bf16 v[24:27], v[168:171], v[216:219], v[24:27]
	v_lshl_add_u64 v[202:203], v[230:231], 0, s[38:39]
	s_mov_b32 m0, s66
	s_nop 0
	global_load_lds_dwordx4 v[202:203], off
	v_mfma_f32_16x16x32_bf16 v[12:15], v[160:163], v[224:227], v[12:15]
	v_mfma_f32_16x16x32_bf16 v[8:11], v[168:171], v[224:227], v[8:11]
	s_setprio 0
	s_setprio 1
	v_mfma_f32_16x16x32_bf16 v[52:55], v[172:175], v[190:193], v[52:55]
	v_mfma_f32_16x16x32_bf16 v[48:51], v[182:185], v[190:193], v[48:51]
	v_mfma_f32_16x16x32_bf16 v[36:39], v[172:175], v[198:201], v[36:39]
	v_mfma_f32_16x16x32_bf16 v[32:35], v[182:185], v[198:201], v[32:35]
	v_mfma_f32_16x16x32_bf16 v[20:23], v[172:175], v[212:215], v[20:23]
	v_mfma_f32_16x16x32_bf16 v[16:19], v[182:185], v[212:215], v[16:19]
	v_mfma_f32_16x16x32_bf16 v[4:7], v[172:175], v[220:223], v[4:7]
	v_mfma_f32_16x16x32_bf16 v[0:3], v[182:185], v[220:223], v[0:3]
	v_mfma_f32_16x16x32_bf16 v[52:55], v[176:179], v[194:197], v[52:55]
	v_mfma_f32_16x16x32_bf16 v[48:51], v[186:189], v[194:197], v[48:51]
	v_mfma_f32_16x16x32_bf16 v[36:39], v[176:179], v[208:211], v[36:39]
	v_mfma_f32_16x16x32_bf16 v[32:35], v[186:189], v[208:211], v[32:35]
	v_mfma_f32_16x16x32_bf16 v[20:23], v[176:179], v[216:219], v[20:23]
	v_mfma_f32_16x16x32_bf16 v[16:19], v[186:189], v[216:219], v[16:19]
	v_lshl_add_u64 v[202:203], v[232:233], 0, s[38:39]
	s_mov_b32 m0, s67
	s_nop 0
	global_load_lds_dwordx4 v[202:203], off
	v_mfma_f32_16x16x32_bf16 v[4:7], v[176:179], v[224:227], v[4:7]
	v_mfma_f32_16x16x32_bf16 v[0:3], v[186:189], v[224:227], v[0:3]
	s_setprio 0
	s_barrier
	s_add_i32 s86, s86, 2
	s_add_u32 s56, s56, 0x100
	s_addc_u32 s57, s57, 0
	s_add_u32 s84, s84, 0x100
	s_addc_u32 s85, s85, 0
	s_cmp_gt_u32 s86, 13
	s_cbranch_scc0 .LBB0_738
	s_and_b64 vcc, exec, s[44:45]
	s_cbranch_vccz .LBB0_741
	s_barrier

; #define PG8_STAGE(bufoff, gbase, voff) do { _Pragma("unroll") for (int _i = 0; _i < 2; ++_i) \
;         __builtin_amdgcn_global_load_lds((const unsigned*)((const char*)(gbase) + (voff)[_i]), (PG8_LAS unsigned*)(lds + (bufoff) + ldsw + _i * 8192), 16, 0, 0); } while (0)
; #define PG8_LDA(dst, b, h) do { _Pragma("unroll") for (int m = 0; m < 4; ++m) _Pragma("unroll") for (int k = 0; k < 2; ++k) dst[m][k] = *(const PG8_LAS bf16x8*)(lds + PG8_SA(b, h) + aoff + m * 2048 + k * 1024); } while (0)
; #define PG8_LDB(dst, b, h) do { _Pragma("unroll") for (int n = 0; n < 2; ++n) _Pragma("unroll") for (int k = 0; k < 2; ++k) dst[n][k] = *(const PG8_LAS bf16x8*)(lds + PG8_SB(b, h) + boff + n * 2048 + k * 1024); } while (0)
; #define PG8_WAIT_V(n) asm volatile("s_waitcnt vmcnt(" #n ")" ::: "memory")
; #define PG8_WAIT_L(n) asm volatile("s_waitcnt lgkmcnt(" #n ")" ::: "memory")
; #define PG8_BAR __builtin_amdgcn_s_barrier()
; #define PG8_SCHED __builtin_amdgcn_sched_barrier(0)
; template <class Epi, class Sched, bool ALIGN_EPI = false, bool SP2 = false>
; __device__ __forceinline__ void gemm_phase(PG8_LAS unsigned char* lds, const Gemm g, const Sched& S, const Epi& E) {
;     ...
;         const bool has_next = S.next(ui + 1, nxt);
;         const char* nA = has_next ? (const char*)g.A + (size_t)nxt.pm * tstep : cA; const char* nB = has_next ? (const char*)g.Bt + (size_t)nxt.pn * tstep : cB;
;         for (int t = 0; t < nt; t += 2) {
;             const bool last = (t == nt - 2);
;             const char* a1 = cA + (size_t)(t + 1) * kstep;
;             const char* a2 = last ? nA : cA + (size_t)(t + 2) * kstep; const char* b2 = last ? nB : cB + (size_t)(t + 2) * kstep;
;             const char* a3 = a2 + kstep; const char* b3 = b2 + kstep;
;             if (last && has_next) S.a_ready(nxt);
;             if constexpr (SP2) {
;             PG8_LDB(B0, 0, 0); PG8_LDB(B1, 0, 1); PG8_SCHED; PG8_LDA(At, 0, 0); PG8_STAGE(PG8_SA(1, 1), a1 + hstep, voffA);
;             PG8_WAIT_V(8); PG8_WAIT_L(0); PG8_BAR; PG8_MMA(0, 0, At, B0); PG8_MMA(0, 1, At, B1); PG8_BAR; PG8_SCHED;
;             PG8_LDA(At, 0, 1); PG8_STAGE(PG8_SB(0, 0), b2, voffB); PG8_STAGE(PG8_SB(0, 1), b2 + hstep, voffB); PG8_STAGE(PG8_SA(0, 0), a2, voffA);
;             PG8_WAIT_V(8); PG8_WAIT_L(0); PG8_BAR; PG8_MMA(1, 0, At, B0); PG8_MMA(1, 1, At, B1); PG8_BAR; PG8_SCHED;
.LBB0_872:
	s_ashr_i32 s49, s48, 31
	s_lshl_b64 s[50:51], s[48:49], 18
	s_add_u32 s50, s92, s50
	s_addc_u32 s51, s93, s51
	s_and_b64 s[52:53], s[10:11], exec
	s_cselect_b32 s49, s51, s59
	s_cselect_b32 s55, s50, s58
	s_ashr_i32 s45, s44, 31
	s_lshl_b64 s[52:53], s[44:45], 18
	s_add_u32 s52, s76, s52
	s_addc_u32 s53, s77, s53
	s_and_b64 s[62:63], s[10:11], exec
	s_cselect_b32 s45, s53, s61
	s_cselect_b32 s84, s52, s60
	s_add_u32 s58, s58, 0x20080
	s_addc_u32 s59, s59, 0
	s_add_u32 s85, s60, 0x100
	s_addc_u32 s86, s61, 0
	s_mov_b32 s87, -2
	s_waitcnt lgkmcnt(0)
	ds_read_b128 v[144:147], v151
	ds_read_b128 v[156:159], v151 offset:1024
	ds_read_b128 v[160:163], v151 offset:2048
	ds_read_b128 v[164:167], v151 offset:3072
	ds_read_b128 v[168:171], v152
	ds_read_b128 v[172:175], v152 offset:1024
	ds_read_b128 v[176:179], v152 offset:2048
	ds_read_b128 v[182:185], v152 offset:3072
	s_add_u32 s3, s58, 0xfffe0080
	s_addc_u32 s33, s59, -1
	s_cmp_eq_u32 s87, 4
	s_cselect_b32 s63, s49, s33
	s_cselect_b32 s62, s55, s3
	s_cselect_b32 s61, s45, s86
	s_cselect_b32 s60, s84, s85
	v_lshl_add_u64 v[202:203], s[58:59], 0, v[136:137]
	s_add_i32 m0, s15, 0xc000
	ds_read_b128 v[186:189], v153
	ds_read_b128 v[190:193], v153 offset:1024
	ds_read_b128 v[194:197], v153 offset:2048
	ds_read_b128 v[198:201], v153 offset:3072
	ds_read_b128 v[208:211], v153 offset:4096
	ds_read_b128 v[212:215], v153 offset:5120
	ds_read_b128 v[216:219], v153 offset:6144
	ds_read_b128 v[220:223], v153 offset:7168
	global_load_lds_dwordx4 v[202:203], off
	v_lshl_add_u64 v[202:203], s[58:59], 0, v[138:139]
	s_add_i32 m0, s15, 0xe000
	s_nop 0
	global_load_lds_dwordx4 v[202:203], off
	s_waitcnt vmcnt(8)
	s_waitcnt lgkmcnt(0)
	s_barrier
	s_setprio 1
	s_waitcnt lgkmcnt(0)
	v_mfma_f32_16x16x32_bf16 v[124:127], v[144:147], v[186:189], 0
	v_mfma_f32_16x16x32_bf16 v[120:123], v[160:163], v[186:189], 0
	v_mfma_f32_16x16x32_bf16 v[108:111], v[144:147], v[194:197], 0
	v_mfma_f32_16x16x32_bf16 v[104:107], v[160:163], v[194:197], 0
	v_mfma_f32_16x16x32_bf16 v[92:95], v[144:147], v[208:211], 0
	v_mfma_f32_16x16x32_bf16 v[88:91], v[160:163], v[208:211], 0
	v_mfma_f32_16x16x32_bf16 v[76:79], v[144:147], v[216:219], 0
	v_mfma_f32_16x16x32_bf16 v[72:75], v[160:163], v[216:219], 0
	v_mfma_f32_16x16x32_bf16 v[124:127], v[156:159], v[190:193], v[124:127]
	v_mfma_f32_16x16x32_bf16 v[120:123], v[164:167], v[190:193], v[120:123]
	v_mfma_f32_16x16x32_bf16 v[108:111], v[156:159], v[198:201], v[108:111]
	v_mfma_f32_16x16x32_bf16 v[104:107], v[164:167], v[198:201], v[104:107]
	v_mfma_f32_16x16x32_bf16 v[92:95], v[156:159], v[212:215], v[92:95]
	v_mfma_f32_16x16x32_bf16 v[88:91], v[164:167], v[212:215], v[88:91]
	v_mfma_f32_16x16x32_bf16 v[76:79], v[156:159], v[220:223], v[76:79]
	v_mfma_f32_16x16x32_bf16 v[72:75], v[164:167], v[220:223], v[72:75]
	s_setprio 0
	s_setprio 1
	v_mfma_f32_16x16x32_bf16 v[116:119], v[168:171], v[186:189], 0
	v_mfma_f32_16x16x32_bf16 v[112:115], v[176:179], v[186:189], 0
	v_mfma_f32_16x16x32_bf16 v[100:103], v[168:171], v[194:197], 0
	v_mfma_f32_16x16x32_bf16 v[96:99], v[176:179], v[194:197], 0
	v_mfma_f32_16x16x32_bf16 v[84:87], v[168:171], v[208:211], 0
	v_mfma_f32_16x16x32_bf16 v[80:83], v[176:179], v[208:211], 0
	v_mfma_f32_16x16x32_bf16 v[68:71], v[168:171], v[216:219], 0
	v_mfma_f32_16x16x32_bf16 v[64:67], v[176:179], v[216:219], 0
	v_mfma_f32_16x16x32_bf16 v[116:119], v[172:175], v[190:193], v[116:119]
	v_mfma_f32_16x16x32_bf16 v[112:115], v[182:185], v[190:193], v[112:115]
	v_mfma_f32_16x16x32_bf16 v[100:103], v[172:175], v[198:201], v[100:103]
	v_mfma_f32_16x16x32_bf16 v[96:99], v[182:185], v[198:201], v[96:99]
	v_mfma_f32_16x16x32_bf16 v[84:87], v[172:175], v[212:215], v[84:87]
	v_mfma_f32_16x16x32_bf16 v[80:83], v[182:185], v[212:215], v[80:83]
	v_mfma_f32_16x16x32_bf16 v[68:71], v[172:175], v[220:223], v[68:71]
	v_mfma_f32_16x16x32_bf16 v[64:67], v[182:185], v[220:223], v[64:67]
	s_setprio 0
	s_barrier
	s_add_i32 s3, s74, s14
	v_lshl_add_u64 v[202:203], s[60:61], 0, v[130:131]
	s_mov_b32 m0, s3
	ds_read_b128 v[186:189], v153 offset:16384
	ds_read_b128 v[190:193], v153 offset:17408
	ds_read_b128 v[194:197], v153 offset:18432
	ds_read_b128 v[198:201], v153 offset:19456
	ds_read_b128 v[208:211], v153 offset:20480
	ds_read_b128 v[212:215], v153 offset:21504
	ds_read_b128 v[216:219], v153 offset:22528
	ds_read_b128 v[220:223], v153 offset:23552
	global_load_lds_dwordx4 v[202:203], off
	s_add_i32 m0, s3, 0x2000
	s_add_u32 s78, s60, 0x20000
	v_lshl_add_u64 v[224:225], s[60:61], 0, v[134:135]
	s_addc_u32 s79, s61, 0
	s_add_i32 s3, s75, s14
	global_load_lds_dwordx4 v[224:225], off
	v_lshl_add_u64 v[226:227], s[78:79], 0, v[130:131]
	s_mov_b32 m0, s3
	global_load_lds_dwordx4 v[226:227], off
	v_lshl_add_u64 v[226:227], s[78:79], 0, v[134:135]
	s_add_i32 m0, s3, 0x2000
	s_nop 0
	global_load_lds_dwordx4 v[226:227], off
	s_waitcnt vmcnt(6)
	s_waitcnt lgkmcnt(0)
	s_barrier
; #define PG8_STAGE(bufoff, gbase, voff) do { _Pragma("unroll") for (int _i = 0; _i < 2; ++_i) \
;         __builtin_amdgcn_global_load_lds((const unsigned*)((const char*)(gbase) + (voff)[_i]), (PG8_LAS unsigned*)(lds + (bufoff) + ldsw + _i * 8192), 16, 0, 0); } while (0)
; #define PG8_LDA(dst, b, h) do { _Pragma("unroll") for (int m = 0; m < 4; ++m) _Pragma("unroll") for (int k = 0; k < 2; ++k) dst[m][k] = *(const PG8_LAS bf16x8*)(lds + PG8_SA(b, h) + aoff + m * 2048 + k * 1024); } while (0)
; #define PG8_LDB(dst, b, h) do { _Pragma("unroll") for (int n = 0; n < 2; ++n) _Pragma("unroll") for (int k = 0; k < 2; ++k) dst[n][k] = *(const PG8_LAS bf16x8*)(lds + PG8_SB(b, h) + boff + n * 2048 + k * 1024); } while (0)
; #define PG8_MMA(ai, bj, At, Bt) do { __builtin_amdgcn_s_setprio(1); _Pragma("unroll") for (int m = 0; m < 4; ++m) _Pragma("unroll") for (int n = 0; n < 2; ++n) _Pragma("unroll") for (int k = 0; k < 2; ++k) \
;         acc[ai][bj][m][n] = __builtin_amdgcn_mfma_f32_16x16x32_bf16(Bt[n][k], At[m][k], acc[ai][bj][m][n], 0, 0, 0); __builtin_amdgcn_s_setprio(0); } while (0)
; #define PG8_WAIT_V(n) asm volatile("s_waitcnt vmcnt(" #n ")" ::: "memory")
; #define PG8_WAIT_L(n) asm volatile("s_waitcnt lgkmcnt(" #n ")" ::: "memory")
; #define PG8_BAR __builtin_amdgcn_s_barrier()
; #define PG8_SCHED __builtin_amdgcn_sched_barrier(0)
; template <class Epi, class Sched, bool ALIGN_EPI = false, bool SP2 = false>
; __device__ __forceinline__ void gemm_phase(PG8_LAS unsigned char* lds, const Gemm g, const Sched& S, const Epi& E) {
;     ...
;             PG8_LDA(At, 0, 1); PG8_STAGE(PG8_SB(0, 0), b2, voffB); PG8_STAGE(PG8_SB(0, 1), b2 + hstep, voffB); PG8_STAGE(PG8_SA(0, 0), a2, voffA);
;             PG8_WAIT_V(8); PG8_WAIT_L(0); PG8_BAR; PG8_MMA(1, 0, At, B0); PG8_MMA(1, 1, At, B1); PG8_BAR; PG8_SCHED;
;             PG8_LDB(B0, 1, 0); PG8_LDB(B1, 1, 1); PG8_SCHED; PG8_LDA(At, 1, 0); PG8_STAGE(PG8_SA(0, 1), a2 + hstep, voffA);
;             PG8_WAIT_V(8); PG8_WAIT_L(0); PG8_BAR; PG8_MMA(0, 0, At, B0); PG8_MMA(0, 1, At, B1); PG8_BAR; PG8_SCHED;
	s_setprio 1
	s_waitcnt lgkmcnt(0)
	v_mfma_f32_16x16x32_bf16 v[60:63], v[144:147], v[186:189], 0
	v_mfma_f32_16x16x32_bf16 v[56:59], v[160:163], v[186:189], 0
	v_mfma_f32_16x16x32_bf16 v[44:47], v[144:147], v[194:197], 0
	v_mfma_f32_16x16x32_bf16 v[40:43], v[160:163], v[194:197], 0
	v_mfma_f32_16x16x32_bf16 v[28:31], v[144:147], v[208:211], 0
	v_mfma_f32_16x16x32_bf16 v[24:27], v[160:163], v[208:211], 0
	v_mfma_f32_16x16x32_bf16 v[12:15], v[144:147], v[216:219], 0
	v_mfma_f32_16x16x32_bf16 v[8:11], v[160:163], v[216:219], 0
	v_mfma_f32_16x16x32_bf16 v[60:63], v[156:159], v[190:193], v[60:63]
	v_mfma_f32_16x16x32_bf16 v[56:59], v[164:167], v[190:193], v[56:59]
	v_mfma_f32_16x16x32_bf16 v[44:47], v[156:159], v[198:201], v[44:47]
	v_mfma_f32_16x16x32_bf16 v[40:43], v[164:167], v[198:201], v[40:43]
	v_mfma_f32_16x16x32_bf16 v[28:31], v[156:159], v[212:215], v[28:31]
	v_mfma_f32_16x16x32_bf16 v[24:27], v[164:167], v[212:215], v[24:27]
	v_lshl_add_u64 v[226:227], s[62:63], 0, v[128:129]
	s_mov_b32 m0, s15
	s_nop 0
	global_load_lds_dwordx4 v[226:227], off
	v_mfma_f32_16x16x32_bf16 v[12:15], v[156:159], v[220:223], v[12:15]
	v_mfma_f32_16x16x32_bf16 v[8:11], v[164:167], v[220:223], v[8:11]
	s_setprio 0
	s_setprio 1
	v_mfma_f32_16x16x32_bf16 v[52:55], v[168:171], v[186:189], 0
	v_mfma_f32_16x16x32_bf16 v[48:51], v[176:179], v[186:189], 0
	v_mfma_f32_16x16x32_bf16 v[36:39], v[168:171], v[194:197], 0
	v_mfma_f32_16x16x32_bf16 v[32:35], v[176:179], v[194:197], 0
	v_mfma_f32_16x16x32_bf16 v[20:23], v[168:171], v[208:211], 0
	v_mfma_f32_16x16x32_bf16 v[16:19], v[176:179], v[208:211], 0
	v_mfma_f32_16x16x32_bf16 v[4:7], v[168:171], v[216:219], 0
	v_mfma_f32_16x16x32_bf16 v[0:3], v[176:179], v[216:219], 0
	v_mfma_f32_16x16x32_bf16 v[52:55], v[172:175], v[190:193], v[52:55]
	v_mfma_f32_16x16x32_bf16 v[48:51], v[182:185], v[190:193], v[48:51]
	v_mfma_f32_16x16x32_bf16 v[36:39], v[172:175], v[198:201], v[36:39]
	v_mfma_f32_16x16x32_bf16 v[32:35], v[182:185], v[198:201], v[32:35]
	v_mfma_f32_16x16x32_bf16 v[20:23], v[172:175], v[212:215], v[20:23]
	v_mfma_f32_16x16x32_bf16 v[16:19], v[182:185], v[212:215], v[16:19]
	v_lshl_add_u64 v[228:229], s[62:63], 0, v[132:133]
	s_mov_b32 m0, s34
	s_nop 0
	global_load_lds_dwordx4 v[228:229], off
	v_mfma_f32_16x16x32_bf16 v[4:7], v[172:175], v[220:223], v[4:7]
	v_mfma_f32_16x16x32_bf16 v[0:3], v[182:185], v[220:223], v[0:3]
	s_setprio 0
	s_barrier
	s_add_i32 s3, 0, 0x18000
	v_add_u32_e32 v155, s3, v149
	s_add_i32 s33, 0, 0x1c000
	ds_read_b128 v[144:147], v155
	ds_read_b128 v[156:159], v155 offset:1024
	ds_read_b128 v[160:163], v155 offset:2048
	ds_read_b128 v[164:167], v155 offset:3072
	v_add_u32_e32 v155, s33, v149
	ds_read_b128 v[168:171], v155
	ds_read_b128 v[172:175], v155 offset:1024
	ds_read_b128 v[176:179], v155 offset:2048
	ds_read_b128 v[182:185], v155 offset:3072
	s_add_u32 s62, s62, 0x20000
	s_addc_u32 s63, s63, 0
	s_mov_b32 m0, s57
	v_lshl_add_u64 v[230:231], s[62:63], 0, v[128:129]
	ds_read_b128 v[186:189], v153 offset:32768
	ds_read_b128 v[190:193], v153 offset:33792
	ds_read_b128 v[194:197], v153 offset:34816
	ds_read_b128 v[198:201], v153 offset:35840
	ds_read_b128 v[208:211], v153 offset:36864
	ds_read_b128 v[212:215], v153 offset:37888
	ds_read_b128 v[216:219], v153 offset:38912
	ds_read_b128 v[220:223], v153 offset:39936
	global_load_lds_dwordx4 v[230:231], off
	v_lshl_add_u64 v[230:231], s[62:63], 0, v[132:133]
	s_mov_b32 m0, s64
	s_nop 0
	global_load_lds_dwordx4 v[230:231], off
	s_waitcnt vmcnt(8)
	s_waitcnt lgkmcnt(0)
	s_barrier
	s_setprio 1
	s_waitcnt lgkmcnt(0)
	v_mfma_f32_16x16x32_bf16 v[124:127], v[144:147], v[186:189], v[124:127]
	v_mfma_f32_16x16x32_bf16 v[120:123], v[160:163], v[186:189], v[120:123]
	v_mfma_f32_16x16x32_bf16 v[108:111], v[144:147], v[194:197], v[108:111]
	v_mfma_f32_16x16x32_bf16 v[104:107], v[160:163], v[194:197], v[104:107]
	v_mfma_f32_16x16x32_bf16 v[92:95], v[144:147], v[208:211], v[92:95]
	v_mfma_f32_16x16x32_bf16 v[88:91], v[160:163], v[208:211], v[88:91]
	v_mfma_f32_16x16x32_bf16 v[76:79], v[144:147], v[216:219], v[76:79]
	v_mfma_f32_16x16x32_bf16 v[72:75], v[160:163], v[216:219], v[72:75]
	v_mfma_f32_16x16x32_bf16 v[124:127], v[156:159], v[190:193], v[124:127]
	v_mfma_f32_16x16x32_bf16 v[120:123], v[164:167], v[190:193], v[120:123]
	v_mfma_f32_16x16x32_bf16 v[108:111], v[156:159], v[198:201], v[108:111]
	v_mfma_f32_16x16x32_bf16 v[104:107], v[164:167], v[198:201], v[104:107]
	v_mfma_f32_16x16x32_bf16 v[92:95], v[156:159], v[212:215], v[92:95]
	v_mfma_f32_16x16x32_bf16 v[88:91], v[164:167], v[212:215], v[88:91]
	v_mfma_f32_16x16x32_bf16 v[76:79], v[156:159], v[220:223], v[76:79]
	v_mfma_f32_16x16x32_bf16 v[72:75], v[164:167], v[220:223], v[72:75]
	s_setprio 0
	s_setprio 1
	v_mfma_f32_16x16x32_bf16 v[116:119], v[168:171], v[186:189], v[116:119]
	v_mfma_f32_16x16x32_bf16 v[112:115], v[176:179], v[186:189], v[112:115]
	v_mfma_f32_16x16x32_bf16 v[100:103], v[168:171], v[194:197], v[100:103]
	v_mfma_f32_16x16x32_bf16 v[96:99], v[176:179], v[194:197], v[96:99]
	v_mfma_f32_16x16x32_bf16 v[84:87], v[168:171], v[208:211], v[84:87]
	v_mfma_f32_16x16x32_bf16 v[80:83], v[176:179], v[208:211], v[80:83]
	v_mfma_f32_16x16x32_bf16 v[68:71], v[168:171], v[216:219], v[68:71]
	v_mfma_f32_16x16x32_bf16 v[64:67], v[176:179], v[216:219], v[64:67]
	v_mfma_f32_16x16x32_bf16 v[116:119], v[172:175], v[190:193], v[116:119]
	v_mfma_f32_16x16x32_bf16 v[112:115], v[182:185], v[190:193], v[112:115]
	v_mfma_f32_16x16x32_bf16 v[100:103], v[172:175], v[198:201], v[100:103]
	v_mfma_f32_16x16x32_bf16 v[96:99], v[182:185], v[198:201], v[96:99]
	v_mfma_f32_16x16x32_bf16 v[84:87], v[172:175], v[212:215], v[84:87]
	v_mfma_f32_16x16x32_bf16 v[80:83], v[182:185], v[212:215], v[80:83]
	v_mfma_f32_16x16x32_bf16 v[68:71], v[172:175], v[220:223], v[68:71]
	v_mfma_f32_16x16x32_bf16 v[64:67], v[182:185], v[220:223], v[64:67]
	s_setprio 0
	s_barrier
; #define PG8_STAGE(bufoff, gbase, voff) do { _Pragma("unroll") for (int _i = 0; _i < 2; ++_i) \
;         __builtin_amdgcn_global_load_lds((const unsigned*)((const char*)(gbase) + (voff)[_i]), (PG8_LAS unsigned*)(lds + (bufoff) + ldsw + _i * 8192), 16, 0, 0); } while (0)
; #define PG8_LDA(dst, b, h) do { _Pragma("unroll") for (int m = 0; m < 4; ++m) _Pragma("unroll") for (int k = 0; k < 2; ++k) dst[m][k] = *(const PG8_LAS bf16x8*)(lds + PG8_SA(b, h) + aoff + m * 2048 + k * 1024); } while (0)
; #define PG8_LDB(dst, b, h) do { _Pragma("unroll") for (int n = 0; n < 2; ++n) _Pragma("unroll") for (int k = 0; k < 2; ++k) dst[n][k] = *(const PG8_LAS bf16x8*)(lds + PG8_SB(b, h) + boff + n * 2048 + k * 1024); } while (0)
; #define PG8_MMA(ai, bj, At, Bt) do { __builtin_amdgcn_s_setprio(1); _Pragma("unroll") for (int m = 0; m < 4; ++m) _Pragma("unroll") for (int n = 0; n < 2; ++n) _Pragma("unroll") for (int k = 0; k < 2; ++k) \
;         acc[ai][bj][m][n] = __builtin_amdgcn_mfma_f32_16x16x32_bf16(Bt[n][k], At[m][k], acc[ai][bj][m][n], 0, 0, 0); __builtin_amdgcn_s_setprio(0); } while (0)
; #define PG8_WAIT_V(n) asm volatile("s_waitcnt vmcnt(" #n ")" ::: "memory")
; template <class Epi, class Sched, bool ALIGN_EPI = false, bool SP2 = false>
; __device__ __forceinline__ void gemm_phase(PG8_LAS unsigned char* lds, const Gemm g, const Sched& S, const Epi& E) {
;     ...
;             PG8_LDB(B0, 0, 0); PG8_LDB(B1, 0, 1); PG8_SCHED; PG8_LDA(At, 0, 0); PG8_STAGE(PG8_SA(1, 1), a1 + hstep, voffA);
;             PG8_WAIT_V(8); PG8_WAIT_L(0); PG8_BAR; PG8_MMA(0, 0, At, B0); PG8_MMA(0, 1, At, B1); PG8_BAR; PG8_SCHED;
;             PG8_LDA(At, 0, 1); PG8_STAGE(PG8_SB(0, 0), b2, voffB); PG8_STAGE(PG8_SB(0, 1), b2 + hstep, voffB); PG8_STAGE(PG8_SA(0, 0), a2, voffA);
;             PG8_WAIT_V(8); PG8_WAIT_L(0); PG8_BAR; PG8_MMA(1, 0, At, B0); PG8_MMA(1, 1, At, B1); PG8_BAR; PG8_SCHED;
;             PG8_LDB(B0, 1, 0); PG8_LDB(B1, 1, 1); PG8_SCHED; PG8_LDA(At, 1, 0); PG8_STAGE(PG8_SA(0, 1), a2 + hstep, voffA);
;             PG8_WAIT_V(8); PG8_WAIT_L(0); PG8_BAR; PG8_MMA(0, 0, At, B0); PG8_MMA(0, 1, At, B1); PG8_BAR; PG8_SCHED;
;             PG8_LDA(At, 1, 1); PG8_STAGE(PG8_SB(1, 0), b3, voffB); PG8_STAGE(PG8_SB(1, 1), b3 + hstep, voffB); PG8_STAGE(PG8_SA(1, 0), a3, voffA);
;             PG8_WAIT_V(8); PG8_WAIT_L(0); PG8_BAR; PG8_MMA(1, 0, At, B0); PG8_MMA(1, 1, At, B1); PG8_BAR; PG8_SCHED;
	s_add_i32 s3, s3, s14
	v_lshl_add_u64 v[202:203], v[202:203], 0, s[38:39]
	s_mov_b32 m0, s3
	ds_read_b128 v[186:189], v153 offset:49152
	ds_read_b128 v[190:193], v153 offset:50176
	ds_read_b128 v[194:197], v153 offset:51200
	ds_read_b128 v[198:201], v153 offset:52224
	ds_read_b128 v[208:211], v153 offset:53248
	ds_read_b128 v[212:215], v153 offset:54272
	ds_read_b128 v[216:219], v153 offset:55296
	ds_read_b128 v[220:223], v153 offset:56320
	global_load_lds_dwordx4 v[202:203], off
	s_add_i32 m0, s3, 0x2000
	s_add_u32 s60, s60, 0x20080
	v_lshl_add_u64 v[202:203], v[224:225], 0, s[38:39]
	s_addc_u32 s61, s61, 0
	s_add_i32 s3, s33, s14
	global_load_lds_dwordx4 v[202:203], off
	v_lshl_add_u64 v[202:203], s[60:61], 0, v[130:131]
	s_mov_b32 m0, s3
	s_nop 0
	global_load_lds_dwordx4 v[202:203], off
	v_lshl_add_u64 v[202:203], s[60:61], 0, v[134:135]
	s_add_i32 m0, s3, 0x2000
	s_nop 0
	global_load_lds_dwordx4 v[202:203], off
	s_waitcnt vmcnt(6)
	s_waitcnt lgkmcnt(0)
	s_barrier
	s_setprio 1
	s_waitcnt lgkmcnt(0)
	v_mfma_f32_16x16x32_bf16 v[60:63], v[144:147], v[186:189], v[60:63]
	v_mfma_f32_16x16x32_bf16 v[56:59], v[160:163], v[186:189], v[56:59]
	v_mfma_f32_16x16x32_bf16 v[44:47], v[144:147], v[194:197], v[44:47]
	v_mfma_f32_16x16x32_bf16 v[40:43], v[160:163], v[194:197], v[40:43]
	v_mfma_f32_16x16x32_bf16 v[28:31], v[144:147], v[208:211], v[28:31]
	v_mfma_f32_16x16x32_bf16 v[24:27], v[160:163], v[208:211], v[24:27]
	v_mfma_f32_16x16x32_bf16 v[12:15], v[144:147], v[216:219], v[12:15]
	v_mfma_f32_16x16x32_bf16 v[8:11], v[160:163], v[216:219], v[8:11]
	v_mfma_f32_16x16x32_bf16 v[60:63], v[156:159], v[190:193], v[60:63]
	v_mfma_f32_16x16x32_bf16 v[56:59], v[164:167], v[190:193], v[56:59]
	v_mfma_f32_16x16x32_bf16 v[44:47], v[156:159], v[198:201], v[44:47]
	v_mfma_f32_16x16x32_bf16 v[40:43], v[164:167], v[198:201], v[40:43]
	v_mfma_f32_16x16x32_bf16 v[28:31], v[156:159], v[212:215], v[28:31]
	v_mfma_f32_16x16x32_bf16 v[24:27], v[164:167], v[212:215], v[24:27]
	v_lshl_add_u64 v[202:203], v[226:227], 0, s[38:39]
	s_mov_b32 m0, s66
	s_nop 0
	global_load_lds_dwordx4 v[202:203], off
	v_mfma_f32_16x16x32_bf16 v[12:15], v[156:159], v[220:223], v[12:15]
	v_mfma_f32_16x16x32_bf16 v[8:11], v[164:167], v[220:223], v[8:11]
	s_setprio 0
	s_setprio 1
	v_mfma_f32_16x16x32_bf16 v[52:55], v[168:171], v[186:189], v[52:55]
	v_mfma_f32_16x16x32_bf16 v[48:51], v[176:179], v[186:189], v[48:51]
	v_mfma_f32_16x16x32_bf16 v[36:39], v[168:171], v[194:197], v[36:39]
	v_mfma_f32_16x16x32_bf16 v[32:35], v[176:179], v[194:197], v[32:35]
	v_mfma_f32_16x16x32_bf16 v[20:23], v[168:171], v[208:211], v[20:23]
	v_mfma_f32_16x16x32_bf16 v[16:19], v[176:179], v[208:211], v[16:19]
	v_mfma_f32_16x16x32_bf16 v[4:7], v[168:171], v[216:219], v[4:7]
	v_mfma_f32_16x16x32_bf16 v[0:3], v[176:179], v[216:219], v[0:3]
	v_mfma_f32_16x16x32_bf16 v[52:55], v[172:175], v[190:193], v[52:55]
	v_mfma_f32_16x16x32_bf16 v[48:51], v[182:185], v[190:193], v[48:51]
	v_mfma_f32_16x16x32_bf16 v[36:39], v[172:175], v[198:201], v[36:39]
	v_mfma_f32_16x16x32_bf16 v[32:35], v[182:185], v[198:201], v[32:35]
	v_mfma_f32_16x16x32_bf16 v[20:23], v[172:175], v[212:215], v[20:23]
	v_mfma_f32_16x16x32_bf16 v[16:19], v[182:185], v[212:215], v[16:19]
	v_lshl_add_u64 v[202:203], v[228:229], 0, s[38:39]
	s_mov_b32 m0, s67
	s_nop 0
	global_load_lds_dwordx4 v[202:203], off
	v_mfma_f32_16x16x32_bf16 v[4:7], v[172:175], v[220:223], v[4:7]
	v_mfma_f32_16x16x32_bf16 v[0:3], v[182:185], v[220:223], v[0:3]
	s_setprio 0
	s_barrier
	s_add_i32 s87, s87, 2
	s_add_u32 s58, s58, 0x100
	s_addc_u32 s59, s59, 0
	s_add_u32 s85, s85, 0x100
	s_addc_u32 s86, s86, 0
.LBB0_873:
	ds_read_b128 v[144:147], v151
	ds_read_b128 v[156:159], v151 offset:1024
	ds_read_b128 v[160:163], v151 offset:2048
	ds_read_b128 v[164:167], v151 offset:3072
	ds_read_b128 v[168:171], v152
	ds_read_b128 v[172:175], v152 offset:1024
	ds_read_b128 v[176:179], v152 offset:2048
	ds_read_b128 v[182:185], v152 offset:3072
	s_add_u32 s3, s58, 0xfffe0080
	s_addc_u32 s33, s59, -1
	s_cmp_eq_u32 s87, 4
	s_cselect_b32 s63, s49, s33
	s_cselect_b32 s62, s55, s3
	s_cselect_b32 s61, s45, s86
	s_cselect_b32 s60, s84, s85
	v_lshl_add_u64 v[202:203], s[58:59], 0, v[136:137]
	s_add_i32 m0, s15, 0xc000
	ds_read_b128 v[186:189], v153
	ds_read_b128 v[190:193], v153 offset:1024
	ds_read_b128 v[194:197], v153 offset:2048
	ds_read_b128 v[198:201], v153 offset:3072
	ds_read_b128 v[208:211], v153 offset:4096
	ds_read_b128 v[212:215], v153 offset:5120
	ds_read_b128 v[216:219], v153 offset:6144
	ds_read_b128 v[220:223], v153 offset:7168
	global_load_lds_dwordx4 v[202:203], off
	v_lshl_add_u64 v[202:203], s[58:59], 0, v[138:139]
	s_add_i32 m0, s15, 0xe000
	s_nop 0
	global_load_lds_dwordx4 v[202:203], off
	s_waitcnt vmcnt(8)
	s_waitcnt lgkmcnt(0)
	s_barrier
; #define PG8_STAGE(bufoff, gbase, voff) do { _Pragma("unroll") for (int _i = 0; _i < 2; ++_i) \
;         __builtin_amdgcn_global_load_lds((const unsigned*)((const char*)(gbase) + (voff)[_i]), (PG8_LAS unsigned*)(lds + (bufoff) + ldsw + _i * 8192), 16, 0, 0); } while (0)
; #define PG8_LDA(dst, b, h) do { _Pragma("unroll") for (int m = 0; m < 4; ++m) _Pragma("unroll") for (int k = 0; k < 2; ++k) dst[m][k] = *(const PG8_LAS bf16x8*)(lds + PG8_SA(b, h) + aoff + m * 2048 + k * 1024); } while (0)
; #define PG8_LDB(dst, b, h) do { _Pragma("unroll") for (int n = 0; n < 2; ++n) _Pragma("unroll") for (int k = 0; k < 2; ++k) dst[n][k] = *(const PG8_LAS bf16x8*)(lds + PG8_SB(b, h) + boff + n * 2048 + k * 1024); } while (0)
; #define PG8_MMA(ai, bj, At, Bt) do { __builtin_amdgcn_s_setprio(1); _Pragma("unroll") for (int m = 0; m < 4; ++m) _Pragma("unroll") for (int n = 0; n < 2; ++n) _Pragma("unroll") for (int k = 0; k < 2; ++k) \
;         acc[ai][bj][m][n] = __builtin_amdgcn_mfma_f32_16x16x32_bf16(Bt[n][k], At[m][k], acc[ai][bj][m][n], 0, 0, 0); __builtin_amdgcn_s_setprio(0); } while (0)
; #define PG8_WAIT_V(n) asm volatile("s_waitcnt vmcnt(" #n ")" ::: "memory")
; #define PG8_WAIT_L(n) asm volatile("s_waitcnt lgkmcnt(" #n ")" ::: "memory")
; #define PG8_BAR __builtin_amdgcn_s_barrier()
; #define PG8_SCHED __builtin_amdgcn_sched_barrier(0)
; template <class Epi, class Sched, bool ALIGN_EPI = false, bool SP2 = false>
; __device__ __forceinline__ void gemm_phase(PG8_LAS unsigned char* lds, const Gemm g, const Sched& S, const Epi& E) {
;     ...
;             PG8_LDB(B0, 0, 0); PG8_LDB(B1, 0, 1); PG8_SCHED; PG8_LDA(At, 0, 0); PG8_STAGE(PG8_SA(1, 1), a1 + hstep, voffA);
;             PG8_WAIT_V(8); PG8_WAIT_L(0); PG8_BAR; PG8_MMA(0, 0, At, B0); PG8_MMA(0, 1, At, B1); PG8_BAR; PG8_SCHED;
;             PG8_LDA(At, 0, 1); PG8_STAGE(PG8_SB(0, 0), b2, voffB); PG8_STAGE(PG8_SB(0, 1), b2 + hstep, voffB); PG8_STAGE(PG8_SA(0, 0), a2, voffA);
;             PG8_WAIT_V(8); PG8_WAIT_L(0); PG8_BAR; PG8_MMA(1, 0, At, B0); PG8_MMA(1, 1, At, B1); PG8_BAR; PG8_SCHED;
	s_setprio 1
	s_waitcnt lgkmcnt(0)
	v_mfma_f32_16x16x32_bf16 v[124:127], v[144:147], v[186:189], v[124:127]
	v_mfma_f32_16x16x32_bf16 v[120:123], v[160:163], v[186:189], v[120:123]
	v_mfma_f32_16x16x32_bf16 v[108:111], v[144:147], v[194:197], v[108:111]
	v_mfma_f32_16x16x32_bf16 v[104:107], v[160:163], v[194:197], v[104:107]
	v_mfma_f32_16x16x32_bf16 v[92:95], v[144:147], v[208:211], v[92:95]
	v_mfma_f32_16x16x32_bf16 v[88:91], v[160:163], v[208:211], v[88:91]
	v_mfma_f32_16x16x32_bf16 v[76:79], v[144:147], v[216:219], v[76:79]
	v_mfma_f32_16x16x32_bf16 v[72:75], v[160:163], v[216:219], v[72:75]
	v_mfma_f32_16x16x32_bf16 v[124:127], v[156:159], v[190:193], v[124:127]
	v_mfma_f32_16x16x32_bf16 v[120:123], v[164:167], v[190:193], v[120:123]
	v_mfma_f32_16x16x32_bf16 v[108:111], v[156:159], v[198:201], v[108:111]
	v_mfma_f32_16x16x32_bf16 v[104:107], v[164:167], v[198:201], v[104:107]
	v_mfma_f32_16x16x32_bf16 v[92:95], v[156:159], v[212:215], v[92:95]
	v_mfma_f32_16x16x32_bf16 v[88:91], v[164:167], v[212:215], v[88:91]
	v_mfma_f32_16x16x32_bf16 v[76:79], v[156:159], v[220:223], v[76:79]
	v_mfma_f32_16x16x32_bf16 v[72:75], v[164:167], v[220:223], v[72:75]
	s_setprio 0
	s_setprio 1
	v_mfma_f32_16x16x32_bf16 v[116:119], v[168:171], v[186:189], v[116:119]
	v_mfma_f32_16x16x32_bf16 v[112:115], v[176:179], v[186:189], v[112:115]
	v_mfma_f32_16x16x32_bf16 v[100:103], v[168:171], v[194:197], v[100:103]
	v_mfma_f32_16x16x32_bf16 v[96:99], v[176:179], v[194:197], v[96:99]
	v_mfma_f32_16x16x32_bf16 v[84:87], v[168:171], v[208:211], v[84:87]
	v_mfma_f32_16x16x32_bf16 v[80:83], v[176:179], v[208:211], v[80:83]
	v_mfma_f32_16x16x32_bf16 v[68:71], v[168:171], v[216:219], v[68:71]
	v_mfma_f32_16x16x32_bf16 v[64:67], v[176:179], v[216:219], v[64:67]
	v_mfma_f32_16x16x32_bf16 v[116:119], v[172:175], v[190:193], v[116:119]
	v_mfma_f32_16x16x32_bf16 v[112:115], v[182:185], v[190:193], v[112:115]
	v_mfma_f32_16x16x32_bf16 v[100:103], v[172:175], v[198:201], v[100:103]
	v_mfma_f32_16x16x32_bf16 v[96:99], v[182:185], v[198:201], v[96:99]
	v_mfma_f32_16x16x32_bf16 v[84:87], v[172:175], v[212:215], v[84:87]
	v_mfma_f32_16x16x32_bf16 v[80:83], v[182:185], v[212:215], v[80:83]
	v_mfma_f32_16x16x32_bf16 v[68:71], v[172:175], v[220:223], v[68:71]
	v_mfma_f32_16x16x32_bf16 v[64:67], v[182:185], v[220:223], v[64:67]
	s_setprio 0
	s_barrier
	s_add_i32 s3, s74, s14
	v_lshl_add_u64 v[202:203], s[60:61], 0, v[130:131]
	s_mov_b32 m0, s3
	ds_read_b128 v[186:189], v153 offset:16384
	ds_read_b128 v[190:193], v153 offset:17408
	ds_read_b128 v[194:197], v153 offset:18432
	ds_read_b128 v[198:201], v153 offset:19456
	ds_read_b128 v[208:211], v153 offset:20480
	ds_read_b128 v[212:215], v153 offset:21504
	ds_read_b128 v[216:219], v153 offset:22528
	ds_read_b128 v[220:223], v153 offset:23552
	global_load_lds_dwordx4 v[202:203], off
	s_add_i32 m0, s3, 0x2000
	s_add_u32 s78, s60, 0x20000
	v_lshl_add_u64 v[224:225], s[60:61], 0, v[134:135]
	s_addc_u32 s79, s61, 0
	s_add_i32 s3, s75, s14
	global_load_lds_dwordx4 v[224:225], off
	v_lshl_add_u64 v[226:227], s[78:79], 0, v[130:131]
	s_mov_b32 m0, s3
	global_load_lds_dwordx4 v[226:227], off
	v_lshl_add_u64 v[226:227], s[78:79], 0, v[134:135]
	s_add_i32 m0, s3, 0x2000
	s_nop 0
	global_load_lds_dwordx4 v[226:227], off
	s_waitcnt vmcnt(6)
	s_waitcnt lgkmcnt(0)
	s_barrier
	s_setprio 1
	s_waitcnt lgkmcnt(0)
	v_mfma_f32_16x16x32_bf16 v[60:63], v[144:147], v[186:189], v[60:63]
	v_mfma_f32_16x16x32_bf16 v[56:59], v[160:163], v[186:189], v[56:59]
	v_mfma_f32_16x16x32_bf16 v[44:47], v[144:147], v[194:197], v[44:47]
	v_mfma_f32_16x16x32_bf16 v[40:43], v[160:163], v[194:197], v[40:43]
	v_mfma_f32_16x16x32_bf16 v[28:31], v[144:147], v[208:211], v[28:31]
	v_mfma_f32_16x16x32_bf16 v[24:27], v[160:163], v[208:211], v[24:27]
	v_mfma_f32_16x16x32_bf16 v[12:15], v[144:147], v[216:219], v[12:15]
	v_mfma_f32_16x16x32_bf16 v[8:11], v[160:163], v[216:219], v[8:11]
	v_mfma_f32_16x16x32_bf16 v[60:63], v[156:159], v[190:193], v[60:63]
	v_mfma_f32_16x16x32_bf16 v[56:59], v[164:167], v[190:193], v[56:59]
	v_mfma_f32_16x16x32_bf16 v[44:47], v[156:159], v[198:201], v[44:47]
	v_mfma_f32_16x16x32_bf16 v[40:43], v[164:167], v[198:201], v[40:43]
	v_mfma_f32_16x16x32_bf16 v[28:31], v[156:159], v[212:215], v[28:31]
	v_mfma_f32_16x16x32_bf16 v[24:27], v[164:167], v[212:215], v[24:27]
	v_lshl_add_u64 v[226:227], s[62:63], 0, v[128:129]
	s_mov_b32 m0, s15
	s_nop 0
	global_load_lds_dwordx4 v[226:227], off
	v_mfma_f32_16x16x32_bf16 v[12:15], v[156:159], v[220:223], v[12:15]
	v_mfma_f32_16x16x32_bf16 v[8:11], v[164:167], v[220:223], v[8:11]
	s_setprio 0
	s_setprio 1
	v_mfma_f32_16x16x32_bf16 v[52:55], v[168:171], v[186:189], v[52:55]
	v_mfma_f32_16x16x32_bf16 v[48:51], v[176:179], v[186:189], v[48:51]
	v_mfma_f32_16x16x32_bf16 v[36:39], v[168:171], v[194:197], v[36:39]
	v_mfma_f32_16x16x32_bf16 v[32:35], v[176:179], v[194:197], v[32:35]
	v_mfma_f32_16x16x32_bf16 v[20:23], v[168:171], v[208:211], v[20:23]
	v_mfma_f32_16x16x32_bf16 v[16:19], v[176:179], v[208:211], v[16:19]
	v_mfma_f32_16x16x32_bf16 v[4:7], v[168:171], v[216:219], v[4:7]
	v_mfma_f32_16x16x32_bf16 v[0:3], v[176:179], v[216:219], v[0:3]
	v_mfma_f32_16x16x32_bf16 v[52:55], v[172:175], v[190:193], v[52:55]
	v_mfma_f32_16x16x32_bf16 v[48:51], v[182:185], v[190:193], v[48:51]
	v_mfma_f32_16x16x32_bf16 v[36:39], v[172:175], v[198:201], v[36:39]
	v_mfma_f32_16x16x32_bf16 v[32:35], v[182:185], v[198:201], v[32:35]
	v_mfma_f32_16x16x32_bf16 v[20:23], v[172:175], v[212:215], v[20:23]
	v_mfma_f32_16x16x32_bf16 v[16:19], v[182:185], v[212:215], v[16:19]
	v_lshl_add_u64 v[228:229], s[62:63], 0, v[132:133]
	s_mov_b32 m0, s34
	s_nop 0
	global_load_lds_dwordx4 v[228:229], off
	v_mfma_f32_16x16x32_bf16 v[4:7], v[172:175], v[220:223], v[4:7]
	v_mfma_f32_16x16x32_bf16 v[0:3], v[182:185], v[220:223], v[0:3]
	s_setprio 0
	s_barrier
; #define PG8_STAGE(bufoff, gbase, voff) do { _Pragma("unroll") for (int _i = 0; _i < 2; ++_i) \
;         __builtin_amdgcn_global_load_lds((const unsigned*)((const char*)(gbase) + (voff)[_i]), (PG8_LAS unsigned*)(lds + (bufoff) + ldsw + _i * 8192), 16, 0, 0); } while (0)
; #define PG8_LDA(dst, b, h) do { _Pragma("unroll") for (int m = 0; m < 4; ++m) _Pragma("unroll") for (int k = 0; k < 2; ++k) dst[m][k] = *(const PG8_LAS bf16x8*)(lds + PG8_SA(b, h) + aoff + m * 2048 + k * 1024); } while (0)
; #define PG8_LDB(dst, b, h) do { _Pragma("unroll") for (int n = 0; n < 2; ++n) _Pragma("unroll") for (int k = 0; k < 2; ++k) dst[n][k] = *(const PG8_LAS bf16x8*)(lds + PG8_SB(b, h) + boff + n * 2048 + k * 1024); } while (0)
; #define PG8_MMA(ai, bj, At, Bt) do { __builtin_amdgcn_s_setprio(1); _Pragma("unroll") for (int m = 0; m < 4; ++m) _Pragma("unroll") for (int n = 0; n < 2; ++n) _Pragma("unroll") for (int k = 0; k < 2; ++k) \
;         acc[ai][bj][m][n] = __builtin_amdgcn_mfma_f32_16x16x32_bf16(Bt[n][k], At[m][k], acc[ai][bj][m][n], 0, 0, 0); __builtin_amdgcn_s_setprio(0); } while (0)
; #define PG8_WAIT_V(n) asm volatile("s_waitcnt vmcnt(" #n ")" ::: "memory")
; #define PG8_WAIT_L(n) asm volatile("s_waitcnt lgkmcnt(" #n ")" ::: "memory")
; #define PG8_BAR __builtin_amdgcn_s_barrier()
; #define PG8_SCHED __builtin_amdgcn_sched_barrier(0)
; template <class Epi, class Sched, bool ALIGN_EPI = false, bool SP2 = false>
; __device__ __forceinline__ void gemm_phase(PG8_LAS unsigned char* lds, const Gemm g, const Sched& S, const Epi& E) {
;     ...
;             PG8_LDB(B0, 1, 0); PG8_LDB(B1, 1, 1); PG8_SCHED; PG8_LDA(At, 1, 0); PG8_STAGE(PG8_SA(0, 1), a2 + hstep, voffA);
;             PG8_WAIT_V(8); PG8_WAIT_L(0); PG8_BAR; PG8_MMA(0, 0, At, B0); PG8_MMA(0, 1, At, B1); PG8_BAR; PG8_SCHED;
	s_add_i32 s3, 0, 0x18000
	v_add_u32_e32 v155, s3, v149
	s_add_i32 s33, 0, 0x1c000
	ds_read_b128 v[144:147], v155
	ds_read_b128 v[156:159], v155 offset:1024
	ds_read_b128 v[160:163], v155 offset:2048
	ds_read_b128 v[164:167], v155 offset:3072
	v_add_u32_e32 v155, s33, v149
	ds_read_b128 v[168:171], v155
	ds_read_b128 v[172:175], v155 offset:1024
	ds_read_b128 v[176:179], v155 offset:2048
	ds_read_b128 v[182:185], v155 offset:3072
	s_add_u32 s62, s62, 0x20000
	s_addc_u32 s63, s63, 0
	s_mov_b32 m0, s57
	v_lshl_add_u64 v[230:231], s[62:63], 0, v[128:129]
	ds_read_b128 v[186:189], v153 offset:32768
	ds_read_b128 v[190:193], v153 offset:33792
	ds_read_b128 v[194:197], v153 offset:34816
	ds_read_b128 v[198:201], v153 offset:35840
	ds_read_b128 v[208:211], v153 offset:36864
	ds_read_b128 v[212:215], v153 offset:37888
	ds_read_b128 v[216:219], v153 offset:38912
	ds_read_b128 v[220:223], v153 offset:39936
	global_load_lds_dwordx4 v[230:231], off
	v_lshl_add_u64 v[230:231], s[62:63], 0, v[132:133]
	s_mov_b32 m0, s64
	s_nop 0
	global_load_lds_dwordx4 v[230:231], off
	s_waitcnt vmcnt(8)
	s_waitcnt lgkmcnt(0)
	s_barrier
	s_setprio 1
	s_waitcnt lgkmcnt(0)
	v_mfma_f32_16x16x32_bf16 v[124:127], v[144:147], v[186:189], v[124:127]
	v_mfma_f32_16x16x32_bf16 v[120:123], v[160:163], v[186:189], v[120:123]
	v_mfma_f32_16x16x32_bf16 v[108:111], v[144:147], v[194:197], v[108:111]
	v_mfma_f32_16x16x32_bf16 v[104:107], v[160:163], v[194:197], v[104:107]
	v_mfma_f32_16x16x32_bf16 v[92:95], v[144:147], v[208:211], v[92:95]
	v_mfma_f32_16x16x32_bf16 v[88:91], v[160:163], v[208:211], v[88:91]
	v_mfma_f32_16x16x32_bf16 v[76:79], v[144:147], v[216:219], v[76:79]
	v_mfma_f32_16x16x32_bf16 v[72:75], v[160:163], v[216:219], v[72:75]
	v_mfma_f32_16x16x32_bf16 v[124:127], v[156:159], v[190:193], v[124:127]
	v_mfma_f32_16x16x32_bf16 v[120:123], v[164:167], v[190:193], v[120:123]
	v_mfma_f32_16x16x32_bf16 v[108:111], v[156:159], v[198:201], v[108:111]
	v_mfma_f32_16x16x32_bf16 v[104:107], v[164:167], v[198:201], v[104:107]
	v_mfma_f32_16x16x32_bf16 v[92:95], v[156:159], v[212:215], v[92:95]
	v_mfma_f32_16x16x32_bf16 v[88:91], v[164:167], v[212:215], v[88:91]
	v_mfma_f32_16x16x32_bf16 v[76:79], v[156:159], v[220:223], v[76:79]
	v_mfma_f32_16x16x32_bf16 v[72:75], v[164:167], v[220:223], v[72:75]
	s_setprio 0
	s_setprio 1
	v_mfma_f32_16x16x32_bf16 v[116:119], v[168:171], v[186:189], v[116:119]
	v_mfma_f32_16x16x32_bf16 v[112:115], v[176:179], v[186:189], v[112:115]
	v_mfma_f32_16x16x32_bf16 v[100:103], v[168:171], v[194:197], v[100:103]
	v_mfma_f32_16x16x32_bf16 v[96:99], v[176:179], v[194:197], v[96:99]
	v_mfma_f32_16x16x32_bf16 v[84:87], v[168:171], v[208:211], v[84:87]
	v_mfma_f32_16x16x32_bf16 v[80:83], v[176:179], v[208:211], v[80:83]
	v_mfma_f32_16x16x32_bf16 v[68:71], v[168:171], v[216:219], v[68:71]
	v_mfma_f32_16x16x32_bf16 v[64:67], v[176:179], v[216:219], v[64:67]
	v_mfma_f32_16x16x32_bf16 v[116:119], v[172:175], v[190:193], v[116:119]
	v_mfma_f32_16x16x32_bf16 v[112:115], v[182:185], v[190:193], v[112:115]
	v_mfma_f32_16x16x32_bf16 v[100:103], v[172:175], v[198:201], v[100:103]
	v_mfma_f32_16x16x32_bf16 v[96:99], v[182:185], v[198:201], v[96:99]
	v_mfma_f32_16x16x32_bf16 v[84:87], v[172:175], v[212:215], v[84:87]
	v_mfma_f32_16x16x32_bf16 v[80:83], v[182:185], v[212:215], v[80:83]
	v_mfma_f32_16x16x32_bf16 v[68:71], v[172:175], v[220:223], v[68:71]
	v_mfma_f32_16x16x32_bf16 v[64:67], v[182:185], v[220:223], v[64:67]
	s_setprio 0
	s_barrier
; #define PG8_STAGE(bufoff, gbase, voff) do { _Pragma("unroll") for (int _i = 0; _i < 2; ++_i) \
;         __builtin_amdgcn_global_load_lds((const unsigned*)((const char*)(gbase) + (voff)[_i]), (PG8_LAS unsigned*)(lds + (bufoff) + ldsw + _i * 8192), 16, 0, 0); } while (0)
; #define PG8_LDA(dst, b, h) do { _Pragma("unroll") for (int m = 0; m < 4; ++m) _Pragma("unroll") for (int k = 0; k < 2; ++k) dst[m][k] = *(const PG8_LAS bf16x8*)(lds + PG8_SA(b, h) + aoff + m * 2048 + k * 1024); } while (0)
; #define PG8_WAIT_V(n) asm volatile("s_waitcnt vmcnt(" #n ")" ::: "memory")
; template <class Epi, class Sched, bool ALIGN_EPI = false, bool SP2 = false>
; __device__ __forceinline__ void gemm_phase(PG8_LAS unsigned char* lds, const Gemm g, const Sched& S, const Epi& E) {
;     ...
;             PG8_LDA(At, 1, 1); PG8_STAGE(PG8_SB(1, 0), b3, voffB); PG8_STAGE(PG8_SB(1, 1), b3 + hstep, voffB); PG8_STAGE(PG8_SA(1, 0), a3, voffA);
;             PG8_WAIT_V(8); PG8_WAIT_L(0); PG8_BAR; PG8_MMA(1, 0, At, B0); PG8_MMA(1, 1, At, B1); PG8_BAR; PG8_SCHED;
;             } else {
;             PG8_LDB(B0, 0, 0); PG8_SCHED; PG8_LDA(At, 0, 0); PG8_STAGE(PG8_SA(1, 1), a1 + hstep, voffA);
;             PG8_WAIT_L(8); PG8_BAR; PG8_WAIT_L(0); PG8_MMA(0, 0, At, B0); PG8_BAR; PG8_SCHED;
;             PG8_LDB(B1, 0, 1); PG8_STAGE(PG8_SB(0, 0), b2, voffB);
;             PG8_BAR; PG8_WAIT_L(0); PG8_MMA(0, 1, At, B1); PG8_BAR;
;             PG8_LDA(At, 0, 1); PG8_STAGE(PG8_SA(0, 0), a2, voffA);
;             PG8_BAR; PG8_WAIT_L(0); PG8_MMA(1, 0, At, B0); PG8_BAR; PG8_SCHED;
;             PG8_STAGE(PG8_SB(0, 1), b2 + hstep, voffB);
;             PG8_WAIT_V(6); PG8_BAR; PG8_MMA(1, 1, At, B1); PG8_BAR;
;             PG8_LDB(B0, 1, 0); PG8_SCHED; PG8_LDA(At, 1, 0); PG8_STAGE(PG8_SA(0, 1), a2 + hstep, voffA);
;             PG8_WAIT_L(8); PG8_BAR; PG8_WAIT_L(0); PG8_MMA(0, 0, At, B0); PG8_BAR; PG8_SCHED;
;             PG8_LDB(B1, 1, 1); PG8_STAGE(PG8_SB(1, 0), b3, voffB);
;             PG8_BAR; PG8_WAIT_L(0); PG8_MMA(0, 1, At, B1); PG8_BAR;
;             PG8_LDA(At, 1, 1); PG8_STAGE(PG8_SA(1, 0), a3, voffA);
;             PG8_BAR; PG8_WAIT_L(0); PG8_MMA(1, 0, At, B0); PG8_BAR; PG8_SCHED;
;             PG8_STAGE(PG8_SB(1, 1), b3 + hstep, voffB);
;             PG8_WAIT_V(6); PG8_BAR; PG8_MMA(1, 1, At, B1); PG8_BAR;
;             }
;         }
;         if constexpr (ALIGN_EPI) { if (wr == 0) PG8_BAR; }
	s_add_i32 s3, s3, s14
	v_lshl_add_u64 v[202:203], v[202:203], 0, s[38:39]
	s_mov_b32 m0, s3
	ds_read_b128 v[186:189], v153 offset:49152
	ds_read_b128 v[190:193], v153 offset:50176
	ds_read_b128 v[194:197], v153 offset:51200
	ds_read_b128 v[198:201], v153 offset:52224
	ds_read_b128 v[208:211], v153 offset:53248
	ds_read_b128 v[212:215], v153 offset:54272
	ds_read_b128 v[216:219], v153 offset:55296
	ds_read_b128 v[220:223], v153 offset:56320
	global_load_lds_dwordx4 v[202:203], off
	s_add_i32 m0, s3, 0x2000
	s_add_u32 s60, s60, 0x20080
	v_lshl_add_u64 v[202:203], v[224:225], 0, s[38:39]
	s_addc_u32 s61, s61, 0
	s_add_i32 s3, s33, s14
	global_load_lds_dwordx4 v[202:203], off
	v_lshl_add_u64 v[202:203], s[60:61], 0, v[130:131]
	s_mov_b32 m0, s3
	s_nop 0
	global_load_lds_dwordx4 v[202:203], off
	v_lshl_add_u64 v[202:203], s[60:61], 0, v[134:135]
	s_add_i32 m0, s3, 0x2000
	s_nop 0
	global_load_lds_dwordx4 v[202:203], off
	s_waitcnt vmcnt(6)
	s_waitcnt lgkmcnt(0)
	s_barrier
	s_setprio 1
	s_waitcnt lgkmcnt(0)
	v_mfma_f32_16x16x32_bf16 v[60:63], v[144:147], v[186:189], v[60:63]
	v_mfma_f32_16x16x32_bf16 v[56:59], v[160:163], v[186:189], v[56:59]
	v_mfma_f32_16x16x32_bf16 v[44:47], v[144:147], v[194:197], v[44:47]
	v_mfma_f32_16x16x32_bf16 v[40:43], v[160:163], v[194:197], v[40:43]
	v_mfma_f32_16x16x32_bf16 v[28:31], v[144:147], v[208:211], v[28:31]
	v_mfma_f32_16x16x32_bf16 v[24:27], v[160:163], v[208:211], v[24:27]
	v_mfma_f32_16x16x32_bf16 v[12:15], v[144:147], v[216:219], v[12:15]
	v_mfma_f32_16x16x32_bf16 v[8:11], v[160:163], v[216:219], v[8:11]
	v_mfma_f32_16x16x32_bf16 v[60:63], v[156:159], v[190:193], v[60:63]
	v_mfma_f32_16x16x32_bf16 v[56:59], v[164:167], v[190:193], v[56:59]
	v_mfma_f32_16x16x32_bf16 v[44:47], v[156:159], v[198:201], v[44:47]
	v_mfma_f32_16x16x32_bf16 v[40:43], v[164:167], v[198:201], v[40:43]
	v_mfma_f32_16x16x32_bf16 v[28:31], v[156:159], v[212:215], v[28:31]
	v_mfma_f32_16x16x32_bf16 v[24:27], v[164:167], v[212:215], v[24:27]
	v_lshl_add_u64 v[202:203], v[226:227], 0, s[38:39]
	s_mov_b32 m0, s66
	s_nop 0
	global_load_lds_dwordx4 v[202:203], off
	v_mfma_f32_16x16x32_bf16 v[12:15], v[156:159], v[220:223], v[12:15]
	v_mfma_f32_16x16x32_bf16 v[8:11], v[164:167], v[220:223], v[8:11]
	s_setprio 0
	s_setprio 1
	v_mfma_f32_16x16x32_bf16 v[52:55], v[168:171], v[186:189], v[52:55]
	v_mfma_f32_16x16x32_bf16 v[48:51], v[176:179], v[186:189], v[48:51]
	v_mfma_f32_16x16x32_bf16 v[36:39], v[168:171], v[194:197], v[36:39]
	v_mfma_f32_16x16x32_bf16 v[32:35], v[176:179], v[194:197], v[32:35]
	v_mfma_f32_16x16x32_bf16 v[20:23], v[168:171], v[208:211], v[20:23]
	v_mfma_f32_16x16x32_bf16 v[16:19], v[176:179], v[208:211], v[16:19]
	v_mfma_f32_16x16x32_bf16 v[4:7], v[168:171], v[216:219], v[4:7]
	v_mfma_f32_16x16x32_bf16 v[0:3], v[176:179], v[216:219], v[0:3]
	v_mfma_f32_16x16x32_bf16 v[52:55], v[172:175], v[190:193], v[52:55]
	v_mfma_f32_16x16x32_bf16 v[48:51], v[182:185], v[190:193], v[48:51]
	v_mfma_f32_16x16x32_bf16 v[36:39], v[172:175], v[198:201], v[36:39]
	v_mfma_f32_16x16x32_bf16 v[32:35], v[182:185], v[198:201], v[32:35]
	v_mfma_f32_16x16x32_bf16 v[20:23], v[172:175], v[212:215], v[20:23]
	v_mfma_f32_16x16x32_bf16 v[16:19], v[182:185], v[212:215], v[16:19]
	v_lshl_add_u64 v[202:203], v[228:229], 0, s[38:39]
	s_mov_b32 m0, s67
	s_nop 0
	global_load_lds_dwordx4 v[202:203], off
	v_mfma_f32_16x16x32_bf16 v[4:7], v[172:175], v[220:223], v[4:7]
	v_mfma_f32_16x16x32_bf16 v[0:3], v[182:185], v[220:223], v[0:3]
	s_setprio 0
	s_barrier
	s_add_i32 s87, s87, 2
	s_add_u32 s58, s58, 0x100
	s_addc_u32 s59, s59, 0
	s_add_u32 s85, s85, 0x100
	s_addc_u32 s86, s86, 0
	s_cmp_gt_u32 s87, 5
	s_cbranch_scc0 .LBB0_873
	s_and_b64 vcc, exec, s[42:43]
	s_cbranch_vccz .LBB0_876
	s_barrier

; #define PG8_STAGE(bufoff, gbase, voff) do { _Pragma("unroll") for (int _i = 0; _i < 2; ++_i) \
;         __builtin_amdgcn_global_load_lds((const unsigned*)((const char*)(gbase) + (voff)[_i]), (PG8_LAS unsigned*)(lds + (bufoff) + ldsw + _i * 8192), 16, 0, 0); } while (0)
; #define PG8_LDA(dst, b, h) do { _Pragma("unroll") for (int m = 0; m < 4; ++m) _Pragma("unroll") for (int k = 0; k < 2; ++k) dst[m][k] = *(const PG8_LAS bf16x8*)(lds + PG8_SA(b, h) + aoff + m * 2048 + k * 1024); } while (0)
; #define PG8_LDB(dst, b, h) do { _Pragma("unroll") for (int n = 0; n < 2; ++n) _Pragma("unroll") for (int k = 0; k < 2; ++k) dst[n][k] = *(const PG8_LAS bf16x8*)(lds + PG8_SB(b, h) + boff + n * 2048 + k * 1024); } while (0)
; #define PG8_WAIT_V(n) asm volatile("s_waitcnt vmcnt(" #n ")" ::: "memory")
; #define PG8_WAIT_L(n) asm volatile("s_waitcnt lgkmcnt(" #n ")" ::: "memory")
; #define PG8_BAR __builtin_amdgcn_s_barrier()
; #define PG8_SCHED __builtin_amdgcn_sched_barrier(0)
; template <class Epi, class Sched, bool ALIGN_EPI = false, bool SP2 = false>
; __device__ __forceinline__ void gemm_phase(PG8_LAS unsigned char* lds, const Gemm g, const Sched& S, const Epi& E) {
;     ...
;         const bool has_next = S.next(ui + 1, nxt);
;         const char* nA = has_next ? (const char*)g.A + (size_t)nxt.pm * tstep : cA; const char* nB = has_next ? (const char*)g.Bt + (size_t)nxt.pn * tstep : cB;
;         for (int t = 0; t < nt; t += 2) {
;             const bool last = (t == nt - 2);
;             const char* a1 = cA + (size_t)(t + 1) * kstep;
;             const char* a2 = last ? nA : cA + (size_t)(t + 2) * kstep; const char* b2 = last ? nB : cB + (size_t)(t + 2) * kstep;
;             const char* a3 = a2 + kstep; const char* b3 = b2 + kstep;
;             if (last && has_next) S.a_ready(nxt);
;             if constexpr (SP2) {
;             PG8_LDB(B0, 0, 0); PG8_LDB(B1, 0, 1); PG8_SCHED; PG8_LDA(At, 0, 0); PG8_STAGE(PG8_SA(1, 1), a1 + hstep, voffA);
;             PG8_WAIT_V(8); PG8_WAIT_L(0); PG8_BAR; PG8_MMA(0, 0, At, B0); PG8_MMA(0, 1, At, B1); PG8_BAR; PG8_SCHED;
;             PG8_LDA(At, 0, 1); PG8_STAGE(PG8_SB(0, 0), b2, voffB); PG8_STAGE(PG8_SB(0, 1), b2 + hstep, voffB); PG8_STAGE(PG8_SA(0, 0), a2, voffA);
;             PG8_WAIT_V(8); PG8_WAIT_L(0); PG8_BAR; PG8_MMA(1, 0, At, B0); PG8_MMA(1, 1, At, B1); PG8_BAR; PG8_SCHED;
.LBB0_956:
	s_ashr_i32 s45, s44, 31
	s_lshl_b64 s[48:49], s[44:45], 19
	s_add_u32 s48, s22, s48
	s_addc_u32 s49, s23, s49
	s_and_b64 s[50:51], s[10:11], exec
	s_cselect_b32 s45, s49, s55
	s_cselect_b32 s75, s48, s54
	s_ashr_i32 s43, s42, 31
	s_lshl_b64 s[50:51], s[42:43], 19
	v_readlane_b32 s3, v250, 18
	s_add_u32 s50, s3, s50
	v_readlane_b32 s3, v250, 19
	s_addc_u32 s51, s3, s51
	s_and_b64 s[58:59], s[10:11], exec
	s_cselect_b32 s43, s51, s57
	s_cselect_b32 s76, s50, s56
	s_add_u32 s54, s54, 0x40080
	s_addc_u32 s55, s55, 0
	s_add_u32 s77, s56, 0x100
	s_addc_u32 s82, s57, 0
	s_mov_b32 s83, -2
	ds_read_b128 v[144:147], v155
	ds_read_b128 v[148:151], v155 offset:1024
	ds_read_b128 v[160:163], v155 offset:2048
	ds_read_b128 v[164:167], v155 offset:3072
	ds_read_b128 v[168:171], v156
	ds_read_b128 v[172:175], v156 offset:1024
	ds_read_b128 v[176:179], v156 offset:2048
	ds_read_b128 v[182:185], v156 offset:3072
	s_add_u32 s3, s54, 0xfffc0080
	s_addc_u32 s33, s55, -1
	s_cmp_eq_u32 s83, 12
	s_cselect_b32 s59, s45, s33
	s_cselect_b32 s58, s75, s3
	s_cselect_b32 s57, s43, s82
	s_cselect_b32 s56, s76, s77
	v_lshl_add_u64 v[202:203], s[54:55], 0, v[136:137]
	s_add_i32 m0, s34, 0xc000
	ds_read_b128 v[186:189], v157
	ds_read_b128 v[190:193], v157 offset:1024
	ds_read_b128 v[194:197], v157 offset:2048
	ds_read_b128 v[198:201], v157 offset:3072
	ds_read_b128 v[208:211], v157 offset:4096
	ds_read_b128 v[212:215], v157 offset:5120
	ds_read_b128 v[216:219], v157 offset:6144
	ds_read_b128 v[220:223], v157 offset:7168
	global_load_lds_dwordx4 v[202:203], off
	v_lshl_add_u64 v[202:203], s[54:55], 0, v[138:139]
	s_add_i32 m0, s34, 0xe000
	s_nop 0
	global_load_lds_dwordx4 v[202:203], off
	s_waitcnt vmcnt(8)
	s_waitcnt lgkmcnt(0)
	s_barrier
	s_setprio 1
	s_waitcnt lgkmcnt(0)
	v_mfma_f32_16x16x32_bf16 v[124:127], v[144:147], v[186:189], 0
	v_mfma_f32_16x16x32_bf16 v[120:123], v[160:163], v[186:189], 0
	v_mfma_f32_16x16x32_bf16 v[108:111], v[144:147], v[194:197], 0
	v_mfma_f32_16x16x32_bf16 v[104:107], v[160:163], v[194:197], 0
	v_mfma_f32_16x16x32_bf16 v[92:95], v[144:147], v[208:211], 0
	v_mfma_f32_16x16x32_bf16 v[88:91], v[160:163], v[208:211], 0
	v_mfma_f32_16x16x32_bf16 v[76:79], v[144:147], v[216:219], 0
	v_mfma_f32_16x16x32_bf16 v[72:75], v[160:163], v[216:219], 0
	v_mfma_f32_16x16x32_bf16 v[124:127], v[148:151], v[190:193], v[124:127]
	v_mfma_f32_16x16x32_bf16 v[120:123], v[164:167], v[190:193], v[120:123]
	v_mfma_f32_16x16x32_bf16 v[108:111], v[148:151], v[198:201], v[108:111]
	v_mfma_f32_16x16x32_bf16 v[104:107], v[164:167], v[198:201], v[104:107]
	v_mfma_f32_16x16x32_bf16 v[92:95], v[148:151], v[212:215], v[92:95]
	v_mfma_f32_16x16x32_bf16 v[88:91], v[164:167], v[212:215], v[88:91]
	v_mfma_f32_16x16x32_bf16 v[76:79], v[148:151], v[220:223], v[76:79]
	v_mfma_f32_16x16x32_bf16 v[72:75], v[164:167], v[220:223], v[72:75]
	s_setprio 0
	s_setprio 1
	v_mfma_f32_16x16x32_bf16 v[116:119], v[168:171], v[186:189], 0
	v_mfma_f32_16x16x32_bf16 v[112:115], v[176:179], v[186:189], 0
	v_mfma_f32_16x16x32_bf16 v[100:103], v[168:171], v[194:197], 0
	v_mfma_f32_16x16x32_bf16 v[96:99], v[176:179], v[194:197], 0
	v_mfma_f32_16x16x32_bf16 v[84:87], v[168:171], v[208:211], 0
	v_mfma_f32_16x16x32_bf16 v[80:83], v[176:179], v[208:211], 0
	v_mfma_f32_16x16x32_bf16 v[68:71], v[168:171], v[216:219], 0
	v_mfma_f32_16x16x32_bf16 v[64:67], v[176:179], v[216:219], 0
	v_mfma_f32_16x16x32_bf16 v[116:119], v[172:175], v[190:193], v[116:119]
	v_mfma_f32_16x16x32_bf16 v[112:115], v[182:185], v[190:193], v[112:115]
	v_mfma_f32_16x16x32_bf16 v[100:103], v[172:175], v[198:201], v[100:103]
	v_mfma_f32_16x16x32_bf16 v[96:99], v[182:185], v[198:201], v[96:99]
	v_mfma_f32_16x16x32_bf16 v[84:87], v[172:175], v[212:215], v[84:87]
	v_mfma_f32_16x16x32_bf16 v[80:83], v[182:185], v[212:215], v[80:83]
	v_mfma_f32_16x16x32_bf16 v[68:71], v[172:175], v[220:223], v[68:71]
	v_mfma_f32_16x16x32_bf16 v[64:67], v[182:185], v[220:223], v[64:67]
	s_setprio 0
	s_barrier
	s_add_i32 s3, s65, s14
	v_lshl_add_u64 v[202:203], s[56:57], 0, v[132:133]
	s_mov_b32 m0, s3
	ds_read_b128 v[186:189], v157 offset:16384
	ds_read_b128 v[190:193], v157 offset:17408
	ds_read_b128 v[194:197], v157 offset:18432
	ds_read_b128 v[198:201], v157 offset:19456
	ds_read_b128 v[208:211], v157 offset:20480
	ds_read_b128 v[212:215], v157 offset:21504
	ds_read_b128 v[216:219], v157 offset:22528
	ds_read_b128 v[220:223], v157 offset:23552
	global_load_lds_dwordx4 v[202:203], off
	s_add_i32 m0, s3, 0x2000
	s_add_u32 s78, s56, 0x40000
	v_lshl_add_u64 v[224:225], s[56:57], 0, v[128:129]
	s_addc_u32 s79, s57, 0
	s_add_i32 s3, s66, s14
	global_load_lds_dwordx4 v[224:225], off
	v_lshl_add_u64 v[226:227], s[78:79], 0, v[132:133]
	s_mov_b32 m0, s3
	global_load_lds_dwordx4 v[226:227], off
	v_lshl_add_u64 v[226:227], s[78:79], 0, v[128:129]
	s_add_i32 m0, s3, 0x2000
	s_nop 0
	global_load_lds_dwordx4 v[226:227], off
	s_waitcnt vmcnt(6)
	s_waitcnt lgkmcnt(0)
	s_barrier
; #define PG8_STAGE(bufoff, gbase, voff) do { _Pragma("unroll") for (int _i = 0; _i < 2; ++_i) \
;         __builtin_amdgcn_global_load_lds((const unsigned*)((const char*)(gbase) + (voff)[_i]), (PG8_LAS unsigned*)(lds + (bufoff) + ldsw + _i * 8192), 16, 0, 0); } while (0)
; #define PG8_LDA(dst, b, h) do { _Pragma("unroll") for (int m = 0; m < 4; ++m) _Pragma("unroll") for (int k = 0; k < 2; ++k) dst[m][k] = *(const PG8_LAS bf16x8*)(lds + PG8_SA(b, h) + aoff + m * 2048 + k * 1024); } while (0)
; #define PG8_LDB(dst, b, h) do { _Pragma("unroll") for (int n = 0; n < 2; ++n) _Pragma("unroll") for (int k = 0; k < 2; ++k) dst[n][k] = *(const PG8_LAS bf16x8*)(lds + PG8_SB(b, h) + boff + n * 2048 + k * 1024); } while (0)
; #define PG8_MMA(ai, bj, At, Bt) do { __builtin_amdgcn_s_setprio(1); _Pragma("unroll") for (int m = 0; m < 4; ++m) _Pragma("unroll") for (int n = 0; n < 2; ++n) _Pragma("unroll") for (int k = 0; k < 2; ++k) \
;         acc[ai][bj][m][n] = __builtin_amdgcn_mfma_f32_16x16x32_bf16(Bt[n][k], At[m][k], acc[ai][bj][m][n], 0, 0, 0); __builtin_amdgcn_s_setprio(0); } while (0)
; #define PG8_WAIT_V(n) asm volatile("s_waitcnt vmcnt(" #n ")" ::: "memory")
; #define PG8_WAIT_L(n) asm volatile("s_waitcnt lgkmcnt(" #n ")" ::: "memory")
; #define PG8_BAR __builtin_amdgcn_s_barrier()
; #define PG8_SCHED __builtin_amdgcn_sched_barrier(0)
; template <class Epi, class Sched, bool ALIGN_EPI = false, bool SP2 = false>
; __device__ __forceinline__ void gemm_phase(PG8_LAS unsigned char* lds, const Gemm g, const Sched& S, const Epi& E) {
;     ...
;             PG8_LDA(At, 0, 1); PG8_STAGE(PG8_SB(0, 0), b2, voffB); PG8_STAGE(PG8_SB(0, 1), b2 + hstep, voffB); PG8_STAGE(PG8_SA(0, 0), a2, voffA);
;             PG8_WAIT_V(8); PG8_WAIT_L(0); PG8_BAR; PG8_MMA(1, 0, At, B0); PG8_MMA(1, 1, At, B1); PG8_BAR; PG8_SCHED;
;             PG8_LDB(B0, 1, 0); PG8_LDB(B1, 1, 1); PG8_SCHED; PG8_LDA(At, 1, 0); PG8_STAGE(PG8_SA(0, 1), a2 + hstep, voffA);
;             PG8_WAIT_V(8); PG8_WAIT_L(0); PG8_BAR; PG8_MMA(0, 0, At, B0); PG8_MMA(0, 1, At, B1); PG8_BAR; PG8_SCHED;
	s_setprio 1
	s_waitcnt lgkmcnt(0)
	v_mfma_f32_16x16x32_bf16 v[60:63], v[144:147], v[186:189], 0
	v_mfma_f32_16x16x32_bf16 v[56:59], v[160:163], v[186:189], 0
	v_mfma_f32_16x16x32_bf16 v[44:47], v[144:147], v[194:197], 0
	v_mfma_f32_16x16x32_bf16 v[40:43], v[160:163], v[194:197], 0
	v_mfma_f32_16x16x32_bf16 v[28:31], v[144:147], v[208:211], 0
	v_mfma_f32_16x16x32_bf16 v[24:27], v[160:163], v[208:211], 0
	v_mfma_f32_16x16x32_bf16 v[12:15], v[144:147], v[216:219], 0
	v_mfma_f32_16x16x32_bf16 v[8:11], v[160:163], v[216:219], 0
	v_mfma_f32_16x16x32_bf16 v[60:63], v[148:151], v[190:193], v[60:63]
	v_mfma_f32_16x16x32_bf16 v[56:59], v[164:167], v[190:193], v[56:59]
	v_mfma_f32_16x16x32_bf16 v[44:47], v[148:151], v[198:201], v[44:47]
	v_mfma_f32_16x16x32_bf16 v[40:43], v[164:167], v[198:201], v[40:43]
	v_mfma_f32_16x16x32_bf16 v[28:31], v[148:151], v[212:215], v[28:31]
	v_mfma_f32_16x16x32_bf16 v[24:27], v[164:167], v[212:215], v[24:27]
	v_lshl_add_u64 v[226:227], s[58:59], 0, v[134:135]
	s_mov_b32 m0, s34
	s_nop 0
	global_load_lds_dwordx4 v[226:227], off
	v_mfma_f32_16x16x32_bf16 v[12:15], v[148:151], v[220:223], v[12:15]
	v_mfma_f32_16x16x32_bf16 v[8:11], v[164:167], v[220:223], v[8:11]
	s_setprio 0
	s_setprio 1
	v_mfma_f32_16x16x32_bf16 v[52:55], v[168:171], v[186:189], 0
	v_mfma_f32_16x16x32_bf16 v[48:51], v[176:179], v[186:189], 0
	v_mfma_f32_16x16x32_bf16 v[36:39], v[168:171], v[194:197], 0
	v_mfma_f32_16x16x32_bf16 v[32:35], v[176:179], v[194:197], 0
	v_mfma_f32_16x16x32_bf16 v[20:23], v[168:171], v[208:211], 0
	v_mfma_f32_16x16x32_bf16 v[16:19], v[176:179], v[208:211], 0
	v_mfma_f32_16x16x32_bf16 v[4:7], v[168:171], v[216:219], 0
	v_mfma_f32_16x16x32_bf16 v[0:3], v[176:179], v[216:219], 0
	v_mfma_f32_16x16x32_bf16 v[52:55], v[172:175], v[190:193], v[52:55]
	v_mfma_f32_16x16x32_bf16 v[48:51], v[182:185], v[190:193], v[48:51]
	v_mfma_f32_16x16x32_bf16 v[36:39], v[172:175], v[198:201], v[36:39]
	v_mfma_f32_16x16x32_bf16 v[32:35], v[182:185], v[198:201], v[32:35]
	v_mfma_f32_16x16x32_bf16 v[20:23], v[172:175], v[212:215], v[20:23]
	v_mfma_f32_16x16x32_bf16 v[16:19], v[182:185], v[212:215], v[16:19]
	v_lshl_add_u64 v[228:229], s[58:59], 0, v[130:131]
	s_mov_b32 m0, s53
	s_nop 0
	global_load_lds_dwordx4 v[228:229], off
	v_mfma_f32_16x16x32_bf16 v[4:7], v[172:175], v[220:223], v[4:7]
	v_mfma_f32_16x16x32_bf16 v[0:3], v[182:185], v[220:223], v[0:3]
	s_setprio 0
	s_barrier
	s_add_i32 s3, 0, 0x18000
	v_add_u32_e32 v159, s3, v153
	s_add_i32 s33, 0, 0x1c000
	ds_read_b128 v[144:147], v159
	ds_read_b128 v[148:151], v159 offset:1024
	ds_read_b128 v[160:163], v159 offset:2048
	ds_read_b128 v[164:167], v159 offset:3072
	v_add_u32_e32 v159, s33, v153
	ds_read_b128 v[168:171], v159
	ds_read_b128 v[172:175], v159 offset:1024
	ds_read_b128 v[176:179], v159 offset:2048
	ds_read_b128 v[182:185], v159 offset:3072
	s_add_u32 s58, s58, 0x40000
	s_addc_u32 s59, s59, 0
	s_mov_b32 m0, s60
	v_lshl_add_u64 v[230:231], s[58:59], 0, v[134:135]
	ds_read_b128 v[186:189], v157 offset:32768
	ds_read_b128 v[190:193], v157 offset:33792
	ds_read_b128 v[194:197], v157 offset:34816
	ds_read_b128 v[198:201], v157 offset:35840
	ds_read_b128 v[208:211], v157 offset:36864
	ds_read_b128 v[212:215], v157 offset:37888
	ds_read_b128 v[216:219], v157 offset:38912
	ds_read_b128 v[220:223], v157 offset:39936
	global_load_lds_dwordx4 v[230:231], off
	v_lshl_add_u64 v[230:231], s[58:59], 0, v[130:131]
	s_mov_b32 m0, s61
	s_nop 0
	global_load_lds_dwordx4 v[230:231], off
	s_waitcnt vmcnt(8)
	s_waitcnt lgkmcnt(0)
	s_barrier
	s_setprio 1
	s_waitcnt lgkmcnt(0)
	v_mfma_f32_16x16x32_bf16 v[124:127], v[144:147], v[186:189], v[124:127]
	v_mfma_f32_16x16x32_bf16 v[120:123], v[160:163], v[186:189], v[120:123]
	v_mfma_f32_16x16x32_bf16 v[108:111], v[144:147], v[194:197], v[108:111]
	v_mfma_f32_16x16x32_bf16 v[104:107], v[160:163], v[194:197], v[104:107]
	v_mfma_f32_16x16x32_bf16 v[92:95], v[144:147], v[208:211], v[92:95]
	v_mfma_f32_16x16x32_bf16 v[88:91], v[160:163], v[208:211], v[88:91]
	v_mfma_f32_16x16x32_bf16 v[76:79], v[144:147], v[216:219], v[76:79]
	v_mfma_f32_16x16x32_bf16 v[72:75], v[160:163], v[216:219], v[72:75]
	v_mfma_f32_16x16x32_bf16 v[124:127], v[148:151], v[190:193], v[124:127]
	v_mfma_f32_16x16x32_bf16 v[120:123], v[164:167], v[190:193], v[120:123]
	v_mfma_f32_16x16x32_bf16 v[108:111], v[148:151], v[198:201], v[108:111]
	v_mfma_f32_16x16x32_bf16 v[104:107], v[164:167], v[198:201], v[104:107]
	v_mfma_f32_16x16x32_bf16 v[92:95], v[148:151], v[212:215], v[92:95]
	v_mfma_f32_16x16x32_bf16 v[88:91], v[164:167], v[212:215], v[88:91]
	v_mfma_f32_16x16x32_bf16 v[76:79], v[148:151], v[220:223], v[76:79]
	v_mfma_f32_16x16x32_bf16 v[72:75], v[164:167], v[220:223], v[72:75]
	s_setprio 0
	s_setprio 1
	v_mfma_f32_16x16x32_bf16 v[116:119], v[168:171], v[186:189], v[116:119]
	v_mfma_f32_16x16x32_bf16 v[112:115], v[176:179], v[186:189], v[112:115]
	v_mfma_f32_16x16x32_bf16 v[100:103], v[168:171], v[194:197], v[100:103]
	v_mfma_f32_16x16x32_bf16 v[96:99], v[176:179], v[194:197], v[96:99]
	v_mfma_f32_16x16x32_bf16 v[84:87], v[168:171], v[208:211], v[84:87]
	v_mfma_f32_16x16x32_bf16 v[80:83], v[176:179], v[208:211], v[80:83]
	v_mfma_f32_16x16x32_bf16 v[68:71], v[168:171], v[216:219], v[68:71]
	v_mfma_f32_16x16x32_bf16 v[64:67], v[176:179], v[216:219], v[64:67]
	v_mfma_f32_16x16x32_bf16 v[116:119], v[172:175], v[190:193], v[116:119]
	v_mfma_f32_16x16x32_bf16 v[112:115], v[182:185], v[190:193], v[112:115]
	v_mfma_f32_16x16x32_bf16 v[100:103], v[172:175], v[198:201], v[100:103]
	v_mfma_f32_16x16x32_bf16 v[96:99], v[182:185], v[198:201], v[96:99]
	v_mfma_f32_16x16x32_bf16 v[84:87], v[172:175], v[212:215], v[84:87]
	v_mfma_f32_16x16x32_bf16 v[80:83], v[182:185], v[212:215], v[80:83]
	v_mfma_f32_16x16x32_bf16 v[68:71], v[172:175], v[220:223], v[68:71]
	v_mfma_f32_16x16x32_bf16 v[64:67], v[182:185], v[220:223], v[64:67]
	s_setprio 0
	s_barrier
; #define PG8_STAGE(bufoff, gbase, voff) do { _Pragma("unroll") for (int _i = 0; _i < 2; ++_i) \
;         __builtin_amdgcn_global_load_lds((const unsigned*)((const char*)(gbase) + (voff)[_i]), (PG8_LAS unsigned*)(lds + (bufoff) + ldsw + _i * 8192), 16, 0, 0); } while (0)
; #define PG8_LDA(dst, b, h) do { _Pragma("unroll") for (int m = 0; m < 4; ++m) _Pragma("unroll") for (int k = 0; k < 2; ++k) dst[m][k] = *(const PG8_LAS bf16x8*)(lds + PG8_SA(b, h) + aoff + m * 2048 + k * 1024); } while (0)
; #define PG8_LDB(dst, b, h) do { _Pragma("unroll") for (int n = 0; n < 2; ++n) _Pragma("unroll") for (int k = 0; k < 2; ++k) dst[n][k] = *(const PG8_LAS bf16x8*)(lds + PG8_SB(b, h) + boff + n * 2048 + k * 1024); } while (0)
; #define PG8_MMA(ai, bj, At, Bt) do { __builtin_amdgcn_s_setprio(1); _Pragma("unroll") for (int m = 0; m < 4; ++m) _Pragma("unroll") for (int n = 0; n < 2; ++n) _Pragma("unroll") for (int k = 0; k < 2; ++k) \
;         acc[ai][bj][m][n] = __builtin_amdgcn_mfma_f32_16x16x32_bf16(Bt[n][k], At[m][k], acc[ai][bj][m][n], 0, 0, 0); __builtin_amdgcn_s_setprio(0); } while (0)
; #define PG8_WAIT_V(n) asm volatile("s_waitcnt vmcnt(" #n ")" ::: "memory")
; template <class Epi, class Sched, bool ALIGN_EPI = false, bool SP2 = false>
; __device__ __forceinline__ void gemm_phase(PG8_LAS unsigned char* lds, const Gemm g, const Sched& S, const Epi& E) {
;     ...
;             PG8_LDB(B0, 0, 0); PG8_LDB(B1, 0, 1); PG8_SCHED; PG8_LDA(At, 0, 0); PG8_STAGE(PG8_SA(1, 1), a1 + hstep, voffA);
;             PG8_WAIT_V(8); PG8_WAIT_L(0); PG8_BAR; PG8_MMA(0, 0, At, B0); PG8_MMA(0, 1, At, B1); PG8_BAR; PG8_SCHED;
;             PG8_LDA(At, 0, 1); PG8_STAGE(PG8_SB(0, 0), b2, voffB); PG8_STAGE(PG8_SB(0, 1), b2 + hstep, voffB); PG8_STAGE(PG8_SA(0, 0), a2, voffA);
;             PG8_WAIT_V(8); PG8_WAIT_L(0); PG8_BAR; PG8_MMA(1, 0, At, B0); PG8_MMA(1, 1, At, B1); PG8_BAR; PG8_SCHED;
;             PG8_LDB(B0, 1, 0); PG8_LDB(B1, 1, 1); PG8_SCHED; PG8_LDA(At, 1, 0); PG8_STAGE(PG8_SA(0, 1), a2 + hstep, voffA);
;             PG8_WAIT_V(8); PG8_WAIT_L(0); PG8_BAR; PG8_MMA(0, 0, At, B0); PG8_MMA(0, 1, At, B1); PG8_BAR; PG8_SCHED;
;             PG8_LDA(At, 1, 1); PG8_STAGE(PG8_SB(1, 0), b3, voffB); PG8_STAGE(PG8_SB(1, 1), b3 + hstep, voffB); PG8_STAGE(PG8_SA(1, 0), a3, voffA);
;             PG8_WAIT_V(8); PG8_WAIT_L(0); PG8_BAR; PG8_MMA(1, 0, At, B0); PG8_MMA(1, 1, At, B1); PG8_BAR; PG8_SCHED;
	s_add_i32 s3, s3, s14
	v_lshl_add_u64 v[202:203], v[202:203], 0, s[36:37]
	s_mov_b32 m0, s3
	ds_read_b128 v[186:189], v157 offset:49152
	ds_read_b128 v[190:193], v157 offset:50176
	ds_read_b128 v[194:197], v157 offset:51200
	ds_read_b128 v[198:201], v157 offset:52224
	ds_read_b128 v[208:211], v157 offset:53248
	ds_read_b128 v[212:215], v157 offset:54272
	ds_read_b128 v[216:219], v157 offset:55296
	ds_read_b128 v[220:223], v157 offset:56320
	global_load_lds_dwordx4 v[202:203], off
	s_add_i32 m0, s3, 0x2000
	s_add_u32 s56, s56, 0x40080
	v_lshl_add_u64 v[202:203], v[224:225], 0, s[36:37]
	s_addc_u32 s57, s57, 0
	s_add_i32 s3, s33, s14
	global_load_lds_dwordx4 v[202:203], off
	v_lshl_add_u64 v[202:203], s[56:57], 0, v[132:133]
	s_mov_b32 m0, s3
	s_nop 0
	global_load_lds_dwordx4 v[202:203], off
	v_lshl_add_u64 v[202:203], s[56:57], 0, v[128:129]
	s_add_i32 m0, s3, 0x2000
	s_nop 0
	global_load_lds_dwordx4 v[202:203], off
	s_waitcnt vmcnt(6)
	s_waitcnt lgkmcnt(0)
	s_barrier
	s_setprio 1
	s_waitcnt lgkmcnt(0)
	v_mfma_f32_16x16x32_bf16 v[60:63], v[144:147], v[186:189], v[60:63]
	v_mfma_f32_16x16x32_bf16 v[56:59], v[160:163], v[186:189], v[56:59]
	v_mfma_f32_16x16x32_bf16 v[44:47], v[144:147], v[194:197], v[44:47]
	v_mfma_f32_16x16x32_bf16 v[40:43], v[160:163], v[194:197], v[40:43]
	v_mfma_f32_16x16x32_bf16 v[28:31], v[144:147], v[208:211], v[28:31]
	v_mfma_f32_16x16x32_bf16 v[24:27], v[160:163], v[208:211], v[24:27]
	v_mfma_f32_16x16x32_bf16 v[12:15], v[144:147], v[216:219], v[12:15]
	v_mfma_f32_16x16x32_bf16 v[8:11], v[160:163], v[216:219], v[8:11]
	v_mfma_f32_16x16x32_bf16 v[60:63], v[148:151], v[190:193], v[60:63]
	v_mfma_f32_16x16x32_bf16 v[56:59], v[164:167], v[190:193], v[56:59]
	v_mfma_f32_16x16x32_bf16 v[44:47], v[148:151], v[198:201], v[44:47]
	v_mfma_f32_16x16x32_bf16 v[40:43], v[164:167], v[198:201], v[40:43]
	v_mfma_f32_16x16x32_bf16 v[28:31], v[148:151], v[212:215], v[28:31]
	v_mfma_f32_16x16x32_bf16 v[24:27], v[164:167], v[212:215], v[24:27]
	v_lshl_add_u64 v[202:203], v[226:227], 0, s[36:37]
	s_mov_b32 m0, s63
	s_nop 0
	global_load_lds_dwordx4 v[202:203], off
	v_mfma_f32_16x16x32_bf16 v[12:15], v[148:151], v[220:223], v[12:15]
	v_mfma_f32_16x16x32_bf16 v[8:11], v[164:167], v[220:223], v[8:11]
	s_setprio 0
	s_setprio 1
	v_mfma_f32_16x16x32_bf16 v[52:55], v[168:171], v[186:189], v[52:55]
	v_mfma_f32_16x16x32_bf16 v[48:51], v[176:179], v[186:189], v[48:51]
	v_mfma_f32_16x16x32_bf16 v[36:39], v[168:171], v[194:197], v[36:39]
	v_mfma_f32_16x16x32_bf16 v[32:35], v[176:179], v[194:197], v[32:35]
	v_mfma_f32_16x16x32_bf16 v[20:23], v[168:171], v[208:211], v[20:23]
	v_mfma_f32_16x16x32_bf16 v[16:19], v[176:179], v[208:211], v[16:19]
	v_mfma_f32_16x16x32_bf16 v[4:7], v[168:171], v[216:219], v[4:7]
	v_mfma_f32_16x16x32_bf16 v[0:3], v[176:179], v[216:219], v[0:3]
	v_mfma_f32_16x16x32_bf16 v[52:55], v[172:175], v[190:193], v[52:55]
	v_mfma_f32_16x16x32_bf16 v[48:51], v[182:185], v[190:193], v[48:51]
	v_mfma_f32_16x16x32_bf16 v[36:39], v[172:175], v[198:201], v[36:39]
	v_mfma_f32_16x16x32_bf16 v[32:35], v[182:185], v[198:201], v[32:35]
	v_mfma_f32_16x16x32_bf16 v[20:23], v[172:175], v[212:215], v[20:23]
	v_mfma_f32_16x16x32_bf16 v[16:19], v[182:185], v[212:215], v[16:19]
	v_lshl_add_u64 v[202:203], v[228:229], 0, s[36:37]
	s_mov_b32 m0, s64
	s_nop 0
	global_load_lds_dwordx4 v[202:203], off
	v_mfma_f32_16x16x32_bf16 v[4:7], v[172:175], v[220:223], v[4:7]
	v_mfma_f32_16x16x32_bf16 v[0:3], v[182:185], v[220:223], v[0:3]
	s_setprio 0
	s_barrier
	s_add_i32 s83, s83, 2
	s_add_u32 s54, s54, 0x100
	s_addc_u32 s55, s55, 0
	s_add_u32 s77, s77, 0x100
	s_addc_u32 s82, s82, 0
.LBB0_957:
	ds_read_b128 v[144:147], v155
	ds_read_b128 v[148:151], v155 offset:1024
	ds_read_b128 v[160:163], v155 offset:2048
	ds_read_b128 v[164:167], v155 offset:3072
	ds_read_b128 v[168:171], v156
	ds_read_b128 v[172:175], v156 offset:1024
	ds_read_b128 v[176:179], v156 offset:2048
	ds_read_b128 v[182:185], v156 offset:3072
	s_add_u32 s3, s54, 0xfffc0080
	s_addc_u32 s33, s55, -1
	s_cmp_eq_u32 s83, 12
	s_cselect_b32 s59, s45, s33
	s_cselect_b32 s58, s75, s3
	s_cselect_b32 s57, s43, s82
	s_cselect_b32 s56, s76, s77
	v_lshl_add_u64 v[202:203], s[54:55], 0, v[136:137]
	s_add_i32 m0, s34, 0xc000
	ds_read_b128 v[186:189], v157
	ds_read_b128 v[190:193], v157 offset:1024
	ds_read_b128 v[194:197], v157 offset:2048
	ds_read_b128 v[198:201], v157 offset:3072
	ds_read_b128 v[208:211], v157 offset:4096
	ds_read_b128 v[212:215], v157 offset:5120
	ds_read_b128 v[216:219], v157 offset:6144
	ds_read_b128 v[220:223], v157 offset:7168
	global_load_lds_dwordx4 v[202:203], off
	v_lshl_add_u64 v[202:203], s[54:55], 0, v[138:139]
	s_add_i32 m0, s34, 0xe000
	s_nop 0
	global_load_lds_dwordx4 v[202:203], off
	s_waitcnt vmcnt(8)
	s_waitcnt lgkmcnt(0)
	s_barrier
; #define PG8_STAGE(bufoff, gbase, voff) do { _Pragma("unroll") for (int _i = 0; _i < 2; ++_i) \
;         __builtin_amdgcn_global_load_lds((const unsigned*)((const char*)(gbase) + (voff)[_i]), (PG8_LAS unsigned*)(lds + (bufoff) + ldsw + _i * 8192), 16, 0, 0); } while (0)
; #define PG8_LDA(dst, b, h) do { _Pragma("unroll") for (int m = 0; m < 4; ++m) _Pragma("unroll") for (int k = 0; k < 2; ++k) dst[m][k] = *(const PG8_LAS bf16x8*)(lds + PG8_SA(b, h) + aoff + m * 2048 + k * 1024); } while (0)
; #define PG8_LDB(dst, b, h) do { _Pragma("unroll") for (int n = 0; n < 2; ++n) _Pragma("unroll") for (int k = 0; k < 2; ++k) dst[n][k] = *(const PG8_LAS bf16x8*)(lds + PG8_SB(b, h) + boff + n * 2048 + k * 1024); } while (0)
; #define PG8_MMA(ai, bj, At, Bt) do { __builtin_amdgcn_s_setprio(1); _Pragma("unroll") for (int m = 0; m < 4; ++m) _Pragma("unroll") for (int n = 0; n < 2; ++n) _Pragma("unroll") for (int k = 0; k < 2; ++k) \
;         acc[ai][bj][m][n] = __builtin_amdgcn_mfma_f32_16x16x32_bf16(Bt[n][k], At[m][k], acc[ai][bj][m][n], 0, 0, 0); __builtin_amdgcn_s_setprio(0); } while (0)
; #define PG8_WAIT_V(n) asm volatile("s_waitcnt vmcnt(" #n ")" ::: "memory")
; #define PG8_WAIT_L(n) asm volatile("s_waitcnt lgkmcnt(" #n ")" ::: "memory")
; #define PG8_BAR __builtin_amdgcn_s_barrier()
; #define PG8_SCHED __builtin_amdgcn_sched_barrier(0)
; template <class Epi, class Sched, bool ALIGN_EPI = false, bool SP2 = false>
; __device__ __forceinline__ void gemm_phase(PG8_LAS unsigned char* lds, const Gemm g, const Sched& S, const Epi& E) {
;     ...
;             PG8_LDB(B0, 0, 0); PG8_LDB(B1, 0, 1); PG8_SCHED; PG8_LDA(At, 0, 0); PG8_STAGE(PG8_SA(1, 1), a1 + hstep, voffA);
;             PG8_WAIT_V(8); PG8_WAIT_L(0); PG8_BAR; PG8_MMA(0, 0, At, B0); PG8_MMA(0, 1, At, B1); PG8_BAR; PG8_SCHED;
;             PG8_LDA(At, 0, 1); PG8_STAGE(PG8_SB(0, 0), b2, voffB); PG8_STAGE(PG8_SB(0, 1), b2 + hstep, voffB); PG8_STAGE(PG8_SA(0, 0), a2, voffA);
;             PG8_WAIT_V(8); PG8_WAIT_L(0); PG8_BAR; PG8_MMA(1, 0, At, B0); PG8_MMA(1, 1, At, B1); PG8_BAR; PG8_SCHED;
	s_setprio 1
	s_waitcnt lgkmcnt(0)
	v_mfma_f32_16x16x32_bf16 v[124:127], v[144:147], v[186:189], v[124:127]
	v_mfma_f32_16x16x32_bf16 v[120:123], v[160:163], v[186:189], v[120:123]
	v_mfma_f32_16x16x32_bf16 v[108:111], v[144:147], v[194:197], v[108:111]
	v_mfma_f32_16x16x32_bf16 v[104:107], v[160:163], v[194:197], v[104:107]
	v_mfma_f32_16x16x32_bf16 v[92:95], v[144:147], v[208:211], v[92:95]
	v_mfma_f32_16x16x32_bf16 v[88:91], v[160:163], v[208:211], v[88:91]
	v_mfma_f32_16x16x32_bf16 v[76:79], v[144:147], v[216:219], v[76:79]
	v_mfma_f32_16x16x32_bf16 v[72:75], v[160:163], v[216:219], v[72:75]
	v_mfma_f32_16x16x32_bf16 v[124:127], v[148:151], v[190:193], v[124:127]
	v_mfma_f32_16x16x32_bf16 v[120:123], v[164:167], v[190:193], v[120:123]
	v_mfma_f32_16x16x32_bf16 v[108:111], v[148:151], v[198:201], v[108:111]
	v_mfma_f32_16x16x32_bf16 v[104:107], v[164:167], v[198:201], v[104:107]
	v_mfma_f32_16x16x32_bf16 v[92:95], v[148:151], v[212:215], v[92:95]
	v_mfma_f32_16x16x32_bf16 v[88:91], v[164:167], v[212:215], v[88:91]
	v_mfma_f32_16x16x32_bf16 v[76:79], v[148:151], v[220:223], v[76:79]
	v_mfma_f32_16x16x32_bf16 v[72:75], v[164:167], v[220:223], v[72:75]
	s_setprio 0
	s_setprio 1
	v_mfma_f32_16x16x32_bf16 v[116:119], v[168:171], v[186:189], v[116:119]
	v_mfma_f32_16x16x32_bf16 v[112:115], v[176:179], v[186:189], v[112:115]
	v_mfma_f32_16x16x32_bf16 v[100:103], v[168:171], v[194:197], v[100:103]
	v_mfma_f32_16x16x32_bf16 v[96:99], v[176:179], v[194:197], v[96:99]
	v_mfma_f32_16x16x32_bf16 v[84:87], v[168:171], v[208:211], v[84:87]
	v_mfma_f32_16x16x32_bf16 v[80:83], v[176:179], v[208:211], v[80:83]
	v_mfma_f32_16x16x32_bf16 v[68:71], v[168:171], v[216:219], v[68:71]
	v_mfma_f32_16x16x32_bf16 v[64:67], v[176:179], v[216:219], v[64:67]
	v_mfma_f32_16x16x32_bf16 v[116:119], v[172:175], v[190:193], v[116:119]
	v_mfma_f32_16x16x32_bf16 v[112:115], v[182:185], v[190:193], v[112:115]
	v_mfma_f32_16x16x32_bf16 v[100:103], v[172:175], v[198:201], v[100:103]
	v_mfma_f32_16x16x32_bf16 v[96:99], v[182:185], v[198:201], v[96:99]
	v_mfma_f32_16x16x32_bf16 v[84:87], v[172:175], v[212:215], v[84:87]
	v_mfma_f32_16x16x32_bf16 v[80:83], v[182:185], v[212:215], v[80:83]
	v_mfma_f32_16x16x32_bf16 v[68:71], v[172:175], v[220:223], v[68:71]
	v_mfma_f32_16x16x32_bf16 v[64:67], v[182:185], v[220:223], v[64:67]
	s_setprio 0
	s_barrier
	s_add_i32 s3, s65, s14
	v_lshl_add_u64 v[202:203], s[56:57], 0, v[132:133]
	s_mov_b32 m0, s3
	ds_read_b128 v[186:189], v157 offset:16384
	ds_read_b128 v[190:193], v157 offset:17408
	ds_read_b128 v[194:197], v157 offset:18432
	ds_read_b128 v[198:201], v157 offset:19456
	ds_read_b128 v[208:211], v157 offset:20480
	ds_read_b128 v[212:215], v157 offset:21504
	ds_read_b128 v[216:219], v157 offset:22528
	ds_read_b128 v[220:223], v157 offset:23552
	global_load_lds_dwordx4 v[202:203], off
	s_add_i32 m0, s3, 0x2000
	s_add_u32 s78, s56, 0x40000
	v_lshl_add_u64 v[224:225], s[56:57], 0, v[128:129]
	s_addc_u32 s79, s57, 0
	s_add_i32 s3, s66, s14
	global_load_lds_dwordx4 v[224:225], off
	v_lshl_add_u64 v[226:227], s[78:79], 0, v[132:133]
	s_mov_b32 m0, s3
	global_load_lds_dwordx4 v[226:227], off
	v_lshl_add_u64 v[226:227], s[78:79], 0, v[128:129]
	s_add_i32 m0, s3, 0x2000
	s_nop 0
	global_load_lds_dwordx4 v[226:227], off
	s_waitcnt vmcnt(6)
	s_waitcnt lgkmcnt(0)
	s_barrier
	s_setprio 1
	s_waitcnt lgkmcnt(0)
	v_mfma_f32_16x16x32_bf16 v[60:63], v[144:147], v[186:189], v[60:63]
	v_mfma_f32_16x16x32_bf16 v[56:59], v[160:163], v[186:189], v[56:59]
	v_mfma_f32_16x16x32_bf16 v[44:47], v[144:147], v[194:197], v[44:47]
	v_mfma_f32_16x16x32_bf16 v[40:43], v[160:163], v[194:197], v[40:43]
	v_mfma_f32_16x16x32_bf16 v[28:31], v[144:147], v[208:211], v[28:31]
	v_mfma_f32_16x16x32_bf16 v[24:27], v[160:163], v[208:211], v[24:27]
	v_mfma_f32_16x16x32_bf16 v[12:15], v[144:147], v[216:219], v[12:15]
	v_mfma_f32_16x16x32_bf16 v[8:11], v[160:163], v[216:219], v[8:11]
	v_mfma_f32_16x16x32_bf16 v[60:63], v[148:151], v[190:193], v[60:63]
	v_mfma_f32_16x16x32_bf16 v[56:59], v[164:167], v[190:193], v[56:59]
	v_mfma_f32_16x16x32_bf16 v[44:47], v[148:151], v[198:201], v[44:47]
	v_mfma_f32_16x16x32_bf16 v[40:43], v[164:167], v[198:201], v[40:43]
	v_mfma_f32_16x16x32_bf16 v[28:31], v[148:151], v[212:215], v[28:31]
	v_mfma_f32_16x16x32_bf16 v[24:27], v[164:167], v[212:215], v[24:27]
	v_lshl_add_u64 v[226:227], s[58:59], 0, v[134:135]
	s_mov_b32 m0, s34
	s_nop 0
	global_load_lds_dwordx4 v[226:227], off
	v_mfma_f32_16x16x32_bf16 v[12:15], v[148:151], v[220:223], v[12:15]
	v_mfma_f32_16x16x32_bf16 v[8:11], v[164:167], v[220:223], v[8:11]
	s_setprio 0
	s_setprio 1
	v_mfma_f32_16x16x32_bf16 v[52:55], v[168:171], v[186:189], v[52:55]
	v_mfma_f32_16x16x32_bf16 v[48:51], v[176:179], v[186:189], v[48:51]
	v_mfma_f32_16x16x32_bf16 v[36:39], v[168:171], v[194:197], v[36:39]
	v_mfma_f32_16x16x32_bf16 v[32:35], v[176:179], v[194:197], v[32:35]
	v_mfma_f32_16x16x32_bf16 v[20:23], v[168:171], v[208:211], v[20:23]
	v_mfma_f32_16x16x32_bf16 v[16:19], v[176:179], v[208:211], v[16:19]
	v_mfma_f32_16x16x32_bf16 v[4:7], v[168:171], v[216:219], v[4:7]
	v_mfma_f32_16x16x32_bf16 v[0:3], v[176:179], v[216:219], v[0:3]
	v_mfma_f32_16x16x32_bf16 v[52:55], v[172:175], v[190:193], v[52:55]
	v_mfma_f32_16x16x32_bf16 v[48:51], v[182:185], v[190:193], v[48:51]
	v_mfma_f32_16x16x32_bf16 v[36:39], v[172:175], v[198:201], v[36:39]
	v_mfma_f32_16x16x32_bf16 v[32:35], v[182:185], v[198:201], v[32:35]
	v_mfma_f32_16x16x32_bf16 v[20:23], v[172:175], v[212:215], v[20:23]
	v_mfma_f32_16x16x32_bf16 v[16:19], v[182:185], v[212:215], v[16:19]
	v_lshl_add_u64 v[228:229], s[58:59], 0, v[130:131]
	s_mov_b32 m0, s53
	s_nop 0
	global_load_lds_dwordx4 v[228:229], off
	v_mfma_f32_16x16x32_bf16 v[4:7], v[172:175], v[220:223], v[4:7]
	v_mfma_f32_16x16x32_bf16 v[0:3], v[182:185], v[220:223], v[0:3]
	s_setprio 0
	s_barrier
; #define PG8_STAGE(bufoff, gbase, voff) do { _Pragma("unroll") for (int _i = 0; _i < 2; ++_i) \
;         __builtin_amdgcn_global_load_lds((const unsigned*)((const char*)(gbase) + (voff)[_i]), (PG8_LAS unsigned*)(lds + (bufoff) + ldsw + _i * 8192), 16, 0, 0); } while (0)
; #define PG8_LDA(dst, b, h) do { _Pragma("unroll") for (int m = 0; m < 4; ++m) _Pragma("unroll") for (int k = 0; k < 2; ++k) dst[m][k] = *(const PG8_LAS bf16x8*)(lds + PG8_SA(b, h) + aoff + m * 2048 + k * 1024); } while (0)
; #define PG8_LDB(dst, b, h) do { _Pragma("unroll") for (int n = 0; n < 2; ++n) _Pragma("unroll") for (int k = 0; k < 2; ++k) dst[n][k] = *(const PG8_LAS bf16x8*)(lds + PG8_SB(b, h) + boff + n * 2048 + k * 1024); } while (0)
; #define PG8_MMA(ai, bj, At, Bt) do { __builtin_amdgcn_s_setprio(1); _Pragma("unroll") for (int m = 0; m < 4; ++m) _Pragma("unroll") for (int n = 0; n < 2; ++n) _Pragma("unroll") for (int k = 0; k < 2; ++k) \
;         acc[ai][bj][m][n] = __builtin_amdgcn_mfma_f32_16x16x32_bf16(Bt[n][k], At[m][k], acc[ai][bj][m][n], 0, 0, 0); __builtin_amdgcn_s_setprio(0); } while (0)
; #define PG8_WAIT_V(n) asm volatile("s_waitcnt vmcnt(" #n ")" ::: "memory")
; #define PG8_WAIT_L(n) asm volatile("s_waitcnt lgkmcnt(" #n ")" ::: "memory")
; #define PG8_BAR __builtin_amdgcn_s_barrier()
; #define PG8_SCHED __builtin_amdgcn_sched_barrier(0)
; template <class Epi, class Sched, bool ALIGN_EPI = false, bool SP2 = false>
; __device__ __forceinline__ void gemm_phase(PG8_LAS unsigned char* lds, const Gemm g, const Sched& S, const Epi& E) {
;     ...
;             PG8_LDB(B0, 1, 0); PG8_LDB(B1, 1, 1); PG8_SCHED; PG8_LDA(At, 1, 0); PG8_STAGE(PG8_SA(0, 1), a2 + hstep, voffA);
;             PG8_WAIT_V(8); PG8_WAIT_L(0); PG8_BAR; PG8_MMA(0, 0, At, B0); PG8_MMA(0, 1, At, B1); PG8_BAR; PG8_SCHED;
	s_add_i32 s3, 0, 0x18000
	v_add_u32_e32 v159, s3, v153
	s_add_i32 s33, 0, 0x1c000
	ds_read_b128 v[144:147], v159
	ds_read_b128 v[148:151], v159 offset:1024
	ds_read_b128 v[160:163], v159 offset:2048
	ds_read_b128 v[164:167], v159 offset:3072
	v_add_u32_e32 v159, s33, v153
	ds_read_b128 v[168:171], v159
	ds_read_b128 v[172:175], v159 offset:1024
	ds_read_b128 v[176:179], v159 offset:2048
	ds_read_b128 v[182:185], v159 offset:3072
	s_add_u32 s58, s58, 0x40000
	s_addc_u32 s59, s59, 0
	s_mov_b32 m0, s60
	v_lshl_add_u64 v[230:231], s[58:59], 0, v[134:135]
	ds_read_b128 v[186:189], v157 offset:32768
	ds_read_b128 v[190:193], v157 offset:33792
	ds_read_b128 v[194:197], v157 offset:34816
	ds_read_b128 v[198:201], v157 offset:35840
	ds_read_b128 v[208:211], v157 offset:36864
	ds_read_b128 v[212:215], v157 offset:37888
	ds_read_b128 v[216:219], v157 offset:38912
	ds_read_b128 v[220:223], v157 offset:39936
	global_load_lds_dwordx4 v[230:231], off
	v_lshl_add_u64 v[230:231], s[58:59], 0, v[130:131]
	s_mov_b32 m0, s61
	s_nop 0
	global_load_lds_dwordx4 v[230:231], off
	s_waitcnt vmcnt(8)
	s_waitcnt lgkmcnt(0)
	s_barrier
	s_setprio 1
	s_waitcnt lgkmcnt(0)
	v_mfma_f32_16x16x32_bf16 v[124:127], v[144:147], v[186:189], v[124:127]
	v_mfma_f32_16x16x32_bf16 v[120:123], v[160:163], v[186:189], v[120:123]
	v_mfma_f32_16x16x32_bf16 v[108:111], v[144:147], v[194:197], v[108:111]
	v_mfma_f32_16x16x32_bf16 v[104:107], v[160:163], v[194:197], v[104:107]
	v_mfma_f32_16x16x32_bf16 v[92:95], v[144:147], v[208:211], v[92:95]
	v_mfma_f32_16x16x32_bf16 v[88:91], v[160:163], v[208:211], v[88:91]
	v_mfma_f32_16x16x32_bf16 v[76:79], v[144:147], v[216:219], v[76:79]
	v_mfma_f32_16x16x32_bf16 v[72:75], v[160:163], v[216:219], v[72:75]
	v_mfma_f32_16x16x32_bf16 v[124:127], v[148:151], v[190:193], v[124:127]
	v_mfma_f32_16x16x32_bf16 v[120:123], v[164:167], v[190:193], v[120:123]
	v_mfma_f32_16x16x32_bf16 v[108:111], v[148:151], v[198:201], v[108:111]
	v_mfma_f32_16x16x32_bf16 v[104:107], v[164:167], v[198:201], v[104:107]
	v_mfma_f32_16x16x32_bf16 v[92:95], v[148:151], v[212:215], v[92:95]
	v_mfma_f32_16x16x32_bf16 v[88:91], v[164:167], v[212:215], v[88:91]
	v_mfma_f32_16x16x32_bf16 v[76:79], v[148:151], v[220:223], v[76:79]
	v_mfma_f32_16x16x32_bf16 v[72:75], v[164:167], v[220:223], v[72:75]
	s_setprio 0
	s_setprio 1
	v_mfma_f32_16x16x32_bf16 v[116:119], v[168:171], v[186:189], v[116:119]
	v_mfma_f32_16x16x32_bf16 v[112:115], v[176:179], v[186:189], v[112:115]
	v_mfma_f32_16x16x32_bf16 v[100:103], v[168:171], v[194:197], v[100:103]
	v_mfma_f32_16x16x32_bf16 v[96:99], v[176:179], v[194:197], v[96:99]
	v_mfma_f32_16x16x32_bf16 v[84:87], v[168:171], v[208:211], v[84:87]
	v_mfma_f32_16x16x32_bf16 v[80:83], v[176:179], v[208:211], v[80:83]
	v_mfma_f32_16x16x32_bf16 v[68:71], v[168:171], v[216:219], v[68:71]
	v_mfma_f32_16x16x32_bf16 v[64:67], v[176:179], v[216:219], v[64:67]
	v_mfma_f32_16x16x32_bf16 v[116:119], v[172:175], v[190:193], v[116:119]
	v_mfma_f32_16x16x32_bf16 v[112:115], v[182:185], v[190:193], v[112:115]
	v_mfma_f32_16x16x32_bf16 v[100:103], v[172:175], v[198:201], v[100:103]
	v_mfma_f32_16x16x32_bf16 v[96:99], v[182:185], v[198:201], v[96:99]
	v_mfma_f32_16x16x32_bf16 v[84:87], v[172:175], v[212:215], v[84:87]
	v_mfma_f32_16x16x32_bf16 v[80:83], v[182:185], v[212:215], v[80:83]
	v_mfma_f32_16x16x32_bf16 v[68:71], v[172:175], v[220:223], v[68:71]
	v_mfma_f32_16x16x32_bf16 v[64:67], v[182:185], v[220:223], v[64:67]
	s_setprio 0
	s_barrier
; #define PG8_STAGE(bufoff, gbase, voff) do { _Pragma("unroll") for (int _i = 0; _i < 2; ++_i) \
;         __builtin_amdgcn_global_load_lds((const unsigned*)((const char*)(gbase) + (voff)[_i]), (PG8_LAS unsigned*)(lds + (bufoff) + ldsw + _i * 8192), 16, 0, 0); } while (0)
; #define PG8_LDA(dst, b, h) do { _Pragma("unroll") for (int m = 0; m < 4; ++m) _Pragma("unroll") for (int k = 0; k < 2; ++k) dst[m][k] = *(const PG8_LAS bf16x8*)(lds + PG8_SA(b, h) + aoff + m * 2048 + k * 1024); } while (0)
; #define PG8_MMA(ai, bj, At, Bt) do { __builtin_amdgcn_s_setprio(1); _Pragma("unroll") for (int m = 0; m < 4; ++m) _Pragma("unroll") for (int n = 0; n < 2; ++n) _Pragma("unroll") for (int k = 0; k < 2; ++k) \
;         acc[ai][bj][m][n] = __builtin_amdgcn_mfma_f32_16x16x32_bf16(Bt[n][k], At[m][k], acc[ai][bj][m][n], 0, 0, 0); __builtin_amdgcn_s_setprio(0); } while (0)
; #define PG8_BAR __builtin_amdgcn_s_barrier()
; __device__ __forceinline__ float row_rs(const float* ssp, int row) { const unsigned long long v = ((const unsigned long long*)ssp)[row];
;     return __builtin_amdgcn_rsqf((float)v * (1.0f / 4294967296.0f) * (1.0f / 1024.0f) + RMS_EPS); }
; __device__ __forceinline__ void fx_add(float* p, size_t idx, float s) { atomicAdd((unsigned long long*)p + idx, (unsigned long long)(long long)(s * 4294967296.0f)); }
; __device__ __forceinline__ unsigned cvtpk(float lo, float hi) { f32x2v_ v = {lo, hi}; bf16x2v_ b = __builtin_convertvector(v, bf16x2v_); return __builtin_bit_cast(unsigned, b); }
;     __device__ __forceinline__ void operator()(const f32x4 (&acc)[2][2][4][2], const Unit& u, int wr, int wc, int fr, int fq) const {
;         const int row0 = u.pm * BM + wr * 64 + fr, col0 = u.pn * HALF + wc * 32 + 8 * fq;
; #pragma unroll
;         for (int ai = 0; ai < 2; ++ai)
; #pragma unroll
;             for (int m = 0; m < 4; ++m) { const int row = row0 + ai * HALF + m * 16; const float rs = row_rs(ss, row);
; template <class Epi, class Sched, bool ALIGN_EPI = false, bool SP2 = false>
; __device__ __forceinline__ void gemm_phase(PG8_LAS unsigned char* lds, const Gemm g, const Sched& S, const Epi& E) {
;     ...
;             PG8_LDA(At, 1, 1); PG8_STAGE(PG8_SB(1, 0), b3, voffB); PG8_STAGE(PG8_SB(1, 1), b3 + hstep, voffB); PG8_STAGE(PG8_SA(1, 0), a3, voffA);
;             PG8_WAIT_V(8); PG8_WAIT_L(0); PG8_BAR; PG8_MMA(1, 0, At, B0); PG8_MMA(1, 1, At, B1); PG8_BAR; PG8_SCHED;
	s_add_i32 s3, s3, s14
	v_lshl_add_u64 v[202:203], v[202:203], 0, s[36:37]
	s_mov_b32 m0, s3
	ds_read_b128 v[186:189], v157 offset:49152
	ds_read_b128 v[190:193], v157 offset:50176
	ds_read_b128 v[194:197], v157 offset:51200
	ds_read_b128 v[198:201], v157 offset:52224
	ds_read_b128 v[208:211], v157 offset:53248
	ds_read_b128 v[212:215], v157 offset:54272
	ds_read_b128 v[216:219], v157 offset:55296
	ds_read_b128 v[220:223], v157 offset:56320
	global_load_lds_dwordx4 v[202:203], off
	s_add_i32 m0, s3, 0x2000
	s_add_u32 s56, s56, 0x40080
	v_lshl_add_u64 v[202:203], v[224:225], 0, s[36:37]
	s_addc_u32 s57, s57, 0
	s_add_i32 s3, s33, s14
	global_load_lds_dwordx4 v[202:203], off
	v_lshl_add_u64 v[202:203], s[56:57], 0, v[132:133]
	s_mov_b32 m0, s3
	s_nop 0
	global_load_lds_dwordx4 v[202:203], off
	v_lshl_add_u64 v[202:203], s[56:57], 0, v[128:129]
	s_add_i32 m0, s3, 0x2000
	s_nop 0
	global_load_lds_dwordx4 v[202:203], off
	s_waitcnt vmcnt(6)
	s_waitcnt lgkmcnt(0)
	s_barrier
	s_setprio 1
	s_waitcnt lgkmcnt(0)
	v_mfma_f32_16x16x32_bf16 v[60:63], v[144:147], v[186:189], v[60:63]
	v_mfma_f32_16x16x32_bf16 v[56:59], v[160:163], v[186:189], v[56:59]
	v_mfma_f32_16x16x32_bf16 v[44:47], v[144:147], v[194:197], v[44:47]
	v_mfma_f32_16x16x32_bf16 v[40:43], v[160:163], v[194:197], v[40:43]
	v_mfma_f32_16x16x32_bf16 v[28:31], v[144:147], v[208:211], v[28:31]
	v_mfma_f32_16x16x32_bf16 v[24:27], v[160:163], v[208:211], v[24:27]
	v_mfma_f32_16x16x32_bf16 v[12:15], v[144:147], v[216:219], v[12:15]
	v_mfma_f32_16x16x32_bf16 v[8:11], v[160:163], v[216:219], v[8:11]
	v_mfma_f32_16x16x32_bf16 v[60:63], v[148:151], v[190:193], v[60:63]
	v_mfma_f32_16x16x32_bf16 v[56:59], v[164:167], v[190:193], v[56:59]
	v_mfma_f32_16x16x32_bf16 v[44:47], v[148:151], v[198:201], v[44:47]
	v_mfma_f32_16x16x32_bf16 v[40:43], v[164:167], v[198:201], v[40:43]
	v_mfma_f32_16x16x32_bf16 v[28:31], v[148:151], v[212:215], v[28:31]
	v_mfma_f32_16x16x32_bf16 v[24:27], v[164:167], v[212:215], v[24:27]
	v_lshl_add_u64 v[202:203], v[226:227], 0, s[36:37]
	s_mov_b32 m0, s63
	s_nop 0
	global_load_lds_dwordx4 v[202:203], off
	v_mfma_f32_16x16x32_bf16 v[12:15], v[148:151], v[220:223], v[12:15]
	v_mfma_f32_16x16x32_bf16 v[8:11], v[164:167], v[220:223], v[8:11]
	s_setprio 0
	s_setprio 1
	v_mfma_f32_16x16x32_bf16 v[52:55], v[168:171], v[186:189], v[52:55]
	v_mfma_f32_16x16x32_bf16 v[48:51], v[176:179], v[186:189], v[48:51]
	v_mfma_f32_16x16x32_bf16 v[36:39], v[168:171], v[194:197], v[36:39]
	v_mfma_f32_16x16x32_bf16 v[32:35], v[176:179], v[194:197], v[32:35]
	v_mfma_f32_16x16x32_bf16 v[20:23], v[168:171], v[208:211], v[20:23]
	v_mfma_f32_16x16x32_bf16 v[16:19], v[176:179], v[208:211], v[16:19]
	v_mfma_f32_16x16x32_bf16 v[4:7], v[168:171], v[216:219], v[4:7]
	v_mfma_f32_16x16x32_bf16 v[0:3], v[176:179], v[216:219], v[0:3]
	v_mfma_f32_16x16x32_bf16 v[52:55], v[172:175], v[190:193], v[52:55]
	v_mfma_f32_16x16x32_bf16 v[48:51], v[182:185], v[190:193], v[48:51]
	v_mfma_f32_16x16x32_bf16 v[36:39], v[172:175], v[198:201], v[36:39]
	v_mfma_f32_16x16x32_bf16 v[32:35], v[182:185], v[198:201], v[32:35]
	v_mfma_f32_16x16x32_bf16 v[20:23], v[172:175], v[212:215], v[20:23]
	v_mfma_f32_16x16x32_bf16 v[16:19], v[182:185], v[212:215], v[16:19]
	v_lshl_add_u64 v[202:203], v[228:229], 0, s[36:37]
	s_mov_b32 m0, s64
	s_nop 0
	global_load_lds_dwordx4 v[202:203], off
	v_mfma_f32_16x16x32_bf16 v[4:7], v[172:175], v[220:223], v[4:7]
	v_mfma_f32_16x16x32_bf16 v[0:3], v[182:185], v[220:223], v[0:3]
	s_setprio 0
	s_barrier
	s_add_i32 s83, s83, 2
	s_add_u32 s54, s54, 0x100
	s_addc_u32 s55, s55, 0
	s_add_u32 s77, s77, 0x100
	s_addc_u32 s82, s82, 0
	s_cmp_gt_u32 s83, 13
	s_cbranch_scc0 .LBB0_957
	v_lshl_add_u32 v144, s52, 8, v152
	v_ashrrev_i32_e32 v145, 31, v144
	v_lshl_add_u64 v[150:151], v[144:145], 3, s[0:1]
	global_load_dwordx2 v[182:183], v[150:151], off
	global_load_dwordx2 v[184:185], v[150:151], off offset:128
	global_load_dwordx2 v[186:187], v[150:151], off offset:256
	global_load_dwordx2 v[188:189], v[150:151], off offset:384
	global_load_dwordx2 v[190:191], v[150:151], off offset:1024
	global_load_dwordx2 v[192:193], v[150:151], off offset:1152
	global_load_dwordx2 v[194:195], v[150:151], off offset:1280
	global_load_dwordx2 v[196:197], v[150:151], off offset:1408
	s_and_b64 vcc, exec, s[38:39]
	s_cbranch_vccz .LBB0_960
	s_barrier

; #define PG8_STAGE(bufoff, gbase, voff) do { _Pragma("unroll") for (int _i = 0; _i < 2; ++_i) \
;         __builtin_amdgcn_global_load_lds((const unsigned*)((const char*)(gbase) + (voff)[_i]), (PG8_LAS unsigned*)(lds + (bufoff) + ldsw + _i * 8192), 16, 0, 0); } while (0)
; #define PG8_LDA(dst, b, h) do { _Pragma("unroll") for (int m = 0; m < 4; ++m) _Pragma("unroll") for (int k = 0; k < 2; ++k) dst[m][k] = *(const PG8_LAS bf16x8*)(lds + PG8_SA(b, h) + aoff + m * 2048 + k * 1024); } while (0)
; #define PG8_LDB(dst, b, h) do { _Pragma("unroll") for (int n = 0; n < 2; ++n) _Pragma("unroll") for (int k = 0; k < 2; ++k) dst[n][k] = *(const PG8_LAS bf16x8*)(lds + PG8_SB(b, h) + boff + n * 2048 + k * 1024); } while (0)
; #define PG8_WAIT_V(n) asm volatile("s_waitcnt vmcnt(" #n ")" ::: "memory")
; #define PG8_WAIT_L(n) asm volatile("s_waitcnt lgkmcnt(" #n ")" ::: "memory")
; #define PG8_BAR __builtin_amdgcn_s_barrier()
; #define PG8_SCHED __builtin_amdgcn_sched_barrier(0)
; template <class Epi, class Sched, bool ALIGN_EPI = false, bool SP2 = false>
; __device__ __forceinline__ void gemm_phase(PG8_LAS unsigned char* lds, const Gemm g, const Sched& S, const Epi& E) {
;     ...
;         const bool has_next = S.next(ui + 1, nxt);
;         const char* nA = has_next ? (const char*)g.A + (size_t)nxt.pm * tstep : cA; const char* nB = has_next ? (const char*)g.Bt + (size_t)nxt.pn * tstep : cB;
;         for (int t = 0; t < nt; t += 2) {
;             const bool last = (t == nt - 2);
;             const char* a1 = cA + (size_t)(t + 1) * kstep;
;             const char* a2 = last ? nA : cA + (size_t)(t + 2) * kstep; const char* b2 = last ? nB : cB + (size_t)(t + 2) * kstep;
;             const char* a3 = a2 + kstep; const char* b3 = b2 + kstep;
;             if (last && has_next) S.a_ready(nxt);
;             if constexpr (SP2) {
;             PG8_LDB(B0, 0, 0); PG8_LDB(B1, 0, 1); PG8_SCHED; PG8_LDA(At, 0, 0); PG8_STAGE(PG8_SA(1, 1), a1 + hstep, voffA);
;             PG8_WAIT_V(8); PG8_WAIT_L(0); PG8_BAR; PG8_MMA(0, 0, At, B0); PG8_MMA(0, 1, At, B1); PG8_BAR; PG8_SCHED;
;             PG8_LDA(At, 0, 1); PG8_STAGE(PG8_SB(0, 0), b2, voffB); PG8_STAGE(PG8_SB(0, 1), b2 + hstep, voffB); PG8_STAGE(PG8_SA(0, 0), a2, voffA);
;             PG8_WAIT_V(8); PG8_WAIT_L(0); PG8_BAR; PG8_MMA(1, 0, At, B0); PG8_MMA(1, 1, At, B1); PG8_BAR; PG8_SCHED;
.LBB0_1034:
	s_add_u32 s75, s52, 0x100
	s_addc_u32 s76, s53, 0
	s_mov_b32 s77, -2
	s_waitcnt lgkmcnt(0)
	ds_read_b128 v[144:147], v151
	ds_read_b128 v[156:159], v151 offset:1024
	ds_read_b128 v[160:163], v151 offset:2048
	ds_read_b128 v[164:167], v151 offset:3072
	ds_read_b128 v[168:171], v152
	ds_read_b128 v[172:175], v152 offset:1024
	ds_read_b128 v[176:179], v152 offset:2048
	ds_read_b128 v[182:185], v152 offset:3072
	s_add_u32 s52, s50, 0x100
	s_addc_u32 s53, s51, 0
	s_cmp_eq_u32 s77, 40
	s_cselect_b32 s57, s1, s53
	s_cselect_b32 s56, s0, s52
	s_cselect_b32 s55, s49, s76
	s_cselect_b32 s54, s48, s75
	v_lshl_add_u64 v[202:203], s[50:51], 0, v[136:137]
	s_add_i32 m0, s14, 0xc000
	ds_read_b128 v[186:189], v153
	ds_read_b128 v[190:193], v153 offset:1024
	ds_read_b128 v[194:197], v153 offset:2048
	ds_read_b128 v[198:201], v153 offset:3072
	ds_read_b128 v[208:211], v153 offset:4096
	ds_read_b128 v[212:215], v153 offset:5120
	ds_read_b128 v[216:219], v153 offset:6144
	ds_read_b128 v[220:223], v153 offset:7168
	global_load_lds_dwordx4 v[202:203], off
	v_lshl_add_u64 v[202:203], s[50:51], 0, v[138:139]
	s_add_i32 m0, s14, 0xe000
	s_nop 0
	global_load_lds_dwordx4 v[202:203], off
	s_waitcnt vmcnt(8)
	s_waitcnt lgkmcnt(0)
	s_barrier
	s_setprio 1
	s_waitcnt lgkmcnt(0)
	v_mfma_f32_16x16x32_bf16 v[124:127], v[144:147], v[186:189], 0
	v_mfma_f32_16x16x32_bf16 v[120:123], v[160:163], v[186:189], 0
	v_mfma_f32_16x16x32_bf16 v[108:111], v[144:147], v[194:197], 0
	v_mfma_f32_16x16x32_bf16 v[104:107], v[160:163], v[194:197], 0
	v_mfma_f32_16x16x32_bf16 v[92:95], v[144:147], v[208:211], 0
	v_mfma_f32_16x16x32_bf16 v[88:91], v[160:163], v[208:211], 0
	v_mfma_f32_16x16x32_bf16 v[76:79], v[144:147], v[216:219], 0
	v_mfma_f32_16x16x32_bf16 v[72:75], v[160:163], v[216:219], 0
	v_mfma_f32_16x16x32_bf16 v[124:127], v[156:159], v[190:193], v[124:127]
	v_mfma_f32_16x16x32_bf16 v[120:123], v[164:167], v[190:193], v[120:123]
	v_mfma_f32_16x16x32_bf16 v[108:111], v[156:159], v[198:201], v[108:111]
	v_mfma_f32_16x16x32_bf16 v[104:107], v[164:167], v[198:201], v[104:107]
	v_mfma_f32_16x16x32_bf16 v[92:95], v[156:159], v[212:215], v[92:95]
	v_mfma_f32_16x16x32_bf16 v[88:91], v[164:167], v[212:215], v[88:91]
	v_mfma_f32_16x16x32_bf16 v[76:79], v[156:159], v[220:223], v[76:79]
	v_mfma_f32_16x16x32_bf16 v[72:75], v[164:167], v[220:223], v[72:75]
	s_setprio 0
	s_setprio 1
	v_mfma_f32_16x16x32_bf16 v[116:119], v[168:171], v[186:189], 0
	v_mfma_f32_16x16x32_bf16 v[112:115], v[176:179], v[186:189], 0
	v_mfma_f32_16x16x32_bf16 v[100:103], v[168:171], v[194:197], 0
	v_mfma_f32_16x16x32_bf16 v[96:99], v[176:179], v[194:197], 0
	v_mfma_f32_16x16x32_bf16 v[84:87], v[168:171], v[208:211], 0
	v_mfma_f32_16x16x32_bf16 v[80:83], v[176:179], v[208:211], 0
	v_mfma_f32_16x16x32_bf16 v[68:71], v[168:171], v[216:219], 0
	v_mfma_f32_16x16x32_bf16 v[64:67], v[176:179], v[216:219], 0
	v_mfma_f32_16x16x32_bf16 v[116:119], v[172:175], v[190:193], v[116:119]
	v_mfma_f32_16x16x32_bf16 v[112:115], v[182:185], v[190:193], v[112:115]
	v_mfma_f32_16x16x32_bf16 v[100:103], v[172:175], v[198:201], v[100:103]
	v_mfma_f32_16x16x32_bf16 v[96:99], v[182:185], v[198:201], v[96:99]
	v_mfma_f32_16x16x32_bf16 v[84:87], v[172:175], v[212:215], v[84:87]
	v_mfma_f32_16x16x32_bf16 v[80:83], v[182:185], v[212:215], v[80:83]
	v_mfma_f32_16x16x32_bf16 v[68:71], v[172:175], v[220:223], v[68:71]
	v_mfma_f32_16x16x32_bf16 v[64:67], v[182:185], v[220:223], v[64:67]
	s_setprio 0
	s_barrier
	s_add_i32 s50, s61, s3
	v_lshl_add_u64 v[202:203], s[54:55], 0, v[130:131]
	s_mov_b32 m0, s50
	ds_read_b128 v[186:189], v153 offset:16384
	ds_read_b128 v[190:193], v153 offset:17408
	ds_read_b128 v[194:197], v153 offset:18432
	ds_read_b128 v[198:201], v153 offset:19456
	ds_read_b128 v[208:211], v153 offset:20480
	ds_read_b128 v[212:215], v153 offset:21504
	ds_read_b128 v[216:219], v153 offset:22528
	ds_read_b128 v[220:223], v153 offset:23552
	global_load_lds_dwordx4 v[202:203], off
	s_add_i32 m0, s50, 0x2000
	s_add_u32 s50, s54, 0xb0000
	v_lshl_add_u64 v[224:225], s[54:55], 0, v[134:135]
	s_addc_u32 s51, s55, 0
	s_add_i32 s78, s62, s3
	global_load_lds_dwordx4 v[224:225], off
	v_lshl_add_u64 v[226:227], s[50:51], 0, v[130:131]
	s_mov_b32 m0, s78
	global_load_lds_dwordx4 v[226:227], off
	v_lshl_add_u64 v[226:227], s[50:51], 0, v[134:135]
	s_add_i32 m0, s78, 0x2000
	s_nop 0
	global_load_lds_dwordx4 v[226:227], off
	s_waitcnt vmcnt(6)
	s_waitcnt lgkmcnt(0)
	s_barrier
; #define PG8_STAGE(bufoff, gbase, voff) do { _Pragma("unroll") for (int _i = 0; _i < 2; ++_i) \
;         __builtin_amdgcn_global_load_lds((const unsigned*)((const char*)(gbase) + (voff)[_i]), (PG8_LAS unsigned*)(lds + (bufoff) + ldsw + _i * 8192), 16, 0, 0); } while (0)
; #define PG8_LDA(dst, b, h) do { _Pragma("unroll") for (int m = 0; m < 4; ++m) _Pragma("unroll") for (int k = 0; k < 2; ++k) dst[m][k] = *(const PG8_LAS bf16x8*)(lds + PG8_SA(b, h) + aoff + m * 2048 + k * 1024); } while (0)
; #define PG8_LDB(dst, b, h) do { _Pragma("unroll") for (int n = 0; n < 2; ++n) _Pragma("unroll") for (int k = 0; k < 2; ++k) dst[n][k] = *(const PG8_LAS bf16x8*)(lds + PG8_SB(b, h) + boff + n * 2048 + k * 1024); } while (0)
; #define PG8_MMA(ai, bj, At, Bt) do { __builtin_amdgcn_s_setprio(1); _Pragma("unroll") for (int m = 0; m < 4; ++m) _Pragma("unroll") for (int n = 0; n < 2; ++n) _Pragma("unroll") for (int k = 0; k < 2; ++k) \
;         acc[ai][bj][m][n] = __builtin_amdgcn_mfma_f32_16x16x32_bf16(Bt[n][k], At[m][k], acc[ai][bj][m][n], 0, 0, 0); __builtin_amdgcn_s_setprio(0); } while (0)
; #define PG8_WAIT_V(n) asm volatile("s_waitcnt vmcnt(" #n ")" ::: "memory")
; #define PG8_WAIT_L(n) asm volatile("s_waitcnt lgkmcnt(" #n ")" ::: "memory")
; #define PG8_BAR __builtin_amdgcn_s_barrier()
; #define PG8_SCHED __builtin_amdgcn_sched_barrier(0)
; template <class Epi, class Sched, bool ALIGN_EPI = false, bool SP2 = false>
; __device__ __forceinline__ void gemm_phase(PG8_LAS unsigned char* lds, const Gemm g, const Sched& S, const Epi& E) {
;     ...
;             PG8_LDA(At, 0, 1); PG8_STAGE(PG8_SB(0, 0), b2, voffB); PG8_STAGE(PG8_SB(0, 1), b2 + hstep, voffB); PG8_STAGE(PG8_SA(0, 0), a2, voffA);
;             PG8_WAIT_V(8); PG8_WAIT_L(0); PG8_BAR; PG8_MMA(1, 0, At, B0); PG8_MMA(1, 1, At, B1); PG8_BAR; PG8_SCHED;
;             PG8_LDB(B0, 1, 0); PG8_LDB(B1, 1, 1); PG8_SCHED; PG8_LDA(At, 1, 0); PG8_STAGE(PG8_SA(0, 1), a2 + hstep, voffA);
;             PG8_WAIT_V(8); PG8_WAIT_L(0); PG8_BAR; PG8_MMA(0, 0, At, B0); PG8_MMA(0, 1, At, B1); PG8_BAR; PG8_SCHED;
	s_setprio 1
	s_waitcnt lgkmcnt(0)
	v_mfma_f32_16x16x32_bf16 v[60:63], v[144:147], v[186:189], 0
	v_mfma_f32_16x16x32_bf16 v[56:59], v[160:163], v[186:189], 0
	v_mfma_f32_16x16x32_bf16 v[44:47], v[144:147], v[194:197], 0
	v_mfma_f32_16x16x32_bf16 v[40:43], v[160:163], v[194:197], 0
	v_mfma_f32_16x16x32_bf16 v[28:31], v[144:147], v[208:211], 0
	v_mfma_f32_16x16x32_bf16 v[24:27], v[160:163], v[208:211], 0
	v_mfma_f32_16x16x32_bf16 v[12:15], v[144:147], v[216:219], 0
	v_mfma_f32_16x16x32_bf16 v[8:11], v[160:163], v[216:219], 0
	v_mfma_f32_16x16x32_bf16 v[60:63], v[156:159], v[190:193], v[60:63]
	v_mfma_f32_16x16x32_bf16 v[56:59], v[164:167], v[190:193], v[56:59]
	v_mfma_f32_16x16x32_bf16 v[44:47], v[156:159], v[198:201], v[44:47]
	v_mfma_f32_16x16x32_bf16 v[40:43], v[164:167], v[198:201], v[40:43]
	v_mfma_f32_16x16x32_bf16 v[28:31], v[156:159], v[212:215], v[28:31]
	v_mfma_f32_16x16x32_bf16 v[24:27], v[164:167], v[212:215], v[24:27]
	v_lshl_add_u64 v[226:227], s[56:57], 0, v[128:129]
	s_mov_b32 m0, s14
	s_nop 0
	global_load_lds_dwordx4 v[226:227], off
	v_mfma_f32_16x16x32_bf16 v[12:15], v[156:159], v[220:223], v[12:15]
	v_mfma_f32_16x16x32_bf16 v[8:11], v[164:167], v[220:223], v[8:11]
	s_setprio 0
	s_setprio 1
	v_mfma_f32_16x16x32_bf16 v[52:55], v[168:171], v[186:189], 0
	v_mfma_f32_16x16x32_bf16 v[48:51], v[176:179], v[186:189], 0
	v_mfma_f32_16x16x32_bf16 v[36:39], v[168:171], v[194:197], 0
	v_mfma_f32_16x16x32_bf16 v[32:35], v[176:179], v[194:197], 0
	v_mfma_f32_16x16x32_bf16 v[20:23], v[168:171], v[208:211], 0
	v_mfma_f32_16x16x32_bf16 v[16:19], v[176:179], v[208:211], 0
	v_mfma_f32_16x16x32_bf16 v[4:7], v[168:171], v[216:219], 0
	v_mfma_f32_16x16x32_bf16 v[0:3], v[176:179], v[216:219], 0
	v_mfma_f32_16x16x32_bf16 v[52:55], v[172:175], v[190:193], v[52:55]
	v_mfma_f32_16x16x32_bf16 v[48:51], v[182:185], v[190:193], v[48:51]
	v_mfma_f32_16x16x32_bf16 v[36:39], v[172:175], v[198:201], v[36:39]
	v_mfma_f32_16x16x32_bf16 v[32:35], v[182:185], v[198:201], v[32:35]
	v_mfma_f32_16x16x32_bf16 v[20:23], v[172:175], v[212:215], v[20:23]
	v_mfma_f32_16x16x32_bf16 v[16:19], v[182:185], v[212:215], v[16:19]
	v_lshl_add_u64 v[228:229], s[56:57], 0, v[132:133]
	s_mov_b32 m0, s15
	s_nop 0
	global_load_lds_dwordx4 v[228:229], off
	v_mfma_f32_16x16x32_bf16 v[4:7], v[172:175], v[220:223], v[4:7]
	v_mfma_f32_16x16x32_bf16 v[0:3], v[182:185], v[220:223], v[0:3]
	s_setprio 0
	s_barrier
	s_add_i32 s78, 0, 0x18000
	v_add_u32_e32 v155, s78, v149
	s_add_i32 s79, 0, 0x1c000
	ds_read_b128 v[144:147], v155
	ds_read_b128 v[156:159], v155 offset:1024
	ds_read_b128 v[160:163], v155 offset:2048
	ds_read_b128 v[164:167], v155 offset:3072
	v_add_u32_e32 v155, s79, v149
	ds_read_b128 v[168:171], v155
	ds_read_b128 v[172:175], v155 offset:1024
	ds_read_b128 v[176:179], v155 offset:2048
	ds_read_b128 v[182:185], v155 offset:3072
	s_add_u32 s50, s56, 0xb0000
	s_addc_u32 s51, s57, 0
	s_mov_b32 m0, s33
	v_lshl_add_u64 v[230:231], s[50:51], 0, v[128:129]
	ds_read_b128 v[186:189], v153 offset:32768
	ds_read_b128 v[190:193], v153 offset:33792
	ds_read_b128 v[194:197], v153 offset:34816
	ds_read_b128 v[198:201], v153 offset:35840
	ds_read_b128 v[208:211], v153 offset:36864
	ds_read_b128 v[212:215], v153 offset:37888
	ds_read_b128 v[216:219], v153 offset:38912
	ds_read_b128 v[220:223], v153 offset:39936
	global_load_lds_dwordx4 v[230:231], off
	v_lshl_add_u64 v[230:231], s[50:51], 0, v[132:133]
	s_mov_b32 m0, s34
	s_nop 0
	global_load_lds_dwordx4 v[230:231], off
	s_waitcnt vmcnt(8)
	s_waitcnt lgkmcnt(0)
	s_barrier
	s_setprio 1
	s_waitcnt lgkmcnt(0)
	v_mfma_f32_16x16x32_bf16 v[124:127], v[144:147], v[186:189], v[124:127]
	v_mfma_f32_16x16x32_bf16 v[120:123], v[160:163], v[186:189], v[120:123]
	v_mfma_f32_16x16x32_bf16 v[108:111], v[144:147], v[194:197], v[108:111]
	v_mfma_f32_16x16x32_bf16 v[104:107], v[160:163], v[194:197], v[104:107]
	v_mfma_f32_16x16x32_bf16 v[92:95], v[144:147], v[208:211], v[92:95]
	v_mfma_f32_16x16x32_bf16 v[88:91], v[160:163], v[208:211], v[88:91]
	v_mfma_f32_16x16x32_bf16 v[76:79], v[144:147], v[216:219], v[76:79]
	v_mfma_f32_16x16x32_bf16 v[72:75], v[160:163], v[216:219], v[72:75]
	v_mfma_f32_16x16x32_bf16 v[124:127], v[156:159], v[190:193], v[124:127]
	v_mfma_f32_16x16x32_bf16 v[120:123], v[164:167], v[190:193], v[120:123]
	v_mfma_f32_16x16x32_bf16 v[108:111], v[156:159], v[198:201], v[108:111]
	v_mfma_f32_16x16x32_bf16 v[104:107], v[164:167], v[198:201], v[104:107]
	v_mfma_f32_16x16x32_bf16 v[92:95], v[156:159], v[212:215], v[92:95]
	v_mfma_f32_16x16x32_bf16 v[88:91], v[164:167], v[212:215], v[88:91]
	v_mfma_f32_16x16x32_bf16 v[76:79], v[156:159], v[220:223], v[76:79]
	v_mfma_f32_16x16x32_bf16 v[72:75], v[164:167], v[220:223], v[72:75]
	s_setprio 0
	s_setprio 1
	v_mfma_f32_16x16x32_bf16 v[116:119], v[168:171], v[186:189], v[116:119]
	v_mfma_f32_16x16x32_bf16 v[112:115], v[176:179], v[186:189], v[112:115]
	v_mfma_f32_16x16x32_bf16 v[100:103], v[168:171], v[194:197], v[100:103]
	v_mfma_f32_16x16x32_bf16 v[96:99], v[176:179], v[194:197], v[96:99]
	v_mfma_f32_16x16x32_bf16 v[84:87], v[168:171], v[208:211], v[84:87]
	v_mfma_f32_16x16x32_bf16 v[80:83], v[176:179], v[208:211], v[80:83]
	v_mfma_f32_16x16x32_bf16 v[68:71], v[168:171], v[216:219], v[68:71]
	v_mfma_f32_16x16x32_bf16 v[64:67], v[176:179], v[216:219], v[64:67]
	v_mfma_f32_16x16x32_bf16 v[116:119], v[172:175], v[190:193], v[116:119]
	v_mfma_f32_16x16x32_bf16 v[112:115], v[182:185], v[190:193], v[112:115]
	v_mfma_f32_16x16x32_bf16 v[100:103], v[172:175], v[198:201], v[100:103]
	v_mfma_f32_16x16x32_bf16 v[96:99], v[182:185], v[198:201], v[96:99]
	v_mfma_f32_16x16x32_bf16 v[84:87], v[172:175], v[212:215], v[84:87]
	v_mfma_f32_16x16x32_bf16 v[80:83], v[182:185], v[212:215], v[80:83]
	v_mfma_f32_16x16x32_bf16 v[68:71], v[172:175], v[220:223], v[68:71]
	v_mfma_f32_16x16x32_bf16 v[64:67], v[182:185], v[220:223], v[64:67]
	s_setprio 0
	s_barrier
; #define PG8_STAGE(bufoff, gbase, voff) do { _Pragma("unroll") for (int _i = 0; _i < 2; ++_i) \
;         __builtin_amdgcn_global_load_lds((const unsigned*)((const char*)(gbase) + (voff)[_i]), (PG8_LAS unsigned*)(lds + (bufoff) + ldsw + _i * 8192), 16, 0, 0); } while (0)
; #define PG8_LDA(dst, b, h) do { _Pragma("unroll") for (int m = 0; m < 4; ++m) _Pragma("unroll") for (int k = 0; k < 2; ++k) dst[m][k] = *(const PG8_LAS bf16x8*)(lds + PG8_SA(b, h) + aoff + m * 2048 + k * 1024); } while (0)
; #define PG8_LDB(dst, b, h) do { _Pragma("unroll") for (int n = 0; n < 2; ++n) _Pragma("unroll") for (int k = 0; k < 2; ++k) dst[n][k] = *(const PG8_LAS bf16x8*)(lds + PG8_SB(b, h) + boff + n * 2048 + k * 1024); } while (0)
; #define PG8_MMA(ai, bj, At, Bt) do { __builtin_amdgcn_s_setprio(1); _Pragma("unroll") for (int m = 0; m < 4; ++m) _Pragma("unroll") for (int n = 0; n < 2; ++n) _Pragma("unroll") for (int k = 0; k < 2; ++k) \
;         acc[ai][bj][m][n] = __builtin_amdgcn_mfma_f32_16x16x32_bf16(Bt[n][k], At[m][k], acc[ai][bj][m][n], 0, 0, 0); __builtin_amdgcn_s_setprio(0); } while (0)
; #define PG8_WAIT_V(n) asm volatile("s_waitcnt vmcnt(" #n ")" ::: "memory")
; template <class Epi, class Sched, bool ALIGN_EPI = false, bool SP2 = false>
; __device__ __forceinline__ void gemm_phase(PG8_LAS unsigned char* lds, const Gemm g, const Sched& S, const Epi& E) {
;     ...
;             PG8_LDB(B0, 0, 0); PG8_LDB(B1, 0, 1); PG8_SCHED; PG8_LDA(At, 0, 0); PG8_STAGE(PG8_SA(1, 1), a1 + hstep, voffA);
;             PG8_WAIT_V(8); PG8_WAIT_L(0); PG8_BAR; PG8_MMA(0, 0, At, B0); PG8_MMA(0, 1, At, B1); PG8_BAR; PG8_SCHED;
;             PG8_LDA(At, 0, 1); PG8_STAGE(PG8_SB(0, 0), b2, voffB); PG8_STAGE(PG8_SB(0, 1), b2 + hstep, voffB); PG8_STAGE(PG8_SA(0, 0), a2, voffA);
;             PG8_WAIT_V(8); PG8_WAIT_L(0); PG8_BAR; PG8_MMA(1, 0, At, B0); PG8_MMA(1, 1, At, B1); PG8_BAR; PG8_SCHED;
;             PG8_LDB(B0, 1, 0); PG8_LDB(B1, 1, 1); PG8_SCHED; PG8_LDA(At, 1, 0); PG8_STAGE(PG8_SA(0, 1), a2 + hstep, voffA);
;             PG8_WAIT_V(8); PG8_WAIT_L(0); PG8_BAR; PG8_MMA(0, 0, At, B0); PG8_MMA(0, 1, At, B1); PG8_BAR; PG8_SCHED;
;             PG8_LDA(At, 1, 1); PG8_STAGE(PG8_SB(1, 0), b3, voffB); PG8_STAGE(PG8_SB(1, 1), b3 + hstep, voffB); PG8_STAGE(PG8_SA(1, 0), a3, voffA);
;             PG8_WAIT_V(8); PG8_WAIT_L(0); PG8_BAR; PG8_MMA(1, 0, At, B0); PG8_MMA(1, 1, At, B1); PG8_BAR; PG8_SCHED;
	s_add_i32 s50, s78, s3
	v_lshl_add_u64 v[202:203], v[202:203], 0, s[42:43]
	s_mov_b32 m0, s50
	ds_read_b128 v[186:189], v153 offset:49152
	ds_read_b128 v[190:193], v153 offset:50176
	ds_read_b128 v[194:197], v153 offset:51200
	ds_read_b128 v[198:201], v153 offset:52224
	ds_read_b128 v[208:211], v153 offset:53248
	ds_read_b128 v[212:215], v153 offset:54272
	ds_read_b128 v[216:219], v153 offset:55296
	ds_read_b128 v[220:223], v153 offset:56320
	global_load_lds_dwordx4 v[202:203], off
	s_add_i32 m0, s50, 0x2000
	s_add_u32 s50, s54, 0xb0080
	v_lshl_add_u64 v[202:203], v[224:225], 0, s[42:43]
	s_addc_u32 s51, s55, 0
	s_add_i32 s54, s79, s3
	global_load_lds_dwordx4 v[202:203], off
	v_lshl_add_u64 v[202:203], s[50:51], 0, v[130:131]
	s_mov_b32 m0, s54
	s_nop 0
	global_load_lds_dwordx4 v[202:203], off
	v_lshl_add_u64 v[202:203], s[50:51], 0, v[134:135]
	s_add_i32 m0, s54, 0x2000
	s_nop 0
	global_load_lds_dwordx4 v[202:203], off
	s_waitcnt vmcnt(6)
	s_waitcnt lgkmcnt(0)
	s_barrier
	s_setprio 1
	s_waitcnt lgkmcnt(0)
	v_mfma_f32_16x16x32_bf16 v[60:63], v[144:147], v[186:189], v[60:63]
	v_mfma_f32_16x16x32_bf16 v[56:59], v[160:163], v[186:189], v[56:59]
	v_mfma_f32_16x16x32_bf16 v[44:47], v[144:147], v[194:197], v[44:47]
	v_mfma_f32_16x16x32_bf16 v[40:43], v[160:163], v[194:197], v[40:43]
	v_mfma_f32_16x16x32_bf16 v[28:31], v[144:147], v[208:211], v[28:31]
	v_mfma_f32_16x16x32_bf16 v[24:27], v[160:163], v[208:211], v[24:27]
	v_mfma_f32_16x16x32_bf16 v[12:15], v[144:147], v[216:219], v[12:15]
	v_mfma_f32_16x16x32_bf16 v[8:11], v[160:163], v[216:219], v[8:11]
	v_mfma_f32_16x16x32_bf16 v[60:63], v[156:159], v[190:193], v[60:63]
	v_mfma_f32_16x16x32_bf16 v[56:59], v[164:167], v[190:193], v[56:59]
	v_mfma_f32_16x16x32_bf16 v[44:47], v[156:159], v[198:201], v[44:47]
	v_mfma_f32_16x16x32_bf16 v[40:43], v[164:167], v[198:201], v[40:43]
	v_mfma_f32_16x16x32_bf16 v[28:31], v[156:159], v[212:215], v[28:31]
	v_mfma_f32_16x16x32_bf16 v[24:27], v[164:167], v[212:215], v[24:27]
	v_lshl_add_u64 v[202:203], v[226:227], 0, s[42:43]
	s_mov_b32 m0, s59
	s_nop 0
	global_load_lds_dwordx4 v[202:203], off
	v_mfma_f32_16x16x32_bf16 v[12:15], v[156:159], v[220:223], v[12:15]
	v_mfma_f32_16x16x32_bf16 v[8:11], v[164:167], v[220:223], v[8:11]
	s_setprio 0
	s_setprio 1
	v_mfma_f32_16x16x32_bf16 v[52:55], v[168:171], v[186:189], v[52:55]
	v_mfma_f32_16x16x32_bf16 v[48:51], v[176:179], v[186:189], v[48:51]
	v_mfma_f32_16x16x32_bf16 v[36:39], v[168:171], v[194:197], v[36:39]
	v_mfma_f32_16x16x32_bf16 v[32:35], v[176:179], v[194:197], v[32:35]
	v_mfma_f32_16x16x32_bf16 v[20:23], v[168:171], v[208:211], v[20:23]
	v_mfma_f32_16x16x32_bf16 v[16:19], v[176:179], v[208:211], v[16:19]
	v_mfma_f32_16x16x32_bf16 v[4:7], v[168:171], v[216:219], v[4:7]
	v_mfma_f32_16x16x32_bf16 v[0:3], v[176:179], v[216:219], v[0:3]
	v_mfma_f32_16x16x32_bf16 v[52:55], v[172:175], v[190:193], v[52:55]
	v_mfma_f32_16x16x32_bf16 v[48:51], v[182:185], v[190:193], v[48:51]
	v_mfma_f32_16x16x32_bf16 v[36:39], v[172:175], v[198:201], v[36:39]
	v_mfma_f32_16x16x32_bf16 v[32:35], v[182:185], v[198:201], v[32:35]
	v_mfma_f32_16x16x32_bf16 v[20:23], v[172:175], v[212:215], v[20:23]
	v_mfma_f32_16x16x32_bf16 v[16:19], v[182:185], v[212:215], v[16:19]
	v_lshl_add_u64 v[202:203], v[228:229], 0, s[42:43]
	s_mov_b32 m0, s60
	s_nop 0
	global_load_lds_dwordx4 v[202:203], off
	v_mfma_f32_16x16x32_bf16 v[4:7], v[172:175], v[220:223], v[4:7]
	v_mfma_f32_16x16x32_bf16 v[0:3], v[182:185], v[220:223], v[0:3]
	s_setprio 0
	s_barrier
	s_add_i32 s77, s77, 2
	s_add_u32 s75, s75, 0x100
	s_addc_u32 s76, s76, 0
	s_mov_b64 s[50:51], s[52:53]
.LBB0_1035:
	ds_read_b128 v[144:147], v151
	ds_read_b128 v[156:159], v151 offset:1024
	ds_read_b128 v[160:163], v151 offset:2048
	ds_read_b128 v[164:167], v151 offset:3072
	ds_read_b128 v[168:171], v152
	ds_read_b128 v[172:175], v152 offset:1024
	ds_read_b128 v[176:179], v152 offset:2048
	ds_read_b128 v[182:185], v152 offset:3072
	s_add_u32 s52, s50, 0x100
	s_addc_u32 s53, s51, 0
	s_cmp_eq_u32 s77, 40
	s_cselect_b32 s57, s1, s53
	s_cselect_b32 s56, s0, s52
	s_cselect_b32 s55, s49, s76
	s_cselect_b32 s54, s48, s75
	v_lshl_add_u64 v[202:203], s[50:51], 0, v[136:137]
	s_add_i32 m0, s14, 0xc000
	ds_read_b128 v[186:189], v153
	ds_read_b128 v[190:193], v153 offset:1024
	ds_read_b128 v[194:197], v153 offset:2048
	ds_read_b128 v[198:201], v153 offset:3072
	ds_read_b128 v[208:211], v153 offset:4096
	ds_read_b128 v[212:215], v153 offset:5120
	ds_read_b128 v[216:219], v153 offset:6144
	ds_read_b128 v[220:223], v153 offset:7168
	global_load_lds_dwordx4 v[202:203], off
	v_lshl_add_u64 v[202:203], s[50:51], 0, v[138:139]
	s_add_i32 m0, s14, 0xe000
	s_nop 0
	global_load_lds_dwordx4 v[202:203], off
	s_waitcnt vmcnt(8)
	s_waitcnt lgkmcnt(0)
	s_barrier
; #define PG8_STAGE(bufoff, gbase, voff) do { _Pragma("unroll") for (int _i = 0; _i < 2; ++_i) \
;         __builtin_amdgcn_global_load_lds((const unsigned*)((const char*)(gbase) + (voff)[_i]), (PG8_LAS unsigned*)(lds + (bufoff) + ldsw + _i * 8192), 16, 0, 0); } while (0)
; #define PG8_LDA(dst, b, h) do { _Pragma("unroll") for (int m = 0; m < 4; ++m) _Pragma("unroll") for (int k = 0; k < 2; ++k) dst[m][k] = *(const PG8_LAS bf16x8*)(lds + PG8_SA(b, h) + aoff + m * 2048 + k * 1024); } while (0)
; #define PG8_LDB(dst, b, h) do { _Pragma("unroll") for (int n = 0; n < 2; ++n) _Pragma("unroll") for (int k = 0; k < 2; ++k) dst[n][k] = *(const PG8_LAS bf16x8*)(lds + PG8_SB(b, h) + boff + n * 2048 + k * 1024); } while (0)
; #define PG8_MMA(ai, bj, At, Bt) do { __builtin_amdgcn_s_setprio(1); _Pragma("unroll") for (int m = 0; m < 4; ++m) _Pragma("unroll") for (int n = 0; n < 2; ++n) _Pragma("unroll") for (int k = 0; k < 2; ++k) \
;         acc[ai][bj][m][n] = __builtin_amdgcn_mfma_f32_16x16x32_bf16(Bt[n][k], At[m][k], acc[ai][bj][m][n], 0, 0, 0); __builtin_amdgcn_s_setprio(0); } while (0)
; #define PG8_WAIT_V(n) asm volatile("s_waitcnt vmcnt(" #n ")" ::: "memory")
; #define PG8_WAIT_L(n) asm volatile("s_waitcnt lgkmcnt(" #n ")" ::: "memory")
; #define PG8_BAR __builtin_amdgcn_s_barrier()
; #define PG8_SCHED __builtin_amdgcn_sched_barrier(0)
; template <class Epi, class Sched, bool ALIGN_EPI = false, bool SP2 = false>
; __device__ __forceinline__ void gemm_phase(PG8_LAS unsigned char* lds, const Gemm g, const Sched& S, const Epi& E) {
;     ...
;             PG8_LDB(B0, 0, 0); PG8_LDB(B1, 0, 1); PG8_SCHED; PG8_LDA(At, 0, 0); PG8_STAGE(PG8_SA(1, 1), a1 + hstep, voffA);
;             PG8_WAIT_V(8); PG8_WAIT_L(0); PG8_BAR; PG8_MMA(0, 0, At, B0); PG8_MMA(0, 1, At, B1); PG8_BAR; PG8_SCHED;
;             PG8_LDA(At, 0, 1); PG8_STAGE(PG8_SB(0, 0), b2, voffB); PG8_STAGE(PG8_SB(0, 1), b2 + hstep, voffB); PG8_STAGE(PG8_SA(0, 0), a2, voffA);
;             PG8_WAIT_V(8); PG8_WAIT_L(0); PG8_BAR; PG8_MMA(1, 0, At, B0); PG8_MMA(1, 1, At, B1); PG8_BAR; PG8_SCHED;
	s_setprio 1
	s_waitcnt lgkmcnt(0)
	v_mfma_f32_16x16x32_bf16 v[124:127], v[144:147], v[186:189], v[124:127]
	v_mfma_f32_16x16x32_bf16 v[120:123], v[160:163], v[186:189], v[120:123]
	v_mfma_f32_16x16x32_bf16 v[108:111], v[144:147], v[194:197], v[108:111]
	v_mfma_f32_16x16x32_bf16 v[104:107], v[160:163], v[194:197], v[104:107]
	v_mfma_f32_16x16x32_bf16 v[92:95], v[144:147], v[208:211], v[92:95]
	v_mfma_f32_16x16x32_bf16 v[88:91], v[160:163], v[208:211], v[88:91]
	v_mfma_f32_16x16x32_bf16 v[76:79], v[144:147], v[216:219], v[76:79]
	v_mfma_f32_16x16x32_bf16 v[72:75], v[160:163], v[216:219], v[72:75]
	v_mfma_f32_16x16x32_bf16 v[124:127], v[156:159], v[190:193], v[124:127]
	v_mfma_f32_16x16x32_bf16 v[120:123], v[164:167], v[190:193], v[120:123]
	v_mfma_f32_16x16x32_bf16 v[108:111], v[156:159], v[198:201], v[108:111]
	v_mfma_f32_16x16x32_bf16 v[104:107], v[164:167], v[198:201], v[104:107]
	v_mfma_f32_16x16x32_bf16 v[92:95], v[156:159], v[212:215], v[92:95]
	v_mfma_f32_16x16x32_bf16 v[88:91], v[164:167], v[212:215], v[88:91]
	v_mfma_f32_16x16x32_bf16 v[76:79], v[156:159], v[220:223], v[76:79]
	v_mfma_f32_16x16x32_bf16 v[72:75], v[164:167], v[220:223], v[72:75]
	s_setprio 0
	s_setprio 1
	v_mfma_f32_16x16x32_bf16 v[116:119], v[168:171], v[186:189], v[116:119]
	v_mfma_f32_16x16x32_bf16 v[112:115], v[176:179], v[186:189], v[112:115]
	v_mfma_f32_16x16x32_bf16 v[100:103], v[168:171], v[194:197], v[100:103]
	v_mfma_f32_16x16x32_bf16 v[96:99], v[176:179], v[194:197], v[96:99]
	v_mfma_f32_16x16x32_bf16 v[84:87], v[168:171], v[208:211], v[84:87]
	v_mfma_f32_16x16x32_bf16 v[80:83], v[176:179], v[208:211], v[80:83]
	v_mfma_f32_16x16x32_bf16 v[68:71], v[168:171], v[216:219], v[68:71]
	v_mfma_f32_16x16x32_bf16 v[64:67], v[176:179], v[216:219], v[64:67]
	v_mfma_f32_16x16x32_bf16 v[116:119], v[172:175], v[190:193], v[116:119]
	v_mfma_f32_16x16x32_bf16 v[112:115], v[182:185], v[190:193], v[112:115]
	v_mfma_f32_16x16x32_bf16 v[100:103], v[172:175], v[198:201], v[100:103]
	v_mfma_f32_16x16x32_bf16 v[96:99], v[182:185], v[198:201], v[96:99]
	v_mfma_f32_16x16x32_bf16 v[84:87], v[172:175], v[212:215], v[84:87]
	v_mfma_f32_16x16x32_bf16 v[80:83], v[182:185], v[212:215], v[80:83]
	v_mfma_f32_16x16x32_bf16 v[68:71], v[172:175], v[220:223], v[68:71]
	v_mfma_f32_16x16x32_bf16 v[64:67], v[182:185], v[220:223], v[64:67]
	s_setprio 0
	s_barrier
	s_add_i32 s50, s61, s3
	v_lshl_add_u64 v[202:203], s[54:55], 0, v[130:131]
	s_mov_b32 m0, s50
	ds_read_b128 v[186:189], v153 offset:16384
	ds_read_b128 v[190:193], v153 offset:17408
	ds_read_b128 v[194:197], v153 offset:18432
	ds_read_b128 v[198:201], v153 offset:19456
	ds_read_b128 v[208:211], v153 offset:20480
	ds_read_b128 v[212:215], v153 offset:21504
	ds_read_b128 v[216:219], v153 offset:22528
	ds_read_b128 v[220:223], v153 offset:23552
	global_load_lds_dwordx4 v[202:203], off
	s_add_i32 m0, s50, 0x2000
	s_add_u32 s50, s54, 0xb0000
	v_lshl_add_u64 v[224:225], s[54:55], 0, v[134:135]
	s_addc_u32 s51, s55, 0
	s_add_i32 s78, s62, s3
	global_load_lds_dwordx4 v[224:225], off
	v_lshl_add_u64 v[226:227], s[50:51], 0, v[130:131]
	s_mov_b32 m0, s78
	global_load_lds_dwordx4 v[226:227], off
	v_lshl_add_u64 v[226:227], s[50:51], 0, v[134:135]
	s_add_i32 m0, s78, 0x2000
	s_nop 0
	global_load_lds_dwordx4 v[226:227], off
	s_waitcnt vmcnt(6)
	s_waitcnt lgkmcnt(0)
	s_barrier
	s_setprio 1
	s_waitcnt lgkmcnt(0)
	v_mfma_f32_16x16x32_bf16 v[60:63], v[144:147], v[186:189], v[60:63]
	v_mfma_f32_16x16x32_bf16 v[56:59], v[160:163], v[186:189], v[56:59]
	v_mfma_f32_16x16x32_bf16 v[44:47], v[144:147], v[194:197], v[44:47]
	v_mfma_f32_16x16x32_bf16 v[40:43], v[160:163], v[194:197], v[40:43]
	v_mfma_f32_16x16x32_bf16 v[28:31], v[144:147], v[208:211], v[28:31]
	v_mfma_f32_16x16x32_bf16 v[24:27], v[160:163], v[208:211], v[24:27]
	v_mfma_f32_16x16x32_bf16 v[12:15], v[144:147], v[216:219], v[12:15]
	v_mfma_f32_16x16x32_bf16 v[8:11], v[160:163], v[216:219], v[8:11]
	v_mfma_f32_16x16x32_bf16 v[60:63], v[156:159], v[190:193], v[60:63]
	v_mfma_f32_16x16x32_bf16 v[56:59], v[164:167], v[190:193], v[56:59]
	v_mfma_f32_16x16x32_bf16 v[44:47], v[156:159], v[198:201], v[44:47]
	v_mfma_f32_16x16x32_bf16 v[40:43], v[164:167], v[198:201], v[40:43]
	v_mfma_f32_16x16x32_bf16 v[28:31], v[156:159], v[212:215], v[28:31]
	v_mfma_f32_16x16x32_bf16 v[24:27], v[164:167], v[212:215], v[24:27]
	v_lshl_add_u64 v[226:227], s[56:57], 0, v[128:129]
	s_mov_b32 m0, s14
	s_nop 0
	global_load_lds_dwordx4 v[226:227], off
	v_mfma_f32_16x16x32_bf16 v[12:15], v[156:159], v[220:223], v[12:15]
	v_mfma_f32_16x16x32_bf16 v[8:11], v[164:167], v[220:223], v[8:11]
	s_setprio 0
	s_setprio 1
	v_mfma_f32_16x16x32_bf16 v[52:55], v[168:171], v[186:189], v[52:55]
	v_mfma_f32_16x16x32_bf16 v[48:51], v[176:179], v[186:189], v[48:51]
	v_mfma_f32_16x16x32_bf16 v[36:39], v[168:171], v[194:197], v[36:39]
	v_mfma_f32_16x16x32_bf16 v[32:35], v[176:179], v[194:197], v[32:35]
	v_mfma_f32_16x16x32_bf16 v[20:23], v[168:171], v[208:211], v[20:23]
	v_mfma_f32_16x16x32_bf16 v[16:19], v[176:179], v[208:211], v[16:19]
	v_mfma_f32_16x16x32_bf16 v[4:7], v[168:171], v[216:219], v[4:7]
	v_mfma_f32_16x16x32_bf16 v[0:3], v[176:179], v[216:219], v[0:3]
	v_mfma_f32_16x16x32_bf16 v[52:55], v[172:175], v[190:193], v[52:55]
	v_mfma_f32_16x16x32_bf16 v[48:51], v[182:185], v[190:193], v[48:51]
	v_mfma_f32_16x16x32_bf16 v[36:39], v[172:175], v[198:201], v[36:39]
	v_mfma_f32_16x16x32_bf16 v[32:35], v[182:185], v[198:201], v[32:35]
	v_mfma_f32_16x16x32_bf16 v[20:23], v[172:175], v[212:215], v[20:23]
	v_mfma_f32_16x16x32_bf16 v[16:19], v[182:185], v[212:215], v[16:19]
	v_lshl_add_u64 v[228:229], s[56:57], 0, v[132:133]
	s_mov_b32 m0, s15
	s_nop 0
	global_load_lds_dwordx4 v[228:229], off
	v_mfma_f32_16x16x32_bf16 v[4:7], v[172:175], v[220:223], v[4:7]
	v_mfma_f32_16x16x32_bf16 v[0:3], v[182:185], v[220:223], v[0:3]
	s_setprio 0
	s_barrier
; #define PG8_STAGE(bufoff, gbase, voff) do { _Pragma("unroll") for (int _i = 0; _i < 2; ++_i) \
;         __builtin_amdgcn_global_load_lds((const unsigned*)((const char*)(gbase) + (voff)[_i]), (PG8_LAS unsigned*)(lds + (bufoff) + ldsw + _i * 8192), 16, 0, 0); } while (0)
; #define PG8_LDA(dst, b, h) do { _Pragma("unroll") for (int m = 0; m < 4; ++m) _Pragma("unroll") for (int k = 0; k < 2; ++k) dst[m][k] = *(const PG8_LAS bf16x8*)(lds + PG8_SA(b, h) + aoff + m * 2048 + k * 1024); } while (0)
; #define PG8_LDB(dst, b, h) do { _Pragma("unroll") for (int n = 0; n < 2; ++n) _Pragma("unroll") for (int k = 0; k < 2; ++k) dst[n][k] = *(const PG8_LAS bf16x8*)(lds + PG8_SB(b, h) + boff + n * 2048 + k * 1024); } while (0)
; #define PG8_MMA(ai, bj, At, Bt) do { __builtin_amdgcn_s_setprio(1); _Pragma("unroll") for (int m = 0; m < 4; ++m) _Pragma("unroll") for (int n = 0; n < 2; ++n) _Pragma("unroll") for (int k = 0; k < 2; ++k) \
;         acc[ai][bj][m][n] = __builtin_amdgcn_mfma_f32_16x16x32_bf16(Bt[n][k], At[m][k], acc[ai][bj][m][n], 0, 0, 0); __builtin_amdgcn_s_setprio(0); } while (0)
; #define PG8_WAIT_V(n) asm volatile("s_waitcnt vmcnt(" #n ")" ::: "memory")
; #define PG8_WAIT_L(n) asm volatile("s_waitcnt lgkmcnt(" #n ")" ::: "memory")
; #define PG8_BAR __builtin_amdgcn_s_barrier()
; #define PG8_SCHED __builtin_amdgcn_sched_barrier(0)
; template <class Epi, class Sched, bool ALIGN_EPI = false, bool SP2 = false>
; __device__ __forceinline__ void gemm_phase(PG8_LAS unsigned char* lds, const Gemm g, const Sched& S, const Epi& E) {
;     ...
;             PG8_LDB(B0, 1, 0); PG8_LDB(B1, 1, 1); PG8_SCHED; PG8_LDA(At, 1, 0); PG8_STAGE(PG8_SA(0, 1), a2 + hstep, voffA);
;             PG8_WAIT_V(8); PG8_WAIT_L(0); PG8_BAR; PG8_MMA(0, 0, At, B0); PG8_MMA(0, 1, At, B1); PG8_BAR; PG8_SCHED;
	s_add_i32 s78, 0, 0x18000
	v_add_u32_e32 v155, s78, v149
	s_add_i32 s79, 0, 0x1c000
	ds_read_b128 v[144:147], v155
	ds_read_b128 v[156:159], v155 offset:1024
	ds_read_b128 v[160:163], v155 offset:2048
	ds_read_b128 v[164:167], v155 offset:3072
	v_add_u32_e32 v155, s79, v149
	ds_read_b128 v[168:171], v155
	ds_read_b128 v[172:175], v155 offset:1024
	ds_read_b128 v[176:179], v155 offset:2048
	ds_read_b128 v[182:185], v155 offset:3072
	s_add_u32 s50, s56, 0xb0000
	s_addc_u32 s51, s57, 0
	s_mov_b32 m0, s33
	v_lshl_add_u64 v[230:231], s[50:51], 0, v[128:129]
	ds_read_b128 v[186:189], v153 offset:32768
	ds_read_b128 v[190:193], v153 offset:33792
	ds_read_b128 v[194:197], v153 offset:34816
	ds_read_b128 v[198:201], v153 offset:35840
	ds_read_b128 v[208:211], v153 offset:36864
	ds_read_b128 v[212:215], v153 offset:37888
	ds_read_b128 v[216:219], v153 offset:38912
	ds_read_b128 v[220:223], v153 offset:39936
	global_load_lds_dwordx4 v[230:231], off
	v_lshl_add_u64 v[230:231], s[50:51], 0, v[132:133]
	s_mov_b32 m0, s34
	s_nop 0
	global_load_lds_dwordx4 v[230:231], off
	s_waitcnt vmcnt(8)
	s_waitcnt lgkmcnt(0)
	s_barrier
	s_setprio 1
	s_waitcnt lgkmcnt(0)
	v_mfma_f32_16x16x32_bf16 v[124:127], v[144:147], v[186:189], v[124:127]
	v_mfma_f32_16x16x32_bf16 v[120:123], v[160:163], v[186:189], v[120:123]
	v_mfma_f32_16x16x32_bf16 v[108:111], v[144:147], v[194:197], v[108:111]
	v_mfma_f32_16x16x32_bf16 v[104:107], v[160:163], v[194:197], v[104:107]
	v_mfma_f32_16x16x32_bf16 v[92:95], v[144:147], v[208:211], v[92:95]
	v_mfma_f32_16x16x32_bf16 v[88:91], v[160:163], v[208:211], v[88:91]
	v_mfma_f32_16x16x32_bf16 v[76:79], v[144:147], v[216:219], v[76:79]
	v_mfma_f32_16x16x32_bf16 v[72:75], v[160:163], v[216:219], v[72:75]
	v_mfma_f32_16x16x32_bf16 v[124:127], v[156:159], v[190:193], v[124:127]
	v_mfma_f32_16x16x32_bf16 v[120:123], v[164:167], v[190:193], v[120:123]
	v_mfma_f32_16x16x32_bf16 v[108:111], v[156:159], v[198:201], v[108:111]
	v_mfma_f32_16x16x32_bf16 v[104:107], v[164:167], v[198:201], v[104:107]
	v_mfma_f32_16x16x32_bf16 v[92:95], v[156:159], v[212:215], v[92:95]
	v_mfma_f32_16x16x32_bf16 v[88:91], v[164:167], v[212:215], v[88:91]
	v_mfma_f32_16x16x32_bf16 v[76:79], v[156:159], v[220:223], v[76:79]
	v_mfma_f32_16x16x32_bf16 v[72:75], v[164:167], v[220:223], v[72:75]
	s_setprio 0
	s_setprio 1
	v_mfma_f32_16x16x32_bf16 v[116:119], v[168:171], v[186:189], v[116:119]
	v_mfma_f32_16x16x32_bf16 v[112:115], v[176:179], v[186:189], v[112:115]
	v_mfma_f32_16x16x32_bf16 v[100:103], v[168:171], v[194:197], v[100:103]
	v_mfma_f32_16x16x32_bf16 v[96:99], v[176:179], v[194:197], v[96:99]
	v_mfma_f32_16x16x32_bf16 v[84:87], v[168:171], v[208:211], v[84:87]
	v_mfma_f32_16x16x32_bf16 v[80:83], v[176:179], v[208:211], v[80:83]
	v_mfma_f32_16x16x32_bf16 v[68:71], v[168:171], v[216:219], v[68:71]
	v_mfma_f32_16x16x32_bf16 v[64:67], v[176:179], v[216:219], v[64:67]
	v_mfma_f32_16x16x32_bf16 v[116:119], v[172:175], v[190:193], v[116:119]
	v_mfma_f32_16x16x32_bf16 v[112:115], v[182:185], v[190:193], v[112:115]
	v_mfma_f32_16x16x32_bf16 v[100:103], v[172:175], v[198:201], v[100:103]
	v_mfma_f32_16x16x32_bf16 v[96:99], v[182:185], v[198:201], v[96:99]
	v_mfma_f32_16x16x32_bf16 v[84:87], v[172:175], v[212:215], v[84:87]
	v_mfma_f32_16x16x32_bf16 v[80:83], v[182:185], v[212:215], v[80:83]
	v_mfma_f32_16x16x32_bf16 v[68:71], v[172:175], v[220:223], v[68:71]
	v_mfma_f32_16x16x32_bf16 v[64:67], v[182:185], v[220:223], v[64:67]
	s_setprio 0
	s_barrier
; #define PG8_STAGE(bufoff, gbase, voff) do { _Pragma("unroll") for (int _i = 0; _i < 2; ++_i) \
;         __builtin_amdgcn_global_load_lds((const unsigned*)((const char*)(gbase) + (voff)[_i]), (PG8_LAS unsigned*)(lds + (bufoff) + ldsw + _i * 8192), 16, 0, 0); } while (0)
; #define PG8_LDA(dst, b, h) do { _Pragma("unroll") for (int m = 0; m < 4; ++m) _Pragma("unroll") for (int k = 0; k < 2; ++k) dst[m][k] = *(const PG8_LAS bf16x8*)(lds + PG8_SA(b, h) + aoff + m * 2048 + k * 1024); } while (0)
; #define PG8_WAIT_V(n) asm volatile("s_waitcnt vmcnt(" #n ")" ::: "memory")
; template <class Epi, class Sched, bool ALIGN_EPI = false, bool SP2 = false>
; __device__ __forceinline__ void gemm_phase(PG8_LAS unsigned char* lds, const Gemm g, const Sched& S, const Epi& E) {
;     ...
;             PG8_LDA(At, 1, 1); PG8_STAGE(PG8_SB(1, 0), b3, voffB); PG8_STAGE(PG8_SB(1, 1), b3 + hstep, voffB); PG8_STAGE(PG8_SA(1, 0), a3, voffA);
;             PG8_WAIT_V(8); PG8_WAIT_L(0); PG8_BAR; PG8_MMA(1, 0, At, B0); PG8_MMA(1, 1, At, B1); PG8_BAR; PG8_SCHED;
;             } else {
;             PG8_LDB(B0, 0, 0); PG8_SCHED; PG8_LDA(At, 0, 0); PG8_STAGE(PG8_SA(1, 1), a1 + hstep, voffA);
;             PG8_WAIT_L(8); PG8_BAR; PG8_WAIT_L(0); PG8_MMA(0, 0, At, B0); PG8_BAR; PG8_SCHED;
;             PG8_LDB(B1, 0, 1); PG8_STAGE(PG8_SB(0, 0), b2, voffB);
;             PG8_BAR; PG8_WAIT_L(0); PG8_MMA(0, 1, At, B1); PG8_BAR;
;             PG8_LDA(At, 0, 1); PG8_STAGE(PG8_SA(0, 0), a2, voffA);
;             PG8_BAR; PG8_WAIT_L(0); PG8_MMA(1, 0, At, B0); PG8_BAR; PG8_SCHED;
;             PG8_STAGE(PG8_SB(0, 1), b2 + hstep, voffB);
;             PG8_WAIT_V(6); PG8_BAR; PG8_MMA(1, 1, At, B1); PG8_BAR;
;             PG8_LDB(B0, 1, 0); PG8_SCHED; PG8_LDA(At, 1, 0); PG8_STAGE(PG8_SA(0, 1), a2 + hstep, voffA);
;             PG8_WAIT_L(8); PG8_BAR; PG8_WAIT_L(0); PG8_MMA(0, 0, At, B0); PG8_BAR; PG8_SCHED;
;             PG8_LDB(B1, 1, 1); PG8_STAGE(PG8_SB(1, 0), b3, voffB);
;             PG8_BAR; PG8_WAIT_L(0); PG8_MMA(0, 1, At, B1); PG8_BAR;
;             PG8_LDA(At, 1, 1); PG8_STAGE(PG8_SA(1, 0), a3, voffA);
;             PG8_BAR; PG8_WAIT_L(0); PG8_MMA(1, 0, At, B0); PG8_BAR; PG8_SCHED;
;             PG8_STAGE(PG8_SB(1, 1), b3 + hstep, voffB);
;             PG8_WAIT_V(6); PG8_BAR; PG8_MMA(1, 1, At, B1); PG8_BAR;
;             }
;         }
;         if constexpr (ALIGN_EPI) { if (wr == 0) PG8_BAR; }
	s_add_i32 s50, s78, s3
	v_lshl_add_u64 v[202:203], v[202:203], 0, s[42:43]
	s_mov_b32 m0, s50
	ds_read_b128 v[186:189], v153 offset:49152
	ds_read_b128 v[190:193], v153 offset:50176
	ds_read_b128 v[194:197], v153 offset:51200
	ds_read_b128 v[198:201], v153 offset:52224
	ds_read_b128 v[208:211], v153 offset:53248
	ds_read_b128 v[212:215], v153 offset:54272
	ds_read_b128 v[216:219], v153 offset:55296
	ds_read_b128 v[220:223], v153 offset:56320
	global_load_lds_dwordx4 v[202:203], off
	s_add_i32 m0, s50, 0x2000
	s_add_u32 s50, s54, 0xb0080
	v_lshl_add_u64 v[202:203], v[224:225], 0, s[42:43]
	s_addc_u32 s51, s55, 0
	s_add_i32 s54, s79, s3
	global_load_lds_dwordx4 v[202:203], off
	v_lshl_add_u64 v[202:203], s[50:51], 0, v[130:131]
	s_mov_b32 m0, s54
	s_nop 0
	global_load_lds_dwordx4 v[202:203], off
	v_lshl_add_u64 v[202:203], s[50:51], 0, v[134:135]
	s_add_i32 m0, s54, 0x2000
	s_nop 0
	global_load_lds_dwordx4 v[202:203], off
	s_waitcnt vmcnt(6)
	s_waitcnt lgkmcnt(0)
	s_barrier
	s_setprio 1
	s_waitcnt lgkmcnt(0)
	v_mfma_f32_16x16x32_bf16 v[60:63], v[144:147], v[186:189], v[60:63]
	v_mfma_f32_16x16x32_bf16 v[56:59], v[160:163], v[186:189], v[56:59]
	v_mfma_f32_16x16x32_bf16 v[44:47], v[144:147], v[194:197], v[44:47]
	v_mfma_f32_16x16x32_bf16 v[40:43], v[160:163], v[194:197], v[40:43]
	v_mfma_f32_16x16x32_bf16 v[28:31], v[144:147], v[208:211], v[28:31]
	v_mfma_f32_16x16x32_bf16 v[24:27], v[160:163], v[208:211], v[24:27]
	v_mfma_f32_16x16x32_bf16 v[12:15], v[144:147], v[216:219], v[12:15]
	v_mfma_f32_16x16x32_bf16 v[8:11], v[160:163], v[216:219], v[8:11]
	v_mfma_f32_16x16x32_bf16 v[60:63], v[156:159], v[190:193], v[60:63]
	v_mfma_f32_16x16x32_bf16 v[56:59], v[164:167], v[190:193], v[56:59]
	v_mfma_f32_16x16x32_bf16 v[44:47], v[156:159], v[198:201], v[44:47]
	v_mfma_f32_16x16x32_bf16 v[40:43], v[164:167], v[198:201], v[40:43]
	v_mfma_f32_16x16x32_bf16 v[28:31], v[156:159], v[212:215], v[28:31]
	v_mfma_f32_16x16x32_bf16 v[24:27], v[164:167], v[212:215], v[24:27]
	v_lshl_add_u64 v[202:203], v[226:227], 0, s[42:43]
	s_mov_b32 m0, s59
	s_nop 0
	global_load_lds_dwordx4 v[202:203], off
	v_mfma_f32_16x16x32_bf16 v[12:15], v[156:159], v[220:223], v[12:15]
	v_mfma_f32_16x16x32_bf16 v[8:11], v[164:167], v[220:223], v[8:11]
	s_setprio 0
	s_setprio 1
	v_mfma_f32_16x16x32_bf16 v[52:55], v[168:171], v[186:189], v[52:55]
	v_mfma_f32_16x16x32_bf16 v[48:51], v[176:179], v[186:189], v[48:51]
	v_mfma_f32_16x16x32_bf16 v[36:39], v[168:171], v[194:197], v[36:39]
	v_mfma_f32_16x16x32_bf16 v[32:35], v[176:179], v[194:197], v[32:35]
	v_mfma_f32_16x16x32_bf16 v[20:23], v[168:171], v[208:211], v[20:23]
	v_mfma_f32_16x16x32_bf16 v[16:19], v[176:179], v[208:211], v[16:19]
	v_mfma_f32_16x16x32_bf16 v[4:7], v[168:171], v[216:219], v[4:7]
	v_mfma_f32_16x16x32_bf16 v[0:3], v[176:179], v[216:219], v[0:3]
	v_mfma_f32_16x16x32_bf16 v[52:55], v[172:175], v[190:193], v[52:55]
	v_mfma_f32_16x16x32_bf16 v[48:51], v[182:185], v[190:193], v[48:51]
	v_mfma_f32_16x16x32_bf16 v[36:39], v[172:175], v[198:201], v[36:39]
	v_mfma_f32_16x16x32_bf16 v[32:35], v[182:185], v[198:201], v[32:35]
	v_mfma_f32_16x16x32_bf16 v[20:23], v[172:175], v[212:215], v[20:23]
	v_mfma_f32_16x16x32_bf16 v[16:19], v[182:185], v[212:215], v[16:19]
	v_lshl_add_u64 v[202:203], v[228:229], 0, s[42:43]
	s_mov_b32 m0, s60
	s_nop 0
	global_load_lds_dwordx4 v[202:203], off
	v_mfma_f32_16x16x32_bf16 v[4:7], v[172:175], v[220:223], v[4:7]
	v_mfma_f32_16x16x32_bf16 v[0:3], v[182:185], v[220:223], v[0:3]
	s_setprio 0
	s_barrier
	s_add_i32 s77, s77, 2
	s_add_u32 s75, s75, 0x100
	s_addc_u32 s76, s76, 0
	s_cmp_gt_u32 s77, 41
	s_mov_b64 s[50:51], s[52:53]
	s_cbranch_scc0 .LBB0_1035
	s_and_b64 vcc, exec, s[44:45]
	s_cbranch_vccz .LBB0_1038
	s_barrier

; #define PG8_STAGE(bufoff, gbase, voff) do { _Pragma("unroll") for (int _i = 0; _i < 2; ++_i) \
;         __builtin_amdgcn_global_load_lds((const unsigned*)((const char*)(gbase) + (voff)[_i]), (PG8_LAS unsigned*)(lds + (bufoff) + ldsw + _i * 8192), 16, 0, 0); } while (0)
; #define PG8_LDA(dst, b, h) do { _Pragma("unroll") for (int m = 0; m < 4; ++m) _Pragma("unroll") for (int k = 0; k < 2; ++k) dst[m][k] = *(const PG8_LAS bf16x8*)(lds + PG8_SA(b, h) + aoff + m * 2048 + k * 1024); } while (0)
; #define PG8_LDB(dst, b, h) do { _Pragma("unroll") for (int n = 0; n < 2; ++n) _Pragma("unroll") for (int k = 0; k < 2; ++k) dst[n][k] = *(const PG8_LAS bf16x8*)(lds + PG8_SB(b, h) + boff + n * 2048 + k * 1024); } while (0)
; #define PG8_WAIT_V(n) asm volatile("s_waitcnt vmcnt(" #n ")" ::: "memory")
; #define PG8_WAIT_L(n) asm volatile("s_waitcnt lgkmcnt(" #n ")" ::: "memory")
; #define PG8_BAR __builtin_amdgcn_s_barrier()
; #define PG8_SCHED __builtin_amdgcn_sched_barrier(0)
; template <class Epi, class Sched, bool ALIGN_EPI = false, bool SP2 = false>
; __device__ __forceinline__ void gemm_phase(PG8_LAS unsigned char* lds, const Gemm g, const Sched& S, const Epi& E) {
;     ...
;         const bool has_next = S.next(ui + 1, nxt);
;         const char* nA = has_next ? (const char*)g.A + (size_t)nxt.pm * tstep : cA; const char* nB = has_next ? (const char*)g.Bt + (size_t)nxt.pn * tstep : cB;
;         for (int t = 0; t < nt; t += 2) {
;             const bool last = (t == nt - 2);
;             const char* a1 = cA + (size_t)(t + 1) * kstep;
;             const char* a2 = last ? nA : cA + (size_t)(t + 2) * kstep; const char* b2 = last ? nB : cB + (size_t)(t + 2) * kstep;
;             const char* a3 = a2 + kstep; const char* b3 = b2 + kstep;
;             if (last && has_next) S.a_ready(nxt);
;             if constexpr (SP2) {
;             PG8_LDB(B0, 0, 0); PG8_LDB(B1, 0, 1); PG8_SCHED; PG8_LDA(At, 0, 0); PG8_STAGE(PG8_SA(1, 1), a1 + hstep, voffA);
;             PG8_WAIT_V(8); PG8_WAIT_L(0); PG8_BAR; PG8_MMA(0, 0, At, B0); PG8_MMA(0, 1, At, B1); PG8_BAR; PG8_SCHED;
;             PG8_LDA(At, 0, 1); PG8_STAGE(PG8_SB(0, 0), b2, voffB); PG8_STAGE(PG8_SB(0, 1), b2 + hstep, voffB); PG8_STAGE(PG8_SA(0, 0), a2, voffA);
;             PG8_WAIT_V(8); PG8_WAIT_L(0); PG8_BAR; PG8_MMA(1, 0, At, B0); PG8_MMA(1, 1, At, B1); PG8_BAR; PG8_SCHED;
.LBB0_1118:
	s_ashr_i32 s45, s44, 31
	s_lshl_b64 s[48:49], s[44:45], 19
	s_add_u32 s48, s22, s48
	s_addc_u32 s49, s23, s49
	s_and_b64 s[50:51], s[10:11], exec
	s_cselect_b32 s45, s49, s55
	s_cselect_b32 s76, s48, s54
	s_ashr_i32 s43, s42, 31
	s_lshl_b64 s[50:51], s[42:43], 19
	s_add_u32 s50, s14, s50
	s_addc_u32 s51, s15, s51
	s_and_b64 s[58:59], s[10:11], exec
	s_cselect_b32 s43, s51, s57
	s_cselect_b32 s77, s50, s56
	s_add_u32 s54, s54, 0x40080
	s_addc_u32 s55, s55, 0
	s_add_u32 s82, s56, 0x100
	s_addc_u32 s83, s57, 0
	s_mov_b32 s84, -2
	ds_read_b128 v[144:147], v155
	ds_read_b128 v[148:151], v155 offset:1024
	ds_read_b128 v[160:163], v155 offset:2048
	ds_read_b128 v[164:167], v155 offset:3072
	ds_read_b128 v[168:171], v156
	ds_read_b128 v[172:175], v156 offset:1024
	ds_read_b128 v[176:179], v156 offset:2048
	ds_read_b128 v[182:185], v156 offset:3072
	s_add_u32 s56, s54, 0xfffc0080
	s_addc_u32 s57, s55, -1
	s_cmp_eq_u32 s84, 12
	s_cselect_b32 s59, s45, s57
	s_cselect_b32 s58, s76, s56
	s_cselect_b32 s57, s43, s83
	s_cselect_b32 s56, s77, s82
	v_lshl_add_u64 v[224:225], s[54:55], 0, v[136:137]
	s_add_i32 m0, s53, 0xc000
	ds_read_b128 v[186:189], v157
	ds_read_b128 v[190:193], v157 offset:1024
	ds_read_b128 v[194:197], v157 offset:2048
	ds_read_b128 v[198:201], v157 offset:3072
	ds_read_b128 v[208:211], v157 offset:4096
	ds_read_b128 v[212:215], v157 offset:5120
	ds_read_b128 v[216:219], v157 offset:6144
	ds_read_b128 v[220:223], v157 offset:7168
	global_load_lds_dwordx4 v[224:225], off
	v_lshl_add_u64 v[224:225], s[54:55], 0, v[138:139]
	s_add_i32 m0, s53, 0xe000
	s_nop 0
	global_load_lds_dwordx4 v[224:225], off
	s_waitcnt vmcnt(8)
	s_waitcnt lgkmcnt(0)
	s_barrier
	s_setprio 1
	s_waitcnt lgkmcnt(0)
	v_mfma_f32_16x16x32_bf16 v[124:127], v[144:147], v[186:189], 0
	v_mfma_f32_16x16x32_bf16 v[120:123], v[160:163], v[186:189], 0
	v_mfma_f32_16x16x32_bf16 v[108:111], v[144:147], v[194:197], 0
	v_mfma_f32_16x16x32_bf16 v[104:107], v[160:163], v[194:197], 0
	v_mfma_f32_16x16x32_bf16 v[92:95], v[144:147], v[208:211], 0
	v_mfma_f32_16x16x32_bf16 v[88:91], v[160:163], v[208:211], 0
	v_mfma_f32_16x16x32_bf16 v[76:79], v[144:147], v[216:219], 0
	v_mfma_f32_16x16x32_bf16 v[72:75], v[160:163], v[216:219], 0
	v_mfma_f32_16x16x32_bf16 v[124:127], v[148:151], v[190:193], v[124:127]
	v_mfma_f32_16x16x32_bf16 v[120:123], v[164:167], v[190:193], v[120:123]
	v_mfma_f32_16x16x32_bf16 v[108:111], v[148:151], v[198:201], v[108:111]
	v_mfma_f32_16x16x32_bf16 v[104:107], v[164:167], v[198:201], v[104:107]
	v_mfma_f32_16x16x32_bf16 v[92:95], v[148:151], v[212:215], v[92:95]
	v_mfma_f32_16x16x32_bf16 v[88:91], v[164:167], v[212:215], v[88:91]
	v_mfma_f32_16x16x32_bf16 v[76:79], v[148:151], v[220:223], v[76:79]
	v_mfma_f32_16x16x32_bf16 v[72:75], v[164:167], v[220:223], v[72:75]
	s_setprio 0
	s_setprio 1
	v_mfma_f32_16x16x32_bf16 v[116:119], v[168:171], v[186:189], 0
	v_mfma_f32_16x16x32_bf16 v[112:115], v[176:179], v[186:189], 0
	v_mfma_f32_16x16x32_bf16 v[100:103], v[168:171], v[194:197], 0
	v_mfma_f32_16x16x32_bf16 v[96:99], v[176:179], v[194:197], 0
	v_mfma_f32_16x16x32_bf16 v[84:87], v[168:171], v[208:211], 0
	v_mfma_f32_16x16x32_bf16 v[80:83], v[176:179], v[208:211], 0
	v_mfma_f32_16x16x32_bf16 v[68:71], v[168:171], v[216:219], 0
	v_mfma_f32_16x16x32_bf16 v[64:67], v[176:179], v[216:219], 0
	v_mfma_f32_16x16x32_bf16 v[116:119], v[172:175], v[190:193], v[116:119]
	v_mfma_f32_16x16x32_bf16 v[112:115], v[182:185], v[190:193], v[112:115]
	v_mfma_f32_16x16x32_bf16 v[100:103], v[172:175], v[198:201], v[100:103]
	v_mfma_f32_16x16x32_bf16 v[96:99], v[182:185], v[198:201], v[96:99]
	v_mfma_f32_16x16x32_bf16 v[84:87], v[172:175], v[212:215], v[84:87]
	v_mfma_f32_16x16x32_bf16 v[80:83], v[182:185], v[212:215], v[80:83]
	v_mfma_f32_16x16x32_bf16 v[68:71], v[172:175], v[220:223], v[68:71]
	v_mfma_f32_16x16x32_bf16 v[64:67], v[182:185], v[220:223], v[64:67]
	s_setprio 0
	s_barrier
	s_add_i32 s78, s66, s33
	v_lshl_add_u64 v[224:225], s[56:57], 0, v[132:133]
	s_mov_b32 m0, s78
	ds_read_b128 v[186:189], v157 offset:16384
	ds_read_b128 v[190:193], v157 offset:17408
	ds_read_b128 v[194:197], v157 offset:18432
	ds_read_b128 v[198:201], v157 offset:19456
	ds_read_b128 v[208:211], v157 offset:20480
	ds_read_b128 v[212:215], v157 offset:21504
	ds_read_b128 v[216:219], v157 offset:22528
	ds_read_b128 v[220:223], v157 offset:23552
	global_load_lds_dwordx4 v[224:225], off
	s_add_i32 m0, s78, 0x2000
	s_add_u32 s78, s56, 0x40000
	v_lshl_add_u64 v[226:227], s[56:57], 0, v[128:129]
	s_addc_u32 s79, s57, 0
	s_add_i32 s85, s67, s33
	global_load_lds_dwordx4 v[226:227], off
	v_lshl_add_u64 v[228:229], s[78:79], 0, v[132:133]
	s_mov_b32 m0, s85
	global_load_lds_dwordx4 v[228:229], off
	v_lshl_add_u64 v[228:229], s[78:79], 0, v[128:129]
	s_add_i32 m0, s85, 0x2000
	s_nop 0
	global_load_lds_dwordx4 v[228:229], off
	s_waitcnt vmcnt(6)
	s_waitcnt lgkmcnt(0)
	s_barrier
; #define PG8_STAGE(bufoff, gbase, voff) do { _Pragma("unroll") for (int _i = 0; _i < 2; ++_i) \
;         __builtin_amdgcn_global_load_lds((const unsigned*)((const char*)(gbase) + (voff)[_i]), (PG8_LAS unsigned*)(lds + (bufoff) + ldsw + _i * 8192), 16, 0, 0); } while (0)
; #define PG8_LDA(dst, b, h) do { _Pragma("unroll") for (int m = 0; m < 4; ++m) _Pragma("unroll") for (int k = 0; k < 2; ++k) dst[m][k] = *(const PG8_LAS bf16x8*)(lds + PG8_SA(b, h) + aoff + m * 2048 + k * 1024); } while (0)
; #define PG8_LDB(dst, b, h) do { _Pragma("unroll") for (int n = 0; n < 2; ++n) _Pragma("unroll") for (int k = 0; k < 2; ++k) dst[n][k] = *(const PG8_LAS bf16x8*)(lds + PG8_SB(b, h) + boff + n * 2048 + k * 1024); } while (0)
; #define PG8_MMA(ai, bj, At, Bt) do { __builtin_amdgcn_s_setprio(1); _Pragma("unroll") for (int m = 0; m < 4; ++m) _Pragma("unroll") for (int n = 0; n < 2; ++n) _Pragma("unroll") for (int k = 0; k < 2; ++k) \
;         acc[ai][bj][m][n] = __builtin_amdgcn_mfma_f32_16x16x32_bf16(Bt[n][k], At[m][k], acc[ai][bj][m][n], 0, 0, 0); __builtin_amdgcn_s_setprio(0); } while (0)
; #define PG8_WAIT_V(n) asm volatile("s_waitcnt vmcnt(" #n ")" ::: "memory")
; #define PG8_WAIT_L(n) asm volatile("s_waitcnt lgkmcnt(" #n ")" ::: "memory")
; #define PG8_BAR __builtin_amdgcn_s_barrier()
; #define PG8_SCHED __builtin_amdgcn_sched_barrier(0)
; template <class Epi, class Sched, bool ALIGN_EPI = false, bool SP2 = false>
; __device__ __forceinline__ void gemm_phase(PG8_LAS unsigned char* lds, const Gemm g, const Sched& S, const Epi& E) {
;     ...
;             PG8_LDA(At, 0, 1); PG8_STAGE(PG8_SB(0, 0), b2, voffB); PG8_STAGE(PG8_SB(0, 1), b2 + hstep, voffB); PG8_STAGE(PG8_SA(0, 0), a2, voffA);
;             PG8_WAIT_V(8); PG8_WAIT_L(0); PG8_BAR; PG8_MMA(1, 0, At, B0); PG8_MMA(1, 1, At, B1); PG8_BAR; PG8_SCHED;
;             PG8_LDB(B0, 1, 0); PG8_LDB(B1, 1, 1); PG8_SCHED; PG8_LDA(At, 1, 0); PG8_STAGE(PG8_SA(0, 1), a2 + hstep, voffA);
;             PG8_WAIT_V(8); PG8_WAIT_L(0); PG8_BAR; PG8_MMA(0, 0, At, B0); PG8_MMA(0, 1, At, B1); PG8_BAR; PG8_SCHED;
	s_setprio 1
	s_waitcnt lgkmcnt(0)
	v_mfma_f32_16x16x32_bf16 v[60:63], v[144:147], v[186:189], 0
	v_mfma_f32_16x16x32_bf16 v[56:59], v[160:163], v[186:189], 0
	v_mfma_f32_16x16x32_bf16 v[44:47], v[144:147], v[194:197], 0
	v_mfma_f32_16x16x32_bf16 v[40:43], v[160:163], v[194:197], 0
	v_mfma_f32_16x16x32_bf16 v[28:31], v[144:147], v[208:211], 0
	v_mfma_f32_16x16x32_bf16 v[24:27], v[160:163], v[208:211], 0
	v_mfma_f32_16x16x32_bf16 v[12:15], v[144:147], v[216:219], 0
	v_mfma_f32_16x16x32_bf16 v[8:11], v[160:163], v[216:219], 0
	v_mfma_f32_16x16x32_bf16 v[60:63], v[148:151], v[190:193], v[60:63]
	v_mfma_f32_16x16x32_bf16 v[56:59], v[164:167], v[190:193], v[56:59]
	v_mfma_f32_16x16x32_bf16 v[44:47], v[148:151], v[198:201], v[44:47]
	v_mfma_f32_16x16x32_bf16 v[40:43], v[164:167], v[198:201], v[40:43]
	v_mfma_f32_16x16x32_bf16 v[28:31], v[148:151], v[212:215], v[28:31]
	v_mfma_f32_16x16x32_bf16 v[24:27], v[164:167], v[212:215], v[24:27]
	v_lshl_add_u64 v[228:229], s[58:59], 0, v[134:135]
	s_mov_b32 m0, s53
	s_nop 0
	global_load_lds_dwordx4 v[228:229], off
	v_mfma_f32_16x16x32_bf16 v[12:15], v[148:151], v[220:223], v[12:15]
	v_mfma_f32_16x16x32_bf16 v[8:11], v[164:167], v[220:223], v[8:11]
	s_setprio 0
	s_setprio 1
	v_mfma_f32_16x16x32_bf16 v[52:55], v[168:171], v[186:189], 0
	v_mfma_f32_16x16x32_bf16 v[48:51], v[176:179], v[186:189], 0
	v_mfma_f32_16x16x32_bf16 v[36:39], v[168:171], v[194:197], 0
	v_mfma_f32_16x16x32_bf16 v[32:35], v[176:179], v[194:197], 0
	v_mfma_f32_16x16x32_bf16 v[20:23], v[168:171], v[208:211], 0
	v_mfma_f32_16x16x32_bf16 v[16:19], v[176:179], v[208:211], 0
	v_mfma_f32_16x16x32_bf16 v[4:7], v[168:171], v[216:219], 0
	v_mfma_f32_16x16x32_bf16 v[0:3], v[176:179], v[216:219], 0
	v_mfma_f32_16x16x32_bf16 v[52:55], v[172:175], v[190:193], v[52:55]
	v_mfma_f32_16x16x32_bf16 v[48:51], v[182:185], v[190:193], v[48:51]
	v_mfma_f32_16x16x32_bf16 v[36:39], v[172:175], v[198:201], v[36:39]
	v_mfma_f32_16x16x32_bf16 v[32:35], v[182:185], v[198:201], v[32:35]
	v_mfma_f32_16x16x32_bf16 v[20:23], v[172:175], v[212:215], v[20:23]
	v_mfma_f32_16x16x32_bf16 v[16:19], v[182:185], v[212:215], v[16:19]
	v_lshl_add_u64 v[230:231], s[58:59], 0, v[130:131]
	s_mov_b32 m0, s60
	s_nop 0
	global_load_lds_dwordx4 v[230:231], off
	v_mfma_f32_16x16x32_bf16 v[4:7], v[172:175], v[220:223], v[4:7]
	v_mfma_f32_16x16x32_bf16 v[0:3], v[182:185], v[220:223], v[0:3]
	s_setprio 0
	s_barrier
	s_add_i32 s78, 0, 0x18000
	v_add_u32_e32 v159, s78, v153
	s_add_i32 s79, 0, 0x1c000
	ds_read_b128 v[144:147], v159
	ds_read_b128 v[148:151], v159 offset:1024
	ds_read_b128 v[160:163], v159 offset:2048
	ds_read_b128 v[164:167], v159 offset:3072
	v_add_u32_e32 v159, s79, v153
	ds_read_b128 v[168:171], v159
	ds_read_b128 v[172:175], v159 offset:1024
	ds_read_b128 v[176:179], v159 offset:2048
	ds_read_b128 v[182:185], v159 offset:3072
	s_add_u32 s58, s58, 0x40000
	s_addc_u32 s59, s59, 0
	s_mov_b32 m0, s61
	v_lshl_add_u64 v[232:233], s[58:59], 0, v[134:135]
	ds_read_b128 v[186:189], v157 offset:32768
	ds_read_b128 v[190:193], v157 offset:33792
	ds_read_b128 v[194:197], v157 offset:34816
	ds_read_b128 v[198:201], v157 offset:35840
	ds_read_b128 v[208:211], v157 offset:36864
	ds_read_b128 v[212:215], v157 offset:37888
	ds_read_b128 v[216:219], v157 offset:38912
	ds_read_b128 v[220:223], v157 offset:39936
	global_load_lds_dwordx4 v[232:233], off
	v_lshl_add_u64 v[232:233], s[58:59], 0, v[130:131]
	s_mov_b32 m0, s62
	s_nop 0
	global_load_lds_dwordx4 v[232:233], off
	s_waitcnt vmcnt(8)
	s_waitcnt lgkmcnt(0)
	s_barrier
	s_setprio 1
	s_waitcnt lgkmcnt(0)
	v_mfma_f32_16x16x32_bf16 v[124:127], v[144:147], v[186:189], v[124:127]
	v_mfma_f32_16x16x32_bf16 v[120:123], v[160:163], v[186:189], v[120:123]
	v_mfma_f32_16x16x32_bf16 v[108:111], v[144:147], v[194:197], v[108:111]
	v_mfma_f32_16x16x32_bf16 v[104:107], v[160:163], v[194:197], v[104:107]
	v_mfma_f32_16x16x32_bf16 v[92:95], v[144:147], v[208:211], v[92:95]
	v_mfma_f32_16x16x32_bf16 v[88:91], v[160:163], v[208:211], v[88:91]
	v_mfma_f32_16x16x32_bf16 v[76:79], v[144:147], v[216:219], v[76:79]
	v_mfma_f32_16x16x32_bf16 v[72:75], v[160:163], v[216:219], v[72:75]
	v_mfma_f32_16x16x32_bf16 v[124:127], v[148:151], v[190:193], v[124:127]
	v_mfma_f32_16x16x32_bf16 v[120:123], v[164:167], v[190:193], v[120:123]
	v_mfma_f32_16x16x32_bf16 v[108:111], v[148:151], v[198:201], v[108:111]
	v_mfma_f32_16x16x32_bf16 v[104:107], v[164:167], v[198:201], v[104:107]
	v_mfma_f32_16x16x32_bf16 v[92:95], v[148:151], v[212:215], v[92:95]
	v_mfma_f32_16x16x32_bf16 v[88:91], v[164:167], v[212:215], v[88:91]
	v_mfma_f32_16x16x32_bf16 v[76:79], v[148:151], v[220:223], v[76:79]
	v_mfma_f32_16x16x32_bf16 v[72:75], v[164:167], v[220:223], v[72:75]
	s_setprio 0
	s_setprio 1
	v_mfma_f32_16x16x32_bf16 v[116:119], v[168:171], v[186:189], v[116:119]
	v_mfma_f32_16x16x32_bf16 v[112:115], v[176:179], v[186:189], v[112:115]
	v_mfma_f32_16x16x32_bf16 v[100:103], v[168:171], v[194:197], v[100:103]
	v_mfma_f32_16x16x32_bf16 v[96:99], v[176:179], v[194:197], v[96:99]
	v_mfma_f32_16x16x32_bf16 v[84:87], v[168:171], v[208:211], v[84:87]
	v_mfma_f32_16x16x32_bf16 v[80:83], v[176:179], v[208:211], v[80:83]
	v_mfma_f32_16x16x32_bf16 v[68:71], v[168:171], v[216:219], v[68:71]
	v_mfma_f32_16x16x32_bf16 v[64:67], v[176:179], v[216:219], v[64:67]
	v_mfma_f32_16x16x32_bf16 v[116:119], v[172:175], v[190:193], v[116:119]
	v_mfma_f32_16x16x32_bf16 v[112:115], v[182:185], v[190:193], v[112:115]
	v_mfma_f32_16x16x32_bf16 v[100:103], v[172:175], v[198:201], v[100:103]
	v_mfma_f32_16x16x32_bf16 v[96:99], v[182:185], v[198:201], v[96:99]
	v_mfma_f32_16x16x32_bf16 v[84:87], v[172:175], v[212:215], v[84:87]
	v_mfma_f32_16x16x32_bf16 v[80:83], v[182:185], v[212:215], v[80:83]
	v_mfma_f32_16x16x32_bf16 v[68:71], v[172:175], v[220:223], v[68:71]
	v_mfma_f32_16x16x32_bf16 v[64:67], v[182:185], v[220:223], v[64:67]
	s_setprio 0
	s_barrier
; #define PG8_STAGE(bufoff, gbase, voff) do { _Pragma("unroll") for (int _i = 0; _i < 2; ++_i) \
;         __builtin_amdgcn_global_load_lds((const unsigned*)((const char*)(gbase) + (voff)[_i]), (PG8_LAS unsigned*)(lds + (bufoff) + ldsw + _i * 8192), 16, 0, 0); } while (0)
; #define PG8_LDA(dst, b, h) do { _Pragma("unroll") for (int m = 0; m < 4; ++m) _Pragma("unroll") for (int k = 0; k < 2; ++k) dst[m][k] = *(const PG8_LAS bf16x8*)(lds + PG8_SA(b, h) + aoff + m * 2048 + k * 1024); } while (0)
; #define PG8_LDB(dst, b, h) do { _Pragma("unroll") for (int n = 0; n < 2; ++n) _Pragma("unroll") for (int k = 0; k < 2; ++k) dst[n][k] = *(const PG8_LAS bf16x8*)(lds + PG8_SB(b, h) + boff + n * 2048 + k * 1024); } while (0)
; #define PG8_MMA(ai, bj, At, Bt) do { __builtin_amdgcn_s_setprio(1); _Pragma("unroll") for (int m = 0; m < 4; ++m) _Pragma("unroll") for (int n = 0; n < 2; ++n) _Pragma("unroll") for (int k = 0; k < 2; ++k) \
;         acc[ai][bj][m][n] = __builtin_amdgcn_mfma_f32_16x16x32_bf16(Bt[n][k], At[m][k], acc[ai][bj][m][n], 0, 0, 0); __builtin_amdgcn_s_setprio(0); } while (0)
; #define PG8_WAIT_V(n) asm volatile("s_waitcnt vmcnt(" #n ")" ::: "memory")
; template <class Epi, class Sched, bool ALIGN_EPI = false, bool SP2 = false>
; __device__ __forceinline__ void gemm_phase(PG8_LAS unsigned char* lds, const Gemm g, const Sched& S, const Epi& E) {
;     ...
;             PG8_LDB(B0, 0, 0); PG8_LDB(B1, 0, 1); PG8_SCHED; PG8_LDA(At, 0, 0); PG8_STAGE(PG8_SA(1, 1), a1 + hstep, voffA);
;             PG8_WAIT_V(8); PG8_WAIT_L(0); PG8_BAR; PG8_MMA(0, 0, At, B0); PG8_MMA(0, 1, At, B1); PG8_BAR; PG8_SCHED;
;             PG8_LDA(At, 0, 1); PG8_STAGE(PG8_SB(0, 0), b2, voffB); PG8_STAGE(PG8_SB(0, 1), b2 + hstep, voffB); PG8_STAGE(PG8_SA(0, 0), a2, voffA);
;             PG8_WAIT_V(8); PG8_WAIT_L(0); PG8_BAR; PG8_MMA(1, 0, At, B0); PG8_MMA(1, 1, At, B1); PG8_BAR; PG8_SCHED;
;             PG8_LDB(B0, 1, 0); PG8_LDB(B1, 1, 1); PG8_SCHED; PG8_LDA(At, 1, 0); PG8_STAGE(PG8_SA(0, 1), a2 + hstep, voffA);
;             PG8_WAIT_V(8); PG8_WAIT_L(0); PG8_BAR; PG8_MMA(0, 0, At, B0); PG8_MMA(0, 1, At, B1); PG8_BAR; PG8_SCHED;
;             PG8_LDA(At, 1, 1); PG8_STAGE(PG8_SB(1, 0), b3, voffB); PG8_STAGE(PG8_SB(1, 1), b3 + hstep, voffB); PG8_STAGE(PG8_SA(1, 0), a3, voffA);
;             PG8_WAIT_V(8); PG8_WAIT_L(0); PG8_BAR; PG8_MMA(1, 0, At, B0); PG8_MMA(1, 1, At, B1); PG8_BAR; PG8_SCHED;
	s_add_i32 s58, s78, s33
	v_lshl_add_u64 v[224:225], v[224:225], 0, s[12:13]
	s_mov_b32 m0, s58
	ds_read_b128 v[186:189], v157 offset:49152
	ds_read_b128 v[190:193], v157 offset:50176
	ds_read_b128 v[194:197], v157 offset:51200
	ds_read_b128 v[198:201], v157 offset:52224
	ds_read_b128 v[208:211], v157 offset:53248
	ds_read_b128 v[212:215], v157 offset:54272
	ds_read_b128 v[216:219], v157 offset:55296
	ds_read_b128 v[220:223], v157 offset:56320
	global_load_lds_dwordx4 v[224:225], off
	s_add_i32 m0, s58, 0x2000
	s_add_u32 s56, s56, 0x40080
	v_lshl_add_u64 v[224:225], v[226:227], 0, s[12:13]
	s_addc_u32 s57, s57, 0
	s_add_i32 s58, s79, s33
	global_load_lds_dwordx4 v[224:225], off
	v_lshl_add_u64 v[224:225], s[56:57], 0, v[132:133]
	s_mov_b32 m0, s58
	s_nop 0
	global_load_lds_dwordx4 v[224:225], off
	v_lshl_add_u64 v[224:225], s[56:57], 0, v[128:129]
	s_add_i32 m0, s58, 0x2000
	s_nop 0
	global_load_lds_dwordx4 v[224:225], off
	s_waitcnt vmcnt(6)
	s_waitcnt lgkmcnt(0)
	s_barrier
	s_setprio 1
	s_waitcnt lgkmcnt(0)
	v_mfma_f32_16x16x32_bf16 v[60:63], v[144:147], v[186:189], v[60:63]
	v_mfma_f32_16x16x32_bf16 v[56:59], v[160:163], v[186:189], v[56:59]
	v_mfma_f32_16x16x32_bf16 v[44:47], v[144:147], v[194:197], v[44:47]
	v_mfma_f32_16x16x32_bf16 v[40:43], v[160:163], v[194:197], v[40:43]
	v_mfma_f32_16x16x32_bf16 v[28:31], v[144:147], v[208:211], v[28:31]
	v_mfma_f32_16x16x32_bf16 v[24:27], v[160:163], v[208:211], v[24:27]
	v_mfma_f32_16x16x32_bf16 v[12:15], v[144:147], v[216:219], v[12:15]
	v_mfma_f32_16x16x32_bf16 v[8:11], v[160:163], v[216:219], v[8:11]
	v_mfma_f32_16x16x32_bf16 v[60:63], v[148:151], v[190:193], v[60:63]
	v_mfma_f32_16x16x32_bf16 v[56:59], v[164:167], v[190:193], v[56:59]
	v_mfma_f32_16x16x32_bf16 v[44:47], v[148:151], v[198:201], v[44:47]
	v_mfma_f32_16x16x32_bf16 v[40:43], v[164:167], v[198:201], v[40:43]
	v_mfma_f32_16x16x32_bf16 v[28:31], v[148:151], v[212:215], v[28:31]
	v_mfma_f32_16x16x32_bf16 v[24:27], v[164:167], v[212:215], v[24:27]
	v_lshl_add_u64 v[224:225], v[228:229], 0, s[12:13]
	s_mov_b32 m0, s64
	s_nop 0
	global_load_lds_dwordx4 v[224:225], off
	v_mfma_f32_16x16x32_bf16 v[12:15], v[148:151], v[220:223], v[12:15]
	v_mfma_f32_16x16x32_bf16 v[8:11], v[164:167], v[220:223], v[8:11]
	s_setprio 0
	s_setprio 1
	v_mfma_f32_16x16x32_bf16 v[52:55], v[168:171], v[186:189], v[52:55]
	v_mfma_f32_16x16x32_bf16 v[48:51], v[176:179], v[186:189], v[48:51]
	v_mfma_f32_16x16x32_bf16 v[36:39], v[168:171], v[194:197], v[36:39]
	v_mfma_f32_16x16x32_bf16 v[32:35], v[176:179], v[194:197], v[32:35]
	v_mfma_f32_16x16x32_bf16 v[20:23], v[168:171], v[208:211], v[20:23]
	v_mfma_f32_16x16x32_bf16 v[16:19], v[176:179], v[208:211], v[16:19]
	v_mfma_f32_16x16x32_bf16 v[4:7], v[168:171], v[216:219], v[4:7]
	v_mfma_f32_16x16x32_bf16 v[0:3], v[176:179], v[216:219], v[0:3]
	v_mfma_f32_16x16x32_bf16 v[52:55], v[172:175], v[190:193], v[52:55]
	v_mfma_f32_16x16x32_bf16 v[48:51], v[182:185], v[190:193], v[48:51]
	v_mfma_f32_16x16x32_bf16 v[36:39], v[172:175], v[198:201], v[36:39]
	v_mfma_f32_16x16x32_bf16 v[32:35], v[182:185], v[198:201], v[32:35]
	v_mfma_f32_16x16x32_bf16 v[20:23], v[172:175], v[212:215], v[20:23]
	v_mfma_f32_16x16x32_bf16 v[16:19], v[182:185], v[212:215], v[16:19]
	v_lshl_add_u64 v[224:225], v[230:231], 0, s[12:13]
	s_mov_b32 m0, s65
	s_nop 0
	global_load_lds_dwordx4 v[224:225], off
	v_mfma_f32_16x16x32_bf16 v[4:7], v[172:175], v[220:223], v[4:7]
	v_mfma_f32_16x16x32_bf16 v[0:3], v[182:185], v[220:223], v[0:3]
	s_setprio 0
	s_barrier
	s_add_i32 s84, s84, 2
	s_add_u32 s54, s54, 0x100
	s_addc_u32 s55, s55, 0
	s_add_u32 s82, s82, 0x100
	s_addc_u32 s83, s83, 0
.LBB0_1119:
	ds_read_b128 v[144:147], v155
	ds_read_b128 v[148:151], v155 offset:1024
	ds_read_b128 v[160:163], v155 offset:2048
	ds_read_b128 v[164:167], v155 offset:3072
	ds_read_b128 v[168:171], v156
	ds_read_b128 v[172:175], v156 offset:1024
	ds_read_b128 v[176:179], v156 offset:2048
	ds_read_b128 v[182:185], v156 offset:3072
	s_add_u32 s56, s54, 0xfffc0080
	s_addc_u32 s57, s55, -1
	s_cmp_eq_u32 s84, 12
	s_cselect_b32 s59, s45, s57
	s_cselect_b32 s58, s76, s56
	s_cselect_b32 s57, s43, s83
	s_cselect_b32 s56, s77, s82
	v_lshl_add_u64 v[224:225], s[54:55], 0, v[136:137]
	s_add_i32 m0, s53, 0xc000
	ds_read_b128 v[186:189], v157
	ds_read_b128 v[190:193], v157 offset:1024
	ds_read_b128 v[194:197], v157 offset:2048
	ds_read_b128 v[198:201], v157 offset:3072
	ds_read_b128 v[208:211], v157 offset:4096
	ds_read_b128 v[212:215], v157 offset:5120
	ds_read_b128 v[216:219], v157 offset:6144
	ds_read_b128 v[220:223], v157 offset:7168
	global_load_lds_dwordx4 v[224:225], off
	v_lshl_add_u64 v[224:225], s[54:55], 0, v[138:139]
	s_add_i32 m0, s53, 0xe000
	s_nop 0
	global_load_lds_dwordx4 v[224:225], off
	s_waitcnt vmcnt(8)
	s_waitcnt lgkmcnt(0)
	s_barrier
; #define PG8_STAGE(bufoff, gbase, voff) do { _Pragma("unroll") for (int _i = 0; _i < 2; ++_i) \
;         __builtin_amdgcn_global_load_lds((const unsigned*)((const char*)(gbase) + (voff)[_i]), (PG8_LAS unsigned*)(lds + (bufoff) + ldsw + _i * 8192), 16, 0, 0); } while (0)
; #define PG8_LDA(dst, b, h) do { _Pragma("unroll") for (int m = 0; m < 4; ++m) _Pragma("unroll") for (int k = 0; k < 2; ++k) dst[m][k] = *(const PG8_LAS bf16x8*)(lds + PG8_SA(b, h) + aoff + m * 2048 + k * 1024); } while (0)
; #define PG8_LDB(dst, b, h) do { _Pragma("unroll") for (int n = 0; n < 2; ++n) _Pragma("unroll") for (int k = 0; k < 2; ++k) dst[n][k] = *(const PG8_LAS bf16x8*)(lds + PG8_SB(b, h) + boff + n * 2048 + k * 1024); } while (0)
; #define PG8_MMA(ai, bj, At, Bt) do { __builtin_amdgcn_s_setprio(1); _Pragma("unroll") for (int m = 0; m < 4; ++m) _Pragma("unroll") for (int n = 0; n < 2; ++n) _Pragma("unroll") for (int k = 0; k < 2; ++k) \
;         acc[ai][bj][m][n] = __builtin_amdgcn_mfma_f32_16x16x32_bf16(Bt[n][k], At[m][k], acc[ai][bj][m][n], 0, 0, 0); __builtin_amdgcn_s_setprio(0); } while (0)
; #define PG8_WAIT_V(n) asm volatile("s_waitcnt vmcnt(" #n ")" ::: "memory")
; #define PG8_WAIT_L(n) asm volatile("s_waitcnt lgkmcnt(" #n ")" ::: "memory")
; #define PG8_BAR __builtin_amdgcn_s_barrier()
; #define PG8_SCHED __builtin_amdgcn_sched_barrier(0)
; template <class Epi, class Sched, bool ALIGN_EPI = false, bool SP2 = false>
; __device__ __forceinline__ void gemm_phase(PG8_LAS unsigned char* lds, const Gemm g, const Sched& S, const Epi& E) {
;     ...
;             PG8_LDB(B0, 0, 0); PG8_LDB(B1, 0, 1); PG8_SCHED; PG8_LDA(At, 0, 0); PG8_STAGE(PG8_SA(1, 1), a1 + hstep, voffA);
;             PG8_WAIT_V(8); PG8_WAIT_L(0); PG8_BAR; PG8_MMA(0, 0, At, B0); PG8_MMA(0, 1, At, B1); PG8_BAR; PG8_SCHED;
;             PG8_LDA(At, 0, 1); PG8_STAGE(PG8_SB(0, 0), b2, voffB); PG8_STAGE(PG8_SB(0, 1), b2 + hstep, voffB); PG8_STAGE(PG8_SA(0, 0), a2, voffA);
;             PG8_WAIT_V(8); PG8_WAIT_L(0); PG8_BAR; PG8_MMA(1, 0, At, B0); PG8_MMA(1, 1, At, B1); PG8_BAR; PG8_SCHED;
	s_setprio 1
	s_waitcnt lgkmcnt(0)
	v_mfma_f32_16x16x32_bf16 v[124:127], v[144:147], v[186:189], v[124:127]
	v_mfma_f32_16x16x32_bf16 v[120:123], v[160:163], v[186:189], v[120:123]
	v_mfma_f32_16x16x32_bf16 v[108:111], v[144:147], v[194:197], v[108:111]
	v_mfma_f32_16x16x32_bf16 v[104:107], v[160:163], v[194:197], v[104:107]
	v_mfma_f32_16x16x32_bf16 v[92:95], v[144:147], v[208:211], v[92:95]
	v_mfma_f32_16x16x32_bf16 v[88:91], v[160:163], v[208:211], v[88:91]
	v_mfma_f32_16x16x32_bf16 v[76:79], v[144:147], v[216:219], v[76:79]
	v_mfma_f32_16x16x32_bf16 v[72:75], v[160:163], v[216:219], v[72:75]
	v_mfma_f32_16x16x32_bf16 v[124:127], v[148:151], v[190:193], v[124:127]
	v_mfma_f32_16x16x32_bf16 v[120:123], v[164:167], v[190:193], v[120:123]
	v_mfma_f32_16x16x32_bf16 v[108:111], v[148:151], v[198:201], v[108:111]
	v_mfma_f32_16x16x32_bf16 v[104:107], v[164:167], v[198:201], v[104:107]
	v_mfma_f32_16x16x32_bf16 v[92:95], v[148:151], v[212:215], v[92:95]
	v_mfma_f32_16x16x32_bf16 v[88:91], v[164:167], v[212:215], v[88:91]
	v_mfma_f32_16x16x32_bf16 v[76:79], v[148:151], v[220:223], v[76:79]
	v_mfma_f32_16x16x32_bf16 v[72:75], v[164:167], v[220:223], v[72:75]
	s_setprio 0
	s_setprio 1
	v_mfma_f32_16x16x32_bf16 v[116:119], v[168:171], v[186:189], v[116:119]
	v_mfma_f32_16x16x32_bf16 v[112:115], v[176:179], v[186:189], v[112:115]
	v_mfma_f32_16x16x32_bf16 v[100:103], v[168:171], v[194:197], v[100:103]
	v_mfma_f32_16x16x32_bf16 v[96:99], v[176:179], v[194:197], v[96:99]
	v_mfma_f32_16x16x32_bf16 v[84:87], v[168:171], v[208:211], v[84:87]
	v_mfma_f32_16x16x32_bf16 v[80:83], v[176:179], v[208:211], v[80:83]
	v_mfma_f32_16x16x32_bf16 v[68:71], v[168:171], v[216:219], v[68:71]
	v_mfma_f32_16x16x32_bf16 v[64:67], v[176:179], v[216:219], v[64:67]
	v_mfma_f32_16x16x32_bf16 v[116:119], v[172:175], v[190:193], v[116:119]
	v_mfma_f32_16x16x32_bf16 v[112:115], v[182:185], v[190:193], v[112:115]
	v_mfma_f32_16x16x32_bf16 v[100:103], v[172:175], v[198:201], v[100:103]
	v_mfma_f32_16x16x32_bf16 v[96:99], v[182:185], v[198:201], v[96:99]
	v_mfma_f32_16x16x32_bf16 v[84:87], v[172:175], v[212:215], v[84:87]
	v_mfma_f32_16x16x32_bf16 v[80:83], v[182:185], v[212:215], v[80:83]
	v_mfma_f32_16x16x32_bf16 v[68:71], v[172:175], v[220:223], v[68:71]
	v_mfma_f32_16x16x32_bf16 v[64:67], v[182:185], v[220:223], v[64:67]
	s_setprio 0
	s_barrier
	s_add_i32 s78, s66, s33
	v_lshl_add_u64 v[224:225], s[56:57], 0, v[132:133]
	s_mov_b32 m0, s78
	ds_read_b128 v[186:189], v157 offset:16384
	ds_read_b128 v[190:193], v157 offset:17408
	ds_read_b128 v[194:197], v157 offset:18432
	ds_read_b128 v[198:201], v157 offset:19456
	ds_read_b128 v[208:211], v157 offset:20480
	ds_read_b128 v[212:215], v157 offset:21504
	ds_read_b128 v[216:219], v157 offset:22528
	ds_read_b128 v[220:223], v157 offset:23552
	global_load_lds_dwordx4 v[224:225], off
	s_add_i32 m0, s78, 0x2000
	s_add_u32 s78, s56, 0x40000
	v_lshl_add_u64 v[226:227], s[56:57], 0, v[128:129]
	s_addc_u32 s79, s57, 0
	s_add_i32 s85, s67, s33
	global_load_lds_dwordx4 v[226:227], off
	v_lshl_add_u64 v[228:229], s[78:79], 0, v[132:133]
	s_mov_b32 m0, s85
	global_load_lds_dwordx4 v[228:229], off
	v_lshl_add_u64 v[228:229], s[78:79], 0, v[128:129]
	s_add_i32 m0, s85, 0x2000
	s_nop 0
	global_load_lds_dwordx4 v[228:229], off
	s_waitcnt vmcnt(6)
	s_waitcnt lgkmcnt(0)
	s_barrier
	s_setprio 1
	s_waitcnt lgkmcnt(0)
	v_mfma_f32_16x16x32_bf16 v[60:63], v[144:147], v[186:189], v[60:63]
	v_mfma_f32_16x16x32_bf16 v[56:59], v[160:163], v[186:189], v[56:59]
	v_mfma_f32_16x16x32_bf16 v[44:47], v[144:147], v[194:197], v[44:47]
	v_mfma_f32_16x16x32_bf16 v[40:43], v[160:163], v[194:197], v[40:43]
	v_mfma_f32_16x16x32_bf16 v[28:31], v[144:147], v[208:211], v[28:31]
	v_mfma_f32_16x16x32_bf16 v[24:27], v[160:163], v[208:211], v[24:27]
	v_mfma_f32_16x16x32_bf16 v[12:15], v[144:147], v[216:219], v[12:15]
	v_mfma_f32_16x16x32_bf16 v[8:11], v[160:163], v[216:219], v[8:11]
	v_mfma_f32_16x16x32_bf16 v[60:63], v[148:151], v[190:193], v[60:63]
	v_mfma_f32_16x16x32_bf16 v[56:59], v[164:167], v[190:193], v[56:59]
	v_mfma_f32_16x16x32_bf16 v[44:47], v[148:151], v[198:201], v[44:47]
	v_mfma_f32_16x16x32_bf16 v[40:43], v[164:167], v[198:201], v[40:43]
	v_mfma_f32_16x16x32_bf16 v[28:31], v[148:151], v[212:215], v[28:31]
	v_mfma_f32_16x16x32_bf16 v[24:27], v[164:167], v[212:215], v[24:27]
	v_lshl_add_u64 v[228:229], s[58:59], 0, v[134:135]
	s_mov_b32 m0, s53
	s_nop 0
	global_load_lds_dwordx4 v[228:229], off
	v_mfma_f32_16x16x32_bf16 v[12:15], v[148:151], v[220:223], v[12:15]
	v_mfma_f32_16x16x32_bf16 v[8:11], v[164:167], v[220:223], v[8:11]
	s_setprio 0
	s_setprio 1
	v_mfma_f32_16x16x32_bf16 v[52:55], v[168:171], v[186:189], v[52:55]
	v_mfma_f32_16x16x32_bf16 v[48:51], v[176:179], v[186:189], v[48:51]
	v_mfma_f32_16x16x32_bf16 v[36:39], v[168:171], v[194:197], v[36:39]
	v_mfma_f32_16x16x32_bf16 v[32:35], v[176:179], v[194:197], v[32:35]
	v_mfma_f32_16x16x32_bf16 v[20:23], v[168:171], v[208:211], v[20:23]
	v_mfma_f32_16x16x32_bf16 v[16:19], v[176:179], v[208:211], v[16:19]
	v_mfma_f32_16x16x32_bf16 v[4:7], v[168:171], v[216:219], v[4:7]
	v_mfma_f32_16x16x32_bf16 v[0:3], v[176:179], v[216:219], v[0:3]
	v_mfma_f32_16x16x32_bf16 v[52:55], v[172:175], v[190:193], v[52:55]
	v_mfma_f32_16x16x32_bf16 v[48:51], v[182:185], v[190:193], v[48:51]
	v_mfma_f32_16x16x32_bf16 v[36:39], v[172:175], v[198:201], v[36:39]
	v_mfma_f32_16x16x32_bf16 v[32:35], v[182:185], v[198:201], v[32:35]
	v_mfma_f32_16x16x32_bf16 v[20:23], v[172:175], v[212:215], v[20:23]
	v_mfma_f32_16x16x32_bf16 v[16:19], v[182:185], v[212:215], v[16:19]
	v_lshl_add_u64 v[230:231], s[58:59], 0, v[130:131]
	s_mov_b32 m0, s60
	s_nop 0
	global_load_lds_dwordx4 v[230:231], off
	v_mfma_f32_16x16x32_bf16 v[4:7], v[172:175], v[220:223], v[4:7]
	v_mfma_f32_16x16x32_bf16 v[0:3], v[182:185], v[220:223], v[0:3]
	s_setprio 0
	s_barrier
; #define PG8_STAGE(bufoff, gbase, voff) do { _Pragma("unroll") for (int _i = 0; _i < 2; ++_i) \
;         __builtin_amdgcn_global_load_lds((const unsigned*)((const char*)(gbase) + (voff)[_i]), (PG8_LAS unsigned*)(lds + (bufoff) + ldsw + _i * 8192), 16, 0, 0); } while (0)
; #define PG8_LDA(dst, b, h) do { _Pragma("unroll") for (int m = 0; m < 4; ++m) _Pragma("unroll") for (int k = 0; k < 2; ++k) dst[m][k] = *(const PG8_LAS bf16x8*)(lds + PG8_SA(b, h) + aoff + m * 2048 + k * 1024); } while (0)
; #define PG8_LDB(dst, b, h) do { _Pragma("unroll") for (int n = 0; n < 2; ++n) _Pragma("unroll") for (int k = 0; k < 2; ++k) dst[n][k] = *(const PG8_LAS bf16x8*)(lds + PG8_SB(b, h) + boff + n * 2048 + k * 1024); } while (0)
; #define PG8_MMA(ai, bj, At, Bt) do { __builtin_amdgcn_s_setprio(1); _Pragma("unroll") for (int m = 0; m < 4; ++m) _Pragma("unroll") for (int n = 0; n < 2; ++n) _Pragma("unroll") for (int k = 0; k < 2; ++k) \
;         acc[ai][bj][m][n] = __builtin_amdgcn_mfma_f32_16x16x32_bf16(Bt[n][k], At[m][k], acc[ai][bj][m][n], 0, 0, 0); __builtin_amdgcn_s_setprio(0); } while (0)
; #define PG8_WAIT_V(n) asm volatile("s_waitcnt vmcnt(" #n ")" ::: "memory")
; #define PG8_WAIT_L(n) asm volatile("s_waitcnt lgkmcnt(" #n ")" ::: "memory")
; #define PG8_BAR __builtin_amdgcn_s_barrier()
; #define PG8_SCHED __builtin_amdgcn_sched_barrier(0)
; template <class Epi, class Sched, bool ALIGN_EPI = false, bool SP2 = false>
; __device__ __forceinline__ void gemm_phase(PG8_LAS unsigned char* lds, const Gemm g, const Sched& S, const Epi& E) {
;     ...
;             PG8_LDB(B0, 1, 0); PG8_LDB(B1, 1, 1); PG8_SCHED; PG8_LDA(At, 1, 0); PG8_STAGE(PG8_SA(0, 1), a2 + hstep, voffA);
;             PG8_WAIT_V(8); PG8_WAIT_L(0); PG8_BAR; PG8_MMA(0, 0, At, B0); PG8_MMA(0, 1, At, B1); PG8_BAR; PG8_SCHED;
	s_add_i32 s78, 0, 0x18000
	v_add_u32_e32 v159, s78, v153
	s_add_i32 s79, 0, 0x1c000
	ds_read_b128 v[144:147], v159
	ds_read_b128 v[148:151], v159 offset:1024
	ds_read_b128 v[160:163], v159 offset:2048
	ds_read_b128 v[164:167], v159 offset:3072
	v_add_u32_e32 v159, s79, v153
	ds_read_b128 v[168:171], v159
	ds_read_b128 v[172:175], v159 offset:1024
	ds_read_b128 v[176:179], v159 offset:2048
	ds_read_b128 v[182:185], v159 offset:3072
	s_add_u32 s58, s58, 0x40000
	s_addc_u32 s59, s59, 0
	s_mov_b32 m0, s61
	v_lshl_add_u64 v[232:233], s[58:59], 0, v[134:135]
	ds_read_b128 v[186:189], v157 offset:32768
	ds_read_b128 v[190:193], v157 offset:33792
	ds_read_b128 v[194:197], v157 offset:34816
	ds_read_b128 v[198:201], v157 offset:35840
	ds_read_b128 v[208:211], v157 offset:36864
	ds_read_b128 v[212:215], v157 offset:37888
	ds_read_b128 v[216:219], v157 offset:38912
	ds_read_b128 v[220:223], v157 offset:39936
	global_load_lds_dwordx4 v[232:233], off
	v_lshl_add_u64 v[232:233], s[58:59], 0, v[130:131]
	s_mov_b32 m0, s62
	s_nop 0
	global_load_lds_dwordx4 v[232:233], off
	s_waitcnt vmcnt(8)
	s_waitcnt lgkmcnt(0)
	s_barrier
	s_setprio 1
	s_waitcnt lgkmcnt(0)
	v_mfma_f32_16x16x32_bf16 v[124:127], v[144:147], v[186:189], v[124:127]
	v_mfma_f32_16x16x32_bf16 v[120:123], v[160:163], v[186:189], v[120:123]
	v_mfma_f32_16x16x32_bf16 v[108:111], v[144:147], v[194:197], v[108:111]
	v_mfma_f32_16x16x32_bf16 v[104:107], v[160:163], v[194:197], v[104:107]
	v_mfma_f32_16x16x32_bf16 v[92:95], v[144:147], v[208:211], v[92:95]
	v_mfma_f32_16x16x32_bf16 v[88:91], v[160:163], v[208:211], v[88:91]
	v_mfma_f32_16x16x32_bf16 v[76:79], v[144:147], v[216:219], v[76:79]
	v_mfma_f32_16x16x32_bf16 v[72:75], v[160:163], v[216:219], v[72:75]
	v_mfma_f32_16x16x32_bf16 v[124:127], v[148:151], v[190:193], v[124:127]
	v_mfma_f32_16x16x32_bf16 v[120:123], v[164:167], v[190:193], v[120:123]
	v_mfma_f32_16x16x32_bf16 v[108:111], v[148:151], v[198:201], v[108:111]
	v_mfma_f32_16x16x32_bf16 v[104:107], v[164:167], v[198:201], v[104:107]
	v_mfma_f32_16x16x32_bf16 v[92:95], v[148:151], v[212:215], v[92:95]
	v_mfma_f32_16x16x32_bf16 v[88:91], v[164:167], v[212:215], v[88:91]
	v_mfma_f32_16x16x32_bf16 v[76:79], v[148:151], v[220:223], v[76:79]
	v_mfma_f32_16x16x32_bf16 v[72:75], v[164:167], v[220:223], v[72:75]
	s_setprio 0
	s_setprio 1
	v_mfma_f32_16x16x32_bf16 v[116:119], v[168:171], v[186:189], v[116:119]
	v_mfma_f32_16x16x32_bf16 v[112:115], v[176:179], v[186:189], v[112:115]
	v_mfma_f32_16x16x32_bf16 v[100:103], v[168:171], v[194:197], v[100:103]
	v_mfma_f32_16x16x32_bf16 v[96:99], v[176:179], v[194:197], v[96:99]
	v_mfma_f32_16x16x32_bf16 v[84:87], v[168:171], v[208:211], v[84:87]
	v_mfma_f32_16x16x32_bf16 v[80:83], v[176:179], v[208:211], v[80:83]
	v_mfma_f32_16x16x32_bf16 v[68:71], v[168:171], v[216:219], v[68:71]
	v_mfma_f32_16x16x32_bf16 v[64:67], v[176:179], v[216:219], v[64:67]
	v_mfma_f32_16x16x32_bf16 v[116:119], v[172:175], v[190:193], v[116:119]
	v_mfma_f32_16x16x32_bf16 v[112:115], v[182:185], v[190:193], v[112:115]
	v_mfma_f32_16x16x32_bf16 v[100:103], v[172:175], v[198:201], v[100:103]
	v_mfma_f32_16x16x32_bf16 v[96:99], v[182:185], v[198:201], v[96:99]
	v_mfma_f32_16x16x32_bf16 v[84:87], v[172:175], v[212:215], v[84:87]
	v_mfma_f32_16x16x32_bf16 v[80:83], v[182:185], v[212:215], v[80:83]
	v_mfma_f32_16x16x32_bf16 v[68:71], v[172:175], v[220:223], v[68:71]
	v_mfma_f32_16x16x32_bf16 v[64:67], v[182:185], v[220:223], v[64:67]
	s_setprio 0
	s_barrier
; #define PG8_STAGE(bufoff, gbase, voff) do { _Pragma("unroll") for (int _i = 0; _i < 2; ++_i) \
;         __builtin_amdgcn_global_load_lds((const unsigned*)((const char*)(gbase) + (voff)[_i]), (PG8_LAS unsigned*)(lds + (bufoff) + ldsw + _i * 8192), 16, 0, 0); } while (0)
; #define PG8_LDA(dst, b, h) do { _Pragma("unroll") for (int m = 0; m < 4; ++m) _Pragma("unroll") for (int k = 0; k < 2; ++k) dst[m][k] = *(const PG8_LAS bf16x8*)(lds + PG8_SA(b, h) + aoff + m * 2048 + k * 1024); } while (0)
; #define PG8_MMA(ai, bj, At, Bt) do { __builtin_amdgcn_s_setprio(1); _Pragma("unroll") for (int m = 0; m < 4; ++m) _Pragma("unroll") for (int n = 0; n < 2; ++n) _Pragma("unroll") for (int k = 0; k < 2; ++k) \
;         acc[ai][bj][m][n] = __builtin_amdgcn_mfma_f32_16x16x32_bf16(Bt[n][k], At[m][k], acc[ai][bj][m][n], 0, 0, 0); __builtin_amdgcn_s_setprio(0); } while (0)
; #define PG8_WAIT_V(n) asm volatile("s_waitcnt vmcnt(" #n ")" ::: "memory")
; #define PG8_WAIT_L(n) asm volatile("s_waitcnt lgkmcnt(" #n ")" ::: "memory")
; #define PG8_BAR __builtin_amdgcn_s_barrier()
; #define PG8_SCHED __builtin_amdgcn_sched_barrier(0)
; template <class Epi, class Sched, bool ALIGN_EPI = false, bool SP2 = false>
; __device__ __forceinline__ void gemm_phase(PG8_LAS unsigned char* lds, const Gemm g, const Sched& S, const Epi& E) {
;     ...
;             PG8_LDA(At, 1, 1); PG8_STAGE(PG8_SB(1, 0), b3, voffB); PG8_STAGE(PG8_SB(1, 1), b3 + hstep, voffB); PG8_STAGE(PG8_SA(1, 0), a3, voffA);
;             PG8_WAIT_V(8); PG8_WAIT_L(0); PG8_BAR; PG8_MMA(1, 0, At, B0); PG8_MMA(1, 1, At, B1); PG8_BAR; PG8_SCHED;
	s_add_i32 s58, s78, s33
	v_lshl_add_u64 v[224:225], v[224:225], 0, s[12:13]
	s_mov_b32 m0, s58
	ds_read_b128 v[186:189], v157 offset:49152
	ds_read_b128 v[190:193], v157 offset:50176
	ds_read_b128 v[194:197], v157 offset:51200
	ds_read_b128 v[198:201], v157 offset:52224
	ds_read_b128 v[208:211], v157 offset:53248
	ds_read_b128 v[212:215], v157 offset:54272
	ds_read_b128 v[216:219], v157 offset:55296
	ds_read_b128 v[220:223], v157 offset:56320
	global_load_lds_dwordx4 v[224:225], off
	s_add_i32 m0, s58, 0x2000
	s_add_u32 s56, s56, 0x40080
	v_lshl_add_u64 v[224:225], v[226:227], 0, s[12:13]
	s_addc_u32 s57, s57, 0
	s_add_i32 s58, s79, s33
	global_load_lds_dwordx4 v[224:225], off
	v_lshl_add_u64 v[224:225], s[56:57], 0, v[132:133]
	s_mov_b32 m0, s58
	s_nop 0
	global_load_lds_dwordx4 v[224:225], off
	v_lshl_add_u64 v[224:225], s[56:57], 0, v[128:129]
	s_add_i32 m0, s58, 0x2000
	s_nop 0
	global_load_lds_dwordx4 v[224:225], off
	s_waitcnt vmcnt(6)
	s_waitcnt lgkmcnt(0)
	s_barrier
	s_setprio 1
	s_waitcnt lgkmcnt(0)
	v_mfma_f32_16x16x32_bf16 v[60:63], v[144:147], v[186:189], v[60:63]
	v_mfma_f32_16x16x32_bf16 v[56:59], v[160:163], v[186:189], v[56:59]
	v_mfma_f32_16x16x32_bf16 v[44:47], v[144:147], v[194:197], v[44:47]
	v_mfma_f32_16x16x32_bf16 v[40:43], v[160:163], v[194:197], v[40:43]
	v_mfma_f32_16x16x32_bf16 v[28:31], v[144:147], v[208:211], v[28:31]
	v_mfma_f32_16x16x32_bf16 v[24:27], v[160:163], v[208:211], v[24:27]
	v_mfma_f32_16x16x32_bf16 v[12:15], v[144:147], v[216:219], v[12:15]
	v_mfma_f32_16x16x32_bf16 v[8:11], v[160:163], v[216:219], v[8:11]
	v_mfma_f32_16x16x32_bf16 v[60:63], v[148:151], v[190:193], v[60:63]
	v_mfma_f32_16x16x32_bf16 v[56:59], v[164:167], v[190:193], v[56:59]
	v_mfma_f32_16x16x32_bf16 v[44:47], v[148:151], v[198:201], v[44:47]
	v_mfma_f32_16x16x32_bf16 v[40:43], v[164:167], v[198:201], v[40:43]
	v_mfma_f32_16x16x32_bf16 v[28:31], v[148:151], v[212:215], v[28:31]
	v_mfma_f32_16x16x32_bf16 v[24:27], v[164:167], v[212:215], v[24:27]
	v_lshl_add_u64 v[224:225], v[228:229], 0, s[12:13]
	s_mov_b32 m0, s64
	s_nop 0
	global_load_lds_dwordx4 v[224:225], off
	v_mfma_f32_16x16x32_bf16 v[12:15], v[148:151], v[220:223], v[12:15]
	v_mfma_f32_16x16x32_bf16 v[8:11], v[164:167], v[220:223], v[8:11]
	s_setprio 0
	s_setprio 1
	v_mfma_f32_16x16x32_bf16 v[52:55], v[168:171], v[186:189], v[52:55]
	v_mfma_f32_16x16x32_bf16 v[48:51], v[176:179], v[186:189], v[48:51]
	v_mfma_f32_16x16x32_bf16 v[36:39], v[168:171], v[194:197], v[36:39]
	v_mfma_f32_16x16x32_bf16 v[32:35], v[176:179], v[194:197], v[32:35]
	v_mfma_f32_16x16x32_bf16 v[20:23], v[168:171], v[208:211], v[20:23]
	v_mfma_f32_16x16x32_bf16 v[16:19], v[176:179], v[208:211], v[16:19]
	v_mfma_f32_16x16x32_bf16 v[4:7], v[168:171], v[216:219], v[4:7]
	v_mfma_f32_16x16x32_bf16 v[0:3], v[176:179], v[216:219], v[0:3]
	v_mfma_f32_16x16x32_bf16 v[52:55], v[172:175], v[190:193], v[52:55]
	v_mfma_f32_16x16x32_bf16 v[48:51], v[182:185], v[190:193], v[48:51]
	v_mfma_f32_16x16x32_bf16 v[36:39], v[172:175], v[198:201], v[36:39]
	v_mfma_f32_16x16x32_bf16 v[32:35], v[182:185], v[198:201], v[32:35]
	v_mfma_f32_16x16x32_bf16 v[20:23], v[172:175], v[212:215], v[20:23]
	v_mfma_f32_16x16x32_bf16 v[16:19], v[182:185], v[212:215], v[16:19]
	v_lshl_add_u64 v[224:225], v[230:231], 0, s[12:13]
	s_mov_b32 m0, s65
	s_nop 0
	global_load_lds_dwordx4 v[224:225], off
	v_mfma_f32_16x16x32_bf16 v[4:7], v[172:175], v[220:223], v[4:7]
	v_mfma_f32_16x16x32_bf16 v[0:3], v[182:185], v[220:223], v[0:3]
	s_setprio 0
	s_barrier
	s_add_i32 s84, s84, 2
	s_add_u32 s54, s54, 0x100
	s_addc_u32 s55, s55, 0
	s_add_u32 s82, s82, 0x100
	s_addc_u32 s83, s83, 0
	s_cmp_gt_u32 s84, 13
	s_cbranch_scc0 .LBB0_1119
	v_lshl_add_u32 v144, s52, 8, v152
	v_ashrrev_i32_e32 v145, 31, v144
	v_lshl_add_u64 v[150:151], v[144:145], 3, s[36:37]
	global_load_dwordx2 v[182:183], v[150:151], off
	global_load_dwordx2 v[184:185], v[150:151], off offset:128
	global_load_dwordx2 v[186:187], v[150:151], off offset:256
	global_load_dwordx2 v[188:189], v[150:151], off offset:384
	global_load_dwordx2 v[190:191], v[150:151], off offset:1024
	global_load_dwordx2 v[192:193], v[150:151], off offset:1152
	global_load_dwordx2 v[194:195], v[150:151], off offset:1280
	global_load_dwordx2 v[196:197], v[150:151], off offset:1408
	s_and_b64 vcc, exec, s[38:39]
	s_cbranch_vccz .LBB0_1122
	s_barrier

; #define PG8_STAGE(bufoff, gbase, voff) do { _Pragma("unroll") for (int _i = 0; _i < 2; ++_i) \
;         __builtin_amdgcn_global_load_lds((const unsigned*)((const char*)(gbase) + (voff)[_i]), (PG8_LAS unsigned*)(lds + (bufoff) + ldsw + _i * 8192), 16, 0, 0); } while (0)
; #define PG8_LDA(dst, b, h) do { _Pragma("unroll") for (int m = 0; m < 4; ++m) _Pragma("unroll") for (int k = 0; k < 2; ++k) dst[m][k] = *(const PG8_LAS bf16x8*)(lds + PG8_SA(b, h) + aoff + m * 2048 + k * 1024); } while (0)
; #define PG8_LDB(dst, b, h) do { _Pragma("unroll") for (int n = 0; n < 2; ++n) _Pragma("unroll") for (int k = 0; k < 2; ++k) dst[n][k] = *(const PG8_LAS bf16x8*)(lds + PG8_SB(b, h) + boff + n * 2048 + k * 1024); } while (0)
; #define PG8_MMA(ai, bj, At, Bt) do { __builtin_amdgcn_s_setprio(1); _Pragma("unroll") for (int m = 0; m < 4; ++m) _Pragma("unroll") for (int n = 0; n < 2; ++n) _Pragma("unroll") for (int k = 0; k < 2; ++k) \
;         acc[ai][bj][m][n] = __builtin_amdgcn_mfma_f32_16x16x32_bf16(Bt[n][k], At[m][k], acc[ai][bj][m][n], 0, 0, 0); __builtin_amdgcn_s_setprio(0); } while (0)
; #define PG8_WAIT_V(n) asm volatile("s_waitcnt vmcnt(" #n ")" ::: "memory")
; #define PG8_BAR __builtin_amdgcn_s_barrier()
; template <class Epi, class Sched, bool ALIGN_EPI = false, bool SP2 = false>
; __device__ __forceinline__ void gemm_phase(PG8_LAS unsigned char* lds, const Gemm g, const Sched& S, const Epi& E) {
;     ...
;         for (int t = 0; t < nt; t += 2) {
;             const bool last = (t == nt - 2);
;             const char* a1 = cA + (size_t)(t + 1) * kstep;
;             const char* a2 = last ? nA : cA + (size_t)(t + 2) * kstep; const char* b2 = last ? nB : cB + (size_t)(t + 2) * kstep;
;             const char* a3 = a2 + kstep; const char* b3 = b2 + kstep;
;             if (last && has_next) S.a_ready(nxt);
;             if constexpr (SP2) {
;             PG8_LDB(B0, 0, 0); PG8_LDB(B1, 0, 1); PG8_SCHED; PG8_LDA(At, 0, 0); PG8_STAGE(PG8_SA(1, 1), a1 + hstep, voffA);
;             PG8_WAIT_V(8); PG8_WAIT_L(0); PG8_BAR; PG8_MMA(0, 0, At, B0); PG8_MMA(0, 1, At, B1); PG8_BAR; PG8_SCHED;
;             PG8_LDA(At, 0, 1); PG8_STAGE(PG8_SB(0, 0), b2, voffB); PG8_STAGE(PG8_SB(0, 1), b2 + hstep, voffB); PG8_STAGE(PG8_SA(0, 0), a2, voffA);
;             PG8_WAIT_V(8); PG8_WAIT_L(0); PG8_BAR; PG8_MMA(1, 0, At, B0); PG8_MMA(1, 1, At, B1); PG8_BAR; PG8_SCHED;
.LBB0_1196:
	s_add_u32 s82, s52, 0x100
	s_addc_u32 s83, s53, 0
	s_mov_b32 s84, -2
	s_waitcnt lgkmcnt(0)
	ds_read_b128 v[144:147], v151
	ds_read_b128 v[156:159], v151 offset:1024
	ds_read_b128 v[160:163], v151 offset:2048
	ds_read_b128 v[164:167], v151 offset:3072
	ds_read_b128 v[168:171], v152
	ds_read_b128 v[172:175], v152 offset:1024
	ds_read_b128 v[176:179], v152 offset:2048
	ds_read_b128 v[182:185], v152 offset:3072
	s_add_u32 s52, s50, 0x100
	s_addc_u32 s53, s51, 0
	s_cmp_eq_u32 s84, 40
	s_cselect_b32 s57, s1, s53
	s_cselect_b32 s56, s0, s52
	s_cselect_b32 s55, s49, s83
	s_cselect_b32 s54, s48, s82
	v_lshl_add_u64 v[224:225], s[50:51], 0, v[136:137]
	s_add_i32 m0, s34, 0xc000
	ds_read_b128 v[186:189], v153
	ds_read_b128 v[190:193], v153 offset:1024
	ds_read_b128 v[194:197], v153 offset:2048
	ds_read_b128 v[198:201], v153 offset:3072
	ds_read_b128 v[208:211], v153 offset:4096
	ds_read_b128 v[212:215], v153 offset:5120
	ds_read_b128 v[216:219], v153 offset:6144
	ds_read_b128 v[220:223], v153 offset:7168
	global_load_lds_dwordx4 v[224:225], off
	v_lshl_add_u64 v[224:225], s[50:51], 0, v[138:139]
	s_add_i32 m0, s34, 0xe000
	s_nop 0
	global_load_lds_dwordx4 v[224:225], off
	s_waitcnt vmcnt(8)
	s_waitcnt lgkmcnt(0)
	s_barrier
	s_setprio 1
	s_waitcnt lgkmcnt(0)
	v_mfma_f32_16x16x32_bf16 v[124:127], v[144:147], v[186:189], 0
	v_mfma_f32_16x16x32_bf16 v[120:123], v[160:163], v[186:189], 0
	v_mfma_f32_16x16x32_bf16 v[108:111], v[144:147], v[194:197], 0
	v_mfma_f32_16x16x32_bf16 v[104:107], v[160:163], v[194:197], 0
	v_mfma_f32_16x16x32_bf16 v[92:95], v[144:147], v[208:211], 0
	v_mfma_f32_16x16x32_bf16 v[88:91], v[160:163], v[208:211], 0
	v_mfma_f32_16x16x32_bf16 v[76:79], v[144:147], v[216:219], 0
	v_mfma_f32_16x16x32_bf16 v[72:75], v[160:163], v[216:219], 0
	v_mfma_f32_16x16x32_bf16 v[124:127], v[156:159], v[190:193], v[124:127]
	v_mfma_f32_16x16x32_bf16 v[120:123], v[164:167], v[190:193], v[120:123]
	v_mfma_f32_16x16x32_bf16 v[108:111], v[156:159], v[198:201], v[108:111]
	v_mfma_f32_16x16x32_bf16 v[104:107], v[164:167], v[198:201], v[104:107]
	v_mfma_f32_16x16x32_bf16 v[92:95], v[156:159], v[212:215], v[92:95]
	v_mfma_f32_16x16x32_bf16 v[88:91], v[164:167], v[212:215], v[88:91]
	v_mfma_f32_16x16x32_bf16 v[76:79], v[156:159], v[220:223], v[76:79]
	v_mfma_f32_16x16x32_bf16 v[72:75], v[164:167], v[220:223], v[72:75]
	s_setprio 0
	s_setprio 1
	v_mfma_f32_16x16x32_bf16 v[116:119], v[168:171], v[186:189], 0
	v_mfma_f32_16x16x32_bf16 v[112:115], v[176:179], v[186:189], 0
	v_mfma_f32_16x16x32_bf16 v[100:103], v[168:171], v[194:197], 0
	v_mfma_f32_16x16x32_bf16 v[96:99], v[176:179], v[194:197], 0
	v_mfma_f32_16x16x32_bf16 v[84:87], v[168:171], v[208:211], 0
	v_mfma_f32_16x16x32_bf16 v[80:83], v[176:179], v[208:211], 0
	v_mfma_f32_16x16x32_bf16 v[68:71], v[168:171], v[216:219], 0
	v_mfma_f32_16x16x32_bf16 v[64:67], v[176:179], v[216:219], 0
	v_mfma_f32_16x16x32_bf16 v[116:119], v[172:175], v[190:193], v[116:119]
	v_mfma_f32_16x16x32_bf16 v[112:115], v[182:185], v[190:193], v[112:115]
	v_mfma_f32_16x16x32_bf16 v[100:103], v[172:175], v[198:201], v[100:103]
	v_mfma_f32_16x16x32_bf16 v[96:99], v[182:185], v[198:201], v[96:99]
	v_mfma_f32_16x16x32_bf16 v[84:87], v[172:175], v[212:215], v[84:87]
	v_mfma_f32_16x16x32_bf16 v[80:83], v[182:185], v[212:215], v[80:83]
	v_mfma_f32_16x16x32_bf16 v[68:71], v[172:175], v[220:223], v[68:71]
	v_mfma_f32_16x16x32_bf16 v[64:67], v[182:185], v[220:223], v[64:67]
	s_setprio 0
	s_barrier
	s_add_i32 s50, s64, s33
	v_lshl_add_u64 v[224:225], s[54:55], 0, v[130:131]
	s_mov_b32 m0, s50
	ds_read_b128 v[186:189], v153 offset:16384
	ds_read_b128 v[190:193], v153 offset:17408
	ds_read_b128 v[194:197], v153 offset:18432
	ds_read_b128 v[198:201], v153 offset:19456
	ds_read_b128 v[208:211], v153 offset:20480
	ds_read_b128 v[212:215], v153 offset:21504
	ds_read_b128 v[216:219], v153 offset:22528
	ds_read_b128 v[220:223], v153 offset:23552
	global_load_lds_dwordx4 v[224:225], off
	s_add_i32 m0, s50, 0x2000
	s_add_u32 s50, s54, 0xb0000
	v_lshl_add_u64 v[226:227], s[54:55], 0, v[134:135]
	s_addc_u32 s51, s55, 0
	s_add_i32 s78, s65, s33
	global_load_lds_dwordx4 v[226:227], off
	v_lshl_add_u64 v[228:229], s[50:51], 0, v[130:131]
	s_mov_b32 m0, s78
	global_load_lds_dwordx4 v[228:229], off
	v_lshl_add_u64 v[228:229], s[50:51], 0, v[134:135]
	s_add_i32 m0, s78, 0x2000
	s_nop 0
	global_load_lds_dwordx4 v[228:229], off
	s_waitcnt vmcnt(6)
	s_waitcnt lgkmcnt(0)
	s_barrier
; #define PG8_STAGE(bufoff, gbase, voff) do { _Pragma("unroll") for (int _i = 0; _i < 2; ++_i) \
;         __builtin_amdgcn_global_load_lds((const unsigned*)((const char*)(gbase) + (voff)[_i]), (PG8_LAS unsigned*)(lds + (bufoff) + ldsw + _i * 8192), 16, 0, 0); } while (0)
; #define PG8_LDA(dst, b, h) do { _Pragma("unroll") for (int m = 0; m < 4; ++m) _Pragma("unroll") for (int k = 0; k < 2; ++k) dst[m][k] = *(const PG8_LAS bf16x8*)(lds + PG8_SA(b, h) + aoff + m * 2048 + k * 1024); } while (0)
; #define PG8_LDB(dst, b, h) do { _Pragma("unroll") for (int n = 0; n < 2; ++n) _Pragma("unroll") for (int k = 0; k < 2; ++k) dst[n][k] = *(const PG8_LAS bf16x8*)(lds + PG8_SB(b, h) + boff + n * 2048 + k * 1024); } while (0)
; #define PG8_MMA(ai, bj, At, Bt) do { __builtin_amdgcn_s_setprio(1); _Pragma("unroll") for (int m = 0; m < 4; ++m) _Pragma("unroll") for (int n = 0; n < 2; ++n) _Pragma("unroll") for (int k = 0; k < 2; ++k) \
;         acc[ai][bj][m][n] = __builtin_amdgcn_mfma_f32_16x16x32_bf16(Bt[n][k], At[m][k], acc[ai][bj][m][n], 0, 0, 0); __builtin_amdgcn_s_setprio(0); } while (0)
; #define PG8_WAIT_V(n) asm volatile("s_waitcnt vmcnt(" #n ")" ::: "memory")
; #define PG8_WAIT_L(n) asm volatile("s_waitcnt lgkmcnt(" #n ")" ::: "memory")
; #define PG8_BAR __builtin_amdgcn_s_barrier()
; #define PG8_SCHED __builtin_amdgcn_sched_barrier(0)
; template <class Epi, class Sched, bool ALIGN_EPI = false, bool SP2 = false>
; __device__ __forceinline__ void gemm_phase(PG8_LAS unsigned char* lds, const Gemm g, const Sched& S, const Epi& E) {
;     ...
;             PG8_WAIT_V(8); PG8_WAIT_L(0); PG8_BAR; PG8_MMA(1, 0, At, B0); PG8_MMA(1, 1, At, B1); PG8_BAR; PG8_SCHED;
;             PG8_LDB(B0, 1, 0); PG8_LDB(B1, 1, 1); PG8_SCHED; PG8_LDA(At, 1, 0); PG8_STAGE(PG8_SA(0, 1), a2 + hstep, voffA);
;             PG8_WAIT_V(8); PG8_WAIT_L(0); PG8_BAR; PG8_MMA(0, 0, At, B0); PG8_MMA(0, 1, At, B1); PG8_BAR; PG8_SCHED;
	s_setprio 1
	s_waitcnt lgkmcnt(0)
	v_mfma_f32_16x16x32_bf16 v[60:63], v[144:147], v[186:189], 0
	v_mfma_f32_16x16x32_bf16 v[56:59], v[160:163], v[186:189], 0
	v_mfma_f32_16x16x32_bf16 v[44:47], v[144:147], v[194:197], 0
	v_mfma_f32_16x16x32_bf16 v[40:43], v[160:163], v[194:197], 0
	v_mfma_f32_16x16x32_bf16 v[28:31], v[144:147], v[208:211], 0
	v_mfma_f32_16x16x32_bf16 v[24:27], v[160:163], v[208:211], 0
	v_mfma_f32_16x16x32_bf16 v[12:15], v[144:147], v[216:219], 0
	v_mfma_f32_16x16x32_bf16 v[8:11], v[160:163], v[216:219], 0
	v_mfma_f32_16x16x32_bf16 v[60:63], v[156:159], v[190:193], v[60:63]
	v_mfma_f32_16x16x32_bf16 v[56:59], v[164:167], v[190:193], v[56:59]
	v_mfma_f32_16x16x32_bf16 v[44:47], v[156:159], v[198:201], v[44:47]
	v_mfma_f32_16x16x32_bf16 v[40:43], v[164:167], v[198:201], v[40:43]
	v_mfma_f32_16x16x32_bf16 v[28:31], v[156:159], v[212:215], v[28:31]
	v_mfma_f32_16x16x32_bf16 v[24:27], v[164:167], v[212:215], v[24:27]
	v_lshl_add_u64 v[228:229], s[56:57], 0, v[128:129]
	s_mov_b32 m0, s34
	s_nop 0
	global_load_lds_dwordx4 v[228:229], off
	v_mfma_f32_16x16x32_bf16 v[12:15], v[156:159], v[220:223], v[12:15]
	v_mfma_f32_16x16x32_bf16 v[8:11], v[164:167], v[220:223], v[8:11]
	s_setprio 0
	s_setprio 1
	v_mfma_f32_16x16x32_bf16 v[52:55], v[168:171], v[186:189], 0
	v_mfma_f32_16x16x32_bf16 v[48:51], v[176:179], v[186:189], 0
	v_mfma_f32_16x16x32_bf16 v[36:39], v[168:171], v[194:197], 0
	v_mfma_f32_16x16x32_bf16 v[32:35], v[176:179], v[194:197], 0
	v_mfma_f32_16x16x32_bf16 v[20:23], v[168:171], v[208:211], 0
	v_mfma_f32_16x16x32_bf16 v[16:19], v[176:179], v[208:211], 0
	v_mfma_f32_16x16x32_bf16 v[4:7], v[168:171], v[216:219], 0
	v_mfma_f32_16x16x32_bf16 v[0:3], v[176:179], v[216:219], 0
	v_mfma_f32_16x16x32_bf16 v[52:55], v[172:175], v[190:193], v[52:55]
	v_mfma_f32_16x16x32_bf16 v[48:51], v[182:185], v[190:193], v[48:51]
	v_mfma_f32_16x16x32_bf16 v[36:39], v[172:175], v[198:201], v[36:39]
	v_mfma_f32_16x16x32_bf16 v[32:35], v[182:185], v[198:201], v[32:35]
	v_mfma_f32_16x16x32_bf16 v[20:23], v[172:175], v[212:215], v[20:23]
	v_mfma_f32_16x16x32_bf16 v[16:19], v[182:185], v[212:215], v[16:19]
	v_lshl_add_u64 v[230:231], s[56:57], 0, v[132:133]
	s_mov_b32 m0, s58
	s_nop 0
	global_load_lds_dwordx4 v[230:231], off
	v_mfma_f32_16x16x32_bf16 v[4:7], v[172:175], v[220:223], v[4:7]
	v_mfma_f32_16x16x32_bf16 v[0:3], v[182:185], v[220:223], v[0:3]
	s_setprio 0
	s_barrier
	s_add_i32 s78, 0, 0x18000
	v_add_u32_e32 v155, s78, v149
	s_add_i32 s79, 0, 0x1c000
	ds_read_b128 v[144:147], v155
	ds_read_b128 v[156:159], v155 offset:1024
	ds_read_b128 v[160:163], v155 offset:2048
	ds_read_b128 v[164:167], v155 offset:3072
	v_add_u32_e32 v155, s79, v149
	ds_read_b128 v[168:171], v155
	ds_read_b128 v[172:175], v155 offset:1024
	ds_read_b128 v[176:179], v155 offset:2048
	ds_read_b128 v[182:185], v155 offset:3072
	s_add_u32 s50, s56, 0xb0000
	s_addc_u32 s51, s57, 0
	s_mov_b32 m0, s59
	v_lshl_add_u64 v[232:233], s[50:51], 0, v[128:129]
	ds_read_b128 v[186:189], v153 offset:32768
	ds_read_b128 v[190:193], v153 offset:33792
	ds_read_b128 v[194:197], v153 offset:34816
	ds_read_b128 v[198:201], v153 offset:35840
	ds_read_b128 v[208:211], v153 offset:36864
	ds_read_b128 v[212:215], v153 offset:37888
	ds_read_b128 v[216:219], v153 offset:38912
	ds_read_b128 v[220:223], v153 offset:39936
	global_load_lds_dwordx4 v[232:233], off
	v_lshl_add_u64 v[232:233], s[50:51], 0, v[132:133]
	s_mov_b32 m0, s60
	s_nop 0
	global_load_lds_dwordx4 v[232:233], off
	s_waitcnt vmcnt(8)
	s_waitcnt lgkmcnt(0)
	s_barrier
	s_setprio 1
	s_waitcnt lgkmcnt(0)
	v_mfma_f32_16x16x32_bf16 v[124:127], v[144:147], v[186:189], v[124:127]
	v_mfma_f32_16x16x32_bf16 v[120:123], v[160:163], v[186:189], v[120:123]
	v_mfma_f32_16x16x32_bf16 v[108:111], v[144:147], v[194:197], v[108:111]
	v_mfma_f32_16x16x32_bf16 v[104:107], v[160:163], v[194:197], v[104:107]
	v_mfma_f32_16x16x32_bf16 v[92:95], v[144:147], v[208:211], v[92:95]
	v_mfma_f32_16x16x32_bf16 v[88:91], v[160:163], v[208:211], v[88:91]
	v_mfma_f32_16x16x32_bf16 v[76:79], v[144:147], v[216:219], v[76:79]
	v_mfma_f32_16x16x32_bf16 v[72:75], v[160:163], v[216:219], v[72:75]
	v_mfma_f32_16x16x32_bf16 v[124:127], v[156:159], v[190:193], v[124:127]
	v_mfma_f32_16x16x32_bf16 v[120:123], v[164:167], v[190:193], v[120:123]
	v_mfma_f32_16x16x32_bf16 v[108:111], v[156:159], v[198:201], v[108:111]
	v_mfma_f32_16x16x32_bf16 v[104:107], v[164:167], v[198:201], v[104:107]
	v_mfma_f32_16x16x32_bf16 v[92:95], v[156:159], v[212:215], v[92:95]
	v_mfma_f32_16x16x32_bf16 v[88:91], v[164:167], v[212:215], v[88:91]
	v_mfma_f32_16x16x32_bf16 v[76:79], v[156:159], v[220:223], v[76:79]
	v_mfma_f32_16x16x32_bf16 v[72:75], v[164:167], v[220:223], v[72:75]
	s_setprio 0
	s_setprio 1
	v_mfma_f32_16x16x32_bf16 v[116:119], v[168:171], v[186:189], v[116:119]
	v_mfma_f32_16x16x32_bf16 v[112:115], v[176:179], v[186:189], v[112:115]
	v_mfma_f32_16x16x32_bf16 v[100:103], v[168:171], v[194:197], v[100:103]
	v_mfma_f32_16x16x32_bf16 v[96:99], v[176:179], v[194:197], v[96:99]
	v_mfma_f32_16x16x32_bf16 v[84:87], v[168:171], v[208:211], v[84:87]
	v_mfma_f32_16x16x32_bf16 v[80:83], v[176:179], v[208:211], v[80:83]
	v_mfma_f32_16x16x32_bf16 v[68:71], v[168:171], v[216:219], v[68:71]
	v_mfma_f32_16x16x32_bf16 v[64:67], v[176:179], v[216:219], v[64:67]
	v_mfma_f32_16x16x32_bf16 v[116:119], v[172:175], v[190:193], v[116:119]
	v_mfma_f32_16x16x32_bf16 v[112:115], v[182:185], v[190:193], v[112:115]
	v_mfma_f32_16x16x32_bf16 v[100:103], v[172:175], v[198:201], v[100:103]
	v_mfma_f32_16x16x32_bf16 v[96:99], v[182:185], v[198:201], v[96:99]
	v_mfma_f32_16x16x32_bf16 v[84:87], v[172:175], v[212:215], v[84:87]
	v_mfma_f32_16x16x32_bf16 v[80:83], v[182:185], v[212:215], v[80:83]
	v_mfma_f32_16x16x32_bf16 v[68:71], v[172:175], v[220:223], v[68:71]
	v_mfma_f32_16x16x32_bf16 v[64:67], v[182:185], v[220:223], v[64:67]
	s_setprio 0
	s_barrier
; #define PG8_STAGE(bufoff, gbase, voff) do { _Pragma("unroll") for (int _i = 0; _i < 2; ++_i) \
;         __builtin_amdgcn_global_load_lds((const unsigned*)((const char*)(gbase) + (voff)[_i]), (PG8_LAS unsigned*)(lds + (bufoff) + ldsw + _i * 8192), 16, 0, 0); } while (0)
; #define PG8_LDA(dst, b, h) do { _Pragma("unroll") for (int m = 0; m < 4; ++m) _Pragma("unroll") for (int k = 0; k < 2; ++k) dst[m][k] = *(const PG8_LAS bf16x8*)(lds + PG8_SA(b, h) + aoff + m * 2048 + k * 1024); } while (0)
; #define PG8_LDB(dst, b, h) do { _Pragma("unroll") for (int n = 0; n < 2; ++n) _Pragma("unroll") for (int k = 0; k < 2; ++k) dst[n][k] = *(const PG8_LAS bf16x8*)(lds + PG8_SB(b, h) + boff + n * 2048 + k * 1024); } while (0)
; #define PG8_MMA(ai, bj, At, Bt) do { __builtin_amdgcn_s_setprio(1); _Pragma("unroll") for (int m = 0; m < 4; ++m) _Pragma("unroll") for (int n = 0; n < 2; ++n) _Pragma("unroll") for (int k = 0; k < 2; ++k) \
;         acc[ai][bj][m][n] = __builtin_amdgcn_mfma_f32_16x16x32_bf16(Bt[n][k], At[m][k], acc[ai][bj][m][n], 0, 0, 0); __builtin_amdgcn_s_setprio(0); } while (0)
; #define PG8_WAIT_V(n) asm volatile("s_waitcnt vmcnt(" #n ")" ::: "memory")
; #define PG8_WAIT_L(n) asm volatile("s_waitcnt lgkmcnt(" #n ")" ::: "memory")
; #define PG8_BAR __builtin_amdgcn_s_barrier()
; #define PG8_SCHED __builtin_amdgcn_sched_barrier(0)
; template <class Epi, class Sched, bool ALIGN_EPI = false, bool SP2 = false>
; __device__ __forceinline__ void gemm_phase(PG8_LAS unsigned char* lds, const Gemm g, const Sched& S, const Epi& E) {
;     ...
;             const bool last = (t == nt - 2);
;             const char* a1 = cA + (size_t)(t + 1) * kstep;
;             const char* a2 = last ? nA : cA + (size_t)(t + 2) * kstep; const char* b2 = last ? nB : cB + (size_t)(t + 2) * kstep;
;             const char* a3 = a2 + kstep; const char* b3 = b2 + kstep;
;             if (last && has_next) S.a_ready(nxt);
;             if constexpr (SP2) {
;             PG8_LDB(B0, 0, 0); PG8_LDB(B1, 0, 1); PG8_SCHED; PG8_LDA(At, 0, 0); PG8_STAGE(PG8_SA(1, 1), a1 + hstep, voffA);
;     ...
;             PG8_LDA(At, 1, 1); PG8_STAGE(PG8_SB(1, 0), b3, voffB); PG8_STAGE(PG8_SB(1, 1), b3 + hstep, voffB); PG8_STAGE(PG8_SA(1, 0), a3, voffA);
;             PG8_WAIT_V(8); PG8_WAIT_L(0); PG8_BAR; PG8_MMA(1, 0, At, B0); PG8_MMA(1, 1, At, B1); PG8_BAR; PG8_SCHED;
	s_add_i32 s50, s78, s33
	v_lshl_add_u64 v[224:225], v[224:225], 0, s[42:43]
	s_mov_b32 m0, s50
	ds_read_b128 v[186:189], v153 offset:49152
	ds_read_b128 v[190:193], v153 offset:50176
	ds_read_b128 v[194:197], v153 offset:51200
	ds_read_b128 v[198:201], v153 offset:52224
	ds_read_b128 v[208:211], v153 offset:53248
	ds_read_b128 v[212:215], v153 offset:54272
	ds_read_b128 v[216:219], v153 offset:55296
	ds_read_b128 v[220:223], v153 offset:56320
	global_load_lds_dwordx4 v[224:225], off
	s_add_i32 m0, s50, 0x2000
	s_add_u32 s50, s54, 0xb0080
	v_lshl_add_u64 v[224:225], v[226:227], 0, s[42:43]
	s_addc_u32 s51, s55, 0
	s_add_i32 s54, s79, s33
	global_load_lds_dwordx4 v[224:225], off
	v_lshl_add_u64 v[224:225], s[50:51], 0, v[130:131]
	s_mov_b32 m0, s54
	s_nop 0
	global_load_lds_dwordx4 v[224:225], off
	v_lshl_add_u64 v[224:225], s[50:51], 0, v[134:135]
	s_add_i32 m0, s54, 0x2000
	s_nop 0
	global_load_lds_dwordx4 v[224:225], off
	s_waitcnt vmcnt(6)
	s_waitcnt lgkmcnt(0)
	s_barrier
	s_setprio 1
	s_waitcnt lgkmcnt(0)
	v_mfma_f32_16x16x32_bf16 v[60:63], v[144:147], v[186:189], v[60:63]
	v_mfma_f32_16x16x32_bf16 v[56:59], v[160:163], v[186:189], v[56:59]
	v_mfma_f32_16x16x32_bf16 v[44:47], v[144:147], v[194:197], v[44:47]
	v_mfma_f32_16x16x32_bf16 v[40:43], v[160:163], v[194:197], v[40:43]
	v_mfma_f32_16x16x32_bf16 v[28:31], v[144:147], v[208:211], v[28:31]
	v_mfma_f32_16x16x32_bf16 v[24:27], v[160:163], v[208:211], v[24:27]
	v_mfma_f32_16x16x32_bf16 v[12:15], v[144:147], v[216:219], v[12:15]
	v_mfma_f32_16x16x32_bf16 v[8:11], v[160:163], v[216:219], v[8:11]
	v_mfma_f32_16x16x32_bf16 v[60:63], v[156:159], v[190:193], v[60:63]
	v_mfma_f32_16x16x32_bf16 v[56:59], v[164:167], v[190:193], v[56:59]
	v_mfma_f32_16x16x32_bf16 v[44:47], v[156:159], v[198:201], v[44:47]
	v_mfma_f32_16x16x32_bf16 v[40:43], v[164:167], v[198:201], v[40:43]
	v_mfma_f32_16x16x32_bf16 v[28:31], v[156:159], v[212:215], v[28:31]
	v_mfma_f32_16x16x32_bf16 v[24:27], v[164:167], v[212:215], v[24:27]
	v_lshl_add_u64 v[224:225], v[228:229], 0, s[42:43]
	s_mov_b32 m0, s62
	s_nop 0
	global_load_lds_dwordx4 v[224:225], off
	v_mfma_f32_16x16x32_bf16 v[12:15], v[156:159], v[220:223], v[12:15]
	v_mfma_f32_16x16x32_bf16 v[8:11], v[164:167], v[220:223], v[8:11]
	s_setprio 0
	s_setprio 1
	v_mfma_f32_16x16x32_bf16 v[52:55], v[168:171], v[186:189], v[52:55]
	v_mfma_f32_16x16x32_bf16 v[48:51], v[176:179], v[186:189], v[48:51]
	v_mfma_f32_16x16x32_bf16 v[36:39], v[168:171], v[194:197], v[36:39]
	v_mfma_f32_16x16x32_bf16 v[32:35], v[176:179], v[194:197], v[32:35]
	v_mfma_f32_16x16x32_bf16 v[20:23], v[168:171], v[208:211], v[20:23]
	v_mfma_f32_16x16x32_bf16 v[16:19], v[176:179], v[208:211], v[16:19]
	v_mfma_f32_16x16x32_bf16 v[4:7], v[168:171], v[216:219], v[4:7]
	v_mfma_f32_16x16x32_bf16 v[0:3], v[176:179], v[216:219], v[0:3]
	v_mfma_f32_16x16x32_bf16 v[52:55], v[172:175], v[190:193], v[52:55]
	v_mfma_f32_16x16x32_bf16 v[48:51], v[182:185], v[190:193], v[48:51]
	v_mfma_f32_16x16x32_bf16 v[36:39], v[172:175], v[198:201], v[36:39]
	v_mfma_f32_16x16x32_bf16 v[32:35], v[182:185], v[198:201], v[32:35]
	v_mfma_f32_16x16x32_bf16 v[20:23], v[172:175], v[212:215], v[20:23]
	v_mfma_f32_16x16x32_bf16 v[16:19], v[182:185], v[212:215], v[16:19]
	v_lshl_add_u64 v[224:225], v[230:231], 0, s[42:43]
	s_mov_b32 m0, s63
	s_nop 0
	global_load_lds_dwordx4 v[224:225], off
	v_mfma_f32_16x16x32_bf16 v[4:7], v[172:175], v[220:223], v[4:7]
	v_mfma_f32_16x16x32_bf16 v[0:3], v[182:185], v[220:223], v[0:3]
	s_setprio 0
	s_barrier
	s_add_i32 s84, s84, 2
	s_add_u32 s82, s82, 0x100
	s_addc_u32 s83, s83, 0
	s_mov_b64 s[50:51], s[52:53]
.LBB0_1197:
	ds_read_b128 v[144:147], v151
	ds_read_b128 v[156:159], v151 offset:1024
	ds_read_b128 v[160:163], v151 offset:2048
	ds_read_b128 v[164:167], v151 offset:3072
	ds_read_b128 v[168:171], v152
	ds_read_b128 v[172:175], v152 offset:1024
	ds_read_b128 v[176:179], v152 offset:2048
	ds_read_b128 v[182:185], v152 offset:3072
	s_add_u32 s52, s50, 0x100
	s_addc_u32 s53, s51, 0
	s_cmp_eq_u32 s84, 40
	s_cselect_b32 s57, s1, s53
	s_cselect_b32 s56, s0, s52
	s_cselect_b32 s55, s49, s83
	s_cselect_b32 s54, s48, s82
	v_lshl_add_u64 v[224:225], s[50:51], 0, v[136:137]
	s_add_i32 m0, s34, 0xc000
	ds_read_b128 v[186:189], v153
	ds_read_b128 v[190:193], v153 offset:1024
	ds_read_b128 v[194:197], v153 offset:2048
	ds_read_b128 v[198:201], v153 offset:3072
	ds_read_b128 v[208:211], v153 offset:4096
	ds_read_b128 v[212:215], v153 offset:5120
	ds_read_b128 v[216:219], v153 offset:6144
	ds_read_b128 v[220:223], v153 offset:7168
	global_load_lds_dwordx4 v[224:225], off
	v_lshl_add_u64 v[224:225], s[50:51], 0, v[138:139]
	s_add_i32 m0, s34, 0xe000
	s_nop 0
	global_load_lds_dwordx4 v[224:225], off
	s_waitcnt vmcnt(8)
	s_waitcnt lgkmcnt(0)
	s_barrier
; #define PG8_STAGE(bufoff, gbase, voff) do { _Pragma("unroll") for (int _i = 0; _i < 2; ++_i) \
;         __builtin_amdgcn_global_load_lds((const unsigned*)((const char*)(gbase) + (voff)[_i]), (PG8_LAS unsigned*)(lds + (bufoff) + ldsw + _i * 8192), 16, 0, 0); } while (0)
; #define PG8_LDA(dst, b, h) do { _Pragma("unroll") for (int m = 0; m < 4; ++m) _Pragma("unroll") for (int k = 0; k < 2; ++k) dst[m][k] = *(const PG8_LAS bf16x8*)(lds + PG8_SA(b, h) + aoff + m * 2048 + k * 1024); } while (0)
; #define PG8_MMA(ai, bj, At, Bt) do { __builtin_amdgcn_s_setprio(1); _Pragma("unroll") for (int m = 0; m < 4; ++m) _Pragma("unroll") for (int n = 0; n < 2; ++n) _Pragma("unroll") for (int k = 0; k < 2; ++k) \
;         acc[ai][bj][m][n] = __builtin_amdgcn_mfma_f32_16x16x32_bf16(Bt[n][k], At[m][k], acc[ai][bj][m][n], 0, 0, 0); __builtin_amdgcn_s_setprio(0); } while (0)
; #define PG8_WAIT_V(n) asm volatile("s_waitcnt vmcnt(" #n ")" ::: "memory")
; #define PG8_WAIT_L(n) asm volatile("s_waitcnt lgkmcnt(" #n ")" ::: "memory")
; #define PG8_BAR __builtin_amdgcn_s_barrier()
; #define PG8_SCHED __builtin_amdgcn_sched_barrier(0)
; template <class Epi, class Sched, bool ALIGN_EPI = false, bool SP2 = false>
; __device__ __forceinline__ void gemm_phase(PG8_LAS unsigned char* lds, const Gemm g, const Sched& S, const Epi& E) {
;     ...
;             PG8_WAIT_V(8); PG8_WAIT_L(0); PG8_BAR; PG8_MMA(0, 0, At, B0); PG8_MMA(0, 1, At, B1); PG8_BAR; PG8_SCHED;
;             PG8_LDA(At, 0, 1); PG8_STAGE(PG8_SB(0, 0), b2, voffB); PG8_STAGE(PG8_SB(0, 1), b2 + hstep, voffB); PG8_STAGE(PG8_SA(0, 0), a2, voffA);
;             PG8_WAIT_V(8); PG8_WAIT_L(0); PG8_BAR; PG8_MMA(1, 0, At, B0); PG8_MMA(1, 1, At, B1); PG8_BAR; PG8_SCHED;
	s_setprio 1
	s_waitcnt lgkmcnt(0)
	v_mfma_f32_16x16x32_bf16 v[124:127], v[144:147], v[186:189], v[124:127]
	v_mfma_f32_16x16x32_bf16 v[120:123], v[160:163], v[186:189], v[120:123]
	v_mfma_f32_16x16x32_bf16 v[108:111], v[144:147], v[194:197], v[108:111]
	v_mfma_f32_16x16x32_bf16 v[104:107], v[160:163], v[194:197], v[104:107]
	v_mfma_f32_16x16x32_bf16 v[92:95], v[144:147], v[208:211], v[92:95]
	v_mfma_f32_16x16x32_bf16 v[88:91], v[160:163], v[208:211], v[88:91]
	v_mfma_f32_16x16x32_bf16 v[76:79], v[144:147], v[216:219], v[76:79]
	v_mfma_f32_16x16x32_bf16 v[72:75], v[160:163], v[216:219], v[72:75]
	v_mfma_f32_16x16x32_bf16 v[124:127], v[156:159], v[190:193], v[124:127]
	v_mfma_f32_16x16x32_bf16 v[120:123], v[164:167], v[190:193], v[120:123]
	v_mfma_f32_16x16x32_bf16 v[108:111], v[156:159], v[198:201], v[108:111]
	v_mfma_f32_16x16x32_bf16 v[104:107], v[164:167], v[198:201], v[104:107]
	v_mfma_f32_16x16x32_bf16 v[92:95], v[156:159], v[212:215], v[92:95]
	v_mfma_f32_16x16x32_bf16 v[88:91], v[164:167], v[212:215], v[88:91]
	v_mfma_f32_16x16x32_bf16 v[76:79], v[156:159], v[220:223], v[76:79]
	v_mfma_f32_16x16x32_bf16 v[72:75], v[164:167], v[220:223], v[72:75]
	s_setprio 0
	s_setprio 1
	v_mfma_f32_16x16x32_bf16 v[116:119], v[168:171], v[186:189], v[116:119]
	v_mfma_f32_16x16x32_bf16 v[112:115], v[176:179], v[186:189], v[112:115]
	v_mfma_f32_16x16x32_bf16 v[100:103], v[168:171], v[194:197], v[100:103]
	v_mfma_f32_16x16x32_bf16 v[96:99], v[176:179], v[194:197], v[96:99]
	v_mfma_f32_16x16x32_bf16 v[84:87], v[168:171], v[208:211], v[84:87]
	v_mfma_f32_16x16x32_bf16 v[80:83], v[176:179], v[208:211], v[80:83]
	v_mfma_f32_16x16x32_bf16 v[68:71], v[168:171], v[216:219], v[68:71]
	v_mfma_f32_16x16x32_bf16 v[64:67], v[176:179], v[216:219], v[64:67]
	v_mfma_f32_16x16x32_bf16 v[116:119], v[172:175], v[190:193], v[116:119]
	v_mfma_f32_16x16x32_bf16 v[112:115], v[182:185], v[190:193], v[112:115]
	v_mfma_f32_16x16x32_bf16 v[100:103], v[172:175], v[198:201], v[100:103]
	v_mfma_f32_16x16x32_bf16 v[96:99], v[182:185], v[198:201], v[96:99]
	v_mfma_f32_16x16x32_bf16 v[84:87], v[172:175], v[212:215], v[84:87]
	v_mfma_f32_16x16x32_bf16 v[80:83], v[182:185], v[212:215], v[80:83]
	v_mfma_f32_16x16x32_bf16 v[68:71], v[172:175], v[220:223], v[68:71]
	v_mfma_f32_16x16x32_bf16 v[64:67], v[182:185], v[220:223], v[64:67]
	s_setprio 0
	s_barrier
	s_add_i32 s50, s64, s33
	v_lshl_add_u64 v[224:225], s[54:55], 0, v[130:131]
	s_mov_b32 m0, s50
	ds_read_b128 v[186:189], v153 offset:16384
	ds_read_b128 v[190:193], v153 offset:17408
	ds_read_b128 v[194:197], v153 offset:18432
	ds_read_b128 v[198:201], v153 offset:19456
	ds_read_b128 v[208:211], v153 offset:20480
	ds_read_b128 v[212:215], v153 offset:21504
	ds_read_b128 v[216:219], v153 offset:22528
	ds_read_b128 v[220:223], v153 offset:23552
	global_load_lds_dwordx4 v[224:225], off
	s_add_i32 m0, s50, 0x2000
	s_add_u32 s50, s54, 0xb0000
	v_lshl_add_u64 v[226:227], s[54:55], 0, v[134:135]
	s_addc_u32 s51, s55, 0
	s_add_i32 s78, s65, s33
	global_load_lds_dwordx4 v[226:227], off
	v_lshl_add_u64 v[228:229], s[50:51], 0, v[130:131]
	s_mov_b32 m0, s78
	global_load_lds_dwordx4 v[228:229], off
	v_lshl_add_u64 v[228:229], s[50:51], 0, v[134:135]
	s_add_i32 m0, s78, 0x2000
	s_nop 0
	global_load_lds_dwordx4 v[228:229], off
	s_waitcnt vmcnt(6)
	s_waitcnt lgkmcnt(0)
	s_barrier
	s_setprio 1
	s_waitcnt lgkmcnt(0)
	v_mfma_f32_16x16x32_bf16 v[60:63], v[144:147], v[186:189], v[60:63]
	v_mfma_f32_16x16x32_bf16 v[56:59], v[160:163], v[186:189], v[56:59]
	v_mfma_f32_16x16x32_bf16 v[44:47], v[144:147], v[194:197], v[44:47]
	v_mfma_f32_16x16x32_bf16 v[40:43], v[160:163], v[194:197], v[40:43]
	v_mfma_f32_16x16x32_bf16 v[28:31], v[144:147], v[208:211], v[28:31]
	v_mfma_f32_16x16x32_bf16 v[24:27], v[160:163], v[208:211], v[24:27]
	v_mfma_f32_16x16x32_bf16 v[12:15], v[144:147], v[216:219], v[12:15]
	v_mfma_f32_16x16x32_bf16 v[8:11], v[160:163], v[216:219], v[8:11]
	v_mfma_f32_16x16x32_bf16 v[60:63], v[156:159], v[190:193], v[60:63]
	v_mfma_f32_16x16x32_bf16 v[56:59], v[164:167], v[190:193], v[56:59]
	v_mfma_f32_16x16x32_bf16 v[44:47], v[156:159], v[198:201], v[44:47]
	v_mfma_f32_16x16x32_bf16 v[40:43], v[164:167], v[198:201], v[40:43]
	v_mfma_f32_16x16x32_bf16 v[28:31], v[156:159], v[212:215], v[28:31]
	v_mfma_f32_16x16x32_bf16 v[24:27], v[164:167], v[212:215], v[24:27]
	v_lshl_add_u64 v[228:229], s[56:57], 0, v[128:129]
	s_mov_b32 m0, s34
	s_nop 0
	global_load_lds_dwordx4 v[228:229], off
	v_mfma_f32_16x16x32_bf16 v[12:15], v[156:159], v[220:223], v[12:15]
	v_mfma_f32_16x16x32_bf16 v[8:11], v[164:167], v[220:223], v[8:11]
	s_setprio 0
	s_setprio 1
	v_mfma_f32_16x16x32_bf16 v[52:55], v[168:171], v[186:189], v[52:55]
	v_mfma_f32_16x16x32_bf16 v[48:51], v[176:179], v[186:189], v[48:51]
	v_mfma_f32_16x16x32_bf16 v[36:39], v[168:171], v[194:197], v[36:39]
	v_mfma_f32_16x16x32_bf16 v[32:35], v[176:179], v[194:197], v[32:35]
	v_mfma_f32_16x16x32_bf16 v[20:23], v[168:171], v[208:211], v[20:23]
	v_mfma_f32_16x16x32_bf16 v[16:19], v[176:179], v[208:211], v[16:19]
	v_mfma_f32_16x16x32_bf16 v[4:7], v[168:171], v[216:219], v[4:7]
	v_mfma_f32_16x16x32_bf16 v[0:3], v[176:179], v[216:219], v[0:3]
	v_mfma_f32_16x16x32_bf16 v[52:55], v[172:175], v[190:193], v[52:55]
	v_mfma_f32_16x16x32_bf16 v[48:51], v[182:185], v[190:193], v[48:51]
	v_mfma_f32_16x16x32_bf16 v[36:39], v[172:175], v[198:201], v[36:39]
	v_mfma_f32_16x16x32_bf16 v[32:35], v[182:185], v[198:201], v[32:35]
	v_mfma_f32_16x16x32_bf16 v[20:23], v[172:175], v[212:215], v[20:23]
	v_mfma_f32_16x16x32_bf16 v[16:19], v[182:185], v[212:215], v[16:19]
	v_lshl_add_u64 v[230:231], s[56:57], 0, v[132:133]
	s_mov_b32 m0, s58
	s_nop 0
	global_load_lds_dwordx4 v[230:231], off
	v_mfma_f32_16x16x32_bf16 v[4:7], v[172:175], v[220:223], v[4:7]
	v_mfma_f32_16x16x32_bf16 v[0:3], v[182:185], v[220:223], v[0:3]
	s_setprio 0
	s_barrier
; #define PG8_STAGE(bufoff, gbase, voff) do { _Pragma("unroll") for (int _i = 0; _i < 2; ++_i) \
;         __builtin_amdgcn_global_load_lds((const unsigned*)((const char*)(gbase) + (voff)[_i]), (PG8_LAS unsigned*)(lds + (bufoff) + ldsw + _i * 8192), 16, 0, 0); } while (0)
; #define PG8_LDA(dst, b, h) do { _Pragma("unroll") for (int m = 0; m < 4; ++m) _Pragma("unroll") for (int k = 0; k < 2; ++k) dst[m][k] = *(const PG8_LAS bf16x8*)(lds + PG8_SA(b, h) + aoff + m * 2048 + k * 1024); } while (0)
; #define PG8_LDB(dst, b, h) do { _Pragma("unroll") for (int n = 0; n < 2; ++n) _Pragma("unroll") for (int k = 0; k < 2; ++k) dst[n][k] = *(const PG8_LAS bf16x8*)(lds + PG8_SB(b, h) + boff + n * 2048 + k * 1024); } while (0)
; #define PG8_MMA(ai, bj, At, Bt) do { __builtin_amdgcn_s_setprio(1); _Pragma("unroll") for (int m = 0; m < 4; ++m) _Pragma("unroll") for (int n = 0; n < 2; ++n) _Pragma("unroll") for (int k = 0; k < 2; ++k) \
;         acc[ai][bj][m][n] = __builtin_amdgcn_mfma_f32_16x16x32_bf16(Bt[n][k], At[m][k], acc[ai][bj][m][n], 0, 0, 0); __builtin_amdgcn_s_setprio(0); } while (0)
; #define PG8_WAIT_V(n) asm volatile("s_waitcnt vmcnt(" #n ")" ::: "memory")
; #define PG8_WAIT_L(n) asm volatile("s_waitcnt lgkmcnt(" #n ")" ::: "memory")
; #define PG8_BAR __builtin_amdgcn_s_barrier()
; #define PG8_SCHED __builtin_amdgcn_sched_barrier(0)
; template <class Epi, class Sched, bool ALIGN_EPI = false, bool SP2 = false>
; __device__ __forceinline__ void gemm_phase(PG8_LAS unsigned char* lds, const Gemm g, const Sched& S, const Epi& E) {
;     ...
;             PG8_LDB(B0, 1, 0); PG8_LDB(B1, 1, 1); PG8_SCHED; PG8_LDA(At, 1, 0); PG8_STAGE(PG8_SA(0, 1), a2 + hstep, voffA);
;             PG8_WAIT_V(8); PG8_WAIT_L(0); PG8_BAR; PG8_MMA(0, 0, At, B0); PG8_MMA(0, 1, At, B1); PG8_BAR; PG8_SCHED;
	s_add_i32 s78, 0, 0x18000
	v_add_u32_e32 v155, s78, v149
	s_add_i32 s79, 0, 0x1c000
	ds_read_b128 v[144:147], v155
	ds_read_b128 v[156:159], v155 offset:1024
	ds_read_b128 v[160:163], v155 offset:2048
	ds_read_b128 v[164:167], v155 offset:3072
	v_add_u32_e32 v155, s79, v149
	ds_read_b128 v[168:171], v155
	ds_read_b128 v[172:175], v155 offset:1024
	ds_read_b128 v[176:179], v155 offset:2048
	ds_read_b128 v[182:185], v155 offset:3072
	s_add_u32 s50, s56, 0xb0000
	s_addc_u32 s51, s57, 0
	s_mov_b32 m0, s59
	v_lshl_add_u64 v[232:233], s[50:51], 0, v[128:129]
	ds_read_b128 v[186:189], v153 offset:32768
	ds_read_b128 v[190:193], v153 offset:33792
	ds_read_b128 v[194:197], v153 offset:34816
	ds_read_b128 v[198:201], v153 offset:35840
	ds_read_b128 v[208:211], v153 offset:36864
	ds_read_b128 v[212:215], v153 offset:37888
	ds_read_b128 v[216:219], v153 offset:38912
	ds_read_b128 v[220:223], v153 offset:39936
	global_load_lds_dwordx4 v[232:233], off
	v_lshl_add_u64 v[232:233], s[50:51], 0, v[132:133]
	s_mov_b32 m0, s60
	s_nop 0
	global_load_lds_dwordx4 v[232:233], off
	s_waitcnt vmcnt(8)
	s_waitcnt lgkmcnt(0)
	s_barrier
	s_setprio 1
	s_waitcnt lgkmcnt(0)
	v_mfma_f32_16x16x32_bf16 v[124:127], v[144:147], v[186:189], v[124:127]
	v_mfma_f32_16x16x32_bf16 v[120:123], v[160:163], v[186:189], v[120:123]
	v_mfma_f32_16x16x32_bf16 v[108:111], v[144:147], v[194:197], v[108:111]
	v_mfma_f32_16x16x32_bf16 v[104:107], v[160:163], v[194:197], v[104:107]
	v_mfma_f32_16x16x32_bf16 v[92:95], v[144:147], v[208:211], v[92:95]
	v_mfma_f32_16x16x32_bf16 v[88:91], v[160:163], v[208:211], v[88:91]
	v_mfma_f32_16x16x32_bf16 v[76:79], v[144:147], v[216:219], v[76:79]
	v_mfma_f32_16x16x32_bf16 v[72:75], v[160:163], v[216:219], v[72:75]
	v_mfma_f32_16x16x32_bf16 v[124:127], v[156:159], v[190:193], v[124:127]
	v_mfma_f32_16x16x32_bf16 v[120:123], v[164:167], v[190:193], v[120:123]
	v_mfma_f32_16x16x32_bf16 v[108:111], v[156:159], v[198:201], v[108:111]
	v_mfma_f32_16x16x32_bf16 v[104:107], v[164:167], v[198:201], v[104:107]
	v_mfma_f32_16x16x32_bf16 v[92:95], v[156:159], v[212:215], v[92:95]
	v_mfma_f32_16x16x32_bf16 v[88:91], v[164:167], v[212:215], v[88:91]
	v_mfma_f32_16x16x32_bf16 v[76:79], v[156:159], v[220:223], v[76:79]
	v_mfma_f32_16x16x32_bf16 v[72:75], v[164:167], v[220:223], v[72:75]
	s_setprio 0
	s_setprio 1
	v_mfma_f32_16x16x32_bf16 v[116:119], v[168:171], v[186:189], v[116:119]
	v_mfma_f32_16x16x32_bf16 v[112:115], v[176:179], v[186:189], v[112:115]
	v_mfma_f32_16x16x32_bf16 v[100:103], v[168:171], v[194:197], v[100:103]
	v_mfma_f32_16x16x32_bf16 v[96:99], v[176:179], v[194:197], v[96:99]
	v_mfma_f32_16x16x32_bf16 v[84:87], v[168:171], v[208:211], v[84:87]
	v_mfma_f32_16x16x32_bf16 v[80:83], v[176:179], v[208:211], v[80:83]
	v_mfma_f32_16x16x32_bf16 v[68:71], v[168:171], v[216:219], v[68:71]
	v_mfma_f32_16x16x32_bf16 v[64:67], v[176:179], v[216:219], v[64:67]
	v_mfma_f32_16x16x32_bf16 v[116:119], v[172:175], v[190:193], v[116:119]
	v_mfma_f32_16x16x32_bf16 v[112:115], v[182:185], v[190:193], v[112:115]
	v_mfma_f32_16x16x32_bf16 v[100:103], v[172:175], v[198:201], v[100:103]
	v_mfma_f32_16x16x32_bf16 v[96:99], v[182:185], v[198:201], v[96:99]
	v_mfma_f32_16x16x32_bf16 v[84:87], v[172:175], v[212:215], v[84:87]
	v_mfma_f32_16x16x32_bf16 v[80:83], v[182:185], v[212:215], v[80:83]
	v_mfma_f32_16x16x32_bf16 v[68:71], v[172:175], v[220:223], v[68:71]
	v_mfma_f32_16x16x32_bf16 v[64:67], v[182:185], v[220:223], v[64:67]
	s_setprio 0
	s_barrier
; #define PG8_STAGE(bufoff, gbase, voff) do { _Pragma("unroll") for (int _i = 0; _i < 2; ++_i) \
;         __builtin_amdgcn_global_load_lds((const unsigned*)((const char*)(gbase) + (voff)[_i]), (PG8_LAS unsigned*)(lds + (bufoff) + ldsw + _i * 8192), 16, 0, 0); } while (0)
; #define PG8_LDA(dst, b, h) do { _Pragma("unroll") for (int m = 0; m < 4; ++m) _Pragma("unroll") for (int k = 0; k < 2; ++k) dst[m][k] = *(const PG8_LAS bf16x8*)(lds + PG8_SA(b, h) + aoff + m * 2048 + k * 1024); } while (0)
; #define PG8_MMA(ai, bj, At, Bt) do { __builtin_amdgcn_s_setprio(1); _Pragma("unroll") for (int m = 0; m < 4; ++m) _Pragma("unroll") for (int n = 0; n < 2; ++n) _Pragma("unroll") for (int k = 0; k < 2; ++k) \
;         acc[ai][bj][m][n] = __builtin_amdgcn_mfma_f32_16x16x32_bf16(Bt[n][k], At[m][k], acc[ai][bj][m][n], 0, 0, 0); __builtin_amdgcn_s_setprio(0); } while (0)
; #define PG8_WAIT_V(n) asm volatile("s_waitcnt vmcnt(" #n ")" ::: "memory")
; #define PG8_WAIT_L(n) asm volatile("s_waitcnt lgkmcnt(" #n ")" ::: "memory")
; #define PG8_BAR __builtin_amdgcn_s_barrier()
; #define PG8_SCHED __builtin_amdgcn_sched_barrier(0)
; template <class Epi, class Sched, bool ALIGN_EPI = false, bool SP2 = false>
; __device__ __forceinline__ void gemm_phase(PG8_LAS unsigned char* lds, const Gemm g, const Sched& S, const Epi& E) {
;     ...
;             PG8_LDA(At, 1, 1); PG8_STAGE(PG8_SB(1, 0), b3, voffB); PG8_STAGE(PG8_SB(1, 1), b3 + hstep, voffB); PG8_STAGE(PG8_SA(1, 0), a3, voffA);
;             PG8_WAIT_V(8); PG8_WAIT_L(0); PG8_BAR; PG8_MMA(1, 0, At, B0); PG8_MMA(1, 1, At, B1); PG8_BAR; PG8_SCHED;
;     ...
;         if constexpr (ALIGN_EPI) { if (wr == 0) PG8_BAR; }
	s_add_i32 s50, s78, s33
	v_lshl_add_u64 v[224:225], v[224:225], 0, s[42:43]
	s_mov_b32 m0, s50
	ds_read_b128 v[186:189], v153 offset:49152
	ds_read_b128 v[190:193], v153 offset:50176
	ds_read_b128 v[194:197], v153 offset:51200
	ds_read_b128 v[198:201], v153 offset:52224
	ds_read_b128 v[208:211], v153 offset:53248
	ds_read_b128 v[212:215], v153 offset:54272
	ds_read_b128 v[216:219], v153 offset:55296
	ds_read_b128 v[220:223], v153 offset:56320
	global_load_lds_dwordx4 v[224:225], off
	s_add_i32 m0, s50, 0x2000
	s_add_u32 s50, s54, 0xb0080
	v_lshl_add_u64 v[224:225], v[226:227], 0, s[42:43]
	s_addc_u32 s51, s55, 0
	s_add_i32 s54, s79, s33
	global_load_lds_dwordx4 v[224:225], off
	v_lshl_add_u64 v[224:225], s[50:51], 0, v[130:131]
	s_mov_b32 m0, s54
	s_nop 0
	global_load_lds_dwordx4 v[224:225], off
	v_lshl_add_u64 v[224:225], s[50:51], 0, v[134:135]
	s_add_i32 m0, s54, 0x2000
	s_nop 0
	global_load_lds_dwordx4 v[224:225], off
	s_waitcnt vmcnt(6)
	s_waitcnt lgkmcnt(0)
	s_barrier
	s_setprio 1
	s_waitcnt lgkmcnt(0)
	v_mfma_f32_16x16x32_bf16 v[60:63], v[144:147], v[186:189], v[60:63]
	v_mfma_f32_16x16x32_bf16 v[56:59], v[160:163], v[186:189], v[56:59]
	v_mfma_f32_16x16x32_bf16 v[44:47], v[144:147], v[194:197], v[44:47]
	v_mfma_f32_16x16x32_bf16 v[40:43], v[160:163], v[194:197], v[40:43]
	v_mfma_f32_16x16x32_bf16 v[28:31], v[144:147], v[208:211], v[28:31]
	v_mfma_f32_16x16x32_bf16 v[24:27], v[160:163], v[208:211], v[24:27]
	v_mfma_f32_16x16x32_bf16 v[12:15], v[144:147], v[216:219], v[12:15]
	v_mfma_f32_16x16x32_bf16 v[8:11], v[160:163], v[216:219], v[8:11]
	v_mfma_f32_16x16x32_bf16 v[60:63], v[156:159], v[190:193], v[60:63]
	v_mfma_f32_16x16x32_bf16 v[56:59], v[164:167], v[190:193], v[56:59]
	v_mfma_f32_16x16x32_bf16 v[44:47], v[156:159], v[198:201], v[44:47]
	v_mfma_f32_16x16x32_bf16 v[40:43], v[164:167], v[198:201], v[40:43]
	v_mfma_f32_16x16x32_bf16 v[28:31], v[156:159], v[212:215], v[28:31]
	v_mfma_f32_16x16x32_bf16 v[24:27], v[164:167], v[212:215], v[24:27]
	v_lshl_add_u64 v[224:225], v[228:229], 0, s[42:43]
	s_mov_b32 m0, s62
	s_nop 0
	global_load_lds_dwordx4 v[224:225], off
	v_mfma_f32_16x16x32_bf16 v[12:15], v[156:159], v[220:223], v[12:15]
	v_mfma_f32_16x16x32_bf16 v[8:11], v[164:167], v[220:223], v[8:11]
	s_setprio 0
	s_setprio 1
	v_mfma_f32_16x16x32_bf16 v[52:55], v[168:171], v[186:189], v[52:55]
	v_mfma_f32_16x16x32_bf16 v[48:51], v[176:179], v[186:189], v[48:51]
	v_mfma_f32_16x16x32_bf16 v[36:39], v[168:171], v[194:197], v[36:39]
	v_mfma_f32_16x16x32_bf16 v[32:35], v[176:179], v[194:197], v[32:35]
	v_mfma_f32_16x16x32_bf16 v[20:23], v[168:171], v[208:211], v[20:23]
	v_mfma_f32_16x16x32_bf16 v[16:19], v[176:179], v[208:211], v[16:19]
	v_mfma_f32_16x16x32_bf16 v[4:7], v[168:171], v[216:219], v[4:7]
	v_mfma_f32_16x16x32_bf16 v[0:3], v[176:179], v[216:219], v[0:3]
	v_mfma_f32_16x16x32_bf16 v[52:55], v[172:175], v[190:193], v[52:55]
	v_mfma_f32_16x16x32_bf16 v[48:51], v[182:185], v[190:193], v[48:51]
	v_mfma_f32_16x16x32_bf16 v[36:39], v[172:175], v[198:201], v[36:39]
	v_mfma_f32_16x16x32_bf16 v[32:35], v[182:185], v[198:201], v[32:35]
	v_mfma_f32_16x16x32_bf16 v[20:23], v[172:175], v[212:215], v[20:23]
	v_mfma_f32_16x16x32_bf16 v[16:19], v[182:185], v[212:215], v[16:19]
	v_lshl_add_u64 v[224:225], v[230:231], 0, s[42:43]
	s_mov_b32 m0, s63
	s_nop 0
	global_load_lds_dwordx4 v[224:225], off
	v_mfma_f32_16x16x32_bf16 v[4:7], v[172:175], v[220:223], v[4:7]
	v_mfma_f32_16x16x32_bf16 v[0:3], v[182:185], v[220:223], v[0:3]
	s_setprio 0
	s_barrier
	s_add_i32 s84, s84, 2
	s_add_u32 s82, s82, 0x100
	s_addc_u32 s83, s83, 0
	s_cmp_gt_u32 s84, 41
	s_mov_b64 s[50:51], s[52:53]
	s_cbranch_scc0 .LBB0_1197
	s_and_b64 vcc, exec, s[44:45]
	s_cbranch_vccz .LBB0_1200
	s_barrier

; #define PG8_STAGE(bufoff, gbase, voff) do { _Pragma("unroll") for (int _i = 0; _i < 2; ++_i) \
;         __builtin_amdgcn_global_load_lds((const unsigned*)((const char*)(gbase) + (voff)[_i]), (PG8_LAS unsigned*)(lds + (bufoff) + ldsw + _i * 8192), 16, 0, 0); } while (0)
; #define PG8_LDA(dst, b, h) do { _Pragma("unroll") for (int m = 0; m < 4; ++m) _Pragma("unroll") for (int k = 0; k < 2; ++k) dst[m][k] = *(const PG8_LAS bf16x8*)(lds + PG8_SA(b, h) + aoff + m * 2048 + k * 1024); } while (0)
; #define PG8_LDB(dst, b, h) do { _Pragma("unroll") for (int n = 0; n < 2; ++n) _Pragma("unroll") for (int k = 0; k < 2; ++k) dst[n][k] = *(const PG8_LAS bf16x8*)(lds + PG8_SB(b, h) + boff + n * 2048 + k * 1024); } while (0)
; #define PG8_MMA(ai, bj, At, Bt) do { __builtin_amdgcn_s_setprio(1); _Pragma("unroll") for (int m = 0; m < 4; ++m) _Pragma("unroll") for (int n = 0; n < 2; ++n) _Pragma("unroll") for (int k = 0; k < 2; ++k) \
;         acc[ai][bj][m][n] = __builtin_amdgcn_mfma_f32_16x16x32_bf16(Bt[n][k], At[m][k], acc[ai][bj][m][n], 0, 0, 0); __builtin_amdgcn_s_setprio(0); } while (0)
; #define PG8_WAIT_V(n) asm volatile("s_waitcnt vmcnt(" #n ")" ::: "memory")
; #define PG8_BAR __builtin_amdgcn_s_barrier()
; template <class Epi, class Sched, bool ALIGN_EPI = false, bool SP2 = false>
; __device__ __forceinline__ void gemm_phase(PG8_LAS unsigned char* lds, const Gemm g, const Sched& S, const Epi& E) {
;     ...
;         for (int t = 0; t < nt; t += 2) {
;             const bool last = (t == nt - 2);
;             const char* a1 = cA + (size_t)(t + 1) * kstep;
;             const char* a2 = last ? nA : cA + (size_t)(t + 2) * kstep; const char* b2 = last ? nB : cB + (size_t)(t + 2) * kstep;
;             const char* a3 = a2 + kstep; const char* b3 = b2 + kstep;
;             if (last && has_next) S.a_ready(nxt);
;             if constexpr (SP2) {
;             PG8_LDB(B0, 0, 0); PG8_LDB(B1, 0, 1); PG8_SCHED; PG8_LDA(At, 0, 0); PG8_STAGE(PG8_SA(1, 1), a1 + hstep, voffA);
;             PG8_WAIT_V(8); PG8_WAIT_L(0); PG8_BAR; PG8_MMA(0, 0, At, B0); PG8_MMA(0, 1, At, B1); PG8_BAR; PG8_SCHED;
;             PG8_LDA(At, 0, 1); PG8_STAGE(PG8_SB(0, 0), b2, voffB); PG8_STAGE(PG8_SB(0, 1), b2 + hstep, voffB); PG8_STAGE(PG8_SA(0, 0), a2, voffA);
;             PG8_WAIT_V(8); PG8_WAIT_L(0); PG8_BAR; PG8_MMA(1, 0, At, B0); PG8_MMA(1, 1, At, B1); PG8_BAR; PG8_SCHED;
.LBB0_1286:
	s_ashr_i32 s51, s50, 31
	s_lshl_b64 s[52:53], s[50:51], 19
	s_add_u32 s52, s22, s52
	s_addc_u32 s53, s23, s53
	s_and_b64 s[54:55], s[12:13], exec
	s_cselect_b32 s51, s53, s59
	s_cselect_b32 s61, s52, s58
	s_ashr_i32 s49, s48, 31
	s_lshl_b64 s[54:55], s[48:49], 19
	v_readlane_b32 s64, v250, 9
	v_readlane_b32 s65, v250, 10
	s_add_u32 s54, s64, s54
	s_addc_u32 s55, s65, s55
	s_and_b64 s[64:65], s[12:13], exec
	s_cselect_b32 s49, s55, s63
	s_cselect_b32 s87, s54, s62
	s_add_u32 s58, s58, 0x40080
	s_addc_u32 s59, s59, 0
	s_add_u32 s88, s62, 0x100
	s_addc_u32 s89, s63, 0
	s_mov_b32 s90, -2
	s_waitcnt lgkmcnt(0)
	ds_read_b128 v[128:131], v181
	ds_read_b128 v[160:163], v181 offset:1024
	ds_read_b128 v[164:167], v181 offset:2048
	ds_read_b128 v[168:171], v181 offset:3072
	ds_read_b128 v[172:175], v203
	ds_read_b128 v[176:179], v203 offset:1024
	ds_read_b128 v[182:185], v203 offset:2048
	ds_read_b128 v[186:189], v203 offset:3072
	s_add_u32 s62, s58, 0xfffc0080
	s_addc_u32 s63, s59, -1
	s_cmp_eq_u32 s90, 12
	s_cselect_b32 s65, s51, s63
	s_cselect_b32 s64, s61, s62
	s_cselect_b32 s63, s49, s89
	s_cselect_b32 s62, s87, s88
	v_lshl_add_u64 v[232:233], s[58:59], 0, v[152:153]
	s_add_i32 m0, s15, 0xc000
	ds_read_b128 v[190:193], v208
	ds_read_b128 v[194:197], v208 offset:1024
	ds_read_b128 v[198:201], v208 offset:2048
	ds_read_b128 v[212:215], v208 offset:3072
	ds_read_b128 v[216:219], v208 offset:4096
	ds_read_b128 v[220:223], v208 offset:5120
	ds_read_b128 v[224:227], v208 offset:6144
	ds_read_b128 v[228:231], v208 offset:7168
	global_load_lds_dwordx4 v[232:233], off
	v_lshl_add_u64 v[232:233], s[58:59], 0, v[154:155]
	s_add_i32 m0, s15, 0xe000
	s_nop 0
	global_load_lds_dwordx4 v[232:233], off
	s_waitcnt vmcnt(8)
	s_waitcnt lgkmcnt(0)
	s_barrier
	s_setprio 1
	s_waitcnt lgkmcnt(0)
	v_mfma_f32_16x16x32_bf16 v[124:127], v[128:131], v[190:193], 0
	v_mfma_f32_16x16x32_bf16 v[120:123], v[164:167], v[190:193], 0
	v_mfma_f32_16x16x32_bf16 v[116:119], v[128:131], v[198:201], 0
	v_mfma_f32_16x16x32_bf16 v[112:115], v[164:167], v[198:201], 0
	v_mfma_f32_16x16x32_bf16 v[108:111], v[128:131], v[216:219], 0
	v_mfma_f32_16x16x32_bf16 v[104:107], v[164:167], v[216:219], 0
	v_mfma_f32_16x16x32_bf16 v[100:103], v[128:131], v[224:227], 0
	v_mfma_f32_16x16x32_bf16 v[96:99], v[164:167], v[224:227], 0
	v_mfma_f32_16x16x32_bf16 v[124:127], v[160:163], v[194:197], v[124:127]
	v_mfma_f32_16x16x32_bf16 v[120:123], v[168:171], v[194:197], v[120:123]
	v_mfma_f32_16x16x32_bf16 v[116:119], v[160:163], v[212:215], v[116:119]
	v_mfma_f32_16x16x32_bf16 v[112:115], v[168:171], v[212:215], v[112:115]
	v_mfma_f32_16x16x32_bf16 v[108:111], v[160:163], v[220:223], v[108:111]
	v_mfma_f32_16x16x32_bf16 v[104:107], v[168:171], v[220:223], v[104:107]
	v_mfma_f32_16x16x32_bf16 v[100:103], v[160:163], v[228:231], v[100:103]
	v_mfma_f32_16x16x32_bf16 v[96:99], v[168:171], v[228:231], v[96:99]
	s_setprio 0
	s_setprio 1
	v_mfma_f32_16x16x32_bf16 v[60:63], v[172:175], v[190:193], 0
	v_mfma_f32_16x16x32_bf16 v[56:59], v[182:185], v[190:193], 0
	v_mfma_f32_16x16x32_bf16 v[52:55], v[172:175], v[198:201], 0
	v_mfma_f32_16x16x32_bf16 v[48:51], v[182:185], v[198:201], 0
	v_mfma_f32_16x16x32_bf16 v[44:47], v[172:175], v[216:219], 0
	v_mfma_f32_16x16x32_bf16 v[40:43], v[182:185], v[216:219], 0
	v_mfma_f32_16x16x32_bf16 v[36:39], v[172:175], v[224:227], 0
	v_mfma_f32_16x16x32_bf16 v[32:35], v[182:185], v[224:227], 0
	v_mfma_f32_16x16x32_bf16 v[60:63], v[176:179], v[194:197], v[60:63]
	v_mfma_f32_16x16x32_bf16 v[56:59], v[186:189], v[194:197], v[56:59]
	v_mfma_f32_16x16x32_bf16 v[52:55], v[176:179], v[212:215], v[52:55]
	v_mfma_f32_16x16x32_bf16 v[48:51], v[186:189], v[212:215], v[48:51]
	v_mfma_f32_16x16x32_bf16 v[44:47], v[176:179], v[220:223], v[44:47]
	v_mfma_f32_16x16x32_bf16 v[40:43], v[186:189], v[220:223], v[40:43]
	v_mfma_f32_16x16x32_bf16 v[36:39], v[176:179], v[228:231], v[36:39]
	v_mfma_f32_16x16x32_bf16 v[32:35], v[186:189], v[228:231], v[32:35]
	s_setprio 0
	s_barrier
	s_add_i32 s78, s75, s14
	v_lshl_add_u64 v[232:233], s[62:63], 0, v[134:135]
	s_mov_b32 m0, s78
	ds_read_b128 v[190:193], v208 offset:16384
	ds_read_b128 v[194:197], v208 offset:17408
	ds_read_b128 v[198:201], v208 offset:18432
	ds_read_b128 v[212:215], v208 offset:19456
	ds_read_b128 v[216:219], v208 offset:20480
	ds_read_b128 v[220:223], v208 offset:21504
	ds_read_b128 v[224:227], v208 offset:22528
	ds_read_b128 v[228:231], v208 offset:23552
	global_load_lds_dwordx4 v[232:233], off
	s_add_i32 m0, s78, 0x2000
	s_add_u32 s78, s62, 0x40000
	v_lshl_add_u64 v[234:235], s[62:63], 0, v[138:139]
	s_addc_u32 s79, s63, 0
	s_add_i32 s91, s76, s14
	global_load_lds_dwordx4 v[234:235], off
	v_lshl_add_u64 v[236:237], s[78:79], 0, v[134:135]
	s_mov_b32 m0, s91
	global_load_lds_dwordx4 v[236:237], off
	v_lshl_add_u64 v[236:237], s[78:79], 0, v[138:139]
	s_add_i32 m0, s91, 0x2000
	s_nop 0
	global_load_lds_dwordx4 v[236:237], off
	s_waitcnt vmcnt(6)
	s_waitcnt lgkmcnt(0)
	s_barrier
; #define PG8_STAGE(bufoff, gbase, voff) do { _Pragma("unroll") for (int _i = 0; _i < 2; ++_i) \
;         __builtin_amdgcn_global_load_lds((const unsigned*)((const char*)(gbase) + (voff)[_i]), (PG8_LAS unsigned*)(lds + (bufoff) + ldsw + _i * 8192), 16, 0, 0); } while (0)
; #define PG8_LDA(dst, b, h) do { _Pragma("unroll") for (int m = 0; m < 4; ++m) _Pragma("unroll") for (int k = 0; k < 2; ++k) dst[m][k] = *(const PG8_LAS bf16x8*)(lds + PG8_SA(b, h) + aoff + m * 2048 + k * 1024); } while (0)
; #define PG8_LDB(dst, b, h) do { _Pragma("unroll") for (int n = 0; n < 2; ++n) _Pragma("unroll") for (int k = 0; k < 2; ++k) dst[n][k] = *(const PG8_LAS bf16x8*)(lds + PG8_SB(b, h) + boff + n * 2048 + k * 1024); } while (0)
; #define PG8_MMA(ai, bj, At, Bt) do { __builtin_amdgcn_s_setprio(1); _Pragma("unroll") for (int m = 0; m < 4; ++m) _Pragma("unroll") for (int n = 0; n < 2; ++n) _Pragma("unroll") for (int k = 0; k < 2; ++k) \
;         acc[ai][bj][m][n] = __builtin_amdgcn_mfma_f32_16x16x32_bf16(Bt[n][k], At[m][k], acc[ai][bj][m][n], 0, 0, 0); __builtin_amdgcn_s_setprio(0); } while (0)
; #define PG8_WAIT_V(n) asm volatile("s_waitcnt vmcnt(" #n ")" ::: "memory")
; #define PG8_WAIT_L(n) asm volatile("s_waitcnt lgkmcnt(" #n ")" ::: "memory")
; #define PG8_BAR __builtin_amdgcn_s_barrier()
; #define PG8_SCHED __builtin_amdgcn_sched_barrier(0)
; template <class Epi, class Sched, bool ALIGN_EPI = false, bool SP2 = false>
; __device__ __forceinline__ void gemm_phase(PG8_LAS unsigned char* lds, const Gemm g, const Sched& S, const Epi& E) {
;     ...
;             PG8_WAIT_V(8); PG8_WAIT_L(0); PG8_BAR; PG8_MMA(1, 0, At, B0); PG8_MMA(1, 1, At, B1); PG8_BAR; PG8_SCHED;
;             PG8_LDB(B0, 1, 0); PG8_LDB(B1, 1, 1); PG8_SCHED; PG8_LDA(At, 1, 0); PG8_STAGE(PG8_SA(0, 1), a2 + hstep, voffA);
;             PG8_WAIT_V(8); PG8_WAIT_L(0); PG8_BAR; PG8_MMA(0, 0, At, B0); PG8_MMA(0, 1, At, B1); PG8_BAR; PG8_SCHED;
	s_setprio 1
	s_waitcnt lgkmcnt(0)
	v_mfma_f32_16x16x32_bf16 v[92:95], v[128:131], v[190:193], 0
	v_mfma_f32_16x16x32_bf16 v[88:91], v[164:167], v[190:193], 0
	v_mfma_f32_16x16x32_bf16 v[84:87], v[128:131], v[198:201], 0
	v_mfma_f32_16x16x32_bf16 v[80:83], v[164:167], v[198:201], 0
	v_mfma_f32_16x16x32_bf16 v[76:79], v[128:131], v[216:219], 0
	v_mfma_f32_16x16x32_bf16 v[72:75], v[164:167], v[216:219], 0
	v_mfma_f32_16x16x32_bf16 v[68:71], v[128:131], v[224:227], 0
	v_mfma_f32_16x16x32_bf16 v[64:67], v[164:167], v[224:227], 0
	v_mfma_f32_16x16x32_bf16 v[92:95], v[160:163], v[194:197], v[92:95]
	v_mfma_f32_16x16x32_bf16 v[88:91], v[168:171], v[194:197], v[88:91]
	v_mfma_f32_16x16x32_bf16 v[84:87], v[160:163], v[212:215], v[84:87]
	v_mfma_f32_16x16x32_bf16 v[80:83], v[168:171], v[212:215], v[80:83]
	v_mfma_f32_16x16x32_bf16 v[76:79], v[160:163], v[220:223], v[76:79]
	v_mfma_f32_16x16x32_bf16 v[72:75], v[168:171], v[220:223], v[72:75]
	v_lshl_add_u64 v[236:237], s[64:65], 0, v[132:133]
	s_mov_b32 m0, s15
	s_nop 0
	global_load_lds_dwordx4 v[236:237], off
	v_mfma_f32_16x16x32_bf16 v[68:71], v[160:163], v[228:231], v[68:71]
	v_mfma_f32_16x16x32_bf16 v[64:67], v[168:171], v[228:231], v[64:67]
	s_setprio 0
	s_setprio 1
	v_mfma_f32_16x16x32_bf16 v[28:31], v[172:175], v[190:193], 0
	v_mfma_f32_16x16x32_bf16 v[24:27], v[182:185], v[190:193], 0
	v_mfma_f32_16x16x32_bf16 v[20:23], v[172:175], v[198:201], 0
	v_mfma_f32_16x16x32_bf16 v[16:19], v[182:185], v[198:201], 0
	v_mfma_f32_16x16x32_bf16 v[12:15], v[172:175], v[216:219], 0
	v_mfma_f32_16x16x32_bf16 v[8:11], v[182:185], v[216:219], 0
	v_mfma_f32_16x16x32_bf16 v[4:7], v[172:175], v[224:227], 0
	v_mfma_f32_16x16x32_bf16 v[0:3], v[182:185], v[224:227], 0
	v_mfma_f32_16x16x32_bf16 v[28:31], v[176:179], v[194:197], v[28:31]
	v_mfma_f32_16x16x32_bf16 v[24:27], v[186:189], v[194:197], v[24:27]
	v_mfma_f32_16x16x32_bf16 v[20:23], v[176:179], v[212:215], v[20:23]
	v_mfma_f32_16x16x32_bf16 v[16:19], v[186:189], v[212:215], v[16:19]
	v_mfma_f32_16x16x32_bf16 v[12:15], v[176:179], v[220:223], v[12:15]
	v_mfma_f32_16x16x32_bf16 v[8:11], v[186:189], v[220:223], v[8:11]
	v_lshl_add_u64 v[238:239], s[64:65], 0, v[136:137]
	s_mov_b32 m0, s33
	s_nop 0
	global_load_lds_dwordx4 v[238:239], off
	v_mfma_f32_16x16x32_bf16 v[4:7], v[176:179], v[228:231], v[4:7]
	v_mfma_f32_16x16x32_bf16 v[0:3], v[186:189], v[228:231], v[0:3]
	s_setprio 0
	s_barrier
	s_add_i32 s78, 0, 0x18000
	v_add_u32_e32 v140, s78, v147
	s_add_i32 s79, 0, 0x1c000
	ds_read_b128 v[128:131], v140
	ds_read_b128 v[160:163], v140 offset:1024
	ds_read_b128 v[164:167], v140 offset:2048
	ds_read_b128 v[168:171], v140 offset:3072
	v_add_u32_e32 v140, s79, v147
	ds_read_b128 v[172:175], v140
	ds_read_b128 v[176:179], v140 offset:1024
	ds_read_b128 v[182:185], v140 offset:2048
	ds_read_b128 v[186:189], v140 offset:3072
	s_add_u32 s64, s64, 0x40000
	s_addc_u32 s65, s65, 0
	s_mov_b32 m0, s34
	v_lshl_add_u64 v[240:241], s[64:65], 0, v[132:133]
	ds_read_b128 v[190:193], v208 offset:32768
	ds_read_b128 v[194:197], v208 offset:33792
	ds_read_b128 v[198:201], v208 offset:34816
	ds_read_b128 v[212:215], v208 offset:35840
	ds_read_b128 v[216:219], v208 offset:36864
	ds_read_b128 v[220:223], v208 offset:37888
	ds_read_b128 v[224:227], v208 offset:38912
	ds_read_b128 v[228:231], v208 offset:39936
	global_load_lds_dwordx4 v[240:241], off
	v_lshl_add_u64 v[240:241], s[64:65], 0, v[136:137]
	s_mov_b32 m0, s57
	s_nop 0
	global_load_lds_dwordx4 v[240:241], off
	s_waitcnt vmcnt(8)
	s_waitcnt lgkmcnt(0)
	s_barrier
	s_setprio 1
	s_waitcnt lgkmcnt(0)
	v_mfma_f32_16x16x32_bf16 v[124:127], v[128:131], v[190:193], v[124:127]
	v_mfma_f32_16x16x32_bf16 v[120:123], v[164:167], v[190:193], v[120:123]
	v_mfma_f32_16x16x32_bf16 v[116:119], v[128:131], v[198:201], v[116:119]
	v_mfma_f32_16x16x32_bf16 v[112:115], v[164:167], v[198:201], v[112:115]
	v_mfma_f32_16x16x32_bf16 v[108:111], v[128:131], v[216:219], v[108:111]
	v_mfma_f32_16x16x32_bf16 v[104:107], v[164:167], v[216:219], v[104:107]
	v_mfma_f32_16x16x32_bf16 v[100:103], v[128:131], v[224:227], v[100:103]
	v_mfma_f32_16x16x32_bf16 v[96:99], v[164:167], v[224:227], v[96:99]
	v_mfma_f32_16x16x32_bf16 v[124:127], v[160:163], v[194:197], v[124:127]
	v_mfma_f32_16x16x32_bf16 v[120:123], v[168:171], v[194:197], v[120:123]
	v_mfma_f32_16x16x32_bf16 v[116:119], v[160:163], v[212:215], v[116:119]
	v_mfma_f32_16x16x32_bf16 v[112:115], v[168:171], v[212:215], v[112:115]
	v_mfma_f32_16x16x32_bf16 v[108:111], v[160:163], v[220:223], v[108:111]
	v_mfma_f32_16x16x32_bf16 v[104:107], v[168:171], v[220:223], v[104:107]
	v_mfma_f32_16x16x32_bf16 v[100:103], v[160:163], v[228:231], v[100:103]
	v_mfma_f32_16x16x32_bf16 v[96:99], v[168:171], v[228:231], v[96:99]
	s_setprio 0
	s_setprio 1
	v_mfma_f32_16x16x32_bf16 v[60:63], v[172:175], v[190:193], v[60:63]
	v_mfma_f32_16x16x32_bf16 v[56:59], v[182:185], v[190:193], v[56:59]
	v_mfma_f32_16x16x32_bf16 v[52:55], v[172:175], v[198:201], v[52:55]
	v_mfma_f32_16x16x32_bf16 v[48:51], v[182:185], v[198:201], v[48:51]
	v_mfma_f32_16x16x32_bf16 v[44:47], v[172:175], v[216:219], v[44:47]
	v_mfma_f32_16x16x32_bf16 v[40:43], v[182:185], v[216:219], v[40:43]
	v_mfma_f32_16x16x32_bf16 v[36:39], v[172:175], v[224:227], v[36:39]
	v_mfma_f32_16x16x32_bf16 v[32:35], v[182:185], v[224:227], v[32:35]
	v_mfma_f32_16x16x32_bf16 v[60:63], v[176:179], v[194:197], v[60:63]
	v_mfma_f32_16x16x32_bf16 v[56:59], v[186:189], v[194:197], v[56:59]
	v_mfma_f32_16x16x32_bf16 v[52:55], v[176:179], v[212:215], v[52:55]
	v_mfma_f32_16x16x32_bf16 v[48:51], v[186:189], v[212:215], v[48:51]
	v_mfma_f32_16x16x32_bf16 v[44:47], v[176:179], v[220:223], v[44:47]
	v_mfma_f32_16x16x32_bf16 v[40:43], v[186:189], v[220:223], v[40:43]
	v_mfma_f32_16x16x32_bf16 v[36:39], v[176:179], v[228:231], v[36:39]
	v_mfma_f32_16x16x32_bf16 v[32:35], v[186:189], v[228:231], v[32:35]
	s_setprio 0
	s_barrier
; #define PG8_STAGE(bufoff, gbase, voff) do { _Pragma("unroll") for (int _i = 0; _i < 2; ++_i) \
;         __builtin_amdgcn_global_load_lds((const unsigned*)((const char*)(gbase) + (voff)[_i]), (PG8_LAS unsigned*)(lds + (bufoff) + ldsw + _i * 8192), 16, 0, 0); } while (0)
; #define PG8_LDA(dst, b, h) do { _Pragma("unroll") for (int m = 0; m < 4; ++m) _Pragma("unroll") for (int k = 0; k < 2; ++k) dst[m][k] = *(const PG8_LAS bf16x8*)(lds + PG8_SA(b, h) + aoff + m * 2048 + k * 1024); } while (0)
; #define PG8_LDB(dst, b, h) do { _Pragma("unroll") for (int n = 0; n < 2; ++n) _Pragma("unroll") for (int k = 0; k < 2; ++k) dst[n][k] = *(const PG8_LAS bf16x8*)(lds + PG8_SB(b, h) + boff + n * 2048 + k * 1024); } while (0)
; #define PG8_MMA(ai, bj, At, Bt) do { __builtin_amdgcn_s_setprio(1); _Pragma("unroll") for (int m = 0; m < 4; ++m) _Pragma("unroll") for (int n = 0; n < 2; ++n) _Pragma("unroll") for (int k = 0; k < 2; ++k) \
;         acc[ai][bj][m][n] = __builtin_amdgcn_mfma_f32_16x16x32_bf16(Bt[n][k], At[m][k], acc[ai][bj][m][n], 0, 0, 0); __builtin_amdgcn_s_setprio(0); } while (0)
; #define PG8_WAIT_V(n) asm volatile("s_waitcnt vmcnt(" #n ")" ::: "memory")
; #define PG8_WAIT_L(n) asm volatile("s_waitcnt lgkmcnt(" #n ")" ::: "memory")
; #define PG8_BAR __builtin_amdgcn_s_barrier()
; #define PG8_SCHED __builtin_amdgcn_sched_barrier(0)
; template <class Epi, class Sched, bool ALIGN_EPI = false, bool SP2 = false>
; __device__ __forceinline__ void gemm_phase(PG8_LAS unsigned char* lds, const Gemm g, const Sched& S, const Epi& E) {
;     ...
;             const bool last = (t == nt - 2);
;             const char* a1 = cA + (size_t)(t + 1) * kstep;
;             const char* a2 = last ? nA : cA + (size_t)(t + 2) * kstep; const char* b2 = last ? nB : cB + (size_t)(t + 2) * kstep;
;             const char* a3 = a2 + kstep; const char* b3 = b2 + kstep;
;             if (last && has_next) S.a_ready(nxt);
;             if constexpr (SP2) {
;             PG8_LDB(B0, 0, 0); PG8_LDB(B1, 0, 1); PG8_SCHED; PG8_LDA(At, 0, 0); PG8_STAGE(PG8_SA(1, 1), a1 + hstep, voffA);
;     ...
;             PG8_LDA(At, 1, 1); PG8_STAGE(PG8_SB(1, 0), b3, voffB); PG8_STAGE(PG8_SB(1, 1), b3 + hstep, voffB); PG8_STAGE(PG8_SA(1, 0), a3, voffA);
;             PG8_WAIT_V(8); PG8_WAIT_L(0); PG8_BAR; PG8_MMA(1, 0, At, B0); PG8_MMA(1, 1, At, B1); PG8_BAR; PG8_SCHED;
	s_add_i32 s64, s78, s14
	v_lshl_add_u64 v[232:233], v[232:233], 0, s[42:43]
	s_mov_b32 m0, s64
	ds_read_b128 v[190:193], v208 offset:49152
	ds_read_b128 v[194:197], v208 offset:50176
	ds_read_b128 v[198:201], v208 offset:51200
	ds_read_b128 v[212:215], v208 offset:52224
	ds_read_b128 v[216:219], v208 offset:53248
	ds_read_b128 v[220:223], v208 offset:54272
	ds_read_b128 v[224:227], v208 offset:55296
	ds_read_b128 v[228:231], v208 offset:56320
	global_load_lds_dwordx4 v[232:233], off
	s_add_i32 m0, s64, 0x2000
	s_add_u32 s62, s62, 0x40080
	v_lshl_add_u64 v[232:233], v[234:235], 0, s[42:43]
	s_addc_u32 s63, s63, 0
	s_add_i32 s64, s79, s14
	global_load_lds_dwordx4 v[232:233], off
	v_lshl_add_u64 v[232:233], s[62:63], 0, v[134:135]
	s_mov_b32 m0, s64
	s_nop 0
	global_load_lds_dwordx4 v[232:233], off
	v_lshl_add_u64 v[232:233], s[62:63], 0, v[138:139]
	s_add_i32 m0, s64, 0x2000
	s_nop 0
	global_load_lds_dwordx4 v[232:233], off
	s_waitcnt vmcnt(6)
	s_waitcnt lgkmcnt(0)
	s_barrier
	s_setprio 1
	s_waitcnt lgkmcnt(0)
	v_mfma_f32_16x16x32_bf16 v[92:95], v[128:131], v[190:193], v[92:95]
	v_mfma_f32_16x16x32_bf16 v[88:91], v[164:167], v[190:193], v[88:91]
	v_mfma_f32_16x16x32_bf16 v[84:87], v[128:131], v[198:201], v[84:87]
	v_mfma_f32_16x16x32_bf16 v[80:83], v[164:167], v[198:201], v[80:83]
	v_mfma_f32_16x16x32_bf16 v[76:79], v[128:131], v[216:219], v[76:79]
	v_mfma_f32_16x16x32_bf16 v[72:75], v[164:167], v[216:219], v[72:75]
	v_mfma_f32_16x16x32_bf16 v[68:71], v[128:131], v[224:227], v[68:71]
	v_mfma_f32_16x16x32_bf16 v[64:67], v[164:167], v[224:227], v[64:67]
	v_mfma_f32_16x16x32_bf16 v[92:95], v[160:163], v[194:197], v[92:95]
	v_mfma_f32_16x16x32_bf16 v[88:91], v[168:171], v[194:197], v[88:91]
	v_mfma_f32_16x16x32_bf16 v[84:87], v[160:163], v[212:215], v[84:87]
	v_mfma_f32_16x16x32_bf16 v[80:83], v[168:171], v[212:215], v[80:83]
	v_mfma_f32_16x16x32_bf16 v[76:79], v[160:163], v[220:223], v[76:79]
	v_mfma_f32_16x16x32_bf16 v[72:75], v[168:171], v[220:223], v[72:75]
	v_lshl_add_u64 v[232:233], v[236:237], 0, s[42:43]
	s_mov_b32 m0, s67
	s_nop 0
	global_load_lds_dwordx4 v[232:233], off
	v_mfma_f32_16x16x32_bf16 v[68:71], v[160:163], v[228:231], v[68:71]
	v_mfma_f32_16x16x32_bf16 v[64:67], v[168:171], v[228:231], v[64:67]
	s_setprio 0
	s_setprio 1
	v_mfma_f32_16x16x32_bf16 v[28:31], v[172:175], v[190:193], v[28:31]
	v_mfma_f32_16x16x32_bf16 v[24:27], v[182:185], v[190:193], v[24:27]
	v_mfma_f32_16x16x32_bf16 v[20:23], v[172:175], v[198:201], v[20:23]
	v_mfma_f32_16x16x32_bf16 v[16:19], v[182:185], v[198:201], v[16:19]
	v_mfma_f32_16x16x32_bf16 v[12:15], v[172:175], v[216:219], v[12:15]
	v_mfma_f32_16x16x32_bf16 v[8:11], v[182:185], v[216:219], v[8:11]
	v_mfma_f32_16x16x32_bf16 v[4:7], v[172:175], v[224:227], v[4:7]
	v_mfma_f32_16x16x32_bf16 v[0:3], v[182:185], v[224:227], v[0:3]
	v_mfma_f32_16x16x32_bf16 v[28:31], v[176:179], v[194:197], v[28:31]
	v_mfma_f32_16x16x32_bf16 v[24:27], v[186:189], v[194:197], v[24:27]
	v_mfma_f32_16x16x32_bf16 v[20:23], v[176:179], v[212:215], v[20:23]
	v_mfma_f32_16x16x32_bf16 v[16:19], v[186:189], v[212:215], v[16:19]
	v_mfma_f32_16x16x32_bf16 v[12:15], v[176:179], v[220:223], v[12:15]
	v_mfma_f32_16x16x32_bf16 v[8:11], v[186:189], v[220:223], v[8:11]
	v_lshl_add_u64 v[232:233], v[238:239], 0, s[42:43]
	s_mov_b32 m0, s74
	s_nop 0
	global_load_lds_dwordx4 v[232:233], off
	v_mfma_f32_16x16x32_bf16 v[4:7], v[176:179], v[228:231], v[4:7]
	v_mfma_f32_16x16x32_bf16 v[0:3], v[186:189], v[228:231], v[0:3]
	s_setprio 0
	s_barrier
	s_add_i32 s90, s90, 2
	s_add_u32 s58, s58, 0x100
	s_addc_u32 s59, s59, 0
	s_add_u32 s88, s88, 0x100
	s_addc_u32 s89, s89, 0
.LBB0_1287:
	ds_read_b128 v[128:131], v181
	ds_read_b128 v[160:163], v181 offset:1024
	ds_read_b128 v[164:167], v181 offset:2048
	ds_read_b128 v[168:171], v181 offset:3072
	ds_read_b128 v[172:175], v203
	ds_read_b128 v[176:179], v203 offset:1024
	ds_read_b128 v[182:185], v203 offset:2048
	ds_read_b128 v[186:189], v203 offset:3072
	s_add_u32 s62, s58, 0xfffc0080
	s_addc_u32 s63, s59, -1
	s_cmp_eq_u32 s90, 12
	s_cselect_b32 s65, s51, s63
	s_cselect_b32 s64, s61, s62
	s_cselect_b32 s63, s49, s89
	s_cselect_b32 s62, s87, s88
	v_lshl_add_u64 v[232:233], s[58:59], 0, v[152:153]
	s_add_i32 m0, s15, 0xc000
	ds_read_b128 v[190:193], v208
	ds_read_b128 v[194:197], v208 offset:1024
	ds_read_b128 v[198:201], v208 offset:2048
	ds_read_b128 v[212:215], v208 offset:3072
	ds_read_b128 v[216:219], v208 offset:4096
	ds_read_b128 v[220:223], v208 offset:5120
	ds_read_b128 v[224:227], v208 offset:6144
	ds_read_b128 v[228:231], v208 offset:7168
	global_load_lds_dwordx4 v[232:233], off
	v_lshl_add_u64 v[232:233], s[58:59], 0, v[154:155]
	s_add_i32 m0, s15, 0xe000
	s_nop 0
	global_load_lds_dwordx4 v[232:233], off
	s_waitcnt vmcnt(8)
	s_waitcnt lgkmcnt(0)
	s_barrier
; #define PG8_STAGE(bufoff, gbase, voff) do { _Pragma("unroll") for (int _i = 0; _i < 2; ++_i) \
;         __builtin_amdgcn_global_load_lds((const unsigned*)((const char*)(gbase) + (voff)[_i]), (PG8_LAS unsigned*)(lds + (bufoff) + ldsw + _i * 8192), 16, 0, 0); } while (0)
; #define PG8_LDA(dst, b, h) do { _Pragma("unroll") for (int m = 0; m < 4; ++m) _Pragma("unroll") for (int k = 0; k < 2; ++k) dst[m][k] = *(const PG8_LAS bf16x8*)(lds + PG8_SA(b, h) + aoff + m * 2048 + k * 1024); } while (0)
; #define PG8_MMA(ai, bj, At, Bt) do { __builtin_amdgcn_s_setprio(1); _Pragma("unroll") for (int m = 0; m < 4; ++m) _Pragma("unroll") for (int n = 0; n < 2; ++n) _Pragma("unroll") for (int k = 0; k < 2; ++k) \
;         acc[ai][bj][m][n] = __builtin_amdgcn_mfma_f32_16x16x32_bf16(Bt[n][k], At[m][k], acc[ai][bj][m][n], 0, 0, 0); __builtin_amdgcn_s_setprio(0); } while (0)
; #define PG8_WAIT_V(n) asm volatile("s_waitcnt vmcnt(" #n ")" ::: "memory")
; #define PG8_WAIT_L(n) asm volatile("s_waitcnt lgkmcnt(" #n ")" ::: "memory")
; #define PG8_BAR __builtin_amdgcn_s_barrier()
; #define PG8_SCHED __builtin_amdgcn_sched_barrier(0)
; template <class Epi, class Sched, bool ALIGN_EPI = false, bool SP2 = false>
; __device__ __forceinline__ void gemm_phase(PG8_LAS unsigned char* lds, const Gemm g, const Sched& S, const Epi& E) {
;     ...
;             PG8_WAIT_V(8); PG8_WAIT_L(0); PG8_BAR; PG8_MMA(0, 0, At, B0); PG8_MMA(0, 1, At, B1); PG8_BAR; PG8_SCHED;
;             PG8_LDA(At, 0, 1); PG8_STAGE(PG8_SB(0, 0), b2, voffB); PG8_STAGE(PG8_SB(0, 1), b2 + hstep, voffB); PG8_STAGE(PG8_SA(0, 0), a2, voffA);
;             PG8_WAIT_V(8); PG8_WAIT_L(0); PG8_BAR; PG8_MMA(1, 0, At, B0); PG8_MMA(1, 1, At, B1); PG8_BAR; PG8_SCHED;
	s_setprio 1
	s_waitcnt lgkmcnt(0)
	v_mfma_f32_16x16x32_bf16 v[124:127], v[128:131], v[190:193], v[124:127]
	v_mfma_f32_16x16x32_bf16 v[120:123], v[164:167], v[190:193], v[120:123]
	v_mfma_f32_16x16x32_bf16 v[116:119], v[128:131], v[198:201], v[116:119]
	v_mfma_f32_16x16x32_bf16 v[112:115], v[164:167], v[198:201], v[112:115]
	v_mfma_f32_16x16x32_bf16 v[108:111], v[128:131], v[216:219], v[108:111]
	v_mfma_f32_16x16x32_bf16 v[104:107], v[164:167], v[216:219], v[104:107]
	v_mfma_f32_16x16x32_bf16 v[100:103], v[128:131], v[224:227], v[100:103]
	v_mfma_f32_16x16x32_bf16 v[96:99], v[164:167], v[224:227], v[96:99]
	v_mfma_f32_16x16x32_bf16 v[124:127], v[160:163], v[194:197], v[124:127]
	v_mfma_f32_16x16x32_bf16 v[120:123], v[168:171], v[194:197], v[120:123]
	v_mfma_f32_16x16x32_bf16 v[116:119], v[160:163], v[212:215], v[116:119]
	v_mfma_f32_16x16x32_bf16 v[112:115], v[168:171], v[212:215], v[112:115]
	v_mfma_f32_16x16x32_bf16 v[108:111], v[160:163], v[220:223], v[108:111]
	v_mfma_f32_16x16x32_bf16 v[104:107], v[168:171], v[220:223], v[104:107]
	v_mfma_f32_16x16x32_bf16 v[100:103], v[160:163], v[228:231], v[100:103]
	v_mfma_f32_16x16x32_bf16 v[96:99], v[168:171], v[228:231], v[96:99]
	s_setprio 0
	s_setprio 1
	v_mfma_f32_16x16x32_bf16 v[60:63], v[172:175], v[190:193], v[60:63]
	v_mfma_f32_16x16x32_bf16 v[56:59], v[182:185], v[190:193], v[56:59]
	v_mfma_f32_16x16x32_bf16 v[52:55], v[172:175], v[198:201], v[52:55]
	v_mfma_f32_16x16x32_bf16 v[48:51], v[182:185], v[198:201], v[48:51]
	v_mfma_f32_16x16x32_bf16 v[44:47], v[172:175], v[216:219], v[44:47]
	v_mfma_f32_16x16x32_bf16 v[40:43], v[182:185], v[216:219], v[40:43]
	v_mfma_f32_16x16x32_bf16 v[36:39], v[172:175], v[224:227], v[36:39]
	v_mfma_f32_16x16x32_bf16 v[32:35], v[182:185], v[224:227], v[32:35]
	v_mfma_f32_16x16x32_bf16 v[60:63], v[176:179], v[194:197], v[60:63]
	v_mfma_f32_16x16x32_bf16 v[56:59], v[186:189], v[194:197], v[56:59]
	v_mfma_f32_16x16x32_bf16 v[52:55], v[176:179], v[212:215], v[52:55]
	v_mfma_f32_16x16x32_bf16 v[48:51], v[186:189], v[212:215], v[48:51]
	v_mfma_f32_16x16x32_bf16 v[44:47], v[176:179], v[220:223], v[44:47]
	v_mfma_f32_16x16x32_bf16 v[40:43], v[186:189], v[220:223], v[40:43]
	v_mfma_f32_16x16x32_bf16 v[36:39], v[176:179], v[228:231], v[36:39]
	v_mfma_f32_16x16x32_bf16 v[32:35], v[186:189], v[228:231], v[32:35]
	s_setprio 0
	s_barrier
	s_add_i32 s78, s75, s14
	v_lshl_add_u64 v[232:233], s[62:63], 0, v[134:135]
	s_mov_b32 m0, s78
	ds_read_b128 v[190:193], v208 offset:16384
	ds_read_b128 v[194:197], v208 offset:17408
	ds_read_b128 v[198:201], v208 offset:18432
	ds_read_b128 v[212:215], v208 offset:19456
	ds_read_b128 v[216:219], v208 offset:20480
	ds_read_b128 v[220:223], v208 offset:21504
	ds_read_b128 v[224:227], v208 offset:22528
	ds_read_b128 v[228:231], v208 offset:23552
	global_load_lds_dwordx4 v[232:233], off
	s_add_i32 m0, s78, 0x2000
	s_add_u32 s78, s62, 0x40000
	v_lshl_add_u64 v[234:235], s[62:63], 0, v[138:139]
	s_addc_u32 s79, s63, 0
	s_add_i32 s91, s76, s14
	global_load_lds_dwordx4 v[234:235], off
	v_lshl_add_u64 v[236:237], s[78:79], 0, v[134:135]
	s_mov_b32 m0, s91
	global_load_lds_dwordx4 v[236:237], off
	v_lshl_add_u64 v[236:237], s[78:79], 0, v[138:139]
	s_add_i32 m0, s91, 0x2000
	s_nop 0
	global_load_lds_dwordx4 v[236:237], off
	s_waitcnt vmcnt(6)
	s_waitcnt lgkmcnt(0)
	s_barrier
	s_setprio 1
	s_waitcnt lgkmcnt(0)
	v_mfma_f32_16x16x32_bf16 v[92:95], v[128:131], v[190:193], v[92:95]
	v_mfma_f32_16x16x32_bf16 v[88:91], v[164:167], v[190:193], v[88:91]
	v_mfma_f32_16x16x32_bf16 v[84:87], v[128:131], v[198:201], v[84:87]
	v_mfma_f32_16x16x32_bf16 v[80:83], v[164:167], v[198:201], v[80:83]
	v_mfma_f32_16x16x32_bf16 v[76:79], v[128:131], v[216:219], v[76:79]
	v_mfma_f32_16x16x32_bf16 v[72:75], v[164:167], v[216:219], v[72:75]
	v_mfma_f32_16x16x32_bf16 v[68:71], v[128:131], v[224:227], v[68:71]
	v_mfma_f32_16x16x32_bf16 v[64:67], v[164:167], v[224:227], v[64:67]
	v_mfma_f32_16x16x32_bf16 v[92:95], v[160:163], v[194:197], v[92:95]
	v_mfma_f32_16x16x32_bf16 v[88:91], v[168:171], v[194:197], v[88:91]
	v_mfma_f32_16x16x32_bf16 v[84:87], v[160:163], v[212:215], v[84:87]
	v_mfma_f32_16x16x32_bf16 v[80:83], v[168:171], v[212:215], v[80:83]
	v_mfma_f32_16x16x32_bf16 v[76:79], v[160:163], v[220:223], v[76:79]
	v_mfma_f32_16x16x32_bf16 v[72:75], v[168:171], v[220:223], v[72:75]
	v_lshl_add_u64 v[236:237], s[64:65], 0, v[132:133]
	s_mov_b32 m0, s15
	s_nop 0
	global_load_lds_dwordx4 v[236:237], off
	v_mfma_f32_16x16x32_bf16 v[68:71], v[160:163], v[228:231], v[68:71]
	v_mfma_f32_16x16x32_bf16 v[64:67], v[168:171], v[228:231], v[64:67]
	s_setprio 0
	s_setprio 1
	v_mfma_f32_16x16x32_bf16 v[28:31], v[172:175], v[190:193], v[28:31]
	v_mfma_f32_16x16x32_bf16 v[24:27], v[182:185], v[190:193], v[24:27]
	v_mfma_f32_16x16x32_bf16 v[20:23], v[172:175], v[198:201], v[20:23]
	v_mfma_f32_16x16x32_bf16 v[16:19], v[182:185], v[198:201], v[16:19]
	v_mfma_f32_16x16x32_bf16 v[12:15], v[172:175], v[216:219], v[12:15]
	v_mfma_f32_16x16x32_bf16 v[8:11], v[182:185], v[216:219], v[8:11]
	v_mfma_f32_16x16x32_bf16 v[4:7], v[172:175], v[224:227], v[4:7]
	v_mfma_f32_16x16x32_bf16 v[0:3], v[182:185], v[224:227], v[0:3]
	v_mfma_f32_16x16x32_bf16 v[28:31], v[176:179], v[194:197], v[28:31]
	v_mfma_f32_16x16x32_bf16 v[24:27], v[186:189], v[194:197], v[24:27]
	v_mfma_f32_16x16x32_bf16 v[20:23], v[176:179], v[212:215], v[20:23]
	v_mfma_f32_16x16x32_bf16 v[16:19], v[186:189], v[212:215], v[16:19]
	v_mfma_f32_16x16x32_bf16 v[12:15], v[176:179], v[220:223], v[12:15]
	v_mfma_f32_16x16x32_bf16 v[8:11], v[186:189], v[220:223], v[8:11]
	v_lshl_add_u64 v[238:239], s[64:65], 0, v[136:137]
	s_mov_b32 m0, s33
	s_nop 0
	global_load_lds_dwordx4 v[238:239], off
	v_mfma_f32_16x16x32_bf16 v[4:7], v[176:179], v[228:231], v[4:7]
	v_mfma_f32_16x16x32_bf16 v[0:3], v[186:189], v[228:231], v[0:3]
	s_setprio 0
	s_barrier
; #define PG8_STAGE(bufoff, gbase, voff) do { _Pragma("unroll") for (int _i = 0; _i < 2; ++_i) \
;         __builtin_amdgcn_global_load_lds((const unsigned*)((const char*)(gbase) + (voff)[_i]), (PG8_LAS unsigned*)(lds + (bufoff) + ldsw + _i * 8192), 16, 0, 0); } while (0)
; #define PG8_LDA(dst, b, h) do { _Pragma("unroll") for (int m = 0; m < 4; ++m) _Pragma("unroll") for (int k = 0; k < 2; ++k) dst[m][k] = *(const PG8_LAS bf16x8*)(lds + PG8_SA(b, h) + aoff + m * 2048 + k * 1024); } while (0)
; #define PG8_LDB(dst, b, h) do { _Pragma("unroll") for (int n = 0; n < 2; ++n) _Pragma("unroll") for (int k = 0; k < 2; ++k) dst[n][k] = *(const PG8_LAS bf16x8*)(lds + PG8_SB(b, h) + boff + n * 2048 + k * 1024); } while (0)
; #define PG8_MMA(ai, bj, At, Bt) do { __builtin_amdgcn_s_setprio(1); _Pragma("unroll") for (int m = 0; m < 4; ++m) _Pragma("unroll") for (int n = 0; n < 2; ++n) _Pragma("unroll") for (int k = 0; k < 2; ++k) \
;         acc[ai][bj][m][n] = __builtin_amdgcn_mfma_f32_16x16x32_bf16(Bt[n][k], At[m][k], acc[ai][bj][m][n], 0, 0, 0); __builtin_amdgcn_s_setprio(0); } while (0)
; #define PG8_WAIT_V(n) asm volatile("s_waitcnt vmcnt(" #n ")" ::: "memory")
; #define PG8_WAIT_L(n) asm volatile("s_waitcnt lgkmcnt(" #n ")" ::: "memory")
; #define PG8_BAR __builtin_amdgcn_s_barrier()
; #define PG8_SCHED __builtin_amdgcn_sched_barrier(0)
; template <class Epi, class Sched, bool ALIGN_EPI = false, bool SP2 = false>
; __device__ __forceinline__ void gemm_phase(PG8_LAS unsigned char* lds, const Gemm g, const Sched& S, const Epi& E) {
;     ...
;             PG8_LDB(B0, 1, 0); PG8_LDB(B1, 1, 1); PG8_SCHED; PG8_LDA(At, 1, 0); PG8_STAGE(PG8_SA(0, 1), a2 + hstep, voffA);
;             PG8_WAIT_V(8); PG8_WAIT_L(0); PG8_BAR; PG8_MMA(0, 0, At, B0); PG8_MMA(0, 1, At, B1); PG8_BAR; PG8_SCHED;
	s_add_i32 s78, 0, 0x18000
	v_add_u32_e32 v140, s78, v147
	s_add_i32 s79, 0, 0x1c000
	ds_read_b128 v[128:131], v140
	ds_read_b128 v[160:163], v140 offset:1024
	ds_read_b128 v[164:167], v140 offset:2048
	ds_read_b128 v[168:171], v140 offset:3072
	v_add_u32_e32 v140, s79, v147
	ds_read_b128 v[172:175], v140
	ds_read_b128 v[176:179], v140 offset:1024
	ds_read_b128 v[182:185], v140 offset:2048
	ds_read_b128 v[186:189], v140 offset:3072
	s_add_u32 s64, s64, 0x40000
	s_addc_u32 s65, s65, 0
	s_mov_b32 m0, s34
	v_lshl_add_u64 v[240:241], s[64:65], 0, v[132:133]
	ds_read_b128 v[190:193], v208 offset:32768
	ds_read_b128 v[194:197], v208 offset:33792
	ds_read_b128 v[198:201], v208 offset:34816
	ds_read_b128 v[212:215], v208 offset:35840
	ds_read_b128 v[216:219], v208 offset:36864
	ds_read_b128 v[220:223], v208 offset:37888
	ds_read_b128 v[224:227], v208 offset:38912
	ds_read_b128 v[228:231], v208 offset:39936
	global_load_lds_dwordx4 v[240:241], off
	v_lshl_add_u64 v[240:241], s[64:65], 0, v[136:137]
	s_mov_b32 m0, s57
	s_nop 0
	global_load_lds_dwordx4 v[240:241], off
	s_waitcnt vmcnt(8)
	s_waitcnt lgkmcnt(0)
	s_barrier
	s_setprio 1
	s_waitcnt lgkmcnt(0)
	v_mfma_f32_16x16x32_bf16 v[124:127], v[128:131], v[190:193], v[124:127]
	v_mfma_f32_16x16x32_bf16 v[120:123], v[164:167], v[190:193], v[120:123]
	v_mfma_f32_16x16x32_bf16 v[116:119], v[128:131], v[198:201], v[116:119]
	v_mfma_f32_16x16x32_bf16 v[112:115], v[164:167], v[198:201], v[112:115]
	v_mfma_f32_16x16x32_bf16 v[108:111], v[128:131], v[216:219], v[108:111]
	v_mfma_f32_16x16x32_bf16 v[104:107], v[164:167], v[216:219], v[104:107]
	v_mfma_f32_16x16x32_bf16 v[100:103], v[128:131], v[224:227], v[100:103]
	v_mfma_f32_16x16x32_bf16 v[96:99], v[164:167], v[224:227], v[96:99]
	v_mfma_f32_16x16x32_bf16 v[124:127], v[160:163], v[194:197], v[124:127]
	v_mfma_f32_16x16x32_bf16 v[120:123], v[168:171], v[194:197], v[120:123]
	v_mfma_f32_16x16x32_bf16 v[116:119], v[160:163], v[212:215], v[116:119]
	v_mfma_f32_16x16x32_bf16 v[112:115], v[168:171], v[212:215], v[112:115]
	v_mfma_f32_16x16x32_bf16 v[108:111], v[160:163], v[220:223], v[108:111]
	v_mfma_f32_16x16x32_bf16 v[104:107], v[168:171], v[220:223], v[104:107]
	v_mfma_f32_16x16x32_bf16 v[100:103], v[160:163], v[228:231], v[100:103]
	v_mfma_f32_16x16x32_bf16 v[96:99], v[168:171], v[228:231], v[96:99]
	s_setprio 0
	s_setprio 1
	v_mfma_f32_16x16x32_bf16 v[60:63], v[172:175], v[190:193], v[60:63]
	v_mfma_f32_16x16x32_bf16 v[56:59], v[182:185], v[190:193], v[56:59]
	v_mfma_f32_16x16x32_bf16 v[52:55], v[172:175], v[198:201], v[52:55]
	v_mfma_f32_16x16x32_bf16 v[48:51], v[182:185], v[198:201], v[48:51]
	v_mfma_f32_16x16x32_bf16 v[44:47], v[172:175], v[216:219], v[44:47]
	v_mfma_f32_16x16x32_bf16 v[40:43], v[182:185], v[216:219], v[40:43]
	v_mfma_f32_16x16x32_bf16 v[36:39], v[172:175], v[224:227], v[36:39]
	v_mfma_f32_16x16x32_bf16 v[32:35], v[182:185], v[224:227], v[32:35]
	v_mfma_f32_16x16x32_bf16 v[60:63], v[176:179], v[194:197], v[60:63]
	v_mfma_f32_16x16x32_bf16 v[56:59], v[186:189], v[194:197], v[56:59]
	v_mfma_f32_16x16x32_bf16 v[52:55], v[176:179], v[212:215], v[52:55]
	v_mfma_f32_16x16x32_bf16 v[48:51], v[186:189], v[212:215], v[48:51]
	v_mfma_f32_16x16x32_bf16 v[44:47], v[176:179], v[220:223], v[44:47]
	v_mfma_f32_16x16x32_bf16 v[40:43], v[186:189], v[220:223], v[40:43]
	v_mfma_f32_16x16x32_bf16 v[36:39], v[176:179], v[228:231], v[36:39]
	v_mfma_f32_16x16x32_bf16 v[32:35], v[186:189], v[228:231], v[32:35]
	s_setprio 0
	s_barrier
; #define PG8_STAGE(bufoff, gbase, voff) do { _Pragma("unroll") for (int _i = 0; _i < 2; ++_i) \
;         __builtin_amdgcn_global_load_lds((const unsigned*)((const char*)(gbase) + (voff)[_i]), (PG8_LAS unsigned*)(lds + (bufoff) + ldsw + _i * 8192), 16, 0, 0); } while (0)
; #define PG8_LDA(dst, b, h) do { _Pragma("unroll") for (int m = 0; m < 4; ++m) _Pragma("unroll") for (int k = 0; k < 2; ++k) dst[m][k] = *(const PG8_LAS bf16x8*)(lds + PG8_SA(b, h) + aoff + m * 2048 + k * 1024); } while (0)
; #define PG8_MMA(ai, bj, At, Bt) do { __builtin_amdgcn_s_setprio(1); _Pragma("unroll") for (int m = 0; m < 4; ++m) _Pragma("unroll") for (int n = 0; n < 2; ++n) _Pragma("unroll") for (int k = 0; k < 2; ++k) \
;         acc[ai][bj][m][n] = __builtin_amdgcn_mfma_f32_16x16x32_bf16(Bt[n][k], At[m][k], acc[ai][bj][m][n], 0, 0, 0); __builtin_amdgcn_s_setprio(0); } while (0)
; #define PG8_WAIT_V(n) asm volatile("s_waitcnt vmcnt(" #n ")" ::: "memory")
; #define PG8_WAIT_L(n) asm volatile("s_waitcnt lgkmcnt(" #n ")" ::: "memory")
; #define PG8_BAR __builtin_amdgcn_s_barrier()
; #define PG8_SCHED __builtin_amdgcn_sched_barrier(0)
; template <class Epi, class Sched, bool ALIGN_EPI = false, bool SP2 = false>
; __device__ __forceinline__ void gemm_phase(PG8_LAS unsigned char* lds, const Gemm g, const Sched& S, const Epi& E) {
;     ...
;             PG8_LDA(At, 1, 1); PG8_STAGE(PG8_SB(1, 0), b3, voffB); PG8_STAGE(PG8_SB(1, 1), b3 + hstep, voffB); PG8_STAGE(PG8_SA(1, 0), a3, voffA);
;             PG8_WAIT_V(8); PG8_WAIT_L(0); PG8_BAR; PG8_MMA(1, 0, At, B0); PG8_MMA(1, 1, At, B1); PG8_BAR; PG8_SCHED;
;     ...
;         if constexpr (ALIGN_EPI) { if (wr == 0) PG8_BAR; }
	s_add_i32 s64, s78, s14
	v_lshl_add_u64 v[232:233], v[232:233], 0, s[42:43]
	s_mov_b32 m0, s64
	ds_read_b128 v[190:193], v208 offset:49152
	ds_read_b128 v[194:197], v208 offset:50176
	ds_read_b128 v[198:201], v208 offset:51200
	ds_read_b128 v[212:215], v208 offset:52224
	ds_read_b128 v[216:219], v208 offset:53248
	ds_read_b128 v[220:223], v208 offset:54272
	ds_read_b128 v[224:227], v208 offset:55296
	ds_read_b128 v[228:231], v208 offset:56320
	global_load_lds_dwordx4 v[232:233], off
	s_add_i32 m0, s64, 0x2000
	s_add_u32 s62, s62, 0x40080
	v_lshl_add_u64 v[232:233], v[234:235], 0, s[42:43]
	s_addc_u32 s63, s63, 0
	s_add_i32 s64, s79, s14
	global_load_lds_dwordx4 v[232:233], off
	v_lshl_add_u64 v[232:233], s[62:63], 0, v[134:135]
	s_mov_b32 m0, s64
	s_nop 0
	global_load_lds_dwordx4 v[232:233], off
	v_lshl_add_u64 v[232:233], s[62:63], 0, v[138:139]
	s_add_i32 m0, s64, 0x2000
	s_nop 0
	global_load_lds_dwordx4 v[232:233], off
	s_waitcnt vmcnt(6)
	s_waitcnt lgkmcnt(0)
	s_barrier
	s_setprio 1
	s_waitcnt lgkmcnt(0)
	v_mfma_f32_16x16x32_bf16 v[92:95], v[128:131], v[190:193], v[92:95]
	v_mfma_f32_16x16x32_bf16 v[88:91], v[164:167], v[190:193], v[88:91]
	v_mfma_f32_16x16x32_bf16 v[84:87], v[128:131], v[198:201], v[84:87]
	v_mfma_f32_16x16x32_bf16 v[80:83], v[164:167], v[198:201], v[80:83]
	v_mfma_f32_16x16x32_bf16 v[76:79], v[128:131], v[216:219], v[76:79]
	v_mfma_f32_16x16x32_bf16 v[72:75], v[164:167], v[216:219], v[72:75]
	v_mfma_f32_16x16x32_bf16 v[68:71], v[128:131], v[224:227], v[68:71]
	v_mfma_f32_16x16x32_bf16 v[64:67], v[164:167], v[224:227], v[64:67]
	v_mfma_f32_16x16x32_bf16 v[92:95], v[160:163], v[194:197], v[92:95]
	v_mfma_f32_16x16x32_bf16 v[88:91], v[168:171], v[194:197], v[88:91]
	v_mfma_f32_16x16x32_bf16 v[84:87], v[160:163], v[212:215], v[84:87]
	v_mfma_f32_16x16x32_bf16 v[80:83], v[168:171], v[212:215], v[80:83]
	v_mfma_f32_16x16x32_bf16 v[76:79], v[160:163], v[220:223], v[76:79]
	v_mfma_f32_16x16x32_bf16 v[72:75], v[168:171], v[220:223], v[72:75]
	v_lshl_add_u64 v[232:233], v[236:237], 0, s[42:43]
	s_mov_b32 m0, s67
	s_nop 0
	global_load_lds_dwordx4 v[232:233], off
	v_mfma_f32_16x16x32_bf16 v[68:71], v[160:163], v[228:231], v[68:71]
	v_mfma_f32_16x16x32_bf16 v[64:67], v[168:171], v[228:231], v[64:67]
	s_setprio 0
	s_setprio 1
	v_mfma_f32_16x16x32_bf16 v[28:31], v[172:175], v[190:193], v[28:31]
	v_mfma_f32_16x16x32_bf16 v[24:27], v[182:185], v[190:193], v[24:27]
	v_mfma_f32_16x16x32_bf16 v[20:23], v[172:175], v[198:201], v[20:23]
	v_mfma_f32_16x16x32_bf16 v[16:19], v[182:185], v[198:201], v[16:19]
	v_mfma_f32_16x16x32_bf16 v[12:15], v[172:175], v[216:219], v[12:15]
	v_mfma_f32_16x16x32_bf16 v[8:11], v[182:185], v[216:219], v[8:11]
	v_mfma_f32_16x16x32_bf16 v[4:7], v[172:175], v[224:227], v[4:7]
	v_mfma_f32_16x16x32_bf16 v[0:3], v[182:185], v[224:227], v[0:3]
	v_mfma_f32_16x16x32_bf16 v[28:31], v[176:179], v[194:197], v[28:31]
	v_mfma_f32_16x16x32_bf16 v[24:27], v[186:189], v[194:197], v[24:27]
	v_mfma_f32_16x16x32_bf16 v[20:23], v[176:179], v[212:215], v[20:23]
	v_mfma_f32_16x16x32_bf16 v[16:19], v[186:189], v[212:215], v[16:19]
	v_mfma_f32_16x16x32_bf16 v[12:15], v[176:179], v[220:223], v[12:15]
	v_mfma_f32_16x16x32_bf16 v[8:11], v[186:189], v[220:223], v[8:11]
	v_lshl_add_u64 v[232:233], v[238:239], 0, s[42:43]
	s_mov_b32 m0, s74
	s_nop 0
	global_load_lds_dwordx4 v[232:233], off
	v_mfma_f32_16x16x32_bf16 v[4:7], v[176:179], v[228:231], v[4:7]
	v_mfma_f32_16x16x32_bf16 v[0:3], v[186:189], v[228:231], v[0:3]
	s_setprio 0
	s_barrier
	s_add_i32 s90, s90, 2
	s_add_u32 s58, s58, 0x100
	s_addc_u32 s59, s59, 0
	s_add_u32 s88, s88, 0x100
	s_addc_u32 s89, s89, 0
	s_cmp_gt_u32 s90, 13
	s_cbranch_scc0 .LBB0_1287
	s_and_b64 vcc, exec, s[44:45]
	s_cbranch_vccz .LBB0_1290
	s_barrier

; #define PG8_STAGE(bufoff, gbase, voff) do { _Pragma("unroll") for (int _i = 0; _i < 2; ++_i) \
;         __builtin_amdgcn_global_load_lds((const unsigned*)((const char*)(gbase) + (voff)[_i]), (PG8_LAS unsigned*)(lds + (bufoff) + ldsw + _i * 8192), 16, 0, 0); } while (0)
; #define PG8_LDA(dst, b, h) do { _Pragma("unroll") for (int m = 0; m < 4; ++m) _Pragma("unroll") for (int k = 0; k < 2; ++k) dst[m][k] = *(const PG8_LAS bf16x8*)(lds + PG8_SA(b, h) + aoff + m * 2048 + k * 1024); } while (0)
; #define PG8_LDB(dst, b, h) do { _Pragma("unroll") for (int n = 0; n < 2; ++n) _Pragma("unroll") for (int k = 0; k < 2; ++k) dst[n][k] = *(const PG8_LAS bf16x8*)(lds + PG8_SB(b, h) + boff + n * 2048 + k * 1024); } while (0)
; #define PG8_MMA(ai, bj, At, Bt) do { __builtin_amdgcn_s_setprio(1); _Pragma("unroll") for (int m = 0; m < 4; ++m) _Pragma("unroll") for (int n = 0; n < 2; ++n) _Pragma("unroll") for (int k = 0; k < 2; ++k) \
;         acc[ai][bj][m][n] = __builtin_amdgcn_mfma_f32_16x16x32_bf16(Bt[n][k], At[m][k], acc[ai][bj][m][n], 0, 0, 0); __builtin_amdgcn_s_setprio(0); } while (0)
; #define PG8_WAIT_V(n) asm volatile("s_waitcnt vmcnt(" #n ")" ::: "memory")
; #define PG8_BAR __builtin_amdgcn_s_barrier()
; template <class Epi, class Sched, bool ALIGN_EPI = false, bool SP2 = false>
; __device__ __forceinline__ void gemm_phase(PG8_LAS unsigned char* lds, const Gemm g, const Sched& S, const Epi& E) {
;     ...
;         for (int t = 0; t < nt; t += 2) {
;             const bool last = (t == nt - 2);
;             const char* a1 = cA + (size_t)(t + 1) * kstep;
;             const char* a2 = last ? nA : cA + (size_t)(t + 2) * kstep; const char* b2 = last ? nB : cB + (size_t)(t + 2) * kstep;
;             const char* a3 = a2 + kstep; const char* b3 = b2 + kstep;
;             if (last && has_next) S.a_ready(nxt);
;             if constexpr (SP2) {
;             PG8_LDB(B0, 0, 0); PG8_LDB(B1, 0, 1); PG8_SCHED; PG8_LDA(At, 0, 0); PG8_STAGE(PG8_SA(1, 1), a1 + hstep, voffA);
;             PG8_WAIT_V(8); PG8_WAIT_L(0); PG8_BAR; PG8_MMA(0, 0, At, B0); PG8_MMA(0, 1, At, B1); PG8_BAR; PG8_SCHED;
;             PG8_LDA(At, 0, 1); PG8_STAGE(PG8_SB(0, 0), b2, voffB); PG8_STAGE(PG8_SB(0, 1), b2 + hstep, voffB); PG8_STAGE(PG8_SA(0, 0), a2, voffA);
;             PG8_WAIT_V(8); PG8_WAIT_L(0); PG8_BAR; PG8_MMA(1, 0, At, B0); PG8_MMA(1, 1, At, B1); PG8_BAR; PG8_SCHED;
.LBB0_1592:
	s_ashr_i32 s39, s38, 31
	s_lshl_b64 s[42:43], s[38:39], 19
	s_add_u32 s42, s40, s42
	s_addc_u32 s43, s41, s43
	s_and_b64 s[44:45], s[10:11], exec
	s_cselect_b32 s39, s43, s51
	s_cselect_b32 s47, s42, s50
	s_ashr_i32 s37, s36, 31
	s_lshl_b64 s[44:45], s[36:37], 19
	v_readlane_b32 s54, v250, 11
	v_readlane_b32 s55, v250, 12
	s_add_u32 s44, s54, s44
	s_addc_u32 s45, s55, s45
	s_and_b64 s[54:55], s[10:11], exec
	s_cselect_b32 s37, s45, s53
	s_cselect_b32 s64, s44, s52
	s_add_u32 s50, s50, 0x40080
	s_addc_u32 s51, s51, 0
	s_add_u32 s65, s52, 0x100
	s_addc_u32 s66, s53, 0
	s_mov_b32 s67, -2
	s_waitcnt lgkmcnt(0)
	ds_read_b128 v[146:149], v152
	ds_read_b128 v[156:159], v152 offset:1024
	ds_read_b128 v[160:163], v152 offset:2048
	ds_read_b128 v[164:167], v152 offset:3072
	ds_read_b128 v[168:171], v153
	ds_read_b128 v[172:175], v153 offset:1024
	ds_read_b128 v[180:183], v153 offset:2048
	ds_read_b128 v[184:187], v153 offset:3072
	s_add_u32 s52, s50, 0xfffc0080
	s_addc_u32 s53, s51, -1
	s_cmp_eq_u32 s67, 12
	s_cselect_b32 s55, s39, s53
	s_cselect_b32 s54, s47, s52
	s_cselect_b32 s53, s37, s66
	s_cselect_b32 s52, s64, s65
	v_lshl_add_u64 v[200:201], s[50:51], 0, v[136:137]
	s_add_i32 m0, s33, 0xc000
	ds_read_b128 v[188:191], v154
	ds_read_b128 v[192:195], v154 offset:1024
	ds_read_b128 v[196:199], v154 offset:2048
	ds_read_b128 v[206:209], v154 offset:3072
	ds_read_b128 v[210:213], v154 offset:4096
	ds_read_b128 v[214:217], v154 offset:5120
	ds_read_b128 v[218:221], v154 offset:6144
	ds_read_b128 v[222:225], v154 offset:7168
	global_load_lds_dwordx4 v[200:201], off
	v_lshl_add_u64 v[200:201], s[50:51], 0, v[138:139]
	s_add_i32 m0, s33, 0xe000
	s_nop 0
	global_load_lds_dwordx4 v[200:201], off
	s_waitcnt vmcnt(8)
	s_waitcnt lgkmcnt(0)
	s_barrier
	s_setprio 1
	s_waitcnt lgkmcnt(0)
	v_mfma_f32_16x16x32_bf16 v[124:127], v[146:149], v[188:191], 0
	v_mfma_f32_16x16x32_bf16 v[120:123], v[160:163], v[188:191], 0
	v_mfma_f32_16x16x32_bf16 v[108:111], v[146:149], v[196:199], 0
	v_mfma_f32_16x16x32_bf16 v[104:107], v[160:163], v[196:199], 0
	v_mfma_f32_16x16x32_bf16 v[92:95], v[146:149], v[210:213], 0
	v_mfma_f32_16x16x32_bf16 v[88:91], v[160:163], v[210:213], 0
	v_mfma_f32_16x16x32_bf16 v[76:79], v[146:149], v[218:221], 0
	v_mfma_f32_16x16x32_bf16 v[72:75], v[160:163], v[218:221], 0
	v_mfma_f32_16x16x32_bf16 v[124:127], v[156:159], v[192:195], v[124:127]
	v_mfma_f32_16x16x32_bf16 v[120:123], v[164:167], v[192:195], v[120:123]
	v_mfma_f32_16x16x32_bf16 v[108:111], v[156:159], v[206:209], v[108:111]
	v_mfma_f32_16x16x32_bf16 v[104:107], v[164:167], v[206:209], v[104:107]
	v_mfma_f32_16x16x32_bf16 v[92:95], v[156:159], v[214:217], v[92:95]
	v_mfma_f32_16x16x32_bf16 v[88:91], v[164:167], v[214:217], v[88:91]
	v_mfma_f32_16x16x32_bf16 v[76:79], v[156:159], v[222:225], v[76:79]
	v_mfma_f32_16x16x32_bf16 v[72:75], v[164:167], v[222:225], v[72:75]
	s_setprio 0
	s_setprio 1
	v_mfma_f32_16x16x32_bf16 v[116:119], v[168:171], v[188:191], 0
	v_mfma_f32_16x16x32_bf16 v[112:115], v[180:183], v[188:191], 0
	v_mfma_f32_16x16x32_bf16 v[100:103], v[168:171], v[196:199], 0
	v_mfma_f32_16x16x32_bf16 v[96:99], v[180:183], v[196:199], 0
	v_mfma_f32_16x16x32_bf16 v[84:87], v[168:171], v[210:213], 0
	v_mfma_f32_16x16x32_bf16 v[80:83], v[180:183], v[210:213], 0
	v_mfma_f32_16x16x32_bf16 v[68:71], v[168:171], v[218:221], 0
	v_mfma_f32_16x16x32_bf16 v[64:67], v[180:183], v[218:221], 0
	v_mfma_f32_16x16x32_bf16 v[116:119], v[172:175], v[192:195], v[116:119]
	v_mfma_f32_16x16x32_bf16 v[112:115], v[184:187], v[192:195], v[112:115]
	v_mfma_f32_16x16x32_bf16 v[100:103], v[172:175], v[206:209], v[100:103]
	v_mfma_f32_16x16x32_bf16 v[96:99], v[184:187], v[206:209], v[96:99]
	v_mfma_f32_16x16x32_bf16 v[84:87], v[172:175], v[214:217], v[84:87]
	v_mfma_f32_16x16x32_bf16 v[80:83], v[184:187], v[214:217], v[80:83]
	v_mfma_f32_16x16x32_bf16 v[68:71], v[172:175], v[222:225], v[68:71]
	v_mfma_f32_16x16x32_bf16 v[64:67], v[184:187], v[222:225], v[64:67]
	s_setprio 0
	s_barrier
	s_add_i32 s74, s60, s15
	v_lshl_add_u64 v[200:201], s[52:53], 0, v[130:131]
	s_mov_b32 m0, s74
	ds_read_b128 v[188:191], v154 offset:16384
	ds_read_b128 v[192:195], v154 offset:17408
	ds_read_b128 v[196:199], v154 offset:18432
	ds_read_b128 v[206:209], v154 offset:19456
	ds_read_b128 v[210:213], v154 offset:20480
	ds_read_b128 v[214:217], v154 offset:21504
	ds_read_b128 v[218:221], v154 offset:22528
	ds_read_b128 v[222:225], v154 offset:23552
	global_load_lds_dwordx4 v[200:201], off
	s_add_i32 m0, s74, 0x2000
	s_add_u32 s74, s52, 0x40000
	v_lshl_add_u64 v[226:227], s[52:53], 0, v[134:135]
	s_addc_u32 s75, s53, 0
	s_add_i32 s76, s61, s15
	global_load_lds_dwordx4 v[226:227], off
	v_lshl_add_u64 v[228:229], s[74:75], 0, v[130:131]
	s_mov_b32 m0, s76
	global_load_lds_dwordx4 v[228:229], off
	v_lshl_add_u64 v[228:229], s[74:75], 0, v[134:135]
	s_add_i32 m0, s76, 0x2000
	s_nop 0
	global_load_lds_dwordx4 v[228:229], off
	s_waitcnt vmcnt(6)
	s_waitcnt lgkmcnt(0)
	s_barrier
; #define PG8_STAGE(bufoff, gbase, voff) do { _Pragma("unroll") for (int _i = 0; _i < 2; ++_i) \
;         __builtin_amdgcn_global_load_lds((const unsigned*)((const char*)(gbase) + (voff)[_i]), (PG8_LAS unsigned*)(lds + (bufoff) + ldsw + _i * 8192), 16, 0, 0); } while (0)
; #define PG8_LDA(dst, b, h) do { _Pragma("unroll") for (int m = 0; m < 4; ++m) _Pragma("unroll") for (int k = 0; k < 2; ++k) dst[m][k] = *(const PG8_LAS bf16x8*)(lds + PG8_SA(b, h) + aoff + m * 2048 + k * 1024); } while (0)
; #define PG8_LDB(dst, b, h) do { _Pragma("unroll") for (int n = 0; n < 2; ++n) _Pragma("unroll") for (int k = 0; k < 2; ++k) dst[n][k] = *(const PG8_LAS bf16x8*)(lds + PG8_SB(b, h) + boff + n * 2048 + k * 1024); } while (0)
; #define PG8_MMA(ai, bj, At, Bt) do { __builtin_amdgcn_s_setprio(1); _Pragma("unroll") for (int m = 0; m < 4; ++m) _Pragma("unroll") for (int n = 0; n < 2; ++n) _Pragma("unroll") for (int k = 0; k < 2; ++k) \
;         acc[ai][bj][m][n] = __builtin_amdgcn_mfma_f32_16x16x32_bf16(Bt[n][k], At[m][k], acc[ai][bj][m][n], 0, 0, 0); __builtin_amdgcn_s_setprio(0); } while (0)
; #define PG8_WAIT_V(n) asm volatile("s_waitcnt vmcnt(" #n ")" ::: "memory")
; #define PG8_WAIT_L(n) asm volatile("s_waitcnt lgkmcnt(" #n ")" ::: "memory")
; #define PG8_BAR __builtin_amdgcn_s_barrier()
; #define PG8_SCHED __builtin_amdgcn_sched_barrier(0)
; template <class Epi, class Sched, bool ALIGN_EPI = false, bool SP2 = false>
; __device__ __forceinline__ void gemm_phase(PG8_LAS unsigned char* lds, const Gemm g, const Sched& S, const Epi& E) {
;     ...
;             PG8_WAIT_V(8); PG8_WAIT_L(0); PG8_BAR; PG8_MMA(1, 0, At, B0); PG8_MMA(1, 1, At, B1); PG8_BAR; PG8_SCHED;
;             PG8_LDB(B0, 1, 0); PG8_LDB(B1, 1, 1); PG8_SCHED; PG8_LDA(At, 1, 0); PG8_STAGE(PG8_SA(0, 1), a2 + hstep, voffA);
;             PG8_WAIT_V(8); PG8_WAIT_L(0); PG8_BAR; PG8_MMA(0, 0, At, B0); PG8_MMA(0, 1, At, B1); PG8_BAR; PG8_SCHED;
	s_setprio 1
	s_waitcnt lgkmcnt(0)
	v_mfma_f32_16x16x32_bf16 v[60:63], v[146:149], v[188:191], 0
	v_mfma_f32_16x16x32_bf16 v[56:59], v[160:163], v[188:191], 0
	v_mfma_f32_16x16x32_bf16 v[44:47], v[146:149], v[196:199], 0
	v_mfma_f32_16x16x32_bf16 v[40:43], v[160:163], v[196:199], 0
	v_mfma_f32_16x16x32_bf16 v[28:31], v[146:149], v[210:213], 0
	v_mfma_f32_16x16x32_bf16 v[24:27], v[160:163], v[210:213], 0
	v_mfma_f32_16x16x32_bf16 v[12:15], v[146:149], v[218:221], 0
	v_mfma_f32_16x16x32_bf16 v[8:11], v[160:163], v[218:221], 0
	v_mfma_f32_16x16x32_bf16 v[60:63], v[156:159], v[192:195], v[60:63]
	v_mfma_f32_16x16x32_bf16 v[56:59], v[164:167], v[192:195], v[56:59]
	v_mfma_f32_16x16x32_bf16 v[44:47], v[156:159], v[206:209], v[44:47]
	v_mfma_f32_16x16x32_bf16 v[40:43], v[164:167], v[206:209], v[40:43]
	v_mfma_f32_16x16x32_bf16 v[28:31], v[156:159], v[214:217], v[28:31]
	v_mfma_f32_16x16x32_bf16 v[24:27], v[164:167], v[214:217], v[24:27]
	v_lshl_add_u64 v[228:229], s[54:55], 0, v[128:129]
	s_mov_b32 m0, s33
	s_nop 0
	global_load_lds_dwordx4 v[228:229], off
	v_mfma_f32_16x16x32_bf16 v[12:15], v[156:159], v[222:225], v[12:15]
	v_mfma_f32_16x16x32_bf16 v[8:11], v[164:167], v[222:225], v[8:11]
	s_setprio 0
	s_setprio 1
	v_mfma_f32_16x16x32_bf16 v[52:55], v[168:171], v[188:191], 0
	v_mfma_f32_16x16x32_bf16 v[48:51], v[180:183], v[188:191], 0
	v_mfma_f32_16x16x32_bf16 v[36:39], v[168:171], v[196:199], 0
	v_mfma_f32_16x16x32_bf16 v[32:35], v[180:183], v[196:199], 0
	v_mfma_f32_16x16x32_bf16 v[20:23], v[168:171], v[210:213], 0
	v_mfma_f32_16x16x32_bf16 v[16:19], v[180:183], v[210:213], 0
	v_mfma_f32_16x16x32_bf16 v[4:7], v[168:171], v[218:221], 0
	v_mfma_f32_16x16x32_bf16 v[0:3], v[180:183], v[218:221], 0
	v_mfma_f32_16x16x32_bf16 v[52:55], v[172:175], v[192:195], v[52:55]
	v_mfma_f32_16x16x32_bf16 v[48:51], v[184:187], v[192:195], v[48:51]
	v_mfma_f32_16x16x32_bf16 v[36:39], v[172:175], v[206:209], v[36:39]
	v_mfma_f32_16x16x32_bf16 v[32:35], v[184:187], v[206:209], v[32:35]
	v_mfma_f32_16x16x32_bf16 v[20:23], v[172:175], v[214:217], v[20:23]
	v_mfma_f32_16x16x32_bf16 v[16:19], v[184:187], v[214:217], v[16:19]
	v_lshl_add_u64 v[230:231], s[54:55], 0, v[132:133]
	s_mov_b32 m0, s34
	s_nop 0
	global_load_lds_dwordx4 v[230:231], off
	v_mfma_f32_16x16x32_bf16 v[4:7], v[172:175], v[222:225], v[4:7]
	v_mfma_f32_16x16x32_bf16 v[0:3], v[184:187], v[222:225], v[0:3]
	s_setprio 0
	s_barrier
	s_add_i32 s74, 0, 0x18000
	s_add_i32 s75, 0, 0x1c000
	v_add_u32_e32 v164, s74, v150
	v_add_u32_e32 v179, s75, v150
	ds_read_b128 v[146:149], v164
	ds_read_b128 v[156:159], v164 offset:1024
	ds_read_b128 v[160:163], v164 offset:2048
	ds_read_b128 v[164:167], v164 offset:3072
	ds_read_b128 v[168:171], v179
	ds_read_b128 v[172:175], v179 offset:1024
	ds_read_b128 v[180:183], v179 offset:2048
	ds_read_b128 v[184:187], v179 offset:3072
	s_add_u32 s54, s54, 0x40000
	s_addc_u32 s55, s55, 0
	s_mov_b32 m0, s49
	v_lshl_add_u64 v[232:233], s[54:55], 0, v[128:129]
	ds_read_b128 v[188:191], v154 offset:32768
	ds_read_b128 v[192:195], v154 offset:33792
	ds_read_b128 v[196:199], v154 offset:34816
	ds_read_b128 v[206:209], v154 offset:35840
	ds_read_b128 v[210:213], v154 offset:36864
	ds_read_b128 v[214:217], v154 offset:37888
	ds_read_b128 v[218:221], v154 offset:38912
	ds_read_b128 v[222:225], v154 offset:39936
	global_load_lds_dwordx4 v[232:233], off
	v_lshl_add_u64 v[232:233], s[54:55], 0, v[132:133]
	s_mov_b32 m0, s56
	s_nop 0
	global_load_lds_dwordx4 v[232:233], off
	s_waitcnt vmcnt(8)
	s_waitcnt lgkmcnt(0)
	s_barrier
	s_setprio 1
	s_waitcnt lgkmcnt(0)
	v_mfma_f32_16x16x32_bf16 v[124:127], v[146:149], v[188:191], v[124:127]
	v_mfma_f32_16x16x32_bf16 v[120:123], v[160:163], v[188:191], v[120:123]
	v_mfma_f32_16x16x32_bf16 v[108:111], v[146:149], v[196:199], v[108:111]
	v_mfma_f32_16x16x32_bf16 v[104:107], v[160:163], v[196:199], v[104:107]
	v_mfma_f32_16x16x32_bf16 v[92:95], v[146:149], v[210:213], v[92:95]
	v_mfma_f32_16x16x32_bf16 v[88:91], v[160:163], v[210:213], v[88:91]
	v_mfma_f32_16x16x32_bf16 v[76:79], v[146:149], v[218:221], v[76:79]
	v_mfma_f32_16x16x32_bf16 v[72:75], v[160:163], v[218:221], v[72:75]
	v_mfma_f32_16x16x32_bf16 v[124:127], v[156:159], v[192:195], v[124:127]
	v_mfma_f32_16x16x32_bf16 v[120:123], v[164:167], v[192:195], v[120:123]
	v_mfma_f32_16x16x32_bf16 v[108:111], v[156:159], v[206:209], v[108:111]
	v_mfma_f32_16x16x32_bf16 v[104:107], v[164:167], v[206:209], v[104:107]
	v_mfma_f32_16x16x32_bf16 v[92:95], v[156:159], v[214:217], v[92:95]
	v_mfma_f32_16x16x32_bf16 v[88:91], v[164:167], v[214:217], v[88:91]
	v_mfma_f32_16x16x32_bf16 v[76:79], v[156:159], v[222:225], v[76:79]
	v_mfma_f32_16x16x32_bf16 v[72:75], v[164:167], v[222:225], v[72:75]
	s_setprio 0
	s_setprio 1
	v_mfma_f32_16x16x32_bf16 v[116:119], v[168:171], v[188:191], v[116:119]
	v_mfma_f32_16x16x32_bf16 v[112:115], v[180:183], v[188:191], v[112:115]
	v_mfma_f32_16x16x32_bf16 v[100:103], v[168:171], v[196:199], v[100:103]
	v_mfma_f32_16x16x32_bf16 v[96:99], v[180:183], v[196:199], v[96:99]
	v_mfma_f32_16x16x32_bf16 v[84:87], v[168:171], v[210:213], v[84:87]
	v_mfma_f32_16x16x32_bf16 v[80:83], v[180:183], v[210:213], v[80:83]
	v_mfma_f32_16x16x32_bf16 v[68:71], v[168:171], v[218:221], v[68:71]
	v_mfma_f32_16x16x32_bf16 v[64:67], v[180:183], v[218:221], v[64:67]
	v_mfma_f32_16x16x32_bf16 v[116:119], v[172:175], v[192:195], v[116:119]
	v_mfma_f32_16x16x32_bf16 v[112:115], v[184:187], v[192:195], v[112:115]
	v_mfma_f32_16x16x32_bf16 v[100:103], v[172:175], v[206:209], v[100:103]
	v_mfma_f32_16x16x32_bf16 v[96:99], v[184:187], v[206:209], v[96:99]
	v_mfma_f32_16x16x32_bf16 v[84:87], v[172:175], v[214:217], v[84:87]
	v_mfma_f32_16x16x32_bf16 v[80:83], v[184:187], v[214:217], v[80:83]
	v_mfma_f32_16x16x32_bf16 v[68:71], v[172:175], v[222:225], v[68:71]
	v_mfma_f32_16x16x32_bf16 v[64:67], v[184:187], v[222:225], v[64:67]
	s_setprio 0
	s_barrier
; #define PG8_STAGE(bufoff, gbase, voff) do { _Pragma("unroll") for (int _i = 0; _i < 2; ++_i) \
;         __builtin_amdgcn_global_load_lds((const unsigned*)((const char*)(gbase) + (voff)[_i]), (PG8_LAS unsigned*)(lds + (bufoff) + ldsw + _i * 8192), 16, 0, 0); } while (0)
; #define PG8_LDA(dst, b, h) do { _Pragma("unroll") for (int m = 0; m < 4; ++m) _Pragma("unroll") for (int k = 0; k < 2; ++k) dst[m][k] = *(const PG8_LAS bf16x8*)(lds + PG8_SA(b, h) + aoff + m * 2048 + k * 1024); } while (0)
; #define PG8_LDB(dst, b, h) do { _Pragma("unroll") for (int n = 0; n < 2; ++n) _Pragma("unroll") for (int k = 0; k < 2; ++k) dst[n][k] = *(const PG8_LAS bf16x8*)(lds + PG8_SB(b, h) + boff + n * 2048 + k * 1024); } while (0)
; #define PG8_MMA(ai, bj, At, Bt) do { __builtin_amdgcn_s_setprio(1); _Pragma("unroll") for (int m = 0; m < 4; ++m) _Pragma("unroll") for (int n = 0; n < 2; ++n) _Pragma("unroll") for (int k = 0; k < 2; ++k) \
;         acc[ai][bj][m][n] = __builtin_amdgcn_mfma_f32_16x16x32_bf16(Bt[n][k], At[m][k], acc[ai][bj][m][n], 0, 0, 0); __builtin_amdgcn_s_setprio(0); } while (0)
; #define PG8_WAIT_V(n) asm volatile("s_waitcnt vmcnt(" #n ")" ::: "memory")
; #define PG8_WAIT_L(n) asm volatile("s_waitcnt lgkmcnt(" #n ")" ::: "memory")
; #define PG8_BAR __builtin_amdgcn_s_barrier()
; #define PG8_SCHED __builtin_amdgcn_sched_barrier(0)
; template <class Epi, class Sched, bool ALIGN_EPI = false, bool SP2 = false>
; __device__ __forceinline__ void gemm_phase(PG8_LAS unsigned char* lds, const Gemm g, const Sched& S, const Epi& E) {
;     ...
;             const bool last = (t == nt - 2);
;             const char* a1 = cA + (size_t)(t + 1) * kstep;
;             const char* a2 = last ? nA : cA + (size_t)(t + 2) * kstep; const char* b2 = last ? nB : cB + (size_t)(t + 2) * kstep;
;             const char* a3 = a2 + kstep; const char* b3 = b2 + kstep;
;             if (last && has_next) S.a_ready(nxt);
;             if constexpr (SP2) {
;             PG8_LDB(B0, 0, 0); PG8_LDB(B1, 0, 1); PG8_SCHED; PG8_LDA(At, 0, 0); PG8_STAGE(PG8_SA(1, 1), a1 + hstep, voffA);
;     ...
;             PG8_LDA(At, 1, 1); PG8_STAGE(PG8_SB(1, 0), b3, voffB); PG8_STAGE(PG8_SB(1, 1), b3 + hstep, voffB); PG8_STAGE(PG8_SA(1, 0), a3, voffA);
;             PG8_WAIT_V(8); PG8_WAIT_L(0); PG8_BAR; PG8_MMA(1, 0, At, B0); PG8_MMA(1, 1, At, B1); PG8_BAR; PG8_SCHED;
	s_add_i32 s54, s74, s15
	v_lshl_add_u64 v[200:201], v[200:201], 0, s[26:27]
	s_mov_b32 m0, s54
	ds_read_b128 v[188:191], v154 offset:49152
	ds_read_b128 v[192:195], v154 offset:50176
	ds_read_b128 v[196:199], v154 offset:51200
	ds_read_b128 v[206:209], v154 offset:52224
	ds_read_b128 v[210:213], v154 offset:53248
	ds_read_b128 v[214:217], v154 offset:54272
	ds_read_b128 v[218:221], v154 offset:55296
	ds_read_b128 v[222:225], v154 offset:56320
	global_load_lds_dwordx4 v[200:201], off
	s_add_i32 m0, s54, 0x2000
	s_add_u32 s52, s52, 0x40080
	v_lshl_add_u64 v[200:201], v[226:227], 0, s[26:27]
	s_addc_u32 s53, s53, 0
	s_add_i32 s54, s75, s15
	global_load_lds_dwordx4 v[200:201], off
	v_lshl_add_u64 v[200:201], s[52:53], 0, v[130:131]
	s_mov_b32 m0, s54
	s_nop 0
	global_load_lds_dwordx4 v[200:201], off
	v_lshl_add_u64 v[200:201], s[52:53], 0, v[134:135]
	s_add_i32 m0, s54, 0x2000
	s_nop 0
	global_load_lds_dwordx4 v[200:201], off
	s_waitcnt vmcnt(6)
	s_waitcnt lgkmcnt(0)
	s_barrier
	s_setprio 1
	s_waitcnt lgkmcnt(0)
	v_mfma_f32_16x16x32_bf16 v[60:63], v[146:149], v[188:191], v[60:63]
	v_mfma_f32_16x16x32_bf16 v[56:59], v[160:163], v[188:191], v[56:59]
	v_mfma_f32_16x16x32_bf16 v[44:47], v[146:149], v[196:199], v[44:47]
	v_mfma_f32_16x16x32_bf16 v[40:43], v[160:163], v[196:199], v[40:43]
	v_mfma_f32_16x16x32_bf16 v[28:31], v[146:149], v[210:213], v[28:31]
	v_mfma_f32_16x16x32_bf16 v[24:27], v[160:163], v[210:213], v[24:27]
	v_mfma_f32_16x16x32_bf16 v[12:15], v[146:149], v[218:221], v[12:15]
	v_mfma_f32_16x16x32_bf16 v[8:11], v[160:163], v[218:221], v[8:11]
	v_mfma_f32_16x16x32_bf16 v[60:63], v[156:159], v[192:195], v[60:63]
	v_mfma_f32_16x16x32_bf16 v[56:59], v[164:167], v[192:195], v[56:59]
	v_mfma_f32_16x16x32_bf16 v[44:47], v[156:159], v[206:209], v[44:47]
	v_mfma_f32_16x16x32_bf16 v[40:43], v[164:167], v[206:209], v[40:43]
	v_mfma_f32_16x16x32_bf16 v[28:31], v[156:159], v[214:217], v[28:31]
	v_mfma_f32_16x16x32_bf16 v[24:27], v[164:167], v[214:217], v[24:27]
	v_lshl_add_u64 v[200:201], v[228:229], 0, s[26:27]
	s_mov_b32 m0, s58
	s_nop 0
	global_load_lds_dwordx4 v[200:201], off
	v_mfma_f32_16x16x32_bf16 v[12:15], v[156:159], v[222:225], v[12:15]
	v_mfma_f32_16x16x32_bf16 v[8:11], v[164:167], v[222:225], v[8:11]
	s_setprio 0
	s_setprio 1
	v_mfma_f32_16x16x32_bf16 v[52:55], v[168:171], v[188:191], v[52:55]
	v_mfma_f32_16x16x32_bf16 v[48:51], v[180:183], v[188:191], v[48:51]
	v_mfma_f32_16x16x32_bf16 v[36:39], v[168:171], v[196:199], v[36:39]
	v_mfma_f32_16x16x32_bf16 v[32:35], v[180:183], v[196:199], v[32:35]
	v_mfma_f32_16x16x32_bf16 v[20:23], v[168:171], v[210:213], v[20:23]
	v_mfma_f32_16x16x32_bf16 v[16:19], v[180:183], v[210:213], v[16:19]
	v_mfma_f32_16x16x32_bf16 v[4:7], v[168:171], v[218:221], v[4:7]
	v_mfma_f32_16x16x32_bf16 v[0:3], v[180:183], v[218:221], v[0:3]
	v_mfma_f32_16x16x32_bf16 v[52:55], v[172:175], v[192:195], v[52:55]
	v_mfma_f32_16x16x32_bf16 v[48:51], v[184:187], v[192:195], v[48:51]
	v_mfma_f32_16x16x32_bf16 v[36:39], v[172:175], v[206:209], v[36:39]
	v_mfma_f32_16x16x32_bf16 v[32:35], v[184:187], v[206:209], v[32:35]
	v_mfma_f32_16x16x32_bf16 v[20:23], v[172:175], v[214:217], v[20:23]
	v_mfma_f32_16x16x32_bf16 v[16:19], v[184:187], v[214:217], v[16:19]
	v_lshl_add_u64 v[200:201], v[230:231], 0, s[26:27]
	s_mov_b32 m0, s59
	s_nop 0
	global_load_lds_dwordx4 v[200:201], off
	v_mfma_f32_16x16x32_bf16 v[4:7], v[172:175], v[222:225], v[4:7]
	v_mfma_f32_16x16x32_bf16 v[0:3], v[184:187], v[222:225], v[0:3]
	s_setprio 0
	s_barrier
	s_add_i32 s67, s67, 2
	s_add_u32 s50, s50, 0x100
	s_addc_u32 s51, s51, 0
	s_add_u32 s65, s65, 0x100
	s_addc_u32 s66, s66, 0
.LBB0_1593:
	ds_read_b128 v[146:149], v152
	ds_read_b128 v[156:159], v152 offset:1024
	ds_read_b128 v[160:163], v152 offset:2048
	ds_read_b128 v[164:167], v152 offset:3072
	ds_read_b128 v[168:171], v153
	ds_read_b128 v[172:175], v153 offset:1024
	ds_read_b128 v[180:183], v153 offset:2048
	ds_read_b128 v[184:187], v153 offset:3072
	s_add_u32 s52, s50, 0xfffc0080
	s_addc_u32 s53, s51, -1
	s_cmp_eq_u32 s67, 12
	s_cselect_b32 s55, s39, s53
	s_cselect_b32 s54, s47, s52
	s_cselect_b32 s53, s37, s66
	s_cselect_b32 s52, s64, s65
	v_lshl_add_u64 v[200:201], s[50:51], 0, v[136:137]
	s_add_i32 m0, s33, 0xc000
	ds_read_b128 v[188:191], v154
	ds_read_b128 v[192:195], v154 offset:1024
	ds_read_b128 v[196:199], v154 offset:2048
	ds_read_b128 v[206:209], v154 offset:3072
	ds_read_b128 v[210:213], v154 offset:4096
	ds_read_b128 v[214:217], v154 offset:5120
	ds_read_b128 v[218:221], v154 offset:6144
	ds_read_b128 v[222:225], v154 offset:7168
	global_load_lds_dwordx4 v[200:201], off
	v_lshl_add_u64 v[200:201], s[50:51], 0, v[138:139]
	s_add_i32 m0, s33, 0xe000
	s_nop 0
	global_load_lds_dwordx4 v[200:201], off
	s_waitcnt vmcnt(8)
	s_waitcnt lgkmcnt(0)
	s_barrier
; #define PG8_STAGE(bufoff, gbase, voff) do { _Pragma("unroll") for (int _i = 0; _i < 2; ++_i) \
;         __builtin_amdgcn_global_load_lds((const unsigned*)((const char*)(gbase) + (voff)[_i]), (PG8_LAS unsigned*)(lds + (bufoff) + ldsw + _i * 8192), 16, 0, 0); } while (0)
; #define PG8_LDA(dst, b, h) do { _Pragma("unroll") for (int m = 0; m < 4; ++m) _Pragma("unroll") for (int k = 0; k < 2; ++k) dst[m][k] = *(const PG8_LAS bf16x8*)(lds + PG8_SA(b, h) + aoff + m * 2048 + k * 1024); } while (0)
; #define PG8_MMA(ai, bj, At, Bt) do { __builtin_amdgcn_s_setprio(1); _Pragma("unroll") for (int m = 0; m < 4; ++m) _Pragma("unroll") for (int n = 0; n < 2; ++n) _Pragma("unroll") for (int k = 0; k < 2; ++k) \
;         acc[ai][bj][m][n] = __builtin_amdgcn_mfma_f32_16x16x32_bf16(Bt[n][k], At[m][k], acc[ai][bj][m][n], 0, 0, 0); __builtin_amdgcn_s_setprio(0); } while (0)
; #define PG8_WAIT_V(n) asm volatile("s_waitcnt vmcnt(" #n ")" ::: "memory")
; #define PG8_WAIT_L(n) asm volatile("s_waitcnt lgkmcnt(" #n ")" ::: "memory")
; #define PG8_BAR __builtin_amdgcn_s_barrier()
; #define PG8_SCHED __builtin_amdgcn_sched_barrier(0)
; template <class Epi, class Sched, bool ALIGN_EPI = false, bool SP2 = false>
; __device__ __forceinline__ void gemm_phase(PG8_LAS unsigned char* lds, const Gemm g, const Sched& S, const Epi& E) {
;     ...
;             PG8_WAIT_V(8); PG8_WAIT_L(0); PG8_BAR; PG8_MMA(0, 0, At, B0); PG8_MMA(0, 1, At, B1); PG8_BAR; PG8_SCHED;
;             PG8_LDA(At, 0, 1); PG8_STAGE(PG8_SB(0, 0), b2, voffB); PG8_STAGE(PG8_SB(0, 1), b2 + hstep, voffB); PG8_STAGE(PG8_SA(0, 0), a2, voffA);
;             PG8_WAIT_V(8); PG8_WAIT_L(0); PG8_BAR; PG8_MMA(1, 0, At, B0); PG8_MMA(1, 1, At, B1); PG8_BAR; PG8_SCHED;
	s_setprio 1
	s_waitcnt lgkmcnt(0)
	v_mfma_f32_16x16x32_bf16 v[124:127], v[146:149], v[188:191], v[124:127]
	v_mfma_f32_16x16x32_bf16 v[120:123], v[160:163], v[188:191], v[120:123]
	v_mfma_f32_16x16x32_bf16 v[108:111], v[146:149], v[196:199], v[108:111]
	v_mfma_f32_16x16x32_bf16 v[104:107], v[160:163], v[196:199], v[104:107]
	v_mfma_f32_16x16x32_bf16 v[92:95], v[146:149], v[210:213], v[92:95]
	v_mfma_f32_16x16x32_bf16 v[88:91], v[160:163], v[210:213], v[88:91]
	v_mfma_f32_16x16x32_bf16 v[76:79], v[146:149], v[218:221], v[76:79]
	v_mfma_f32_16x16x32_bf16 v[72:75], v[160:163], v[218:221], v[72:75]
	v_mfma_f32_16x16x32_bf16 v[124:127], v[156:159], v[192:195], v[124:127]
	v_mfma_f32_16x16x32_bf16 v[120:123], v[164:167], v[192:195], v[120:123]
	v_mfma_f32_16x16x32_bf16 v[108:111], v[156:159], v[206:209], v[108:111]
	v_mfma_f32_16x16x32_bf16 v[104:107], v[164:167], v[206:209], v[104:107]
	v_mfma_f32_16x16x32_bf16 v[92:95], v[156:159], v[214:217], v[92:95]
	v_mfma_f32_16x16x32_bf16 v[88:91], v[164:167], v[214:217], v[88:91]
	v_mfma_f32_16x16x32_bf16 v[76:79], v[156:159], v[222:225], v[76:79]
	v_mfma_f32_16x16x32_bf16 v[72:75], v[164:167], v[222:225], v[72:75]
	s_setprio 0
	s_setprio 1
	v_mfma_f32_16x16x32_bf16 v[116:119], v[168:171], v[188:191], v[116:119]
	v_mfma_f32_16x16x32_bf16 v[112:115], v[180:183], v[188:191], v[112:115]
	v_mfma_f32_16x16x32_bf16 v[100:103], v[168:171], v[196:199], v[100:103]
	v_mfma_f32_16x16x32_bf16 v[96:99], v[180:183], v[196:199], v[96:99]
	v_mfma_f32_16x16x32_bf16 v[84:87], v[168:171], v[210:213], v[84:87]
	v_mfma_f32_16x16x32_bf16 v[80:83], v[180:183], v[210:213], v[80:83]
	v_mfma_f32_16x16x32_bf16 v[68:71], v[168:171], v[218:221], v[68:71]
	v_mfma_f32_16x16x32_bf16 v[64:67], v[180:183], v[218:221], v[64:67]
	v_mfma_f32_16x16x32_bf16 v[116:119], v[172:175], v[192:195], v[116:119]
	v_mfma_f32_16x16x32_bf16 v[112:115], v[184:187], v[192:195], v[112:115]
	v_mfma_f32_16x16x32_bf16 v[100:103], v[172:175], v[206:209], v[100:103]
	v_mfma_f32_16x16x32_bf16 v[96:99], v[184:187], v[206:209], v[96:99]
	v_mfma_f32_16x16x32_bf16 v[84:87], v[172:175], v[214:217], v[84:87]
	v_mfma_f32_16x16x32_bf16 v[80:83], v[184:187], v[214:217], v[80:83]
	v_mfma_f32_16x16x32_bf16 v[68:71], v[172:175], v[222:225], v[68:71]
	v_mfma_f32_16x16x32_bf16 v[64:67], v[184:187], v[222:225], v[64:67]
	s_setprio 0
	s_barrier
	s_add_i32 s74, s60, s15
	v_lshl_add_u64 v[200:201], s[52:53], 0, v[130:131]
	s_mov_b32 m0, s74
	ds_read_b128 v[188:191], v154 offset:16384
	ds_read_b128 v[192:195], v154 offset:17408
	ds_read_b128 v[196:199], v154 offset:18432
	ds_read_b128 v[206:209], v154 offset:19456
	ds_read_b128 v[210:213], v154 offset:20480
	ds_read_b128 v[214:217], v154 offset:21504
	ds_read_b128 v[218:221], v154 offset:22528
	ds_read_b128 v[222:225], v154 offset:23552
	global_load_lds_dwordx4 v[200:201], off
	s_add_i32 m0, s74, 0x2000
	s_add_u32 s74, s52, 0x40000
	v_lshl_add_u64 v[226:227], s[52:53], 0, v[134:135]
	s_addc_u32 s75, s53, 0
	s_add_i32 s76, s61, s15
	global_load_lds_dwordx4 v[226:227], off
	v_lshl_add_u64 v[228:229], s[74:75], 0, v[130:131]
	s_mov_b32 m0, s76
	global_load_lds_dwordx4 v[228:229], off
	v_lshl_add_u64 v[228:229], s[74:75], 0, v[134:135]
	s_add_i32 m0, s76, 0x2000
	s_nop 0
	global_load_lds_dwordx4 v[228:229], off
	s_waitcnt vmcnt(6)
	s_waitcnt lgkmcnt(0)
	s_barrier
	s_setprio 1
	s_waitcnt lgkmcnt(0)
	v_mfma_f32_16x16x32_bf16 v[60:63], v[146:149], v[188:191], v[60:63]
	v_mfma_f32_16x16x32_bf16 v[56:59], v[160:163], v[188:191], v[56:59]
	v_mfma_f32_16x16x32_bf16 v[44:47], v[146:149], v[196:199], v[44:47]
	v_mfma_f32_16x16x32_bf16 v[40:43], v[160:163], v[196:199], v[40:43]
	v_mfma_f32_16x16x32_bf16 v[28:31], v[146:149], v[210:213], v[28:31]
	v_mfma_f32_16x16x32_bf16 v[24:27], v[160:163], v[210:213], v[24:27]
	v_mfma_f32_16x16x32_bf16 v[12:15], v[146:149], v[218:221], v[12:15]
	v_mfma_f32_16x16x32_bf16 v[8:11], v[160:163], v[218:221], v[8:11]
	v_mfma_f32_16x16x32_bf16 v[60:63], v[156:159], v[192:195], v[60:63]
	v_mfma_f32_16x16x32_bf16 v[56:59], v[164:167], v[192:195], v[56:59]
	v_mfma_f32_16x16x32_bf16 v[44:47], v[156:159], v[206:209], v[44:47]
	v_mfma_f32_16x16x32_bf16 v[40:43], v[164:167], v[206:209], v[40:43]
	v_mfma_f32_16x16x32_bf16 v[28:31], v[156:159], v[214:217], v[28:31]
	v_mfma_f32_16x16x32_bf16 v[24:27], v[164:167], v[214:217], v[24:27]
	v_lshl_add_u64 v[228:229], s[54:55], 0, v[128:129]
	s_mov_b32 m0, s33
	s_nop 0
	global_load_lds_dwordx4 v[228:229], off
	v_mfma_f32_16x16x32_bf16 v[12:15], v[156:159], v[222:225], v[12:15]
	v_mfma_f32_16x16x32_bf16 v[8:11], v[164:167], v[222:225], v[8:11]
	s_setprio 0
	s_setprio 1
	v_mfma_f32_16x16x32_bf16 v[52:55], v[168:171], v[188:191], v[52:55]
	v_mfma_f32_16x16x32_bf16 v[48:51], v[180:183], v[188:191], v[48:51]
	v_mfma_f32_16x16x32_bf16 v[36:39], v[168:171], v[196:199], v[36:39]
	v_mfma_f32_16x16x32_bf16 v[32:35], v[180:183], v[196:199], v[32:35]
	v_mfma_f32_16x16x32_bf16 v[20:23], v[168:171], v[210:213], v[20:23]
	v_mfma_f32_16x16x32_bf16 v[16:19], v[180:183], v[210:213], v[16:19]
	v_mfma_f32_16x16x32_bf16 v[4:7], v[168:171], v[218:221], v[4:7]
	v_mfma_f32_16x16x32_bf16 v[0:3], v[180:183], v[218:221], v[0:3]
	v_mfma_f32_16x16x32_bf16 v[52:55], v[172:175], v[192:195], v[52:55]
	v_mfma_f32_16x16x32_bf16 v[48:51], v[184:187], v[192:195], v[48:51]
	v_mfma_f32_16x16x32_bf16 v[36:39], v[172:175], v[206:209], v[36:39]
	v_mfma_f32_16x16x32_bf16 v[32:35], v[184:187], v[206:209], v[32:35]
	v_mfma_f32_16x16x32_bf16 v[20:23], v[172:175], v[214:217], v[20:23]
	v_mfma_f32_16x16x32_bf16 v[16:19], v[184:187], v[214:217], v[16:19]
	v_lshl_add_u64 v[230:231], s[54:55], 0, v[132:133]
	s_mov_b32 m0, s34
	s_nop 0
	global_load_lds_dwordx4 v[230:231], off
	v_mfma_f32_16x16x32_bf16 v[4:7], v[172:175], v[222:225], v[4:7]
	v_mfma_f32_16x16x32_bf16 v[0:3], v[184:187], v[222:225], v[0:3]
	s_setprio 0
	s_barrier
; #define PG8_STAGE(bufoff, gbase, voff) do { _Pragma("unroll") for (int _i = 0; _i < 2; ++_i) \
;         __builtin_amdgcn_global_load_lds((const unsigned*)((const char*)(gbase) + (voff)[_i]), (PG8_LAS unsigned*)(lds + (bufoff) + ldsw + _i * 8192), 16, 0, 0); } while (0)
; #define PG8_LDA(dst, b, h) do { _Pragma("unroll") for (int m = 0; m < 4; ++m) _Pragma("unroll") for (int k = 0; k < 2; ++k) dst[m][k] = *(const PG8_LAS bf16x8*)(lds + PG8_SA(b, h) + aoff + m * 2048 + k * 1024); } while (0)
; #define PG8_LDB(dst, b, h) do { _Pragma("unroll") for (int n = 0; n < 2; ++n) _Pragma("unroll") for (int k = 0; k < 2; ++k) dst[n][k] = *(const PG8_LAS bf16x8*)(lds + PG8_SB(b, h) + boff + n * 2048 + k * 1024); } while (0)
; #define PG8_MMA(ai, bj, At, Bt) do { __builtin_amdgcn_s_setprio(1); _Pragma("unroll") for (int m = 0; m < 4; ++m) _Pragma("unroll") for (int n = 0; n < 2; ++n) _Pragma("unroll") for (int k = 0; k < 2; ++k) \
;         acc[ai][bj][m][n] = __builtin_amdgcn_mfma_f32_16x16x32_bf16(Bt[n][k], At[m][k], acc[ai][bj][m][n], 0, 0, 0); __builtin_amdgcn_s_setprio(0); } while (0)
; #define PG8_WAIT_V(n) asm volatile("s_waitcnt vmcnt(" #n ")" ::: "memory")
; #define PG8_WAIT_L(n) asm volatile("s_waitcnt lgkmcnt(" #n ")" ::: "memory")
; #define PG8_BAR __builtin_amdgcn_s_barrier()
; #define PG8_SCHED __builtin_amdgcn_sched_barrier(0)
; template <class Epi, class Sched, bool ALIGN_EPI = false, bool SP2 = false>
; __device__ __forceinline__ void gemm_phase(PG8_LAS unsigned char* lds, const Gemm g, const Sched& S, const Epi& E) {
;     ...
;             PG8_LDB(B0, 1, 0); PG8_LDB(B1, 1, 1); PG8_SCHED; PG8_LDA(At, 1, 0); PG8_STAGE(PG8_SA(0, 1), a2 + hstep, voffA);
;             PG8_WAIT_V(8); PG8_WAIT_L(0); PG8_BAR; PG8_MMA(0, 0, At, B0); PG8_MMA(0, 1, At, B1); PG8_BAR; PG8_SCHED;
	s_add_i32 s74, 0, 0x18000
	s_add_i32 s75, 0, 0x1c000
	v_add_u32_e32 v164, s74, v150
	v_add_u32_e32 v179, s75, v150
	ds_read_b128 v[146:149], v164
	ds_read_b128 v[156:159], v164 offset:1024
	ds_read_b128 v[160:163], v164 offset:2048
	ds_read_b128 v[164:167], v164 offset:3072
	ds_read_b128 v[168:171], v179
	ds_read_b128 v[172:175], v179 offset:1024
	ds_read_b128 v[180:183], v179 offset:2048
	ds_read_b128 v[184:187], v179 offset:3072
	s_add_u32 s54, s54, 0x40000
	s_addc_u32 s55, s55, 0
	s_mov_b32 m0, s49
	v_lshl_add_u64 v[232:233], s[54:55], 0, v[128:129]
	ds_read_b128 v[188:191], v154 offset:32768
	ds_read_b128 v[192:195], v154 offset:33792
	ds_read_b128 v[196:199], v154 offset:34816
	ds_read_b128 v[206:209], v154 offset:35840
	ds_read_b128 v[210:213], v154 offset:36864
	ds_read_b128 v[214:217], v154 offset:37888
	ds_read_b128 v[218:221], v154 offset:38912
	ds_read_b128 v[222:225], v154 offset:39936
	global_load_lds_dwordx4 v[232:233], off
	v_lshl_add_u64 v[232:233], s[54:55], 0, v[132:133]
	s_mov_b32 m0, s56
	s_nop 0
	global_load_lds_dwordx4 v[232:233], off
	s_waitcnt vmcnt(8)
	s_waitcnt lgkmcnt(0)
	s_barrier
	s_setprio 1
	s_waitcnt lgkmcnt(0)
	v_mfma_f32_16x16x32_bf16 v[124:127], v[146:149], v[188:191], v[124:127]
	v_mfma_f32_16x16x32_bf16 v[120:123], v[160:163], v[188:191], v[120:123]
	v_mfma_f32_16x16x32_bf16 v[108:111], v[146:149], v[196:199], v[108:111]
	v_mfma_f32_16x16x32_bf16 v[104:107], v[160:163], v[196:199], v[104:107]
	v_mfma_f32_16x16x32_bf16 v[92:95], v[146:149], v[210:213], v[92:95]
	v_mfma_f32_16x16x32_bf16 v[88:91], v[160:163], v[210:213], v[88:91]
	v_mfma_f32_16x16x32_bf16 v[76:79], v[146:149], v[218:221], v[76:79]
	v_mfma_f32_16x16x32_bf16 v[72:75], v[160:163], v[218:221], v[72:75]
	v_mfma_f32_16x16x32_bf16 v[124:127], v[156:159], v[192:195], v[124:127]
	v_mfma_f32_16x16x32_bf16 v[120:123], v[164:167], v[192:195], v[120:123]
	v_mfma_f32_16x16x32_bf16 v[108:111], v[156:159], v[206:209], v[108:111]
	v_mfma_f32_16x16x32_bf16 v[104:107], v[164:167], v[206:209], v[104:107]
	v_mfma_f32_16x16x32_bf16 v[92:95], v[156:159], v[214:217], v[92:95]
	v_mfma_f32_16x16x32_bf16 v[88:91], v[164:167], v[214:217], v[88:91]
	v_mfma_f32_16x16x32_bf16 v[76:79], v[156:159], v[222:225], v[76:79]
	v_mfma_f32_16x16x32_bf16 v[72:75], v[164:167], v[222:225], v[72:75]
	s_setprio 0
	s_setprio 1
	v_mfma_f32_16x16x32_bf16 v[116:119], v[168:171], v[188:191], v[116:119]
	v_mfma_f32_16x16x32_bf16 v[112:115], v[180:183], v[188:191], v[112:115]
	v_mfma_f32_16x16x32_bf16 v[100:103], v[168:171], v[196:199], v[100:103]
	v_mfma_f32_16x16x32_bf16 v[96:99], v[180:183], v[196:199], v[96:99]
	v_mfma_f32_16x16x32_bf16 v[84:87], v[168:171], v[210:213], v[84:87]
	v_mfma_f32_16x16x32_bf16 v[80:83], v[180:183], v[210:213], v[80:83]
	v_mfma_f32_16x16x32_bf16 v[68:71], v[168:171], v[218:221], v[68:71]
	v_mfma_f32_16x16x32_bf16 v[64:67], v[180:183], v[218:221], v[64:67]
	v_mfma_f32_16x16x32_bf16 v[116:119], v[172:175], v[192:195], v[116:119]
	v_mfma_f32_16x16x32_bf16 v[112:115], v[184:187], v[192:195], v[112:115]
	v_mfma_f32_16x16x32_bf16 v[100:103], v[172:175], v[206:209], v[100:103]
	v_mfma_f32_16x16x32_bf16 v[96:99], v[184:187], v[206:209], v[96:99]
	v_mfma_f32_16x16x32_bf16 v[84:87], v[172:175], v[214:217], v[84:87]
	v_mfma_f32_16x16x32_bf16 v[80:83], v[184:187], v[214:217], v[80:83]
	v_mfma_f32_16x16x32_bf16 v[68:71], v[172:175], v[222:225], v[68:71]
	v_mfma_f32_16x16x32_bf16 v[64:67], v[184:187], v[222:225], v[64:67]
	s_setprio 0
	s_barrier
; #define PG8_STAGE(bufoff, gbase, voff) do { _Pragma("unroll") for (int _i = 0; _i < 2; ++_i) \
;         __builtin_amdgcn_global_load_lds((const unsigned*)((const char*)(gbase) + (voff)[_i]), (PG8_LAS unsigned*)(lds + (bufoff) + ldsw + _i * 8192), 16, 0, 0); } while (0)
; #define PG8_LDA(dst, b, h) do { _Pragma("unroll") for (int m = 0; m < 4; ++m) _Pragma("unroll") for (int k = 0; k < 2; ++k) dst[m][k] = *(const PG8_LAS bf16x8*)(lds + PG8_SA(b, h) + aoff + m * 2048 + k * 1024); } while (0)
; #define PG8_MMA(ai, bj, At, Bt) do { __builtin_amdgcn_s_setprio(1); _Pragma("unroll") for (int m = 0; m < 4; ++m) _Pragma("unroll") for (int n = 0; n < 2; ++n) _Pragma("unroll") for (int k = 0; k < 2; ++k) \
;         acc[ai][bj][m][n] = __builtin_amdgcn_mfma_f32_16x16x32_bf16(Bt[n][k], At[m][k], acc[ai][bj][m][n], 0, 0, 0); __builtin_amdgcn_s_setprio(0); } while (0)
; #define PG8_WAIT_V(n) asm volatile("s_waitcnt vmcnt(" #n ")" ::: "memory")
; #define PG8_WAIT_L(n) asm volatile("s_waitcnt lgkmcnt(" #n ")" ::: "memory")
; #define PG8_BAR __builtin_amdgcn_s_barrier()
; #define PG8_SCHED __builtin_amdgcn_sched_barrier(0)
; template <class Epi, class Sched, bool ALIGN_EPI = false, bool SP2 = false>
; __device__ __forceinline__ void gemm_phase(PG8_LAS unsigned char* lds, const Gemm g, const Sched& S, const Epi& E) {
;     ...
;             PG8_LDA(At, 1, 1); PG8_STAGE(PG8_SB(1, 0), b3, voffB); PG8_STAGE(PG8_SB(1, 1), b3 + hstep, voffB); PG8_STAGE(PG8_SA(1, 0), a3, voffA);
;             PG8_WAIT_V(8); PG8_WAIT_L(0); PG8_BAR; PG8_MMA(1, 0, At, B0); PG8_MMA(1, 1, At, B1); PG8_BAR; PG8_SCHED;
;     ...
;         if constexpr (ALIGN_EPI) { if (wr == 0) PG8_BAR; }
	s_add_i32 s54, s74, s15
	v_lshl_add_u64 v[200:201], v[200:201], 0, s[26:27]
	s_mov_b32 m0, s54
	ds_read_b128 v[188:191], v154 offset:49152
	ds_read_b128 v[192:195], v154 offset:50176
	ds_read_b128 v[196:199], v154 offset:51200
	ds_read_b128 v[206:209], v154 offset:52224
	ds_read_b128 v[210:213], v154 offset:53248
	ds_read_b128 v[214:217], v154 offset:54272
	ds_read_b128 v[218:221], v154 offset:55296
	ds_read_b128 v[222:225], v154 offset:56320
	global_load_lds_dwordx4 v[200:201], off
	s_add_i32 m0, s54, 0x2000
	s_add_u32 s52, s52, 0x40080
	v_lshl_add_u64 v[200:201], v[226:227], 0, s[26:27]
	s_addc_u32 s53, s53, 0
	s_add_i32 s54, s75, s15
	global_load_lds_dwordx4 v[200:201], off
	v_lshl_add_u64 v[200:201], s[52:53], 0, v[130:131]
	s_mov_b32 m0, s54
	s_nop 0
	global_load_lds_dwordx4 v[200:201], off
	v_lshl_add_u64 v[200:201], s[52:53], 0, v[134:135]
	s_add_i32 m0, s54, 0x2000
	s_nop 0
	global_load_lds_dwordx4 v[200:201], off
	s_waitcnt vmcnt(6)
	s_waitcnt lgkmcnt(0)
	s_barrier
	s_setprio 1
	s_waitcnt lgkmcnt(0)
	v_mfma_f32_16x16x32_bf16 v[60:63], v[146:149], v[188:191], v[60:63]
	v_mfma_f32_16x16x32_bf16 v[56:59], v[160:163], v[188:191], v[56:59]
	v_mfma_f32_16x16x32_bf16 v[44:47], v[146:149], v[196:199], v[44:47]
	v_mfma_f32_16x16x32_bf16 v[40:43], v[160:163], v[196:199], v[40:43]
	v_mfma_f32_16x16x32_bf16 v[28:31], v[146:149], v[210:213], v[28:31]
	v_mfma_f32_16x16x32_bf16 v[24:27], v[160:163], v[210:213], v[24:27]
	v_mfma_f32_16x16x32_bf16 v[12:15], v[146:149], v[218:221], v[12:15]
	v_mfma_f32_16x16x32_bf16 v[8:11], v[160:163], v[218:221], v[8:11]
	v_mfma_f32_16x16x32_bf16 v[60:63], v[156:159], v[192:195], v[60:63]
	v_mfma_f32_16x16x32_bf16 v[56:59], v[164:167], v[192:195], v[56:59]
	v_mfma_f32_16x16x32_bf16 v[44:47], v[156:159], v[206:209], v[44:47]
	v_mfma_f32_16x16x32_bf16 v[40:43], v[164:167], v[206:209], v[40:43]
	v_mfma_f32_16x16x32_bf16 v[28:31], v[156:159], v[214:217], v[28:31]
	v_mfma_f32_16x16x32_bf16 v[24:27], v[164:167], v[214:217], v[24:27]
	v_lshl_add_u64 v[200:201], v[228:229], 0, s[26:27]
	s_mov_b32 m0, s58
	s_nop 0
	global_load_lds_dwordx4 v[200:201], off
	v_mfma_f32_16x16x32_bf16 v[12:15], v[156:159], v[222:225], v[12:15]
	v_mfma_f32_16x16x32_bf16 v[8:11], v[164:167], v[222:225], v[8:11]
	s_setprio 0
	s_setprio 1
	v_mfma_f32_16x16x32_bf16 v[52:55], v[168:171], v[188:191], v[52:55]
	v_mfma_f32_16x16x32_bf16 v[48:51], v[180:183], v[188:191], v[48:51]
	v_mfma_f32_16x16x32_bf16 v[36:39], v[168:171], v[196:199], v[36:39]
	v_mfma_f32_16x16x32_bf16 v[32:35], v[180:183], v[196:199], v[32:35]
	v_mfma_f32_16x16x32_bf16 v[20:23], v[168:171], v[210:213], v[20:23]
	v_mfma_f32_16x16x32_bf16 v[16:19], v[180:183], v[210:213], v[16:19]
	v_mfma_f32_16x16x32_bf16 v[4:7], v[168:171], v[218:221], v[4:7]
	v_mfma_f32_16x16x32_bf16 v[0:3], v[180:183], v[218:221], v[0:3]
	v_mfma_f32_16x16x32_bf16 v[52:55], v[172:175], v[192:195], v[52:55]
	v_mfma_f32_16x16x32_bf16 v[48:51], v[184:187], v[192:195], v[48:51]
	v_mfma_f32_16x16x32_bf16 v[36:39], v[172:175], v[206:209], v[36:39]
	v_mfma_f32_16x16x32_bf16 v[32:35], v[184:187], v[206:209], v[32:35]
	v_mfma_f32_16x16x32_bf16 v[20:23], v[172:175], v[214:217], v[20:23]
	v_mfma_f32_16x16x32_bf16 v[16:19], v[184:187], v[214:217], v[16:19]
	v_lshl_add_u64 v[200:201], v[230:231], 0, s[26:27]
	s_mov_b32 m0, s59
	s_nop 0
	global_load_lds_dwordx4 v[200:201], off
	v_mfma_f32_16x16x32_bf16 v[4:7], v[172:175], v[222:225], v[4:7]
	v_mfma_f32_16x16x32_bf16 v[0:3], v[184:187], v[222:225], v[0:3]
	s_setprio 0
	s_barrier
	s_add_i32 s67, s67, 2
	s_add_u32 s50, s50, 0x100
	s_addc_u32 s51, s51, 0
	s_add_u32 s65, s65, 0x100
	s_addc_u32 s66, s66, 0
	s_cmp_gt_u32 s67, 13
	s_cbranch_scc0 .LBB0_1593
	s_and_b64 vcc, exec, s[28:29]
	s_cbranch_vccz .LBB0_1596
	s_barrier

; #define PG8_STAGE(bufoff, gbase, voff) do { _Pragma("unroll") for (int _i = 0; _i < 2; ++_i) \
;         __builtin_amdgcn_global_load_lds((const unsigned*)((const char*)(gbase) + (voff)[_i]), (PG8_LAS unsigned*)(lds + (bufoff) + ldsw + _i * 8192), 16, 0, 0); } while (0)
; #define PG8_LDA(dst, b, h) do { _Pragma("unroll") for (int m = 0; m < 4; ++m) _Pragma("unroll") for (int k = 0; k < 2; ++k) dst[m][k] = *(const PG8_LAS bf16x8*)(lds + PG8_SA(b, h) + aoff + m * 2048 + k * 1024); } while (0)
; #define PG8_LDB(dst, b, h) do { _Pragma("unroll") for (int n = 0; n < 2; ++n) _Pragma("unroll") for (int k = 0; k < 2; ++k) dst[n][k] = *(const PG8_LAS bf16x8*)(lds + PG8_SB(b, h) + boff + n * 2048 + k * 1024); } while (0)
; #define PG8_MMA(ai, bj, At, Bt) do { __builtin_amdgcn_s_setprio(1); _Pragma("unroll") for (int m = 0; m < 4; ++m) _Pragma("unroll") for (int n = 0; n < 2; ++n) _Pragma("unroll") for (int k = 0; k < 2; ++k) \
;         acc[ai][bj][m][n] = __builtin_amdgcn_mfma_f32_16x16x32_bf16(Bt[n][k], At[m][k], acc[ai][bj][m][n], 0, 0, 0); __builtin_amdgcn_s_setprio(0); } while (0)
; #define PG8_WAIT_V(n) asm volatile("s_waitcnt vmcnt(" #n ")" ::: "memory")
; #define PG8_BAR __builtin_amdgcn_s_barrier()
; template <class Epi, class Sched, bool ALIGN_EPI = false, bool SP2 = false>
; __device__ __forceinline__ void gemm_phase(PG8_LAS unsigned char* lds, const Gemm g, const Sched& S, const Epi& E) {
;     ...
;         for (int t = 0; t < nt; t += 2) {
;             const bool last = (t == nt - 2);
;             const char* a1 = cA + (size_t)(t + 1) * kstep;
;             const char* a2 = last ? nA : cA + (size_t)(t + 2) * kstep; const char* b2 = last ? nB : cB + (size_t)(t + 2) * kstep;
;             const char* a3 = a2 + kstep; const char* b3 = b2 + kstep;
;             if (last && has_next) S.a_ready(nxt);
;             if constexpr (SP2) {
;             PG8_LDB(B0, 0, 0); PG8_LDB(B1, 0, 1); PG8_SCHED; PG8_LDA(At, 0, 0); PG8_STAGE(PG8_SA(1, 1), a1 + hstep, voffA);
;             PG8_WAIT_V(8); PG8_WAIT_L(0); PG8_BAR; PG8_MMA(0, 0, At, B0); PG8_MMA(0, 1, At, B1); PG8_BAR; PG8_SCHED;
;             PG8_LDA(At, 0, 1); PG8_STAGE(PG8_SB(0, 0), b2, voffB); PG8_STAGE(PG8_SB(0, 1), b2 + hstep, voffB); PG8_STAGE(PG8_SA(0, 0), a2, voffA);
;             PG8_WAIT_V(8); PG8_WAIT_L(0); PG8_BAR; PG8_MMA(1, 0, At, B0); PG8_MMA(1, 1, At, B1); PG8_BAR; PG8_SCHED;
.LBB0_1680:
	s_ashr_i32 s47, s46, 31
	s_lshl_b64 s[48:49], s[46:47], 19
	s_add_u32 s48, s22, s48
	s_addc_u32 s49, s23, s49
	s_and_b64 s[50:51], s[4:5], exec
	s_cselect_b32 s47, s49, s53
	s_cselect_b32 s77, s48, s52
	s_ashr_i32 s45, s44, 31
	s_lshl_b64 s[50:51], s[44:45], 19
	s_add_u32 s50, s15, s50
	s_addc_u32 s51, s33, s51
	s_and_b64 s[56:57], s[4:5], exec
	s_cselect_b32 s45, s51, s55
	s_cselect_b32 s78, s50, s54
	s_add_u32 s52, s52, 0x40080
	s_addc_u32 s53, s53, 0
	s_add_u32 s79, s54, 0x100
	s_addc_u32 s80, s55, 0
	s_mov_b32 s81, -2
	ds_read_b128 v[146:149], v152
	ds_read_b128 v[156:159], v152 offset:1024
	ds_read_b128 v[160:163], v152 offset:2048
	ds_read_b128 v[164:167], v152 offset:3072
	ds_read_b128 v[168:171], v153
	ds_read_b128 v[172:175], v153 offset:1024
	ds_read_b128 v[180:183], v153 offset:2048
	ds_read_b128 v[184:187], v153 offset:3072
	s_add_u32 s54, s52, 0xfffc0080
	s_addc_u32 s55, s53, -1
	s_cmp_eq_u32 s81, 12
	s_cselect_b32 s57, s47, s55
	s_cselect_b32 s56, s77, s54
	s_cselect_b32 s55, s45, s80
	s_cselect_b32 s54, s78, s79
	v_lshl_add_u64 v[200:201], s[52:53], 0, v[136:137]
	s_add_i32 m0, s58, 0xc000
	ds_read_b128 v[188:191], v154
	ds_read_b128 v[192:195], v154 offset:1024
	ds_read_b128 v[196:199], v154 offset:2048
	ds_read_b128 v[206:209], v154 offset:3072
	ds_read_b128 v[210:213], v154 offset:4096
	ds_read_b128 v[214:217], v154 offset:5120
	ds_read_b128 v[218:221], v154 offset:6144
	ds_read_b128 v[222:225], v154 offset:7168
	global_load_lds_dwordx4 v[200:201], off
	v_lshl_add_u64 v[200:201], s[52:53], 0, v[138:139]
	s_add_i32 m0, s58, 0xe000
	s_nop 0
	global_load_lds_dwordx4 v[200:201], off
	s_waitcnt vmcnt(8)
	s_waitcnt lgkmcnt(0)
	s_barrier
	s_setprio 1
	s_waitcnt lgkmcnt(0)
	v_mfma_f32_16x16x32_bf16 v[124:127], v[146:149], v[188:191], 0
	v_mfma_f32_16x16x32_bf16 v[120:123], v[160:163], v[188:191], 0
	v_mfma_f32_16x16x32_bf16 v[108:111], v[146:149], v[196:199], 0
	v_mfma_f32_16x16x32_bf16 v[104:107], v[160:163], v[196:199], 0
	v_mfma_f32_16x16x32_bf16 v[92:95], v[146:149], v[210:213], 0
	v_mfma_f32_16x16x32_bf16 v[88:91], v[160:163], v[210:213], 0
	v_mfma_f32_16x16x32_bf16 v[76:79], v[146:149], v[218:221], 0
	v_mfma_f32_16x16x32_bf16 v[72:75], v[160:163], v[218:221], 0
	v_mfma_f32_16x16x32_bf16 v[124:127], v[156:159], v[192:195], v[124:127]
	v_mfma_f32_16x16x32_bf16 v[120:123], v[164:167], v[192:195], v[120:123]
	v_mfma_f32_16x16x32_bf16 v[108:111], v[156:159], v[206:209], v[108:111]
	v_mfma_f32_16x16x32_bf16 v[104:107], v[164:167], v[206:209], v[104:107]
	v_mfma_f32_16x16x32_bf16 v[92:95], v[156:159], v[214:217], v[92:95]
	v_mfma_f32_16x16x32_bf16 v[88:91], v[164:167], v[214:217], v[88:91]
	v_mfma_f32_16x16x32_bf16 v[76:79], v[156:159], v[222:225], v[76:79]
	v_mfma_f32_16x16x32_bf16 v[72:75], v[164:167], v[222:225], v[72:75]
	s_setprio 0
	s_setprio 1
	v_mfma_f32_16x16x32_bf16 v[116:119], v[168:171], v[188:191], 0
	v_mfma_f32_16x16x32_bf16 v[112:115], v[180:183], v[188:191], 0
	v_mfma_f32_16x16x32_bf16 v[100:103], v[168:171], v[196:199], 0
	v_mfma_f32_16x16x32_bf16 v[96:99], v[180:183], v[196:199], 0
	v_mfma_f32_16x16x32_bf16 v[84:87], v[168:171], v[210:213], 0
	v_mfma_f32_16x16x32_bf16 v[80:83], v[180:183], v[210:213], 0
	v_mfma_f32_16x16x32_bf16 v[68:71], v[168:171], v[218:221], 0
	v_mfma_f32_16x16x32_bf16 v[64:67], v[180:183], v[218:221], 0
	v_mfma_f32_16x16x32_bf16 v[116:119], v[172:175], v[192:195], v[116:119]
	v_mfma_f32_16x16x32_bf16 v[112:115], v[184:187], v[192:195], v[112:115]
	v_mfma_f32_16x16x32_bf16 v[100:103], v[172:175], v[206:209], v[100:103]
	v_mfma_f32_16x16x32_bf16 v[96:99], v[184:187], v[206:209], v[96:99]
	v_mfma_f32_16x16x32_bf16 v[84:87], v[172:175], v[214:217], v[84:87]
	v_mfma_f32_16x16x32_bf16 v[80:83], v[184:187], v[214:217], v[80:83]
	v_mfma_f32_16x16x32_bf16 v[68:71], v[172:175], v[222:225], v[68:71]
	v_mfma_f32_16x16x32_bf16 v[64:67], v[184:187], v[222:225], v[64:67]
	s_setprio 0
	s_barrier
	s_add_i32 s82, s65, s34
	v_lshl_add_u64 v[200:201], s[54:55], 0, v[132:133]
	s_mov_b32 m0, s82
	ds_read_b128 v[188:191], v154 offset:16384
	ds_read_b128 v[192:195], v154 offset:17408
	ds_read_b128 v[196:199], v154 offset:18432
	ds_read_b128 v[206:209], v154 offset:19456
	ds_read_b128 v[210:213], v154 offset:20480
	ds_read_b128 v[214:217], v154 offset:21504
	ds_read_b128 v[218:221], v154 offset:22528
	ds_read_b128 v[222:225], v154 offset:23552
	global_load_lds_dwordx4 v[200:201], off
	s_add_i32 m0, s82, 0x2000
	s_add_u32 s82, s54, 0x40000
	v_lshl_add_u64 v[226:227], s[54:55], 0, v[128:129]
	s_addc_u32 s83, s55, 0
	s_add_i32 s84, s66, s34
	global_load_lds_dwordx4 v[226:227], off
	v_lshl_add_u64 v[228:229], s[82:83], 0, v[132:133]
	s_mov_b32 m0, s84
	global_load_lds_dwordx4 v[228:229], off
	v_lshl_add_u64 v[228:229], s[82:83], 0, v[128:129]
	s_add_i32 m0, s84, 0x2000
	s_nop 0
	global_load_lds_dwordx4 v[228:229], off
	s_waitcnt vmcnt(6)
	s_waitcnt lgkmcnt(0)
	s_barrier
; #define PG8_STAGE(bufoff, gbase, voff) do { _Pragma("unroll") for (int _i = 0; _i < 2; ++_i) \
;         __builtin_amdgcn_global_load_lds((const unsigned*)((const char*)(gbase) + (voff)[_i]), (PG8_LAS unsigned*)(lds + (bufoff) + ldsw + _i * 8192), 16, 0, 0); } while (0)
; #define PG8_LDA(dst, b, h) do { _Pragma("unroll") for (int m = 0; m < 4; ++m) _Pragma("unroll") for (int k = 0; k < 2; ++k) dst[m][k] = *(const PG8_LAS bf16x8*)(lds + PG8_SA(b, h) + aoff + m * 2048 + k * 1024); } while (0)
; #define PG8_LDB(dst, b, h) do { _Pragma("unroll") for (int n = 0; n < 2; ++n) _Pragma("unroll") for (int k = 0; k < 2; ++k) dst[n][k] = *(const PG8_LAS bf16x8*)(lds + PG8_SB(b, h) + boff + n * 2048 + k * 1024); } while (0)
; #define PG8_MMA(ai, bj, At, Bt) do { __builtin_amdgcn_s_setprio(1); _Pragma("unroll") for (int m = 0; m < 4; ++m) _Pragma("unroll") for (int n = 0; n < 2; ++n) _Pragma("unroll") for (int k = 0; k < 2; ++k) \
;         acc[ai][bj][m][n] = __builtin_amdgcn_mfma_f32_16x16x32_bf16(Bt[n][k], At[m][k], acc[ai][bj][m][n], 0, 0, 0); __builtin_amdgcn_s_setprio(0); } while (0)
; #define PG8_WAIT_V(n) asm volatile("s_waitcnt vmcnt(" #n ")" ::: "memory")
; #define PG8_WAIT_L(n) asm volatile("s_waitcnt lgkmcnt(" #n ")" ::: "memory")
; #define PG8_BAR __builtin_amdgcn_s_barrier()
; #define PG8_SCHED __builtin_amdgcn_sched_barrier(0)
; template <class Epi, class Sched, bool ALIGN_EPI = false, bool SP2 = false>
; __device__ __forceinline__ void gemm_phase(PG8_LAS unsigned char* lds, const Gemm g, const Sched& S, const Epi& E) {
;     ...
;             PG8_WAIT_V(8); PG8_WAIT_L(0); PG8_BAR; PG8_MMA(1, 0, At, B0); PG8_MMA(1, 1, At, B1); PG8_BAR; PG8_SCHED;
;             PG8_LDB(B0, 1, 0); PG8_LDB(B1, 1, 1); PG8_SCHED; PG8_LDA(At, 1, 0); PG8_STAGE(PG8_SA(0, 1), a2 + hstep, voffA);
;             PG8_WAIT_V(8); PG8_WAIT_L(0); PG8_BAR; PG8_MMA(0, 0, At, B0); PG8_MMA(0, 1, At, B1); PG8_BAR; PG8_SCHED;
	s_setprio 1
	s_waitcnt lgkmcnt(0)
	v_mfma_f32_16x16x32_bf16 v[60:63], v[146:149], v[188:191], 0
	v_mfma_f32_16x16x32_bf16 v[56:59], v[160:163], v[188:191], 0
	v_mfma_f32_16x16x32_bf16 v[44:47], v[146:149], v[196:199], 0
	v_mfma_f32_16x16x32_bf16 v[40:43], v[160:163], v[196:199], 0
	v_mfma_f32_16x16x32_bf16 v[28:31], v[146:149], v[210:213], 0
	v_mfma_f32_16x16x32_bf16 v[24:27], v[160:163], v[210:213], 0
	v_mfma_f32_16x16x32_bf16 v[12:15], v[146:149], v[218:221], 0
	v_mfma_f32_16x16x32_bf16 v[8:11], v[160:163], v[218:221], 0
	v_mfma_f32_16x16x32_bf16 v[60:63], v[156:159], v[192:195], v[60:63]
	v_mfma_f32_16x16x32_bf16 v[56:59], v[164:167], v[192:195], v[56:59]
	v_mfma_f32_16x16x32_bf16 v[44:47], v[156:159], v[206:209], v[44:47]
	v_mfma_f32_16x16x32_bf16 v[40:43], v[164:167], v[206:209], v[40:43]
	v_mfma_f32_16x16x32_bf16 v[28:31], v[156:159], v[214:217], v[28:31]
	v_mfma_f32_16x16x32_bf16 v[24:27], v[164:167], v[214:217], v[24:27]
	v_lshl_add_u64 v[228:229], s[56:57], 0, v[134:135]
	s_mov_b32 m0, s58
	s_nop 0
	global_load_lds_dwordx4 v[228:229], off
	v_mfma_f32_16x16x32_bf16 v[12:15], v[156:159], v[222:225], v[12:15]
	v_mfma_f32_16x16x32_bf16 v[8:11], v[164:167], v[222:225], v[8:11]
	s_setprio 0
	s_setprio 1
	v_mfma_f32_16x16x32_bf16 v[52:55], v[168:171], v[188:191], 0
	v_mfma_f32_16x16x32_bf16 v[48:51], v[180:183], v[188:191], 0
	v_mfma_f32_16x16x32_bf16 v[36:39], v[168:171], v[196:199], 0
	v_mfma_f32_16x16x32_bf16 v[32:35], v[180:183], v[196:199], 0
	v_mfma_f32_16x16x32_bf16 v[20:23], v[168:171], v[210:213], 0
	v_mfma_f32_16x16x32_bf16 v[16:19], v[180:183], v[210:213], 0
	v_mfma_f32_16x16x32_bf16 v[4:7], v[168:171], v[218:221], 0
	v_mfma_f32_16x16x32_bf16 v[0:3], v[180:183], v[218:221], 0
	v_mfma_f32_16x16x32_bf16 v[52:55], v[172:175], v[192:195], v[52:55]
	v_mfma_f32_16x16x32_bf16 v[48:51], v[184:187], v[192:195], v[48:51]
	v_mfma_f32_16x16x32_bf16 v[36:39], v[172:175], v[206:209], v[36:39]
	v_mfma_f32_16x16x32_bf16 v[32:35], v[184:187], v[206:209], v[32:35]
	v_mfma_f32_16x16x32_bf16 v[20:23], v[172:175], v[214:217], v[20:23]
	v_mfma_f32_16x16x32_bf16 v[16:19], v[184:187], v[214:217], v[16:19]
	v_lshl_add_u64 v[230:231], s[56:57], 0, v[130:131]
	s_mov_b32 m0, s59
	s_nop 0
	global_load_lds_dwordx4 v[230:231], off
	v_mfma_f32_16x16x32_bf16 v[4:7], v[172:175], v[222:225], v[4:7]
	v_mfma_f32_16x16x32_bf16 v[0:3], v[184:187], v[222:225], v[0:3]
	s_setprio 0
	s_barrier
	s_add_i32 s82, 0, 0x18000
	s_add_i32 s83, 0, 0x1c000
	v_add_u32_e32 v164, s82, v150
	v_add_u32_e32 v179, s83, v150
	ds_read_b128 v[146:149], v164
	ds_read_b128 v[156:159], v164 offset:1024
	ds_read_b128 v[160:163], v164 offset:2048
	ds_read_b128 v[164:167], v164 offset:3072
	ds_read_b128 v[168:171], v179
	ds_read_b128 v[172:175], v179 offset:1024
	ds_read_b128 v[180:183], v179 offset:2048
	ds_read_b128 v[184:187], v179 offset:3072
	s_add_u32 s56, s56, 0x40000
	s_addc_u32 s57, s57, 0
	s_mov_b32 m0, s60
	v_lshl_add_u64 v[232:233], s[56:57], 0, v[134:135]
	ds_read_b128 v[188:191], v154 offset:32768
	ds_read_b128 v[192:195], v154 offset:33792
	ds_read_b128 v[196:199], v154 offset:34816
	ds_read_b128 v[206:209], v154 offset:35840
	ds_read_b128 v[210:213], v154 offset:36864
	ds_read_b128 v[214:217], v154 offset:37888
	ds_read_b128 v[218:221], v154 offset:38912
	ds_read_b128 v[222:225], v154 offset:39936
	global_load_lds_dwordx4 v[232:233], off
	v_lshl_add_u64 v[232:233], s[56:57], 0, v[130:131]
	s_mov_b32 m0, s61
	s_nop 0
	global_load_lds_dwordx4 v[232:233], off
	s_waitcnt vmcnt(8)
	s_waitcnt lgkmcnt(0)
	s_barrier
	s_setprio 1
	s_waitcnt lgkmcnt(0)
	v_mfma_f32_16x16x32_bf16 v[124:127], v[146:149], v[188:191], v[124:127]
	v_mfma_f32_16x16x32_bf16 v[120:123], v[160:163], v[188:191], v[120:123]
	v_mfma_f32_16x16x32_bf16 v[108:111], v[146:149], v[196:199], v[108:111]
	v_mfma_f32_16x16x32_bf16 v[104:107], v[160:163], v[196:199], v[104:107]
	v_mfma_f32_16x16x32_bf16 v[92:95], v[146:149], v[210:213], v[92:95]
	v_mfma_f32_16x16x32_bf16 v[88:91], v[160:163], v[210:213], v[88:91]
	v_mfma_f32_16x16x32_bf16 v[76:79], v[146:149], v[218:221], v[76:79]
	v_mfma_f32_16x16x32_bf16 v[72:75], v[160:163], v[218:221], v[72:75]
	v_mfma_f32_16x16x32_bf16 v[124:127], v[156:159], v[192:195], v[124:127]
	v_mfma_f32_16x16x32_bf16 v[120:123], v[164:167], v[192:195], v[120:123]
	v_mfma_f32_16x16x32_bf16 v[108:111], v[156:159], v[206:209], v[108:111]
	v_mfma_f32_16x16x32_bf16 v[104:107], v[164:167], v[206:209], v[104:107]
	v_mfma_f32_16x16x32_bf16 v[92:95], v[156:159], v[214:217], v[92:95]
	v_mfma_f32_16x16x32_bf16 v[88:91], v[164:167], v[214:217], v[88:91]
	v_mfma_f32_16x16x32_bf16 v[76:79], v[156:159], v[222:225], v[76:79]
	v_mfma_f32_16x16x32_bf16 v[72:75], v[164:167], v[222:225], v[72:75]
	s_setprio 0
	s_setprio 1
	v_mfma_f32_16x16x32_bf16 v[116:119], v[168:171], v[188:191], v[116:119]
	v_mfma_f32_16x16x32_bf16 v[112:115], v[180:183], v[188:191], v[112:115]
	v_mfma_f32_16x16x32_bf16 v[100:103], v[168:171], v[196:199], v[100:103]
	v_mfma_f32_16x16x32_bf16 v[96:99], v[180:183], v[196:199], v[96:99]
	v_mfma_f32_16x16x32_bf16 v[84:87], v[168:171], v[210:213], v[84:87]
	v_mfma_f32_16x16x32_bf16 v[80:83], v[180:183], v[210:213], v[80:83]
	v_mfma_f32_16x16x32_bf16 v[68:71], v[168:171], v[218:221], v[68:71]
	v_mfma_f32_16x16x32_bf16 v[64:67], v[180:183], v[218:221], v[64:67]
	v_mfma_f32_16x16x32_bf16 v[116:119], v[172:175], v[192:195], v[116:119]
	v_mfma_f32_16x16x32_bf16 v[112:115], v[184:187], v[192:195], v[112:115]
	v_mfma_f32_16x16x32_bf16 v[100:103], v[172:175], v[206:209], v[100:103]
	v_mfma_f32_16x16x32_bf16 v[96:99], v[184:187], v[206:209], v[96:99]
	v_mfma_f32_16x16x32_bf16 v[84:87], v[172:175], v[214:217], v[84:87]
	v_mfma_f32_16x16x32_bf16 v[80:83], v[184:187], v[214:217], v[80:83]
	v_mfma_f32_16x16x32_bf16 v[68:71], v[172:175], v[222:225], v[68:71]
	v_mfma_f32_16x16x32_bf16 v[64:67], v[184:187], v[222:225], v[64:67]
	s_setprio 0
	s_barrier
; #define PG8_STAGE(bufoff, gbase, voff) do { _Pragma("unroll") for (int _i = 0; _i < 2; ++_i) \
;         __builtin_amdgcn_global_load_lds((const unsigned*)((const char*)(gbase) + (voff)[_i]), (PG8_LAS unsigned*)(lds + (bufoff) + ldsw + _i * 8192), 16, 0, 0); } while (0)
; #define PG8_LDA(dst, b, h) do { _Pragma("unroll") for (int m = 0; m < 4; ++m) _Pragma("unroll") for (int k = 0; k < 2; ++k) dst[m][k] = *(const PG8_LAS bf16x8*)(lds + PG8_SA(b, h) + aoff + m * 2048 + k * 1024); } while (0)
; #define PG8_LDB(dst, b, h) do { _Pragma("unroll") for (int n = 0; n < 2; ++n) _Pragma("unroll") for (int k = 0; k < 2; ++k) dst[n][k] = *(const PG8_LAS bf16x8*)(lds + PG8_SB(b, h) + boff + n * 2048 + k * 1024); } while (0)
; #define PG8_MMA(ai, bj, At, Bt) do { __builtin_amdgcn_s_setprio(1); _Pragma("unroll") for (int m = 0; m < 4; ++m) _Pragma("unroll") for (int n = 0; n < 2; ++n) _Pragma("unroll") for (int k = 0; k < 2; ++k) \
;         acc[ai][bj][m][n] = __builtin_amdgcn_mfma_f32_16x16x32_bf16(Bt[n][k], At[m][k], acc[ai][bj][m][n], 0, 0, 0); __builtin_amdgcn_s_setprio(0); } while (0)
; #define PG8_WAIT_V(n) asm volatile("s_waitcnt vmcnt(" #n ")" ::: "memory")
; #define PG8_WAIT_L(n) asm volatile("s_waitcnt lgkmcnt(" #n ")" ::: "memory")
; #define PG8_BAR __builtin_amdgcn_s_barrier()
; #define PG8_SCHED __builtin_amdgcn_sched_barrier(0)
; template <class Epi, class Sched, bool ALIGN_EPI = false, bool SP2 = false>
; __device__ __forceinline__ void gemm_phase(PG8_LAS unsigned char* lds, const Gemm g, const Sched& S, const Epi& E) {
;     ...
;             const bool last = (t == nt - 2);
;             const char* a1 = cA + (size_t)(t + 1) * kstep;
;             const char* a2 = last ? nA : cA + (size_t)(t + 2) * kstep; const char* b2 = last ? nB : cB + (size_t)(t + 2) * kstep;
;             const char* a3 = a2 + kstep; const char* b3 = b2 + kstep;
;             if (last && has_next) S.a_ready(nxt);
;             if constexpr (SP2) {
;             PG8_LDB(B0, 0, 0); PG8_LDB(B1, 0, 1); PG8_SCHED; PG8_LDA(At, 0, 0); PG8_STAGE(PG8_SA(1, 1), a1 + hstep, voffA);
;     ...
;             PG8_LDA(At, 1, 1); PG8_STAGE(PG8_SB(1, 0), b3, voffB); PG8_STAGE(PG8_SB(1, 1), b3 + hstep, voffB); PG8_STAGE(PG8_SA(1, 0), a3, voffA);
;             PG8_WAIT_V(8); PG8_WAIT_L(0); PG8_BAR; PG8_MMA(1, 0, At, B0); PG8_MMA(1, 1, At, B1); PG8_BAR; PG8_SCHED;
	s_add_i32 s56, s82, s34
	v_lshl_add_u64 v[200:201], v[200:201], 0, s[26:27]
	s_mov_b32 m0, s56
	ds_read_b128 v[188:191], v154 offset:49152
	ds_read_b128 v[192:195], v154 offset:50176
	ds_read_b128 v[196:199], v154 offset:51200
	ds_read_b128 v[206:209], v154 offset:52224
	ds_read_b128 v[210:213], v154 offset:53248
	ds_read_b128 v[214:217], v154 offset:54272
	ds_read_b128 v[218:221], v154 offset:55296
	ds_read_b128 v[222:225], v154 offset:56320
	global_load_lds_dwordx4 v[200:201], off
	s_add_i32 m0, s56, 0x2000
	s_add_u32 s54, s54, 0x40080
	v_lshl_add_u64 v[200:201], v[226:227], 0, s[26:27]
	s_addc_u32 s55, s55, 0
	s_add_i32 s56, s83, s34
	global_load_lds_dwordx4 v[200:201], off
	v_lshl_add_u64 v[200:201], s[54:55], 0, v[132:133]
	s_mov_b32 m0, s56
	s_nop 0
	global_load_lds_dwordx4 v[200:201], off
	v_lshl_add_u64 v[200:201], s[54:55], 0, v[128:129]
	s_add_i32 m0, s56, 0x2000
	s_nop 0
	global_load_lds_dwordx4 v[200:201], off
	s_waitcnt vmcnt(6)
	s_waitcnt lgkmcnt(0)
	s_barrier
	s_setprio 1
	s_waitcnt lgkmcnt(0)
	v_mfma_f32_16x16x32_bf16 v[60:63], v[146:149], v[188:191], v[60:63]
	v_mfma_f32_16x16x32_bf16 v[56:59], v[160:163], v[188:191], v[56:59]
	v_mfma_f32_16x16x32_bf16 v[44:47], v[146:149], v[196:199], v[44:47]
	v_mfma_f32_16x16x32_bf16 v[40:43], v[160:163], v[196:199], v[40:43]
	v_mfma_f32_16x16x32_bf16 v[28:31], v[146:149], v[210:213], v[28:31]
	v_mfma_f32_16x16x32_bf16 v[24:27], v[160:163], v[210:213], v[24:27]
	v_mfma_f32_16x16x32_bf16 v[12:15], v[146:149], v[218:221], v[12:15]
	v_mfma_f32_16x16x32_bf16 v[8:11], v[160:163], v[218:221], v[8:11]
	v_mfma_f32_16x16x32_bf16 v[60:63], v[156:159], v[192:195], v[60:63]
	v_mfma_f32_16x16x32_bf16 v[56:59], v[164:167], v[192:195], v[56:59]
	v_mfma_f32_16x16x32_bf16 v[44:47], v[156:159], v[206:209], v[44:47]
	v_mfma_f32_16x16x32_bf16 v[40:43], v[164:167], v[206:209], v[40:43]
	v_mfma_f32_16x16x32_bf16 v[28:31], v[156:159], v[214:217], v[28:31]
	v_mfma_f32_16x16x32_bf16 v[24:27], v[164:167], v[214:217], v[24:27]
	v_lshl_add_u64 v[200:201], v[228:229], 0, s[26:27]
	s_mov_b32 m0, s63
	s_nop 0
	global_load_lds_dwordx4 v[200:201], off
	v_mfma_f32_16x16x32_bf16 v[12:15], v[156:159], v[222:225], v[12:15]
	v_mfma_f32_16x16x32_bf16 v[8:11], v[164:167], v[222:225], v[8:11]
	s_setprio 0
	s_setprio 1
	v_mfma_f32_16x16x32_bf16 v[52:55], v[168:171], v[188:191], v[52:55]
	v_mfma_f32_16x16x32_bf16 v[48:51], v[180:183], v[188:191], v[48:51]
	v_mfma_f32_16x16x32_bf16 v[36:39], v[168:171], v[196:199], v[36:39]
	v_mfma_f32_16x16x32_bf16 v[32:35], v[180:183], v[196:199], v[32:35]
	v_mfma_f32_16x16x32_bf16 v[20:23], v[168:171], v[210:213], v[20:23]
	v_mfma_f32_16x16x32_bf16 v[16:19], v[180:183], v[210:213], v[16:19]
	v_mfma_f32_16x16x32_bf16 v[4:7], v[168:171], v[218:221], v[4:7]
	v_mfma_f32_16x16x32_bf16 v[0:3], v[180:183], v[218:221], v[0:3]
	v_mfma_f32_16x16x32_bf16 v[52:55], v[172:175], v[192:195], v[52:55]
	v_mfma_f32_16x16x32_bf16 v[48:51], v[184:187], v[192:195], v[48:51]
	v_mfma_f32_16x16x32_bf16 v[36:39], v[172:175], v[206:209], v[36:39]
	v_mfma_f32_16x16x32_bf16 v[32:35], v[184:187], v[206:209], v[32:35]
	v_mfma_f32_16x16x32_bf16 v[20:23], v[172:175], v[214:217], v[20:23]
	v_mfma_f32_16x16x32_bf16 v[16:19], v[184:187], v[214:217], v[16:19]
	v_lshl_add_u64 v[200:201], v[230:231], 0, s[26:27]
	s_mov_b32 m0, s64
	s_nop 0
	global_load_lds_dwordx4 v[200:201], off
	v_mfma_f32_16x16x32_bf16 v[4:7], v[172:175], v[222:225], v[4:7]
	v_mfma_f32_16x16x32_bf16 v[0:3], v[184:187], v[222:225], v[0:3]
	s_setprio 0
	s_barrier
	s_add_i32 s81, s81, 2
	s_add_u32 s52, s52, 0x100
	s_addc_u32 s53, s53, 0
	s_add_u32 s79, s79, 0x100
	s_addc_u32 s80, s80, 0
.LBB0_1681:
	ds_read_b128 v[146:149], v152
	ds_read_b128 v[156:159], v152 offset:1024
	ds_read_b128 v[160:163], v152 offset:2048
	ds_read_b128 v[164:167], v152 offset:3072
	ds_read_b128 v[168:171], v153
	ds_read_b128 v[172:175], v153 offset:1024
	ds_read_b128 v[180:183], v153 offset:2048
	ds_read_b128 v[184:187], v153 offset:3072
	s_add_u32 s54, s52, 0xfffc0080
	s_addc_u32 s55, s53, -1
	s_cmp_eq_u32 s81, 12
	s_cselect_b32 s57, s47, s55
	s_cselect_b32 s56, s77, s54
	s_cselect_b32 s55, s45, s80
	s_cselect_b32 s54, s78, s79
	v_lshl_add_u64 v[200:201], s[52:53], 0, v[136:137]
	s_add_i32 m0, s58, 0xc000
	ds_read_b128 v[188:191], v154
	ds_read_b128 v[192:195], v154 offset:1024
	ds_read_b128 v[196:199], v154 offset:2048
	ds_read_b128 v[206:209], v154 offset:3072
	ds_read_b128 v[210:213], v154 offset:4096
	ds_read_b128 v[214:217], v154 offset:5120
	ds_read_b128 v[218:221], v154 offset:6144
	ds_read_b128 v[222:225], v154 offset:7168
	global_load_lds_dwordx4 v[200:201], off
	v_lshl_add_u64 v[200:201], s[52:53], 0, v[138:139]
	s_add_i32 m0, s58, 0xe000
	s_nop 0
	global_load_lds_dwordx4 v[200:201], off
	s_waitcnt vmcnt(8)
	s_waitcnt lgkmcnt(0)
	s_barrier
; #define PG8_STAGE(bufoff, gbase, voff) do { _Pragma("unroll") for (int _i = 0; _i < 2; ++_i) \
;         __builtin_amdgcn_global_load_lds((const unsigned*)((const char*)(gbase) + (voff)[_i]), (PG8_LAS unsigned*)(lds + (bufoff) + ldsw + _i * 8192), 16, 0, 0); } while (0)
; #define PG8_LDA(dst, b, h) do { _Pragma("unroll") for (int m = 0; m < 4; ++m) _Pragma("unroll") for (int k = 0; k < 2; ++k) dst[m][k] = *(const PG8_LAS bf16x8*)(lds + PG8_SA(b, h) + aoff + m * 2048 + k * 1024); } while (0)
; #define PG8_MMA(ai, bj, At, Bt) do { __builtin_amdgcn_s_setprio(1); _Pragma("unroll") for (int m = 0; m < 4; ++m) _Pragma("unroll") for (int n = 0; n < 2; ++n) _Pragma("unroll") for (int k = 0; k < 2; ++k) \
;         acc[ai][bj][m][n] = __builtin_amdgcn_mfma_f32_16x16x32_bf16(Bt[n][k], At[m][k], acc[ai][bj][m][n], 0, 0, 0); __builtin_amdgcn_s_setprio(0); } while (0)
; #define PG8_WAIT_V(n) asm volatile("s_waitcnt vmcnt(" #n ")" ::: "memory")
; #define PG8_WAIT_L(n) asm volatile("s_waitcnt lgkmcnt(" #n ")" ::: "memory")
; #define PG8_BAR __builtin_amdgcn_s_barrier()
; #define PG8_SCHED __builtin_amdgcn_sched_barrier(0)
; template <class Epi, class Sched, bool ALIGN_EPI = false, bool SP2 = false>
; __device__ __forceinline__ void gemm_phase(PG8_LAS unsigned char* lds, const Gemm g, const Sched& S, const Epi& E) {
;     ...
;             PG8_WAIT_V(8); PG8_WAIT_L(0); PG8_BAR; PG8_MMA(0, 0, At, B0); PG8_MMA(0, 1, At, B1); PG8_BAR; PG8_SCHED;
;             PG8_LDA(At, 0, 1); PG8_STAGE(PG8_SB(0, 0), b2, voffB); PG8_STAGE(PG8_SB(0, 1), b2 + hstep, voffB); PG8_STAGE(PG8_SA(0, 0), a2, voffA);
;             PG8_WAIT_V(8); PG8_WAIT_L(0); PG8_BAR; PG8_MMA(1, 0, At, B0); PG8_MMA(1, 1, At, B1); PG8_BAR; PG8_SCHED;
	s_setprio 1
	s_waitcnt lgkmcnt(0)
	v_mfma_f32_16x16x32_bf16 v[124:127], v[146:149], v[188:191], v[124:127]
	v_mfma_f32_16x16x32_bf16 v[120:123], v[160:163], v[188:191], v[120:123]
	v_mfma_f32_16x16x32_bf16 v[108:111], v[146:149], v[196:199], v[108:111]
	v_mfma_f32_16x16x32_bf16 v[104:107], v[160:163], v[196:199], v[104:107]
	v_mfma_f32_16x16x32_bf16 v[92:95], v[146:149], v[210:213], v[92:95]
	v_mfma_f32_16x16x32_bf16 v[88:91], v[160:163], v[210:213], v[88:91]
	v_mfma_f32_16x16x32_bf16 v[76:79], v[146:149], v[218:221], v[76:79]
	v_mfma_f32_16x16x32_bf16 v[72:75], v[160:163], v[218:221], v[72:75]
	v_mfma_f32_16x16x32_bf16 v[124:127], v[156:159], v[192:195], v[124:127]
	v_mfma_f32_16x16x32_bf16 v[120:123], v[164:167], v[192:195], v[120:123]
	v_mfma_f32_16x16x32_bf16 v[108:111], v[156:159], v[206:209], v[108:111]
	v_mfma_f32_16x16x32_bf16 v[104:107], v[164:167], v[206:209], v[104:107]
	v_mfma_f32_16x16x32_bf16 v[92:95], v[156:159], v[214:217], v[92:95]
	v_mfma_f32_16x16x32_bf16 v[88:91], v[164:167], v[214:217], v[88:91]
	v_mfma_f32_16x16x32_bf16 v[76:79], v[156:159], v[222:225], v[76:79]
	v_mfma_f32_16x16x32_bf16 v[72:75], v[164:167], v[222:225], v[72:75]
	s_setprio 0
	s_setprio 1
	v_mfma_f32_16x16x32_bf16 v[116:119], v[168:171], v[188:191], v[116:119]
	v_mfma_f32_16x16x32_bf16 v[112:115], v[180:183], v[188:191], v[112:115]
	v_mfma_f32_16x16x32_bf16 v[100:103], v[168:171], v[196:199], v[100:103]
	v_mfma_f32_16x16x32_bf16 v[96:99], v[180:183], v[196:199], v[96:99]
	v_mfma_f32_16x16x32_bf16 v[84:87], v[168:171], v[210:213], v[84:87]
	v_mfma_f32_16x16x32_bf16 v[80:83], v[180:183], v[210:213], v[80:83]
	v_mfma_f32_16x16x32_bf16 v[68:71], v[168:171], v[218:221], v[68:71]
	v_mfma_f32_16x16x32_bf16 v[64:67], v[180:183], v[218:221], v[64:67]
	v_mfma_f32_16x16x32_bf16 v[116:119], v[172:175], v[192:195], v[116:119]
	v_mfma_f32_16x16x32_bf16 v[112:115], v[184:187], v[192:195], v[112:115]
	v_mfma_f32_16x16x32_bf16 v[100:103], v[172:175], v[206:209], v[100:103]
	v_mfma_f32_16x16x32_bf16 v[96:99], v[184:187], v[206:209], v[96:99]
	v_mfma_f32_16x16x32_bf16 v[84:87], v[172:175], v[214:217], v[84:87]
	v_mfma_f32_16x16x32_bf16 v[80:83], v[184:187], v[214:217], v[80:83]
	v_mfma_f32_16x16x32_bf16 v[68:71], v[172:175], v[222:225], v[68:71]
	v_mfma_f32_16x16x32_bf16 v[64:67], v[184:187], v[222:225], v[64:67]
	s_setprio 0
	s_barrier
	s_add_i32 s82, s65, s34
	v_lshl_add_u64 v[200:201], s[54:55], 0, v[132:133]
	s_mov_b32 m0, s82
	ds_read_b128 v[188:191], v154 offset:16384
	ds_read_b128 v[192:195], v154 offset:17408
	ds_read_b128 v[196:199], v154 offset:18432
	ds_read_b128 v[206:209], v154 offset:19456
	ds_read_b128 v[210:213], v154 offset:20480
	ds_read_b128 v[214:217], v154 offset:21504
	ds_read_b128 v[218:221], v154 offset:22528
	ds_read_b128 v[222:225], v154 offset:23552
	global_load_lds_dwordx4 v[200:201], off
	s_add_i32 m0, s82, 0x2000
	s_add_u32 s82, s54, 0x40000
	v_lshl_add_u64 v[226:227], s[54:55], 0, v[128:129]
	s_addc_u32 s83, s55, 0
	s_add_i32 s84, s66, s34
	global_load_lds_dwordx4 v[226:227], off
	v_lshl_add_u64 v[228:229], s[82:83], 0, v[132:133]
	s_mov_b32 m0, s84
	global_load_lds_dwordx4 v[228:229], off
	v_lshl_add_u64 v[228:229], s[82:83], 0, v[128:129]
	s_add_i32 m0, s84, 0x2000
	s_nop 0
	global_load_lds_dwordx4 v[228:229], off
	s_waitcnt vmcnt(6)
	s_waitcnt lgkmcnt(0)
	s_barrier
	s_setprio 1
	s_waitcnt lgkmcnt(0)
	v_mfma_f32_16x16x32_bf16 v[60:63], v[146:149], v[188:191], v[60:63]
	v_mfma_f32_16x16x32_bf16 v[56:59], v[160:163], v[188:191], v[56:59]
	v_mfma_f32_16x16x32_bf16 v[44:47], v[146:149], v[196:199], v[44:47]
	v_mfma_f32_16x16x32_bf16 v[40:43], v[160:163], v[196:199], v[40:43]
	v_mfma_f32_16x16x32_bf16 v[28:31], v[146:149], v[210:213], v[28:31]
	v_mfma_f32_16x16x32_bf16 v[24:27], v[160:163], v[210:213], v[24:27]
	v_mfma_f32_16x16x32_bf16 v[12:15], v[146:149], v[218:221], v[12:15]
	v_mfma_f32_16x16x32_bf16 v[8:11], v[160:163], v[218:221], v[8:11]
	v_mfma_f32_16x16x32_bf16 v[60:63], v[156:159], v[192:195], v[60:63]
	v_mfma_f32_16x16x32_bf16 v[56:59], v[164:167], v[192:195], v[56:59]
	v_mfma_f32_16x16x32_bf16 v[44:47], v[156:159], v[206:209], v[44:47]
	v_mfma_f32_16x16x32_bf16 v[40:43], v[164:167], v[206:209], v[40:43]
	v_mfma_f32_16x16x32_bf16 v[28:31], v[156:159], v[214:217], v[28:31]
	v_mfma_f32_16x16x32_bf16 v[24:27], v[164:167], v[214:217], v[24:27]
	v_lshl_add_u64 v[228:229], s[56:57], 0, v[134:135]
	s_mov_b32 m0, s58
	s_nop 0
	global_load_lds_dwordx4 v[228:229], off
	v_mfma_f32_16x16x32_bf16 v[12:15], v[156:159], v[222:225], v[12:15]
	v_mfma_f32_16x16x32_bf16 v[8:11], v[164:167], v[222:225], v[8:11]
	s_setprio 0
	s_setprio 1
	v_mfma_f32_16x16x32_bf16 v[52:55], v[168:171], v[188:191], v[52:55]
	v_mfma_f32_16x16x32_bf16 v[48:51], v[180:183], v[188:191], v[48:51]
	v_mfma_f32_16x16x32_bf16 v[36:39], v[168:171], v[196:199], v[36:39]
	v_mfma_f32_16x16x32_bf16 v[32:35], v[180:183], v[196:199], v[32:35]
	v_mfma_f32_16x16x32_bf16 v[20:23], v[168:171], v[210:213], v[20:23]
	v_mfma_f32_16x16x32_bf16 v[16:19], v[180:183], v[210:213], v[16:19]
	v_mfma_f32_16x16x32_bf16 v[4:7], v[168:171], v[218:221], v[4:7]
	v_mfma_f32_16x16x32_bf16 v[0:3], v[180:183], v[218:221], v[0:3]
	v_mfma_f32_16x16x32_bf16 v[52:55], v[172:175], v[192:195], v[52:55]
	v_mfma_f32_16x16x32_bf16 v[48:51], v[184:187], v[192:195], v[48:51]
	v_mfma_f32_16x16x32_bf16 v[36:39], v[172:175], v[206:209], v[36:39]
	v_mfma_f32_16x16x32_bf16 v[32:35], v[184:187], v[206:209], v[32:35]
	v_mfma_f32_16x16x32_bf16 v[20:23], v[172:175], v[214:217], v[20:23]
	v_mfma_f32_16x16x32_bf16 v[16:19], v[184:187], v[214:217], v[16:19]
	v_lshl_add_u64 v[230:231], s[56:57], 0, v[130:131]
	s_mov_b32 m0, s59
	s_nop 0
	global_load_lds_dwordx4 v[230:231], off
	v_mfma_f32_16x16x32_bf16 v[4:7], v[172:175], v[222:225], v[4:7]
	v_mfma_f32_16x16x32_bf16 v[0:3], v[184:187], v[222:225], v[0:3]
	s_setprio 0
	s_barrier
; #define PG8_STAGE(bufoff, gbase, voff) do { _Pragma("unroll") for (int _i = 0; _i < 2; ++_i) \
;         __builtin_amdgcn_global_load_lds((const unsigned*)((const char*)(gbase) + (voff)[_i]), (PG8_LAS unsigned*)(lds + (bufoff) + ldsw + _i * 8192), 16, 0, 0); } while (0)
; #define PG8_LDA(dst, b, h) do { _Pragma("unroll") for (int m = 0; m < 4; ++m) _Pragma("unroll") for (int k = 0; k < 2; ++k) dst[m][k] = *(const PG8_LAS bf16x8*)(lds + PG8_SA(b, h) + aoff + m * 2048 + k * 1024); } while (0)
; #define PG8_LDB(dst, b, h) do { _Pragma("unroll") for (int n = 0; n < 2; ++n) _Pragma("unroll") for (int k = 0; k < 2; ++k) dst[n][k] = *(const PG8_LAS bf16x8*)(lds + PG8_SB(b, h) + boff + n * 2048 + k * 1024); } while (0)
; #define PG8_MMA(ai, bj, At, Bt) do { __builtin_amdgcn_s_setprio(1); _Pragma("unroll") for (int m = 0; m < 4; ++m) _Pragma("unroll") for (int n = 0; n < 2; ++n) _Pragma("unroll") for (int k = 0; k < 2; ++k) \
;         acc[ai][bj][m][n] = __builtin_amdgcn_mfma_f32_16x16x32_bf16(Bt[n][k], At[m][k], acc[ai][bj][m][n], 0, 0, 0); __builtin_amdgcn_s_setprio(0); } while (0)
; #define PG8_WAIT_V(n) asm volatile("s_waitcnt vmcnt(" #n ")" ::: "memory")
; #define PG8_WAIT_L(n) asm volatile("s_waitcnt lgkmcnt(" #n ")" ::: "memory")
; #define PG8_BAR __builtin_amdgcn_s_barrier()
; #define PG8_SCHED __builtin_amdgcn_sched_barrier(0)
; template <class Epi, class Sched, bool ALIGN_EPI = false, bool SP2 = false>
; __device__ __forceinline__ void gemm_phase(PG8_LAS unsigned char* lds, const Gemm g, const Sched& S, const Epi& E) {
;     ...
;             PG8_LDB(B0, 1, 0); PG8_LDB(B1, 1, 1); PG8_SCHED; PG8_LDA(At, 1, 0); PG8_STAGE(PG8_SA(0, 1), a2 + hstep, voffA);
;             PG8_WAIT_V(8); PG8_WAIT_L(0); PG8_BAR; PG8_MMA(0, 0, At, B0); PG8_MMA(0, 1, At, B1); PG8_BAR; PG8_SCHED;
	s_add_i32 s82, 0, 0x18000
	s_add_i32 s83, 0, 0x1c000
	v_add_u32_e32 v164, s82, v150
	v_add_u32_e32 v179, s83, v150
	ds_read_b128 v[146:149], v164
	ds_read_b128 v[156:159], v164 offset:1024
	ds_read_b128 v[160:163], v164 offset:2048
	ds_read_b128 v[164:167], v164 offset:3072
	ds_read_b128 v[168:171], v179
	ds_read_b128 v[172:175], v179 offset:1024
	ds_read_b128 v[180:183], v179 offset:2048
	ds_read_b128 v[184:187], v179 offset:3072
	s_add_u32 s56, s56, 0x40000
	s_addc_u32 s57, s57, 0
	s_mov_b32 m0, s60
	v_lshl_add_u64 v[232:233], s[56:57], 0, v[134:135]
	ds_read_b128 v[188:191], v154 offset:32768
	ds_read_b128 v[192:195], v154 offset:33792
	ds_read_b128 v[196:199], v154 offset:34816
	ds_read_b128 v[206:209], v154 offset:35840
	ds_read_b128 v[210:213], v154 offset:36864
	ds_read_b128 v[214:217], v154 offset:37888
	ds_read_b128 v[218:221], v154 offset:38912
	ds_read_b128 v[222:225], v154 offset:39936
	global_load_lds_dwordx4 v[232:233], off
	v_lshl_add_u64 v[232:233], s[56:57], 0, v[130:131]
	s_mov_b32 m0, s61
	s_nop 0
	global_load_lds_dwordx4 v[232:233], off
	s_waitcnt vmcnt(8)
	s_waitcnt lgkmcnt(0)
	s_barrier
	s_setprio 1
	s_waitcnt lgkmcnt(0)
	v_mfma_f32_16x16x32_bf16 v[124:127], v[146:149], v[188:191], v[124:127]
	v_mfma_f32_16x16x32_bf16 v[120:123], v[160:163], v[188:191], v[120:123]
	v_mfma_f32_16x16x32_bf16 v[108:111], v[146:149], v[196:199], v[108:111]
	v_mfma_f32_16x16x32_bf16 v[104:107], v[160:163], v[196:199], v[104:107]
	v_mfma_f32_16x16x32_bf16 v[92:95], v[146:149], v[210:213], v[92:95]
	v_mfma_f32_16x16x32_bf16 v[88:91], v[160:163], v[210:213], v[88:91]
	v_mfma_f32_16x16x32_bf16 v[76:79], v[146:149], v[218:221], v[76:79]
	v_mfma_f32_16x16x32_bf16 v[72:75], v[160:163], v[218:221], v[72:75]
	v_mfma_f32_16x16x32_bf16 v[124:127], v[156:159], v[192:195], v[124:127]
	v_mfma_f32_16x16x32_bf16 v[120:123], v[164:167], v[192:195], v[120:123]
	v_mfma_f32_16x16x32_bf16 v[108:111], v[156:159], v[206:209], v[108:111]
	v_mfma_f32_16x16x32_bf16 v[104:107], v[164:167], v[206:209], v[104:107]
	v_mfma_f32_16x16x32_bf16 v[92:95], v[156:159], v[214:217], v[92:95]
	v_mfma_f32_16x16x32_bf16 v[88:91], v[164:167], v[214:217], v[88:91]
	v_mfma_f32_16x16x32_bf16 v[76:79], v[156:159], v[222:225], v[76:79]
	v_mfma_f32_16x16x32_bf16 v[72:75], v[164:167], v[222:225], v[72:75]
	s_setprio 0
	s_setprio 1
	v_mfma_f32_16x16x32_bf16 v[116:119], v[168:171], v[188:191], v[116:119]
	v_mfma_f32_16x16x32_bf16 v[112:115], v[180:183], v[188:191], v[112:115]
	v_mfma_f32_16x16x32_bf16 v[100:103], v[168:171], v[196:199], v[100:103]
	v_mfma_f32_16x16x32_bf16 v[96:99], v[180:183], v[196:199], v[96:99]
	v_mfma_f32_16x16x32_bf16 v[84:87], v[168:171], v[210:213], v[84:87]
	v_mfma_f32_16x16x32_bf16 v[80:83], v[180:183], v[210:213], v[80:83]
	v_mfma_f32_16x16x32_bf16 v[68:71], v[168:171], v[218:221], v[68:71]
	v_mfma_f32_16x16x32_bf16 v[64:67], v[180:183], v[218:221], v[64:67]
	v_mfma_f32_16x16x32_bf16 v[116:119], v[172:175], v[192:195], v[116:119]
	v_mfma_f32_16x16x32_bf16 v[112:115], v[184:187], v[192:195], v[112:115]
	v_mfma_f32_16x16x32_bf16 v[100:103], v[172:175], v[206:209], v[100:103]
	v_mfma_f32_16x16x32_bf16 v[96:99], v[184:187], v[206:209], v[96:99]
	v_mfma_f32_16x16x32_bf16 v[84:87], v[172:175], v[214:217], v[84:87]
	v_mfma_f32_16x16x32_bf16 v[80:83], v[184:187], v[214:217], v[80:83]
	v_mfma_f32_16x16x32_bf16 v[68:71], v[172:175], v[222:225], v[68:71]
	v_mfma_f32_16x16x32_bf16 v[64:67], v[184:187], v[222:225], v[64:67]
	s_setprio 0
	s_barrier
; #define PG8_STAGE(bufoff, gbase, voff) do { _Pragma("unroll") for (int _i = 0; _i < 2; ++_i) \
;         __builtin_amdgcn_global_load_lds((const unsigned*)((const char*)(gbase) + (voff)[_i]), (PG8_LAS unsigned*)(lds + (bufoff) + ldsw + _i * 8192), 16, 0, 0); } while (0)
; #define PG8_LDA(dst, b, h) do { _Pragma("unroll") for (int m = 0; m < 4; ++m) _Pragma("unroll") for (int k = 0; k < 2; ++k) dst[m][k] = *(const PG8_LAS bf16x8*)(lds + PG8_SA(b, h) + aoff + m * 2048 + k * 1024); } while (0)
; #define PG8_MMA(ai, bj, At, Bt) do { __builtin_amdgcn_s_setprio(1); _Pragma("unroll") for (int m = 0; m < 4; ++m) _Pragma("unroll") for (int n = 0; n < 2; ++n) _Pragma("unroll") for (int k = 0; k < 2; ++k) \
;         acc[ai][bj][m][n] = __builtin_amdgcn_mfma_f32_16x16x32_bf16(Bt[n][k], At[m][k], acc[ai][bj][m][n], 0, 0, 0); __builtin_amdgcn_s_setprio(0); } while (0)
; #define PG8_WAIT_V(n) asm volatile("s_waitcnt vmcnt(" #n ")" ::: "memory")
; #define PG8_WAIT_L(n) asm volatile("s_waitcnt lgkmcnt(" #n ")" ::: "memory")
; #define PG8_BAR __builtin_amdgcn_s_barrier()
; #define PG8_SCHED __builtin_amdgcn_sched_barrier(0)
; template <class Epi, class Sched, bool ALIGN_EPI = false, bool SP2 = false>
; __device__ __forceinline__ void gemm_phase(PG8_LAS unsigned char* lds, const Gemm g, const Sched& S, const Epi& E) {
;     ...
;             PG8_LDA(At, 1, 1); PG8_STAGE(PG8_SB(1, 0), b3, voffB); PG8_STAGE(PG8_SB(1, 1), b3 + hstep, voffB); PG8_STAGE(PG8_SA(1, 0), a3, voffA);
;             PG8_WAIT_V(8); PG8_WAIT_L(0); PG8_BAR; PG8_MMA(1, 0, At, B0); PG8_MMA(1, 1, At, B1); PG8_BAR; PG8_SCHED;
;     ...
;         if constexpr (ALIGN_EPI) { if (wr == 0) PG8_BAR; }
	s_add_i32 s56, s82, s34
	v_lshl_add_u64 v[200:201], v[200:201], 0, s[26:27]
	s_mov_b32 m0, s56
	ds_read_b128 v[188:191], v154 offset:49152
	ds_read_b128 v[192:195], v154 offset:50176
	ds_read_b128 v[196:199], v154 offset:51200
	ds_read_b128 v[206:209], v154 offset:52224
	ds_read_b128 v[210:213], v154 offset:53248
	ds_read_b128 v[214:217], v154 offset:54272
	ds_read_b128 v[218:221], v154 offset:55296
	ds_read_b128 v[222:225], v154 offset:56320
	global_load_lds_dwordx4 v[200:201], off
	s_add_i32 m0, s56, 0x2000
	s_add_u32 s54, s54, 0x40080
	v_lshl_add_u64 v[200:201], v[226:227], 0, s[26:27]
	s_addc_u32 s55, s55, 0
	s_add_i32 s56, s83, s34
	global_load_lds_dwordx4 v[200:201], off
	v_lshl_add_u64 v[200:201], s[54:55], 0, v[132:133]
	s_mov_b32 m0, s56
	s_nop 0
	global_load_lds_dwordx4 v[200:201], off
	v_lshl_add_u64 v[200:201], s[54:55], 0, v[128:129]
	s_add_i32 m0, s56, 0x2000
	s_nop 0
	global_load_lds_dwordx4 v[200:201], off
	s_waitcnt vmcnt(6)
	s_waitcnt lgkmcnt(0)
	s_barrier
	s_setprio 1
	s_waitcnt lgkmcnt(0)
	v_mfma_f32_16x16x32_bf16 v[60:63], v[146:149], v[188:191], v[60:63]
	v_mfma_f32_16x16x32_bf16 v[56:59], v[160:163], v[188:191], v[56:59]
	v_mfma_f32_16x16x32_bf16 v[44:47], v[146:149], v[196:199], v[44:47]
	v_mfma_f32_16x16x32_bf16 v[40:43], v[160:163], v[196:199], v[40:43]
	v_mfma_f32_16x16x32_bf16 v[28:31], v[146:149], v[210:213], v[28:31]
	v_mfma_f32_16x16x32_bf16 v[24:27], v[160:163], v[210:213], v[24:27]
	v_mfma_f32_16x16x32_bf16 v[12:15], v[146:149], v[218:221], v[12:15]
	v_mfma_f32_16x16x32_bf16 v[8:11], v[160:163], v[218:221], v[8:11]
	v_mfma_f32_16x16x32_bf16 v[60:63], v[156:159], v[192:195], v[60:63]
	v_mfma_f32_16x16x32_bf16 v[56:59], v[164:167], v[192:195], v[56:59]
	v_mfma_f32_16x16x32_bf16 v[44:47], v[156:159], v[206:209], v[44:47]
	v_mfma_f32_16x16x32_bf16 v[40:43], v[164:167], v[206:209], v[40:43]
	v_mfma_f32_16x16x32_bf16 v[28:31], v[156:159], v[214:217], v[28:31]
	v_mfma_f32_16x16x32_bf16 v[24:27], v[164:167], v[214:217], v[24:27]
	v_lshl_add_u64 v[200:201], v[228:229], 0, s[26:27]
	s_mov_b32 m0, s63
	s_nop 0
	global_load_lds_dwordx4 v[200:201], off
	v_mfma_f32_16x16x32_bf16 v[12:15], v[156:159], v[222:225], v[12:15]
	v_mfma_f32_16x16x32_bf16 v[8:11], v[164:167], v[222:225], v[8:11]
	s_setprio 0
	s_setprio 1
	v_mfma_f32_16x16x32_bf16 v[52:55], v[168:171], v[188:191], v[52:55]
	v_mfma_f32_16x16x32_bf16 v[48:51], v[180:183], v[188:191], v[48:51]
	v_mfma_f32_16x16x32_bf16 v[36:39], v[168:171], v[196:199], v[36:39]
	v_mfma_f32_16x16x32_bf16 v[32:35], v[180:183], v[196:199], v[32:35]
	v_mfma_f32_16x16x32_bf16 v[20:23], v[168:171], v[210:213], v[20:23]
	v_mfma_f32_16x16x32_bf16 v[16:19], v[180:183], v[210:213], v[16:19]
	v_mfma_f32_16x16x32_bf16 v[4:7], v[168:171], v[218:221], v[4:7]
	v_mfma_f32_16x16x32_bf16 v[0:3], v[180:183], v[218:221], v[0:3]
	v_mfma_f32_16x16x32_bf16 v[52:55], v[172:175], v[192:195], v[52:55]
	v_mfma_f32_16x16x32_bf16 v[48:51], v[184:187], v[192:195], v[48:51]
	v_mfma_f32_16x16x32_bf16 v[36:39], v[172:175], v[206:209], v[36:39]
	v_mfma_f32_16x16x32_bf16 v[32:35], v[184:187], v[206:209], v[32:35]
	v_mfma_f32_16x16x32_bf16 v[20:23], v[172:175], v[214:217], v[20:23]
	v_mfma_f32_16x16x32_bf16 v[16:19], v[184:187], v[214:217], v[16:19]
	v_lshl_add_u64 v[200:201], v[230:231], 0, s[26:27]
	s_mov_b32 m0, s64
	s_nop 0
	global_load_lds_dwordx4 v[200:201], off
	v_mfma_f32_16x16x32_bf16 v[4:7], v[172:175], v[222:225], v[4:7]
	v_mfma_f32_16x16x32_bf16 v[0:3], v[184:187], v[222:225], v[0:3]
	s_setprio 0
	s_barrier
	s_add_i32 s81, s81, 2
	s_add_u32 s52, s52, 0x100
	s_addc_u32 s53, s53, 0
	s_add_u32 s79, s79, 0x100
	s_addc_u32 s80, s80, 0
	s_cmp_gt_u32 s81, 13
	s_cbranch_scc0 .LBB0_1681
	s_and_b64 vcc, exec, s[28:29]
	s_cbranch_vccz .LBB0_1684
	s_barrier

; #define PG8_STAGE(bufoff, gbase, voff) do { _Pragma("unroll") for (int _i = 0; _i < 2; ++_i) \
;         __builtin_amdgcn_global_load_lds((const unsigned*)((const char*)(gbase) + (voff)[_i]), (PG8_LAS unsigned*)(lds + (bufoff) + ldsw + _i * 8192), 16, 0, 0); } while (0)
; #define PG8_LDA(dst, b, h) do { _Pragma("unroll") for (int m = 0; m < 4; ++m) _Pragma("unroll") for (int k = 0; k < 2; ++k) dst[m][k] = *(const PG8_LAS bf16x8*)(lds + PG8_SA(b, h) + aoff + m * 2048 + k * 1024); } while (0)
; #define PG8_LDB(dst, b, h) do { _Pragma("unroll") for (int n = 0; n < 2; ++n) _Pragma("unroll") for (int k = 0; k < 2; ++k) dst[n][k] = *(const PG8_LAS bf16x8*)(lds + PG8_SB(b, h) + boff + n * 2048 + k * 1024); } while (0)
; #define PG8_WAIT_V(n) asm volatile("s_waitcnt vmcnt(" #n ")" ::: "memory")
; #define PG8_WAIT_L(n) asm volatile("s_waitcnt lgkmcnt(" #n ")" ::: "memory")
; #define PG8_BAR __builtin_amdgcn_s_barrier()
; #define PG8_SCHED __builtin_amdgcn_sched_barrier(0)
; template <class Epi, class Sched, bool ALIGN_EPI = false, bool SP2 = false>
; __device__ __forceinline__ void gemm_phase(PG8_LAS unsigned char* lds, const Gemm g, const Sched& S, const Epi& E) {
;     ...
;         const bool has_next = S.next(ui + 1, nxt);
;         const char* nA = has_next ? (const char*)g.A + (size_t)nxt.pm * tstep : cA; const char* nB = has_next ? (const char*)g.Bt + (size_t)nxt.pn * tstep : cB;
;         for (int t = 0; t < nt; t += 2) {
;             const bool last = (t == nt - 2);
;             const char* a1 = cA + (size_t)(t + 1) * kstep;
;             const char* a2 = last ? nA : cA + (size_t)(t + 2) * kstep; const char* b2 = last ? nB : cB + (size_t)(t + 2) * kstep;
;             const char* a3 = a2 + kstep; const char* b3 = b2 + kstep;
;             if (last && has_next) S.a_ready(nxt);
;             if constexpr (SP2) {
;             PG8_LDB(B0, 0, 0); PG8_LDB(B1, 0, 1); PG8_SCHED; PG8_LDA(At, 0, 0); PG8_STAGE(PG8_SA(1, 1), a1 + hstep, voffA);
;             PG8_WAIT_V(8); PG8_WAIT_L(0); PG8_BAR; PG8_MMA(0, 0, At, B0); PG8_MMA(0, 1, At, B1); PG8_BAR; PG8_SCHED;
;             PG8_LDA(At, 0, 1); PG8_STAGE(PG8_SB(0, 0), b2, voffB); PG8_STAGE(PG8_SB(0, 1), b2 + hstep, voffB); PG8_STAGE(PG8_SA(0, 0), a2, voffA);
;             PG8_WAIT_V(8); PG8_WAIT_L(0); PG8_BAR; PG8_MMA(1, 0, At, B0); PG8_MMA(1, 1, At, B1); PG8_BAR; PG8_SCHED;
.LBB0_1815:
	s_ashr_i32 s29, s28, 31
	s_lshl_b64 s[36:37], s[28:29], 18
	s_add_u32 s36, s92, s36
	s_addc_u32 s37, s93, s37
	s_and_b64 s[38:39], s[6:7], exec
	s_cselect_b32 s29, s37, s45
	s_cselect_b32 s41, s36, s44
	s_ashr_i32 s27, s26, 31
	s_lshl_b64 s[38:39], s[26:27], 18
	s_add_u32 s38, s3, s38
	s_addc_u32 s39, s14, s39
	s_and_b64 s[48:49], s[6:7], exec
	s_cselect_b32 s27, s39, s47
	s_cselect_b32 s58, s38, s46
	s_add_u32 s44, s44, 0x20080
	s_addc_u32 s45, s45, 0
	s_add_u32 s59, s46, 0x100
	s_addc_u32 s60, s47, 0
	s_mov_b32 s61, -2
	s_waitcnt lgkmcnt(0)
	ds_read_b128 v[144:147], v151
	ds_read_b128 v[156:159], v151 offset:1024
	ds_read_b128 v[160:163], v151 offset:2048
	ds_read_b128 v[164:167], v151 offset:3072
	ds_read_b128 v[168:171], v152
	ds_read_b128 v[172:175], v152 offset:1024
	ds_read_b128 v[176:179], v152 offset:2048
	ds_read_b128 v[180:183], v152 offset:3072
	s_add_u32 s46, s44, 0xfffe0080
	s_addc_u32 s47, s45, -1
	s_cmp_eq_u32 s61, 4
	s_cselect_b32 s49, s29, s47
	s_cselect_b32 s48, s41, s46
	s_cselect_b32 s47, s27, s60
	s_cselect_b32 s46, s58, s59
	v_lshl_add_u64 v[218:219], s[44:45], 0, v[136:137]
	s_add_i32 m0, s33, 0xc000
	ds_read_b128 v[184:187], v153
	ds_read_b128 v[188:191], v153 offset:1024
	ds_read_b128 v[192:195], v153 offset:2048
	ds_read_b128 v[196:199], v153 offset:3072
	ds_read_b128 v[200:203], v153 offset:4096
	ds_read_b128 v[206:209], v153 offset:5120
	ds_read_b128 v[210:213], v153 offset:6144
	ds_read_b128 v[214:217], v153 offset:7168
	global_load_lds_dwordx4 v[218:219], off
	v_lshl_add_u64 v[218:219], s[44:45], 0, v[138:139]
	s_add_i32 m0, s33, 0xe000
	s_nop 0
	global_load_lds_dwordx4 v[218:219], off
	s_waitcnt vmcnt(8)
	s_waitcnt lgkmcnt(0)
	s_barrier
	s_setprio 1
	s_waitcnt lgkmcnt(0)
	v_mfma_f32_16x16x32_bf16 v[124:127], v[144:147], v[184:187], 0
	v_mfma_f32_16x16x32_bf16 v[120:123], v[160:163], v[184:187], 0
	v_mfma_f32_16x16x32_bf16 v[108:111], v[144:147], v[192:195], 0
	v_mfma_f32_16x16x32_bf16 v[104:107], v[160:163], v[192:195], 0
	v_mfma_f32_16x16x32_bf16 v[92:95], v[144:147], v[200:203], 0
	v_mfma_f32_16x16x32_bf16 v[88:91], v[160:163], v[200:203], 0
	v_mfma_f32_16x16x32_bf16 v[76:79], v[144:147], v[210:213], 0
	v_mfma_f32_16x16x32_bf16 v[72:75], v[160:163], v[210:213], 0
	v_mfma_f32_16x16x32_bf16 v[124:127], v[156:159], v[188:191], v[124:127]
	v_mfma_f32_16x16x32_bf16 v[120:123], v[164:167], v[188:191], v[120:123]
	v_mfma_f32_16x16x32_bf16 v[108:111], v[156:159], v[196:199], v[108:111]
	v_mfma_f32_16x16x32_bf16 v[104:107], v[164:167], v[196:199], v[104:107]
	v_mfma_f32_16x16x32_bf16 v[92:95], v[156:159], v[206:209], v[92:95]
	v_mfma_f32_16x16x32_bf16 v[88:91], v[164:167], v[206:209], v[88:91]
	v_mfma_f32_16x16x32_bf16 v[76:79], v[156:159], v[214:217], v[76:79]
	v_mfma_f32_16x16x32_bf16 v[72:75], v[164:167], v[214:217], v[72:75]
	s_setprio 0
	s_setprio 1
	v_mfma_f32_16x16x32_bf16 v[116:119], v[168:171], v[184:187], 0
	v_mfma_f32_16x16x32_bf16 v[112:115], v[176:179], v[184:187], 0
	v_mfma_f32_16x16x32_bf16 v[100:103], v[168:171], v[192:195], 0
	v_mfma_f32_16x16x32_bf16 v[96:99], v[176:179], v[192:195], 0
	v_mfma_f32_16x16x32_bf16 v[84:87], v[168:171], v[200:203], 0
	v_mfma_f32_16x16x32_bf16 v[80:83], v[176:179], v[200:203], 0
	v_mfma_f32_16x16x32_bf16 v[68:71], v[168:171], v[210:213], 0
	v_mfma_f32_16x16x32_bf16 v[64:67], v[176:179], v[210:213], 0
	v_mfma_f32_16x16x32_bf16 v[116:119], v[172:175], v[188:191], v[116:119]
	v_mfma_f32_16x16x32_bf16 v[112:115], v[180:183], v[188:191], v[112:115]
	v_mfma_f32_16x16x32_bf16 v[100:103], v[172:175], v[196:199], v[100:103]
	v_mfma_f32_16x16x32_bf16 v[96:99], v[180:183], v[196:199], v[96:99]
	v_mfma_f32_16x16x32_bf16 v[84:87], v[172:175], v[206:209], v[84:87]
	v_mfma_f32_16x16x32_bf16 v[80:83], v[180:183], v[206:209], v[80:83]
	v_mfma_f32_16x16x32_bf16 v[68:71], v[172:175], v[214:217], v[68:71]
	v_mfma_f32_16x16x32_bf16 v[64:67], v[180:183], v[214:217], v[64:67]
	s_setprio 0
	s_barrier
	s_add_i32 s62, s54, s15
	v_lshl_add_u64 v[218:219], s[46:47], 0, v[130:131]
	s_mov_b32 m0, s62
	ds_read_b128 v[184:187], v153 offset:16384
	ds_read_b128 v[188:191], v153 offset:17408
	ds_read_b128 v[192:195], v153 offset:18432
	ds_read_b128 v[196:199], v153 offset:19456
	ds_read_b128 v[200:203], v153 offset:20480
	ds_read_b128 v[206:209], v153 offset:21504
	ds_read_b128 v[210:213], v153 offset:22528
	ds_read_b128 v[214:217], v153 offset:23552
	global_load_lds_dwordx4 v[218:219], off
	s_add_i32 m0, s62, 0x2000
	s_add_u32 s62, s46, 0x20000
	v_lshl_add_u64 v[220:221], s[46:47], 0, v[134:135]
	s_addc_u32 s63, s47, 0
	s_add_i32 s64, s55, s15
	global_load_lds_dwordx4 v[220:221], off
	v_lshl_add_u64 v[222:223], s[62:63], 0, v[130:131]
	s_mov_b32 m0, s64
	global_load_lds_dwordx4 v[222:223], off
	v_lshl_add_u64 v[222:223], s[62:63], 0, v[134:135]
	s_add_i32 m0, s64, 0x2000
	s_nop 0
	global_load_lds_dwordx4 v[222:223], off
	s_waitcnt vmcnt(6)
	s_waitcnt lgkmcnt(0)
	s_barrier
; #define PG8_STAGE(bufoff, gbase, voff) do { _Pragma("unroll") for (int _i = 0; _i < 2; ++_i) \
;         __builtin_amdgcn_global_load_lds((const unsigned*)((const char*)(gbase) + (voff)[_i]), (PG8_LAS unsigned*)(lds + (bufoff) + ldsw + _i * 8192), 16, 0, 0); } while (0)
; #define PG8_LDA(dst, b, h) do { _Pragma("unroll") for (int m = 0; m < 4; ++m) _Pragma("unroll") for (int k = 0; k < 2; ++k) dst[m][k] = *(const PG8_LAS bf16x8*)(lds + PG8_SA(b, h) + aoff + m * 2048 + k * 1024); } while (0)
; #define PG8_LDB(dst, b, h) do { _Pragma("unroll") for (int n = 0; n < 2; ++n) _Pragma("unroll") for (int k = 0; k < 2; ++k) dst[n][k] = *(const PG8_LAS bf16x8*)(lds + PG8_SB(b, h) + boff + n * 2048 + k * 1024); } while (0)
; #define PG8_MMA(ai, bj, At, Bt) do { __builtin_amdgcn_s_setprio(1); _Pragma("unroll") for (int m = 0; m < 4; ++m) _Pragma("unroll") for (int n = 0; n < 2; ++n) _Pragma("unroll") for (int k = 0; k < 2; ++k) \
;         acc[ai][bj][m][n] = __builtin_amdgcn_mfma_f32_16x16x32_bf16(Bt[n][k], At[m][k], acc[ai][bj][m][n], 0, 0, 0); __builtin_amdgcn_s_setprio(0); } while (0)
; #define PG8_WAIT_V(n) asm volatile("s_waitcnt vmcnt(" #n ")" ::: "memory")
; #define PG8_WAIT_L(n) asm volatile("s_waitcnt lgkmcnt(" #n ")" ::: "memory")
; #define PG8_BAR __builtin_amdgcn_s_barrier()
; #define PG8_SCHED __builtin_amdgcn_sched_barrier(0)
; template <class Epi, class Sched, bool ALIGN_EPI = false, bool SP2 = false>
; __device__ __forceinline__ void gemm_phase(PG8_LAS unsigned char* lds, const Gemm g, const Sched& S, const Epi& E) {
;     ...
;             PG8_LDA(At, 0, 1); PG8_STAGE(PG8_SB(0, 0), b2, voffB); PG8_STAGE(PG8_SB(0, 1), b2 + hstep, voffB); PG8_STAGE(PG8_SA(0, 0), a2, voffA);
;             PG8_WAIT_V(8); PG8_WAIT_L(0); PG8_BAR; PG8_MMA(1, 0, At, B0); PG8_MMA(1, 1, At, B1); PG8_BAR; PG8_SCHED;
;             PG8_LDB(B0, 1, 0); PG8_LDB(B1, 1, 1); PG8_SCHED; PG8_LDA(At, 1, 0); PG8_STAGE(PG8_SA(0, 1), a2 + hstep, voffA);
;             PG8_WAIT_V(8); PG8_WAIT_L(0); PG8_BAR; PG8_MMA(0, 0, At, B0); PG8_MMA(0, 1, At, B1); PG8_BAR; PG8_SCHED;
	s_setprio 1
	s_waitcnt lgkmcnt(0)
	v_mfma_f32_16x16x32_bf16 v[60:63], v[144:147], v[184:187], 0
	v_mfma_f32_16x16x32_bf16 v[56:59], v[160:163], v[184:187], 0
	v_mfma_f32_16x16x32_bf16 v[44:47], v[144:147], v[192:195], 0
	v_mfma_f32_16x16x32_bf16 v[40:43], v[160:163], v[192:195], 0
	v_mfma_f32_16x16x32_bf16 v[28:31], v[144:147], v[200:203], 0
	v_mfma_f32_16x16x32_bf16 v[24:27], v[160:163], v[200:203], 0
	v_mfma_f32_16x16x32_bf16 v[12:15], v[144:147], v[210:213], 0
	v_mfma_f32_16x16x32_bf16 v[8:11], v[160:163], v[210:213], 0
	v_mfma_f32_16x16x32_bf16 v[60:63], v[156:159], v[188:191], v[60:63]
	v_mfma_f32_16x16x32_bf16 v[56:59], v[164:167], v[188:191], v[56:59]
	v_mfma_f32_16x16x32_bf16 v[44:47], v[156:159], v[196:199], v[44:47]
	v_mfma_f32_16x16x32_bf16 v[40:43], v[164:167], v[196:199], v[40:43]
	v_mfma_f32_16x16x32_bf16 v[28:31], v[156:159], v[206:209], v[28:31]
	v_mfma_f32_16x16x32_bf16 v[24:27], v[164:167], v[206:209], v[24:27]
	v_lshl_add_u64 v[222:223], s[48:49], 0, v[128:129]
	s_mov_b32 m0, s33
	s_nop 0
	global_load_lds_dwordx4 v[222:223], off
	v_mfma_f32_16x16x32_bf16 v[12:15], v[156:159], v[214:217], v[12:15]
	v_mfma_f32_16x16x32_bf16 v[8:11], v[164:167], v[214:217], v[8:11]
	s_setprio 0
	s_setprio 1
	v_mfma_f32_16x16x32_bf16 v[52:55], v[168:171], v[184:187], 0
	v_mfma_f32_16x16x32_bf16 v[48:51], v[176:179], v[184:187], 0
	v_mfma_f32_16x16x32_bf16 v[36:39], v[168:171], v[192:195], 0
	v_mfma_f32_16x16x32_bf16 v[32:35], v[176:179], v[192:195], 0
	v_mfma_f32_16x16x32_bf16 v[20:23], v[168:171], v[200:203], 0
	v_mfma_f32_16x16x32_bf16 v[16:19], v[176:179], v[200:203], 0
	v_mfma_f32_16x16x32_bf16 v[4:7], v[168:171], v[210:213], 0
	v_mfma_f32_16x16x32_bf16 v[0:3], v[176:179], v[210:213], 0
	v_mfma_f32_16x16x32_bf16 v[52:55], v[172:175], v[188:191], v[52:55]
	v_mfma_f32_16x16x32_bf16 v[48:51], v[180:183], v[188:191], v[48:51]
	v_mfma_f32_16x16x32_bf16 v[36:39], v[172:175], v[196:199], v[36:39]
	v_mfma_f32_16x16x32_bf16 v[32:35], v[180:183], v[196:199], v[32:35]
	v_mfma_f32_16x16x32_bf16 v[20:23], v[172:175], v[206:209], v[20:23]
	v_mfma_f32_16x16x32_bf16 v[16:19], v[180:183], v[206:209], v[16:19]
	v_lshl_add_u64 v[224:225], s[48:49], 0, v[132:133]
	s_mov_b32 m0, s34
	s_nop 0
	global_load_lds_dwordx4 v[224:225], off
	v_mfma_f32_16x16x32_bf16 v[4:7], v[172:175], v[214:217], v[4:7]
	v_mfma_f32_16x16x32_bf16 v[0:3], v[180:183], v[214:217], v[0:3]
	s_setprio 0
	s_barrier
	s_add_i32 s62, 0, 0x18000
	v_add_u32_e32 v155, s62, v149
	s_add_i32 s63, 0, 0x1c000
	ds_read_b128 v[144:147], v155
	ds_read_b128 v[156:159], v155 offset:1024
	ds_read_b128 v[160:163], v155 offset:2048
	ds_read_b128 v[164:167], v155 offset:3072
	v_add_u32_e32 v155, s63, v149
	ds_read_b128 v[168:171], v155
	ds_read_b128 v[172:175], v155 offset:1024
	ds_read_b128 v[176:179], v155 offset:2048
	ds_read_b128 v[180:183], v155 offset:3072
	s_add_u32 s48, s48, 0x20000
	s_addc_u32 s49, s49, 0
	s_mov_b32 m0, s43
	v_lshl_add_u64 v[226:227], s[48:49], 0, v[128:129]
	ds_read_b128 v[184:187], v153 offset:32768
	ds_read_b128 v[188:191], v153 offset:33792
	ds_read_b128 v[192:195], v153 offset:34816
	ds_read_b128 v[196:199], v153 offset:35840
	ds_read_b128 v[200:203], v153 offset:36864
	ds_read_b128 v[206:209], v153 offset:37888
	ds_read_b128 v[210:213], v153 offset:38912
	ds_read_b128 v[214:217], v153 offset:39936
	global_load_lds_dwordx4 v[226:227], off
	v_lshl_add_u64 v[226:227], s[48:49], 0, v[132:133]
	s_mov_b32 m0, s50
	s_nop 0
	global_load_lds_dwordx4 v[226:227], off
	s_waitcnt vmcnt(8)
	s_waitcnt lgkmcnt(0)
	s_barrier
	s_setprio 1
	s_waitcnt lgkmcnt(0)
	v_mfma_f32_16x16x32_bf16 v[124:127], v[144:147], v[184:187], v[124:127]
	v_mfma_f32_16x16x32_bf16 v[120:123], v[160:163], v[184:187], v[120:123]
	v_mfma_f32_16x16x32_bf16 v[108:111], v[144:147], v[192:195], v[108:111]
	v_mfma_f32_16x16x32_bf16 v[104:107], v[160:163], v[192:195], v[104:107]
	v_mfma_f32_16x16x32_bf16 v[92:95], v[144:147], v[200:203], v[92:95]
	v_mfma_f32_16x16x32_bf16 v[88:91], v[160:163], v[200:203], v[88:91]
	v_mfma_f32_16x16x32_bf16 v[76:79], v[144:147], v[210:213], v[76:79]
	v_mfma_f32_16x16x32_bf16 v[72:75], v[160:163], v[210:213], v[72:75]
	v_mfma_f32_16x16x32_bf16 v[124:127], v[156:159], v[188:191], v[124:127]
	v_mfma_f32_16x16x32_bf16 v[120:123], v[164:167], v[188:191], v[120:123]
	v_mfma_f32_16x16x32_bf16 v[108:111], v[156:159], v[196:199], v[108:111]
	v_mfma_f32_16x16x32_bf16 v[104:107], v[164:167], v[196:199], v[104:107]
	v_mfma_f32_16x16x32_bf16 v[92:95], v[156:159], v[206:209], v[92:95]
	v_mfma_f32_16x16x32_bf16 v[88:91], v[164:167], v[206:209], v[88:91]
	v_mfma_f32_16x16x32_bf16 v[76:79], v[156:159], v[214:217], v[76:79]
	v_mfma_f32_16x16x32_bf16 v[72:75], v[164:167], v[214:217], v[72:75]
	s_setprio 0
	s_setprio 1
	v_mfma_f32_16x16x32_bf16 v[116:119], v[168:171], v[184:187], v[116:119]
	v_mfma_f32_16x16x32_bf16 v[112:115], v[176:179], v[184:187], v[112:115]
	v_mfma_f32_16x16x32_bf16 v[100:103], v[168:171], v[192:195], v[100:103]
	v_mfma_f32_16x16x32_bf16 v[96:99], v[176:179], v[192:195], v[96:99]
	v_mfma_f32_16x16x32_bf16 v[84:87], v[168:171], v[200:203], v[84:87]
	v_mfma_f32_16x16x32_bf16 v[80:83], v[176:179], v[200:203], v[80:83]
	v_mfma_f32_16x16x32_bf16 v[68:71], v[168:171], v[210:213], v[68:71]
	v_mfma_f32_16x16x32_bf16 v[64:67], v[176:179], v[210:213], v[64:67]
	v_mfma_f32_16x16x32_bf16 v[116:119], v[172:175], v[188:191], v[116:119]
	v_mfma_f32_16x16x32_bf16 v[112:115], v[180:183], v[188:191], v[112:115]
	v_mfma_f32_16x16x32_bf16 v[100:103], v[172:175], v[196:199], v[100:103]
	v_mfma_f32_16x16x32_bf16 v[96:99], v[180:183], v[196:199], v[96:99]
	v_mfma_f32_16x16x32_bf16 v[84:87], v[172:175], v[206:209], v[84:87]
	v_mfma_f32_16x16x32_bf16 v[80:83], v[180:183], v[206:209], v[80:83]
	v_mfma_f32_16x16x32_bf16 v[68:71], v[172:175], v[214:217], v[68:71]
	v_mfma_f32_16x16x32_bf16 v[64:67], v[180:183], v[214:217], v[64:67]
	s_setprio 0
	s_barrier
; #define PG8_STAGE(bufoff, gbase, voff) do { _Pragma("unroll") for (int _i = 0; _i < 2; ++_i) \
;         __builtin_amdgcn_global_load_lds((const unsigned*)((const char*)(gbase) + (voff)[_i]), (PG8_LAS unsigned*)(lds + (bufoff) + ldsw + _i * 8192), 16, 0, 0); } while (0)
; #define PG8_LDA(dst, b, h) do { _Pragma("unroll") for (int m = 0; m < 4; ++m) _Pragma("unroll") for (int k = 0; k < 2; ++k) dst[m][k] = *(const PG8_LAS bf16x8*)(lds + PG8_SA(b, h) + aoff + m * 2048 + k * 1024); } while (0)
; #define PG8_LDB(dst, b, h) do { _Pragma("unroll") for (int n = 0; n < 2; ++n) _Pragma("unroll") for (int k = 0; k < 2; ++k) dst[n][k] = *(const PG8_LAS bf16x8*)(lds + PG8_SB(b, h) + boff + n * 2048 + k * 1024); } while (0)
; #define PG8_MMA(ai, bj, At, Bt) do { __builtin_amdgcn_s_setprio(1); _Pragma("unroll") for (int m = 0; m < 4; ++m) _Pragma("unroll") for (int n = 0; n < 2; ++n) _Pragma("unroll") for (int k = 0; k < 2; ++k) \
;         acc[ai][bj][m][n] = __builtin_amdgcn_mfma_f32_16x16x32_bf16(Bt[n][k], At[m][k], acc[ai][bj][m][n], 0, 0, 0); __builtin_amdgcn_s_setprio(0); } while (0)
; #define PG8_WAIT_V(n) asm volatile("s_waitcnt vmcnt(" #n ")" ::: "memory")
; #define PG8_WAIT_L(n) asm volatile("s_waitcnt lgkmcnt(" #n ")" ::: "memory")
; #define PG8_BAR __builtin_amdgcn_s_barrier()
; #define PG8_SCHED __builtin_amdgcn_sched_barrier(0)
; template <class Epi, class Sched, bool ALIGN_EPI = false, bool SP2 = false>
; __device__ __forceinline__ void gemm_phase(PG8_LAS unsigned char* lds, const Gemm g, const Sched& S, const Epi& E) {
;     ...
;             PG8_LDB(B0, 0, 0); PG8_LDB(B1, 0, 1); PG8_SCHED; PG8_LDA(At, 0, 0); PG8_STAGE(PG8_SA(1, 1), a1 + hstep, voffA);
;             PG8_WAIT_V(8); PG8_WAIT_L(0); PG8_BAR; PG8_MMA(0, 0, At, B0); PG8_MMA(0, 1, At, B1); PG8_BAR; PG8_SCHED;
;     ...
;             PG8_WAIT_V(8); PG8_WAIT_L(0); PG8_BAR; PG8_MMA(0, 0, At, B0); PG8_MMA(0, 1, At, B1); PG8_BAR; PG8_SCHED;
;             PG8_LDA(At, 1, 1); PG8_STAGE(PG8_SB(1, 0), b3, voffB); PG8_STAGE(PG8_SB(1, 1), b3 + hstep, voffB); PG8_STAGE(PG8_SA(1, 0), a3, voffA);
;             PG8_WAIT_V(8); PG8_WAIT_L(0); PG8_BAR; PG8_MMA(1, 0, At, B0); PG8_MMA(1, 1, At, B1); PG8_BAR; PG8_SCHED;
	s_add_i32 s48, s62, s15
	v_lshl_add_u64 v[218:219], v[218:219], 0, s[12:13]
	s_mov_b32 m0, s48
	ds_read_b128 v[184:187], v153 offset:49152
	ds_read_b128 v[188:191], v153 offset:50176
	ds_read_b128 v[192:195], v153 offset:51200
	ds_read_b128 v[196:199], v153 offset:52224
	ds_read_b128 v[200:203], v153 offset:53248
	ds_read_b128 v[206:209], v153 offset:54272
	ds_read_b128 v[210:213], v153 offset:55296
	ds_read_b128 v[214:217], v153 offset:56320
	global_load_lds_dwordx4 v[218:219], off
	s_add_i32 m0, s48, 0x2000
	s_add_u32 s46, s46, 0x20080
	v_lshl_add_u64 v[218:219], v[220:221], 0, s[12:13]
	s_addc_u32 s47, s47, 0
	s_add_i32 s48, s63, s15
	global_load_lds_dwordx4 v[218:219], off
	v_lshl_add_u64 v[218:219], s[46:47], 0, v[130:131]
	s_mov_b32 m0, s48
	s_nop 0
	global_load_lds_dwordx4 v[218:219], off
	v_lshl_add_u64 v[218:219], s[46:47], 0, v[134:135]
	s_add_i32 m0, s48, 0x2000
	s_nop 0
	global_load_lds_dwordx4 v[218:219], off
	s_waitcnt vmcnt(6)
	s_waitcnt lgkmcnt(0)
	s_barrier
	s_setprio 1
	s_waitcnt lgkmcnt(0)
	v_mfma_f32_16x16x32_bf16 v[60:63], v[144:147], v[184:187], v[60:63]
	v_mfma_f32_16x16x32_bf16 v[56:59], v[160:163], v[184:187], v[56:59]
	v_mfma_f32_16x16x32_bf16 v[44:47], v[144:147], v[192:195], v[44:47]
	v_mfma_f32_16x16x32_bf16 v[40:43], v[160:163], v[192:195], v[40:43]
	v_mfma_f32_16x16x32_bf16 v[28:31], v[144:147], v[200:203], v[28:31]
	v_mfma_f32_16x16x32_bf16 v[24:27], v[160:163], v[200:203], v[24:27]
	v_mfma_f32_16x16x32_bf16 v[12:15], v[144:147], v[210:213], v[12:15]
	v_mfma_f32_16x16x32_bf16 v[8:11], v[160:163], v[210:213], v[8:11]
	v_mfma_f32_16x16x32_bf16 v[60:63], v[156:159], v[188:191], v[60:63]
	v_mfma_f32_16x16x32_bf16 v[56:59], v[164:167], v[188:191], v[56:59]
	v_mfma_f32_16x16x32_bf16 v[44:47], v[156:159], v[196:199], v[44:47]
	v_mfma_f32_16x16x32_bf16 v[40:43], v[164:167], v[196:199], v[40:43]
	v_mfma_f32_16x16x32_bf16 v[28:31], v[156:159], v[206:209], v[28:31]
	v_mfma_f32_16x16x32_bf16 v[24:27], v[164:167], v[206:209], v[24:27]
	v_lshl_add_u64 v[218:219], v[222:223], 0, s[12:13]
	s_mov_b32 m0, s52
	s_nop 0
	global_load_lds_dwordx4 v[218:219], off
	v_mfma_f32_16x16x32_bf16 v[12:15], v[156:159], v[214:217], v[12:15]
	v_mfma_f32_16x16x32_bf16 v[8:11], v[164:167], v[214:217], v[8:11]
	s_setprio 0
	s_setprio 1
	v_mfma_f32_16x16x32_bf16 v[52:55], v[168:171], v[184:187], v[52:55]
	v_mfma_f32_16x16x32_bf16 v[48:51], v[176:179], v[184:187], v[48:51]
	v_mfma_f32_16x16x32_bf16 v[36:39], v[168:171], v[192:195], v[36:39]
	v_mfma_f32_16x16x32_bf16 v[32:35], v[176:179], v[192:195], v[32:35]
	v_mfma_f32_16x16x32_bf16 v[20:23], v[168:171], v[200:203], v[20:23]
	v_mfma_f32_16x16x32_bf16 v[16:19], v[176:179], v[200:203], v[16:19]
	v_mfma_f32_16x16x32_bf16 v[4:7], v[168:171], v[210:213], v[4:7]
	v_mfma_f32_16x16x32_bf16 v[0:3], v[176:179], v[210:213], v[0:3]
	v_mfma_f32_16x16x32_bf16 v[52:55], v[172:175], v[188:191], v[52:55]
	v_mfma_f32_16x16x32_bf16 v[48:51], v[180:183], v[188:191], v[48:51]
	v_mfma_f32_16x16x32_bf16 v[36:39], v[172:175], v[196:199], v[36:39]
	v_mfma_f32_16x16x32_bf16 v[32:35], v[180:183], v[196:199], v[32:35]
	v_mfma_f32_16x16x32_bf16 v[20:23], v[172:175], v[206:209], v[20:23]
	v_mfma_f32_16x16x32_bf16 v[16:19], v[180:183], v[206:209], v[16:19]
	v_lshl_add_u64 v[218:219], v[224:225], 0, s[12:13]
	s_mov_b32 m0, s53
	s_nop 0
	global_load_lds_dwordx4 v[218:219], off
	v_mfma_f32_16x16x32_bf16 v[4:7], v[172:175], v[214:217], v[4:7]
	v_mfma_f32_16x16x32_bf16 v[0:3], v[180:183], v[214:217], v[0:3]
	s_setprio 0
	s_barrier
	s_add_i32 s61, s61, 2
	s_add_u32 s44, s44, 0x100
	s_addc_u32 s45, s45, 0
	s_add_u32 s59, s59, 0x100
	s_addc_u32 s60, s60, 0
.LBB0_1816:
	ds_read_b128 v[144:147], v151
	ds_read_b128 v[156:159], v151 offset:1024
	ds_read_b128 v[160:163], v151 offset:2048
	ds_read_b128 v[164:167], v151 offset:3072
	ds_read_b128 v[168:171], v152
	ds_read_b128 v[172:175], v152 offset:1024
	ds_read_b128 v[176:179], v152 offset:2048
	ds_read_b128 v[180:183], v152 offset:3072
	s_add_u32 s46, s44, 0xfffe0080
	s_addc_u32 s47, s45, -1
	s_cmp_eq_u32 s61, 4
	s_cselect_b32 s49, s29, s47
	s_cselect_b32 s48, s41, s46
	s_cselect_b32 s47, s27, s60
	s_cselect_b32 s46, s58, s59
	v_lshl_add_u64 v[218:219], s[44:45], 0, v[136:137]
	s_add_i32 m0, s33, 0xc000
	ds_read_b128 v[184:187], v153
	ds_read_b128 v[188:191], v153 offset:1024
	ds_read_b128 v[192:195], v153 offset:2048
	ds_read_b128 v[196:199], v153 offset:3072
	ds_read_b128 v[200:203], v153 offset:4096
	ds_read_b128 v[206:209], v153 offset:5120
	ds_read_b128 v[210:213], v153 offset:6144
	ds_read_b128 v[214:217], v153 offset:7168
	global_load_lds_dwordx4 v[218:219], off
	v_lshl_add_u64 v[218:219], s[44:45], 0, v[138:139]
	s_add_i32 m0, s33, 0xe000
	s_nop 0
	global_load_lds_dwordx4 v[218:219], off
	s_waitcnt vmcnt(8)
	s_waitcnt lgkmcnt(0)
	s_barrier
; #define PG8_STAGE(bufoff, gbase, voff) do { _Pragma("unroll") for (int _i = 0; _i < 2; ++_i) \
;         __builtin_amdgcn_global_load_lds((const unsigned*)((const char*)(gbase) + (voff)[_i]), (PG8_LAS unsigned*)(lds + (bufoff) + ldsw + _i * 8192), 16, 0, 0); } while (0)
; #define PG8_LDA(dst, b, h) do { _Pragma("unroll") for (int m = 0; m < 4; ++m) _Pragma("unroll") for (int k = 0; k < 2; ++k) dst[m][k] = *(const PG8_LAS bf16x8*)(lds + PG8_SA(b, h) + aoff + m * 2048 + k * 1024); } while (0)
; #define PG8_LDB(dst, b, h) do { _Pragma("unroll") for (int n = 0; n < 2; ++n) _Pragma("unroll") for (int k = 0; k < 2; ++k) dst[n][k] = *(const PG8_LAS bf16x8*)(lds + PG8_SB(b, h) + boff + n * 2048 + k * 1024); } while (0)
; #define PG8_MMA(ai, bj, At, Bt) do { __builtin_amdgcn_s_setprio(1); _Pragma("unroll") for (int m = 0; m < 4; ++m) _Pragma("unroll") for (int n = 0; n < 2; ++n) _Pragma("unroll") for (int k = 0; k < 2; ++k) \
;         acc[ai][bj][m][n] = __builtin_amdgcn_mfma_f32_16x16x32_bf16(Bt[n][k], At[m][k], acc[ai][bj][m][n], 0, 0, 0); __builtin_amdgcn_s_setprio(0); } while (0)
; #define PG8_WAIT_V(n) asm volatile("s_waitcnt vmcnt(" #n ")" ::: "memory")
; #define PG8_WAIT_L(n) asm volatile("s_waitcnt lgkmcnt(" #n ")" ::: "memory")
; #define PG8_BAR __builtin_amdgcn_s_barrier()
; #define PG8_SCHED __builtin_amdgcn_sched_barrier(0)
; template <class Epi, class Sched, bool ALIGN_EPI = false, bool SP2 = false>
; __device__ __forceinline__ void gemm_phase(PG8_LAS unsigned char* lds, const Gemm g, const Sched& S, const Epi& E) {
;     ...
;             PG8_LDB(B0, 0, 0); PG8_LDB(B1, 0, 1); PG8_SCHED; PG8_LDA(At, 0, 0); PG8_STAGE(PG8_SA(1, 1), a1 + hstep, voffA);
;             PG8_WAIT_V(8); PG8_WAIT_L(0); PG8_BAR; PG8_MMA(0, 0, At, B0); PG8_MMA(0, 1, At, B1); PG8_BAR; PG8_SCHED;
;             PG8_LDA(At, 0, 1); PG8_STAGE(PG8_SB(0, 0), b2, voffB); PG8_STAGE(PG8_SB(0, 1), b2 + hstep, voffB); PG8_STAGE(PG8_SA(0, 0), a2, voffA);
;             PG8_WAIT_V(8); PG8_WAIT_L(0); PG8_BAR; PG8_MMA(1, 0, At, B0); PG8_MMA(1, 1, At, B1); PG8_BAR; PG8_SCHED;
	s_setprio 1
	s_waitcnt lgkmcnt(0)
	v_mfma_f32_16x16x32_bf16 v[124:127], v[144:147], v[184:187], v[124:127]
	v_mfma_f32_16x16x32_bf16 v[120:123], v[160:163], v[184:187], v[120:123]
	v_mfma_f32_16x16x32_bf16 v[108:111], v[144:147], v[192:195], v[108:111]
	v_mfma_f32_16x16x32_bf16 v[104:107], v[160:163], v[192:195], v[104:107]
	v_mfma_f32_16x16x32_bf16 v[92:95], v[144:147], v[200:203], v[92:95]
	v_mfma_f32_16x16x32_bf16 v[88:91], v[160:163], v[200:203], v[88:91]
	v_mfma_f32_16x16x32_bf16 v[76:79], v[144:147], v[210:213], v[76:79]
	v_mfma_f32_16x16x32_bf16 v[72:75], v[160:163], v[210:213], v[72:75]
	v_mfma_f32_16x16x32_bf16 v[124:127], v[156:159], v[188:191], v[124:127]
	v_mfma_f32_16x16x32_bf16 v[120:123], v[164:167], v[188:191], v[120:123]
	v_mfma_f32_16x16x32_bf16 v[108:111], v[156:159], v[196:199], v[108:111]
	v_mfma_f32_16x16x32_bf16 v[104:107], v[164:167], v[196:199], v[104:107]
	v_mfma_f32_16x16x32_bf16 v[92:95], v[156:159], v[206:209], v[92:95]
	v_mfma_f32_16x16x32_bf16 v[88:91], v[164:167], v[206:209], v[88:91]
	v_mfma_f32_16x16x32_bf16 v[76:79], v[156:159], v[214:217], v[76:79]
	v_mfma_f32_16x16x32_bf16 v[72:75], v[164:167], v[214:217], v[72:75]
	s_setprio 0
	s_setprio 1
	v_mfma_f32_16x16x32_bf16 v[116:119], v[168:171], v[184:187], v[116:119]
	v_mfma_f32_16x16x32_bf16 v[112:115], v[176:179], v[184:187], v[112:115]
	v_mfma_f32_16x16x32_bf16 v[100:103], v[168:171], v[192:195], v[100:103]
	v_mfma_f32_16x16x32_bf16 v[96:99], v[176:179], v[192:195], v[96:99]
	v_mfma_f32_16x16x32_bf16 v[84:87], v[168:171], v[200:203], v[84:87]
	v_mfma_f32_16x16x32_bf16 v[80:83], v[176:179], v[200:203], v[80:83]
	v_mfma_f32_16x16x32_bf16 v[68:71], v[168:171], v[210:213], v[68:71]
	v_mfma_f32_16x16x32_bf16 v[64:67], v[176:179], v[210:213], v[64:67]
	v_mfma_f32_16x16x32_bf16 v[116:119], v[172:175], v[188:191], v[116:119]
	v_mfma_f32_16x16x32_bf16 v[112:115], v[180:183], v[188:191], v[112:115]
	v_mfma_f32_16x16x32_bf16 v[100:103], v[172:175], v[196:199], v[100:103]
	v_mfma_f32_16x16x32_bf16 v[96:99], v[180:183], v[196:199], v[96:99]
	v_mfma_f32_16x16x32_bf16 v[84:87], v[172:175], v[206:209], v[84:87]
	v_mfma_f32_16x16x32_bf16 v[80:83], v[180:183], v[206:209], v[80:83]
	v_mfma_f32_16x16x32_bf16 v[68:71], v[172:175], v[214:217], v[68:71]
	v_mfma_f32_16x16x32_bf16 v[64:67], v[180:183], v[214:217], v[64:67]
	s_setprio 0
	s_barrier
	s_add_i32 s62, s54, s15
	v_lshl_add_u64 v[218:219], s[46:47], 0, v[130:131]
	s_mov_b32 m0, s62
	ds_read_b128 v[184:187], v153 offset:16384
	ds_read_b128 v[188:191], v153 offset:17408
	ds_read_b128 v[192:195], v153 offset:18432
	ds_read_b128 v[196:199], v153 offset:19456
	ds_read_b128 v[200:203], v153 offset:20480
	ds_read_b128 v[206:209], v153 offset:21504
	ds_read_b128 v[210:213], v153 offset:22528
	ds_read_b128 v[214:217], v153 offset:23552
	global_load_lds_dwordx4 v[218:219], off
	s_add_i32 m0, s62, 0x2000
	s_add_u32 s62, s46, 0x20000
	v_lshl_add_u64 v[220:221], s[46:47], 0, v[134:135]
	s_addc_u32 s63, s47, 0
	s_add_i32 s64, s55, s15
	global_load_lds_dwordx4 v[220:221], off
	v_lshl_add_u64 v[222:223], s[62:63], 0, v[130:131]
	s_mov_b32 m0, s64
	global_load_lds_dwordx4 v[222:223], off
	v_lshl_add_u64 v[222:223], s[62:63], 0, v[134:135]
	s_add_i32 m0, s64, 0x2000
	s_nop 0
	global_load_lds_dwordx4 v[222:223], off
	s_waitcnt vmcnt(6)
	s_waitcnt lgkmcnt(0)
	s_barrier
	s_setprio 1
	s_waitcnt lgkmcnt(0)
	v_mfma_f32_16x16x32_bf16 v[60:63], v[144:147], v[184:187], v[60:63]
	v_mfma_f32_16x16x32_bf16 v[56:59], v[160:163], v[184:187], v[56:59]
	v_mfma_f32_16x16x32_bf16 v[44:47], v[144:147], v[192:195], v[44:47]
	v_mfma_f32_16x16x32_bf16 v[40:43], v[160:163], v[192:195], v[40:43]
	v_mfma_f32_16x16x32_bf16 v[28:31], v[144:147], v[200:203], v[28:31]
	v_mfma_f32_16x16x32_bf16 v[24:27], v[160:163], v[200:203], v[24:27]
	v_mfma_f32_16x16x32_bf16 v[12:15], v[144:147], v[210:213], v[12:15]
	v_mfma_f32_16x16x32_bf16 v[8:11], v[160:163], v[210:213], v[8:11]
	v_mfma_f32_16x16x32_bf16 v[60:63], v[156:159], v[188:191], v[60:63]
	v_mfma_f32_16x16x32_bf16 v[56:59], v[164:167], v[188:191], v[56:59]
	v_mfma_f32_16x16x32_bf16 v[44:47], v[156:159], v[196:199], v[44:47]
	v_mfma_f32_16x16x32_bf16 v[40:43], v[164:167], v[196:199], v[40:43]
	v_mfma_f32_16x16x32_bf16 v[28:31], v[156:159], v[206:209], v[28:31]
	v_mfma_f32_16x16x32_bf16 v[24:27], v[164:167], v[206:209], v[24:27]
	v_lshl_add_u64 v[222:223], s[48:49], 0, v[128:129]
	s_mov_b32 m0, s33
	s_nop 0
	global_load_lds_dwordx4 v[222:223], off
	v_mfma_f32_16x16x32_bf16 v[12:15], v[156:159], v[214:217], v[12:15]
	v_mfma_f32_16x16x32_bf16 v[8:11], v[164:167], v[214:217], v[8:11]
	s_setprio 0
	s_setprio 1
	v_mfma_f32_16x16x32_bf16 v[52:55], v[168:171], v[184:187], v[52:55]
	v_mfma_f32_16x16x32_bf16 v[48:51], v[176:179], v[184:187], v[48:51]
	v_mfma_f32_16x16x32_bf16 v[36:39], v[168:171], v[192:195], v[36:39]
	v_mfma_f32_16x16x32_bf16 v[32:35], v[176:179], v[192:195], v[32:35]
	v_mfma_f32_16x16x32_bf16 v[20:23], v[168:171], v[200:203], v[20:23]
	v_mfma_f32_16x16x32_bf16 v[16:19], v[176:179], v[200:203], v[16:19]
	v_mfma_f32_16x16x32_bf16 v[4:7], v[168:171], v[210:213], v[4:7]
	v_mfma_f32_16x16x32_bf16 v[0:3], v[176:179], v[210:213], v[0:3]
	v_mfma_f32_16x16x32_bf16 v[52:55], v[172:175], v[188:191], v[52:55]
	v_mfma_f32_16x16x32_bf16 v[48:51], v[180:183], v[188:191], v[48:51]
	v_mfma_f32_16x16x32_bf16 v[36:39], v[172:175], v[196:199], v[36:39]
	v_mfma_f32_16x16x32_bf16 v[32:35], v[180:183], v[196:199], v[32:35]
	v_mfma_f32_16x16x32_bf16 v[20:23], v[172:175], v[206:209], v[20:23]
	v_mfma_f32_16x16x32_bf16 v[16:19], v[180:183], v[206:209], v[16:19]
	v_lshl_add_u64 v[224:225], s[48:49], 0, v[132:133]
	s_mov_b32 m0, s34
	s_nop 0
	global_load_lds_dwordx4 v[224:225], off
	v_mfma_f32_16x16x32_bf16 v[4:7], v[172:175], v[214:217], v[4:7]
	v_mfma_f32_16x16x32_bf16 v[0:3], v[180:183], v[214:217], v[0:3]
	s_setprio 0
	s_barrier
; #define PG8_STAGE(bufoff, gbase, voff) do { _Pragma("unroll") for (int _i = 0; _i < 2; ++_i) \
;         __builtin_amdgcn_global_load_lds((const unsigned*)((const char*)(gbase) + (voff)[_i]), (PG8_LAS unsigned*)(lds + (bufoff) + ldsw + _i * 8192), 16, 0, 0); } while (0)
; #define PG8_LDA(dst, b, h) do { _Pragma("unroll") for (int m = 0; m < 4; ++m) _Pragma("unroll") for (int k = 0; k < 2; ++k) dst[m][k] = *(const PG8_LAS bf16x8*)(lds + PG8_SA(b, h) + aoff + m * 2048 + k * 1024); } while (0)
; #define PG8_LDB(dst, b, h) do { _Pragma("unroll") for (int n = 0; n < 2; ++n) _Pragma("unroll") for (int k = 0; k < 2; ++k) dst[n][k] = *(const PG8_LAS bf16x8*)(lds + PG8_SB(b, h) + boff + n * 2048 + k * 1024); } while (0)
; #define PG8_MMA(ai, bj, At, Bt) do { __builtin_amdgcn_s_setprio(1); _Pragma("unroll") for (int m = 0; m < 4; ++m) _Pragma("unroll") for (int n = 0; n < 2; ++n) _Pragma("unroll") for (int k = 0; k < 2; ++k) \
;         acc[ai][bj][m][n] = __builtin_amdgcn_mfma_f32_16x16x32_bf16(Bt[n][k], At[m][k], acc[ai][bj][m][n], 0, 0, 0); __builtin_amdgcn_s_setprio(0); } while (0)
; #define PG8_WAIT_V(n) asm volatile("s_waitcnt vmcnt(" #n ")" ::: "memory")
; #define PG8_WAIT_L(n) asm volatile("s_waitcnt lgkmcnt(" #n ")" ::: "memory")
; #define PG8_BAR __builtin_amdgcn_s_barrier()
; #define PG8_SCHED __builtin_amdgcn_sched_barrier(0)
; template <class Epi, class Sched, bool ALIGN_EPI = false, bool SP2 = false>
; __device__ __forceinline__ void gemm_phase(PG8_LAS unsigned char* lds, const Gemm g, const Sched& S, const Epi& E) {
;     ...
;             PG8_LDB(B0, 1, 0); PG8_LDB(B1, 1, 1); PG8_SCHED; PG8_LDA(At, 1, 0); PG8_STAGE(PG8_SA(0, 1), a2 + hstep, voffA);
;             PG8_WAIT_V(8); PG8_WAIT_L(0); PG8_BAR; PG8_MMA(0, 0, At, B0); PG8_MMA(0, 1, At, B1); PG8_BAR; PG8_SCHED;
	s_add_i32 s62, 0, 0x18000
	v_add_u32_e32 v155, s62, v149
	s_add_i32 s63, 0, 0x1c000
	ds_read_b128 v[144:147], v155
	ds_read_b128 v[156:159], v155 offset:1024
	ds_read_b128 v[160:163], v155 offset:2048
	ds_read_b128 v[164:167], v155 offset:3072
	v_add_u32_e32 v155, s63, v149
	ds_read_b128 v[168:171], v155
	ds_read_b128 v[172:175], v155 offset:1024
	ds_read_b128 v[176:179], v155 offset:2048
	ds_read_b128 v[180:183], v155 offset:3072
	s_add_u32 s48, s48, 0x20000
	s_addc_u32 s49, s49, 0
	s_mov_b32 m0, s43
	v_lshl_add_u64 v[226:227], s[48:49], 0, v[128:129]
	ds_read_b128 v[184:187], v153 offset:32768
	ds_read_b128 v[188:191], v153 offset:33792
	ds_read_b128 v[192:195], v153 offset:34816
	ds_read_b128 v[196:199], v153 offset:35840
	ds_read_b128 v[200:203], v153 offset:36864
	ds_read_b128 v[206:209], v153 offset:37888
	ds_read_b128 v[210:213], v153 offset:38912
	ds_read_b128 v[214:217], v153 offset:39936
	global_load_lds_dwordx4 v[226:227], off
	v_lshl_add_u64 v[226:227], s[48:49], 0, v[132:133]
	s_mov_b32 m0, s50
	s_nop 0
	global_load_lds_dwordx4 v[226:227], off
	s_waitcnt vmcnt(8)
	s_waitcnt lgkmcnt(0)
	s_barrier
	s_setprio 1
	s_waitcnt lgkmcnt(0)
	v_mfma_f32_16x16x32_bf16 v[124:127], v[144:147], v[184:187], v[124:127]
	v_mfma_f32_16x16x32_bf16 v[120:123], v[160:163], v[184:187], v[120:123]
	v_mfma_f32_16x16x32_bf16 v[108:111], v[144:147], v[192:195], v[108:111]
	v_mfma_f32_16x16x32_bf16 v[104:107], v[160:163], v[192:195], v[104:107]
	v_mfma_f32_16x16x32_bf16 v[92:95], v[144:147], v[200:203], v[92:95]
	v_mfma_f32_16x16x32_bf16 v[88:91], v[160:163], v[200:203], v[88:91]
	v_mfma_f32_16x16x32_bf16 v[76:79], v[144:147], v[210:213], v[76:79]
	v_mfma_f32_16x16x32_bf16 v[72:75], v[160:163], v[210:213], v[72:75]
	v_mfma_f32_16x16x32_bf16 v[124:127], v[156:159], v[188:191], v[124:127]
	v_mfma_f32_16x16x32_bf16 v[120:123], v[164:167], v[188:191], v[120:123]
	v_mfma_f32_16x16x32_bf16 v[108:111], v[156:159], v[196:199], v[108:111]
	v_mfma_f32_16x16x32_bf16 v[104:107], v[164:167], v[196:199], v[104:107]
	v_mfma_f32_16x16x32_bf16 v[92:95], v[156:159], v[206:209], v[92:95]
	v_mfma_f32_16x16x32_bf16 v[88:91], v[164:167], v[206:209], v[88:91]
	v_mfma_f32_16x16x32_bf16 v[76:79], v[156:159], v[214:217], v[76:79]
	v_mfma_f32_16x16x32_bf16 v[72:75], v[164:167], v[214:217], v[72:75]
	s_setprio 0
	s_setprio 1
	v_mfma_f32_16x16x32_bf16 v[116:119], v[168:171], v[184:187], v[116:119]
	v_mfma_f32_16x16x32_bf16 v[112:115], v[176:179], v[184:187], v[112:115]
	v_mfma_f32_16x16x32_bf16 v[100:103], v[168:171], v[192:195], v[100:103]
	v_mfma_f32_16x16x32_bf16 v[96:99], v[176:179], v[192:195], v[96:99]
	v_mfma_f32_16x16x32_bf16 v[84:87], v[168:171], v[200:203], v[84:87]
	v_mfma_f32_16x16x32_bf16 v[80:83], v[176:179], v[200:203], v[80:83]
	v_mfma_f32_16x16x32_bf16 v[68:71], v[168:171], v[210:213], v[68:71]
	v_mfma_f32_16x16x32_bf16 v[64:67], v[176:179], v[210:213], v[64:67]
	v_mfma_f32_16x16x32_bf16 v[116:119], v[172:175], v[188:191], v[116:119]
	v_mfma_f32_16x16x32_bf16 v[112:115], v[180:183], v[188:191], v[112:115]
	v_mfma_f32_16x16x32_bf16 v[100:103], v[172:175], v[196:199], v[100:103]
	v_mfma_f32_16x16x32_bf16 v[96:99], v[180:183], v[196:199], v[96:99]
	v_mfma_f32_16x16x32_bf16 v[84:87], v[172:175], v[206:209], v[84:87]
	v_mfma_f32_16x16x32_bf16 v[80:83], v[180:183], v[206:209], v[80:83]
	v_mfma_f32_16x16x32_bf16 v[68:71], v[172:175], v[214:217], v[68:71]
	v_mfma_f32_16x16x32_bf16 v[64:67], v[180:183], v[214:217], v[64:67]
	s_setprio 0
	s_barrier
; #define PG8_STAGE(bufoff, gbase, voff) do { _Pragma("unroll") for (int _i = 0; _i < 2; ++_i) \
;         __builtin_amdgcn_global_load_lds((const unsigned*)((const char*)(gbase) + (voff)[_i]), (PG8_LAS unsigned*)(lds + (bufoff) + ldsw + _i * 8192), 16, 0, 0); } while (0)
; #define PG8_LDA(dst, b, h) do { _Pragma("unroll") for (int m = 0; m < 4; ++m) _Pragma("unroll") for (int k = 0; k < 2; ++k) dst[m][k] = *(const PG8_LAS bf16x8*)(lds + PG8_SA(b, h) + aoff + m * 2048 + k * 1024); } while (0)
; #define PG8_MMA(ai, bj, At, Bt) do { __builtin_amdgcn_s_setprio(1); _Pragma("unroll") for (int m = 0; m < 4; ++m) _Pragma("unroll") for (int n = 0; n < 2; ++n) _Pragma("unroll") for (int k = 0; k < 2; ++k) \
;         acc[ai][bj][m][n] = __builtin_amdgcn_mfma_f32_16x16x32_bf16(Bt[n][k], At[m][k], acc[ai][bj][m][n], 0, 0, 0); __builtin_amdgcn_s_setprio(0); } while (0)
; #define PG8_WAIT_V(n) asm volatile("s_waitcnt vmcnt(" #n ")" ::: "memory")
; #define PG8_WAIT_L(n) asm volatile("s_waitcnt lgkmcnt(" #n ")" ::: "memory")
; #define PG8_BAR __builtin_amdgcn_s_barrier()
; #define PG8_SCHED __builtin_amdgcn_sched_barrier(0)
; template <class Epi, class Sched, bool ALIGN_EPI = false, bool SP2 = false>
; __device__ __forceinline__ void gemm_phase(PG8_LAS unsigned char* lds, const Gemm g, const Sched& S, const Epi& E) {
;     ...
;             PG8_WAIT_V(8); PG8_WAIT_L(0); PG8_BAR; PG8_MMA(0, 0, At, B0); PG8_MMA(0, 1, At, B1); PG8_BAR; PG8_SCHED;
;             PG8_LDA(At, 1, 1); PG8_STAGE(PG8_SB(1, 0), b3, voffB); PG8_STAGE(PG8_SB(1, 1), b3 + hstep, voffB); PG8_STAGE(PG8_SA(1, 0), a3, voffA);
;             PG8_WAIT_V(8); PG8_WAIT_L(0); PG8_BAR; PG8_MMA(1, 0, At, B0); PG8_MMA(1, 1, At, B1); PG8_BAR; PG8_SCHED;
;     ...
;         if constexpr (ALIGN_EPI) { if (wr == 0) PG8_BAR; }
	s_add_i32 s48, s62, s15
	v_lshl_add_u64 v[218:219], v[218:219], 0, s[12:13]
	s_mov_b32 m0, s48
	ds_read_b128 v[184:187], v153 offset:49152
	ds_read_b128 v[188:191], v153 offset:50176
	ds_read_b128 v[192:195], v153 offset:51200
	ds_read_b128 v[196:199], v153 offset:52224
	ds_read_b128 v[200:203], v153 offset:53248
	ds_read_b128 v[206:209], v153 offset:54272
	ds_read_b128 v[210:213], v153 offset:55296
	ds_read_b128 v[214:217], v153 offset:56320
	global_load_lds_dwordx4 v[218:219], off
	s_add_i32 m0, s48, 0x2000
	s_add_u32 s46, s46, 0x20080
	v_lshl_add_u64 v[218:219], v[220:221], 0, s[12:13]
	s_addc_u32 s47, s47, 0
	s_add_i32 s48, s63, s15
	global_load_lds_dwordx4 v[218:219], off
	v_lshl_add_u64 v[218:219], s[46:47], 0, v[130:131]
	s_mov_b32 m0, s48
	s_nop 0
	global_load_lds_dwordx4 v[218:219], off
	v_lshl_add_u64 v[218:219], s[46:47], 0, v[134:135]
	s_add_i32 m0, s48, 0x2000
	s_nop 0
	global_load_lds_dwordx4 v[218:219], off
	s_waitcnt vmcnt(6)
	s_waitcnt lgkmcnt(0)
	s_barrier
	s_setprio 1
	s_waitcnt lgkmcnt(0)
	v_mfma_f32_16x16x32_bf16 v[60:63], v[144:147], v[184:187], v[60:63]
	v_mfma_f32_16x16x32_bf16 v[56:59], v[160:163], v[184:187], v[56:59]
	v_mfma_f32_16x16x32_bf16 v[44:47], v[144:147], v[192:195], v[44:47]
	v_mfma_f32_16x16x32_bf16 v[40:43], v[160:163], v[192:195], v[40:43]
	v_mfma_f32_16x16x32_bf16 v[28:31], v[144:147], v[200:203], v[28:31]
	v_mfma_f32_16x16x32_bf16 v[24:27], v[160:163], v[200:203], v[24:27]
	v_mfma_f32_16x16x32_bf16 v[12:15], v[144:147], v[210:213], v[12:15]
	v_mfma_f32_16x16x32_bf16 v[8:11], v[160:163], v[210:213], v[8:11]
	v_mfma_f32_16x16x32_bf16 v[60:63], v[156:159], v[188:191], v[60:63]
	v_mfma_f32_16x16x32_bf16 v[56:59], v[164:167], v[188:191], v[56:59]
	v_mfma_f32_16x16x32_bf16 v[44:47], v[156:159], v[196:199], v[44:47]
	v_mfma_f32_16x16x32_bf16 v[40:43], v[164:167], v[196:199], v[40:43]
	v_mfma_f32_16x16x32_bf16 v[28:31], v[156:159], v[206:209], v[28:31]
	v_mfma_f32_16x16x32_bf16 v[24:27], v[164:167], v[206:209], v[24:27]
	v_lshl_add_u64 v[218:219], v[222:223], 0, s[12:13]
	s_mov_b32 m0, s52
	s_nop 0
	global_load_lds_dwordx4 v[218:219], off
	v_mfma_f32_16x16x32_bf16 v[12:15], v[156:159], v[214:217], v[12:15]
	v_mfma_f32_16x16x32_bf16 v[8:11], v[164:167], v[214:217], v[8:11]
	s_setprio 0
	s_setprio 1
	v_mfma_f32_16x16x32_bf16 v[52:55], v[168:171], v[184:187], v[52:55]
	v_mfma_f32_16x16x32_bf16 v[48:51], v[176:179], v[184:187], v[48:51]
	v_mfma_f32_16x16x32_bf16 v[36:39], v[168:171], v[192:195], v[36:39]
	v_mfma_f32_16x16x32_bf16 v[32:35], v[176:179], v[192:195], v[32:35]
	v_mfma_f32_16x16x32_bf16 v[20:23], v[168:171], v[200:203], v[20:23]
	v_mfma_f32_16x16x32_bf16 v[16:19], v[176:179], v[200:203], v[16:19]
	v_mfma_f32_16x16x32_bf16 v[4:7], v[168:171], v[210:213], v[4:7]
	v_mfma_f32_16x16x32_bf16 v[0:3], v[176:179], v[210:213], v[0:3]
	v_mfma_f32_16x16x32_bf16 v[52:55], v[172:175], v[188:191], v[52:55]
	v_mfma_f32_16x16x32_bf16 v[48:51], v[180:183], v[188:191], v[48:51]
	v_mfma_f32_16x16x32_bf16 v[36:39], v[172:175], v[196:199], v[36:39]
	v_mfma_f32_16x16x32_bf16 v[32:35], v[180:183], v[196:199], v[32:35]
	v_mfma_f32_16x16x32_bf16 v[20:23], v[172:175], v[206:209], v[20:23]
	v_mfma_f32_16x16x32_bf16 v[16:19], v[180:183], v[206:209], v[16:19]
	v_lshl_add_u64 v[218:219], v[224:225], 0, s[12:13]
	s_mov_b32 m0, s53
	s_nop 0
	global_load_lds_dwordx4 v[218:219], off
	v_mfma_f32_16x16x32_bf16 v[4:7], v[172:175], v[214:217], v[4:7]
	v_mfma_f32_16x16x32_bf16 v[0:3], v[180:183], v[214:217], v[0:3]
	s_setprio 0
	s_barrier
	s_add_i32 s61, s61, 2
	s_add_u32 s44, s44, 0x100
	s_addc_u32 s45, s45, 0
	s_add_u32 s59, s59, 0x100
	s_addc_u32 s60, s60, 0
	s_cmp_gt_u32 s61, 5
	s_cbranch_scc0 .LBB0_1816
	s_and_b64 vcc, exec, s[24:25]
	s_cbranch_vccz .LBB0_1819
	s_barrier

; #define PG8_STAGE(bufoff, gbase, voff) do { _Pragma("unroll") for (int _i = 0; _i < 2; ++_i) \
;         __builtin_amdgcn_global_load_lds((const unsigned*)((const char*)(gbase) + (voff)[_i]), (PG8_LAS unsigned*)(lds + (bufoff) + ldsw + _i * 8192), 16, 0, 0); } while (0)
; #define PG8_LDA(dst, b, h) do { _Pragma("unroll") for (int m = 0; m < 4; ++m) _Pragma("unroll") for (int k = 0; k < 2; ++k) dst[m][k] = *(const PG8_LAS bf16x8*)(lds + PG8_SA(b, h) + aoff + m * 2048 + k * 1024); } while (0)
; #define PG8_LDB(dst, b, h) do { _Pragma("unroll") for (int n = 0; n < 2; ++n) _Pragma("unroll") for (int k = 0; k < 2; ++k) dst[n][k] = *(const PG8_LAS bf16x8*)(lds + PG8_SB(b, h) + boff + n * 2048 + k * 1024); } while (0)
; #define PG8_WAIT_V(n) asm volatile("s_waitcnt vmcnt(" #n ")" ::: "memory")
; #define PG8_WAIT_L(n) asm volatile("s_waitcnt lgkmcnt(" #n ")" ::: "memory")
; #define PG8_BAR __builtin_amdgcn_s_barrier()
; #define PG8_SCHED __builtin_amdgcn_sched_barrier(0)
; template <class Epi, class Sched, bool ALIGN_EPI = false, bool SP2 = false>
; __device__ __forceinline__ void gemm_phase(PG8_LAS unsigned char* lds, const Gemm g, const Sched& S, const Epi& E) {
;     ...
;         const bool has_next = S.next(ui + 1, nxt);
;         const char* nA = has_next ? (const char*)g.A + (size_t)nxt.pm * tstep : cA; const char* nB = has_next ? (const char*)g.Bt + (size_t)nxt.pn * tstep : cB;
;         for (int t = 0; t < nt; t += 2) {
;             const bool last = (t == nt - 2);
;             const char* a1 = cA + (size_t)(t + 1) * kstep;
;             const char* a2 = last ? nA : cA + (size_t)(t + 2) * kstep; const char* b2 = last ? nB : cB + (size_t)(t + 2) * kstep;
;             const char* a3 = a2 + kstep; const char* b3 = b2 + kstep;
;             if (last && has_next) S.a_ready(nxt);
;             if constexpr (SP2) {
;             PG8_LDB(B0, 0, 0); PG8_LDB(B1, 0, 1); PG8_SCHED; PG8_LDA(At, 0, 0); PG8_STAGE(PG8_SA(1, 1), a1 + hstep, voffA);
;             PG8_WAIT_V(8); PG8_WAIT_L(0); PG8_BAR; PG8_MMA(0, 0, At, B0); PG8_MMA(0, 1, At, B1); PG8_BAR; PG8_SCHED;
;             PG8_LDA(At, 0, 1); PG8_STAGE(PG8_SB(0, 0), b2, voffB); PG8_STAGE(PG8_SB(0, 1), b2 + hstep, voffB); PG8_STAGE(PG8_SA(0, 0), a2, voffA);
;             PG8_WAIT_V(8); PG8_WAIT_L(0); PG8_BAR; PG8_MMA(1, 0, At, B0); PG8_MMA(1, 1, At, B1); PG8_BAR; PG8_SCHED;
.LBB0_1899:
	s_ashr_i32 s25, s24, 31
	s_lshl_b64 s[26:27], s[24:25], 19
	s_add_u32 s26, s22, s26
	s_addc_u32 s27, s23, s27
	s_and_b64 s[28:29], s[4:5], exec
	s_cselect_b32 s25, s27, s39
	s_cselect_b32 s53, s26, s38
	s_ashr_i32 s13, s12, 31
	s_lshl_b64 s[28:29], s[12:13], 19
	s_add_u32 s28, s3, s28
	s_addc_u32 s29, s14, s29
	s_and_b64 s[42:43], s[4:5], exec
	s_cselect_b32 s13, s29, s41
	s_cselect_b32 s54, s28, s40
	s_add_u32 s38, s38, 0x40080
	s_addc_u32 s39, s39, 0
	s_add_u32 s55, s40, 0x100
	s_addc_u32 s56, s41, 0
	s_mov_b32 s57, -2
	ds_read_b128 v[144:147], v155
	ds_read_b128 v[148:151], v155 offset:1024
	ds_read_b128 v[160:163], v155 offset:2048
	ds_read_b128 v[164:167], v155 offset:3072
	ds_read_b128 v[168:171], v156
	ds_read_b128 v[172:175], v156 offset:1024
	ds_read_b128 v[176:179], v156 offset:2048
	ds_read_b128 v[180:183], v156 offset:3072
	s_add_u32 s40, s38, 0xfffc0080
	s_addc_u32 s41, s39, -1
	s_cmp_eq_u32 s57, 12
	s_cselect_b32 s43, s25, s41
	s_cselect_b32 s42, s53, s40
	s_cselect_b32 s41, s13, s56
	s_cselect_b32 s40, s54, s55
	v_lshl_add_u64 v[218:219], s[38:39], 0, v[136:137]
	s_add_i32 m0, s34, 0xc000
	ds_read_b128 v[184:187], v157
	ds_read_b128 v[188:191], v157 offset:1024
	ds_read_b128 v[192:195], v157 offset:2048
	ds_read_b128 v[196:199], v157 offset:3072
	ds_read_b128 v[200:203], v157 offset:4096
	ds_read_b128 v[206:209], v157 offset:5120
	ds_read_b128 v[210:213], v157 offset:6144
	ds_read_b128 v[214:217], v157 offset:7168
	global_load_lds_dwordx4 v[218:219], off
	v_lshl_add_u64 v[218:219], s[38:39], 0, v[138:139]
	s_add_i32 m0, s34, 0xe000
	s_nop 0
	global_load_lds_dwordx4 v[218:219], off
	s_waitcnt vmcnt(8)
	s_waitcnt lgkmcnt(0)
	s_barrier
	s_setprio 1
	s_waitcnt lgkmcnt(0)
	v_mfma_f32_16x16x32_bf16 v[124:127], v[144:147], v[184:187], 0
	v_mfma_f32_16x16x32_bf16 v[120:123], v[160:163], v[184:187], 0
	v_mfma_f32_16x16x32_bf16 v[108:111], v[144:147], v[192:195], 0
	v_mfma_f32_16x16x32_bf16 v[104:107], v[160:163], v[192:195], 0
	v_mfma_f32_16x16x32_bf16 v[92:95], v[144:147], v[200:203], 0
	v_mfma_f32_16x16x32_bf16 v[88:91], v[160:163], v[200:203], 0
	v_mfma_f32_16x16x32_bf16 v[76:79], v[144:147], v[210:213], 0
	v_mfma_f32_16x16x32_bf16 v[72:75], v[160:163], v[210:213], 0
	v_mfma_f32_16x16x32_bf16 v[124:127], v[148:151], v[188:191], v[124:127]
	v_mfma_f32_16x16x32_bf16 v[120:123], v[164:167], v[188:191], v[120:123]
	v_mfma_f32_16x16x32_bf16 v[108:111], v[148:151], v[196:199], v[108:111]
	v_mfma_f32_16x16x32_bf16 v[104:107], v[164:167], v[196:199], v[104:107]
	v_mfma_f32_16x16x32_bf16 v[92:95], v[148:151], v[206:209], v[92:95]
	v_mfma_f32_16x16x32_bf16 v[88:91], v[164:167], v[206:209], v[88:91]
	v_mfma_f32_16x16x32_bf16 v[76:79], v[148:151], v[214:217], v[76:79]
	v_mfma_f32_16x16x32_bf16 v[72:75], v[164:167], v[214:217], v[72:75]
	s_setprio 0
	s_setprio 1
	v_mfma_f32_16x16x32_bf16 v[116:119], v[168:171], v[184:187], 0
	v_mfma_f32_16x16x32_bf16 v[112:115], v[176:179], v[184:187], 0
	v_mfma_f32_16x16x32_bf16 v[100:103], v[168:171], v[192:195], 0
	v_mfma_f32_16x16x32_bf16 v[96:99], v[176:179], v[192:195], 0
	v_mfma_f32_16x16x32_bf16 v[84:87], v[168:171], v[200:203], 0
	v_mfma_f32_16x16x32_bf16 v[80:83], v[176:179], v[200:203], 0
	v_mfma_f32_16x16x32_bf16 v[68:71], v[168:171], v[210:213], 0
	v_mfma_f32_16x16x32_bf16 v[64:67], v[176:179], v[210:213], 0
	v_mfma_f32_16x16x32_bf16 v[116:119], v[172:175], v[188:191], v[116:119]
	v_mfma_f32_16x16x32_bf16 v[112:115], v[180:183], v[188:191], v[112:115]
	v_mfma_f32_16x16x32_bf16 v[100:103], v[172:175], v[196:199], v[100:103]
	v_mfma_f32_16x16x32_bf16 v[96:99], v[180:183], v[196:199], v[96:99]
	v_mfma_f32_16x16x32_bf16 v[84:87], v[172:175], v[206:209], v[84:87]
	v_mfma_f32_16x16x32_bf16 v[80:83], v[180:183], v[206:209], v[80:83]
	v_mfma_f32_16x16x32_bf16 v[68:71], v[172:175], v[214:217], v[68:71]
	v_mfma_f32_16x16x32_bf16 v[64:67], v[180:183], v[214:217], v[64:67]
	s_setprio 0
	s_barrier
	s_add_i32 s58, s49, s15
	v_lshl_add_u64 v[218:219], s[40:41], 0, v[132:133]
	s_mov_b32 m0, s58
	ds_read_b128 v[184:187], v157 offset:16384
	ds_read_b128 v[188:191], v157 offset:17408
	ds_read_b128 v[192:195], v157 offset:18432
	ds_read_b128 v[196:199], v157 offset:19456
	ds_read_b128 v[200:203], v157 offset:20480
	ds_read_b128 v[206:209], v157 offset:21504
	ds_read_b128 v[210:213], v157 offset:22528
	ds_read_b128 v[214:217], v157 offset:23552
	global_load_lds_dwordx4 v[218:219], off
	s_add_i32 m0, s58, 0x2000
	s_add_u32 s58, s40, 0x40000
	v_lshl_add_u64 v[220:221], s[40:41], 0, v[128:129]
	s_addc_u32 s59, s41, 0
	s_add_i32 s60, s50, s15
	global_load_lds_dwordx4 v[220:221], off
	v_lshl_add_u64 v[222:223], s[58:59], 0, v[132:133]
	s_mov_b32 m0, s60
	global_load_lds_dwordx4 v[222:223], off
	v_lshl_add_u64 v[222:223], s[58:59], 0, v[128:129]
	s_add_i32 m0, s60, 0x2000
	s_nop 0
	global_load_lds_dwordx4 v[222:223], off
	s_waitcnt vmcnt(6)
	s_waitcnt lgkmcnt(0)
	s_barrier
; #define PG8_STAGE(bufoff, gbase, voff) do { _Pragma("unroll") for (int _i = 0; _i < 2; ++_i) \
;         __builtin_amdgcn_global_load_lds((const unsigned*)((const char*)(gbase) + (voff)[_i]), (PG8_LAS unsigned*)(lds + (bufoff) + ldsw + _i * 8192), 16, 0, 0); } while (0)
; #define PG8_LDA(dst, b, h) do { _Pragma("unroll") for (int m = 0; m < 4; ++m) _Pragma("unroll") for (int k = 0; k < 2; ++k) dst[m][k] = *(const PG8_LAS bf16x8*)(lds + PG8_SA(b, h) + aoff + m * 2048 + k * 1024); } while (0)
; #define PG8_LDB(dst, b, h) do { _Pragma("unroll") for (int n = 0; n < 2; ++n) _Pragma("unroll") for (int k = 0; k < 2; ++k) dst[n][k] = *(const PG8_LAS bf16x8*)(lds + PG8_SB(b, h) + boff + n * 2048 + k * 1024); } while (0)
; #define PG8_MMA(ai, bj, At, Bt) do { __builtin_amdgcn_s_setprio(1); _Pragma("unroll") for (int m = 0; m < 4; ++m) _Pragma("unroll") for (int n = 0; n < 2; ++n) _Pragma("unroll") for (int k = 0; k < 2; ++k) \
;         acc[ai][bj][m][n] = __builtin_amdgcn_mfma_f32_16x16x32_bf16(Bt[n][k], At[m][k], acc[ai][bj][m][n], 0, 0, 0); __builtin_amdgcn_s_setprio(0); } while (0)
; #define PG8_WAIT_V(n) asm volatile("s_waitcnt vmcnt(" #n ")" ::: "memory")
; #define PG8_WAIT_L(n) asm volatile("s_waitcnt lgkmcnt(" #n ")" ::: "memory")
; #define PG8_BAR __builtin_amdgcn_s_barrier()
; #define PG8_SCHED __builtin_amdgcn_sched_barrier(0)
; template <class Epi, class Sched, bool ALIGN_EPI = false, bool SP2 = false>
; __device__ __forceinline__ void gemm_phase(PG8_LAS unsigned char* lds, const Gemm g, const Sched& S, const Epi& E) {
;     ...
;             PG8_LDA(At, 0, 1); PG8_STAGE(PG8_SB(0, 0), b2, voffB); PG8_STAGE(PG8_SB(0, 1), b2 + hstep, voffB); PG8_STAGE(PG8_SA(0, 0), a2, voffA);
;             PG8_WAIT_V(8); PG8_WAIT_L(0); PG8_BAR; PG8_MMA(1, 0, At, B0); PG8_MMA(1, 1, At, B1); PG8_BAR; PG8_SCHED;
;             PG8_LDB(B0, 1, 0); PG8_LDB(B1, 1, 1); PG8_SCHED; PG8_LDA(At, 1, 0); PG8_STAGE(PG8_SA(0, 1), a2 + hstep, voffA);
;             PG8_WAIT_V(8); PG8_WAIT_L(0); PG8_BAR; PG8_MMA(0, 0, At, B0); PG8_MMA(0, 1, At, B1); PG8_BAR; PG8_SCHED;
	s_setprio 1
	s_waitcnt lgkmcnt(0)
	v_mfma_f32_16x16x32_bf16 v[60:63], v[144:147], v[184:187], 0
	v_mfma_f32_16x16x32_bf16 v[56:59], v[160:163], v[184:187], 0
	v_mfma_f32_16x16x32_bf16 v[44:47], v[144:147], v[192:195], 0
	v_mfma_f32_16x16x32_bf16 v[40:43], v[160:163], v[192:195], 0
	v_mfma_f32_16x16x32_bf16 v[28:31], v[144:147], v[200:203], 0
	v_mfma_f32_16x16x32_bf16 v[24:27], v[160:163], v[200:203], 0
	v_mfma_f32_16x16x32_bf16 v[12:15], v[144:147], v[210:213], 0
	v_mfma_f32_16x16x32_bf16 v[8:11], v[160:163], v[210:213], 0
	v_mfma_f32_16x16x32_bf16 v[60:63], v[148:151], v[188:191], v[60:63]
	v_mfma_f32_16x16x32_bf16 v[56:59], v[164:167], v[188:191], v[56:59]
	v_mfma_f32_16x16x32_bf16 v[44:47], v[148:151], v[196:199], v[44:47]
	v_mfma_f32_16x16x32_bf16 v[40:43], v[164:167], v[196:199], v[40:43]
	v_mfma_f32_16x16x32_bf16 v[28:31], v[148:151], v[206:209], v[28:31]
	v_mfma_f32_16x16x32_bf16 v[24:27], v[164:167], v[206:209], v[24:27]
	v_lshl_add_u64 v[222:223], s[42:43], 0, v[134:135]
	s_mov_b32 m0, s34
	s_nop 0
	global_load_lds_dwordx4 v[222:223], off
	v_mfma_f32_16x16x32_bf16 v[12:15], v[148:151], v[214:217], v[12:15]
	v_mfma_f32_16x16x32_bf16 v[8:11], v[164:167], v[214:217], v[8:11]
	s_setprio 0
	s_setprio 1
	v_mfma_f32_16x16x32_bf16 v[52:55], v[168:171], v[184:187], 0
	v_mfma_f32_16x16x32_bf16 v[48:51], v[176:179], v[184:187], 0
	v_mfma_f32_16x16x32_bf16 v[36:39], v[168:171], v[192:195], 0
	v_mfma_f32_16x16x32_bf16 v[32:35], v[176:179], v[192:195], 0
	v_mfma_f32_16x16x32_bf16 v[20:23], v[168:171], v[200:203], 0
	v_mfma_f32_16x16x32_bf16 v[16:19], v[176:179], v[200:203], 0
	v_mfma_f32_16x16x32_bf16 v[4:7], v[168:171], v[210:213], 0
	v_mfma_f32_16x16x32_bf16 v[0:3], v[176:179], v[210:213], 0
	v_mfma_f32_16x16x32_bf16 v[52:55], v[172:175], v[188:191], v[52:55]
	v_mfma_f32_16x16x32_bf16 v[48:51], v[180:183], v[188:191], v[48:51]
	v_mfma_f32_16x16x32_bf16 v[36:39], v[172:175], v[196:199], v[36:39]
	v_mfma_f32_16x16x32_bf16 v[32:35], v[180:183], v[196:199], v[32:35]
	v_mfma_f32_16x16x32_bf16 v[20:23], v[172:175], v[206:209], v[20:23]
	v_mfma_f32_16x16x32_bf16 v[16:19], v[180:183], v[206:209], v[16:19]
	v_lshl_add_u64 v[224:225], s[42:43], 0, v[130:131]
	s_mov_b32 m0, s37
	s_nop 0
	global_load_lds_dwordx4 v[224:225], off
	v_mfma_f32_16x16x32_bf16 v[4:7], v[172:175], v[214:217], v[4:7]
	v_mfma_f32_16x16x32_bf16 v[0:3], v[180:183], v[214:217], v[0:3]
	s_setprio 0
	s_barrier
	s_add_i32 s58, 0, 0x18000
	v_add_u32_e32 v159, s58, v153
	s_add_i32 s59, 0, 0x1c000
	ds_read_b128 v[144:147], v159
	ds_read_b128 v[148:151], v159 offset:1024
	ds_read_b128 v[160:163], v159 offset:2048
	ds_read_b128 v[164:167], v159 offset:3072
	v_add_u32_e32 v159, s59, v153
	ds_read_b128 v[168:171], v159
	ds_read_b128 v[172:175], v159 offset:1024
	ds_read_b128 v[176:179], v159 offset:2048
	ds_read_b128 v[180:183], v159 offset:3072
	s_add_u32 s42, s42, 0x40000
	s_addc_u32 s43, s43, 0
	s_mov_b32 m0, s44
	v_lshl_add_u64 v[226:227], s[42:43], 0, v[134:135]
	ds_read_b128 v[184:187], v157 offset:32768
	ds_read_b128 v[188:191], v157 offset:33792
	ds_read_b128 v[192:195], v157 offset:34816
	ds_read_b128 v[196:199], v157 offset:35840
	ds_read_b128 v[200:203], v157 offset:36864
	ds_read_b128 v[206:209], v157 offset:37888
	ds_read_b128 v[210:213], v157 offset:38912
	ds_read_b128 v[214:217], v157 offset:39936
	global_load_lds_dwordx4 v[226:227], off
	v_lshl_add_u64 v[226:227], s[42:43], 0, v[130:131]
	s_mov_b32 m0, s45
	s_nop 0
	global_load_lds_dwordx4 v[226:227], off
	s_waitcnt vmcnt(8)
	s_waitcnt lgkmcnt(0)
	s_barrier
	s_setprio 1
	s_waitcnt lgkmcnt(0)
	v_mfma_f32_16x16x32_bf16 v[124:127], v[144:147], v[184:187], v[124:127]
	v_mfma_f32_16x16x32_bf16 v[120:123], v[160:163], v[184:187], v[120:123]
	v_mfma_f32_16x16x32_bf16 v[108:111], v[144:147], v[192:195], v[108:111]
	v_mfma_f32_16x16x32_bf16 v[104:107], v[160:163], v[192:195], v[104:107]
	v_mfma_f32_16x16x32_bf16 v[92:95], v[144:147], v[200:203], v[92:95]
	v_mfma_f32_16x16x32_bf16 v[88:91], v[160:163], v[200:203], v[88:91]
	v_mfma_f32_16x16x32_bf16 v[76:79], v[144:147], v[210:213], v[76:79]
	v_mfma_f32_16x16x32_bf16 v[72:75], v[160:163], v[210:213], v[72:75]
	v_mfma_f32_16x16x32_bf16 v[124:127], v[148:151], v[188:191], v[124:127]
	v_mfma_f32_16x16x32_bf16 v[120:123], v[164:167], v[188:191], v[120:123]
	v_mfma_f32_16x16x32_bf16 v[108:111], v[148:151], v[196:199], v[108:111]
	v_mfma_f32_16x16x32_bf16 v[104:107], v[164:167], v[196:199], v[104:107]
	v_mfma_f32_16x16x32_bf16 v[92:95], v[148:151], v[206:209], v[92:95]
	v_mfma_f32_16x16x32_bf16 v[88:91], v[164:167], v[206:209], v[88:91]
	v_mfma_f32_16x16x32_bf16 v[76:79], v[148:151], v[214:217], v[76:79]
	v_mfma_f32_16x16x32_bf16 v[72:75], v[164:167], v[214:217], v[72:75]
	s_setprio 0
	s_setprio 1
	v_mfma_f32_16x16x32_bf16 v[116:119], v[168:171], v[184:187], v[116:119]
	v_mfma_f32_16x16x32_bf16 v[112:115], v[176:179], v[184:187], v[112:115]
	v_mfma_f32_16x16x32_bf16 v[100:103], v[168:171], v[192:195], v[100:103]
	v_mfma_f32_16x16x32_bf16 v[96:99], v[176:179], v[192:195], v[96:99]
	v_mfma_f32_16x16x32_bf16 v[84:87], v[168:171], v[200:203], v[84:87]
	v_mfma_f32_16x16x32_bf16 v[80:83], v[176:179], v[200:203], v[80:83]
	v_mfma_f32_16x16x32_bf16 v[68:71], v[168:171], v[210:213], v[68:71]
	v_mfma_f32_16x16x32_bf16 v[64:67], v[176:179], v[210:213], v[64:67]
	v_mfma_f32_16x16x32_bf16 v[116:119], v[172:175], v[188:191], v[116:119]
	v_mfma_f32_16x16x32_bf16 v[112:115], v[180:183], v[188:191], v[112:115]
	v_mfma_f32_16x16x32_bf16 v[100:103], v[172:175], v[196:199], v[100:103]
	v_mfma_f32_16x16x32_bf16 v[96:99], v[180:183], v[196:199], v[96:99]
	v_mfma_f32_16x16x32_bf16 v[84:87], v[172:175], v[206:209], v[84:87]
	v_mfma_f32_16x16x32_bf16 v[80:83], v[180:183], v[206:209], v[80:83]
	v_mfma_f32_16x16x32_bf16 v[68:71], v[172:175], v[214:217], v[68:71]
	v_mfma_f32_16x16x32_bf16 v[64:67], v[180:183], v[214:217], v[64:67]
	s_setprio 0
	s_barrier
; #define PG8_STAGE(bufoff, gbase, voff) do { _Pragma("unroll") for (int _i = 0; _i < 2; ++_i) \
;         __builtin_amdgcn_global_load_lds((const unsigned*)((const char*)(gbase) + (voff)[_i]), (PG8_LAS unsigned*)(lds + (bufoff) + ldsw + _i * 8192), 16, 0, 0); } while (0)
; #define PG8_LDA(dst, b, h) do { _Pragma("unroll") for (int m = 0; m < 4; ++m) _Pragma("unroll") for (int k = 0; k < 2; ++k) dst[m][k] = *(const PG8_LAS bf16x8*)(lds + PG8_SA(b, h) + aoff + m * 2048 + k * 1024); } while (0)
; #define PG8_LDB(dst, b, h) do { _Pragma("unroll") for (int n = 0; n < 2; ++n) _Pragma("unroll") for (int k = 0; k < 2; ++k) dst[n][k] = *(const PG8_LAS bf16x8*)(lds + PG8_SB(b, h) + boff + n * 2048 + k * 1024); } while (0)
; #define PG8_MMA(ai, bj, At, Bt) do { __builtin_amdgcn_s_setprio(1); _Pragma("unroll") for (int m = 0; m < 4; ++m) _Pragma("unroll") for (int n = 0; n < 2; ++n) _Pragma("unroll") for (int k = 0; k < 2; ++k) \
;         acc[ai][bj][m][n] = __builtin_amdgcn_mfma_f32_16x16x32_bf16(Bt[n][k], At[m][k], acc[ai][bj][m][n], 0, 0, 0); __builtin_amdgcn_s_setprio(0); } while (0)
; #define PG8_WAIT_V(n) asm volatile("s_waitcnt vmcnt(" #n ")" ::: "memory")
; #define PG8_WAIT_L(n) asm volatile("s_waitcnt lgkmcnt(" #n ")" ::: "memory")
; #define PG8_BAR __builtin_amdgcn_s_barrier()
; #define PG8_SCHED __builtin_amdgcn_sched_barrier(0)
; template <class Epi, class Sched, bool ALIGN_EPI = false, bool SP2 = false>
; __device__ __forceinline__ void gemm_phase(PG8_LAS unsigned char* lds, const Gemm g, const Sched& S, const Epi& E) {
;     ...
;             PG8_LDB(B0, 0, 0); PG8_LDB(B1, 0, 1); PG8_SCHED; PG8_LDA(At, 0, 0); PG8_STAGE(PG8_SA(1, 1), a1 + hstep, voffA);
;             PG8_WAIT_V(8); PG8_WAIT_L(0); PG8_BAR; PG8_MMA(0, 0, At, B0); PG8_MMA(0, 1, At, B1); PG8_BAR; PG8_SCHED;
;     ...
;             PG8_WAIT_V(8); PG8_WAIT_L(0); PG8_BAR; PG8_MMA(0, 0, At, B0); PG8_MMA(0, 1, At, B1); PG8_BAR; PG8_SCHED;
;             PG8_LDA(At, 1, 1); PG8_STAGE(PG8_SB(1, 0), b3, voffB); PG8_STAGE(PG8_SB(1, 1), b3 + hstep, voffB); PG8_STAGE(PG8_SA(1, 0), a3, voffA);
;             PG8_WAIT_V(8); PG8_WAIT_L(0); PG8_BAR; PG8_MMA(1, 0, At, B0); PG8_MMA(1, 1, At, B1); PG8_BAR; PG8_SCHED;
	s_add_i32 s42, s58, s15
	v_lshl_add_u64 v[218:219], v[218:219], 0, s[8:9]
	s_mov_b32 m0, s42
	ds_read_b128 v[184:187], v157 offset:49152
	ds_read_b128 v[188:191], v157 offset:50176
	ds_read_b128 v[192:195], v157 offset:51200
	ds_read_b128 v[196:199], v157 offset:52224
	ds_read_b128 v[200:203], v157 offset:53248
	ds_read_b128 v[206:209], v157 offset:54272
	ds_read_b128 v[210:213], v157 offset:55296
	ds_read_b128 v[214:217], v157 offset:56320
	global_load_lds_dwordx4 v[218:219], off
	s_add_i32 m0, s42, 0x2000
	s_add_u32 s40, s40, 0x40080
	v_lshl_add_u64 v[218:219], v[220:221], 0, s[8:9]
	s_addc_u32 s41, s41, 0
	s_add_i32 s42, s59, s15
	global_load_lds_dwordx4 v[218:219], off
	v_lshl_add_u64 v[218:219], s[40:41], 0, v[132:133]
	s_mov_b32 m0, s42
	s_nop 0
	global_load_lds_dwordx4 v[218:219], off
	v_lshl_add_u64 v[218:219], s[40:41], 0, v[128:129]
	s_add_i32 m0, s42, 0x2000
	s_nop 0
	global_load_lds_dwordx4 v[218:219], off
	s_waitcnt vmcnt(6)
	s_waitcnt lgkmcnt(0)
	s_barrier
	s_setprio 1
	s_waitcnt lgkmcnt(0)
	v_mfma_f32_16x16x32_bf16 v[60:63], v[144:147], v[184:187], v[60:63]
	v_mfma_f32_16x16x32_bf16 v[56:59], v[160:163], v[184:187], v[56:59]
	v_mfma_f32_16x16x32_bf16 v[44:47], v[144:147], v[192:195], v[44:47]
	v_mfma_f32_16x16x32_bf16 v[40:43], v[160:163], v[192:195], v[40:43]
	v_mfma_f32_16x16x32_bf16 v[28:31], v[144:147], v[200:203], v[28:31]
	v_mfma_f32_16x16x32_bf16 v[24:27], v[160:163], v[200:203], v[24:27]
	v_mfma_f32_16x16x32_bf16 v[12:15], v[144:147], v[210:213], v[12:15]
	v_mfma_f32_16x16x32_bf16 v[8:11], v[160:163], v[210:213], v[8:11]
	v_mfma_f32_16x16x32_bf16 v[60:63], v[148:151], v[188:191], v[60:63]
	v_mfma_f32_16x16x32_bf16 v[56:59], v[164:167], v[188:191], v[56:59]
	v_mfma_f32_16x16x32_bf16 v[44:47], v[148:151], v[196:199], v[44:47]
	v_mfma_f32_16x16x32_bf16 v[40:43], v[164:167], v[196:199], v[40:43]
	v_mfma_f32_16x16x32_bf16 v[28:31], v[148:151], v[206:209], v[28:31]
	v_mfma_f32_16x16x32_bf16 v[24:27], v[164:167], v[206:209], v[24:27]
	v_lshl_add_u64 v[218:219], v[222:223], 0, s[8:9]
	s_mov_b32 m0, s47
	s_nop 0
	global_load_lds_dwordx4 v[218:219], off
	v_mfma_f32_16x16x32_bf16 v[12:15], v[148:151], v[214:217], v[12:15]
	v_mfma_f32_16x16x32_bf16 v[8:11], v[164:167], v[214:217], v[8:11]
	s_setprio 0
	s_setprio 1
	v_mfma_f32_16x16x32_bf16 v[52:55], v[168:171], v[184:187], v[52:55]
	v_mfma_f32_16x16x32_bf16 v[48:51], v[176:179], v[184:187], v[48:51]
	v_mfma_f32_16x16x32_bf16 v[36:39], v[168:171], v[192:195], v[36:39]
	v_mfma_f32_16x16x32_bf16 v[32:35], v[176:179], v[192:195], v[32:35]
	v_mfma_f32_16x16x32_bf16 v[20:23], v[168:171], v[200:203], v[20:23]
	v_mfma_f32_16x16x32_bf16 v[16:19], v[176:179], v[200:203], v[16:19]
	v_mfma_f32_16x16x32_bf16 v[4:7], v[168:171], v[210:213], v[4:7]
	v_mfma_f32_16x16x32_bf16 v[0:3], v[176:179], v[210:213], v[0:3]
	v_mfma_f32_16x16x32_bf16 v[52:55], v[172:175], v[188:191], v[52:55]
	v_mfma_f32_16x16x32_bf16 v[48:51], v[180:183], v[188:191], v[48:51]
	v_mfma_f32_16x16x32_bf16 v[36:39], v[172:175], v[196:199], v[36:39]
	v_mfma_f32_16x16x32_bf16 v[32:35], v[180:183], v[196:199], v[32:35]
	v_mfma_f32_16x16x32_bf16 v[20:23], v[172:175], v[206:209], v[20:23]
	v_mfma_f32_16x16x32_bf16 v[16:19], v[180:183], v[206:209], v[16:19]
	v_lshl_add_u64 v[218:219], v[224:225], 0, s[8:9]
	s_mov_b32 m0, s48
	s_nop 0
	global_load_lds_dwordx4 v[218:219], off
	v_mfma_f32_16x16x32_bf16 v[4:7], v[172:175], v[214:217], v[4:7]
	v_mfma_f32_16x16x32_bf16 v[0:3], v[180:183], v[214:217], v[0:3]
	s_setprio 0
	s_barrier
	s_add_i32 s57, s57, 2
	s_add_u32 s38, s38, 0x100
	s_addc_u32 s39, s39, 0
	s_add_u32 s55, s55, 0x100
	s_addc_u32 s56, s56, 0
.LBB0_1900:
	ds_read_b128 v[144:147], v155
	ds_read_b128 v[148:151], v155 offset:1024
	ds_read_b128 v[160:163], v155 offset:2048
	ds_read_b128 v[164:167], v155 offset:3072
	ds_read_b128 v[168:171], v156
	ds_read_b128 v[172:175], v156 offset:1024
	ds_read_b128 v[176:179], v156 offset:2048
	ds_read_b128 v[180:183], v156 offset:3072
	s_add_u32 s40, s38, 0xfffc0080
	s_addc_u32 s41, s39, -1
	s_cmp_eq_u32 s57, 12
	s_cselect_b32 s43, s25, s41
	s_cselect_b32 s42, s53, s40
	s_cselect_b32 s41, s13, s56
	s_cselect_b32 s40, s54, s55
	v_lshl_add_u64 v[218:219], s[38:39], 0, v[136:137]
	s_add_i32 m0, s34, 0xc000
	ds_read_b128 v[184:187], v157
	ds_read_b128 v[188:191], v157 offset:1024
	ds_read_b128 v[192:195], v157 offset:2048
	ds_read_b128 v[196:199], v157 offset:3072
	ds_read_b128 v[200:203], v157 offset:4096
	ds_read_b128 v[206:209], v157 offset:5120
	ds_read_b128 v[210:213], v157 offset:6144
	ds_read_b128 v[214:217], v157 offset:7168
	global_load_lds_dwordx4 v[218:219], off
	v_lshl_add_u64 v[218:219], s[38:39], 0, v[138:139]
	s_add_i32 m0, s34, 0xe000
	s_nop 0
	global_load_lds_dwordx4 v[218:219], off
	s_waitcnt vmcnt(8)
	s_waitcnt lgkmcnt(0)
	s_barrier
; #define PG8_STAGE(bufoff, gbase, voff) do { _Pragma("unroll") for (int _i = 0; _i < 2; ++_i) \
;         __builtin_amdgcn_global_load_lds((const unsigned*)((const char*)(gbase) + (voff)[_i]), (PG8_LAS unsigned*)(lds + (bufoff) + ldsw + _i * 8192), 16, 0, 0); } while (0)
; #define PG8_LDA(dst, b, h) do { _Pragma("unroll") for (int m = 0; m < 4; ++m) _Pragma("unroll") for (int k = 0; k < 2; ++k) dst[m][k] = *(const PG8_LAS bf16x8*)(lds + PG8_SA(b, h) + aoff + m * 2048 + k * 1024); } while (0)
; #define PG8_LDB(dst, b, h) do { _Pragma("unroll") for (int n = 0; n < 2; ++n) _Pragma("unroll") for (int k = 0; k < 2; ++k) dst[n][k] = *(const PG8_LAS bf16x8*)(lds + PG8_SB(b, h) + boff + n * 2048 + k * 1024); } while (0)
; #define PG8_MMA(ai, bj, At, Bt) do { __builtin_amdgcn_s_setprio(1); _Pragma("unroll") for (int m = 0; m < 4; ++m) _Pragma("unroll") for (int n = 0; n < 2; ++n) _Pragma("unroll") for (int k = 0; k < 2; ++k) \
;         acc[ai][bj][m][n] = __builtin_amdgcn_mfma_f32_16x16x32_bf16(Bt[n][k], At[m][k], acc[ai][bj][m][n], 0, 0, 0); __builtin_amdgcn_s_setprio(0); } while (0)
; #define PG8_WAIT_V(n) asm volatile("s_waitcnt vmcnt(" #n ")" ::: "memory")
; #define PG8_WAIT_L(n) asm volatile("s_waitcnt lgkmcnt(" #n ")" ::: "memory")
; #define PG8_BAR __builtin_amdgcn_s_barrier()
; #define PG8_SCHED __builtin_amdgcn_sched_barrier(0)
; template <class Epi, class Sched, bool ALIGN_EPI = false, bool SP2 = false>
; __device__ __forceinline__ void gemm_phase(PG8_LAS unsigned char* lds, const Gemm g, const Sched& S, const Epi& E) {
;     ...
;             PG8_LDB(B0, 0, 0); PG8_LDB(B1, 0, 1); PG8_SCHED; PG8_LDA(At, 0, 0); PG8_STAGE(PG8_SA(1, 1), a1 + hstep, voffA);
;             PG8_WAIT_V(8); PG8_WAIT_L(0); PG8_BAR; PG8_MMA(0, 0, At, B0); PG8_MMA(0, 1, At, B1); PG8_BAR; PG8_SCHED;
;             PG8_LDA(At, 0, 1); PG8_STAGE(PG8_SB(0, 0), b2, voffB); PG8_STAGE(PG8_SB(0, 1), b2 + hstep, voffB); PG8_STAGE(PG8_SA(0, 0), a2, voffA);
;             PG8_WAIT_V(8); PG8_WAIT_L(0); PG8_BAR; PG8_MMA(1, 0, At, B0); PG8_MMA(1, 1, At, B1); PG8_BAR; PG8_SCHED;
	s_setprio 1
	s_waitcnt lgkmcnt(0)
	v_mfma_f32_16x16x32_bf16 v[124:127], v[144:147], v[184:187], v[124:127]
	v_mfma_f32_16x16x32_bf16 v[120:123], v[160:163], v[184:187], v[120:123]
	v_mfma_f32_16x16x32_bf16 v[108:111], v[144:147], v[192:195], v[108:111]
	v_mfma_f32_16x16x32_bf16 v[104:107], v[160:163], v[192:195], v[104:107]
	v_mfma_f32_16x16x32_bf16 v[92:95], v[144:147], v[200:203], v[92:95]
	v_mfma_f32_16x16x32_bf16 v[88:91], v[160:163], v[200:203], v[88:91]
	v_mfma_f32_16x16x32_bf16 v[76:79], v[144:147], v[210:213], v[76:79]
	v_mfma_f32_16x16x32_bf16 v[72:75], v[160:163], v[210:213], v[72:75]
	v_mfma_f32_16x16x32_bf16 v[124:127], v[148:151], v[188:191], v[124:127]
	v_mfma_f32_16x16x32_bf16 v[120:123], v[164:167], v[188:191], v[120:123]
	v_mfma_f32_16x16x32_bf16 v[108:111], v[148:151], v[196:199], v[108:111]
	v_mfma_f32_16x16x32_bf16 v[104:107], v[164:167], v[196:199], v[104:107]
	v_mfma_f32_16x16x32_bf16 v[92:95], v[148:151], v[206:209], v[92:95]
	v_mfma_f32_16x16x32_bf16 v[88:91], v[164:167], v[206:209], v[88:91]
	v_mfma_f32_16x16x32_bf16 v[76:79], v[148:151], v[214:217], v[76:79]
	v_mfma_f32_16x16x32_bf16 v[72:75], v[164:167], v[214:217], v[72:75]
	s_setprio 0
	s_setprio 1
	v_mfma_f32_16x16x32_bf16 v[116:119], v[168:171], v[184:187], v[116:119]
	v_mfma_f32_16x16x32_bf16 v[112:115], v[176:179], v[184:187], v[112:115]
	v_mfma_f32_16x16x32_bf16 v[100:103], v[168:171], v[192:195], v[100:103]
	v_mfma_f32_16x16x32_bf16 v[96:99], v[176:179], v[192:195], v[96:99]
	v_mfma_f32_16x16x32_bf16 v[84:87], v[168:171], v[200:203], v[84:87]
	v_mfma_f32_16x16x32_bf16 v[80:83], v[176:179], v[200:203], v[80:83]
	v_mfma_f32_16x16x32_bf16 v[68:71], v[168:171], v[210:213], v[68:71]
	v_mfma_f32_16x16x32_bf16 v[64:67], v[176:179], v[210:213], v[64:67]
	v_mfma_f32_16x16x32_bf16 v[116:119], v[172:175], v[188:191], v[116:119]
	v_mfma_f32_16x16x32_bf16 v[112:115], v[180:183], v[188:191], v[112:115]
	v_mfma_f32_16x16x32_bf16 v[100:103], v[172:175], v[196:199], v[100:103]
	v_mfma_f32_16x16x32_bf16 v[96:99], v[180:183], v[196:199], v[96:99]
	v_mfma_f32_16x16x32_bf16 v[84:87], v[172:175], v[206:209], v[84:87]
	v_mfma_f32_16x16x32_bf16 v[80:83], v[180:183], v[206:209], v[80:83]
	v_mfma_f32_16x16x32_bf16 v[68:71], v[172:175], v[214:217], v[68:71]
	v_mfma_f32_16x16x32_bf16 v[64:67], v[180:183], v[214:217], v[64:67]
	s_setprio 0
	s_barrier
	s_add_i32 s58, s49, s15
	v_lshl_add_u64 v[218:219], s[40:41], 0, v[132:133]
	s_mov_b32 m0, s58
	ds_read_b128 v[184:187], v157 offset:16384
	ds_read_b128 v[188:191], v157 offset:17408
	ds_read_b128 v[192:195], v157 offset:18432
	ds_read_b128 v[196:199], v157 offset:19456
	ds_read_b128 v[200:203], v157 offset:20480
	ds_read_b128 v[206:209], v157 offset:21504
	ds_read_b128 v[210:213], v157 offset:22528
	ds_read_b128 v[214:217], v157 offset:23552
	global_load_lds_dwordx4 v[218:219], off
	s_add_i32 m0, s58, 0x2000
	s_add_u32 s58, s40, 0x40000
	v_lshl_add_u64 v[220:221], s[40:41], 0, v[128:129]
	s_addc_u32 s59, s41, 0
	s_add_i32 s60, s50, s15
	global_load_lds_dwordx4 v[220:221], off
	v_lshl_add_u64 v[222:223], s[58:59], 0, v[132:133]
	s_mov_b32 m0, s60
	global_load_lds_dwordx4 v[222:223], off
	v_lshl_add_u64 v[222:223], s[58:59], 0, v[128:129]
	s_add_i32 m0, s60, 0x2000
	s_nop 0
	global_load_lds_dwordx4 v[222:223], off
	s_waitcnt vmcnt(6)
	s_waitcnt lgkmcnt(0)
	s_barrier
	s_setprio 1
	s_waitcnt lgkmcnt(0)
	v_mfma_f32_16x16x32_bf16 v[60:63], v[144:147], v[184:187], v[60:63]
	v_mfma_f32_16x16x32_bf16 v[56:59], v[160:163], v[184:187], v[56:59]
	v_mfma_f32_16x16x32_bf16 v[44:47], v[144:147], v[192:195], v[44:47]
	v_mfma_f32_16x16x32_bf16 v[40:43], v[160:163], v[192:195], v[40:43]
	v_mfma_f32_16x16x32_bf16 v[28:31], v[144:147], v[200:203], v[28:31]
	v_mfma_f32_16x16x32_bf16 v[24:27], v[160:163], v[200:203], v[24:27]
	v_mfma_f32_16x16x32_bf16 v[12:15], v[144:147], v[210:213], v[12:15]
	v_mfma_f32_16x16x32_bf16 v[8:11], v[160:163], v[210:213], v[8:11]
	v_mfma_f32_16x16x32_bf16 v[60:63], v[148:151], v[188:191], v[60:63]
	v_mfma_f32_16x16x32_bf16 v[56:59], v[164:167], v[188:191], v[56:59]
	v_mfma_f32_16x16x32_bf16 v[44:47], v[148:151], v[196:199], v[44:47]
	v_mfma_f32_16x16x32_bf16 v[40:43], v[164:167], v[196:199], v[40:43]
	v_mfma_f32_16x16x32_bf16 v[28:31], v[148:151], v[206:209], v[28:31]
	v_mfma_f32_16x16x32_bf16 v[24:27], v[164:167], v[206:209], v[24:27]
	v_lshl_add_u64 v[222:223], s[42:43], 0, v[134:135]
	s_mov_b32 m0, s34
	s_nop 0
	global_load_lds_dwordx4 v[222:223], off
	v_mfma_f32_16x16x32_bf16 v[12:15], v[148:151], v[214:217], v[12:15]
	v_mfma_f32_16x16x32_bf16 v[8:11], v[164:167], v[214:217], v[8:11]
	s_setprio 0
	s_setprio 1
	v_mfma_f32_16x16x32_bf16 v[52:55], v[168:171], v[184:187], v[52:55]
	v_mfma_f32_16x16x32_bf16 v[48:51], v[176:179], v[184:187], v[48:51]
	v_mfma_f32_16x16x32_bf16 v[36:39], v[168:171], v[192:195], v[36:39]
	v_mfma_f32_16x16x32_bf16 v[32:35], v[176:179], v[192:195], v[32:35]
	v_mfma_f32_16x16x32_bf16 v[20:23], v[168:171], v[200:203], v[20:23]
	v_mfma_f32_16x16x32_bf16 v[16:19], v[176:179], v[200:203], v[16:19]
	v_mfma_f32_16x16x32_bf16 v[4:7], v[168:171], v[210:213], v[4:7]
	v_mfma_f32_16x16x32_bf16 v[0:3], v[176:179], v[210:213], v[0:3]
	v_mfma_f32_16x16x32_bf16 v[52:55], v[172:175], v[188:191], v[52:55]
	v_mfma_f32_16x16x32_bf16 v[48:51], v[180:183], v[188:191], v[48:51]
	v_mfma_f32_16x16x32_bf16 v[36:39], v[172:175], v[196:199], v[36:39]
	v_mfma_f32_16x16x32_bf16 v[32:35], v[180:183], v[196:199], v[32:35]
	v_mfma_f32_16x16x32_bf16 v[20:23], v[172:175], v[206:209], v[20:23]
	v_mfma_f32_16x16x32_bf16 v[16:19], v[180:183], v[206:209], v[16:19]
	v_lshl_add_u64 v[224:225], s[42:43], 0, v[130:131]
	s_mov_b32 m0, s37
	s_nop 0
	global_load_lds_dwordx4 v[224:225], off
	v_mfma_f32_16x16x32_bf16 v[4:7], v[172:175], v[214:217], v[4:7]
	v_mfma_f32_16x16x32_bf16 v[0:3], v[180:183], v[214:217], v[0:3]
	s_setprio 0
	s_barrier
; #define PG8_STAGE(bufoff, gbase, voff) do { _Pragma("unroll") for (int _i = 0; _i < 2; ++_i) \
;         __builtin_amdgcn_global_load_lds((const unsigned*)((const char*)(gbase) + (voff)[_i]), (PG8_LAS unsigned*)(lds + (bufoff) + ldsw + _i * 8192), 16, 0, 0); } while (0)
; #define PG8_LDA(dst, b, h) do { _Pragma("unroll") for (int m = 0; m < 4; ++m) _Pragma("unroll") for (int k = 0; k < 2; ++k) dst[m][k] = *(const PG8_LAS bf16x8*)(lds + PG8_SA(b, h) + aoff + m * 2048 + k * 1024); } while (0)
; #define PG8_LDB(dst, b, h) do { _Pragma("unroll") for (int n = 0; n < 2; ++n) _Pragma("unroll") for (int k = 0; k < 2; ++k) dst[n][k] = *(const PG8_LAS bf16x8*)(lds + PG8_SB(b, h) + boff + n * 2048 + k * 1024); } while (0)
; #define PG8_MMA(ai, bj, At, Bt) do { __builtin_amdgcn_s_setprio(1); _Pragma("unroll") for (int m = 0; m < 4; ++m) _Pragma("unroll") for (int n = 0; n < 2; ++n) _Pragma("unroll") for (int k = 0; k < 2; ++k) \
;         acc[ai][bj][m][n] = __builtin_amdgcn_mfma_f32_16x16x32_bf16(Bt[n][k], At[m][k], acc[ai][bj][m][n], 0, 0, 0); __builtin_amdgcn_s_setprio(0); } while (0)
; #define PG8_WAIT_V(n) asm volatile("s_waitcnt vmcnt(" #n ")" ::: "memory")
; #define PG8_WAIT_L(n) asm volatile("s_waitcnt lgkmcnt(" #n ")" ::: "memory")
; #define PG8_BAR __builtin_amdgcn_s_barrier()
; #define PG8_SCHED __builtin_amdgcn_sched_barrier(0)
; template <class Epi, class Sched, bool ALIGN_EPI = false, bool SP2 = false>
; __device__ __forceinline__ void gemm_phase(PG8_LAS unsigned char* lds, const Gemm g, const Sched& S, const Epi& E) {
;     ...
;             PG8_LDB(B0, 1, 0); PG8_LDB(B1, 1, 1); PG8_SCHED; PG8_LDA(At, 1, 0); PG8_STAGE(PG8_SA(0, 1), a2 + hstep, voffA);
;             PG8_WAIT_V(8); PG8_WAIT_L(0); PG8_BAR; PG8_MMA(0, 0, At, B0); PG8_MMA(0, 1, At, B1); PG8_BAR; PG8_SCHED;
	s_add_i32 s58, 0, 0x18000
	v_add_u32_e32 v159, s58, v153
	s_add_i32 s59, 0, 0x1c000
	ds_read_b128 v[144:147], v159
	ds_read_b128 v[148:151], v159 offset:1024
	ds_read_b128 v[160:163], v159 offset:2048
	ds_read_b128 v[164:167], v159 offset:3072
	v_add_u32_e32 v159, s59, v153
	ds_read_b128 v[168:171], v159
	ds_read_b128 v[172:175], v159 offset:1024
	ds_read_b128 v[176:179], v159 offset:2048
	ds_read_b128 v[180:183], v159 offset:3072
	s_add_u32 s42, s42, 0x40000
	s_addc_u32 s43, s43, 0
	s_mov_b32 m0, s44
	v_lshl_add_u64 v[226:227], s[42:43], 0, v[134:135]
	ds_read_b128 v[184:187], v157 offset:32768
	ds_read_b128 v[188:191], v157 offset:33792
	ds_read_b128 v[192:195], v157 offset:34816
	ds_read_b128 v[196:199], v157 offset:35840
	ds_read_b128 v[200:203], v157 offset:36864
	ds_read_b128 v[206:209], v157 offset:37888
	ds_read_b128 v[210:213], v157 offset:38912
	ds_read_b128 v[214:217], v157 offset:39936
	global_load_lds_dwordx4 v[226:227], off
	v_lshl_add_u64 v[226:227], s[42:43], 0, v[130:131]
	s_mov_b32 m0, s45
	s_nop 0
	global_load_lds_dwordx4 v[226:227], off
	s_waitcnt vmcnt(8)
	s_waitcnt lgkmcnt(0)
	s_barrier
	s_setprio 1
	s_waitcnt lgkmcnt(0)
	v_mfma_f32_16x16x32_bf16 v[124:127], v[144:147], v[184:187], v[124:127]
	v_mfma_f32_16x16x32_bf16 v[120:123], v[160:163], v[184:187], v[120:123]
	v_mfma_f32_16x16x32_bf16 v[108:111], v[144:147], v[192:195], v[108:111]
	v_mfma_f32_16x16x32_bf16 v[104:107], v[160:163], v[192:195], v[104:107]
	v_mfma_f32_16x16x32_bf16 v[92:95], v[144:147], v[200:203], v[92:95]
	v_mfma_f32_16x16x32_bf16 v[88:91], v[160:163], v[200:203], v[88:91]
	v_mfma_f32_16x16x32_bf16 v[76:79], v[144:147], v[210:213], v[76:79]
	v_mfma_f32_16x16x32_bf16 v[72:75], v[160:163], v[210:213], v[72:75]
	v_mfma_f32_16x16x32_bf16 v[124:127], v[148:151], v[188:191], v[124:127]
	v_mfma_f32_16x16x32_bf16 v[120:123], v[164:167], v[188:191], v[120:123]
	v_mfma_f32_16x16x32_bf16 v[108:111], v[148:151], v[196:199], v[108:111]
	v_mfma_f32_16x16x32_bf16 v[104:107], v[164:167], v[196:199], v[104:107]
	v_mfma_f32_16x16x32_bf16 v[92:95], v[148:151], v[206:209], v[92:95]
	v_mfma_f32_16x16x32_bf16 v[88:91], v[164:167], v[206:209], v[88:91]
	v_mfma_f32_16x16x32_bf16 v[76:79], v[148:151], v[214:217], v[76:79]
	v_mfma_f32_16x16x32_bf16 v[72:75], v[164:167], v[214:217], v[72:75]
	s_setprio 0
	s_setprio 1
	v_mfma_f32_16x16x32_bf16 v[116:119], v[168:171], v[184:187], v[116:119]
	v_mfma_f32_16x16x32_bf16 v[112:115], v[176:179], v[184:187], v[112:115]
	v_mfma_f32_16x16x32_bf16 v[100:103], v[168:171], v[192:195], v[100:103]
	v_mfma_f32_16x16x32_bf16 v[96:99], v[176:179], v[192:195], v[96:99]
	v_mfma_f32_16x16x32_bf16 v[84:87], v[168:171], v[200:203], v[84:87]
	v_mfma_f32_16x16x32_bf16 v[80:83], v[176:179], v[200:203], v[80:83]
	v_mfma_f32_16x16x32_bf16 v[68:71], v[168:171], v[210:213], v[68:71]
	v_mfma_f32_16x16x32_bf16 v[64:67], v[176:179], v[210:213], v[64:67]
	v_mfma_f32_16x16x32_bf16 v[116:119], v[172:175], v[188:191], v[116:119]
	v_mfma_f32_16x16x32_bf16 v[112:115], v[180:183], v[188:191], v[112:115]
	v_mfma_f32_16x16x32_bf16 v[100:103], v[172:175], v[196:199], v[100:103]
	v_mfma_f32_16x16x32_bf16 v[96:99], v[180:183], v[196:199], v[96:99]
	v_mfma_f32_16x16x32_bf16 v[84:87], v[172:175], v[206:209], v[84:87]
	v_mfma_f32_16x16x32_bf16 v[80:83], v[180:183], v[206:209], v[80:83]
	v_mfma_f32_16x16x32_bf16 v[68:71], v[172:175], v[214:217], v[68:71]
	v_mfma_f32_16x16x32_bf16 v[64:67], v[180:183], v[214:217], v[64:67]
	s_setprio 0
	s_barrier
; #define PG8_STAGE(bufoff, gbase, voff) do { _Pragma("unroll") for (int _i = 0; _i < 2; ++_i) \
;         __builtin_amdgcn_global_load_lds((const unsigned*)((const char*)(gbase) + (voff)[_i]), (PG8_LAS unsigned*)(lds + (bufoff) + ldsw + _i * 8192), 16, 0, 0); } while (0)
; #define PG8_LDA(dst, b, h) do { _Pragma("unroll") for (int m = 0; m < 4; ++m) _Pragma("unroll") for (int k = 0; k < 2; ++k) dst[m][k] = *(const PG8_LAS bf16x8*)(lds + PG8_SA(b, h) + aoff + m * 2048 + k * 1024); } while (0)
; #define PG8_MMA(ai, bj, At, Bt) do { __builtin_amdgcn_s_setprio(1); _Pragma("unroll") for (int m = 0; m < 4; ++m) _Pragma("unroll") for (int n = 0; n < 2; ++n) _Pragma("unroll") for (int k = 0; k < 2; ++k) \
;         acc[ai][bj][m][n] = __builtin_amdgcn_mfma_f32_16x16x32_bf16(Bt[n][k], At[m][k], acc[ai][bj][m][n], 0, 0, 0); __builtin_amdgcn_s_setprio(0); } while (0)
; #define PG8_WAIT_V(n) asm volatile("s_waitcnt vmcnt(" #n ")" ::: "memory")
; #define PG8_WAIT_L(n) asm volatile("s_waitcnt lgkmcnt(" #n ")" ::: "memory")
; #define PG8_BAR __builtin_amdgcn_s_barrier()
; #define PG8_SCHED __builtin_amdgcn_sched_barrier(0)
;     __device__ __forceinline__ void operator()(const f32x4 (&acc)[2][2][4][2], const Unit& u, int wr, int wc, int fr, int fq) const {
;     ...
;             for (int m = 0; m < 4; ++m) { const int row = row0 + ai * HALF + m * 16; const float rs = row_rs(ss, row);
; template <class Epi, class Sched, bool ALIGN_EPI = false, bool SP2 = false>
; __device__ __forceinline__ void gemm_phase(PG8_LAS unsigned char* lds, const Gemm g, const Sched& S, const Epi& E) {
;     ...
;             PG8_WAIT_V(8); PG8_WAIT_L(0); PG8_BAR; PG8_MMA(0, 0, At, B0); PG8_MMA(0, 1, At, B1); PG8_BAR; PG8_SCHED;
;             PG8_LDA(At, 1, 1); PG8_STAGE(PG8_SB(1, 0), b3, voffB); PG8_STAGE(PG8_SB(1, 1), b3 + hstep, voffB); PG8_STAGE(PG8_SA(1, 0), a3, voffA);
;             PG8_WAIT_V(8); PG8_WAIT_L(0); PG8_BAR; PG8_MMA(1, 0, At, B0); PG8_MMA(1, 1, At, B1); PG8_BAR; PG8_SCHED;
;     ...
;         if constexpr (ALIGN_EPI) { if (wr == 0) PG8_BAR; }
;         if constexpr (!Epi::AFTER_DRAIN) { E(acc, cur, wr, wc, fr, fq); S.done(cur); }
	s_add_i32 s42, s58, s15
	v_lshl_add_u64 v[218:219], v[218:219], 0, s[8:9]
	s_mov_b32 m0, s42
	ds_read_b128 v[184:187], v157 offset:49152
	ds_read_b128 v[188:191], v157 offset:50176
	ds_read_b128 v[192:195], v157 offset:51200
	ds_read_b128 v[196:199], v157 offset:52224
	ds_read_b128 v[200:203], v157 offset:53248
	ds_read_b128 v[206:209], v157 offset:54272
	ds_read_b128 v[210:213], v157 offset:55296
	ds_read_b128 v[214:217], v157 offset:56320
	global_load_lds_dwordx4 v[218:219], off
	s_add_i32 m0, s42, 0x2000
	s_add_u32 s40, s40, 0x40080
	v_lshl_add_u64 v[218:219], v[220:221], 0, s[8:9]
	s_addc_u32 s41, s41, 0
	s_add_i32 s42, s59, s15
	global_load_lds_dwordx4 v[218:219], off
	v_lshl_add_u64 v[218:219], s[40:41], 0, v[132:133]
	s_mov_b32 m0, s42
	s_nop 0
	global_load_lds_dwordx4 v[218:219], off
	v_lshl_add_u64 v[218:219], s[40:41], 0, v[128:129]
	s_add_i32 m0, s42, 0x2000
	s_nop 0
	global_load_lds_dwordx4 v[218:219], off
	s_waitcnt vmcnt(6)
	s_waitcnt lgkmcnt(0)
	s_barrier
	s_setprio 1
	s_waitcnt lgkmcnt(0)
	v_mfma_f32_16x16x32_bf16 v[60:63], v[144:147], v[184:187], v[60:63]
	v_mfma_f32_16x16x32_bf16 v[56:59], v[160:163], v[184:187], v[56:59]
	v_mfma_f32_16x16x32_bf16 v[44:47], v[144:147], v[192:195], v[44:47]
	v_mfma_f32_16x16x32_bf16 v[40:43], v[160:163], v[192:195], v[40:43]
	v_mfma_f32_16x16x32_bf16 v[28:31], v[144:147], v[200:203], v[28:31]
	v_mfma_f32_16x16x32_bf16 v[24:27], v[160:163], v[200:203], v[24:27]
	v_mfma_f32_16x16x32_bf16 v[12:15], v[144:147], v[210:213], v[12:15]
	v_mfma_f32_16x16x32_bf16 v[8:11], v[160:163], v[210:213], v[8:11]
	v_mfma_f32_16x16x32_bf16 v[60:63], v[148:151], v[188:191], v[60:63]
	v_mfma_f32_16x16x32_bf16 v[56:59], v[164:167], v[188:191], v[56:59]
	v_mfma_f32_16x16x32_bf16 v[44:47], v[148:151], v[196:199], v[44:47]
	v_mfma_f32_16x16x32_bf16 v[40:43], v[164:167], v[196:199], v[40:43]
	v_mfma_f32_16x16x32_bf16 v[28:31], v[148:151], v[206:209], v[28:31]
	v_mfma_f32_16x16x32_bf16 v[24:27], v[164:167], v[206:209], v[24:27]
	v_lshl_add_u64 v[218:219], v[222:223], 0, s[8:9]
	s_mov_b32 m0, s47
	s_nop 0
	global_load_lds_dwordx4 v[218:219], off
	v_mfma_f32_16x16x32_bf16 v[12:15], v[148:151], v[214:217], v[12:15]
	v_mfma_f32_16x16x32_bf16 v[8:11], v[164:167], v[214:217], v[8:11]
	s_setprio 0
	s_setprio 1
	v_mfma_f32_16x16x32_bf16 v[52:55], v[168:171], v[184:187], v[52:55]
	v_mfma_f32_16x16x32_bf16 v[48:51], v[176:179], v[184:187], v[48:51]
	v_mfma_f32_16x16x32_bf16 v[36:39], v[168:171], v[192:195], v[36:39]
	v_mfma_f32_16x16x32_bf16 v[32:35], v[176:179], v[192:195], v[32:35]
	v_mfma_f32_16x16x32_bf16 v[20:23], v[168:171], v[200:203], v[20:23]
	v_mfma_f32_16x16x32_bf16 v[16:19], v[176:179], v[200:203], v[16:19]
	v_mfma_f32_16x16x32_bf16 v[4:7], v[168:171], v[210:213], v[4:7]
	v_mfma_f32_16x16x32_bf16 v[0:3], v[176:179], v[210:213], v[0:3]
	v_mfma_f32_16x16x32_bf16 v[52:55], v[172:175], v[188:191], v[52:55]
	v_mfma_f32_16x16x32_bf16 v[48:51], v[180:183], v[188:191], v[48:51]
	v_mfma_f32_16x16x32_bf16 v[36:39], v[172:175], v[196:199], v[36:39]
	v_mfma_f32_16x16x32_bf16 v[32:35], v[180:183], v[196:199], v[32:35]
	v_mfma_f32_16x16x32_bf16 v[20:23], v[172:175], v[206:209], v[20:23]
	v_mfma_f32_16x16x32_bf16 v[16:19], v[180:183], v[206:209], v[16:19]
	v_lshl_add_u64 v[218:219], v[224:225], 0, s[8:9]
	s_mov_b32 m0, s48
	s_nop 0
	global_load_lds_dwordx4 v[218:219], off
	v_mfma_f32_16x16x32_bf16 v[4:7], v[172:175], v[214:217], v[4:7]
	v_mfma_f32_16x16x32_bf16 v[0:3], v[180:183], v[214:217], v[0:3]
	s_setprio 0
	s_barrier
	s_add_i32 s57, s57, 2
	s_add_u32 s38, s38, 0x100
	s_addc_u32 s39, s39, 0
	s_add_u32 s55, s55, 0x100
	s_addc_u32 s56, s56, 0
	s_cmp_gt_u32 s57, 13
	s_cbranch_scc0 .LBB0_1900
	v_lshl_add_u32 v144, s36, 8, v152
	v_ashrrev_i32_e32 v145, 31, v144
	v_lshl_add_u64 v[150:151], v[144:145], 3, s[0:1]
	global_load_dwordx2 v[182:183], v[150:151], off
	global_load_dwordx2 v[184:185], v[150:151], off offset:128
	global_load_dwordx2 v[186:187], v[150:151], off offset:256
	global_load_dwordx2 v[188:189], v[150:151], off offset:384
	global_load_dwordx2 v[190:191], v[150:151], off offset:1024
	global_load_dwordx2 v[192:193], v[150:151], off offset:1152
	global_load_dwordx2 v[194:195], v[150:151], off offset:1280
	global_load_dwordx2 v[196:197], v[150:151], off offset:1408
	s_and_b64 vcc, exec, s[10:11]
	s_cbranch_vccz .LBB0_1903
	s_barrier

; #define PG8_STAGE(bufoff, gbase, voff) do { _Pragma("unroll") for (int _i = 0; _i < 2; ++_i) \
;         __builtin_amdgcn_global_load_lds((const unsigned*)((const char*)(gbase) + (voff)[_i]), (PG8_LAS unsigned*)(lds + (bufoff) + ldsw + _i * 8192), 16, 0, 0); } while (0)
; #define PG8_LDA(dst, b, h) do { _Pragma("unroll") for (int m = 0; m < 4; ++m) _Pragma("unroll") for (int k = 0; k < 2; ++k) dst[m][k] = *(const PG8_LAS bf16x8*)(lds + PG8_SA(b, h) + aoff + m * 2048 + k * 1024); } while (0)
; #define PG8_LDB(dst, b, h) do { _Pragma("unroll") for (int n = 0; n < 2; ++n) _Pragma("unroll") for (int k = 0; k < 2; ++k) dst[n][k] = *(const PG8_LAS bf16x8*)(lds + PG8_SB(b, h) + boff + n * 2048 + k * 1024); } while (0)
; #define PG8_MMA(ai, bj, At, Bt) do { __builtin_amdgcn_s_setprio(1); _Pragma("unroll") for (int m = 0; m < 4; ++m) _Pragma("unroll") for (int n = 0; n < 2; ++n) _Pragma("unroll") for (int k = 0; k < 2; ++k) \
;         acc[ai][bj][m][n] = __builtin_amdgcn_mfma_f32_16x16x32_bf16(Bt[n][k], At[m][k], acc[ai][bj][m][n], 0, 0, 0); __builtin_amdgcn_s_setprio(0); } while (0)
; #define PG8_WAIT_V(n) asm volatile("s_waitcnt vmcnt(" #n ")" ::: "memory")
; #define PG8_BAR __builtin_amdgcn_s_barrier()
; template <class Epi, class Sched, bool ALIGN_EPI = false, bool SP2 = false>
; __device__ __forceinline__ void gemm_phase(PG8_LAS unsigned char* lds, const Gemm g, const Sched& S, const Epi& E) {
;     ...
;         for (int t = 0; t < nt; t += 2) {
;             const bool last = (t == nt - 2);
;             const char* a1 = cA + (size_t)(t + 1) * kstep;
;             const char* a2 = last ? nA : cA + (size_t)(t + 2) * kstep; const char* b2 = last ? nB : cB + (size_t)(t + 2) * kstep;
;             const char* a3 = a2 + kstep; const char* b3 = b2 + kstep;
;             if (last && has_next) S.a_ready(nxt);
;             if constexpr (SP2) {
;             PG8_LDB(B0, 0, 0); PG8_LDB(B1, 0, 1); PG8_SCHED; PG8_LDA(At, 0, 0); PG8_STAGE(PG8_SA(1, 1), a1 + hstep, voffA);
;             PG8_WAIT_V(8); PG8_WAIT_L(0); PG8_BAR; PG8_MMA(0, 0, At, B0); PG8_MMA(0, 1, At, B1); PG8_BAR; PG8_SCHED;
;             PG8_LDA(At, 0, 1); PG8_STAGE(PG8_SB(0, 0), b2, voffB); PG8_STAGE(PG8_SB(0, 1), b2 + hstep, voffB); PG8_STAGE(PG8_SA(0, 0), a2, voffA);
;             PG8_WAIT_V(8); PG8_WAIT_L(0); PG8_BAR; PG8_MMA(1, 0, At, B0); PG8_MMA(1, 1, At, B1); PG8_BAR; PG8_SCHED;
.LBB0_1977:
	s_add_u32 s53, s28, 0x100
	s_addc_u32 s54, s29, 0
	s_mov_b32 s55, -2
	s_waitcnt lgkmcnt(0)
	ds_read_b128 v[144:147], v151
	ds_read_b128 v[156:159], v151 offset:1024
	ds_read_b128 v[160:163], v151 offset:2048
	ds_read_b128 v[164:167], v151 offset:3072
	ds_read_b128 v[168:171], v152
	ds_read_b128 v[172:175], v152 offset:1024
	ds_read_b128 v[176:179], v152 offset:2048
	ds_read_b128 v[180:183], v152 offset:3072
	s_add_u32 s28, s26, 0x100
	s_addc_u32 s29, s27, 0
	s_cmp_eq_u32 s55, 40
	s_cselect_b32 s39, s1, s29
	s_cselect_b32 s38, s0, s28
	s_cselect_b32 s37, s25, s54
	s_cselect_b32 s36, s24, s53
	v_lshl_add_u64 v[218:219], s[26:27], 0, v[136:137]
	s_add_i32 m0, s33, 0xc000
	ds_read_b128 v[184:187], v153
	ds_read_b128 v[188:191], v153 offset:1024
	ds_read_b128 v[192:195], v153 offset:2048
	ds_read_b128 v[196:199], v153 offset:3072
	ds_read_b128 v[200:203], v153 offset:4096
	ds_read_b128 v[206:209], v153 offset:5120
	ds_read_b128 v[210:213], v153 offset:6144
	ds_read_b128 v[214:217], v153 offset:7168
	global_load_lds_dwordx4 v[218:219], off
	v_lshl_add_u64 v[218:219], s[26:27], 0, v[138:139]
	s_add_i32 m0, s33, 0xe000
	s_nop 0
	global_load_lds_dwordx4 v[218:219], off
	s_waitcnt vmcnt(8)
	s_waitcnt lgkmcnt(0)
	s_barrier
	s_setprio 1
	s_waitcnt lgkmcnt(0)
	v_mfma_f32_16x16x32_bf16 v[124:127], v[144:147], v[184:187], 0
	v_mfma_f32_16x16x32_bf16 v[120:123], v[160:163], v[184:187], 0
	v_mfma_f32_16x16x32_bf16 v[108:111], v[144:147], v[192:195], 0
	v_mfma_f32_16x16x32_bf16 v[104:107], v[160:163], v[192:195], 0
	v_mfma_f32_16x16x32_bf16 v[92:95], v[144:147], v[200:203], 0
	v_mfma_f32_16x16x32_bf16 v[88:91], v[160:163], v[200:203], 0
	v_mfma_f32_16x16x32_bf16 v[76:79], v[144:147], v[210:213], 0
	v_mfma_f32_16x16x32_bf16 v[72:75], v[160:163], v[210:213], 0
	v_mfma_f32_16x16x32_bf16 v[124:127], v[156:159], v[188:191], v[124:127]
	v_mfma_f32_16x16x32_bf16 v[120:123], v[164:167], v[188:191], v[120:123]
	v_mfma_f32_16x16x32_bf16 v[108:111], v[156:159], v[196:199], v[108:111]
	v_mfma_f32_16x16x32_bf16 v[104:107], v[164:167], v[196:199], v[104:107]
	v_mfma_f32_16x16x32_bf16 v[92:95], v[156:159], v[206:209], v[92:95]
	v_mfma_f32_16x16x32_bf16 v[88:91], v[164:167], v[206:209], v[88:91]
	v_mfma_f32_16x16x32_bf16 v[76:79], v[156:159], v[214:217], v[76:79]
	v_mfma_f32_16x16x32_bf16 v[72:75], v[164:167], v[214:217], v[72:75]
	s_setprio 0
	s_setprio 1
	v_mfma_f32_16x16x32_bf16 v[116:119], v[168:171], v[184:187], 0
	v_mfma_f32_16x16x32_bf16 v[112:115], v[176:179], v[184:187], 0
	v_mfma_f32_16x16x32_bf16 v[100:103], v[168:171], v[192:195], 0
	v_mfma_f32_16x16x32_bf16 v[96:99], v[176:179], v[192:195], 0
	v_mfma_f32_16x16x32_bf16 v[84:87], v[168:171], v[200:203], 0
	v_mfma_f32_16x16x32_bf16 v[80:83], v[176:179], v[200:203], 0
	v_mfma_f32_16x16x32_bf16 v[68:71], v[168:171], v[210:213], 0
	v_mfma_f32_16x16x32_bf16 v[64:67], v[176:179], v[210:213], 0
	v_mfma_f32_16x16x32_bf16 v[116:119], v[172:175], v[188:191], v[116:119]
	v_mfma_f32_16x16x32_bf16 v[112:115], v[180:183], v[188:191], v[112:115]
	v_mfma_f32_16x16x32_bf16 v[100:103], v[172:175], v[196:199], v[100:103]
	v_mfma_f32_16x16x32_bf16 v[96:99], v[180:183], v[196:199], v[96:99]
	v_mfma_f32_16x16x32_bf16 v[84:87], v[172:175], v[206:209], v[84:87]
	v_mfma_f32_16x16x32_bf16 v[80:83], v[180:183], v[206:209], v[80:83]
	v_mfma_f32_16x16x32_bf16 v[68:71], v[172:175], v[214:217], v[68:71]
	v_mfma_f32_16x16x32_bf16 v[64:67], v[180:183], v[214:217], v[64:67]
	s_setprio 0
	s_barrier
	s_add_i32 s26, s45, s15
	v_lshl_add_u64 v[218:219], s[36:37], 0, v[130:131]
	s_mov_b32 m0, s26
	ds_read_b128 v[184:187], v153 offset:16384
	ds_read_b128 v[188:191], v153 offset:17408
	ds_read_b128 v[192:195], v153 offset:18432
	ds_read_b128 v[196:199], v153 offset:19456
	ds_read_b128 v[200:203], v153 offset:20480
	ds_read_b128 v[206:209], v153 offset:21504
	ds_read_b128 v[210:213], v153 offset:22528
	ds_read_b128 v[214:217], v153 offset:23552
	global_load_lds_dwordx4 v[218:219], off
	s_add_i32 m0, s26, 0x2000
	s_add_u32 s26, s36, 0xb0000
	v_lshl_add_u64 v[220:221], s[36:37], 0, v[134:135]
	s_addc_u32 s27, s37, 0
	s_add_i32 s56, s46, s15
	global_load_lds_dwordx4 v[220:221], off
	v_lshl_add_u64 v[222:223], s[26:27], 0, v[130:131]
	s_mov_b32 m0, s56
	global_load_lds_dwordx4 v[222:223], off
	v_lshl_add_u64 v[222:223], s[26:27], 0, v[134:135]
	s_add_i32 m0, s56, 0x2000
	s_nop 0
	global_load_lds_dwordx4 v[222:223], off
	s_waitcnt vmcnt(6)
	s_waitcnt lgkmcnt(0)
	s_barrier
; #define PG8_STAGE(bufoff, gbase, voff) do { _Pragma("unroll") for (int _i = 0; _i < 2; ++_i) \
;         __builtin_amdgcn_global_load_lds((const unsigned*)((const char*)(gbase) + (voff)[_i]), (PG8_LAS unsigned*)(lds + (bufoff) + ldsw + _i * 8192), 16, 0, 0); } while (0)
; #define PG8_LDA(dst, b, h) do { _Pragma("unroll") for (int m = 0; m < 4; ++m) _Pragma("unroll") for (int k = 0; k < 2; ++k) dst[m][k] = *(const PG8_LAS bf16x8*)(lds + PG8_SA(b, h) + aoff + m * 2048 + k * 1024); } while (0)
; #define PG8_LDB(dst, b, h) do { _Pragma("unroll") for (int n = 0; n < 2; ++n) _Pragma("unroll") for (int k = 0; k < 2; ++k) dst[n][k] = *(const PG8_LAS bf16x8*)(lds + PG8_SB(b, h) + boff + n * 2048 + k * 1024); } while (0)
; #define PG8_MMA(ai, bj, At, Bt) do { __builtin_amdgcn_s_setprio(1); _Pragma("unroll") for (int m = 0; m < 4; ++m) _Pragma("unroll") for (int n = 0; n < 2; ++n) _Pragma("unroll") for (int k = 0; k < 2; ++k) \
;         acc[ai][bj][m][n] = __builtin_amdgcn_mfma_f32_16x16x32_bf16(Bt[n][k], At[m][k], acc[ai][bj][m][n], 0, 0, 0); __builtin_amdgcn_s_setprio(0); } while (0)
; #define PG8_WAIT_V(n) asm volatile("s_waitcnt vmcnt(" #n ")" ::: "memory")
; #define PG8_WAIT_L(n) asm volatile("s_waitcnt lgkmcnt(" #n ")" ::: "memory")
; #define PG8_BAR __builtin_amdgcn_s_barrier()
; #define PG8_SCHED __builtin_amdgcn_sched_barrier(0)
; template <class Epi, class Sched, bool ALIGN_EPI = false, bool SP2 = false>
; __device__ __forceinline__ void gemm_phase(PG8_LAS unsigned char* lds, const Gemm g, const Sched& S, const Epi& E) {
;     ...
;             PG8_LDA(At, 0, 1); PG8_STAGE(PG8_SB(0, 0), b2, voffB); PG8_STAGE(PG8_SB(0, 1), b2 + hstep, voffB); PG8_STAGE(PG8_SA(0, 0), a2, voffA);
;             PG8_WAIT_V(8); PG8_WAIT_L(0); PG8_BAR; PG8_MMA(1, 0, At, B0); PG8_MMA(1, 1, At, B1); PG8_BAR; PG8_SCHED;
;             PG8_LDB(B0, 1, 0); PG8_LDB(B1, 1, 1); PG8_SCHED; PG8_LDA(At, 1, 0); PG8_STAGE(PG8_SA(0, 1), a2 + hstep, voffA);
;             PG8_WAIT_V(8); PG8_WAIT_L(0); PG8_BAR; PG8_MMA(0, 0, At, B0); PG8_MMA(0, 1, At, B1); PG8_BAR; PG8_SCHED;
	s_setprio 1
	s_waitcnt lgkmcnt(0)
	v_mfma_f32_16x16x32_bf16 v[60:63], v[144:147], v[184:187], 0
	v_mfma_f32_16x16x32_bf16 v[56:59], v[160:163], v[184:187], 0
	v_mfma_f32_16x16x32_bf16 v[44:47], v[144:147], v[192:195], 0
	v_mfma_f32_16x16x32_bf16 v[40:43], v[160:163], v[192:195], 0
	v_mfma_f32_16x16x32_bf16 v[28:31], v[144:147], v[200:203], 0
	v_mfma_f32_16x16x32_bf16 v[24:27], v[160:163], v[200:203], 0
	v_mfma_f32_16x16x32_bf16 v[12:15], v[144:147], v[210:213], 0
	v_mfma_f32_16x16x32_bf16 v[8:11], v[160:163], v[210:213], 0
	v_mfma_f32_16x16x32_bf16 v[60:63], v[156:159], v[188:191], v[60:63]
	v_mfma_f32_16x16x32_bf16 v[56:59], v[164:167], v[188:191], v[56:59]
	v_mfma_f32_16x16x32_bf16 v[44:47], v[156:159], v[196:199], v[44:47]
	v_mfma_f32_16x16x32_bf16 v[40:43], v[164:167], v[196:199], v[40:43]
	v_mfma_f32_16x16x32_bf16 v[28:31], v[156:159], v[206:209], v[28:31]
	v_mfma_f32_16x16x32_bf16 v[24:27], v[164:167], v[206:209], v[24:27]
	v_lshl_add_u64 v[222:223], s[38:39], 0, v[128:129]
	s_mov_b32 m0, s33
	s_nop 0
	global_load_lds_dwordx4 v[222:223], off
	v_mfma_f32_16x16x32_bf16 v[12:15], v[156:159], v[214:217], v[12:15]
	v_mfma_f32_16x16x32_bf16 v[8:11], v[164:167], v[214:217], v[8:11]
	s_setprio 0
	s_setprio 1
	v_mfma_f32_16x16x32_bf16 v[52:55], v[168:171], v[184:187], 0
	v_mfma_f32_16x16x32_bf16 v[48:51], v[176:179], v[184:187], 0
	v_mfma_f32_16x16x32_bf16 v[36:39], v[168:171], v[192:195], 0
	v_mfma_f32_16x16x32_bf16 v[32:35], v[176:179], v[192:195], 0
	v_mfma_f32_16x16x32_bf16 v[20:23], v[168:171], v[200:203], 0
	v_mfma_f32_16x16x32_bf16 v[16:19], v[176:179], v[200:203], 0
	v_mfma_f32_16x16x32_bf16 v[4:7], v[168:171], v[210:213], 0
	v_mfma_f32_16x16x32_bf16 v[0:3], v[176:179], v[210:213], 0
	v_mfma_f32_16x16x32_bf16 v[52:55], v[172:175], v[188:191], v[52:55]
	v_mfma_f32_16x16x32_bf16 v[48:51], v[180:183], v[188:191], v[48:51]
	v_mfma_f32_16x16x32_bf16 v[36:39], v[172:175], v[196:199], v[36:39]
	v_mfma_f32_16x16x32_bf16 v[32:35], v[180:183], v[196:199], v[32:35]
	v_mfma_f32_16x16x32_bf16 v[20:23], v[172:175], v[206:209], v[20:23]
	v_mfma_f32_16x16x32_bf16 v[16:19], v[180:183], v[206:209], v[16:19]
	v_lshl_add_u64 v[224:225], s[38:39], 0, v[132:133]
	s_mov_b32 m0, s34
	s_nop 0
	global_load_lds_dwordx4 v[224:225], off
	v_mfma_f32_16x16x32_bf16 v[4:7], v[172:175], v[214:217], v[4:7]
	v_mfma_f32_16x16x32_bf16 v[0:3], v[180:183], v[214:217], v[0:3]
	s_setprio 0
	s_barrier
	s_add_i32 s56, 0, 0x18000
	v_add_u32_e32 v155, s56, v149
	s_add_i32 s57, 0, 0x1c000
	ds_read_b128 v[144:147], v155
	ds_read_b128 v[156:159], v155 offset:1024
	ds_read_b128 v[160:163], v155 offset:2048
	ds_read_b128 v[164:167], v155 offset:3072
	v_add_u32_e32 v155, s57, v149
	ds_read_b128 v[168:171], v155
	ds_read_b128 v[172:175], v155 offset:1024
	ds_read_b128 v[176:179], v155 offset:2048
	ds_read_b128 v[180:183], v155 offset:3072
	s_add_u32 s26, s38, 0xb0000
	s_addc_u32 s27, s39, 0
	s_mov_b32 m0, s40
	v_lshl_add_u64 v[226:227], s[26:27], 0, v[128:129]
	ds_read_b128 v[184:187], v153 offset:32768
	ds_read_b128 v[188:191], v153 offset:33792
	ds_read_b128 v[192:195], v153 offset:34816
	ds_read_b128 v[196:199], v153 offset:35840
	ds_read_b128 v[200:203], v153 offset:36864
	ds_read_b128 v[206:209], v153 offset:37888
	ds_read_b128 v[210:213], v153 offset:38912
	ds_read_b128 v[214:217], v153 offset:39936
	global_load_lds_dwordx4 v[226:227], off
	v_lshl_add_u64 v[226:227], s[26:27], 0, v[132:133]
	s_mov_b32 m0, s41
	s_nop 0
	global_load_lds_dwordx4 v[226:227], off
	s_waitcnt vmcnt(8)
	s_waitcnt lgkmcnt(0)
	s_barrier
	s_setprio 1
	s_waitcnt lgkmcnt(0)
	v_mfma_f32_16x16x32_bf16 v[124:127], v[144:147], v[184:187], v[124:127]
	v_mfma_f32_16x16x32_bf16 v[120:123], v[160:163], v[184:187], v[120:123]
	v_mfma_f32_16x16x32_bf16 v[108:111], v[144:147], v[192:195], v[108:111]
	v_mfma_f32_16x16x32_bf16 v[104:107], v[160:163], v[192:195], v[104:107]
	v_mfma_f32_16x16x32_bf16 v[92:95], v[144:147], v[200:203], v[92:95]
	v_mfma_f32_16x16x32_bf16 v[88:91], v[160:163], v[200:203], v[88:91]
	v_mfma_f32_16x16x32_bf16 v[76:79], v[144:147], v[210:213], v[76:79]
	v_mfma_f32_16x16x32_bf16 v[72:75], v[160:163], v[210:213], v[72:75]
	v_mfma_f32_16x16x32_bf16 v[124:127], v[156:159], v[188:191], v[124:127]
	v_mfma_f32_16x16x32_bf16 v[120:123], v[164:167], v[188:191], v[120:123]
	v_mfma_f32_16x16x32_bf16 v[108:111], v[156:159], v[196:199], v[108:111]
	v_mfma_f32_16x16x32_bf16 v[104:107], v[164:167], v[196:199], v[104:107]
	v_mfma_f32_16x16x32_bf16 v[92:95], v[156:159], v[206:209], v[92:95]
	v_mfma_f32_16x16x32_bf16 v[88:91], v[164:167], v[206:209], v[88:91]
	v_mfma_f32_16x16x32_bf16 v[76:79], v[156:159], v[214:217], v[76:79]
	v_mfma_f32_16x16x32_bf16 v[72:75], v[164:167], v[214:217], v[72:75]
	s_setprio 0
	s_setprio 1
	v_mfma_f32_16x16x32_bf16 v[116:119], v[168:171], v[184:187], v[116:119]
	v_mfma_f32_16x16x32_bf16 v[112:115], v[176:179], v[184:187], v[112:115]
	v_mfma_f32_16x16x32_bf16 v[100:103], v[168:171], v[192:195], v[100:103]
	v_mfma_f32_16x16x32_bf16 v[96:99], v[176:179], v[192:195], v[96:99]
	v_mfma_f32_16x16x32_bf16 v[84:87], v[168:171], v[200:203], v[84:87]
	v_mfma_f32_16x16x32_bf16 v[80:83], v[176:179], v[200:203], v[80:83]
	v_mfma_f32_16x16x32_bf16 v[68:71], v[168:171], v[210:213], v[68:71]
	v_mfma_f32_16x16x32_bf16 v[64:67], v[176:179], v[210:213], v[64:67]
	v_mfma_f32_16x16x32_bf16 v[116:119], v[172:175], v[188:191], v[116:119]
	v_mfma_f32_16x16x32_bf16 v[112:115], v[180:183], v[188:191], v[112:115]
	v_mfma_f32_16x16x32_bf16 v[100:103], v[172:175], v[196:199], v[100:103]
	v_mfma_f32_16x16x32_bf16 v[96:99], v[180:183], v[196:199], v[96:99]
	v_mfma_f32_16x16x32_bf16 v[84:87], v[172:175], v[206:209], v[84:87]
	v_mfma_f32_16x16x32_bf16 v[80:83], v[180:183], v[206:209], v[80:83]
	v_mfma_f32_16x16x32_bf16 v[68:71], v[172:175], v[214:217], v[68:71]
	v_mfma_f32_16x16x32_bf16 v[64:67], v[180:183], v[214:217], v[64:67]
	s_setprio 0
	s_barrier
; #define PG8_STAGE(bufoff, gbase, voff) do { _Pragma("unroll") for (int _i = 0; _i < 2; ++_i) \
;         __builtin_amdgcn_global_load_lds((const unsigned*)((const char*)(gbase) + (voff)[_i]), (PG8_LAS unsigned*)(lds + (bufoff) + ldsw + _i * 8192), 16, 0, 0); } while (0)
; #define PG8_LDA(dst, b, h) do { _Pragma("unroll") for (int m = 0; m < 4; ++m) _Pragma("unroll") for (int k = 0; k < 2; ++k) dst[m][k] = *(const PG8_LAS bf16x8*)(lds + PG8_SA(b, h) + aoff + m * 2048 + k * 1024); } while (0)
; #define PG8_LDB(dst, b, h) do { _Pragma("unroll") for (int n = 0; n < 2; ++n) _Pragma("unroll") for (int k = 0; k < 2; ++k) dst[n][k] = *(const PG8_LAS bf16x8*)(lds + PG8_SB(b, h) + boff + n * 2048 + k * 1024); } while (0)
; #define PG8_MMA(ai, bj, At, Bt) do { __builtin_amdgcn_s_setprio(1); _Pragma("unroll") for (int m = 0; m < 4; ++m) _Pragma("unroll") for (int n = 0; n < 2; ++n) _Pragma("unroll") for (int k = 0; k < 2; ++k) \
;         acc[ai][bj][m][n] = __builtin_amdgcn_mfma_f32_16x16x32_bf16(Bt[n][k], At[m][k], acc[ai][bj][m][n], 0, 0, 0); __builtin_amdgcn_s_setprio(0); } while (0)
; #define PG8_WAIT_V(n) asm volatile("s_waitcnt vmcnt(" #n ")" ::: "memory")
; #define PG8_WAIT_L(n) asm volatile("s_waitcnt lgkmcnt(" #n ")" ::: "memory")
; #define PG8_BAR __builtin_amdgcn_s_barrier()
; #define PG8_SCHED __builtin_amdgcn_sched_barrier(0)
; template <class Epi, class Sched, bool ALIGN_EPI = false, bool SP2 = false>
; __device__ __forceinline__ void gemm_phase(PG8_LAS unsigned char* lds, const Gemm g, const Sched& S, const Epi& E) {
;     ...
;             PG8_LDB(B0, 0, 0); PG8_LDB(B1, 0, 1); PG8_SCHED; PG8_LDA(At, 0, 0); PG8_STAGE(PG8_SA(1, 1), a1 + hstep, voffA);
;             PG8_WAIT_V(8); PG8_WAIT_L(0); PG8_BAR; PG8_MMA(0, 0, At, B0); PG8_MMA(0, 1, At, B1); PG8_BAR; PG8_SCHED;
;     ...
;             PG8_WAIT_V(8); PG8_WAIT_L(0); PG8_BAR; PG8_MMA(0, 0, At, B0); PG8_MMA(0, 1, At, B1); PG8_BAR; PG8_SCHED;
;             PG8_LDA(At, 1, 1); PG8_STAGE(PG8_SB(1, 0), b3, voffB); PG8_STAGE(PG8_SB(1, 1), b3 + hstep, voffB); PG8_STAGE(PG8_SA(1, 0), a3, voffA);
;             PG8_WAIT_V(8); PG8_WAIT_L(0); PG8_BAR; PG8_MMA(1, 0, At, B0); PG8_MMA(1, 1, At, B1); PG8_BAR; PG8_SCHED;
	s_add_i32 s26, s56, s15
	v_lshl_add_u64 v[218:219], v[218:219], 0, s[12:13]
	s_mov_b32 m0, s26
	ds_read_b128 v[184:187], v153 offset:49152
	ds_read_b128 v[188:191], v153 offset:50176
	ds_read_b128 v[192:195], v153 offset:51200
	ds_read_b128 v[196:199], v153 offset:52224
	ds_read_b128 v[200:203], v153 offset:53248
	ds_read_b128 v[206:209], v153 offset:54272
	ds_read_b128 v[210:213], v153 offset:55296
	ds_read_b128 v[214:217], v153 offset:56320
	global_load_lds_dwordx4 v[218:219], off
	s_add_i32 m0, s26, 0x2000
	s_add_u32 s26, s36, 0xb0080
	v_lshl_add_u64 v[218:219], v[220:221], 0, s[12:13]
	s_addc_u32 s27, s37, 0
	s_add_i32 s36, s57, s15
	global_load_lds_dwordx4 v[218:219], off
	v_lshl_add_u64 v[218:219], s[26:27], 0, v[130:131]
	s_mov_b32 m0, s36
	s_nop 0
	global_load_lds_dwordx4 v[218:219], off
	v_lshl_add_u64 v[218:219], s[26:27], 0, v[134:135]
	s_add_i32 m0, s36, 0x2000
	s_nop 0
	global_load_lds_dwordx4 v[218:219], off
	s_waitcnt vmcnt(6)
	s_waitcnt lgkmcnt(0)
	s_barrier
	s_setprio 1
	s_waitcnt lgkmcnt(0)
	v_mfma_f32_16x16x32_bf16 v[60:63], v[144:147], v[184:187], v[60:63]
	v_mfma_f32_16x16x32_bf16 v[56:59], v[160:163], v[184:187], v[56:59]
	v_mfma_f32_16x16x32_bf16 v[44:47], v[144:147], v[192:195], v[44:47]
	v_mfma_f32_16x16x32_bf16 v[40:43], v[160:163], v[192:195], v[40:43]
	v_mfma_f32_16x16x32_bf16 v[28:31], v[144:147], v[200:203], v[28:31]
	v_mfma_f32_16x16x32_bf16 v[24:27], v[160:163], v[200:203], v[24:27]
	v_mfma_f32_16x16x32_bf16 v[12:15], v[144:147], v[210:213], v[12:15]
	v_mfma_f32_16x16x32_bf16 v[8:11], v[160:163], v[210:213], v[8:11]
	v_mfma_f32_16x16x32_bf16 v[60:63], v[156:159], v[188:191], v[60:63]
	v_mfma_f32_16x16x32_bf16 v[56:59], v[164:167], v[188:191], v[56:59]
	v_mfma_f32_16x16x32_bf16 v[44:47], v[156:159], v[196:199], v[44:47]
	v_mfma_f32_16x16x32_bf16 v[40:43], v[164:167], v[196:199], v[40:43]
	v_mfma_f32_16x16x32_bf16 v[28:31], v[156:159], v[206:209], v[28:31]
	v_mfma_f32_16x16x32_bf16 v[24:27], v[164:167], v[206:209], v[24:27]
	v_lshl_add_u64 v[218:219], v[222:223], 0, s[12:13]
	s_mov_b32 m0, s43
	s_nop 0
	global_load_lds_dwordx4 v[218:219], off
	v_mfma_f32_16x16x32_bf16 v[12:15], v[156:159], v[214:217], v[12:15]
	v_mfma_f32_16x16x32_bf16 v[8:11], v[164:167], v[214:217], v[8:11]
	s_setprio 0
	s_setprio 1
	v_mfma_f32_16x16x32_bf16 v[52:55], v[168:171], v[184:187], v[52:55]
	v_mfma_f32_16x16x32_bf16 v[48:51], v[176:179], v[184:187], v[48:51]
	v_mfma_f32_16x16x32_bf16 v[36:39], v[168:171], v[192:195], v[36:39]
	v_mfma_f32_16x16x32_bf16 v[32:35], v[176:179], v[192:195], v[32:35]
	v_mfma_f32_16x16x32_bf16 v[20:23], v[168:171], v[200:203], v[20:23]
	v_mfma_f32_16x16x32_bf16 v[16:19], v[176:179], v[200:203], v[16:19]
	v_mfma_f32_16x16x32_bf16 v[4:7], v[168:171], v[210:213], v[4:7]
	v_mfma_f32_16x16x32_bf16 v[0:3], v[176:179], v[210:213], v[0:3]
	v_mfma_f32_16x16x32_bf16 v[52:55], v[172:175], v[188:191], v[52:55]
	v_mfma_f32_16x16x32_bf16 v[48:51], v[180:183], v[188:191], v[48:51]
	v_mfma_f32_16x16x32_bf16 v[36:39], v[172:175], v[196:199], v[36:39]
	v_mfma_f32_16x16x32_bf16 v[32:35], v[180:183], v[196:199], v[32:35]
	v_mfma_f32_16x16x32_bf16 v[20:23], v[172:175], v[206:209], v[20:23]
	v_mfma_f32_16x16x32_bf16 v[16:19], v[180:183], v[206:209], v[16:19]
	v_lshl_add_u64 v[218:219], v[224:225], 0, s[12:13]
	s_mov_b32 m0, s44
	s_nop 0
	global_load_lds_dwordx4 v[218:219], off
	v_mfma_f32_16x16x32_bf16 v[4:7], v[172:175], v[214:217], v[4:7]
	v_mfma_f32_16x16x32_bf16 v[0:3], v[180:183], v[214:217], v[0:3]
	s_setprio 0
	s_barrier
	s_add_i32 s55, s55, 2
	s_add_u32 s53, s53, 0x100
	s_addc_u32 s54, s54, 0
	s_mov_b64 s[26:27], s[28:29]
.LBB0_1978:
	ds_read_b128 v[144:147], v151
	ds_read_b128 v[156:159], v151 offset:1024
	ds_read_b128 v[160:163], v151 offset:2048
	ds_read_b128 v[164:167], v151 offset:3072
	ds_read_b128 v[168:171], v152
	ds_read_b128 v[172:175], v152 offset:1024
	ds_read_b128 v[176:179], v152 offset:2048
	ds_read_b128 v[180:183], v152 offset:3072
	s_add_u32 s28, s26, 0x100
	s_addc_u32 s29, s27, 0
	s_cmp_eq_u32 s55, 40
	s_cselect_b32 s39, s1, s29
	s_cselect_b32 s38, s0, s28
	s_cselect_b32 s37, s25, s54
	s_cselect_b32 s36, s24, s53
	v_lshl_add_u64 v[218:219], s[26:27], 0, v[136:137]
	s_add_i32 m0, s33, 0xc000
	ds_read_b128 v[184:187], v153
	ds_read_b128 v[188:191], v153 offset:1024
	ds_read_b128 v[192:195], v153 offset:2048
	ds_read_b128 v[196:199], v153 offset:3072
	ds_read_b128 v[200:203], v153 offset:4096
	ds_read_b128 v[206:209], v153 offset:5120
	ds_read_b128 v[210:213], v153 offset:6144
	ds_read_b128 v[214:217], v153 offset:7168
	global_load_lds_dwordx4 v[218:219], off
	v_lshl_add_u64 v[218:219], s[26:27], 0, v[138:139]
	s_add_i32 m0, s33, 0xe000
	s_nop 0
	global_load_lds_dwordx4 v[218:219], off
	s_waitcnt vmcnt(8)
	s_waitcnt lgkmcnt(0)
	s_barrier
; #define PG8_STAGE(bufoff, gbase, voff) do { _Pragma("unroll") for (int _i = 0; _i < 2; ++_i) \
;         __builtin_amdgcn_global_load_lds((const unsigned*)((const char*)(gbase) + (voff)[_i]), (PG8_LAS unsigned*)(lds + (bufoff) + ldsw + _i * 8192), 16, 0, 0); } while (0)
; #define PG8_LDA(dst, b, h) do { _Pragma("unroll") for (int m = 0; m < 4; ++m) _Pragma("unroll") for (int k = 0; k < 2; ++k) dst[m][k] = *(const PG8_LAS bf16x8*)(lds + PG8_SA(b, h) + aoff + m * 2048 + k * 1024); } while (0)
; #define PG8_LDB(dst, b, h) do { _Pragma("unroll") for (int n = 0; n < 2; ++n) _Pragma("unroll") for (int k = 0; k < 2; ++k) dst[n][k] = *(const PG8_LAS bf16x8*)(lds + PG8_SB(b, h) + boff + n * 2048 + k * 1024); } while (0)
; #define PG8_MMA(ai, bj, At, Bt) do { __builtin_amdgcn_s_setprio(1); _Pragma("unroll") for (int m = 0; m < 4; ++m) _Pragma("unroll") for (int n = 0; n < 2; ++n) _Pragma("unroll") for (int k = 0; k < 2; ++k) \
;         acc[ai][bj][m][n] = __builtin_amdgcn_mfma_f32_16x16x32_bf16(Bt[n][k], At[m][k], acc[ai][bj][m][n], 0, 0, 0); __builtin_amdgcn_s_setprio(0); } while (0)
; #define PG8_WAIT_V(n) asm volatile("s_waitcnt vmcnt(" #n ")" ::: "memory")
; #define PG8_WAIT_L(n) asm volatile("s_waitcnt lgkmcnt(" #n ")" ::: "memory")
; #define PG8_BAR __builtin_amdgcn_s_barrier()
; #define PG8_SCHED __builtin_amdgcn_sched_barrier(0)
; template <class Epi, class Sched, bool ALIGN_EPI = false, bool SP2 = false>
; __device__ __forceinline__ void gemm_phase(PG8_LAS unsigned char* lds, const Gemm g, const Sched& S, const Epi& E) {
;     ...
;             PG8_LDB(B0, 0, 0); PG8_LDB(B1, 0, 1); PG8_SCHED; PG8_LDA(At, 0, 0); PG8_STAGE(PG8_SA(1, 1), a1 + hstep, voffA);
;             PG8_WAIT_V(8); PG8_WAIT_L(0); PG8_BAR; PG8_MMA(0, 0, At, B0); PG8_MMA(0, 1, At, B1); PG8_BAR; PG8_SCHED;
;             PG8_LDA(At, 0, 1); PG8_STAGE(PG8_SB(0, 0), b2, voffB); PG8_STAGE(PG8_SB(0, 1), b2 + hstep, voffB); PG8_STAGE(PG8_SA(0, 0), a2, voffA);
;             PG8_WAIT_V(8); PG8_WAIT_L(0); PG8_BAR; PG8_MMA(1, 0, At, B0); PG8_MMA(1, 1, At, B1); PG8_BAR; PG8_SCHED;
	s_setprio 1
	s_waitcnt lgkmcnt(0)
	v_mfma_f32_16x16x32_bf16 v[124:127], v[144:147], v[184:187], v[124:127]
	v_mfma_f32_16x16x32_bf16 v[120:123], v[160:163], v[184:187], v[120:123]
	v_mfma_f32_16x16x32_bf16 v[108:111], v[144:147], v[192:195], v[108:111]
	v_mfma_f32_16x16x32_bf16 v[104:107], v[160:163], v[192:195], v[104:107]
	v_mfma_f32_16x16x32_bf16 v[92:95], v[144:147], v[200:203], v[92:95]
	v_mfma_f32_16x16x32_bf16 v[88:91], v[160:163], v[200:203], v[88:91]
	v_mfma_f32_16x16x32_bf16 v[76:79], v[144:147], v[210:213], v[76:79]
	v_mfma_f32_16x16x32_bf16 v[72:75], v[160:163], v[210:213], v[72:75]
	v_mfma_f32_16x16x32_bf16 v[124:127], v[156:159], v[188:191], v[124:127]
	v_mfma_f32_16x16x32_bf16 v[120:123], v[164:167], v[188:191], v[120:123]
	v_mfma_f32_16x16x32_bf16 v[108:111], v[156:159], v[196:199], v[108:111]
	v_mfma_f32_16x16x32_bf16 v[104:107], v[164:167], v[196:199], v[104:107]
	v_mfma_f32_16x16x32_bf16 v[92:95], v[156:159], v[206:209], v[92:95]
	v_mfma_f32_16x16x32_bf16 v[88:91], v[164:167], v[206:209], v[88:91]
	v_mfma_f32_16x16x32_bf16 v[76:79], v[156:159], v[214:217], v[76:79]
	v_mfma_f32_16x16x32_bf16 v[72:75], v[164:167], v[214:217], v[72:75]
	s_setprio 0
	s_setprio 1
	v_mfma_f32_16x16x32_bf16 v[116:119], v[168:171], v[184:187], v[116:119]
	v_mfma_f32_16x16x32_bf16 v[112:115], v[176:179], v[184:187], v[112:115]
	v_mfma_f32_16x16x32_bf16 v[100:103], v[168:171], v[192:195], v[100:103]
	v_mfma_f32_16x16x32_bf16 v[96:99], v[176:179], v[192:195], v[96:99]
	v_mfma_f32_16x16x32_bf16 v[84:87], v[168:171], v[200:203], v[84:87]
	v_mfma_f32_16x16x32_bf16 v[80:83], v[176:179], v[200:203], v[80:83]
	v_mfma_f32_16x16x32_bf16 v[68:71], v[168:171], v[210:213], v[68:71]
	v_mfma_f32_16x16x32_bf16 v[64:67], v[176:179], v[210:213], v[64:67]
	v_mfma_f32_16x16x32_bf16 v[116:119], v[172:175], v[188:191], v[116:119]
	v_mfma_f32_16x16x32_bf16 v[112:115], v[180:183], v[188:191], v[112:115]
	v_mfma_f32_16x16x32_bf16 v[100:103], v[172:175], v[196:199], v[100:103]
	v_mfma_f32_16x16x32_bf16 v[96:99], v[180:183], v[196:199], v[96:99]
	v_mfma_f32_16x16x32_bf16 v[84:87], v[172:175], v[206:209], v[84:87]
	v_mfma_f32_16x16x32_bf16 v[80:83], v[180:183], v[206:209], v[80:83]
	v_mfma_f32_16x16x32_bf16 v[68:71], v[172:175], v[214:217], v[68:71]
	v_mfma_f32_16x16x32_bf16 v[64:67], v[180:183], v[214:217], v[64:67]
	s_setprio 0
	s_barrier
	s_add_i32 s26, s45, s15
	v_lshl_add_u64 v[218:219], s[36:37], 0, v[130:131]
	s_mov_b32 m0, s26
	ds_read_b128 v[184:187], v153 offset:16384
	ds_read_b128 v[188:191], v153 offset:17408
	ds_read_b128 v[192:195], v153 offset:18432
	ds_read_b128 v[196:199], v153 offset:19456
	ds_read_b128 v[200:203], v153 offset:20480
	ds_read_b128 v[206:209], v153 offset:21504
	ds_read_b128 v[210:213], v153 offset:22528
	ds_read_b128 v[214:217], v153 offset:23552
	global_load_lds_dwordx4 v[218:219], off
	s_add_i32 m0, s26, 0x2000
	s_add_u32 s26, s36, 0xb0000
	v_lshl_add_u64 v[220:221], s[36:37], 0, v[134:135]
	s_addc_u32 s27, s37, 0
	s_add_i32 s56, s46, s15
	global_load_lds_dwordx4 v[220:221], off
	v_lshl_add_u64 v[222:223], s[26:27], 0, v[130:131]
	s_mov_b32 m0, s56
	global_load_lds_dwordx4 v[222:223], off
	v_lshl_add_u64 v[222:223], s[26:27], 0, v[134:135]
	s_add_i32 m0, s56, 0x2000
	s_nop 0
	global_load_lds_dwordx4 v[222:223], off
	s_waitcnt vmcnt(6)
	s_waitcnt lgkmcnt(0)
	s_barrier
	s_setprio 1
	s_waitcnt lgkmcnt(0)
	v_mfma_f32_16x16x32_bf16 v[60:63], v[144:147], v[184:187], v[60:63]
	v_mfma_f32_16x16x32_bf16 v[56:59], v[160:163], v[184:187], v[56:59]
	v_mfma_f32_16x16x32_bf16 v[44:47], v[144:147], v[192:195], v[44:47]
	v_mfma_f32_16x16x32_bf16 v[40:43], v[160:163], v[192:195], v[40:43]
	v_mfma_f32_16x16x32_bf16 v[28:31], v[144:147], v[200:203], v[28:31]
	v_mfma_f32_16x16x32_bf16 v[24:27], v[160:163], v[200:203], v[24:27]
	v_mfma_f32_16x16x32_bf16 v[12:15], v[144:147], v[210:213], v[12:15]
	v_mfma_f32_16x16x32_bf16 v[8:11], v[160:163], v[210:213], v[8:11]
	v_mfma_f32_16x16x32_bf16 v[60:63], v[156:159], v[188:191], v[60:63]
	v_mfma_f32_16x16x32_bf16 v[56:59], v[164:167], v[188:191], v[56:59]
	v_mfma_f32_16x16x32_bf16 v[44:47], v[156:159], v[196:199], v[44:47]
	v_mfma_f32_16x16x32_bf16 v[40:43], v[164:167], v[196:199], v[40:43]
	v_mfma_f32_16x16x32_bf16 v[28:31], v[156:159], v[206:209], v[28:31]
	v_mfma_f32_16x16x32_bf16 v[24:27], v[164:167], v[206:209], v[24:27]
	v_lshl_add_u64 v[222:223], s[38:39], 0, v[128:129]
	s_mov_b32 m0, s33
	s_nop 0
	global_load_lds_dwordx4 v[222:223], off
	v_mfma_f32_16x16x32_bf16 v[12:15], v[156:159], v[214:217], v[12:15]
	v_mfma_f32_16x16x32_bf16 v[8:11], v[164:167], v[214:217], v[8:11]
	s_setprio 0
	s_setprio 1
	v_mfma_f32_16x16x32_bf16 v[52:55], v[168:171], v[184:187], v[52:55]
	v_mfma_f32_16x16x32_bf16 v[48:51], v[176:179], v[184:187], v[48:51]
	v_mfma_f32_16x16x32_bf16 v[36:39], v[168:171], v[192:195], v[36:39]
	v_mfma_f32_16x16x32_bf16 v[32:35], v[176:179], v[192:195], v[32:35]
	v_mfma_f32_16x16x32_bf16 v[20:23], v[168:171], v[200:203], v[20:23]
	v_mfma_f32_16x16x32_bf16 v[16:19], v[176:179], v[200:203], v[16:19]
	v_mfma_f32_16x16x32_bf16 v[4:7], v[168:171], v[210:213], v[4:7]
	v_mfma_f32_16x16x32_bf16 v[0:3], v[176:179], v[210:213], v[0:3]
	v_mfma_f32_16x16x32_bf16 v[52:55], v[172:175], v[188:191], v[52:55]
	v_mfma_f32_16x16x32_bf16 v[48:51], v[180:183], v[188:191], v[48:51]
	v_mfma_f32_16x16x32_bf16 v[36:39], v[172:175], v[196:199], v[36:39]
	v_mfma_f32_16x16x32_bf16 v[32:35], v[180:183], v[196:199], v[32:35]
	v_mfma_f32_16x16x32_bf16 v[20:23], v[172:175], v[206:209], v[20:23]
	v_mfma_f32_16x16x32_bf16 v[16:19], v[180:183], v[206:209], v[16:19]
	v_lshl_add_u64 v[224:225], s[38:39], 0, v[132:133]
	s_mov_b32 m0, s34
	s_nop 0
	global_load_lds_dwordx4 v[224:225], off
	v_mfma_f32_16x16x32_bf16 v[4:7], v[172:175], v[214:217], v[4:7]
	v_mfma_f32_16x16x32_bf16 v[0:3], v[180:183], v[214:217], v[0:3]
	s_setprio 0
	s_barrier
; #define PG8_STAGE(bufoff, gbase, voff) do { _Pragma("unroll") for (int _i = 0; _i < 2; ++_i) \
;         __builtin_amdgcn_global_load_lds((const unsigned*)((const char*)(gbase) + (voff)[_i]), (PG8_LAS unsigned*)(lds + (bufoff) + ldsw + _i * 8192), 16, 0, 0); } while (0)
; #define PG8_LDA(dst, b, h) do { _Pragma("unroll") for (int m = 0; m < 4; ++m) _Pragma("unroll") for (int k = 0; k < 2; ++k) dst[m][k] = *(const PG8_LAS bf16x8*)(lds + PG8_SA(b, h) + aoff + m * 2048 + k * 1024); } while (0)
; #define PG8_LDB(dst, b, h) do { _Pragma("unroll") for (int n = 0; n < 2; ++n) _Pragma("unroll") for (int k = 0; k < 2; ++k) dst[n][k] = *(const PG8_LAS bf16x8*)(lds + PG8_SB(b, h) + boff + n * 2048 + k * 1024); } while (0)
; #define PG8_MMA(ai, bj, At, Bt) do { __builtin_amdgcn_s_setprio(1); _Pragma("unroll") for (int m = 0; m < 4; ++m) _Pragma("unroll") for (int n = 0; n < 2; ++n) _Pragma("unroll") for (int k = 0; k < 2; ++k) \
;         acc[ai][bj][m][n] = __builtin_amdgcn_mfma_f32_16x16x32_bf16(Bt[n][k], At[m][k], acc[ai][bj][m][n], 0, 0, 0); __builtin_amdgcn_s_setprio(0); } while (0)
; #define PG8_WAIT_V(n) asm volatile("s_waitcnt vmcnt(" #n ")" ::: "memory")
; #define PG8_WAIT_L(n) asm volatile("s_waitcnt lgkmcnt(" #n ")" ::: "memory")
; #define PG8_BAR __builtin_amdgcn_s_barrier()
; #define PG8_SCHED __builtin_amdgcn_sched_barrier(0)
; template <class Epi, class Sched, bool ALIGN_EPI = false, bool SP2 = false>
; __device__ __forceinline__ void gemm_phase(PG8_LAS unsigned char* lds, const Gemm g, const Sched& S, const Epi& E) {
;     ...
;             PG8_LDB(B0, 1, 0); PG8_LDB(B1, 1, 1); PG8_SCHED; PG8_LDA(At, 1, 0); PG8_STAGE(PG8_SA(0, 1), a2 + hstep, voffA);
;             PG8_WAIT_V(8); PG8_WAIT_L(0); PG8_BAR; PG8_MMA(0, 0, At, B0); PG8_MMA(0, 1, At, B1); PG8_BAR; PG8_SCHED;
	s_add_i32 s56, 0, 0x18000
	v_add_u32_e32 v155, s56, v149
	s_add_i32 s57, 0, 0x1c000
	ds_read_b128 v[144:147], v155
	ds_read_b128 v[156:159], v155 offset:1024
	ds_read_b128 v[160:163], v155 offset:2048
	ds_read_b128 v[164:167], v155 offset:3072
	v_add_u32_e32 v155, s57, v149
	ds_read_b128 v[168:171], v155
	ds_read_b128 v[172:175], v155 offset:1024
	ds_read_b128 v[176:179], v155 offset:2048
	ds_read_b128 v[180:183], v155 offset:3072
	s_add_u32 s26, s38, 0xb0000
	s_addc_u32 s27, s39, 0
	s_mov_b32 m0, s40
	v_lshl_add_u64 v[226:227], s[26:27], 0, v[128:129]
	ds_read_b128 v[184:187], v153 offset:32768
	ds_read_b128 v[188:191], v153 offset:33792
	ds_read_b128 v[192:195], v153 offset:34816
	ds_read_b128 v[196:199], v153 offset:35840
	ds_read_b128 v[200:203], v153 offset:36864
	ds_read_b128 v[206:209], v153 offset:37888
	ds_read_b128 v[210:213], v153 offset:38912
	ds_read_b128 v[214:217], v153 offset:39936
	global_load_lds_dwordx4 v[226:227], off
	v_lshl_add_u64 v[226:227], s[26:27], 0, v[132:133]
	s_mov_b32 m0, s41
	s_nop 0
	global_load_lds_dwordx4 v[226:227], off
	s_waitcnt vmcnt(8)
	s_waitcnt lgkmcnt(0)
	s_barrier
	s_setprio 1
	s_waitcnt lgkmcnt(0)
	v_mfma_f32_16x16x32_bf16 v[124:127], v[144:147], v[184:187], v[124:127]
	v_mfma_f32_16x16x32_bf16 v[120:123], v[160:163], v[184:187], v[120:123]
	v_mfma_f32_16x16x32_bf16 v[108:111], v[144:147], v[192:195], v[108:111]
	v_mfma_f32_16x16x32_bf16 v[104:107], v[160:163], v[192:195], v[104:107]
	v_mfma_f32_16x16x32_bf16 v[92:95], v[144:147], v[200:203], v[92:95]
	v_mfma_f32_16x16x32_bf16 v[88:91], v[160:163], v[200:203], v[88:91]
	v_mfma_f32_16x16x32_bf16 v[76:79], v[144:147], v[210:213], v[76:79]
	v_mfma_f32_16x16x32_bf16 v[72:75], v[160:163], v[210:213], v[72:75]
	v_mfma_f32_16x16x32_bf16 v[124:127], v[156:159], v[188:191], v[124:127]
	v_mfma_f32_16x16x32_bf16 v[120:123], v[164:167], v[188:191], v[120:123]
	v_mfma_f32_16x16x32_bf16 v[108:111], v[156:159], v[196:199], v[108:111]
	v_mfma_f32_16x16x32_bf16 v[104:107], v[164:167], v[196:199], v[104:107]
	v_mfma_f32_16x16x32_bf16 v[92:95], v[156:159], v[206:209], v[92:95]
	v_mfma_f32_16x16x32_bf16 v[88:91], v[164:167], v[206:209], v[88:91]
	v_mfma_f32_16x16x32_bf16 v[76:79], v[156:159], v[214:217], v[76:79]
	v_mfma_f32_16x16x32_bf16 v[72:75], v[164:167], v[214:217], v[72:75]
	s_setprio 0
	s_setprio 1
	v_mfma_f32_16x16x32_bf16 v[116:119], v[168:171], v[184:187], v[116:119]
	v_mfma_f32_16x16x32_bf16 v[112:115], v[176:179], v[184:187], v[112:115]
	v_mfma_f32_16x16x32_bf16 v[100:103], v[168:171], v[192:195], v[100:103]
	v_mfma_f32_16x16x32_bf16 v[96:99], v[176:179], v[192:195], v[96:99]
	v_mfma_f32_16x16x32_bf16 v[84:87], v[168:171], v[200:203], v[84:87]
	v_mfma_f32_16x16x32_bf16 v[80:83], v[176:179], v[200:203], v[80:83]
	v_mfma_f32_16x16x32_bf16 v[68:71], v[168:171], v[210:213], v[68:71]
	v_mfma_f32_16x16x32_bf16 v[64:67], v[176:179], v[210:213], v[64:67]
	v_mfma_f32_16x16x32_bf16 v[116:119], v[172:175], v[188:191], v[116:119]
	v_mfma_f32_16x16x32_bf16 v[112:115], v[180:183], v[188:191], v[112:115]
	v_mfma_f32_16x16x32_bf16 v[100:103], v[172:175], v[196:199], v[100:103]
	v_mfma_f32_16x16x32_bf16 v[96:99], v[180:183], v[196:199], v[96:99]
	v_mfma_f32_16x16x32_bf16 v[84:87], v[172:175], v[206:209], v[84:87]
	v_mfma_f32_16x16x32_bf16 v[80:83], v[180:183], v[206:209], v[80:83]
	v_mfma_f32_16x16x32_bf16 v[68:71], v[172:175], v[214:217], v[68:71]
	v_mfma_f32_16x16x32_bf16 v[64:67], v[180:183], v[214:217], v[64:67]
	s_setprio 0
	s_barrier
; #define PG8_STAGE(bufoff, gbase, voff) do { _Pragma("unroll") for (int _i = 0; _i < 2; ++_i) \
;         __builtin_amdgcn_global_load_lds((const unsigned*)((const char*)(gbase) + (voff)[_i]), (PG8_LAS unsigned*)(lds + (bufoff) + ldsw + _i * 8192), 16, 0, 0); } while (0)
; #define PG8_LDA(dst, b, h) do { _Pragma("unroll") for (int m = 0; m < 4; ++m) _Pragma("unroll") for (int k = 0; k < 2; ++k) dst[m][k] = *(const PG8_LAS bf16x8*)(lds + PG8_SA(b, h) + aoff + m * 2048 + k * 1024); } while (0)
; #define PG8_MMA(ai, bj, At, Bt) do { __builtin_amdgcn_s_setprio(1); _Pragma("unroll") for (int m = 0; m < 4; ++m) _Pragma("unroll") for (int n = 0; n < 2; ++n) _Pragma("unroll") for (int k = 0; k < 2; ++k) \
;         acc[ai][bj][m][n] = __builtin_amdgcn_mfma_f32_16x16x32_bf16(Bt[n][k], At[m][k], acc[ai][bj][m][n], 0, 0, 0); __builtin_amdgcn_s_setprio(0); } while (0)
; #define PG8_WAIT_V(n) asm volatile("s_waitcnt vmcnt(" #n ")" ::: "memory")
; #define PG8_WAIT_L(n) asm volatile("s_waitcnt lgkmcnt(" #n ")" ::: "memory")
; #define PG8_BAR __builtin_amdgcn_s_barrier()
; #define PG8_SCHED __builtin_amdgcn_sched_barrier(0)
; template <class Epi, class Sched, bool ALIGN_EPI = false, bool SP2 = false>
; __device__ __forceinline__ void gemm_phase(PG8_LAS unsigned char* lds, const Gemm g, const Sched& S, const Epi& E) {
;     ...
;             PG8_WAIT_V(8); PG8_WAIT_L(0); PG8_BAR; PG8_MMA(0, 0, At, B0); PG8_MMA(0, 1, At, B1); PG8_BAR; PG8_SCHED;
;             PG8_LDA(At, 1, 1); PG8_STAGE(PG8_SB(1, 0), b3, voffB); PG8_STAGE(PG8_SB(1, 1), b3 + hstep, voffB); PG8_STAGE(PG8_SA(1, 0), a3, voffA);
;             PG8_WAIT_V(8); PG8_WAIT_L(0); PG8_BAR; PG8_MMA(1, 0, At, B0); PG8_MMA(1, 1, At, B1); PG8_BAR; PG8_SCHED;
;     ...
;         if constexpr (ALIGN_EPI) { if (wr == 0) PG8_BAR; }
	s_add_i32 s26, s56, s15
	v_lshl_add_u64 v[218:219], v[218:219], 0, s[12:13]
	s_mov_b32 m0, s26
	ds_read_b128 v[184:187], v153 offset:49152
	ds_read_b128 v[188:191], v153 offset:50176
	ds_read_b128 v[192:195], v153 offset:51200
	ds_read_b128 v[196:199], v153 offset:52224
	ds_read_b128 v[200:203], v153 offset:53248
	ds_read_b128 v[206:209], v153 offset:54272
	ds_read_b128 v[210:213], v153 offset:55296
	ds_read_b128 v[214:217], v153 offset:56320
	global_load_lds_dwordx4 v[218:219], off
	s_add_i32 m0, s26, 0x2000
	s_add_u32 s26, s36, 0xb0080
	v_lshl_add_u64 v[218:219], v[220:221], 0, s[12:13]
	s_addc_u32 s27, s37, 0
	s_add_i32 s36, s57, s15
	global_load_lds_dwordx4 v[218:219], off
	v_lshl_add_u64 v[218:219], s[26:27], 0, v[130:131]
	s_mov_b32 m0, s36
	s_nop 0
	global_load_lds_dwordx4 v[218:219], off
	v_lshl_add_u64 v[218:219], s[26:27], 0, v[134:135]
	s_add_i32 m0, s36, 0x2000
	s_nop 0
	global_load_lds_dwordx4 v[218:219], off
	s_waitcnt vmcnt(6)
	s_waitcnt lgkmcnt(0)
	s_barrier
	s_setprio 1
	s_waitcnt lgkmcnt(0)
	v_mfma_f32_16x16x32_bf16 v[60:63], v[144:147], v[184:187], v[60:63]
	v_mfma_f32_16x16x32_bf16 v[56:59], v[160:163], v[184:187], v[56:59]
	v_mfma_f32_16x16x32_bf16 v[44:47], v[144:147], v[192:195], v[44:47]
	v_mfma_f32_16x16x32_bf16 v[40:43], v[160:163], v[192:195], v[40:43]
	v_mfma_f32_16x16x32_bf16 v[28:31], v[144:147], v[200:203], v[28:31]
	v_mfma_f32_16x16x32_bf16 v[24:27], v[160:163], v[200:203], v[24:27]
	v_mfma_f32_16x16x32_bf16 v[12:15], v[144:147], v[210:213], v[12:15]
	v_mfma_f32_16x16x32_bf16 v[8:11], v[160:163], v[210:213], v[8:11]
	v_mfma_f32_16x16x32_bf16 v[60:63], v[156:159], v[188:191], v[60:63]
	v_mfma_f32_16x16x32_bf16 v[56:59], v[164:167], v[188:191], v[56:59]
	v_mfma_f32_16x16x32_bf16 v[44:47], v[156:159], v[196:199], v[44:47]
	v_mfma_f32_16x16x32_bf16 v[40:43], v[164:167], v[196:199], v[40:43]
	v_mfma_f32_16x16x32_bf16 v[28:31], v[156:159], v[206:209], v[28:31]
	v_mfma_f32_16x16x32_bf16 v[24:27], v[164:167], v[206:209], v[24:27]
	v_lshl_add_u64 v[218:219], v[222:223], 0, s[12:13]
	s_mov_b32 m0, s43
	s_nop 0
	global_load_lds_dwordx4 v[218:219], off
	v_mfma_f32_16x16x32_bf16 v[12:15], v[156:159], v[214:217], v[12:15]
	v_mfma_f32_16x16x32_bf16 v[8:11], v[164:167], v[214:217], v[8:11]
	s_setprio 0
	s_setprio 1
	v_mfma_f32_16x16x32_bf16 v[52:55], v[168:171], v[184:187], v[52:55]
	v_mfma_f32_16x16x32_bf16 v[48:51], v[176:179], v[184:187], v[48:51]
	v_mfma_f32_16x16x32_bf16 v[36:39], v[168:171], v[192:195], v[36:39]
	v_mfma_f32_16x16x32_bf16 v[32:35], v[176:179], v[192:195], v[32:35]
	v_mfma_f32_16x16x32_bf16 v[20:23], v[168:171], v[200:203], v[20:23]
	v_mfma_f32_16x16x32_bf16 v[16:19], v[176:179], v[200:203], v[16:19]
	v_mfma_f32_16x16x32_bf16 v[4:7], v[168:171], v[210:213], v[4:7]
	v_mfma_f32_16x16x32_bf16 v[0:3], v[176:179], v[210:213], v[0:3]
	v_mfma_f32_16x16x32_bf16 v[52:55], v[172:175], v[188:191], v[52:55]
	v_mfma_f32_16x16x32_bf16 v[48:51], v[180:183], v[188:191], v[48:51]
	v_mfma_f32_16x16x32_bf16 v[36:39], v[172:175], v[196:199], v[36:39]
	v_mfma_f32_16x16x32_bf16 v[32:35], v[180:183], v[196:199], v[32:35]
	v_mfma_f32_16x16x32_bf16 v[20:23], v[172:175], v[206:209], v[20:23]
	v_mfma_f32_16x16x32_bf16 v[16:19], v[180:183], v[206:209], v[16:19]
	v_lshl_add_u64 v[218:219], v[224:225], 0, s[12:13]
	s_mov_b32 m0, s44
	s_nop 0
	global_load_lds_dwordx4 v[218:219], off
	v_mfma_f32_16x16x32_bf16 v[4:7], v[172:175], v[214:217], v[4:7]
	v_mfma_f32_16x16x32_bf16 v[0:3], v[180:183], v[214:217], v[0:3]
	s_setprio 0
	s_barrier
	s_add_i32 s55, s55, 2
	s_add_u32 s53, s53, 0x100
	s_addc_u32 s54, s54, 0
	s_cmp_gt_u32 s55, 41
	s_mov_b64 s[26:27], s[28:29]
	s_cbranch_scc0 .LBB0_1978
	s_and_b64 vcc, exec, s[16:17]
	s_cbranch_vccz .LBB0_1981
	s_barrier
